# GEMM k-loops: segment-edge rotation (load-segment address prep and loop back-edge bookkeeping moved ahead of the preceding barrier)
# baseline (speedup 1.0000x reference)
; #define G_STAGE(bufoff, gbase, voff) do { _Pragma("unroll") for (int _i = 0; _i < 2; ++_i) \
;         __builtin_amdgcn_global_load_lds((const unsigned*)((const char*)(gbase) + voff[_i]), (LAS unsigned*)(lds + (bufoff) + ldsw + _i * 8192), 16, 0, 0); } while (0)
; #define G_LDA(dst, b, h) do { _Pragma("unroll") for (int m = 0; m < 4; ++m) _Pragma("unroll") for (int k = 0; k < 2; ++k) dst[m][k] = *(const LAS bf16x8*)(lds + G_SA(b, h) + aoff + m * 2048 + k * 1024); } while (0)
; #define G_LDB(dst, b, h) do { _Pragma("unroll") for (int n = 0; n < 2; ++n) _Pragma("unroll") for (int k = 0; k < 2; ++k) dst[n][k] = *(const LAS bf16x8*)(lds + G_SB(b, h) + boff + n * 2048 + k * 1024); } while (0)
; #define G_MMA(ai, bj, At_, Bt_) do { __builtin_amdgcn_s_setprio(1); _Pragma("unroll") for (int m = 0; m < 4; ++m) _Pragma("unroll") for (int n = 0; n < 2; ++n) _Pragma("unroll") for (int k = 0; k < 2; ++k) \
;         acc[ai][bj][m][n] = __builtin_amdgcn_mfma_f32_16x16x32_bf16(Bt_[n][k], At_[m][k], acc[ai][bj][m][n], 0, 0, 0); __builtin_amdgcn_s_setprio(0); } while (0)
; #define WAIT_V(n) asm volatile("s_waitcnt vmcnt(" #n ")" ::: "memory")
; #define WAIT_L(n) asm volatile("s_waitcnt lgkmcnt(" #n ")" ::: "memory")
; #define BAR __builtin_amdgcn_s_barrier()
; #define SCHED __builtin_amdgcn_sched_barrier(0)
; template <class Get, class Epi>
; DI void gemm_loop(int ntiles, int ld, char* shm, const Get& get, const Epi& epi) {
;     ...
;             G_LDB(B0, 0, 0); G_LDB(B1, 0, 1); SCHED; G_LDA(At, 0, 0); G_STAGE(G_SA(1, 1), a1 + hstep, voffA);
;             WAIT_V(8); WAIT_L(0); BAR; G_MMA(0, 0, At, B0); G_MMA(0, 1, At, B1); BAR; SCHED;
;             G_LDA(At, 0, 1); G_STAGE(G_SB(0, 0), b2, voffB); G_STAGE(G_SB(0, 1), b2 + hstep, voffB); G_STAGE(G_SA(0, 0), a2, voffA);
;             WAIT_V(8); WAIT_L(0); BAR; G_MMA(1, 0, At, B0); G_MMA(1, 1, At, B1); BAR; SCHED;
.Lpeel_431:
	ds_read_b128 v[146:149], v141
	ds_read_b128 v[150:153], v141 offset:1024
	ds_read_b128 v[154:157], v141 offset:2048
	ds_read_b128 v[158:161], v141 offset:3072
	ds_read_b128 v[162:165], v142
	ds_read_b128 v[166:169], v142 offset:1024
	ds_read_b128 v[170:173], v142 offset:2048
	ds_read_b128 v[174:177], v142 offset:3072
	s_add_u32 s14, s34, 0xfff00080
	s_addc_u32 s15, s35, -1
	s_cmp_eq_u32 s81, 60
	s_cselect_b32 s37, s74, s15
	s_cselect_b32 s36, s75, s14
	s_cselect_b32 s15, s76, s80
	s_cselect_b32 s14, s78, s79
	s_mov_b32 m0, s56
	v_lshl_add_u64 v[182:183], s[34:35], 0, v[136:137]
	ds_read_b128 v[178:181], v143
	ds_read_b128 v[188:191], v143 offset:1024
	ds_read_b128 v[192:195], v143 offset:2048
	ds_read_b128 v[196:199], v143 offset:3072
	ds_read_b128 v[200:203], v143 offset:4096
	ds_read_b128 v[204:207], v143 offset:5120
	ds_read_b128 v[208:211], v143 offset:6144
	ds_read_b128 v[212:215], v143 offset:7168
	global_load_lds_dwordx4 v[182:183], off
	v_lshl_add_u64 v[182:183], s[34:35], 0, v[138:139]
	s_add_i32 m0, s43, 0xe000
	s_nop 0
	global_load_lds_dwordx4 v[182:183], off
	s_waitcnt vmcnt(8)
	s_waitcnt lgkmcnt(0)
	s_barrier
	s_setprio 1
	s_waitcnt lgkmcnt(0)
	v_mfma_f32_16x16x32_bf16 v[124:127], v[146:149], v[178:181], 0
	v_mfma_f32_16x16x32_bf16 v[120:123], v[154:157], v[178:181], 0
	v_mfma_f32_16x16x32_bf16 v[116:119], v[146:149], v[192:195], 0
	v_mfma_f32_16x16x32_bf16 v[112:115], v[154:157], v[192:195], 0
	v_mfma_f32_16x16x32_bf16 v[100:103], v[146:149], v[200:203], 0
	v_mfma_f32_16x16x32_bf16 v[96:99], v[154:157], v[200:203], 0
	v_mfma_f32_16x16x32_bf16 v[84:87], v[146:149], v[208:211], 0
	v_mfma_f32_16x16x32_bf16 v[80:83], v[154:157], v[208:211], 0
	v_mfma_f32_16x16x32_bf16 v[124:127], v[150:153], v[188:191], v[124:127]
	v_mfma_f32_16x16x32_bf16 v[120:123], v[158:161], v[188:191], v[120:123]
	v_mfma_f32_16x16x32_bf16 v[116:119], v[150:153], v[196:199], v[116:119]
	v_mfma_f32_16x16x32_bf16 v[112:115], v[158:161], v[196:199], v[112:115]
	v_mfma_f32_16x16x32_bf16 v[100:103], v[150:153], v[204:207], v[100:103]
	v_mfma_f32_16x16x32_bf16 v[96:99], v[158:161], v[204:207], v[96:99]
	v_mfma_f32_16x16x32_bf16 v[84:87], v[150:153], v[212:215], v[84:87]
	v_mfma_f32_16x16x32_bf16 v[80:83], v[158:161], v[212:215], v[80:83]
	s_setprio 0
	s_setprio 1
	v_mfma_f32_16x16x32_bf16 v[108:111], v[162:165], v[178:181], 0
	v_mfma_f32_16x16x32_bf16 v[104:107], v[170:173], v[178:181], 0
	v_mfma_f32_16x16x32_bf16 v[92:95], v[162:165], v[192:195], 0
	v_mfma_f32_16x16x32_bf16 v[88:91], v[170:173], v[192:195], 0
	v_mfma_f32_16x16x32_bf16 v[76:79], v[162:165], v[200:203], 0
	v_mfma_f32_16x16x32_bf16 v[72:75], v[170:173], v[200:203], 0
	v_mfma_f32_16x16x32_bf16 v[68:71], v[162:165], v[208:211], 0
	v_mfma_f32_16x16x32_bf16 v[64:67], v[170:173], v[208:211], 0
	v_mfma_f32_16x16x32_bf16 v[108:111], v[166:169], v[188:191], v[108:111]
	v_mfma_f32_16x16x32_bf16 v[104:107], v[174:177], v[188:191], v[104:107]
	v_mfma_f32_16x16x32_bf16 v[92:95], v[166:169], v[196:199], v[92:95]
	v_mfma_f32_16x16x32_bf16 v[88:91], v[174:177], v[196:199], v[88:91]
	v_mfma_f32_16x16x32_bf16 v[76:79], v[166:169], v[204:207], v[76:79]
	v_mfma_f32_16x16x32_bf16 v[72:75], v[174:177], v[204:207], v[72:75]
	v_mfma_f32_16x16x32_bf16 v[68:71], v[166:169], v[212:215], v[68:71]
	v_mfma_f32_16x16x32_bf16 v[64:67], v[174:177], v[212:215], v[64:67]
	s_setprio 0
	s_add_i32 s82, s54, s38
	v_lshl_add_u64 v[182:183], s[14:15], 0, v[132:133]
	s_mov_b32 m0, s82
	s_barrier
	ds_read_b128 v[178:181], v143 offset:16384
	ds_read_b128 v[188:191], v143 offset:17408
	ds_read_b128 v[192:195], v143 offset:18432
	ds_read_b128 v[196:199], v143 offset:19456
	ds_read_b128 v[200:203], v143 offset:20480
	ds_read_b128 v[204:207], v143 offset:21504
	ds_read_b128 v[208:211], v143 offset:22528
	ds_read_b128 v[212:215], v143 offset:23552
	global_load_lds_dwordx4 v[182:183], off
	s_add_i32 m0, s82, 0x2000
	s_add_u32 s82, s14, 0x100000
	v_lshl_add_u64 v[184:185], s[14:15], 0, v[128:129]
	s_addc_u32 s83, s15, 0
	s_add_i32 s84, s55, s38
	global_load_lds_dwordx4 v[184:185], off
	v_lshl_add_u64 v[186:187], s[82:83], 0, v[132:133]
	s_mov_b32 m0, s84
	v_lshl_add_u64 v[216:217], s[36:37], 0, v[130:131]
	global_load_lds_dwordx4 v[186:187], off
	v_lshl_add_u64 v[186:187], s[82:83], 0, v[128:129]
	s_add_i32 m0, s84, 0x2000
	s_nop 0
	global_load_lds_dwordx4 v[186:187], off
	v_lshl_add_u64 v[186:187], s[36:37], 0, v[134:135]
	s_mov_b32 m0, s43
	s_nop 0
	global_load_lds_dwordx4 v[186:187], off
	s_mov_b32 m0, s44
	s_nop 0
	global_load_lds_dwordx4 v[216:217], off
	s_waitcnt vmcnt(8)
	s_waitcnt lgkmcnt(0)
	s_barrier
; #define G_STAGE(bufoff, gbase, voff) do { _Pragma("unroll") for (int _i = 0; _i < 2; ++_i) \
;         __builtin_amdgcn_global_load_lds((const unsigned*)((const char*)(gbase) + voff[_i]), (LAS unsigned*)(lds + (bufoff) + ldsw + _i * 8192), 16, 0, 0); } while (0)
; #define G_LDA(dst, b, h) do { _Pragma("unroll") for (int m = 0; m < 4; ++m) _Pragma("unroll") for (int k = 0; k < 2; ++k) dst[m][k] = *(const LAS bf16x8*)(lds + G_SA(b, h) + aoff + m * 2048 + k * 1024); } while (0)
; #define G_LDB(dst, b, h) do { _Pragma("unroll") for (int n = 0; n < 2; ++n) _Pragma("unroll") for (int k = 0; k < 2; ++k) dst[n][k] = *(const LAS bf16x8*)(lds + G_SB(b, h) + boff + n * 2048 + k * 1024); } while (0)
; #define G_MMA(ai, bj, At_, Bt_) do { __builtin_amdgcn_s_setprio(1); _Pragma("unroll") for (int m = 0; m < 4; ++m) _Pragma("unroll") for (int n = 0; n < 2; ++n) _Pragma("unroll") for (int k = 0; k < 2; ++k) \
;         acc[ai][bj][m][n] = __builtin_amdgcn_mfma_f32_16x16x32_bf16(Bt_[n][k], At_[m][k], acc[ai][bj][m][n], 0, 0, 0); __builtin_amdgcn_s_setprio(0); } while (0)
; #define WAIT_V(n) asm volatile("s_waitcnt vmcnt(" #n ")" ::: "memory")
; #define WAIT_L(n) asm volatile("s_waitcnt lgkmcnt(" #n ")" ::: "memory")
; #define BAR __builtin_amdgcn_s_barrier()
; #define SCHED __builtin_amdgcn_sched_barrier(0)
; template <class Get, class Epi>
; DI void gemm_loop(int ntiles, int ld, char* shm, const Get& get, const Epi& epi) {
;     ...
;             WAIT_V(8); WAIT_L(0); BAR; G_MMA(1, 0, At, B0); G_MMA(1, 1, At, B1); BAR; SCHED;
;             G_LDB(B0, 1, 0); G_LDB(B1, 1, 1); SCHED; G_LDA(At, 1, 0); G_STAGE(G_SA(0, 1), a2 + hstep, voffA);
;             WAIT_V(8); WAIT_L(0); BAR; G_MMA(0, 0, At, B0); G_MMA(0, 1, At, B1); BAR; SCHED;
;             G_LDA(At, 1, 1); G_STAGE(G_SB(1, 0), b3, voffB); G_STAGE(G_SB(1, 1), b3 + hstep, voffB); G_STAGE(G_SA(1, 0), a3, voffA);
	s_setprio 1
	s_waitcnt lgkmcnt(0)
	v_mfma_f32_16x16x32_bf16 v[60:63], v[146:149], v[178:181], 0
	v_mfma_f32_16x16x32_bf16 v[56:59], v[154:157], v[178:181], 0
	v_mfma_f32_16x16x32_bf16 v[52:55], v[146:149], v[192:195], 0
	v_mfma_f32_16x16x32_bf16 v[48:51], v[154:157], v[192:195], 0
	v_mfma_f32_16x16x32_bf16 v[36:39], v[146:149], v[200:203], 0
	v_mfma_f32_16x16x32_bf16 v[32:35], v[154:157], v[200:203], 0
	v_mfma_f32_16x16x32_bf16 v[20:23], v[146:149], v[208:211], 0
	v_mfma_f32_16x16x32_bf16 v[16:19], v[154:157], v[208:211], 0
	v_mfma_f32_16x16x32_bf16 v[60:63], v[150:153], v[188:191], v[60:63]
	v_mfma_f32_16x16x32_bf16 v[56:59], v[158:161], v[188:191], v[56:59]
	v_mfma_f32_16x16x32_bf16 v[52:55], v[150:153], v[196:199], v[52:55]
	v_mfma_f32_16x16x32_bf16 v[48:51], v[158:161], v[196:199], v[48:51]
	v_mfma_f32_16x16x32_bf16 v[36:39], v[150:153], v[204:207], v[36:39]
	v_mfma_f32_16x16x32_bf16 v[32:35], v[158:161], v[204:207], v[32:35]
	v_mfma_f32_16x16x32_bf16 v[20:23], v[150:153], v[212:215], v[20:23]
	v_mfma_f32_16x16x32_bf16 v[16:19], v[158:161], v[212:215], v[16:19]
	s_setprio 0
	s_setprio 1
	v_mfma_f32_16x16x32_bf16 v[44:47], v[162:165], v[178:181], 0
	v_mfma_f32_16x16x32_bf16 v[40:43], v[170:173], v[178:181], 0
	v_mfma_f32_16x16x32_bf16 v[28:31], v[162:165], v[192:195], 0
	v_mfma_f32_16x16x32_bf16 v[24:27], v[170:173], v[192:195], 0
	v_mfma_f32_16x16x32_bf16 v[12:15], v[162:165], v[200:203], 0
	v_mfma_f32_16x16x32_bf16 v[8:11], v[170:173], v[200:203], 0
	v_mfma_f32_16x16x32_bf16 v[4:7], v[162:165], v[208:211], 0
	v_mfma_f32_16x16x32_bf16 v[0:3], v[170:173], v[208:211], 0
	v_mfma_f32_16x16x32_bf16 v[44:47], v[166:169], v[188:191], v[44:47]
	v_mfma_f32_16x16x32_bf16 v[40:43], v[174:177], v[188:191], v[40:43]
	v_mfma_f32_16x16x32_bf16 v[28:31], v[166:169], v[196:199], v[28:31]
	v_mfma_f32_16x16x32_bf16 v[24:27], v[174:177], v[196:199], v[24:27]
	v_mfma_f32_16x16x32_bf16 v[12:15], v[166:169], v[204:207], v[12:15]
	v_mfma_f32_16x16x32_bf16 v[8:11], v[174:177], v[204:207], v[8:11]
	v_mfma_f32_16x16x32_bf16 v[4:7], v[166:169], v[212:215], v[4:7]
	v_mfma_f32_16x16x32_bf16 v[0:3], v[174:177], v[212:215], v[0:3]
	s_setprio 0
	s_add_i32 s82, 0, 0x18000
	v_add_u32_e32 v145, s82, v140
	s_add_i32 s83, 0, 0x1c000
	s_barrier
	ds_read_b128 v[146:149], v145
	ds_read_b128 v[150:153], v145 offset:1024
	ds_read_b128 v[154:157], v145 offset:2048
	ds_read_b128 v[158:161], v145 offset:3072
	v_add_u32_e32 v145, s83, v140
	ds_read_b128 v[162:165], v145
	ds_read_b128 v[166:169], v145 offset:1024
	ds_read_b128 v[170:173], v145 offset:2048
	ds_read_b128 v[174:177], v145 offset:3072
	s_add_u32 s36, s36, 0x100000
	s_addc_u32 s37, s37, 0
	s_mov_b32 m0, s45
	v_lshl_add_u64 v[218:219], s[36:37], 0, v[134:135]
	ds_read_b128 v[178:181], v143 offset:32768
	ds_read_b128 v[188:191], v143 offset:33792
	ds_read_b128 v[192:195], v143 offset:34816
	ds_read_b128 v[196:199], v143 offset:35840
	ds_read_b128 v[200:203], v143 offset:36864
	ds_read_b128 v[204:207], v143 offset:37888
	ds_read_b128 v[208:211], v143 offset:38912
	ds_read_b128 v[212:215], v143 offset:39936
	global_load_lds_dwordx4 v[218:219], off
	v_lshl_add_u64 v[218:219], s[36:37], 0, v[130:131]
	s_mov_b32 m0, s46
	s_nop 0
	global_load_lds_dwordx4 v[218:219], off
	s_waitcnt vmcnt(8)
	s_waitcnt lgkmcnt(0)
	s_barrier
	s_setprio 1
	s_waitcnt lgkmcnt(0)
	v_mfma_f32_16x16x32_bf16 v[124:127], v[146:149], v[178:181], v[124:127]
	v_mfma_f32_16x16x32_bf16 v[120:123], v[154:157], v[178:181], v[120:123]
	v_mfma_f32_16x16x32_bf16 v[116:119], v[146:149], v[192:195], v[116:119]
	v_mfma_f32_16x16x32_bf16 v[112:115], v[154:157], v[192:195], v[112:115]
	v_mfma_f32_16x16x32_bf16 v[100:103], v[146:149], v[200:203], v[100:103]
	v_mfma_f32_16x16x32_bf16 v[96:99], v[154:157], v[200:203], v[96:99]
	v_mfma_f32_16x16x32_bf16 v[84:87], v[146:149], v[208:211], v[84:87]
	v_mfma_f32_16x16x32_bf16 v[80:83], v[154:157], v[208:211], v[80:83]
	v_mfma_f32_16x16x32_bf16 v[124:127], v[150:153], v[188:191], v[124:127]
	v_mfma_f32_16x16x32_bf16 v[120:123], v[158:161], v[188:191], v[120:123]
	v_mfma_f32_16x16x32_bf16 v[116:119], v[150:153], v[196:199], v[116:119]
	v_mfma_f32_16x16x32_bf16 v[112:115], v[158:161], v[196:199], v[112:115]
	v_mfma_f32_16x16x32_bf16 v[100:103], v[150:153], v[204:207], v[100:103]
	v_mfma_f32_16x16x32_bf16 v[96:99], v[158:161], v[204:207], v[96:99]
	v_mfma_f32_16x16x32_bf16 v[84:87], v[150:153], v[212:215], v[84:87]
	v_mfma_f32_16x16x32_bf16 v[80:83], v[158:161], v[212:215], v[80:83]
	s_setprio 0
	s_setprio 1
	v_mfma_f32_16x16x32_bf16 v[108:111], v[162:165], v[178:181], v[108:111]
	v_mfma_f32_16x16x32_bf16 v[104:107], v[170:173], v[178:181], v[104:107]
	v_mfma_f32_16x16x32_bf16 v[92:95], v[162:165], v[192:195], v[92:95]
	v_mfma_f32_16x16x32_bf16 v[88:91], v[170:173], v[192:195], v[88:91]
	v_mfma_f32_16x16x32_bf16 v[76:79], v[162:165], v[200:203], v[76:79]
	v_mfma_f32_16x16x32_bf16 v[72:75], v[170:173], v[200:203], v[72:75]
	v_mfma_f32_16x16x32_bf16 v[68:71], v[162:165], v[208:211], v[68:71]
	v_mfma_f32_16x16x32_bf16 v[64:67], v[170:173], v[208:211], v[64:67]
	v_mfma_f32_16x16x32_bf16 v[108:111], v[166:169], v[188:191], v[108:111]
	v_mfma_f32_16x16x32_bf16 v[104:107], v[174:177], v[188:191], v[104:107]
	v_mfma_f32_16x16x32_bf16 v[92:95], v[166:169], v[196:199], v[92:95]
	v_mfma_f32_16x16x32_bf16 v[88:91], v[174:177], v[196:199], v[88:91]
	v_mfma_f32_16x16x32_bf16 v[76:79], v[166:169], v[204:207], v[76:79]
	v_mfma_f32_16x16x32_bf16 v[72:75], v[174:177], v[204:207], v[72:75]
	v_mfma_f32_16x16x32_bf16 v[68:71], v[166:169], v[212:215], v[68:71]
	v_mfma_f32_16x16x32_bf16 v[64:67], v[174:177], v[212:215], v[64:67]
	s_setprio 0
	s_add_i32 s36, s82, s38
	v_lshl_add_u64 v[182:183], v[182:183], 0, s[8:9]
	s_mov_b32 m0, s36
	s_barrier
; #define G_STAGE(bufoff, gbase, voff) do { _Pragma("unroll") for (int _i = 0; _i < 2; ++_i) \
;         __builtin_amdgcn_global_load_lds((const unsigned*)((const char*)(gbase) + voff[_i]), (LAS unsigned*)(lds + (bufoff) + ldsw + _i * 8192), 16, 0, 0); } while (0)
; #define G_LDA(dst, b, h) do { _Pragma("unroll") for (int m = 0; m < 4; ++m) _Pragma("unroll") for (int k = 0; k < 2; ++k) dst[m][k] = *(const LAS bf16x8*)(lds + G_SA(b, h) + aoff + m * 2048 + k * 1024); } while (0)
; #define G_LDB(dst, b, h) do { _Pragma("unroll") for (int n = 0; n < 2; ++n) _Pragma("unroll") for (int k = 0; k < 2; ++k) dst[n][k] = *(const LAS bf16x8*)(lds + G_SB(b, h) + boff + n * 2048 + k * 1024); } while (0)
; #define G_MMA(ai, bj, At_, Bt_) do { __builtin_amdgcn_s_setprio(1); _Pragma("unroll") for (int m = 0; m < 4; ++m) _Pragma("unroll") for (int n = 0; n < 2; ++n) _Pragma("unroll") for (int k = 0; k < 2; ++k) \
;         acc[ai][bj][m][n] = __builtin_amdgcn_mfma_f32_16x16x32_bf16(Bt_[n][k], At_[m][k], acc[ai][bj][m][n], 0, 0, 0); __builtin_amdgcn_s_setprio(0); } while (0)
; #define WAIT_V(n) asm volatile("s_waitcnt vmcnt(" #n ")" ::: "memory")
; #define WAIT_L(n) asm volatile("s_waitcnt lgkmcnt(" #n ")" ::: "memory")
; #define BAR __builtin_amdgcn_s_barrier()
; #define SCHED __builtin_amdgcn_sched_barrier(0)
; template <class Get, class Epi>
; DI void gemm_loop(int ntiles, int ld, char* shm, const Get& get, const Epi& epi) {
;     ...
;             G_LDB(B0, 0, 0); G_LDB(B1, 0, 1); SCHED; G_LDA(At, 0, 0); G_STAGE(G_SA(1, 1), a1 + hstep, voffA);
;             WAIT_V(8); WAIT_L(0); BAR; G_MMA(0, 0, At, B0); G_MMA(0, 1, At, B1); BAR; SCHED;
;     ...
;             G_LDA(At, 1, 1); G_STAGE(G_SB(1, 0), b3, voffB); G_STAGE(G_SB(1, 1), b3 + hstep, voffB); G_STAGE(G_SA(1, 0), a3, voffA);
;             WAIT_V(8); WAIT_L(0); BAR; G_MMA(1, 0, At, B0); G_MMA(1, 1, At, B1); BAR; SCHED;
;         }
	ds_read_b128 v[178:181], v143 offset:49152
	ds_read_b128 v[188:191], v143 offset:50176
	ds_read_b128 v[192:195], v143 offset:51200
	ds_read_b128 v[196:199], v143 offset:52224
	ds_read_b128 v[200:203], v143 offset:53248
	ds_read_b128 v[204:207], v143 offset:54272
	ds_read_b128 v[208:211], v143 offset:55296
	ds_read_b128 v[212:215], v143 offset:56320
	global_load_lds_dwordx4 v[182:183], off
	s_add_i32 m0, s36, 0x2000
	s_add_u32 s14, s14, 0x100080
	v_lshl_add_u64 v[182:183], v[184:185], 0, s[8:9]
	s_addc_u32 s15, s15, 0
	s_add_i32 s36, s83, s38
	global_load_lds_dwordx4 v[182:183], off
	v_lshl_add_u64 v[182:183], s[14:15], 0, v[132:133]
	s_mov_b32 m0, s36
	s_nop 0
	global_load_lds_dwordx4 v[182:183], off
	v_lshl_add_u64 v[182:183], s[14:15], 0, v[128:129]
	s_add_i32 m0, s36, 0x2000
	s_nop 0
	global_load_lds_dwordx4 v[182:183], off
	v_lshl_add_u64 v[182:183], v[186:187], 0, s[8:9]
	s_mov_b32 m0, s47
	s_nop 0
	global_load_lds_dwordx4 v[182:183], off
	v_lshl_add_u64 v[182:183], v[216:217], 0, s[8:9]
	s_mov_b32 m0, s50
	s_nop 0
	global_load_lds_dwordx4 v[182:183], off
	s_waitcnt vmcnt(8)
	s_waitcnt lgkmcnt(0)
	s_barrier
	s_setprio 1
	s_waitcnt lgkmcnt(0)
	v_mfma_f32_16x16x32_bf16 v[60:63], v[146:149], v[178:181], v[60:63]
	v_mfma_f32_16x16x32_bf16 v[56:59], v[154:157], v[178:181], v[56:59]
	v_mfma_f32_16x16x32_bf16 v[52:55], v[146:149], v[192:195], v[52:55]
	v_mfma_f32_16x16x32_bf16 v[48:51], v[154:157], v[192:195], v[48:51]
	v_mfma_f32_16x16x32_bf16 v[36:39], v[146:149], v[200:203], v[36:39]
	v_mfma_f32_16x16x32_bf16 v[32:35], v[154:157], v[200:203], v[32:35]
	v_mfma_f32_16x16x32_bf16 v[20:23], v[146:149], v[208:211], v[20:23]
	v_mfma_f32_16x16x32_bf16 v[16:19], v[154:157], v[208:211], v[16:19]
	v_mfma_f32_16x16x32_bf16 v[60:63], v[150:153], v[188:191], v[60:63]
	v_mfma_f32_16x16x32_bf16 v[56:59], v[158:161], v[188:191], v[56:59]
	v_mfma_f32_16x16x32_bf16 v[52:55], v[150:153], v[196:199], v[52:55]
	v_mfma_f32_16x16x32_bf16 v[48:51], v[158:161], v[196:199], v[48:51]
	v_mfma_f32_16x16x32_bf16 v[36:39], v[150:153], v[204:207], v[36:39]
	v_mfma_f32_16x16x32_bf16 v[32:35], v[158:161], v[204:207], v[32:35]
	v_mfma_f32_16x16x32_bf16 v[20:23], v[150:153], v[212:215], v[20:23]
	v_mfma_f32_16x16x32_bf16 v[16:19], v[158:161], v[212:215], v[16:19]
	s_setprio 0
	s_setprio 1
	v_mfma_f32_16x16x32_bf16 v[44:47], v[162:165], v[178:181], v[44:47]
	v_mfma_f32_16x16x32_bf16 v[40:43], v[170:173], v[178:181], v[40:43]
	v_mfma_f32_16x16x32_bf16 v[28:31], v[162:165], v[192:195], v[28:31]
	v_mfma_f32_16x16x32_bf16 v[24:27], v[170:173], v[192:195], v[24:27]
	v_mfma_f32_16x16x32_bf16 v[12:15], v[162:165], v[200:203], v[12:15]
	v_mfma_f32_16x16x32_bf16 v[8:11], v[170:173], v[200:203], v[8:11]
	v_mfma_f32_16x16x32_bf16 v[4:7], v[162:165], v[208:211], v[4:7]
	v_mfma_f32_16x16x32_bf16 v[0:3], v[170:173], v[208:211], v[0:3]
	v_mfma_f32_16x16x32_bf16 v[44:47], v[166:169], v[188:191], v[44:47]
	v_mfma_f32_16x16x32_bf16 v[40:43], v[174:177], v[188:191], v[40:43]
	v_mfma_f32_16x16x32_bf16 v[28:31], v[166:169], v[196:199], v[28:31]
	v_mfma_f32_16x16x32_bf16 v[24:27], v[174:177], v[196:199], v[24:27]
	v_mfma_f32_16x16x32_bf16 v[12:15], v[166:169], v[204:207], v[12:15]
	v_mfma_f32_16x16x32_bf16 v[8:11], v[174:177], v[204:207], v[8:11]
	v_mfma_f32_16x16x32_bf16 v[4:7], v[166:169], v[212:215], v[4:7]
	v_mfma_f32_16x16x32_bf16 v[0:3], v[174:177], v[212:215], v[0:3]
	s_setprio 0
	s_add_i32 s81, s81, 2
	s_add_u32 s34, s34, 0x100
	s_addc_u32 s35, s35, 0
	s_add_u32 s79, s79, 0x100
	s_addc_u32 s80, s80, 0
	s_cmp_gt_u32 s81, 61
	s_barrier
	s_cbranch_scc0 .LBB0_431
	s_branch .Lpost_431
.LBB0_431:
	ds_read_b128 v[146:149], v141
	ds_read_b128 v[150:153], v141 offset:1024
	ds_read_b128 v[154:157], v141 offset:2048
	ds_read_b128 v[158:161], v141 offset:3072
	ds_read_b128 v[162:165], v142
	ds_read_b128 v[166:169], v142 offset:1024
	ds_read_b128 v[170:173], v142 offset:2048
	ds_read_b128 v[174:177], v142 offset:3072
	s_add_u32 s14, s34, 0xfff00080
	s_addc_u32 s15, s35, -1
	s_cmp_eq_u32 s81, 60
	s_cselect_b32 s37, s74, s15
	s_cselect_b32 s36, s75, s14
	s_cselect_b32 s15, s76, s80
	s_cselect_b32 s14, s78, s79
	s_mov_b32 m0, s56
	v_lshl_add_u64 v[182:183], s[34:35], 0, v[136:137]
	ds_read_b128 v[178:181], v143
	ds_read_b128 v[188:191], v143 offset:1024
	ds_read_b128 v[192:195], v143 offset:2048
	ds_read_b128 v[196:199], v143 offset:3072
	ds_read_b128 v[200:203], v143 offset:4096
	ds_read_b128 v[204:207], v143 offset:5120
	ds_read_b128 v[208:211], v143 offset:6144
	ds_read_b128 v[212:215], v143 offset:7168
	global_load_lds_dwordx4 v[182:183], off
	v_lshl_add_u64 v[182:183], s[34:35], 0, v[138:139]
	s_add_i32 m0, s43, 0xe000
	s_nop 0
	global_load_lds_dwordx4 v[182:183], off
	s_waitcnt vmcnt(8)
	s_waitcnt lgkmcnt(0)
	s_barrier
; #define G_STAGE(bufoff, gbase, voff) do { _Pragma("unroll") for (int _i = 0; _i < 2; ++_i) \
;         __builtin_amdgcn_global_load_lds((const unsigned*)((const char*)(gbase) + voff[_i]), (LAS unsigned*)(lds + (bufoff) + ldsw + _i * 8192), 16, 0, 0); } while (0)
; #define G_LDA(dst, b, h) do { _Pragma("unroll") for (int m = 0; m < 4; ++m) _Pragma("unroll") for (int k = 0; k < 2; ++k) dst[m][k] = *(const LAS bf16x8*)(lds + G_SA(b, h) + aoff + m * 2048 + k * 1024); } while (0)
; #define G_LDB(dst, b, h) do { _Pragma("unroll") for (int n = 0; n < 2; ++n) _Pragma("unroll") for (int k = 0; k < 2; ++k) dst[n][k] = *(const LAS bf16x8*)(lds + G_SB(b, h) + boff + n * 2048 + k * 1024); } while (0)
; #define G_MMA(ai, bj, At_, Bt_) do { __builtin_amdgcn_s_setprio(1); _Pragma("unroll") for (int m = 0; m < 4; ++m) _Pragma("unroll") for (int n = 0; n < 2; ++n) _Pragma("unroll") for (int k = 0; k < 2; ++k) \
;         acc[ai][bj][m][n] = __builtin_amdgcn_mfma_f32_16x16x32_bf16(Bt_[n][k], At_[m][k], acc[ai][bj][m][n], 0, 0, 0); __builtin_amdgcn_s_setprio(0); } while (0)
; #define WAIT_V(n) asm volatile("s_waitcnt vmcnt(" #n ")" ::: "memory")
; #define WAIT_L(n) asm volatile("s_waitcnt lgkmcnt(" #n ")" ::: "memory")
; #define BAR __builtin_amdgcn_s_barrier()
; #define SCHED __builtin_amdgcn_sched_barrier(0)
; template <class Get, class Epi>
; DI void gemm_loop(int ntiles, int ld, char* shm, const Get& get, const Epi& epi) {
;     ...
;             WAIT_V(8); WAIT_L(0); BAR; G_MMA(0, 0, At, B0); G_MMA(0, 1, At, B1); BAR; SCHED;
;             G_LDA(At, 0, 1); G_STAGE(G_SB(0, 0), b2, voffB); G_STAGE(G_SB(0, 1), b2 + hstep, voffB); G_STAGE(G_SA(0, 0), a2, voffA);
;             WAIT_V(8); WAIT_L(0); BAR; G_MMA(1, 0, At, B0); G_MMA(1, 1, At, B1); BAR; SCHED;
;             G_LDB(B0, 1, 0); G_LDB(B1, 1, 1); SCHED; G_LDA(At, 1, 0); G_STAGE(G_SA(0, 1), a2 + hstep, voffA);
	s_setprio 1
	s_waitcnt lgkmcnt(0)
	v_mfma_f32_16x16x32_bf16 v[124:127], v[146:149], v[178:181], v[124:127]
	v_mfma_f32_16x16x32_bf16 v[120:123], v[154:157], v[178:181], v[120:123]
	v_mfma_f32_16x16x32_bf16 v[116:119], v[146:149], v[192:195], v[116:119]
	v_mfma_f32_16x16x32_bf16 v[112:115], v[154:157], v[192:195], v[112:115]
	v_mfma_f32_16x16x32_bf16 v[100:103], v[146:149], v[200:203], v[100:103]
	v_mfma_f32_16x16x32_bf16 v[96:99], v[154:157], v[200:203], v[96:99]
	v_mfma_f32_16x16x32_bf16 v[84:87], v[146:149], v[208:211], v[84:87]
	v_mfma_f32_16x16x32_bf16 v[80:83], v[154:157], v[208:211], v[80:83]
	v_mfma_f32_16x16x32_bf16 v[124:127], v[150:153], v[188:191], v[124:127]
	v_mfma_f32_16x16x32_bf16 v[120:123], v[158:161], v[188:191], v[120:123]
	v_mfma_f32_16x16x32_bf16 v[116:119], v[150:153], v[196:199], v[116:119]
	v_mfma_f32_16x16x32_bf16 v[112:115], v[158:161], v[196:199], v[112:115]
	v_mfma_f32_16x16x32_bf16 v[100:103], v[150:153], v[204:207], v[100:103]
	v_mfma_f32_16x16x32_bf16 v[96:99], v[158:161], v[204:207], v[96:99]
	v_mfma_f32_16x16x32_bf16 v[84:87], v[150:153], v[212:215], v[84:87]
	v_mfma_f32_16x16x32_bf16 v[80:83], v[158:161], v[212:215], v[80:83]
	s_setprio 0
	s_setprio 1
	v_mfma_f32_16x16x32_bf16 v[108:111], v[162:165], v[178:181], v[108:111]
	v_mfma_f32_16x16x32_bf16 v[104:107], v[170:173], v[178:181], v[104:107]
	v_mfma_f32_16x16x32_bf16 v[92:95], v[162:165], v[192:195], v[92:95]
	v_mfma_f32_16x16x32_bf16 v[88:91], v[170:173], v[192:195], v[88:91]
	v_mfma_f32_16x16x32_bf16 v[76:79], v[162:165], v[200:203], v[76:79]
	v_mfma_f32_16x16x32_bf16 v[72:75], v[170:173], v[200:203], v[72:75]
	v_mfma_f32_16x16x32_bf16 v[68:71], v[162:165], v[208:211], v[68:71]
	v_mfma_f32_16x16x32_bf16 v[64:67], v[170:173], v[208:211], v[64:67]
	v_mfma_f32_16x16x32_bf16 v[108:111], v[166:169], v[188:191], v[108:111]
	v_mfma_f32_16x16x32_bf16 v[104:107], v[174:177], v[188:191], v[104:107]
	v_mfma_f32_16x16x32_bf16 v[92:95], v[166:169], v[196:199], v[92:95]
	v_mfma_f32_16x16x32_bf16 v[88:91], v[174:177], v[196:199], v[88:91]
	v_mfma_f32_16x16x32_bf16 v[76:79], v[166:169], v[204:207], v[76:79]
	v_mfma_f32_16x16x32_bf16 v[72:75], v[174:177], v[204:207], v[72:75]
	v_mfma_f32_16x16x32_bf16 v[68:71], v[166:169], v[212:215], v[68:71]
	v_mfma_f32_16x16x32_bf16 v[64:67], v[174:177], v[212:215], v[64:67]
	s_setprio 0
	s_add_i32 s82, s54, s38
	v_lshl_add_u64 v[182:183], s[14:15], 0, v[132:133]
	s_mov_b32 m0, s82
	s_barrier
	ds_read_b128 v[178:181], v143 offset:16384
	ds_read_b128 v[188:191], v143 offset:17408
	ds_read_b128 v[192:195], v143 offset:18432
	ds_read_b128 v[196:199], v143 offset:19456
	ds_read_b128 v[200:203], v143 offset:20480
	ds_read_b128 v[204:207], v143 offset:21504
	ds_read_b128 v[208:211], v143 offset:22528
	ds_read_b128 v[212:215], v143 offset:23552
	global_load_lds_dwordx4 v[182:183], off
	s_add_i32 m0, s82, 0x2000
	s_add_u32 s82, s14, 0x100000
	v_lshl_add_u64 v[184:185], s[14:15], 0, v[128:129]
	s_addc_u32 s83, s15, 0
	s_add_i32 s84, s55, s38
	global_load_lds_dwordx4 v[184:185], off
	v_lshl_add_u64 v[186:187], s[82:83], 0, v[132:133]
	s_mov_b32 m0, s84
	v_lshl_add_u64 v[216:217], s[36:37], 0, v[130:131]
	global_load_lds_dwordx4 v[186:187], off
	v_lshl_add_u64 v[186:187], s[82:83], 0, v[128:129]
	s_add_i32 m0, s84, 0x2000
	s_nop 0
	global_load_lds_dwordx4 v[186:187], off
	v_lshl_add_u64 v[186:187], s[36:37], 0, v[134:135]
	s_mov_b32 m0, s43
	s_nop 0
	global_load_lds_dwordx4 v[186:187], off
	s_mov_b32 m0, s44
	s_nop 0
	global_load_lds_dwordx4 v[216:217], off
	s_waitcnt vmcnt(8)
	s_waitcnt lgkmcnt(0)
	s_barrier
	s_setprio 1
	s_waitcnt lgkmcnt(0)
	v_mfma_f32_16x16x32_bf16 v[60:63], v[146:149], v[178:181], v[60:63]
	v_mfma_f32_16x16x32_bf16 v[56:59], v[154:157], v[178:181], v[56:59]
	v_mfma_f32_16x16x32_bf16 v[52:55], v[146:149], v[192:195], v[52:55]
	v_mfma_f32_16x16x32_bf16 v[48:51], v[154:157], v[192:195], v[48:51]
	v_mfma_f32_16x16x32_bf16 v[36:39], v[146:149], v[200:203], v[36:39]
	v_mfma_f32_16x16x32_bf16 v[32:35], v[154:157], v[200:203], v[32:35]
	v_mfma_f32_16x16x32_bf16 v[20:23], v[146:149], v[208:211], v[20:23]
	v_mfma_f32_16x16x32_bf16 v[16:19], v[154:157], v[208:211], v[16:19]
	v_mfma_f32_16x16x32_bf16 v[60:63], v[150:153], v[188:191], v[60:63]
	v_mfma_f32_16x16x32_bf16 v[56:59], v[158:161], v[188:191], v[56:59]
	v_mfma_f32_16x16x32_bf16 v[52:55], v[150:153], v[196:199], v[52:55]
	v_mfma_f32_16x16x32_bf16 v[48:51], v[158:161], v[196:199], v[48:51]
	v_mfma_f32_16x16x32_bf16 v[36:39], v[150:153], v[204:207], v[36:39]
	v_mfma_f32_16x16x32_bf16 v[32:35], v[158:161], v[204:207], v[32:35]
	v_mfma_f32_16x16x32_bf16 v[20:23], v[150:153], v[212:215], v[20:23]
	v_mfma_f32_16x16x32_bf16 v[16:19], v[158:161], v[212:215], v[16:19]
	s_setprio 0
	s_setprio 1
	v_mfma_f32_16x16x32_bf16 v[44:47], v[162:165], v[178:181], v[44:47]
	v_mfma_f32_16x16x32_bf16 v[40:43], v[170:173], v[178:181], v[40:43]
	v_mfma_f32_16x16x32_bf16 v[28:31], v[162:165], v[192:195], v[28:31]
	v_mfma_f32_16x16x32_bf16 v[24:27], v[170:173], v[192:195], v[24:27]
	v_mfma_f32_16x16x32_bf16 v[12:15], v[162:165], v[200:203], v[12:15]
	v_mfma_f32_16x16x32_bf16 v[8:11], v[170:173], v[200:203], v[8:11]
	v_mfma_f32_16x16x32_bf16 v[4:7], v[162:165], v[208:211], v[4:7]
	v_mfma_f32_16x16x32_bf16 v[0:3], v[170:173], v[208:211], v[0:3]
	v_mfma_f32_16x16x32_bf16 v[44:47], v[166:169], v[188:191], v[44:47]
	v_mfma_f32_16x16x32_bf16 v[40:43], v[174:177], v[188:191], v[40:43]
	v_mfma_f32_16x16x32_bf16 v[28:31], v[166:169], v[196:199], v[28:31]
	v_mfma_f32_16x16x32_bf16 v[24:27], v[174:177], v[196:199], v[24:27]
	v_mfma_f32_16x16x32_bf16 v[12:15], v[166:169], v[204:207], v[12:15]
	v_mfma_f32_16x16x32_bf16 v[8:11], v[174:177], v[204:207], v[8:11]
	v_mfma_f32_16x16x32_bf16 v[4:7], v[166:169], v[212:215], v[4:7]
	v_mfma_f32_16x16x32_bf16 v[0:3], v[174:177], v[212:215], v[0:3]
	s_setprio 0
	s_add_i32 s82, 0, 0x18000
	v_add_u32_e32 v145, s82, v140
	s_add_i32 s83, 0, 0x1c000
	s_barrier
; #define G_STAGE(bufoff, gbase, voff) do { _Pragma("unroll") for (int _i = 0; _i < 2; ++_i) \
;         __builtin_amdgcn_global_load_lds((const unsigned*)((const char*)(gbase) + voff[_i]), (LAS unsigned*)(lds + (bufoff) + ldsw + _i * 8192), 16, 0, 0); } while (0)
; #define G_LDA(dst, b, h) do { _Pragma("unroll") for (int m = 0; m < 4; ++m) _Pragma("unroll") for (int k = 0; k < 2; ++k) dst[m][k] = *(const LAS bf16x8*)(lds + G_SA(b, h) + aoff + m * 2048 + k * 1024); } while (0)
; #define G_LDB(dst, b, h) do { _Pragma("unroll") for (int n = 0; n < 2; ++n) _Pragma("unroll") for (int k = 0; k < 2; ++k) dst[n][k] = *(const LAS bf16x8*)(lds + G_SB(b, h) + boff + n * 2048 + k * 1024); } while (0)
; #define G_MMA(ai, bj, At_, Bt_) do { __builtin_amdgcn_s_setprio(1); _Pragma("unroll") for (int m = 0; m < 4; ++m) _Pragma("unroll") for (int n = 0; n < 2; ++n) _Pragma("unroll") for (int k = 0; k < 2; ++k) \
;         acc[ai][bj][m][n] = __builtin_amdgcn_mfma_f32_16x16x32_bf16(Bt_[n][k], At_[m][k], acc[ai][bj][m][n], 0, 0, 0); __builtin_amdgcn_s_setprio(0); } while (0)
; #define WAIT_V(n) asm volatile("s_waitcnt vmcnt(" #n ")" ::: "memory")
; #define WAIT_L(n) asm volatile("s_waitcnt lgkmcnt(" #n ")" ::: "memory")
; #define BAR __builtin_amdgcn_s_barrier()
; #define SCHED __builtin_amdgcn_sched_barrier(0)
; template <class Get, class Epi>
; DI void gemm_loop(int ntiles, int ld, char* shm, const Get& get, const Epi& epi) {
;     ...
;             G_LDB(B0, 1, 0); G_LDB(B1, 1, 1); SCHED; G_LDA(At, 1, 0); G_STAGE(G_SA(0, 1), a2 + hstep, voffA);
;             WAIT_V(8); WAIT_L(0); BAR; G_MMA(0, 0, At, B0); G_MMA(0, 1, At, B1); BAR; SCHED;
;             G_LDA(At, 1, 1); G_STAGE(G_SB(1, 0), b3, voffB); G_STAGE(G_SB(1, 1), b3 + hstep, voffB); G_STAGE(G_SA(1, 0), a3, voffA);
	ds_read_b128 v[146:149], v145
	ds_read_b128 v[150:153], v145 offset:1024
	ds_read_b128 v[154:157], v145 offset:2048
	ds_read_b128 v[158:161], v145 offset:3072
	v_add_u32_e32 v145, s83, v140
	ds_read_b128 v[162:165], v145
	ds_read_b128 v[166:169], v145 offset:1024
	ds_read_b128 v[170:173], v145 offset:2048
	ds_read_b128 v[174:177], v145 offset:3072
	s_add_u32 s36, s36, 0x100000
	s_addc_u32 s37, s37, 0
	s_mov_b32 m0, s45
	v_lshl_add_u64 v[218:219], s[36:37], 0, v[134:135]
	ds_read_b128 v[178:181], v143 offset:32768
	ds_read_b128 v[188:191], v143 offset:33792
	ds_read_b128 v[192:195], v143 offset:34816
	ds_read_b128 v[196:199], v143 offset:35840
	ds_read_b128 v[200:203], v143 offset:36864
	ds_read_b128 v[204:207], v143 offset:37888
	ds_read_b128 v[208:211], v143 offset:38912
	ds_read_b128 v[212:215], v143 offset:39936
	global_load_lds_dwordx4 v[218:219], off
	v_lshl_add_u64 v[218:219], s[36:37], 0, v[130:131]
	s_mov_b32 m0, s46
	s_nop 0
	global_load_lds_dwordx4 v[218:219], off
	s_waitcnt vmcnt(8)
	s_waitcnt lgkmcnt(0)
	s_barrier
	s_setprio 1
	s_waitcnt lgkmcnt(0)
	v_mfma_f32_16x16x32_bf16 v[124:127], v[146:149], v[178:181], v[124:127]
	v_mfma_f32_16x16x32_bf16 v[120:123], v[154:157], v[178:181], v[120:123]
	v_mfma_f32_16x16x32_bf16 v[116:119], v[146:149], v[192:195], v[116:119]
	v_mfma_f32_16x16x32_bf16 v[112:115], v[154:157], v[192:195], v[112:115]
	v_mfma_f32_16x16x32_bf16 v[100:103], v[146:149], v[200:203], v[100:103]
	v_mfma_f32_16x16x32_bf16 v[96:99], v[154:157], v[200:203], v[96:99]
	v_mfma_f32_16x16x32_bf16 v[84:87], v[146:149], v[208:211], v[84:87]
	v_mfma_f32_16x16x32_bf16 v[80:83], v[154:157], v[208:211], v[80:83]
	v_mfma_f32_16x16x32_bf16 v[124:127], v[150:153], v[188:191], v[124:127]
	v_mfma_f32_16x16x32_bf16 v[120:123], v[158:161], v[188:191], v[120:123]
	v_mfma_f32_16x16x32_bf16 v[116:119], v[150:153], v[196:199], v[116:119]
	v_mfma_f32_16x16x32_bf16 v[112:115], v[158:161], v[196:199], v[112:115]
	v_mfma_f32_16x16x32_bf16 v[100:103], v[150:153], v[204:207], v[100:103]
	v_mfma_f32_16x16x32_bf16 v[96:99], v[158:161], v[204:207], v[96:99]
	v_mfma_f32_16x16x32_bf16 v[84:87], v[150:153], v[212:215], v[84:87]
	v_mfma_f32_16x16x32_bf16 v[80:83], v[158:161], v[212:215], v[80:83]
	s_setprio 0
	s_setprio 1
	v_mfma_f32_16x16x32_bf16 v[108:111], v[162:165], v[178:181], v[108:111]
	v_mfma_f32_16x16x32_bf16 v[104:107], v[170:173], v[178:181], v[104:107]
	v_mfma_f32_16x16x32_bf16 v[92:95], v[162:165], v[192:195], v[92:95]
	v_mfma_f32_16x16x32_bf16 v[88:91], v[170:173], v[192:195], v[88:91]
	v_mfma_f32_16x16x32_bf16 v[76:79], v[162:165], v[200:203], v[76:79]
	v_mfma_f32_16x16x32_bf16 v[72:75], v[170:173], v[200:203], v[72:75]
	v_mfma_f32_16x16x32_bf16 v[68:71], v[162:165], v[208:211], v[68:71]
	v_mfma_f32_16x16x32_bf16 v[64:67], v[170:173], v[208:211], v[64:67]
	v_mfma_f32_16x16x32_bf16 v[108:111], v[166:169], v[188:191], v[108:111]
	v_mfma_f32_16x16x32_bf16 v[104:107], v[174:177], v[188:191], v[104:107]
	v_mfma_f32_16x16x32_bf16 v[92:95], v[166:169], v[196:199], v[92:95]
	v_mfma_f32_16x16x32_bf16 v[88:91], v[174:177], v[196:199], v[88:91]
	v_mfma_f32_16x16x32_bf16 v[76:79], v[166:169], v[204:207], v[76:79]
	v_mfma_f32_16x16x32_bf16 v[72:75], v[174:177], v[204:207], v[72:75]
	v_mfma_f32_16x16x32_bf16 v[68:71], v[166:169], v[212:215], v[68:71]
	v_mfma_f32_16x16x32_bf16 v[64:67], v[174:177], v[212:215], v[64:67]
	s_setprio 0
	s_add_i32 s36, s82, s38
	v_lshl_add_u64 v[182:183], v[182:183], 0, s[8:9]
	s_mov_b32 m0, s36
	s_barrier
; #define G_STAGE(bufoff, gbase, voff) do { _Pragma("unroll") for (int _i = 0; _i < 2; ++_i) \
;         __builtin_amdgcn_global_load_lds((const unsigned*)((const char*)(gbase) + voff[_i]), (LAS unsigned*)(lds + (bufoff) + ldsw + _i * 8192), 16, 0, 0); } while (0)
; #define G_LDA(dst, b, h) do { _Pragma("unroll") for (int m = 0; m < 4; ++m) _Pragma("unroll") for (int k = 0; k < 2; ++k) dst[m][k] = *(const LAS bf16x8*)(lds + G_SA(b, h) + aoff + m * 2048 + k * 1024); } while (0)
; #define G_MMA(ai, bj, At_, Bt_) do { __builtin_amdgcn_s_setprio(1); _Pragma("unroll") for (int m = 0; m < 4; ++m) _Pragma("unroll") for (int n = 0; n < 2; ++n) _Pragma("unroll") for (int k = 0; k < 2; ++k) \
;         acc[ai][bj][m][n] = __builtin_amdgcn_mfma_f32_16x16x32_bf16(Bt_[n][k], At_[m][k], acc[ai][bj][m][n], 0, 0, 0); __builtin_amdgcn_s_setprio(0); } while (0)
; #define WAIT_V(n) asm volatile("s_waitcnt vmcnt(" #n ")" ::: "memory")
; #define WAIT_L(n) asm volatile("s_waitcnt lgkmcnt(" #n ")" ::: "memory")
; #define BAR __builtin_amdgcn_s_barrier()
; #define SCHED __builtin_amdgcn_sched_barrier(0)
; template <class Get, class Epi>
; DI void gemm_loop(int ntiles, int ld, char* shm, const Get& get, const Epi& epi) {
;     ...
;             G_LDA(At, 1, 1); G_STAGE(G_SB(1, 0), b3, voffB); G_STAGE(G_SB(1, 1), b3 + hstep, voffB); G_STAGE(G_SA(1, 0), a3, voffA);
;             WAIT_V(8); WAIT_L(0); BAR; G_MMA(1, 0, At, B0); G_MMA(1, 1, At, B1); BAR; SCHED;
;         }
	ds_read_b128 v[178:181], v143 offset:49152
	ds_read_b128 v[188:191], v143 offset:50176
	ds_read_b128 v[192:195], v143 offset:51200
	ds_read_b128 v[196:199], v143 offset:52224
	ds_read_b128 v[200:203], v143 offset:53248
	ds_read_b128 v[204:207], v143 offset:54272
	ds_read_b128 v[208:211], v143 offset:55296
	ds_read_b128 v[212:215], v143 offset:56320
	global_load_lds_dwordx4 v[182:183], off
	s_add_i32 m0, s36, 0x2000
	s_add_u32 s14, s14, 0x100080
	v_lshl_add_u64 v[182:183], v[184:185], 0, s[8:9]
	s_addc_u32 s15, s15, 0
	s_add_i32 s36, s83, s38
	global_load_lds_dwordx4 v[182:183], off
	v_lshl_add_u64 v[182:183], s[14:15], 0, v[132:133]
	s_mov_b32 m0, s36
	s_nop 0
	global_load_lds_dwordx4 v[182:183], off
	v_lshl_add_u64 v[182:183], s[14:15], 0, v[128:129]
	s_add_i32 m0, s36, 0x2000
	s_nop 0
	global_load_lds_dwordx4 v[182:183], off
	v_lshl_add_u64 v[182:183], v[186:187], 0, s[8:9]
	s_mov_b32 m0, s47
	s_nop 0
	global_load_lds_dwordx4 v[182:183], off
	v_lshl_add_u64 v[182:183], v[216:217], 0, s[8:9]
	s_mov_b32 m0, s50
	s_nop 0
	global_load_lds_dwordx4 v[182:183], off
	s_waitcnt vmcnt(8)
	s_waitcnt lgkmcnt(0)
	s_barrier
	s_setprio 1
	s_waitcnt lgkmcnt(0)
	v_mfma_f32_16x16x32_bf16 v[60:63], v[146:149], v[178:181], v[60:63]
	v_mfma_f32_16x16x32_bf16 v[56:59], v[154:157], v[178:181], v[56:59]
	v_mfma_f32_16x16x32_bf16 v[52:55], v[146:149], v[192:195], v[52:55]
	v_mfma_f32_16x16x32_bf16 v[48:51], v[154:157], v[192:195], v[48:51]
	v_mfma_f32_16x16x32_bf16 v[36:39], v[146:149], v[200:203], v[36:39]
	v_mfma_f32_16x16x32_bf16 v[32:35], v[154:157], v[200:203], v[32:35]
	v_mfma_f32_16x16x32_bf16 v[20:23], v[146:149], v[208:211], v[20:23]
	v_mfma_f32_16x16x32_bf16 v[16:19], v[154:157], v[208:211], v[16:19]
	v_mfma_f32_16x16x32_bf16 v[60:63], v[150:153], v[188:191], v[60:63]
	v_mfma_f32_16x16x32_bf16 v[56:59], v[158:161], v[188:191], v[56:59]
	v_mfma_f32_16x16x32_bf16 v[52:55], v[150:153], v[196:199], v[52:55]
	v_mfma_f32_16x16x32_bf16 v[48:51], v[158:161], v[196:199], v[48:51]
	v_mfma_f32_16x16x32_bf16 v[36:39], v[150:153], v[204:207], v[36:39]
	v_mfma_f32_16x16x32_bf16 v[32:35], v[158:161], v[204:207], v[32:35]
	v_mfma_f32_16x16x32_bf16 v[20:23], v[150:153], v[212:215], v[20:23]
	v_mfma_f32_16x16x32_bf16 v[16:19], v[158:161], v[212:215], v[16:19]
	s_setprio 0
	s_setprio 1
	v_mfma_f32_16x16x32_bf16 v[44:47], v[162:165], v[178:181], v[44:47]
	v_mfma_f32_16x16x32_bf16 v[40:43], v[170:173], v[178:181], v[40:43]
	v_mfma_f32_16x16x32_bf16 v[28:31], v[162:165], v[192:195], v[28:31]
	v_mfma_f32_16x16x32_bf16 v[24:27], v[170:173], v[192:195], v[24:27]
	v_mfma_f32_16x16x32_bf16 v[12:15], v[162:165], v[200:203], v[12:15]
	v_mfma_f32_16x16x32_bf16 v[8:11], v[170:173], v[200:203], v[8:11]
	v_mfma_f32_16x16x32_bf16 v[4:7], v[162:165], v[208:211], v[4:7]
	v_mfma_f32_16x16x32_bf16 v[0:3], v[170:173], v[208:211], v[0:3]
	v_mfma_f32_16x16x32_bf16 v[44:47], v[166:169], v[188:191], v[44:47]
	v_mfma_f32_16x16x32_bf16 v[40:43], v[174:177], v[188:191], v[40:43]
	v_mfma_f32_16x16x32_bf16 v[28:31], v[166:169], v[196:199], v[28:31]
	v_mfma_f32_16x16x32_bf16 v[24:27], v[174:177], v[196:199], v[24:27]
	v_mfma_f32_16x16x32_bf16 v[12:15], v[166:169], v[204:207], v[12:15]
	v_mfma_f32_16x16x32_bf16 v[8:11], v[174:177], v[204:207], v[8:11]
	v_mfma_f32_16x16x32_bf16 v[4:7], v[166:169], v[212:215], v[4:7]
	v_mfma_f32_16x16x32_bf16 v[0:3], v[174:177], v[212:215], v[0:3]
	s_setprio 0
	s_add_i32 s81, s81, 2
	s_add_u32 s34, s34, 0x100
	s_addc_u32 s35, s35, 0
	s_add_u32 s79, s79, 0x100
	s_addc_u32 s80, s80, 0
	s_cmp_gt_u32 s81, 61
	s_barrier
	s_cbranch_scc0 .LBB0_431

; #define G_STAGE(bufoff, gbase, voff) do { _Pragma("unroll") for (int _i = 0; _i < 2; ++_i) \
;         __builtin_amdgcn_global_load_lds((const unsigned*)((const char*)(gbase) + voff[_i]), (LAS unsigned*)(lds + (bufoff) + ldsw + _i * 8192), 16, 0, 0); } while (0)
; #define G_LDA(dst, b, h) do { _Pragma("unroll") for (int m = 0; m < 4; ++m) _Pragma("unroll") for (int k = 0; k < 2; ++k) dst[m][k] = *(const LAS bf16x8*)(lds + G_SA(b, h) + aoff + m * 2048 + k * 1024); } while (0)
; #define G_LDB(dst, b, h) do { _Pragma("unroll") for (int n = 0; n < 2; ++n) _Pragma("unroll") for (int k = 0; k < 2; ++k) dst[n][k] = *(const LAS bf16x8*)(lds + G_SB(b, h) + boff + n * 2048 + k * 1024); } while (0)
; #define G_MMA(ai, bj, At_, Bt_) do { __builtin_amdgcn_s_setprio(1); _Pragma("unroll") for (int m = 0; m < 4; ++m) _Pragma("unroll") for (int n = 0; n < 2; ++n) _Pragma("unroll") for (int k = 0; k < 2; ++k) \
;         acc[ai][bj][m][n] = __builtin_amdgcn_mfma_f32_16x16x32_bf16(Bt_[n][k], At_[m][k], acc[ai][bj][m][n], 0, 0, 0); __builtin_amdgcn_s_setprio(0); } while (0)
; #define WAIT_V(n) asm volatile("s_waitcnt vmcnt(" #n ")" ::: "memory")
; #define WAIT_L(n) asm volatile("s_waitcnt lgkmcnt(" #n ")" ::: "memory")
; #define BAR __builtin_amdgcn_s_barrier()
; #define SCHED __builtin_amdgcn_sched_barrier(0)
; template <class Get, class Epi>
; DI void gemm_loop(int ntiles, int ld, char* shm, const Get& get, const Epi& epi) {
;     ...
;             G_LDB(B0, 0, 0); G_LDB(B1, 0, 1); SCHED; G_LDA(At, 0, 0); G_STAGE(G_SA(1, 1), a1 + hstep, voffA);
;             WAIT_V(8); WAIT_L(0); BAR; G_MMA(0, 0, At, B0); G_MMA(0, 1, At, B1); BAR; SCHED;
;             G_LDA(At, 0, 1); G_STAGE(G_SB(0, 0), b2, voffB); G_STAGE(G_SB(0, 1), b2 + hstep, voffB); G_STAGE(G_SA(0, 0), a2, voffA);
;             WAIT_V(8); WAIT_L(0); BAR; G_MMA(1, 0, At, B0); G_MMA(1, 1, At, B1); BAR; SCHED;
;             G_LDB(B0, 1, 0); G_LDB(B1, 1, 1); SCHED; G_LDA(At, 1, 0); G_STAGE(G_SA(0, 1), a2 + hstep, voffA);
.Lpeel_445:
	ds_read_b128 v[146:149], v140
	ds_read_b128 v[150:153], v140 offset:1024
	ds_read_b128 v[154:157], v140 offset:2048
	ds_read_b128 v[158:161], v140 offset:3072
	ds_read_b128 v[162:165], v141
	ds_read_b128 v[166:169], v141 offset:1024
	ds_read_b128 v[170:173], v141 offset:2048
	ds_read_b128 v[174:177], v141 offset:3072
	s_add_u32 s14, s36, 0xfffe0080
	s_addc_u32 s15, s37, -1
	s_cmp_eq_u32 s81, 4
	s_cselect_b32 s39, s3, s15
	s_cselect_b32 s38, s2, s14
	s_cselect_b32 s15, s76, s80
	s_cselect_b32 s14, s78, s79
	s_mov_b32 m0, s50
	v_lshl_add_u64 v[182:183], s[36:37], 0, v[136:137]
	ds_read_b128 v[178:181], v142
	ds_read_b128 v[188:191], v142 offset:1024
	ds_read_b128 v[192:195], v142 offset:2048
	ds_read_b128 v[196:199], v142 offset:3072
	ds_read_b128 v[200:203], v142 offset:4096
	ds_read_b128 v[204:207], v142 offset:5120
	ds_read_b128 v[208:211], v142 offset:6144
	ds_read_b128 v[212:215], v142 offset:7168
	global_load_lds_dwordx4 v[182:183], off
	v_lshl_add_u64 v[182:183], s[36:37], 0, v[138:139]
	s_mov_b32 m0, s51
	s_nop 0
	global_load_lds_dwordx4 v[182:183], off
	s_waitcnt vmcnt(8)
	s_waitcnt lgkmcnt(0)
	s_barrier
	s_setprio 1
	s_waitcnt lgkmcnt(0)
	v_mfma_f32_16x16x32_bf16 v[124:127], v[146:149], v[178:181], 0
	v_mfma_f32_16x16x32_bf16 v[120:123], v[154:157], v[178:181], 0
	v_mfma_f32_16x16x32_bf16 v[116:119], v[146:149], v[192:195], 0
	v_mfma_f32_16x16x32_bf16 v[112:115], v[154:157], v[192:195], 0
	v_mfma_f32_16x16x32_bf16 v[100:103], v[146:149], v[200:203], 0
	v_mfma_f32_16x16x32_bf16 v[96:99], v[154:157], v[200:203], 0
	v_mfma_f32_16x16x32_bf16 v[84:87], v[146:149], v[208:211], 0
	v_mfma_f32_16x16x32_bf16 v[80:83], v[154:157], v[208:211], 0
	v_mfma_f32_16x16x32_bf16 v[124:127], v[150:153], v[188:191], v[124:127]
	v_mfma_f32_16x16x32_bf16 v[120:123], v[158:161], v[188:191], v[120:123]
	v_mfma_f32_16x16x32_bf16 v[116:119], v[150:153], v[196:199], v[116:119]
	v_mfma_f32_16x16x32_bf16 v[112:115], v[158:161], v[196:199], v[112:115]
	v_mfma_f32_16x16x32_bf16 v[100:103], v[150:153], v[204:207], v[100:103]
	v_mfma_f32_16x16x32_bf16 v[96:99], v[158:161], v[204:207], v[96:99]
	v_mfma_f32_16x16x32_bf16 v[84:87], v[150:153], v[212:215], v[84:87]
	v_mfma_f32_16x16x32_bf16 v[80:83], v[158:161], v[212:215], v[80:83]
	s_setprio 0
	s_setprio 1
	v_mfma_f32_16x16x32_bf16 v[108:111], v[162:165], v[178:181], 0
	v_mfma_f32_16x16x32_bf16 v[104:107], v[170:173], v[178:181], 0
	v_mfma_f32_16x16x32_bf16 v[92:95], v[162:165], v[192:195], 0
	v_mfma_f32_16x16x32_bf16 v[88:91], v[170:173], v[192:195], 0
	v_mfma_f32_16x16x32_bf16 v[76:79], v[162:165], v[200:203], 0
	v_mfma_f32_16x16x32_bf16 v[72:75], v[170:173], v[200:203], 0
	v_mfma_f32_16x16x32_bf16 v[68:71], v[162:165], v[208:211], 0
	v_mfma_f32_16x16x32_bf16 v[64:67], v[170:173], v[208:211], 0
	v_mfma_f32_16x16x32_bf16 v[108:111], v[166:169], v[188:191], v[108:111]
	v_mfma_f32_16x16x32_bf16 v[104:107], v[174:177], v[188:191], v[104:107]
	v_mfma_f32_16x16x32_bf16 v[92:95], v[166:169], v[196:199], v[92:95]
	v_mfma_f32_16x16x32_bf16 v[88:91], v[174:177], v[196:199], v[88:91]
	v_mfma_f32_16x16x32_bf16 v[76:79], v[166:169], v[204:207], v[76:79]
	v_mfma_f32_16x16x32_bf16 v[72:75], v[174:177], v[204:207], v[72:75]
	v_mfma_f32_16x16x32_bf16 v[68:71], v[166:169], v[212:215], v[68:71]
	v_mfma_f32_16x16x32_bf16 v[64:67], v[174:177], v[212:215], v[64:67]
	s_setprio 0
	s_mov_b32 m0, s54
	v_lshl_add_u64 v[182:183], s[14:15], 0, v[132:133]
	s_add_u32 s82, s14, 0x20000
	s_barrier
	ds_read_b128 v[178:181], v142 offset:16384
	ds_read_b128 v[188:191], v142 offset:17408
	ds_read_b128 v[192:195], v142 offset:18432
	ds_read_b128 v[196:199], v142 offset:19456
	ds_read_b128 v[200:203], v142 offset:20480
	ds_read_b128 v[204:207], v142 offset:21504
	ds_read_b128 v[208:211], v142 offset:22528
	ds_read_b128 v[212:215], v142 offset:23552
	global_load_lds_dwordx4 v[182:183], off
	v_lshl_add_u64 v[184:185], s[14:15], 0, v[128:129]
	s_mov_b32 m0, s55
	s_addc_u32 s83, s15, 0
	global_load_lds_dwordx4 v[184:185], off
	v_lshl_add_u64 v[186:187], s[82:83], 0, v[132:133]
	s_mov_b32 m0, s56
	v_lshl_add_u64 v[216:217], s[38:39], 0, v[130:131]
	global_load_lds_dwordx4 v[186:187], off
	v_lshl_add_u64 v[186:187], s[82:83], 0, v[128:129]
	s_mov_b32 m0, s57
	s_nop 0
	global_load_lds_dwordx4 v[186:187], off
	v_lshl_add_u64 v[186:187], s[38:39], 0, v[134:135]
	s_mov_b32 m0, s41
	s_nop 0
	global_load_lds_dwordx4 v[186:187], off
	s_mov_b32 m0, s43
	s_nop 0
	global_load_lds_dwordx4 v[216:217], off
	s_waitcnt vmcnt(8)
	s_waitcnt lgkmcnt(0)
	s_barrier
	s_setprio 1
	s_waitcnt lgkmcnt(0)
	v_mfma_f32_16x16x32_bf16 v[60:63], v[146:149], v[178:181], 0
	v_mfma_f32_16x16x32_bf16 v[56:59], v[154:157], v[178:181], 0
	v_mfma_f32_16x16x32_bf16 v[52:55], v[146:149], v[192:195], 0
	v_mfma_f32_16x16x32_bf16 v[48:51], v[154:157], v[192:195], 0
	v_mfma_f32_16x16x32_bf16 v[36:39], v[146:149], v[200:203], 0
	v_mfma_f32_16x16x32_bf16 v[32:35], v[154:157], v[200:203], 0
	v_mfma_f32_16x16x32_bf16 v[20:23], v[146:149], v[208:211], 0
	v_mfma_f32_16x16x32_bf16 v[16:19], v[154:157], v[208:211], 0
	v_mfma_f32_16x16x32_bf16 v[60:63], v[150:153], v[188:191], v[60:63]
	v_mfma_f32_16x16x32_bf16 v[56:59], v[158:161], v[188:191], v[56:59]
	v_mfma_f32_16x16x32_bf16 v[52:55], v[150:153], v[196:199], v[52:55]
	v_mfma_f32_16x16x32_bf16 v[48:51], v[158:161], v[196:199], v[48:51]
	v_mfma_f32_16x16x32_bf16 v[36:39], v[150:153], v[204:207], v[36:39]
	v_mfma_f32_16x16x32_bf16 v[32:35], v[158:161], v[204:207], v[32:35]
	v_mfma_f32_16x16x32_bf16 v[20:23], v[150:153], v[212:215], v[20:23]
	v_mfma_f32_16x16x32_bf16 v[16:19], v[158:161], v[212:215], v[16:19]
	s_setprio 0
	s_setprio 1
	v_mfma_f32_16x16x32_bf16 v[44:47], v[162:165], v[178:181], 0
	v_mfma_f32_16x16x32_bf16 v[40:43], v[170:173], v[178:181], 0
	v_mfma_f32_16x16x32_bf16 v[28:31], v[162:165], v[192:195], 0
	v_mfma_f32_16x16x32_bf16 v[24:27], v[170:173], v[192:195], 0
	v_mfma_f32_16x16x32_bf16 v[12:15], v[162:165], v[200:203], 0
	v_mfma_f32_16x16x32_bf16 v[8:11], v[170:173], v[200:203], 0
	v_mfma_f32_16x16x32_bf16 v[4:7], v[162:165], v[208:211], 0
	v_mfma_f32_16x16x32_bf16 v[0:3], v[170:173], v[208:211], 0
	v_mfma_f32_16x16x32_bf16 v[44:47], v[166:169], v[188:191], v[44:47]
	v_mfma_f32_16x16x32_bf16 v[40:43], v[174:177], v[188:191], v[40:43]
	v_mfma_f32_16x16x32_bf16 v[28:31], v[166:169], v[196:199], v[28:31]
	v_mfma_f32_16x16x32_bf16 v[24:27], v[174:177], v[196:199], v[24:27]
	v_mfma_f32_16x16x32_bf16 v[12:15], v[166:169], v[204:207], v[12:15]
	v_mfma_f32_16x16x32_bf16 v[8:11], v[174:177], v[204:207], v[8:11]
	v_mfma_f32_16x16x32_bf16 v[4:7], v[166:169], v[212:215], v[4:7]
	v_mfma_f32_16x16x32_bf16 v[0:3], v[174:177], v[212:215], v[0:3]
	s_setprio 0
	s_barrier
; #define G_STAGE(bufoff, gbase, voff) do { _Pragma("unroll") for (int _i = 0; _i < 2; ++_i) \
;         __builtin_amdgcn_global_load_lds((const unsigned*)((const char*)(gbase) + voff[_i]), (LAS unsigned*)(lds + (bufoff) + ldsw + _i * 8192), 16, 0, 0); } while (0)
; #define G_LDA(dst, b, h) do { _Pragma("unroll") for (int m = 0; m < 4; ++m) _Pragma("unroll") for (int k = 0; k < 2; ++k) dst[m][k] = *(const LAS bf16x8*)(lds + G_SA(b, h) + aoff + m * 2048 + k * 1024); } while (0)
; #define G_LDB(dst, b, h) do { _Pragma("unroll") for (int n = 0; n < 2; ++n) _Pragma("unroll") for (int k = 0; k < 2; ++k) dst[n][k] = *(const LAS bf16x8*)(lds + G_SB(b, h) + boff + n * 2048 + k * 1024); } while (0)
; #define G_MMA(ai, bj, At_, Bt_) do { __builtin_amdgcn_s_setprio(1); _Pragma("unroll") for (int m = 0; m < 4; ++m) _Pragma("unroll") for (int n = 0; n < 2; ++n) _Pragma("unroll") for (int k = 0; k < 2; ++k) \
;         acc[ai][bj][m][n] = __builtin_amdgcn_mfma_f32_16x16x32_bf16(Bt_[n][k], At_[m][k], acc[ai][bj][m][n], 0, 0, 0); __builtin_amdgcn_s_setprio(0); } while (0)
; #define WAIT_V(n) asm volatile("s_waitcnt vmcnt(" #n ")" ::: "memory")
; #define WAIT_L(n) asm volatile("s_waitcnt lgkmcnt(" #n ")" ::: "memory")
; #define BAR __builtin_amdgcn_s_barrier()
; #define SCHED __builtin_amdgcn_sched_barrier(0)
; template <class Get, class Epi>
; DI void gemm_loop(int ntiles, int ld, char* shm, const Get& get, const Epi& epi) {
;     ...
;             G_LDB(B0, 1, 0); G_LDB(B1, 1, 1); SCHED; G_LDA(At, 1, 0); G_STAGE(G_SA(0, 1), a2 + hstep, voffA);
;             WAIT_V(8); WAIT_L(0); BAR; G_MMA(0, 0, At, B0); G_MMA(0, 1, At, B1); BAR; SCHED;
;             G_LDA(At, 1, 1); G_STAGE(G_SB(1, 0), b3, voffB); G_STAGE(G_SB(1, 1), b3 + hstep, voffB); G_STAGE(G_SA(1, 0), a3, voffA);
;             WAIT_V(8); WAIT_L(0); BAR; G_MMA(1, 0, At, B0); G_MMA(1, 1, At, B1); BAR; SCHED;
	ds_read_b128 v[146:149], v143
	ds_read_b128 v[150:153], v143 offset:1024
	ds_read_b128 v[154:157], v143 offset:2048
	ds_read_b128 v[158:161], v143 offset:3072
	ds_read_b128 v[162:165], v144
	ds_read_b128 v[166:169], v144 offset:1024
	ds_read_b128 v[170:173], v144 offset:2048
	ds_read_b128 v[174:177], v144 offset:3072
	s_add_u32 s38, s38, 0x20000
	s_addc_u32 s39, s39, 0
	s_mov_b32 m0, s44
	v_lshl_add_u64 v[218:219], s[38:39], 0, v[134:135]
	ds_read_b128 v[178:181], v142 offset:32768
	ds_read_b128 v[188:191], v142 offset:33792
	ds_read_b128 v[192:195], v142 offset:34816
	ds_read_b128 v[196:199], v142 offset:35840
	ds_read_b128 v[200:203], v142 offset:36864
	ds_read_b128 v[204:207], v142 offset:37888
	ds_read_b128 v[208:211], v142 offset:38912
	ds_read_b128 v[212:215], v142 offset:39936
	global_load_lds_dwordx4 v[218:219], off
	v_lshl_add_u64 v[218:219], s[38:39], 0, v[130:131]
	s_mov_b32 m0, s45
	s_nop 0
	global_load_lds_dwordx4 v[218:219], off
	s_waitcnt vmcnt(8)
	s_waitcnt lgkmcnt(0)
	s_barrier
	s_setprio 1
	s_waitcnt lgkmcnt(0)
	v_mfma_f32_16x16x32_bf16 v[124:127], v[146:149], v[178:181], v[124:127]
	v_mfma_f32_16x16x32_bf16 v[120:123], v[154:157], v[178:181], v[120:123]
	v_mfma_f32_16x16x32_bf16 v[116:119], v[146:149], v[192:195], v[116:119]
	v_mfma_f32_16x16x32_bf16 v[112:115], v[154:157], v[192:195], v[112:115]
	v_mfma_f32_16x16x32_bf16 v[100:103], v[146:149], v[200:203], v[100:103]
	v_mfma_f32_16x16x32_bf16 v[96:99], v[154:157], v[200:203], v[96:99]
	v_mfma_f32_16x16x32_bf16 v[84:87], v[146:149], v[208:211], v[84:87]
	v_mfma_f32_16x16x32_bf16 v[80:83], v[154:157], v[208:211], v[80:83]
	v_mfma_f32_16x16x32_bf16 v[124:127], v[150:153], v[188:191], v[124:127]
	v_mfma_f32_16x16x32_bf16 v[120:123], v[158:161], v[188:191], v[120:123]
	v_mfma_f32_16x16x32_bf16 v[116:119], v[150:153], v[196:199], v[116:119]
	v_mfma_f32_16x16x32_bf16 v[112:115], v[158:161], v[196:199], v[112:115]
	v_mfma_f32_16x16x32_bf16 v[100:103], v[150:153], v[204:207], v[100:103]
	v_mfma_f32_16x16x32_bf16 v[96:99], v[158:161], v[204:207], v[96:99]
	v_mfma_f32_16x16x32_bf16 v[84:87], v[150:153], v[212:215], v[84:87]
	v_mfma_f32_16x16x32_bf16 v[80:83], v[158:161], v[212:215], v[80:83]
	s_setprio 0
	s_setprio 1
	v_mfma_f32_16x16x32_bf16 v[108:111], v[162:165], v[178:181], v[108:111]
	v_mfma_f32_16x16x32_bf16 v[104:107], v[170:173], v[178:181], v[104:107]
	v_mfma_f32_16x16x32_bf16 v[92:95], v[162:165], v[192:195], v[92:95]
	v_mfma_f32_16x16x32_bf16 v[88:91], v[170:173], v[192:195], v[88:91]
	v_mfma_f32_16x16x32_bf16 v[76:79], v[162:165], v[200:203], v[76:79]
	v_mfma_f32_16x16x32_bf16 v[72:75], v[170:173], v[200:203], v[72:75]
	v_mfma_f32_16x16x32_bf16 v[68:71], v[162:165], v[208:211], v[68:71]
	v_mfma_f32_16x16x32_bf16 v[64:67], v[170:173], v[208:211], v[64:67]
	v_mfma_f32_16x16x32_bf16 v[108:111], v[166:169], v[188:191], v[108:111]
	v_mfma_f32_16x16x32_bf16 v[104:107], v[174:177], v[188:191], v[104:107]
	v_mfma_f32_16x16x32_bf16 v[92:95], v[166:169], v[196:199], v[92:95]
	v_mfma_f32_16x16x32_bf16 v[88:91], v[174:177], v[196:199], v[88:91]
	v_mfma_f32_16x16x32_bf16 v[76:79], v[166:169], v[204:207], v[76:79]
	v_mfma_f32_16x16x32_bf16 v[72:75], v[174:177], v[204:207], v[72:75]
	v_mfma_f32_16x16x32_bf16 v[68:71], v[166:169], v[212:215], v[68:71]
	v_mfma_f32_16x16x32_bf16 v[64:67], v[174:177], v[212:215], v[64:67]
	s_setprio 0
	s_mov_b32 m0, s58
	v_lshl_add_u64 v[182:183], v[182:183], 0, s[12:13]
	s_add_u32 s14, s14, 0x20080
	s_barrier
	ds_read_b128 v[178:181], v142 offset:49152
	ds_read_b128 v[188:191], v142 offset:50176
	ds_read_b128 v[192:195], v142 offset:51200
	ds_read_b128 v[196:199], v142 offset:52224
	ds_read_b128 v[200:203], v142 offset:53248
	ds_read_b128 v[204:207], v142 offset:54272
	ds_read_b128 v[208:211], v142 offset:55296
	ds_read_b128 v[212:215], v142 offset:56320
	global_load_lds_dwordx4 v[182:183], off
	v_lshl_add_u64 v[182:183], v[184:185], 0, s[12:13]
	s_mov_b32 m0, s59
	s_addc_u32 s15, s15, 0
	global_load_lds_dwordx4 v[182:183], off
	v_lshl_add_u64 v[182:183], s[14:15], 0, v[132:133]
	s_mov_b32 m0, s72
	s_nop 0
	global_load_lds_dwordx4 v[182:183], off
	v_lshl_add_u64 v[182:183], s[14:15], 0, v[128:129]
	s_mov_b32 m0, s73
	s_nop 0
	global_load_lds_dwordx4 v[182:183], off
	v_lshl_add_u64 v[182:183], v[186:187], 0, s[12:13]
	s_mov_b32 m0, s46
	s_nop 0
	global_load_lds_dwordx4 v[182:183], off
	v_lshl_add_u64 v[182:183], v[216:217], 0, s[12:13]
	s_mov_b32 m0, s47
	s_nop 0
	global_load_lds_dwordx4 v[182:183], off
	s_waitcnt vmcnt(8)
	s_waitcnt lgkmcnt(0)
	s_barrier
	s_setprio 1
	s_waitcnt lgkmcnt(0)
	v_mfma_f32_16x16x32_bf16 v[60:63], v[146:149], v[178:181], v[60:63]
	v_mfma_f32_16x16x32_bf16 v[56:59], v[154:157], v[178:181], v[56:59]
	v_mfma_f32_16x16x32_bf16 v[52:55], v[146:149], v[192:195], v[52:55]
	v_mfma_f32_16x16x32_bf16 v[48:51], v[154:157], v[192:195], v[48:51]
	v_mfma_f32_16x16x32_bf16 v[36:39], v[146:149], v[200:203], v[36:39]
	v_mfma_f32_16x16x32_bf16 v[32:35], v[154:157], v[200:203], v[32:35]
	v_mfma_f32_16x16x32_bf16 v[20:23], v[146:149], v[208:211], v[20:23]
	v_mfma_f32_16x16x32_bf16 v[16:19], v[154:157], v[208:211], v[16:19]
	v_mfma_f32_16x16x32_bf16 v[60:63], v[150:153], v[188:191], v[60:63]
	v_mfma_f32_16x16x32_bf16 v[56:59], v[158:161], v[188:191], v[56:59]
	v_mfma_f32_16x16x32_bf16 v[52:55], v[150:153], v[196:199], v[52:55]
	v_mfma_f32_16x16x32_bf16 v[48:51], v[158:161], v[196:199], v[48:51]
	v_mfma_f32_16x16x32_bf16 v[36:39], v[150:153], v[204:207], v[36:39]
	v_mfma_f32_16x16x32_bf16 v[32:35], v[158:161], v[204:207], v[32:35]
	v_mfma_f32_16x16x32_bf16 v[20:23], v[150:153], v[212:215], v[20:23]
	v_mfma_f32_16x16x32_bf16 v[16:19], v[158:161], v[212:215], v[16:19]
	s_setprio 0
	s_setprio 1
	v_mfma_f32_16x16x32_bf16 v[44:47], v[162:165], v[178:181], v[44:47]
	v_mfma_f32_16x16x32_bf16 v[40:43], v[170:173], v[178:181], v[40:43]
	v_mfma_f32_16x16x32_bf16 v[28:31], v[162:165], v[192:195], v[28:31]
	v_mfma_f32_16x16x32_bf16 v[24:27], v[170:173], v[192:195], v[24:27]
	v_mfma_f32_16x16x32_bf16 v[12:15], v[162:165], v[200:203], v[12:15]
	v_mfma_f32_16x16x32_bf16 v[8:11], v[170:173], v[200:203], v[8:11]
	v_mfma_f32_16x16x32_bf16 v[4:7], v[162:165], v[208:211], v[4:7]
	v_mfma_f32_16x16x32_bf16 v[0:3], v[170:173], v[208:211], v[0:3]
	v_mfma_f32_16x16x32_bf16 v[44:47], v[166:169], v[188:191], v[44:47]
	v_mfma_f32_16x16x32_bf16 v[40:43], v[174:177], v[188:191], v[40:43]
	v_mfma_f32_16x16x32_bf16 v[28:31], v[166:169], v[196:199], v[28:31]
	v_mfma_f32_16x16x32_bf16 v[24:27], v[174:177], v[196:199], v[24:27]
	v_mfma_f32_16x16x32_bf16 v[12:15], v[166:169], v[204:207], v[12:15]
	v_mfma_f32_16x16x32_bf16 v[8:11], v[174:177], v[204:207], v[8:11]
	v_mfma_f32_16x16x32_bf16 v[4:7], v[166:169], v[212:215], v[4:7]
	v_mfma_f32_16x16x32_bf16 v[0:3], v[174:177], v[212:215], v[0:3]
	s_setprio 0
	s_add_i32 s81, s81, 2
	s_add_u32 s36, s36, 0x100
	s_addc_u32 s37, s37, 0
	s_add_u32 s79, s79, 0x100
	s_addc_u32 s80, s80, 0
	s_cmp_gt_u32 s81, 5
	s_barrier
	s_cbranch_scc0 .LBB0_445
	s_branch .Lpost_445
; #define G_STAGE(bufoff, gbase, voff) do { _Pragma("unroll") for (int _i = 0; _i < 2; ++_i) \
;         __builtin_amdgcn_global_load_lds((const unsigned*)((const char*)(gbase) + voff[_i]), (LAS unsigned*)(lds + (bufoff) + ldsw + _i * 8192), 16, 0, 0); } while (0)
; #define G_LDA(dst, b, h) do { _Pragma("unroll") for (int m = 0; m < 4; ++m) _Pragma("unroll") for (int k = 0; k < 2; ++k) dst[m][k] = *(const LAS bf16x8*)(lds + G_SA(b, h) + aoff + m * 2048 + k * 1024); } while (0)
; #define G_LDB(dst, b, h) do { _Pragma("unroll") for (int n = 0; n < 2; ++n) _Pragma("unroll") for (int k = 0; k < 2; ++k) dst[n][k] = *(const LAS bf16x8*)(lds + G_SB(b, h) + boff + n * 2048 + k * 1024); } while (0)
; #define G_MMA(ai, bj, At_, Bt_) do { __builtin_amdgcn_s_setprio(1); _Pragma("unroll") for (int m = 0; m < 4; ++m) _Pragma("unroll") for (int n = 0; n < 2; ++n) _Pragma("unroll") for (int k = 0; k < 2; ++k) \
;         acc[ai][bj][m][n] = __builtin_amdgcn_mfma_f32_16x16x32_bf16(Bt_[n][k], At_[m][k], acc[ai][bj][m][n], 0, 0, 0); __builtin_amdgcn_s_setprio(0); } while (0)
; #define WAIT_V(n) asm volatile("s_waitcnt vmcnt(" #n ")" ::: "memory")
; #define WAIT_L(n) asm volatile("s_waitcnt lgkmcnt(" #n ")" ::: "memory")
; #define BAR __builtin_amdgcn_s_barrier()
; #define SCHED __builtin_amdgcn_sched_barrier(0)
; template <class Get, class Epi>
; DI void gemm_loop(int ntiles, int ld, char* shm, const Get& get, const Epi& epi) {
;     ...
;             G_LDB(B0, 0, 0); G_LDB(B1, 0, 1); SCHED; G_LDA(At, 0, 0); G_STAGE(G_SA(1, 1), a1 + hstep, voffA);
;             WAIT_V(8); WAIT_L(0); BAR; G_MMA(0, 0, At, B0); G_MMA(0, 1, At, B1); BAR; SCHED;
;             G_LDA(At, 0, 1); G_STAGE(G_SB(0, 0), b2, voffB); G_STAGE(G_SB(0, 1), b2 + hstep, voffB); G_STAGE(G_SA(0, 0), a2, voffA);
.LBB0_445:
	ds_read_b128 v[146:149], v140
	ds_read_b128 v[150:153], v140 offset:1024
	ds_read_b128 v[154:157], v140 offset:2048
	ds_read_b128 v[158:161], v140 offset:3072
	ds_read_b128 v[162:165], v141
	ds_read_b128 v[166:169], v141 offset:1024
	ds_read_b128 v[170:173], v141 offset:2048
	ds_read_b128 v[174:177], v141 offset:3072
	s_add_u32 s14, s36, 0xfffe0080
	s_addc_u32 s15, s37, -1
	s_cmp_eq_u32 s81, 4
	s_cselect_b32 s39, s3, s15
	s_cselect_b32 s38, s2, s14
	s_cselect_b32 s15, s76, s80
	s_cselect_b32 s14, s78, s79
	s_mov_b32 m0, s50
	v_lshl_add_u64 v[182:183], s[36:37], 0, v[136:137]
	ds_read_b128 v[178:181], v142
	ds_read_b128 v[188:191], v142 offset:1024
	ds_read_b128 v[192:195], v142 offset:2048
	ds_read_b128 v[196:199], v142 offset:3072
	ds_read_b128 v[200:203], v142 offset:4096
	ds_read_b128 v[204:207], v142 offset:5120
	ds_read_b128 v[208:211], v142 offset:6144
	ds_read_b128 v[212:215], v142 offset:7168
	global_load_lds_dwordx4 v[182:183], off
	v_lshl_add_u64 v[182:183], s[36:37], 0, v[138:139]
	s_mov_b32 m0, s51
	s_nop 0
	global_load_lds_dwordx4 v[182:183], off
	s_waitcnt vmcnt(8)
	s_waitcnt lgkmcnt(0)
	s_barrier
	s_setprio 1
	s_waitcnt lgkmcnt(0)
	v_mfma_f32_16x16x32_bf16 v[124:127], v[146:149], v[178:181], v[124:127]
	v_mfma_f32_16x16x32_bf16 v[120:123], v[154:157], v[178:181], v[120:123]
	v_mfma_f32_16x16x32_bf16 v[116:119], v[146:149], v[192:195], v[116:119]
	v_mfma_f32_16x16x32_bf16 v[112:115], v[154:157], v[192:195], v[112:115]
	v_mfma_f32_16x16x32_bf16 v[100:103], v[146:149], v[200:203], v[100:103]
	v_mfma_f32_16x16x32_bf16 v[96:99], v[154:157], v[200:203], v[96:99]
	v_mfma_f32_16x16x32_bf16 v[84:87], v[146:149], v[208:211], v[84:87]
	v_mfma_f32_16x16x32_bf16 v[80:83], v[154:157], v[208:211], v[80:83]
	v_mfma_f32_16x16x32_bf16 v[124:127], v[150:153], v[188:191], v[124:127]
	v_mfma_f32_16x16x32_bf16 v[120:123], v[158:161], v[188:191], v[120:123]
	v_mfma_f32_16x16x32_bf16 v[116:119], v[150:153], v[196:199], v[116:119]
	v_mfma_f32_16x16x32_bf16 v[112:115], v[158:161], v[196:199], v[112:115]
	v_mfma_f32_16x16x32_bf16 v[100:103], v[150:153], v[204:207], v[100:103]
	v_mfma_f32_16x16x32_bf16 v[96:99], v[158:161], v[204:207], v[96:99]
	v_mfma_f32_16x16x32_bf16 v[84:87], v[150:153], v[212:215], v[84:87]
	v_mfma_f32_16x16x32_bf16 v[80:83], v[158:161], v[212:215], v[80:83]
	s_setprio 0
	s_setprio 1
	v_mfma_f32_16x16x32_bf16 v[108:111], v[162:165], v[178:181], v[108:111]
	v_mfma_f32_16x16x32_bf16 v[104:107], v[170:173], v[178:181], v[104:107]
	v_mfma_f32_16x16x32_bf16 v[92:95], v[162:165], v[192:195], v[92:95]
	v_mfma_f32_16x16x32_bf16 v[88:91], v[170:173], v[192:195], v[88:91]
	v_mfma_f32_16x16x32_bf16 v[76:79], v[162:165], v[200:203], v[76:79]
	v_mfma_f32_16x16x32_bf16 v[72:75], v[170:173], v[200:203], v[72:75]
	v_mfma_f32_16x16x32_bf16 v[68:71], v[162:165], v[208:211], v[68:71]
	v_mfma_f32_16x16x32_bf16 v[64:67], v[170:173], v[208:211], v[64:67]
	v_mfma_f32_16x16x32_bf16 v[108:111], v[166:169], v[188:191], v[108:111]
	v_mfma_f32_16x16x32_bf16 v[104:107], v[174:177], v[188:191], v[104:107]
	v_mfma_f32_16x16x32_bf16 v[92:95], v[166:169], v[196:199], v[92:95]
	v_mfma_f32_16x16x32_bf16 v[88:91], v[174:177], v[196:199], v[88:91]
	v_mfma_f32_16x16x32_bf16 v[76:79], v[166:169], v[204:207], v[76:79]
	v_mfma_f32_16x16x32_bf16 v[72:75], v[174:177], v[204:207], v[72:75]
	v_mfma_f32_16x16x32_bf16 v[68:71], v[166:169], v[212:215], v[68:71]
	v_mfma_f32_16x16x32_bf16 v[64:67], v[174:177], v[212:215], v[64:67]
	s_setprio 0
	s_mov_b32 m0, s54
	v_lshl_add_u64 v[182:183], s[14:15], 0, v[132:133]
	s_add_u32 s82, s14, 0x20000
	s_barrier
	ds_read_b128 v[178:181], v142 offset:16384
	ds_read_b128 v[188:191], v142 offset:17408
	ds_read_b128 v[192:195], v142 offset:18432
	ds_read_b128 v[196:199], v142 offset:19456
	ds_read_b128 v[200:203], v142 offset:20480
	ds_read_b128 v[204:207], v142 offset:21504
	ds_read_b128 v[208:211], v142 offset:22528
	ds_read_b128 v[212:215], v142 offset:23552
	global_load_lds_dwordx4 v[182:183], off
	v_lshl_add_u64 v[184:185], s[14:15], 0, v[128:129]
	s_mov_b32 m0, s55
	s_addc_u32 s83, s15, 0
	global_load_lds_dwordx4 v[184:185], off
	v_lshl_add_u64 v[186:187], s[82:83], 0, v[132:133]
	s_mov_b32 m0, s56
	v_lshl_add_u64 v[216:217], s[38:39], 0, v[130:131]
	global_load_lds_dwordx4 v[186:187], off
	v_lshl_add_u64 v[186:187], s[82:83], 0, v[128:129]
	s_mov_b32 m0, s57
	s_nop 0
	global_load_lds_dwordx4 v[186:187], off
	v_lshl_add_u64 v[186:187], s[38:39], 0, v[134:135]
	s_mov_b32 m0, s41
	s_nop 0
	global_load_lds_dwordx4 v[186:187], off
	s_mov_b32 m0, s43
	s_nop 0
	global_load_lds_dwordx4 v[216:217], off
	s_waitcnt vmcnt(8)
	s_waitcnt lgkmcnt(0)
	s_barrier
; #define G_STAGE(bufoff, gbase, voff) do { _Pragma("unroll") for (int _i = 0; _i < 2; ++_i) \
;         __builtin_amdgcn_global_load_lds((const unsigned*)((const char*)(gbase) + voff[_i]), (LAS unsigned*)(lds + (bufoff) + ldsw + _i * 8192), 16, 0, 0); } while (0)
; #define G_LDA(dst, b, h) do { _Pragma("unroll") for (int m = 0; m < 4; ++m) _Pragma("unroll") for (int k = 0; k < 2; ++k) dst[m][k] = *(const LAS bf16x8*)(lds + G_SA(b, h) + aoff + m * 2048 + k * 1024); } while (0)
; #define G_LDB(dst, b, h) do { _Pragma("unroll") for (int n = 0; n < 2; ++n) _Pragma("unroll") for (int k = 0; k < 2; ++k) dst[n][k] = *(const LAS bf16x8*)(lds + G_SB(b, h) + boff + n * 2048 + k * 1024); } while (0)
; #define G_MMA(ai, bj, At_, Bt_) do { __builtin_amdgcn_s_setprio(1); _Pragma("unroll") for (int m = 0; m < 4; ++m) _Pragma("unroll") for (int n = 0; n < 2; ++n) _Pragma("unroll") for (int k = 0; k < 2; ++k) \
;         acc[ai][bj][m][n] = __builtin_amdgcn_mfma_f32_16x16x32_bf16(Bt_[n][k], At_[m][k], acc[ai][bj][m][n], 0, 0, 0); __builtin_amdgcn_s_setprio(0); } while (0)
; #define WAIT_V(n) asm volatile("s_waitcnt vmcnt(" #n ")" ::: "memory")
; #define WAIT_L(n) asm volatile("s_waitcnt lgkmcnt(" #n ")" ::: "memory")
; #define BAR __builtin_amdgcn_s_barrier()
; #define SCHED __builtin_amdgcn_sched_barrier(0)
; template <class Get, class Epi>
; DI void gemm_loop(int ntiles, int ld, char* shm, const Get& get, const Epi& epi) {
;     ...
;             WAIT_V(8); WAIT_L(0); BAR; G_MMA(1, 0, At, B0); G_MMA(1, 1, At, B1); BAR; SCHED;
;             G_LDB(B0, 1, 0); G_LDB(B1, 1, 1); SCHED; G_LDA(At, 1, 0); G_STAGE(G_SA(0, 1), a2 + hstep, voffA);
;             WAIT_V(8); WAIT_L(0); BAR; G_MMA(0, 0, At, B0); G_MMA(0, 1, At, B1); BAR; SCHED;
;             G_LDA(At, 1, 1); G_STAGE(G_SB(1, 0), b3, voffB); G_STAGE(G_SB(1, 1), b3 + hstep, voffB); G_STAGE(G_SA(1, 0), a3, voffA);
	s_setprio 1
	s_waitcnt lgkmcnt(0)
	v_mfma_f32_16x16x32_bf16 v[60:63], v[146:149], v[178:181], v[60:63]
	v_mfma_f32_16x16x32_bf16 v[56:59], v[154:157], v[178:181], v[56:59]
	v_mfma_f32_16x16x32_bf16 v[52:55], v[146:149], v[192:195], v[52:55]
	v_mfma_f32_16x16x32_bf16 v[48:51], v[154:157], v[192:195], v[48:51]
	v_mfma_f32_16x16x32_bf16 v[36:39], v[146:149], v[200:203], v[36:39]
	v_mfma_f32_16x16x32_bf16 v[32:35], v[154:157], v[200:203], v[32:35]
	v_mfma_f32_16x16x32_bf16 v[20:23], v[146:149], v[208:211], v[20:23]
	v_mfma_f32_16x16x32_bf16 v[16:19], v[154:157], v[208:211], v[16:19]
	v_mfma_f32_16x16x32_bf16 v[60:63], v[150:153], v[188:191], v[60:63]
	v_mfma_f32_16x16x32_bf16 v[56:59], v[158:161], v[188:191], v[56:59]
	v_mfma_f32_16x16x32_bf16 v[52:55], v[150:153], v[196:199], v[52:55]
	v_mfma_f32_16x16x32_bf16 v[48:51], v[158:161], v[196:199], v[48:51]
	v_mfma_f32_16x16x32_bf16 v[36:39], v[150:153], v[204:207], v[36:39]
	v_mfma_f32_16x16x32_bf16 v[32:35], v[158:161], v[204:207], v[32:35]
	v_mfma_f32_16x16x32_bf16 v[20:23], v[150:153], v[212:215], v[20:23]
	v_mfma_f32_16x16x32_bf16 v[16:19], v[158:161], v[212:215], v[16:19]
	s_setprio 0
	s_setprio 1
	v_mfma_f32_16x16x32_bf16 v[44:47], v[162:165], v[178:181], v[44:47]
	v_mfma_f32_16x16x32_bf16 v[40:43], v[170:173], v[178:181], v[40:43]
	v_mfma_f32_16x16x32_bf16 v[28:31], v[162:165], v[192:195], v[28:31]
	v_mfma_f32_16x16x32_bf16 v[24:27], v[170:173], v[192:195], v[24:27]
	v_mfma_f32_16x16x32_bf16 v[12:15], v[162:165], v[200:203], v[12:15]
	v_mfma_f32_16x16x32_bf16 v[8:11], v[170:173], v[200:203], v[8:11]
	v_mfma_f32_16x16x32_bf16 v[4:7], v[162:165], v[208:211], v[4:7]
	v_mfma_f32_16x16x32_bf16 v[0:3], v[170:173], v[208:211], v[0:3]
	v_mfma_f32_16x16x32_bf16 v[44:47], v[166:169], v[188:191], v[44:47]
	v_mfma_f32_16x16x32_bf16 v[40:43], v[174:177], v[188:191], v[40:43]
	v_mfma_f32_16x16x32_bf16 v[28:31], v[166:169], v[196:199], v[28:31]
	v_mfma_f32_16x16x32_bf16 v[24:27], v[174:177], v[196:199], v[24:27]
	v_mfma_f32_16x16x32_bf16 v[12:15], v[166:169], v[204:207], v[12:15]
	v_mfma_f32_16x16x32_bf16 v[8:11], v[174:177], v[204:207], v[8:11]
	v_mfma_f32_16x16x32_bf16 v[4:7], v[166:169], v[212:215], v[4:7]
	v_mfma_f32_16x16x32_bf16 v[0:3], v[174:177], v[212:215], v[0:3]
	s_setprio 0
	s_barrier
	ds_read_b128 v[146:149], v143
	ds_read_b128 v[150:153], v143 offset:1024
	ds_read_b128 v[154:157], v143 offset:2048
	ds_read_b128 v[158:161], v143 offset:3072
	ds_read_b128 v[162:165], v144
	ds_read_b128 v[166:169], v144 offset:1024
	ds_read_b128 v[170:173], v144 offset:2048
	ds_read_b128 v[174:177], v144 offset:3072
	s_add_u32 s38, s38, 0x20000
	s_addc_u32 s39, s39, 0
	s_mov_b32 m0, s44
	v_lshl_add_u64 v[218:219], s[38:39], 0, v[134:135]
	ds_read_b128 v[178:181], v142 offset:32768
	ds_read_b128 v[188:191], v142 offset:33792
	ds_read_b128 v[192:195], v142 offset:34816
	ds_read_b128 v[196:199], v142 offset:35840
	ds_read_b128 v[200:203], v142 offset:36864
	ds_read_b128 v[204:207], v142 offset:37888
	ds_read_b128 v[208:211], v142 offset:38912
	ds_read_b128 v[212:215], v142 offset:39936
	global_load_lds_dwordx4 v[218:219], off
	v_lshl_add_u64 v[218:219], s[38:39], 0, v[130:131]
	s_mov_b32 m0, s45
	s_nop 0
	global_load_lds_dwordx4 v[218:219], off
	s_waitcnt vmcnt(8)
	s_waitcnt lgkmcnt(0)
	s_barrier
	s_setprio 1
	s_waitcnt lgkmcnt(0)
	v_mfma_f32_16x16x32_bf16 v[124:127], v[146:149], v[178:181], v[124:127]
	v_mfma_f32_16x16x32_bf16 v[120:123], v[154:157], v[178:181], v[120:123]
	v_mfma_f32_16x16x32_bf16 v[116:119], v[146:149], v[192:195], v[116:119]
	v_mfma_f32_16x16x32_bf16 v[112:115], v[154:157], v[192:195], v[112:115]
	v_mfma_f32_16x16x32_bf16 v[100:103], v[146:149], v[200:203], v[100:103]
	v_mfma_f32_16x16x32_bf16 v[96:99], v[154:157], v[200:203], v[96:99]
	v_mfma_f32_16x16x32_bf16 v[84:87], v[146:149], v[208:211], v[84:87]
	v_mfma_f32_16x16x32_bf16 v[80:83], v[154:157], v[208:211], v[80:83]
	v_mfma_f32_16x16x32_bf16 v[124:127], v[150:153], v[188:191], v[124:127]
	v_mfma_f32_16x16x32_bf16 v[120:123], v[158:161], v[188:191], v[120:123]
	v_mfma_f32_16x16x32_bf16 v[116:119], v[150:153], v[196:199], v[116:119]
	v_mfma_f32_16x16x32_bf16 v[112:115], v[158:161], v[196:199], v[112:115]
	v_mfma_f32_16x16x32_bf16 v[100:103], v[150:153], v[204:207], v[100:103]
	v_mfma_f32_16x16x32_bf16 v[96:99], v[158:161], v[204:207], v[96:99]
	v_mfma_f32_16x16x32_bf16 v[84:87], v[150:153], v[212:215], v[84:87]
	v_mfma_f32_16x16x32_bf16 v[80:83], v[158:161], v[212:215], v[80:83]
	s_setprio 0
	s_setprio 1
	v_mfma_f32_16x16x32_bf16 v[108:111], v[162:165], v[178:181], v[108:111]
	v_mfma_f32_16x16x32_bf16 v[104:107], v[170:173], v[178:181], v[104:107]
	v_mfma_f32_16x16x32_bf16 v[92:95], v[162:165], v[192:195], v[92:95]
	v_mfma_f32_16x16x32_bf16 v[88:91], v[170:173], v[192:195], v[88:91]
	v_mfma_f32_16x16x32_bf16 v[76:79], v[162:165], v[200:203], v[76:79]
	v_mfma_f32_16x16x32_bf16 v[72:75], v[170:173], v[200:203], v[72:75]
	v_mfma_f32_16x16x32_bf16 v[68:71], v[162:165], v[208:211], v[68:71]
	v_mfma_f32_16x16x32_bf16 v[64:67], v[170:173], v[208:211], v[64:67]
	v_mfma_f32_16x16x32_bf16 v[108:111], v[166:169], v[188:191], v[108:111]
	v_mfma_f32_16x16x32_bf16 v[104:107], v[174:177], v[188:191], v[104:107]
	v_mfma_f32_16x16x32_bf16 v[92:95], v[166:169], v[196:199], v[92:95]
	v_mfma_f32_16x16x32_bf16 v[88:91], v[174:177], v[196:199], v[88:91]
	v_mfma_f32_16x16x32_bf16 v[76:79], v[166:169], v[204:207], v[76:79]
	v_mfma_f32_16x16x32_bf16 v[72:75], v[174:177], v[204:207], v[72:75]
	v_mfma_f32_16x16x32_bf16 v[68:71], v[166:169], v[212:215], v[68:71]
	v_mfma_f32_16x16x32_bf16 v[64:67], v[174:177], v[212:215], v[64:67]
	s_setprio 0
	s_mov_b32 m0, s58
	v_lshl_add_u64 v[182:183], v[182:183], 0, s[12:13]
	s_add_u32 s14, s14, 0x20080
	s_barrier
; #define G_STAGE(bufoff, gbase, voff) do { _Pragma("unroll") for (int _i = 0; _i < 2; ++_i) \
;         __builtin_amdgcn_global_load_lds((const unsigned*)((const char*)(gbase) + voff[_i]), (LAS unsigned*)(lds + (bufoff) + ldsw + _i * 8192), 16, 0, 0); } while (0)
; #define G_LDA(dst, b, h) do { _Pragma("unroll") for (int m = 0; m < 4; ++m) _Pragma("unroll") for (int k = 0; k < 2; ++k) dst[m][k] = *(const LAS bf16x8*)(lds + G_SA(b, h) + aoff + m * 2048 + k * 1024); } while (0)
; #define G_MMA(ai, bj, At_, Bt_) do { __builtin_amdgcn_s_setprio(1); _Pragma("unroll") for (int m = 0; m < 4; ++m) _Pragma("unroll") for (int n = 0; n < 2; ++n) _Pragma("unroll") for (int k = 0; k < 2; ++k) \
;         acc[ai][bj][m][n] = __builtin_amdgcn_mfma_f32_16x16x32_bf16(Bt_[n][k], At_[m][k], acc[ai][bj][m][n], 0, 0, 0); __builtin_amdgcn_s_setprio(0); } while (0)
; #define WAIT_V(n) asm volatile("s_waitcnt vmcnt(" #n ")" ::: "memory")
; #define WAIT_L(n) asm volatile("s_waitcnt lgkmcnt(" #n ")" ::: "memory")
; #define BAR __builtin_amdgcn_s_barrier()
; #define SCHED __builtin_amdgcn_sched_barrier(0)
; template <class Get, class Epi>
; DI void gemm_loop(int ntiles, int ld, char* shm, const Get& get, const Epi& epi) {
;     ...
;             G_LDA(At, 1, 1); G_STAGE(G_SB(1, 0), b3, voffB); G_STAGE(G_SB(1, 1), b3 + hstep, voffB); G_STAGE(G_SA(1, 0), a3, voffA);
;             WAIT_V(8); WAIT_L(0); BAR; G_MMA(1, 0, At, B0); G_MMA(1, 1, At, B1); BAR; SCHED;
;         }
	ds_read_b128 v[178:181], v142 offset:49152
	ds_read_b128 v[188:191], v142 offset:50176
	ds_read_b128 v[192:195], v142 offset:51200
	ds_read_b128 v[196:199], v142 offset:52224
	ds_read_b128 v[200:203], v142 offset:53248
	ds_read_b128 v[204:207], v142 offset:54272
	ds_read_b128 v[208:211], v142 offset:55296
	ds_read_b128 v[212:215], v142 offset:56320
	global_load_lds_dwordx4 v[182:183], off
	v_lshl_add_u64 v[182:183], v[184:185], 0, s[12:13]
	s_mov_b32 m0, s59
	s_addc_u32 s15, s15, 0
	global_load_lds_dwordx4 v[182:183], off
	v_lshl_add_u64 v[182:183], s[14:15], 0, v[132:133]
	s_mov_b32 m0, s72
	s_nop 0
	global_load_lds_dwordx4 v[182:183], off
	v_lshl_add_u64 v[182:183], s[14:15], 0, v[128:129]
	s_mov_b32 m0, s73
	s_nop 0
	global_load_lds_dwordx4 v[182:183], off
	v_lshl_add_u64 v[182:183], v[186:187], 0, s[12:13]
	s_mov_b32 m0, s46
	s_nop 0
	global_load_lds_dwordx4 v[182:183], off
	v_lshl_add_u64 v[182:183], v[216:217], 0, s[12:13]
	s_mov_b32 m0, s47
	s_nop 0
	global_load_lds_dwordx4 v[182:183], off
	s_waitcnt vmcnt(8)
	s_waitcnt lgkmcnt(0)
	s_barrier
	s_setprio 1
	s_waitcnt lgkmcnt(0)
	v_mfma_f32_16x16x32_bf16 v[60:63], v[146:149], v[178:181], v[60:63]
	v_mfma_f32_16x16x32_bf16 v[56:59], v[154:157], v[178:181], v[56:59]
	v_mfma_f32_16x16x32_bf16 v[52:55], v[146:149], v[192:195], v[52:55]
	v_mfma_f32_16x16x32_bf16 v[48:51], v[154:157], v[192:195], v[48:51]
	v_mfma_f32_16x16x32_bf16 v[36:39], v[146:149], v[200:203], v[36:39]
	v_mfma_f32_16x16x32_bf16 v[32:35], v[154:157], v[200:203], v[32:35]
	v_mfma_f32_16x16x32_bf16 v[20:23], v[146:149], v[208:211], v[20:23]
	v_mfma_f32_16x16x32_bf16 v[16:19], v[154:157], v[208:211], v[16:19]
	v_mfma_f32_16x16x32_bf16 v[60:63], v[150:153], v[188:191], v[60:63]
	v_mfma_f32_16x16x32_bf16 v[56:59], v[158:161], v[188:191], v[56:59]
	v_mfma_f32_16x16x32_bf16 v[52:55], v[150:153], v[196:199], v[52:55]
	v_mfma_f32_16x16x32_bf16 v[48:51], v[158:161], v[196:199], v[48:51]
	v_mfma_f32_16x16x32_bf16 v[36:39], v[150:153], v[204:207], v[36:39]
	v_mfma_f32_16x16x32_bf16 v[32:35], v[158:161], v[204:207], v[32:35]
	v_mfma_f32_16x16x32_bf16 v[20:23], v[150:153], v[212:215], v[20:23]
	v_mfma_f32_16x16x32_bf16 v[16:19], v[158:161], v[212:215], v[16:19]
	s_setprio 0
	s_setprio 1
	v_mfma_f32_16x16x32_bf16 v[44:47], v[162:165], v[178:181], v[44:47]
	v_mfma_f32_16x16x32_bf16 v[40:43], v[170:173], v[178:181], v[40:43]
	v_mfma_f32_16x16x32_bf16 v[28:31], v[162:165], v[192:195], v[28:31]
	v_mfma_f32_16x16x32_bf16 v[24:27], v[170:173], v[192:195], v[24:27]
	v_mfma_f32_16x16x32_bf16 v[12:15], v[162:165], v[200:203], v[12:15]
	v_mfma_f32_16x16x32_bf16 v[8:11], v[170:173], v[200:203], v[8:11]
	v_mfma_f32_16x16x32_bf16 v[4:7], v[162:165], v[208:211], v[4:7]
	v_mfma_f32_16x16x32_bf16 v[0:3], v[170:173], v[208:211], v[0:3]
	v_mfma_f32_16x16x32_bf16 v[44:47], v[166:169], v[188:191], v[44:47]
	v_mfma_f32_16x16x32_bf16 v[40:43], v[174:177], v[188:191], v[40:43]
	v_mfma_f32_16x16x32_bf16 v[28:31], v[166:169], v[196:199], v[28:31]
	v_mfma_f32_16x16x32_bf16 v[24:27], v[174:177], v[196:199], v[24:27]
	v_mfma_f32_16x16x32_bf16 v[12:15], v[166:169], v[204:207], v[12:15]
	v_mfma_f32_16x16x32_bf16 v[8:11], v[174:177], v[204:207], v[8:11]
	v_mfma_f32_16x16x32_bf16 v[4:7], v[166:169], v[212:215], v[4:7]
	v_mfma_f32_16x16x32_bf16 v[0:3], v[174:177], v[212:215], v[0:3]
	s_setprio 0
	s_add_i32 s81, s81, 2
	s_add_u32 s36, s36, 0x100
	s_addc_u32 s37, s37, 0
	s_add_u32 s79, s79, 0x100
	s_addc_u32 s80, s80, 0
	s_cmp_gt_u32 s81, 5
	s_barrier
	s_cbranch_scc0 .LBB0_445

; #define G_STAGE(bufoff, gbase, voff) do { _Pragma("unroll") for (int _i = 0; _i < 2; ++_i) \
;         __builtin_amdgcn_global_load_lds((const unsigned*)((const char*)(gbase) + voff[_i]), (LAS unsigned*)(lds + (bufoff) + ldsw + _i * 8192), 16, 0, 0); } while (0)
; #define G_LDA(dst, b, h) do { _Pragma("unroll") for (int m = 0; m < 4; ++m) _Pragma("unroll") for (int k = 0; k < 2; ++k) dst[m][k] = *(const LAS bf16x8*)(lds + G_SA(b, h) + aoff + m * 2048 + k * 1024); } while (0)
; #define G_LDB(dst, b, h) do { _Pragma("unroll") for (int n = 0; n < 2; ++n) _Pragma("unroll") for (int k = 0; k < 2; ++k) dst[n][k] = *(const LAS bf16x8*)(lds + G_SB(b, h) + boff + n * 2048 + k * 1024); } while (0)
; #define G_MMA(ai, bj, At_, Bt_) do { __builtin_amdgcn_s_setprio(1); _Pragma("unroll") for (int m = 0; m < 4; ++m) _Pragma("unroll") for (int n = 0; n < 2; ++n) _Pragma("unroll") for (int k = 0; k < 2; ++k) \
;         acc[ai][bj][m][n] = __builtin_amdgcn_mfma_f32_16x16x32_bf16(Bt_[n][k], At_[m][k], acc[ai][bj][m][n], 0, 0, 0); __builtin_amdgcn_s_setprio(0); } while (0)
; #define WAIT_V(n) asm volatile("s_waitcnt vmcnt(" #n ")" ::: "memory")
; #define WAIT_L(n) asm volatile("s_waitcnt lgkmcnt(" #n ")" ::: "memory")
; #define BAR __builtin_amdgcn_s_barrier()
; #define SCHED __builtin_amdgcn_sched_barrier(0)
; template <class Get, class Epi>
; DI void gemm_loop(int ntiles, int ld, char* shm, const Get& get, const Epi& epi) {
;     ...
;             G_LDB(B0, 0, 0); G_LDB(B1, 0, 1); SCHED; G_LDA(At, 0, 0); G_STAGE(G_SA(1, 1), a1 + hstep, voffA);
;             WAIT_V(8); WAIT_L(0); BAR; G_MMA(0, 0, At, B0); G_MMA(0, 1, At, B1); BAR; SCHED;
;             G_LDA(At, 0, 1); G_STAGE(G_SB(0, 0), b2, voffB); G_STAGE(G_SB(0, 1), b2 + hstep, voffB); G_STAGE(G_SA(0, 0), a2, voffA);
;             WAIT_V(8); WAIT_L(0); BAR; G_MMA(1, 0, At, B0); G_MMA(1, 1, At, B1); BAR; SCHED;
.Lpeel_528:
	ds_read_b128 v[128:131], v177
	ds_read_b128 v[132:135], v177 offset:1024
	ds_read_b128 v[136:139], v177 offset:2048
	ds_read_b128 v[140:143], v177 offset:3072
	ds_read_b128 v[144:147], v178
	ds_read_b128 v[148:151], v178 offset:1024
	ds_read_b128 v[164:167], v178 offset:2048
	ds_read_b128 v[168:171], v178 offset:3072
	s_add_i32 s83, s14, 2
	s_add_u32 s15, s44, 0xfffc0080
	s_addc_u32 s46, s45, -1
	s_cmp_eq_u32 s54, s14
	s_cselect_b32 s14, s43, s55
	s_cselect_b32 s47, s3, s46
	s_cselect_b32 s46, s35, s15
	s_cselect_b32 s15, s37, s82
	v_lshl_add_u64 v[184:185], s[44:45], 0, v[160:161]
	s_add_i32 m0, s57, 0xc000
	ds_read_b128 v[172:175], v179
	ds_read_b128 v[180:183], v179 offset:1024
	ds_read_b128 v[188:191], v179 offset:2048
	ds_read_b128 v[192:195], v179 offset:3072
	ds_read_b128 v[196:199], v179 offset:4096
	ds_read_b128 v[200:203], v179 offset:5120
	ds_read_b128 v[204:207], v179 offset:6144
	ds_read_b128 v[208:211], v179 offset:7168
	global_load_lds_dwordx4 v[184:185], off
	v_lshl_add_u64 v[184:185], s[44:45], 0, v[162:163]
	s_add_i32 m0, s57, 0xe000
	s_nop 0
	global_load_lds_dwordx4 v[184:185], off
	s_waitcnt vmcnt(8)
	s_waitcnt lgkmcnt(0)
	s_barrier
	s_setprio 1
	s_waitcnt lgkmcnt(0)
	v_mfma_f32_16x16x32_bf16 v[124:127], v[128:131], v[172:175], 0
	v_mfma_f32_16x16x32_bf16 v[120:123], v[136:139], v[172:175], 0
	v_mfma_f32_16x16x32_bf16 v[116:119], v[128:131], v[188:191], 0
	v_mfma_f32_16x16x32_bf16 v[112:115], v[136:139], v[188:191], 0
	v_mfma_f32_16x16x32_bf16 v[108:111], v[128:131], v[196:199], 0
	v_mfma_f32_16x16x32_bf16 v[104:107], v[136:139], v[196:199], 0
	v_mfma_f32_16x16x32_bf16 v[100:103], v[128:131], v[204:207], 0
	v_mfma_f32_16x16x32_bf16 v[96:99], v[136:139], v[204:207], 0
	v_mfma_f32_16x16x32_bf16 v[124:127], v[132:135], v[180:183], v[124:127]
	v_mfma_f32_16x16x32_bf16 v[120:123], v[140:143], v[180:183], v[120:123]
	v_mfma_f32_16x16x32_bf16 v[116:119], v[132:135], v[192:195], v[116:119]
	v_mfma_f32_16x16x32_bf16 v[112:115], v[140:143], v[192:195], v[112:115]
	v_mfma_f32_16x16x32_bf16 v[108:111], v[132:135], v[200:203], v[108:111]
	v_mfma_f32_16x16x32_bf16 v[104:107], v[140:143], v[200:203], v[104:107]
	v_mfma_f32_16x16x32_bf16 v[100:103], v[132:135], v[208:211], v[100:103]
	v_mfma_f32_16x16x32_bf16 v[96:99], v[140:143], v[208:211], v[96:99]
	s_setprio 0
	s_setprio 1
	v_mfma_f32_16x16x32_bf16 v[60:63], v[144:147], v[172:175], 0
	v_mfma_f32_16x16x32_bf16 v[56:59], v[164:167], v[172:175], 0
	v_mfma_f32_16x16x32_bf16 v[52:55], v[144:147], v[188:191], 0
	v_mfma_f32_16x16x32_bf16 v[48:51], v[164:167], v[188:191], 0
	v_mfma_f32_16x16x32_bf16 v[44:47], v[144:147], v[196:199], 0
	v_mfma_f32_16x16x32_bf16 v[40:43], v[164:167], v[196:199], 0
	v_mfma_f32_16x16x32_bf16 v[36:39], v[144:147], v[204:207], 0
	v_mfma_f32_16x16x32_bf16 v[32:35], v[164:167], v[204:207], 0
	v_mfma_f32_16x16x32_bf16 v[60:63], v[148:151], v[180:183], v[60:63]
	v_mfma_f32_16x16x32_bf16 v[56:59], v[168:171], v[180:183], v[56:59]
	v_mfma_f32_16x16x32_bf16 v[52:55], v[148:151], v[192:195], v[52:55]
	v_mfma_f32_16x16x32_bf16 v[48:51], v[168:171], v[192:195], v[48:51]
	v_mfma_f32_16x16x32_bf16 v[44:47], v[148:151], v[200:203], v[44:47]
	v_mfma_f32_16x16x32_bf16 v[40:43], v[168:171], v[200:203], v[40:43]
	v_mfma_f32_16x16x32_bf16 v[36:39], v[148:151], v[208:211], v[36:39]
	v_mfma_f32_16x16x32_bf16 v[32:35], v[168:171], v[208:211], v[32:35]
	s_setprio 0
	s_add_i32 s84, s78, s56
	v_lshl_add_u64 v[184:185], s[14:15], 0, v[154:155]
	s_mov_b32 m0, s84
	s_barrier
	ds_read_b128 v[172:175], v179 offset:16384
	ds_read_b128 v[180:183], v179 offset:17408
	ds_read_b128 v[188:191], v179 offset:18432
	ds_read_b128 v[192:195], v179 offset:19456
	ds_read_b128 v[196:199], v179 offset:20480
	ds_read_b128 v[200:203], v179 offset:21504
	ds_read_b128 v[204:207], v179 offset:22528
	ds_read_b128 v[208:211], v179 offset:23552
	global_load_lds_dwordx4 v[184:185], off
	s_add_i32 m0, s84, 0x2000
	s_add_u32 s84, s14, 0x40000
	v_lshl_add_u64 v[186:187], s[14:15], 0, v[158:159]
	s_addc_u32 s85, s15, 0
	s_add_i32 s86, s79, s56
	global_load_lds_dwordx4 v[186:187], off
	v_lshl_add_u64 v[212:213], s[84:85], 0, v[154:155]
	s_mov_b32 m0, s86
	v_lshl_add_u64 v[214:215], s[46:47], 0, v[156:157]
	global_load_lds_dwordx4 v[212:213], off
	v_lshl_add_u64 v[212:213], s[84:85], 0, v[158:159]
	s_add_i32 m0, s86, 0x2000
	s_nop 0
	global_load_lds_dwordx4 v[212:213], off
	v_lshl_add_u64 v[212:213], s[46:47], 0, v[152:153]
	s_mov_b32 m0, s57
	s_nop 0
	global_load_lds_dwordx4 v[212:213], off
	s_mov_b32 m0, s58
	s_nop 0
	global_load_lds_dwordx4 v[214:215], off
	s_waitcnt vmcnt(8)
	s_waitcnt lgkmcnt(0)
	s_barrier
; #define G_STAGE(bufoff, gbase, voff) do { _Pragma("unroll") for (int _i = 0; _i < 2; ++_i) \
;         __builtin_amdgcn_global_load_lds((const unsigned*)((const char*)(gbase) + voff[_i]), (LAS unsigned*)(lds + (bufoff) + ldsw + _i * 8192), 16, 0, 0); } while (0)
; #define G_LDA(dst, b, h) do { _Pragma("unroll") for (int m = 0; m < 4; ++m) _Pragma("unroll") for (int k = 0; k < 2; ++k) dst[m][k] = *(const LAS bf16x8*)(lds + G_SA(b, h) + aoff + m * 2048 + k * 1024); } while (0)
; #define G_LDB(dst, b, h) do { _Pragma("unroll") for (int n = 0; n < 2; ++n) _Pragma("unroll") for (int k = 0; k < 2; ++k) dst[n][k] = *(const LAS bf16x8*)(lds + G_SB(b, h) + boff + n * 2048 + k * 1024); } while (0)
; #define G_MMA(ai, bj, At_, Bt_) do { __builtin_amdgcn_s_setprio(1); _Pragma("unroll") for (int m = 0; m < 4; ++m) _Pragma("unroll") for (int n = 0; n < 2; ++n) _Pragma("unroll") for (int k = 0; k < 2; ++k) \
;         acc[ai][bj][m][n] = __builtin_amdgcn_mfma_f32_16x16x32_bf16(Bt_[n][k], At_[m][k], acc[ai][bj][m][n], 0, 0, 0); __builtin_amdgcn_s_setprio(0); } while (0)
; #define WAIT_V(n) asm volatile("s_waitcnt vmcnt(" #n ")" ::: "memory")
; #define WAIT_L(n) asm volatile("s_waitcnt lgkmcnt(" #n ")" ::: "memory")
; #define BAR __builtin_amdgcn_s_barrier()
; #define SCHED __builtin_amdgcn_sched_barrier(0)
; template <class Get, class Epi>
; DI void gemm_loop(int ntiles, int ld, char* shm, const Get& get, const Epi& epi) {
;     ...
;             WAIT_V(8); WAIT_L(0); BAR; G_MMA(1, 0, At, B0); G_MMA(1, 1, At, B1); BAR; SCHED;
;             G_LDB(B0, 1, 0); G_LDB(B1, 1, 1); SCHED; G_LDA(At, 1, 0); G_STAGE(G_SA(0, 1), a2 + hstep, voffA);
;             WAIT_V(8); WAIT_L(0); BAR; G_MMA(0, 0, At, B0); G_MMA(0, 1, At, B1); BAR; SCHED;
;             G_LDA(At, 1, 1); G_STAGE(G_SB(1, 0), b3, voffB); G_STAGE(G_SB(1, 1), b3 + hstep, voffB); G_STAGE(G_SA(1, 0), a3, voffA);
	s_setprio 1
	s_waitcnt lgkmcnt(0)
	v_mfma_f32_16x16x32_bf16 v[92:95], v[128:131], v[172:175], 0
	v_mfma_f32_16x16x32_bf16 v[88:91], v[136:139], v[172:175], 0
	v_mfma_f32_16x16x32_bf16 v[84:87], v[128:131], v[188:191], 0
	v_mfma_f32_16x16x32_bf16 v[80:83], v[136:139], v[188:191], 0
	v_mfma_f32_16x16x32_bf16 v[76:79], v[128:131], v[196:199], 0
	v_mfma_f32_16x16x32_bf16 v[72:75], v[136:139], v[196:199], 0
	v_mfma_f32_16x16x32_bf16 v[68:71], v[128:131], v[204:207], 0
	v_mfma_f32_16x16x32_bf16 v[64:67], v[136:139], v[204:207], 0
	v_mfma_f32_16x16x32_bf16 v[92:95], v[132:135], v[180:183], v[92:95]
	v_mfma_f32_16x16x32_bf16 v[88:91], v[140:143], v[180:183], v[88:91]
	v_mfma_f32_16x16x32_bf16 v[84:87], v[132:135], v[192:195], v[84:87]
	v_mfma_f32_16x16x32_bf16 v[80:83], v[140:143], v[192:195], v[80:83]
	v_mfma_f32_16x16x32_bf16 v[76:79], v[132:135], v[200:203], v[76:79]
	v_mfma_f32_16x16x32_bf16 v[72:75], v[140:143], v[200:203], v[72:75]
	v_mfma_f32_16x16x32_bf16 v[68:71], v[132:135], v[208:211], v[68:71]
	v_mfma_f32_16x16x32_bf16 v[64:67], v[140:143], v[208:211], v[64:67]
	s_setprio 0
	s_setprio 1
	v_mfma_f32_16x16x32_bf16 v[28:31], v[144:147], v[172:175], 0
	v_mfma_f32_16x16x32_bf16 v[24:27], v[164:167], v[172:175], 0
	v_mfma_f32_16x16x32_bf16 v[20:23], v[144:147], v[188:191], 0
	v_mfma_f32_16x16x32_bf16 v[16:19], v[164:167], v[188:191], 0
	v_mfma_f32_16x16x32_bf16 v[12:15], v[144:147], v[196:199], 0
	v_mfma_f32_16x16x32_bf16 v[8:11], v[164:167], v[196:199], 0
	v_mfma_f32_16x16x32_bf16 v[4:7], v[144:147], v[204:207], 0
	v_mfma_f32_16x16x32_bf16 v[0:3], v[164:167], v[204:207], 0
	v_mfma_f32_16x16x32_bf16 v[28:31], v[148:151], v[180:183], v[28:31]
	v_mfma_f32_16x16x32_bf16 v[24:27], v[168:171], v[180:183], v[24:27]
	v_mfma_f32_16x16x32_bf16 v[20:23], v[148:151], v[192:195], v[20:23]
	v_mfma_f32_16x16x32_bf16 v[16:19], v[168:171], v[192:195], v[16:19]
	v_mfma_f32_16x16x32_bf16 v[12:15], v[148:151], v[200:203], v[12:15]
	v_mfma_f32_16x16x32_bf16 v[8:11], v[168:171], v[200:203], v[8:11]
	v_mfma_f32_16x16x32_bf16 v[4:7], v[148:151], v[208:211], v[4:7]
	v_mfma_f32_16x16x32_bf16 v[0:3], v[168:171], v[208:211], v[0:3]
	s_setprio 0
	s_add_i32 s84, 0, 0x18000
	s_add_i32 s85, 0, 0x1c000
	v_add_u32_e32 v140, s84, v176
	s_barrier
	v_add_u32_e32 v168, s85, v176
	ds_read_b128 v[128:131], v140
	ds_read_b128 v[132:135], v140 offset:1024
	ds_read_b128 v[136:139], v140 offset:2048
	ds_read_b128 v[140:143], v140 offset:3072
	ds_read_b128 v[144:147], v168
	ds_read_b128 v[148:151], v168 offset:1024
	ds_read_b128 v[164:167], v168 offset:2048
	ds_read_b128 v[168:171], v168 offset:3072
	s_add_u32 s46, s46, 0x40000
	s_addc_u32 s47, s47, 0
	s_mov_b32 m0, s59
	v_lshl_add_u64 v[216:217], s[46:47], 0, v[152:153]
	ds_read_b128 v[172:175], v179 offset:32768
	ds_read_b128 v[180:183], v179 offset:33792
	ds_read_b128 v[188:191], v179 offset:34816
	ds_read_b128 v[192:195], v179 offset:35840
	ds_read_b128 v[196:199], v179 offset:36864
	ds_read_b128 v[200:203], v179 offset:37888
	ds_read_b128 v[204:207], v179 offset:38912
	ds_read_b128 v[208:211], v179 offset:39936
	global_load_lds_dwordx4 v[216:217], off
	v_lshl_add_u64 v[216:217], s[46:47], 0, v[156:157]
	s_mov_b32 m0, s72
	s_nop 0
	global_load_lds_dwordx4 v[216:217], off
	s_waitcnt vmcnt(8)
	s_waitcnt lgkmcnt(0)
	s_barrier
	s_setprio 1
	s_waitcnt lgkmcnt(0)
	v_mfma_f32_16x16x32_bf16 v[124:127], v[128:131], v[172:175], v[124:127]
	v_mfma_f32_16x16x32_bf16 v[120:123], v[136:139], v[172:175], v[120:123]
	v_mfma_f32_16x16x32_bf16 v[116:119], v[128:131], v[188:191], v[116:119]
	v_mfma_f32_16x16x32_bf16 v[112:115], v[136:139], v[188:191], v[112:115]
	v_mfma_f32_16x16x32_bf16 v[108:111], v[128:131], v[196:199], v[108:111]
	v_mfma_f32_16x16x32_bf16 v[104:107], v[136:139], v[196:199], v[104:107]
	v_mfma_f32_16x16x32_bf16 v[100:103], v[128:131], v[204:207], v[100:103]
	v_mfma_f32_16x16x32_bf16 v[96:99], v[136:139], v[204:207], v[96:99]
	v_mfma_f32_16x16x32_bf16 v[124:127], v[132:135], v[180:183], v[124:127]
	v_mfma_f32_16x16x32_bf16 v[120:123], v[140:143], v[180:183], v[120:123]
	v_mfma_f32_16x16x32_bf16 v[116:119], v[132:135], v[192:195], v[116:119]
	v_mfma_f32_16x16x32_bf16 v[112:115], v[140:143], v[192:195], v[112:115]
	v_mfma_f32_16x16x32_bf16 v[108:111], v[132:135], v[200:203], v[108:111]
	v_mfma_f32_16x16x32_bf16 v[104:107], v[140:143], v[200:203], v[104:107]
	v_mfma_f32_16x16x32_bf16 v[100:103], v[132:135], v[208:211], v[100:103]
	v_mfma_f32_16x16x32_bf16 v[96:99], v[140:143], v[208:211], v[96:99]
	s_setprio 0
	s_setprio 1
	v_mfma_f32_16x16x32_bf16 v[60:63], v[144:147], v[172:175], v[60:63]
	v_mfma_f32_16x16x32_bf16 v[56:59], v[164:167], v[172:175], v[56:59]
	v_mfma_f32_16x16x32_bf16 v[52:55], v[144:147], v[188:191], v[52:55]
	v_mfma_f32_16x16x32_bf16 v[48:51], v[164:167], v[188:191], v[48:51]
	v_mfma_f32_16x16x32_bf16 v[44:47], v[144:147], v[196:199], v[44:47]
	v_mfma_f32_16x16x32_bf16 v[40:43], v[164:167], v[196:199], v[40:43]
	v_mfma_f32_16x16x32_bf16 v[36:39], v[144:147], v[204:207], v[36:39]
	v_mfma_f32_16x16x32_bf16 v[32:35], v[164:167], v[204:207], v[32:35]
	v_mfma_f32_16x16x32_bf16 v[60:63], v[148:151], v[180:183], v[60:63]
	v_mfma_f32_16x16x32_bf16 v[56:59], v[168:171], v[180:183], v[56:59]
	v_mfma_f32_16x16x32_bf16 v[52:55], v[148:151], v[192:195], v[52:55]
	v_mfma_f32_16x16x32_bf16 v[48:51], v[168:171], v[192:195], v[48:51]
	v_mfma_f32_16x16x32_bf16 v[44:47], v[148:151], v[200:203], v[44:47]
	v_mfma_f32_16x16x32_bf16 v[40:43], v[168:171], v[200:203], v[40:43]
	v_mfma_f32_16x16x32_bf16 v[36:39], v[148:151], v[208:211], v[36:39]
	v_mfma_f32_16x16x32_bf16 v[32:35], v[168:171], v[208:211], v[32:35]
	s_setprio 0
	s_add_i32 s46, s84, s56
	v_lshl_add_u64 v[184:185], v[184:185], 0, s[10:11]
	s_mov_b32 m0, s46
	s_barrier
; #define G_STAGE(bufoff, gbase, voff) do { _Pragma("unroll") for (int _i = 0; _i < 2; ++_i) \
;         __builtin_amdgcn_global_load_lds((const unsigned*)((const char*)(gbase) + voff[_i]), (LAS unsigned*)(lds + (bufoff) + ldsw + _i * 8192), 16, 0, 0); } while (0)
; #define G_LDA(dst, b, h) do { _Pragma("unroll") for (int m = 0; m < 4; ++m) _Pragma("unroll") for (int k = 0; k < 2; ++k) dst[m][k] = *(const LAS bf16x8*)(lds + G_SA(b, h) + aoff + m * 2048 + k * 1024); } while (0)
; #define G_LDB(dst, b, h) do { _Pragma("unroll") for (int n = 0; n < 2; ++n) _Pragma("unroll") for (int k = 0; k < 2; ++k) dst[n][k] = *(const LAS bf16x8*)(lds + G_SB(b, h) + boff + n * 2048 + k * 1024); } while (0)
; #define G_MMA(ai, bj, At_, Bt_) do { __builtin_amdgcn_s_setprio(1); _Pragma("unroll") for (int m = 0; m < 4; ++m) _Pragma("unroll") for (int n = 0; n < 2; ++n) _Pragma("unroll") for (int k = 0; k < 2; ++k) \
;         acc[ai][bj][m][n] = __builtin_amdgcn_mfma_f32_16x16x32_bf16(Bt_[n][k], At_[m][k], acc[ai][bj][m][n], 0, 0, 0); __builtin_amdgcn_s_setprio(0); } while (0)
; #define WAIT_V(n) asm volatile("s_waitcnt vmcnt(" #n ")" ::: "memory")
; #define WAIT_L(n) asm volatile("s_waitcnt lgkmcnt(" #n ")" ::: "memory")
; #define BAR __builtin_amdgcn_s_barrier()
; #define SCHED __builtin_amdgcn_sched_barrier(0)
; template <class Get, class Epi>
; DI void gemm_loop(int ntiles, int ld, char* shm, const Get& get, const Epi& epi) {
;     ...
;             G_LDB(B0, 0, 0); G_LDB(B1, 0, 1); SCHED; G_LDA(At, 0, 0); G_STAGE(G_SA(1, 1), a1 + hstep, voffA);
;             WAIT_V(8); WAIT_L(0); BAR; G_MMA(0, 0, At, B0); G_MMA(0, 1, At, B1); BAR; SCHED;
;             G_LDA(At, 0, 1); G_STAGE(G_SB(0, 0), b2, voffB); G_STAGE(G_SB(0, 1), b2 + hstep, voffB); G_STAGE(G_SA(0, 0), a2, voffA);
;             WAIT_V(8); WAIT_L(0); BAR; G_MMA(1, 0, At, B0); G_MMA(1, 1, At, B1); BAR; SCHED;
;             G_LDB(B0, 1, 0); G_LDB(B1, 1, 1); SCHED; G_LDA(At, 1, 0); G_STAGE(G_SA(0, 1), a2 + hstep, voffA);
;             WAIT_V(8); WAIT_L(0); BAR; G_MMA(0, 0, At, B0); G_MMA(0, 1, At, B1); BAR; SCHED;
;             G_LDA(At, 1, 1); G_STAGE(G_SB(1, 0), b3, voffB); G_STAGE(G_SB(1, 1), b3 + hstep, voffB); G_STAGE(G_SA(1, 0), a3, voffA);
;             WAIT_V(8); WAIT_L(0); BAR; G_MMA(1, 0, At, B0); G_MMA(1, 1, At, B1); BAR; SCHED;
	ds_read_b128 v[172:175], v179 offset:49152
	ds_read_b128 v[180:183], v179 offset:50176
	ds_read_b128 v[188:191], v179 offset:51200
	ds_read_b128 v[192:195], v179 offset:52224
	ds_read_b128 v[196:199], v179 offset:53248
	ds_read_b128 v[200:203], v179 offset:54272
	ds_read_b128 v[204:207], v179 offset:55296
	ds_read_b128 v[208:211], v179 offset:56320
	global_load_lds_dwordx4 v[184:185], off
	s_add_i32 m0, s46, 0x2000
	s_add_u32 s14, s14, 0x40080
	v_lshl_add_u64 v[184:185], v[186:187], 0, s[10:11]
	s_addc_u32 s15, s15, 0
	s_add_i32 s46, s85, s56
	global_load_lds_dwordx4 v[184:185], off
	v_lshl_add_u64 v[184:185], s[14:15], 0, v[154:155]
	s_mov_b32 m0, s46
	s_nop 0
	global_load_lds_dwordx4 v[184:185], off
	v_lshl_add_u64 v[184:185], s[14:15], 0, v[158:159]
	s_add_i32 m0, s46, 0x2000
	s_nop 0
	global_load_lds_dwordx4 v[184:185], off
	v_lshl_add_u64 v[184:185], v[212:213], 0, s[10:11]
	s_mov_b32 m0, s75
	s_nop 0
	global_load_lds_dwordx4 v[184:185], off
	v_lshl_add_u64 v[184:185], v[214:215], 0, s[10:11]
	s_mov_b32 m0, s76
	s_nop 0
	global_load_lds_dwordx4 v[184:185], off
	s_waitcnt vmcnt(8)
	s_waitcnt lgkmcnt(0)
	s_barrier
	s_setprio 1
	s_waitcnt lgkmcnt(0)
	v_mfma_f32_16x16x32_bf16 v[92:95], v[128:131], v[172:175], v[92:95]
	v_mfma_f32_16x16x32_bf16 v[88:91], v[136:139], v[172:175], v[88:91]
	v_mfma_f32_16x16x32_bf16 v[84:87], v[128:131], v[188:191], v[84:87]
	v_mfma_f32_16x16x32_bf16 v[80:83], v[136:139], v[188:191], v[80:83]
	v_mfma_f32_16x16x32_bf16 v[76:79], v[128:131], v[196:199], v[76:79]
	v_mfma_f32_16x16x32_bf16 v[72:75], v[136:139], v[196:199], v[72:75]
	v_mfma_f32_16x16x32_bf16 v[68:71], v[128:131], v[204:207], v[68:71]
	v_mfma_f32_16x16x32_bf16 v[64:67], v[136:139], v[204:207], v[64:67]
	v_mfma_f32_16x16x32_bf16 v[92:95], v[132:135], v[180:183], v[92:95]
	v_mfma_f32_16x16x32_bf16 v[88:91], v[140:143], v[180:183], v[88:91]
	v_mfma_f32_16x16x32_bf16 v[84:87], v[132:135], v[192:195], v[84:87]
	v_mfma_f32_16x16x32_bf16 v[80:83], v[140:143], v[192:195], v[80:83]
	v_mfma_f32_16x16x32_bf16 v[76:79], v[132:135], v[200:203], v[76:79]
	v_mfma_f32_16x16x32_bf16 v[72:75], v[140:143], v[200:203], v[72:75]
	v_mfma_f32_16x16x32_bf16 v[68:71], v[132:135], v[208:211], v[68:71]
	v_mfma_f32_16x16x32_bf16 v[64:67], v[140:143], v[208:211], v[64:67]
	s_setprio 0
	s_setprio 1
	v_mfma_f32_16x16x32_bf16 v[28:31], v[144:147], v[172:175], v[28:31]
	v_mfma_f32_16x16x32_bf16 v[24:27], v[164:167], v[172:175], v[24:27]
	v_mfma_f32_16x16x32_bf16 v[20:23], v[144:147], v[188:191], v[20:23]
	v_mfma_f32_16x16x32_bf16 v[16:19], v[164:167], v[188:191], v[16:19]
	v_mfma_f32_16x16x32_bf16 v[12:15], v[144:147], v[196:199], v[12:15]
	v_mfma_f32_16x16x32_bf16 v[8:11], v[164:167], v[196:199], v[8:11]
	v_mfma_f32_16x16x32_bf16 v[4:7], v[144:147], v[204:207], v[4:7]
	v_mfma_f32_16x16x32_bf16 v[0:3], v[164:167], v[204:207], v[0:3]
	v_mfma_f32_16x16x32_bf16 v[28:31], v[148:151], v[180:183], v[28:31]
	v_mfma_f32_16x16x32_bf16 v[24:27], v[168:171], v[180:183], v[24:27]
	v_mfma_f32_16x16x32_bf16 v[20:23], v[148:151], v[192:195], v[20:23]
	v_mfma_f32_16x16x32_bf16 v[16:19], v[168:171], v[192:195], v[16:19]
	v_mfma_f32_16x16x32_bf16 v[12:15], v[148:151], v[200:203], v[12:15]
	v_mfma_f32_16x16x32_bf16 v[8:11], v[168:171], v[200:203], v[8:11]
	v_mfma_f32_16x16x32_bf16 v[4:7], v[148:151], v[208:211], v[4:7]
	v_mfma_f32_16x16x32_bf16 v[0:3], v[168:171], v[208:211], v[0:3]
	s_setprio 0
	s_add_u32 s44, s44, 0x100
	s_addc_u32 s45, s45, 0
	s_add_u32 s55, s55, 0x100
	s_addc_u32 s82, s82, 0
	s_cmp_ge_u32 s83, s51
	s_mov_b32 s14, s83
	s_barrier
	s_cbranch_scc0 .LBB0_528
	s_branch .Lpost_528
.LBB0_528:
	ds_read_b128 v[128:131], v177
	ds_read_b128 v[132:135], v177 offset:1024
	ds_read_b128 v[136:139], v177 offset:2048
	ds_read_b128 v[140:143], v177 offset:3072
	ds_read_b128 v[144:147], v178
	ds_read_b128 v[148:151], v178 offset:1024
	ds_read_b128 v[164:167], v178 offset:2048
	ds_read_b128 v[168:171], v178 offset:3072
	s_add_i32 s83, s14, 2
	s_add_u32 s15, s44, 0xfffc0080
	s_addc_u32 s46, s45, -1
	s_cmp_eq_u32 s54, s14
	s_cselect_b32 s14, s43, s55
	s_cselect_b32 s47, s3, s46
	s_cselect_b32 s46, s35, s15
	s_cselect_b32 s15, s37, s82
	v_lshl_add_u64 v[184:185], s[44:45], 0, v[160:161]
	s_add_i32 m0, s57, 0xc000
	ds_read_b128 v[172:175], v179
	ds_read_b128 v[180:183], v179 offset:1024
	ds_read_b128 v[188:191], v179 offset:2048
	ds_read_b128 v[192:195], v179 offset:3072
	ds_read_b128 v[196:199], v179 offset:4096
	ds_read_b128 v[200:203], v179 offset:5120
	ds_read_b128 v[204:207], v179 offset:6144
	ds_read_b128 v[208:211], v179 offset:7168
	global_load_lds_dwordx4 v[184:185], off
	v_lshl_add_u64 v[184:185], s[44:45], 0, v[162:163]
	s_add_i32 m0, s57, 0xe000
	s_nop 0
	global_load_lds_dwordx4 v[184:185], off
	s_waitcnt vmcnt(8)
	s_waitcnt lgkmcnt(0)
	s_barrier
; #define G_STAGE(bufoff, gbase, voff) do { _Pragma("unroll") for (int _i = 0; _i < 2; ++_i) \
;         __builtin_amdgcn_global_load_lds((const unsigned*)((const char*)(gbase) + voff[_i]), (LAS unsigned*)(lds + (bufoff) + ldsw + _i * 8192), 16, 0, 0); } while (0)
; #define G_LDA(dst, b, h) do { _Pragma("unroll") for (int m = 0; m < 4; ++m) _Pragma("unroll") for (int k = 0; k < 2; ++k) dst[m][k] = *(const LAS bf16x8*)(lds + G_SA(b, h) + aoff + m * 2048 + k * 1024); } while (0)
; #define G_LDB(dst, b, h) do { _Pragma("unroll") for (int n = 0; n < 2; ++n) _Pragma("unroll") for (int k = 0; k < 2; ++k) dst[n][k] = *(const LAS bf16x8*)(lds + G_SB(b, h) + boff + n * 2048 + k * 1024); } while (0)
; #define G_MMA(ai, bj, At_, Bt_) do { __builtin_amdgcn_s_setprio(1); _Pragma("unroll") for (int m = 0; m < 4; ++m) _Pragma("unroll") for (int n = 0; n < 2; ++n) _Pragma("unroll") for (int k = 0; k < 2; ++k) \
;         acc[ai][bj][m][n] = __builtin_amdgcn_mfma_f32_16x16x32_bf16(Bt_[n][k], At_[m][k], acc[ai][bj][m][n], 0, 0, 0); __builtin_amdgcn_s_setprio(0); } while (0)
; #define WAIT_V(n) asm volatile("s_waitcnt vmcnt(" #n ")" ::: "memory")
; #define WAIT_L(n) asm volatile("s_waitcnt lgkmcnt(" #n ")" ::: "memory")
; #define BAR __builtin_amdgcn_s_barrier()
; #define SCHED __builtin_amdgcn_sched_barrier(0)
; template <class Get, class Epi>
; DI void gemm_loop(int ntiles, int ld, char* shm, const Get& get, const Epi& epi) {
;     ...
;             WAIT_V(8); WAIT_L(0); BAR; G_MMA(0, 0, At, B0); G_MMA(0, 1, At, B1); BAR; SCHED;
;             G_LDA(At, 0, 1); G_STAGE(G_SB(0, 0), b2, voffB); G_STAGE(G_SB(0, 1), b2 + hstep, voffB); G_STAGE(G_SA(0, 0), a2, voffA);
;             WAIT_V(8); WAIT_L(0); BAR; G_MMA(1, 0, At, B0); G_MMA(1, 1, At, B1); BAR; SCHED;
;             G_LDB(B0, 1, 0); G_LDB(B1, 1, 1); SCHED; G_LDA(At, 1, 0); G_STAGE(G_SA(0, 1), a2 + hstep, voffA);
	s_setprio 1
	s_waitcnt lgkmcnt(0)
	v_mfma_f32_16x16x32_bf16 v[124:127], v[128:131], v[172:175], v[124:127]
	v_mfma_f32_16x16x32_bf16 v[120:123], v[136:139], v[172:175], v[120:123]
	v_mfma_f32_16x16x32_bf16 v[116:119], v[128:131], v[188:191], v[116:119]
	v_mfma_f32_16x16x32_bf16 v[112:115], v[136:139], v[188:191], v[112:115]
	v_mfma_f32_16x16x32_bf16 v[108:111], v[128:131], v[196:199], v[108:111]
	v_mfma_f32_16x16x32_bf16 v[104:107], v[136:139], v[196:199], v[104:107]
	v_mfma_f32_16x16x32_bf16 v[100:103], v[128:131], v[204:207], v[100:103]
	v_mfma_f32_16x16x32_bf16 v[96:99], v[136:139], v[204:207], v[96:99]
	v_mfma_f32_16x16x32_bf16 v[124:127], v[132:135], v[180:183], v[124:127]
	v_mfma_f32_16x16x32_bf16 v[120:123], v[140:143], v[180:183], v[120:123]
	v_mfma_f32_16x16x32_bf16 v[116:119], v[132:135], v[192:195], v[116:119]
	v_mfma_f32_16x16x32_bf16 v[112:115], v[140:143], v[192:195], v[112:115]
	v_mfma_f32_16x16x32_bf16 v[108:111], v[132:135], v[200:203], v[108:111]
	v_mfma_f32_16x16x32_bf16 v[104:107], v[140:143], v[200:203], v[104:107]
	v_mfma_f32_16x16x32_bf16 v[100:103], v[132:135], v[208:211], v[100:103]
	v_mfma_f32_16x16x32_bf16 v[96:99], v[140:143], v[208:211], v[96:99]
	s_setprio 0
	s_setprio 1
	v_mfma_f32_16x16x32_bf16 v[60:63], v[144:147], v[172:175], v[60:63]
	v_mfma_f32_16x16x32_bf16 v[56:59], v[164:167], v[172:175], v[56:59]
	v_mfma_f32_16x16x32_bf16 v[52:55], v[144:147], v[188:191], v[52:55]
	v_mfma_f32_16x16x32_bf16 v[48:51], v[164:167], v[188:191], v[48:51]
	v_mfma_f32_16x16x32_bf16 v[44:47], v[144:147], v[196:199], v[44:47]
	v_mfma_f32_16x16x32_bf16 v[40:43], v[164:167], v[196:199], v[40:43]
	v_mfma_f32_16x16x32_bf16 v[36:39], v[144:147], v[204:207], v[36:39]
	v_mfma_f32_16x16x32_bf16 v[32:35], v[164:167], v[204:207], v[32:35]
	v_mfma_f32_16x16x32_bf16 v[60:63], v[148:151], v[180:183], v[60:63]
	v_mfma_f32_16x16x32_bf16 v[56:59], v[168:171], v[180:183], v[56:59]
	v_mfma_f32_16x16x32_bf16 v[52:55], v[148:151], v[192:195], v[52:55]
	v_mfma_f32_16x16x32_bf16 v[48:51], v[168:171], v[192:195], v[48:51]
	v_mfma_f32_16x16x32_bf16 v[44:47], v[148:151], v[200:203], v[44:47]
	v_mfma_f32_16x16x32_bf16 v[40:43], v[168:171], v[200:203], v[40:43]
	v_mfma_f32_16x16x32_bf16 v[36:39], v[148:151], v[208:211], v[36:39]
	v_mfma_f32_16x16x32_bf16 v[32:35], v[168:171], v[208:211], v[32:35]
	s_setprio 0
	s_add_i32 s84, s78, s56
	v_lshl_add_u64 v[184:185], s[14:15], 0, v[154:155]
	s_mov_b32 m0, s84
	s_barrier
	ds_read_b128 v[172:175], v179 offset:16384
	ds_read_b128 v[180:183], v179 offset:17408
	ds_read_b128 v[188:191], v179 offset:18432
	ds_read_b128 v[192:195], v179 offset:19456
	ds_read_b128 v[196:199], v179 offset:20480
	ds_read_b128 v[200:203], v179 offset:21504
	ds_read_b128 v[204:207], v179 offset:22528
	ds_read_b128 v[208:211], v179 offset:23552
	global_load_lds_dwordx4 v[184:185], off
	s_add_i32 m0, s84, 0x2000
	s_add_u32 s84, s14, 0x40000
	v_lshl_add_u64 v[186:187], s[14:15], 0, v[158:159]
	s_addc_u32 s85, s15, 0
	s_add_i32 s86, s79, s56
	global_load_lds_dwordx4 v[186:187], off
	v_lshl_add_u64 v[212:213], s[84:85], 0, v[154:155]
	s_mov_b32 m0, s86
	v_lshl_add_u64 v[214:215], s[46:47], 0, v[156:157]
	global_load_lds_dwordx4 v[212:213], off
	v_lshl_add_u64 v[212:213], s[84:85], 0, v[158:159]
	s_add_i32 m0, s86, 0x2000
	s_nop 0
	global_load_lds_dwordx4 v[212:213], off
	v_lshl_add_u64 v[212:213], s[46:47], 0, v[152:153]
	s_mov_b32 m0, s57
	s_nop 0
	global_load_lds_dwordx4 v[212:213], off
	s_mov_b32 m0, s58
	s_nop 0
	global_load_lds_dwordx4 v[214:215], off
	s_waitcnt vmcnt(8)
	s_waitcnt lgkmcnt(0)
	s_barrier
	s_setprio 1
	s_waitcnt lgkmcnt(0)
	v_mfma_f32_16x16x32_bf16 v[92:95], v[128:131], v[172:175], v[92:95]
	v_mfma_f32_16x16x32_bf16 v[88:91], v[136:139], v[172:175], v[88:91]
	v_mfma_f32_16x16x32_bf16 v[84:87], v[128:131], v[188:191], v[84:87]
	v_mfma_f32_16x16x32_bf16 v[80:83], v[136:139], v[188:191], v[80:83]
	v_mfma_f32_16x16x32_bf16 v[76:79], v[128:131], v[196:199], v[76:79]
	v_mfma_f32_16x16x32_bf16 v[72:75], v[136:139], v[196:199], v[72:75]
	v_mfma_f32_16x16x32_bf16 v[68:71], v[128:131], v[204:207], v[68:71]
	v_mfma_f32_16x16x32_bf16 v[64:67], v[136:139], v[204:207], v[64:67]
	v_mfma_f32_16x16x32_bf16 v[92:95], v[132:135], v[180:183], v[92:95]
	v_mfma_f32_16x16x32_bf16 v[88:91], v[140:143], v[180:183], v[88:91]
	v_mfma_f32_16x16x32_bf16 v[84:87], v[132:135], v[192:195], v[84:87]
	v_mfma_f32_16x16x32_bf16 v[80:83], v[140:143], v[192:195], v[80:83]
	v_mfma_f32_16x16x32_bf16 v[76:79], v[132:135], v[200:203], v[76:79]
	v_mfma_f32_16x16x32_bf16 v[72:75], v[140:143], v[200:203], v[72:75]
	v_mfma_f32_16x16x32_bf16 v[68:71], v[132:135], v[208:211], v[68:71]
	v_mfma_f32_16x16x32_bf16 v[64:67], v[140:143], v[208:211], v[64:67]
	s_setprio 0
	s_setprio 1
	v_mfma_f32_16x16x32_bf16 v[28:31], v[144:147], v[172:175], v[28:31]
	v_mfma_f32_16x16x32_bf16 v[24:27], v[164:167], v[172:175], v[24:27]
	v_mfma_f32_16x16x32_bf16 v[20:23], v[144:147], v[188:191], v[20:23]
	v_mfma_f32_16x16x32_bf16 v[16:19], v[164:167], v[188:191], v[16:19]
	v_mfma_f32_16x16x32_bf16 v[12:15], v[144:147], v[196:199], v[12:15]
	v_mfma_f32_16x16x32_bf16 v[8:11], v[164:167], v[196:199], v[8:11]
	v_mfma_f32_16x16x32_bf16 v[4:7], v[144:147], v[204:207], v[4:7]
	v_mfma_f32_16x16x32_bf16 v[0:3], v[164:167], v[204:207], v[0:3]
	v_mfma_f32_16x16x32_bf16 v[28:31], v[148:151], v[180:183], v[28:31]
	v_mfma_f32_16x16x32_bf16 v[24:27], v[168:171], v[180:183], v[24:27]
	v_mfma_f32_16x16x32_bf16 v[20:23], v[148:151], v[192:195], v[20:23]
	v_mfma_f32_16x16x32_bf16 v[16:19], v[168:171], v[192:195], v[16:19]
	v_mfma_f32_16x16x32_bf16 v[12:15], v[148:151], v[200:203], v[12:15]
	v_mfma_f32_16x16x32_bf16 v[8:11], v[168:171], v[200:203], v[8:11]
	v_mfma_f32_16x16x32_bf16 v[4:7], v[148:151], v[208:211], v[4:7]
	v_mfma_f32_16x16x32_bf16 v[0:3], v[168:171], v[208:211], v[0:3]
	s_setprio 0
	s_add_i32 s84, 0, 0x18000
	s_add_i32 s85, 0, 0x1c000
	v_add_u32_e32 v140, s84, v176
	s_barrier
; #define G_STAGE(bufoff, gbase, voff) do { _Pragma("unroll") for (int _i = 0; _i < 2; ++_i) \
;         __builtin_amdgcn_global_load_lds((const unsigned*)((const char*)(gbase) + voff[_i]), (LAS unsigned*)(lds + (bufoff) + ldsw + _i * 8192), 16, 0, 0); } while (0)
; #define G_LDA(dst, b, h) do { _Pragma("unroll") for (int m = 0; m < 4; ++m) _Pragma("unroll") for (int k = 0; k < 2; ++k) dst[m][k] = *(const LAS bf16x8*)(lds + G_SA(b, h) + aoff + m * 2048 + k * 1024); } while (0)
; #define G_LDB(dst, b, h) do { _Pragma("unroll") for (int n = 0; n < 2; ++n) _Pragma("unroll") for (int k = 0; k < 2; ++k) dst[n][k] = *(const LAS bf16x8*)(lds + G_SB(b, h) + boff + n * 2048 + k * 1024); } while (0)
; #define G_MMA(ai, bj, At_, Bt_) do { __builtin_amdgcn_s_setprio(1); _Pragma("unroll") for (int m = 0; m < 4; ++m) _Pragma("unroll") for (int n = 0; n < 2; ++n) _Pragma("unroll") for (int k = 0; k < 2; ++k) \
;         acc[ai][bj][m][n] = __builtin_amdgcn_mfma_f32_16x16x32_bf16(Bt_[n][k], At_[m][k], acc[ai][bj][m][n], 0, 0, 0); __builtin_amdgcn_s_setprio(0); } while (0)
; #define WAIT_V(n) asm volatile("s_waitcnt vmcnt(" #n ")" ::: "memory")
; #define WAIT_L(n) asm volatile("s_waitcnt lgkmcnt(" #n ")" ::: "memory")
; #define BAR __builtin_amdgcn_s_barrier()
; #define SCHED __builtin_amdgcn_sched_barrier(0)
; template <class Get, class Epi>
; DI void gemm_loop(int ntiles, int ld, char* shm, const Get& get, const Epi& epi) {
;     ...
;             G_LDB(B0, 1, 0); G_LDB(B1, 1, 1); SCHED; G_LDA(At, 1, 0); G_STAGE(G_SA(0, 1), a2 + hstep, voffA);
;             WAIT_V(8); WAIT_L(0); BAR; G_MMA(0, 0, At, B0); G_MMA(0, 1, At, B1); BAR; SCHED;
;             G_LDA(At, 1, 1); G_STAGE(G_SB(1, 0), b3, voffB); G_STAGE(G_SB(1, 1), b3 + hstep, voffB); G_STAGE(G_SA(1, 0), a3, voffA);
	v_add_u32_e32 v168, s85, v176
	ds_read_b128 v[128:131], v140
	ds_read_b128 v[132:135], v140 offset:1024
	ds_read_b128 v[136:139], v140 offset:2048
	ds_read_b128 v[140:143], v140 offset:3072
	ds_read_b128 v[144:147], v168
	ds_read_b128 v[148:151], v168 offset:1024
	ds_read_b128 v[164:167], v168 offset:2048
	ds_read_b128 v[168:171], v168 offset:3072
	s_add_u32 s46, s46, 0x40000
	s_addc_u32 s47, s47, 0
	s_mov_b32 m0, s59
	v_lshl_add_u64 v[216:217], s[46:47], 0, v[152:153]
	ds_read_b128 v[172:175], v179 offset:32768
	ds_read_b128 v[180:183], v179 offset:33792
	ds_read_b128 v[188:191], v179 offset:34816
	ds_read_b128 v[192:195], v179 offset:35840
	ds_read_b128 v[196:199], v179 offset:36864
	ds_read_b128 v[200:203], v179 offset:37888
	ds_read_b128 v[204:207], v179 offset:38912
	ds_read_b128 v[208:211], v179 offset:39936
	global_load_lds_dwordx4 v[216:217], off
	v_lshl_add_u64 v[216:217], s[46:47], 0, v[156:157]
	s_mov_b32 m0, s72
	s_nop 0
	global_load_lds_dwordx4 v[216:217], off
	s_waitcnt vmcnt(8)
	s_waitcnt lgkmcnt(0)
	s_barrier
	s_setprio 1
	s_waitcnt lgkmcnt(0)
	v_mfma_f32_16x16x32_bf16 v[124:127], v[128:131], v[172:175], v[124:127]
	v_mfma_f32_16x16x32_bf16 v[120:123], v[136:139], v[172:175], v[120:123]
	v_mfma_f32_16x16x32_bf16 v[116:119], v[128:131], v[188:191], v[116:119]
	v_mfma_f32_16x16x32_bf16 v[112:115], v[136:139], v[188:191], v[112:115]
	v_mfma_f32_16x16x32_bf16 v[108:111], v[128:131], v[196:199], v[108:111]
	v_mfma_f32_16x16x32_bf16 v[104:107], v[136:139], v[196:199], v[104:107]
	v_mfma_f32_16x16x32_bf16 v[100:103], v[128:131], v[204:207], v[100:103]
	v_mfma_f32_16x16x32_bf16 v[96:99], v[136:139], v[204:207], v[96:99]
	v_mfma_f32_16x16x32_bf16 v[124:127], v[132:135], v[180:183], v[124:127]
	v_mfma_f32_16x16x32_bf16 v[120:123], v[140:143], v[180:183], v[120:123]
	v_mfma_f32_16x16x32_bf16 v[116:119], v[132:135], v[192:195], v[116:119]
	v_mfma_f32_16x16x32_bf16 v[112:115], v[140:143], v[192:195], v[112:115]
	v_mfma_f32_16x16x32_bf16 v[108:111], v[132:135], v[200:203], v[108:111]
	v_mfma_f32_16x16x32_bf16 v[104:107], v[140:143], v[200:203], v[104:107]
	v_mfma_f32_16x16x32_bf16 v[100:103], v[132:135], v[208:211], v[100:103]
	v_mfma_f32_16x16x32_bf16 v[96:99], v[140:143], v[208:211], v[96:99]
	s_setprio 0
	s_setprio 1
	v_mfma_f32_16x16x32_bf16 v[60:63], v[144:147], v[172:175], v[60:63]
	v_mfma_f32_16x16x32_bf16 v[56:59], v[164:167], v[172:175], v[56:59]
	v_mfma_f32_16x16x32_bf16 v[52:55], v[144:147], v[188:191], v[52:55]
	v_mfma_f32_16x16x32_bf16 v[48:51], v[164:167], v[188:191], v[48:51]
	v_mfma_f32_16x16x32_bf16 v[44:47], v[144:147], v[196:199], v[44:47]
	v_mfma_f32_16x16x32_bf16 v[40:43], v[164:167], v[196:199], v[40:43]
	v_mfma_f32_16x16x32_bf16 v[36:39], v[144:147], v[204:207], v[36:39]
	v_mfma_f32_16x16x32_bf16 v[32:35], v[164:167], v[204:207], v[32:35]
	v_mfma_f32_16x16x32_bf16 v[60:63], v[148:151], v[180:183], v[60:63]
	v_mfma_f32_16x16x32_bf16 v[56:59], v[168:171], v[180:183], v[56:59]
	v_mfma_f32_16x16x32_bf16 v[52:55], v[148:151], v[192:195], v[52:55]
	v_mfma_f32_16x16x32_bf16 v[48:51], v[168:171], v[192:195], v[48:51]
	v_mfma_f32_16x16x32_bf16 v[44:47], v[148:151], v[200:203], v[44:47]
	v_mfma_f32_16x16x32_bf16 v[40:43], v[168:171], v[200:203], v[40:43]
	v_mfma_f32_16x16x32_bf16 v[36:39], v[148:151], v[208:211], v[36:39]
	v_mfma_f32_16x16x32_bf16 v[32:35], v[168:171], v[208:211], v[32:35]
	s_setprio 0
	s_add_i32 s46, s84, s56
	v_lshl_add_u64 v[184:185], v[184:185], 0, s[10:11]
	s_mov_b32 m0, s46
	s_barrier
; #define G_STAGE(bufoff, gbase, voff) do { _Pragma("unroll") for (int _i = 0; _i < 2; ++_i) \
;         __builtin_amdgcn_global_load_lds((const unsigned*)((const char*)(gbase) + voff[_i]), (LAS unsigned*)(lds + (bufoff) + ldsw + _i * 8192), 16, 0, 0); } while (0)
; #define G_LDA(dst, b, h) do { _Pragma("unroll") for (int m = 0; m < 4; ++m) _Pragma("unroll") for (int k = 0; k < 2; ++k) dst[m][k] = *(const LAS bf16x8*)(lds + G_SA(b, h) + aoff + m * 2048 + k * 1024); } while (0)
; #define G_MMA(ai, bj, At_, Bt_) do { __builtin_amdgcn_s_setprio(1); _Pragma("unroll") for (int m = 0; m < 4; ++m) _Pragma("unroll") for (int n = 0; n < 2; ++n) _Pragma("unroll") for (int k = 0; k < 2; ++k) \
;         acc[ai][bj][m][n] = __builtin_amdgcn_mfma_f32_16x16x32_bf16(Bt_[n][k], At_[m][k], acc[ai][bj][m][n], 0, 0, 0); __builtin_amdgcn_s_setprio(0); } while (0)
; #define WAIT_V(n) asm volatile("s_waitcnt vmcnt(" #n ")" ::: "memory")
; #define WAIT_L(n) asm volatile("s_waitcnt lgkmcnt(" #n ")" ::: "memory")
; #define BAR __builtin_amdgcn_s_barrier()
; #define SCHED __builtin_amdgcn_sched_barrier(0)
; template <class Get, class Epi>
; DI void gemm_loop(int ntiles, int ld, char* shm, const Get& get, const Epi& epi) {
;     ...
;             G_LDA(At, 1, 1); G_STAGE(G_SB(1, 0), b3, voffB); G_STAGE(G_SB(1, 1), b3 + hstep, voffB); G_STAGE(G_SA(1, 0), a3, voffA);
;             WAIT_V(8); WAIT_L(0); BAR; G_MMA(1, 0, At, B0); G_MMA(1, 1, At, B1); BAR; SCHED;
;         }
	ds_read_b128 v[172:175], v179 offset:49152
	ds_read_b128 v[180:183], v179 offset:50176
	ds_read_b128 v[188:191], v179 offset:51200
	ds_read_b128 v[192:195], v179 offset:52224
	ds_read_b128 v[196:199], v179 offset:53248
	ds_read_b128 v[200:203], v179 offset:54272
	ds_read_b128 v[204:207], v179 offset:55296
	ds_read_b128 v[208:211], v179 offset:56320
	global_load_lds_dwordx4 v[184:185], off
	s_add_i32 m0, s46, 0x2000
	s_add_u32 s14, s14, 0x40080
	v_lshl_add_u64 v[184:185], v[186:187], 0, s[10:11]
	s_addc_u32 s15, s15, 0
	s_add_i32 s46, s85, s56
	global_load_lds_dwordx4 v[184:185], off
	v_lshl_add_u64 v[184:185], s[14:15], 0, v[154:155]
	s_mov_b32 m0, s46
	s_nop 0
	global_load_lds_dwordx4 v[184:185], off
	v_lshl_add_u64 v[184:185], s[14:15], 0, v[158:159]
	s_add_i32 m0, s46, 0x2000
	s_nop 0
	global_load_lds_dwordx4 v[184:185], off
	v_lshl_add_u64 v[184:185], v[212:213], 0, s[10:11]
	s_mov_b32 m0, s75
	s_nop 0
	global_load_lds_dwordx4 v[184:185], off
	v_lshl_add_u64 v[184:185], v[214:215], 0, s[10:11]
	s_mov_b32 m0, s76
	s_nop 0
	global_load_lds_dwordx4 v[184:185], off
	s_waitcnt vmcnt(8)
	s_waitcnt lgkmcnt(0)
	s_barrier
	s_setprio 1
	s_waitcnt lgkmcnt(0)
	v_mfma_f32_16x16x32_bf16 v[92:95], v[128:131], v[172:175], v[92:95]
	v_mfma_f32_16x16x32_bf16 v[88:91], v[136:139], v[172:175], v[88:91]
	v_mfma_f32_16x16x32_bf16 v[84:87], v[128:131], v[188:191], v[84:87]
	v_mfma_f32_16x16x32_bf16 v[80:83], v[136:139], v[188:191], v[80:83]
	v_mfma_f32_16x16x32_bf16 v[76:79], v[128:131], v[196:199], v[76:79]
	v_mfma_f32_16x16x32_bf16 v[72:75], v[136:139], v[196:199], v[72:75]
	v_mfma_f32_16x16x32_bf16 v[68:71], v[128:131], v[204:207], v[68:71]
	v_mfma_f32_16x16x32_bf16 v[64:67], v[136:139], v[204:207], v[64:67]
	v_mfma_f32_16x16x32_bf16 v[92:95], v[132:135], v[180:183], v[92:95]
	v_mfma_f32_16x16x32_bf16 v[88:91], v[140:143], v[180:183], v[88:91]
	v_mfma_f32_16x16x32_bf16 v[84:87], v[132:135], v[192:195], v[84:87]
	v_mfma_f32_16x16x32_bf16 v[80:83], v[140:143], v[192:195], v[80:83]
	v_mfma_f32_16x16x32_bf16 v[76:79], v[132:135], v[200:203], v[76:79]
	v_mfma_f32_16x16x32_bf16 v[72:75], v[140:143], v[200:203], v[72:75]
	v_mfma_f32_16x16x32_bf16 v[68:71], v[132:135], v[208:211], v[68:71]
	v_mfma_f32_16x16x32_bf16 v[64:67], v[140:143], v[208:211], v[64:67]
	s_setprio 0
	s_setprio 1
	v_mfma_f32_16x16x32_bf16 v[28:31], v[144:147], v[172:175], v[28:31]
	v_mfma_f32_16x16x32_bf16 v[24:27], v[164:167], v[172:175], v[24:27]
	v_mfma_f32_16x16x32_bf16 v[20:23], v[144:147], v[188:191], v[20:23]
	v_mfma_f32_16x16x32_bf16 v[16:19], v[164:167], v[188:191], v[16:19]
	v_mfma_f32_16x16x32_bf16 v[12:15], v[144:147], v[196:199], v[12:15]
	v_mfma_f32_16x16x32_bf16 v[8:11], v[164:167], v[196:199], v[8:11]
	v_mfma_f32_16x16x32_bf16 v[4:7], v[144:147], v[204:207], v[4:7]
	v_mfma_f32_16x16x32_bf16 v[0:3], v[164:167], v[204:207], v[0:3]
	v_mfma_f32_16x16x32_bf16 v[28:31], v[148:151], v[180:183], v[28:31]
	v_mfma_f32_16x16x32_bf16 v[24:27], v[168:171], v[180:183], v[24:27]
	v_mfma_f32_16x16x32_bf16 v[20:23], v[148:151], v[192:195], v[20:23]
	v_mfma_f32_16x16x32_bf16 v[16:19], v[168:171], v[192:195], v[16:19]
	v_mfma_f32_16x16x32_bf16 v[12:15], v[148:151], v[200:203], v[12:15]
	v_mfma_f32_16x16x32_bf16 v[8:11], v[168:171], v[200:203], v[8:11]
	v_mfma_f32_16x16x32_bf16 v[4:7], v[148:151], v[208:211], v[4:7]
	v_mfma_f32_16x16x32_bf16 v[0:3], v[168:171], v[208:211], v[0:3]
	s_setprio 0
	s_add_u32 s44, s44, 0x100
	s_addc_u32 s45, s45, 0
	s_add_u32 s55, s55, 0x100
	s_addc_u32 s82, s82, 0
	s_cmp_ge_u32 s83, s51
	s_mov_b32 s14, s83
	s_barrier
	s_cbranch_scc0 .LBB0_528

; #define G_STAGE(bufoff, gbase, voff) do { _Pragma("unroll") for (int _i = 0; _i < 2; ++_i) \
;         __builtin_amdgcn_global_load_lds((const unsigned*)((const char*)(gbase) + voff[_i]), (LAS unsigned*)(lds + (bufoff) + ldsw + _i * 8192), 16, 0, 0); } while (0)
; #define G_LDA(dst, b, h) do { _Pragma("unroll") for (int m = 0; m < 4; ++m) _Pragma("unroll") for (int k = 0; k < 2; ++k) dst[m][k] = *(const LAS bf16x8*)(lds + G_SA(b, h) + aoff + m * 2048 + k * 1024); } while (0)
; #define G_LDB(dst, b, h) do { _Pragma("unroll") for (int n = 0; n < 2; ++n) _Pragma("unroll") for (int k = 0; k < 2; ++k) dst[n][k] = *(const LAS bf16x8*)(lds + G_SB(b, h) + boff + n * 2048 + k * 1024); } while (0)
; #define G_MMA(ai, bj, At_, Bt_) do { __builtin_amdgcn_s_setprio(1); _Pragma("unroll") for (int m = 0; m < 4; ++m) _Pragma("unroll") for (int n = 0; n < 2; ++n) _Pragma("unroll") for (int k = 0; k < 2; ++k) \
;         acc[ai][bj][m][n] = __builtin_amdgcn_mfma_f32_16x16x32_bf16(Bt_[n][k], At_[m][k], acc[ai][bj][m][n], 0, 0, 0); __builtin_amdgcn_s_setprio(0); } while (0)
; #define WAIT_V(n) asm volatile("s_waitcnt vmcnt(" #n ")" ::: "memory")
; #define WAIT_L(n) asm volatile("s_waitcnt lgkmcnt(" #n ")" ::: "memory")
; #define BAR __builtin_amdgcn_s_barrier()
; #define SCHED __builtin_amdgcn_sched_barrier(0)
; template <class Get, class Epi>
; DI void gemm_loop(int ntiles, int ld, char* shm, const Get& get, const Epi& epi) {
;     ...
;             const bool last = (t == nt - 2);
;             const char* a1 = cA + (size_t)(t + 1) * kstep;
;             const char* a2 = last ? nA : cA + (size_t)(t + 2) * kstep; const char* b2 = last ? nB : cB + (size_t)(t + 2) * kstep;
;             const char* a3 = a2 + kstep; const char* b3 = b2 + kstep;
;             G_LDB(B0, 0, 0); G_LDB(B1, 0, 1); SCHED; G_LDA(At, 0, 0); G_STAGE(G_SA(1, 1), a1 + hstep, voffA);
;             WAIT_V(8); WAIT_L(0); BAR; G_MMA(0, 0, At, B0); G_MMA(0, 1, At, B1); BAR; SCHED;
;             G_LDA(At, 0, 1); G_STAGE(G_SB(0, 0), b2, voffB); G_STAGE(G_SB(0, 1), b2 + hstep, voffB); G_STAGE(G_SA(0, 0), a2, voffA);
.Lpeel_763:
	ds_read_b128 v[144:147], v141
	ds_read_b128 v[148:151], v141 offset:1024
	ds_read_b128 v[152:155], v141 offset:2048
	ds_read_b128 v[156:159], v141 offset:3072
	ds_read_b128 v[160:163], v142
	ds_read_b128 v[164:167], v142 offset:1024
	ds_read_b128 v[168:171], v142 offset:2048
	ds_read_b128 v[172:175], v142 offset:3072
	s_add_u32 s14, s36, 0xfffc0080
	s_addc_u32 s15, s37, -1
	s_cmp_eq_u32 s54, 12
	s_cselect_b32 s39, s9, s15
	s_cselect_b32 s38, s50, s14
	s_cselect_b32 s15, s11, s53
	s_cselect_b32 s14, s51, s52
	v_lshl_add_u64 v[184:185], s[36:37], 0, v[136:137]
	s_add_i32 m0, s31, 0xc000
	ds_read_b128 v[176:179], v143
	ds_read_b128 v[180:183], v143 offset:1024
	ds_read_b128 v[188:191], v143 offset:2048
	ds_read_b128 v[192:195], v143 offset:3072
	ds_read_b128 v[196:199], v143 offset:4096
	ds_read_b128 v[200:203], v143 offset:5120
	ds_read_b128 v[204:207], v143 offset:6144
	ds_read_b128 v[208:211], v143 offset:7168
	global_load_lds_dwordx4 v[184:185], off
	v_lshl_add_u64 v[184:185], s[36:37], 0, v[138:139]
	s_add_i32 m0, s31, 0xe000
	s_nop 0
	global_load_lds_dwordx4 v[184:185], off
	s_waitcnt vmcnt(8)
	s_waitcnt lgkmcnt(0)
	s_barrier
	s_setprio 1
	s_waitcnt lgkmcnt(0)
	v_mfma_f32_16x16x32_bf16 v[124:127], v[144:147], v[176:179], 0
	v_mfma_f32_16x16x32_bf16 v[120:123], v[152:155], v[176:179], 0
	v_mfma_f32_16x16x32_bf16 v[108:111], v[144:147], v[188:191], 0
	v_mfma_f32_16x16x32_bf16 v[104:107], v[152:155], v[188:191], 0
	v_mfma_f32_16x16x32_bf16 v[92:95], v[144:147], v[196:199], 0
	v_mfma_f32_16x16x32_bf16 v[88:91], v[152:155], v[196:199], 0
	v_mfma_f32_16x16x32_bf16 v[76:79], v[144:147], v[204:207], 0
	v_mfma_f32_16x16x32_bf16 v[72:75], v[152:155], v[204:207], 0
	v_mfma_f32_16x16x32_bf16 v[124:127], v[148:151], v[180:183], v[124:127]
	v_mfma_f32_16x16x32_bf16 v[120:123], v[156:159], v[180:183], v[120:123]
	v_mfma_f32_16x16x32_bf16 v[108:111], v[148:151], v[192:195], v[108:111]
	v_mfma_f32_16x16x32_bf16 v[104:107], v[156:159], v[192:195], v[104:107]
	v_mfma_f32_16x16x32_bf16 v[92:95], v[148:151], v[200:203], v[92:95]
	v_mfma_f32_16x16x32_bf16 v[88:91], v[156:159], v[200:203], v[88:91]
	v_mfma_f32_16x16x32_bf16 v[76:79], v[148:151], v[208:211], v[76:79]
	v_mfma_f32_16x16x32_bf16 v[72:75], v[156:159], v[208:211], v[72:75]
	s_setprio 0
	s_setprio 1
	v_mfma_f32_16x16x32_bf16 v[116:119], v[160:163], v[176:179], 0
	v_mfma_f32_16x16x32_bf16 v[112:115], v[168:171], v[176:179], 0
	v_mfma_f32_16x16x32_bf16 v[100:103], v[160:163], v[188:191], 0
	v_mfma_f32_16x16x32_bf16 v[96:99], v[168:171], v[188:191], 0
	v_mfma_f32_16x16x32_bf16 v[84:87], v[160:163], v[196:199], 0
	v_mfma_f32_16x16x32_bf16 v[80:83], v[168:171], v[196:199], 0
	v_mfma_f32_16x16x32_bf16 v[68:71], v[160:163], v[204:207], 0
	v_mfma_f32_16x16x32_bf16 v[64:67], v[168:171], v[204:207], 0
	v_mfma_f32_16x16x32_bf16 v[116:119], v[164:167], v[180:183], v[116:119]
	v_mfma_f32_16x16x32_bf16 v[112:115], v[172:175], v[180:183], v[112:115]
	v_mfma_f32_16x16x32_bf16 v[100:103], v[164:167], v[192:195], v[100:103]
	v_mfma_f32_16x16x32_bf16 v[96:99], v[172:175], v[192:195], v[96:99]
	v_mfma_f32_16x16x32_bf16 v[84:87], v[164:167], v[200:203], v[84:87]
	v_mfma_f32_16x16x32_bf16 v[80:83], v[172:175], v[200:203], v[80:83]
	v_mfma_f32_16x16x32_bf16 v[68:71], v[164:167], v[208:211], v[68:71]
	v_mfma_f32_16x16x32_bf16 v[64:67], v[172:175], v[208:211], v[64:67]
	s_setprio 0
	s_add_i32 s55, s45, s26
	v_lshl_add_u64 v[184:185], s[14:15], 0, v[132:133]
	s_mov_b32 m0, s55
	s_barrier
	ds_read_b128 v[176:179], v143 offset:16384
	ds_read_b128 v[180:183], v143 offset:17408
	ds_read_b128 v[188:191], v143 offset:18432
	ds_read_b128 v[192:195], v143 offset:19456
	ds_read_b128 v[196:199], v143 offset:20480
	ds_read_b128 v[200:203], v143 offset:21504
	ds_read_b128 v[204:207], v143 offset:22528
	ds_read_b128 v[208:211], v143 offset:23552
	global_load_lds_dwordx4 v[184:185], off
	s_add_i32 m0, s55, 0x2000
	s_add_u32 s56, s14, 0x40000
	v_lshl_add_u64 v[186:187], s[14:15], 0, v[128:129]
	s_addc_u32 s57, s15, 0
	s_add_i32 s55, s46, s26
	global_load_lds_dwordx4 v[186:187], off
	v_lshl_add_u64 v[212:213], s[56:57], 0, v[132:133]
	s_mov_b32 m0, s55
	v_lshl_add_u64 v[214:215], s[38:39], 0, v[130:131]
	global_load_lds_dwordx4 v[212:213], off
	v_lshl_add_u64 v[212:213], s[56:57], 0, v[128:129]
	s_add_i32 m0, s55, 0x2000
	s_nop 0
	global_load_lds_dwordx4 v[212:213], off
	v_lshl_add_u64 v[212:213], s[38:39], 0, v[134:135]
	s_mov_b32 m0, s31
	s_nop 0
	global_load_lds_dwordx4 v[212:213], off
	s_mov_b32 m0, s35
	s_nop 0
	global_load_lds_dwordx4 v[214:215], off
	s_waitcnt vmcnt(8)
	s_waitcnt lgkmcnt(0)
	s_barrier
; #define G_STAGE(bufoff, gbase, voff) do { _Pragma("unroll") for (int _i = 0; _i < 2; ++_i) \
;         __builtin_amdgcn_global_load_lds((const unsigned*)((const char*)(gbase) + voff[_i]), (LAS unsigned*)(lds + (bufoff) + ldsw + _i * 8192), 16, 0, 0); } while (0)
; #define G_LDA(dst, b, h) do { _Pragma("unroll") for (int m = 0; m < 4; ++m) _Pragma("unroll") for (int k = 0; k < 2; ++k) dst[m][k] = *(const LAS bf16x8*)(lds + G_SA(b, h) + aoff + m * 2048 + k * 1024); } while (0)
; #define G_LDB(dst, b, h) do { _Pragma("unroll") for (int n = 0; n < 2; ++n) _Pragma("unroll") for (int k = 0; k < 2; ++k) dst[n][k] = *(const LAS bf16x8*)(lds + G_SB(b, h) + boff + n * 2048 + k * 1024); } while (0)
; #define G_MMA(ai, bj, At_, Bt_) do { __builtin_amdgcn_s_setprio(1); _Pragma("unroll") for (int m = 0; m < 4; ++m) _Pragma("unroll") for (int n = 0; n < 2; ++n) _Pragma("unroll") for (int k = 0; k < 2; ++k) \
;         acc[ai][bj][m][n] = __builtin_amdgcn_mfma_f32_16x16x32_bf16(Bt_[n][k], At_[m][k], acc[ai][bj][m][n], 0, 0, 0); __builtin_amdgcn_s_setprio(0); } while (0)
; #define WAIT_V(n) asm volatile("s_waitcnt vmcnt(" #n ")" ::: "memory")
; #define WAIT_L(n) asm volatile("s_waitcnt lgkmcnt(" #n ")" ::: "memory")
; #define BAR __builtin_amdgcn_s_barrier()
; #define SCHED __builtin_amdgcn_sched_barrier(0)
; template <class Get, class Epi>
; DI void gemm_loop(int ntiles, int ld, char* shm, const Get& get, const Epi& epi) {
;     ...
;             WAIT_V(8); WAIT_L(0); BAR; G_MMA(1, 0, At, B0); G_MMA(1, 1, At, B1); BAR; SCHED;
;             G_LDB(B0, 1, 0); G_LDB(B1, 1, 1); SCHED; G_LDA(At, 1, 0); G_STAGE(G_SA(0, 1), a2 + hstep, voffA);
;             WAIT_V(8); WAIT_L(0); BAR; G_MMA(0, 0, At, B0); G_MMA(0, 1, At, B1); BAR; SCHED;
	s_setprio 1
	s_waitcnt lgkmcnt(0)
	v_mfma_f32_16x16x32_bf16 v[60:63], v[144:147], v[176:179], 0
	v_mfma_f32_16x16x32_bf16 v[56:59], v[152:155], v[176:179], 0
	v_mfma_f32_16x16x32_bf16 v[44:47], v[144:147], v[188:191], 0
	v_mfma_f32_16x16x32_bf16 v[40:43], v[152:155], v[188:191], 0
	v_mfma_f32_16x16x32_bf16 v[28:31], v[144:147], v[196:199], 0
	v_mfma_f32_16x16x32_bf16 v[24:27], v[152:155], v[196:199], 0
	v_mfma_f32_16x16x32_bf16 v[12:15], v[144:147], v[204:207], 0
	v_mfma_f32_16x16x32_bf16 v[8:11], v[152:155], v[204:207], 0
	v_mfma_f32_16x16x32_bf16 v[60:63], v[148:151], v[180:183], v[60:63]
	v_mfma_f32_16x16x32_bf16 v[56:59], v[156:159], v[180:183], v[56:59]
	v_mfma_f32_16x16x32_bf16 v[44:47], v[148:151], v[192:195], v[44:47]
	v_mfma_f32_16x16x32_bf16 v[40:43], v[156:159], v[192:195], v[40:43]
	v_mfma_f32_16x16x32_bf16 v[28:31], v[148:151], v[200:203], v[28:31]
	v_mfma_f32_16x16x32_bf16 v[24:27], v[156:159], v[200:203], v[24:27]
	v_mfma_f32_16x16x32_bf16 v[12:15], v[148:151], v[208:211], v[12:15]
	v_mfma_f32_16x16x32_bf16 v[8:11], v[156:159], v[208:211], v[8:11]
	s_setprio 0
	s_setprio 1
	v_mfma_f32_16x16x32_bf16 v[52:55], v[160:163], v[176:179], 0
	v_mfma_f32_16x16x32_bf16 v[48:51], v[168:171], v[176:179], 0
	v_mfma_f32_16x16x32_bf16 v[36:39], v[160:163], v[188:191], 0
	v_mfma_f32_16x16x32_bf16 v[32:35], v[168:171], v[188:191], 0
	v_mfma_f32_16x16x32_bf16 v[20:23], v[160:163], v[196:199], 0
	v_mfma_f32_16x16x32_bf16 v[16:19], v[168:171], v[196:199], 0
	v_mfma_f32_16x16x32_bf16 v[4:7], v[160:163], v[204:207], 0
	v_mfma_f32_16x16x32_bf16 v[0:3], v[168:171], v[204:207], 0
	v_mfma_f32_16x16x32_bf16 v[52:55], v[164:167], v[180:183], v[52:55]
	v_mfma_f32_16x16x32_bf16 v[48:51], v[172:175], v[180:183], v[48:51]
	v_mfma_f32_16x16x32_bf16 v[36:39], v[164:167], v[192:195], v[36:39]
	v_mfma_f32_16x16x32_bf16 v[32:35], v[172:175], v[192:195], v[32:35]
	v_mfma_f32_16x16x32_bf16 v[20:23], v[164:167], v[200:203], v[20:23]
	v_mfma_f32_16x16x32_bf16 v[16:19], v[172:175], v[200:203], v[16:19]
	v_mfma_f32_16x16x32_bf16 v[4:7], v[164:167], v[208:211], v[4:7]
	v_mfma_f32_16x16x32_bf16 v[0:3], v[172:175], v[208:211], v[0:3]
	s_setprio 0
	s_add_i32 s55, 0, 0x18000
	s_add_i32 s56, 0, 0x1c000
	v_add_u32_e32 v156, s55, v140
	s_barrier
	v_add_u32_e32 v172, s56, v140
	ds_read_b128 v[144:147], v156
	ds_read_b128 v[148:151], v156 offset:1024
	ds_read_b128 v[152:155], v156 offset:2048
	ds_read_b128 v[156:159], v156 offset:3072
	ds_read_b128 v[160:163], v172
	ds_read_b128 v[164:167], v172 offset:1024
	ds_read_b128 v[168:171], v172 offset:2048
	ds_read_b128 v[172:175], v172 offset:3072
	s_add_u32 s38, s38, 0x40000
	s_addc_u32 s39, s39, 0
	s_mov_b32 m0, s41
	v_lshl_add_u64 v[216:217], s[38:39], 0, v[134:135]
	ds_read_b128 v[176:179], v143 offset:32768
	ds_read_b128 v[180:183], v143 offset:33792
	ds_read_b128 v[188:191], v143 offset:34816
	ds_read_b128 v[192:195], v143 offset:35840
	ds_read_b128 v[196:199], v143 offset:36864
	ds_read_b128 v[200:203], v143 offset:37888
	ds_read_b128 v[204:207], v143 offset:38912
	ds_read_b128 v[208:211], v143 offset:39936
	global_load_lds_dwordx4 v[216:217], off
	v_lshl_add_u64 v[216:217], s[38:39], 0, v[130:131]
	s_mov_b32 m0, s42
	s_nop 0
	global_load_lds_dwordx4 v[216:217], off
	s_waitcnt vmcnt(8)
	s_waitcnt lgkmcnt(0)
	s_barrier
	s_setprio 1
	s_waitcnt lgkmcnt(0)
	v_mfma_f32_16x16x32_bf16 v[124:127], v[144:147], v[176:179], v[124:127]
	v_mfma_f32_16x16x32_bf16 v[120:123], v[152:155], v[176:179], v[120:123]
	v_mfma_f32_16x16x32_bf16 v[108:111], v[144:147], v[188:191], v[108:111]
	v_mfma_f32_16x16x32_bf16 v[104:107], v[152:155], v[188:191], v[104:107]
	v_mfma_f32_16x16x32_bf16 v[92:95], v[144:147], v[196:199], v[92:95]
	v_mfma_f32_16x16x32_bf16 v[88:91], v[152:155], v[196:199], v[88:91]
	v_mfma_f32_16x16x32_bf16 v[76:79], v[144:147], v[204:207], v[76:79]
	v_mfma_f32_16x16x32_bf16 v[72:75], v[152:155], v[204:207], v[72:75]
	v_mfma_f32_16x16x32_bf16 v[124:127], v[148:151], v[180:183], v[124:127]
	v_mfma_f32_16x16x32_bf16 v[120:123], v[156:159], v[180:183], v[120:123]
	v_mfma_f32_16x16x32_bf16 v[108:111], v[148:151], v[192:195], v[108:111]
	v_mfma_f32_16x16x32_bf16 v[104:107], v[156:159], v[192:195], v[104:107]
	v_mfma_f32_16x16x32_bf16 v[92:95], v[148:151], v[200:203], v[92:95]
	v_mfma_f32_16x16x32_bf16 v[88:91], v[156:159], v[200:203], v[88:91]
	v_mfma_f32_16x16x32_bf16 v[76:79], v[148:151], v[208:211], v[76:79]
	v_mfma_f32_16x16x32_bf16 v[72:75], v[156:159], v[208:211], v[72:75]
	s_setprio 0
	s_setprio 1
	v_mfma_f32_16x16x32_bf16 v[116:119], v[160:163], v[176:179], v[116:119]
	v_mfma_f32_16x16x32_bf16 v[112:115], v[168:171], v[176:179], v[112:115]
	v_mfma_f32_16x16x32_bf16 v[100:103], v[160:163], v[188:191], v[100:103]
	v_mfma_f32_16x16x32_bf16 v[96:99], v[168:171], v[188:191], v[96:99]
	v_mfma_f32_16x16x32_bf16 v[84:87], v[160:163], v[196:199], v[84:87]
	v_mfma_f32_16x16x32_bf16 v[80:83], v[168:171], v[196:199], v[80:83]
	v_mfma_f32_16x16x32_bf16 v[68:71], v[160:163], v[204:207], v[68:71]
	v_mfma_f32_16x16x32_bf16 v[64:67], v[168:171], v[204:207], v[64:67]
	v_mfma_f32_16x16x32_bf16 v[116:119], v[164:167], v[180:183], v[116:119]
	v_mfma_f32_16x16x32_bf16 v[112:115], v[172:175], v[180:183], v[112:115]
	v_mfma_f32_16x16x32_bf16 v[100:103], v[164:167], v[192:195], v[100:103]
	v_mfma_f32_16x16x32_bf16 v[96:99], v[172:175], v[192:195], v[96:99]
	v_mfma_f32_16x16x32_bf16 v[84:87], v[164:167], v[200:203], v[84:87]
	v_mfma_f32_16x16x32_bf16 v[80:83], v[172:175], v[200:203], v[80:83]
	v_mfma_f32_16x16x32_bf16 v[68:71], v[164:167], v[208:211], v[68:71]
	v_mfma_f32_16x16x32_bf16 v[64:67], v[172:175], v[208:211], v[64:67]
	s_setprio 0
	s_add_i32 s38, s55, s26
	v_lshl_add_u64 v[184:185], v[184:185], 0, s[2:3]
	s_mov_b32 m0, s38
	s_barrier
; #define G_STAGE(bufoff, gbase, voff) do { _Pragma("unroll") for (int _i = 0; _i < 2; ++_i) \
;         __builtin_amdgcn_global_load_lds((const unsigned*)((const char*)(gbase) + voff[_i]), (LAS unsigned*)(lds + (bufoff) + ldsw + _i * 8192), 16, 0, 0); } while (0)
; #define G_LDA(dst, b, h) do { _Pragma("unroll") for (int m = 0; m < 4; ++m) _Pragma("unroll") for (int k = 0; k < 2; ++k) dst[m][k] = *(const LAS bf16x8*)(lds + G_SA(b, h) + aoff + m * 2048 + k * 1024); } while (0)
; #define G_LDB(dst, b, h) do { _Pragma("unroll") for (int n = 0; n < 2; ++n) _Pragma("unroll") for (int k = 0; k < 2; ++k) dst[n][k] = *(const LAS bf16x8*)(lds + G_SB(b, h) + boff + n * 2048 + k * 1024); } while (0)
; #define G_MMA(ai, bj, At_, Bt_) do { __builtin_amdgcn_s_setprio(1); _Pragma("unroll") for (int m = 0; m < 4; ++m) _Pragma("unroll") for (int n = 0; n < 2; ++n) _Pragma("unroll") for (int k = 0; k < 2; ++k) \
;         acc[ai][bj][m][n] = __builtin_amdgcn_mfma_f32_16x16x32_bf16(Bt_[n][k], At_[m][k], acc[ai][bj][m][n], 0, 0, 0); __builtin_amdgcn_s_setprio(0); } while (0)
; #define WAIT_V(n) asm volatile("s_waitcnt vmcnt(" #n ")" ::: "memory")
; #define BAR __builtin_amdgcn_s_barrier()
; template <class Get, class Epi>
; DI void gemm_loop(int ntiles, int ld, char* shm, const Get& get, const Epi& epi) {
;     ...
;             const char* a2 = last ? nA : cA + (size_t)(t + 2) * kstep; const char* b2 = last ? nB : cB + (size_t)(t + 2) * kstep;
;             const char* a3 = a2 + kstep; const char* b3 = b2 + kstep;
;             G_LDB(B0, 0, 0); G_LDB(B1, 0, 1); SCHED; G_LDA(At, 0, 0); G_STAGE(G_SA(1, 1), a1 + hstep, voffA);
;             WAIT_V(8); WAIT_L(0); BAR; G_MMA(0, 0, At, B0); G_MMA(0, 1, At, B1); BAR; SCHED;
;             G_LDA(At, 0, 1); G_STAGE(G_SB(0, 0), b2, voffB); G_STAGE(G_SB(0, 1), b2 + hstep, voffB); G_STAGE(G_SA(0, 0), a2, voffA);
;             WAIT_V(8); WAIT_L(0); BAR; G_MMA(1, 0, At, B0); G_MMA(1, 1, At, B1); BAR; SCHED;
;             G_LDB(B0, 1, 0); G_LDB(B1, 1, 1); SCHED; G_LDA(At, 1, 0); G_STAGE(G_SA(0, 1), a2 + hstep, voffA);
;             WAIT_V(8); WAIT_L(0); BAR; G_MMA(0, 0, At, B0); G_MMA(0, 1, At, B1); BAR; SCHED;
;             G_LDA(At, 1, 1); G_STAGE(G_SB(1, 0), b3, voffB); G_STAGE(G_SB(1, 1), b3 + hstep, voffB); G_STAGE(G_SA(1, 0), a3, voffA);
;             WAIT_V(8); WAIT_L(0); BAR; G_MMA(1, 0, At, B0); G_MMA(1, 1, At, B1); BAR; SCHED;
	ds_read_b128 v[176:179], v143 offset:49152
	ds_read_b128 v[180:183], v143 offset:50176
	ds_read_b128 v[188:191], v143 offset:51200
	ds_read_b128 v[192:195], v143 offset:52224
	ds_read_b128 v[196:199], v143 offset:53248
	ds_read_b128 v[200:203], v143 offset:54272
	ds_read_b128 v[204:207], v143 offset:55296
	ds_read_b128 v[208:211], v143 offset:56320
	global_load_lds_dwordx4 v[184:185], off
	s_add_i32 m0, s38, 0x2000
	s_add_u32 s14, s14, 0x40080
	v_lshl_add_u64 v[184:185], v[186:187], 0, s[2:3]
	s_addc_u32 s15, s15, 0
	s_add_i32 s38, s56, s26
	global_load_lds_dwordx4 v[184:185], off
	v_lshl_add_u64 v[184:185], s[14:15], 0, v[132:133]
	s_mov_b32 m0, s38
	s_nop 0
	global_load_lds_dwordx4 v[184:185], off
	v_lshl_add_u64 v[184:185], s[14:15], 0, v[128:129]
	s_add_i32 m0, s38, 0x2000
	s_nop 0
	global_load_lds_dwordx4 v[184:185], off
	v_lshl_add_u64 v[184:185], v[212:213], 0, s[2:3]
	s_mov_b32 m0, s43
	s_nop 0
	global_load_lds_dwordx4 v[184:185], off
	v_lshl_add_u64 v[184:185], v[214:215], 0, s[2:3]
	s_mov_b32 m0, s44
	s_nop 0
	global_load_lds_dwordx4 v[184:185], off
	s_waitcnt vmcnt(8)
	s_waitcnt lgkmcnt(0)
	s_barrier
	s_setprio 1
	s_waitcnt lgkmcnt(0)
	v_mfma_f32_16x16x32_bf16 v[60:63], v[144:147], v[176:179], v[60:63]
	v_mfma_f32_16x16x32_bf16 v[56:59], v[152:155], v[176:179], v[56:59]
	v_mfma_f32_16x16x32_bf16 v[44:47], v[144:147], v[188:191], v[44:47]
	v_mfma_f32_16x16x32_bf16 v[40:43], v[152:155], v[188:191], v[40:43]
	v_mfma_f32_16x16x32_bf16 v[28:31], v[144:147], v[196:199], v[28:31]
	v_mfma_f32_16x16x32_bf16 v[24:27], v[152:155], v[196:199], v[24:27]
	v_mfma_f32_16x16x32_bf16 v[12:15], v[144:147], v[204:207], v[12:15]
	v_mfma_f32_16x16x32_bf16 v[8:11], v[152:155], v[204:207], v[8:11]
	v_mfma_f32_16x16x32_bf16 v[60:63], v[148:151], v[180:183], v[60:63]
	v_mfma_f32_16x16x32_bf16 v[56:59], v[156:159], v[180:183], v[56:59]
	v_mfma_f32_16x16x32_bf16 v[44:47], v[148:151], v[192:195], v[44:47]
	v_mfma_f32_16x16x32_bf16 v[40:43], v[156:159], v[192:195], v[40:43]
	v_mfma_f32_16x16x32_bf16 v[28:31], v[148:151], v[200:203], v[28:31]
	v_mfma_f32_16x16x32_bf16 v[24:27], v[156:159], v[200:203], v[24:27]
	v_mfma_f32_16x16x32_bf16 v[12:15], v[148:151], v[208:211], v[12:15]
	v_mfma_f32_16x16x32_bf16 v[8:11], v[156:159], v[208:211], v[8:11]
	s_setprio 0
	s_setprio 1
	v_mfma_f32_16x16x32_bf16 v[52:55], v[160:163], v[176:179], v[52:55]
	v_mfma_f32_16x16x32_bf16 v[48:51], v[168:171], v[176:179], v[48:51]
	v_mfma_f32_16x16x32_bf16 v[36:39], v[160:163], v[188:191], v[36:39]
	v_mfma_f32_16x16x32_bf16 v[32:35], v[168:171], v[188:191], v[32:35]
	v_mfma_f32_16x16x32_bf16 v[20:23], v[160:163], v[196:199], v[20:23]
	v_mfma_f32_16x16x32_bf16 v[16:19], v[168:171], v[196:199], v[16:19]
	v_mfma_f32_16x16x32_bf16 v[4:7], v[160:163], v[204:207], v[4:7]
	v_mfma_f32_16x16x32_bf16 v[0:3], v[168:171], v[204:207], v[0:3]
	v_mfma_f32_16x16x32_bf16 v[52:55], v[164:167], v[180:183], v[52:55]
	v_mfma_f32_16x16x32_bf16 v[48:51], v[172:175], v[180:183], v[48:51]
	v_mfma_f32_16x16x32_bf16 v[36:39], v[164:167], v[192:195], v[36:39]
	v_mfma_f32_16x16x32_bf16 v[32:35], v[172:175], v[192:195], v[32:35]
	v_mfma_f32_16x16x32_bf16 v[20:23], v[164:167], v[200:203], v[20:23]
	v_mfma_f32_16x16x32_bf16 v[16:19], v[172:175], v[200:203], v[16:19]
	v_mfma_f32_16x16x32_bf16 v[4:7], v[164:167], v[208:211], v[4:7]
	v_mfma_f32_16x16x32_bf16 v[0:3], v[172:175], v[208:211], v[0:3]
	s_setprio 0
	s_add_i32 s54, s54, 2
	s_add_u32 s36, s36, 0x100
	s_addc_u32 s37, s37, 0
	s_add_u32 s52, s52, 0x100
	s_addc_u32 s53, s53, 0
	s_cmp_gt_u32 s54, 13
	s_barrier
	s_cbranch_scc0 .LBB0_763
	s_branch .Lpost_763
.LBB0_763:
	ds_read_b128 v[144:147], v141
	ds_read_b128 v[148:151], v141 offset:1024
	ds_read_b128 v[152:155], v141 offset:2048
	ds_read_b128 v[156:159], v141 offset:3072
	ds_read_b128 v[160:163], v142
	ds_read_b128 v[164:167], v142 offset:1024
	ds_read_b128 v[168:171], v142 offset:2048
	ds_read_b128 v[172:175], v142 offset:3072
	s_add_u32 s14, s36, 0xfffc0080
	s_addc_u32 s15, s37, -1
	s_cmp_eq_u32 s54, 12
	s_cselect_b32 s39, s9, s15
	s_cselect_b32 s38, s50, s14
	s_cselect_b32 s15, s11, s53
	s_cselect_b32 s14, s51, s52
	v_lshl_add_u64 v[184:185], s[36:37], 0, v[136:137]
	s_add_i32 m0, s31, 0xc000
	ds_read_b128 v[176:179], v143
	ds_read_b128 v[180:183], v143 offset:1024
	ds_read_b128 v[188:191], v143 offset:2048
	ds_read_b128 v[192:195], v143 offset:3072
	ds_read_b128 v[196:199], v143 offset:4096
	ds_read_b128 v[200:203], v143 offset:5120
	ds_read_b128 v[204:207], v143 offset:6144
	ds_read_b128 v[208:211], v143 offset:7168
	global_load_lds_dwordx4 v[184:185], off
	v_lshl_add_u64 v[184:185], s[36:37], 0, v[138:139]
	s_add_i32 m0, s31, 0xe000
	s_nop 0
	global_load_lds_dwordx4 v[184:185], off
	s_waitcnt vmcnt(8)
	s_waitcnt lgkmcnt(0)
	s_barrier
; #define G_STAGE(bufoff, gbase, voff) do { _Pragma("unroll") for (int _i = 0; _i < 2; ++_i) \
;         __builtin_amdgcn_global_load_lds((const unsigned*)((const char*)(gbase) + voff[_i]), (LAS unsigned*)(lds + (bufoff) + ldsw + _i * 8192), 16, 0, 0); } while (0)
; #define G_LDA(dst, b, h) do { _Pragma("unroll") for (int m = 0; m < 4; ++m) _Pragma("unroll") for (int k = 0; k < 2; ++k) dst[m][k] = *(const LAS bf16x8*)(lds + G_SA(b, h) + aoff + m * 2048 + k * 1024); } while (0)
; #define G_LDB(dst, b, h) do { _Pragma("unroll") for (int n = 0; n < 2; ++n) _Pragma("unroll") for (int k = 0; k < 2; ++k) dst[n][k] = *(const LAS bf16x8*)(lds + G_SB(b, h) + boff + n * 2048 + k * 1024); } while (0)
; #define G_MMA(ai, bj, At_, Bt_) do { __builtin_amdgcn_s_setprio(1); _Pragma("unroll") for (int m = 0; m < 4; ++m) _Pragma("unroll") for (int n = 0; n < 2; ++n) _Pragma("unroll") for (int k = 0; k < 2; ++k) \
;         acc[ai][bj][m][n] = __builtin_amdgcn_mfma_f32_16x16x32_bf16(Bt_[n][k], At_[m][k], acc[ai][bj][m][n], 0, 0, 0); __builtin_amdgcn_s_setprio(0); } while (0)
; #define WAIT_V(n) asm volatile("s_waitcnt vmcnt(" #n ")" ::: "memory")
; #define WAIT_L(n) asm volatile("s_waitcnt lgkmcnt(" #n ")" ::: "memory")
; #define BAR __builtin_amdgcn_s_barrier()
; #define SCHED __builtin_amdgcn_sched_barrier(0)
; template <class Get, class Epi>
; DI void gemm_loop(int ntiles, int ld, char* shm, const Get& get, const Epi& epi) {
;     ...
;             WAIT_V(8); WAIT_L(0); BAR; G_MMA(0, 0, At, B0); G_MMA(0, 1, At, B1); BAR; SCHED;
;             G_LDA(At, 0, 1); G_STAGE(G_SB(0, 0), b2, voffB); G_STAGE(G_SB(0, 1), b2 + hstep, voffB); G_STAGE(G_SA(0, 0), a2, voffA);
;             WAIT_V(8); WAIT_L(0); BAR; G_MMA(1, 0, At, B0); G_MMA(1, 1, At, B1); BAR; SCHED;
;             G_LDB(B0, 1, 0); G_LDB(B1, 1, 1); SCHED; G_LDA(At, 1, 0); G_STAGE(G_SA(0, 1), a2 + hstep, voffA);
	s_setprio 1
	s_waitcnt lgkmcnt(0)
	v_mfma_f32_16x16x32_bf16 v[124:127], v[144:147], v[176:179], v[124:127]
	v_mfma_f32_16x16x32_bf16 v[120:123], v[152:155], v[176:179], v[120:123]
	v_mfma_f32_16x16x32_bf16 v[108:111], v[144:147], v[188:191], v[108:111]
	v_mfma_f32_16x16x32_bf16 v[104:107], v[152:155], v[188:191], v[104:107]
	v_mfma_f32_16x16x32_bf16 v[92:95], v[144:147], v[196:199], v[92:95]
	v_mfma_f32_16x16x32_bf16 v[88:91], v[152:155], v[196:199], v[88:91]
	v_mfma_f32_16x16x32_bf16 v[76:79], v[144:147], v[204:207], v[76:79]
	v_mfma_f32_16x16x32_bf16 v[72:75], v[152:155], v[204:207], v[72:75]
	v_mfma_f32_16x16x32_bf16 v[124:127], v[148:151], v[180:183], v[124:127]
	v_mfma_f32_16x16x32_bf16 v[120:123], v[156:159], v[180:183], v[120:123]
	v_mfma_f32_16x16x32_bf16 v[108:111], v[148:151], v[192:195], v[108:111]
	v_mfma_f32_16x16x32_bf16 v[104:107], v[156:159], v[192:195], v[104:107]
	v_mfma_f32_16x16x32_bf16 v[92:95], v[148:151], v[200:203], v[92:95]
	v_mfma_f32_16x16x32_bf16 v[88:91], v[156:159], v[200:203], v[88:91]
	v_mfma_f32_16x16x32_bf16 v[76:79], v[148:151], v[208:211], v[76:79]
	v_mfma_f32_16x16x32_bf16 v[72:75], v[156:159], v[208:211], v[72:75]
	s_setprio 0
	s_setprio 1
	v_mfma_f32_16x16x32_bf16 v[116:119], v[160:163], v[176:179], v[116:119]
	v_mfma_f32_16x16x32_bf16 v[112:115], v[168:171], v[176:179], v[112:115]
	v_mfma_f32_16x16x32_bf16 v[100:103], v[160:163], v[188:191], v[100:103]
	v_mfma_f32_16x16x32_bf16 v[96:99], v[168:171], v[188:191], v[96:99]
	v_mfma_f32_16x16x32_bf16 v[84:87], v[160:163], v[196:199], v[84:87]
	v_mfma_f32_16x16x32_bf16 v[80:83], v[168:171], v[196:199], v[80:83]
	v_mfma_f32_16x16x32_bf16 v[68:71], v[160:163], v[204:207], v[68:71]
	v_mfma_f32_16x16x32_bf16 v[64:67], v[168:171], v[204:207], v[64:67]
	v_mfma_f32_16x16x32_bf16 v[116:119], v[164:167], v[180:183], v[116:119]
	v_mfma_f32_16x16x32_bf16 v[112:115], v[172:175], v[180:183], v[112:115]
	v_mfma_f32_16x16x32_bf16 v[100:103], v[164:167], v[192:195], v[100:103]
	v_mfma_f32_16x16x32_bf16 v[96:99], v[172:175], v[192:195], v[96:99]
	v_mfma_f32_16x16x32_bf16 v[84:87], v[164:167], v[200:203], v[84:87]
	v_mfma_f32_16x16x32_bf16 v[80:83], v[172:175], v[200:203], v[80:83]
	v_mfma_f32_16x16x32_bf16 v[68:71], v[164:167], v[208:211], v[68:71]
	v_mfma_f32_16x16x32_bf16 v[64:67], v[172:175], v[208:211], v[64:67]
	s_setprio 0
	s_add_i32 s55, s45, s26
	v_lshl_add_u64 v[184:185], s[14:15], 0, v[132:133]
	s_mov_b32 m0, s55
	s_barrier
	ds_read_b128 v[176:179], v143 offset:16384
	ds_read_b128 v[180:183], v143 offset:17408
	ds_read_b128 v[188:191], v143 offset:18432
	ds_read_b128 v[192:195], v143 offset:19456
	ds_read_b128 v[196:199], v143 offset:20480
	ds_read_b128 v[200:203], v143 offset:21504
	ds_read_b128 v[204:207], v143 offset:22528
	ds_read_b128 v[208:211], v143 offset:23552
	global_load_lds_dwordx4 v[184:185], off
	s_add_i32 m0, s55, 0x2000
	s_add_u32 s56, s14, 0x40000
	v_lshl_add_u64 v[186:187], s[14:15], 0, v[128:129]
	s_addc_u32 s57, s15, 0
	s_add_i32 s55, s46, s26
	global_load_lds_dwordx4 v[186:187], off
	v_lshl_add_u64 v[212:213], s[56:57], 0, v[132:133]
	s_mov_b32 m0, s55
	v_lshl_add_u64 v[214:215], s[38:39], 0, v[130:131]
	global_load_lds_dwordx4 v[212:213], off
	v_lshl_add_u64 v[212:213], s[56:57], 0, v[128:129]
	s_add_i32 m0, s55, 0x2000
	s_nop 0
	global_load_lds_dwordx4 v[212:213], off
	v_lshl_add_u64 v[212:213], s[38:39], 0, v[134:135]
	s_mov_b32 m0, s31
	s_nop 0
	global_load_lds_dwordx4 v[212:213], off
	s_mov_b32 m0, s35
	s_nop 0
	global_load_lds_dwordx4 v[214:215], off
	s_waitcnt vmcnt(8)
	s_waitcnt lgkmcnt(0)
	s_barrier
	s_setprio 1
	s_waitcnt lgkmcnt(0)
	v_mfma_f32_16x16x32_bf16 v[60:63], v[144:147], v[176:179], v[60:63]
	v_mfma_f32_16x16x32_bf16 v[56:59], v[152:155], v[176:179], v[56:59]
	v_mfma_f32_16x16x32_bf16 v[44:47], v[144:147], v[188:191], v[44:47]
	v_mfma_f32_16x16x32_bf16 v[40:43], v[152:155], v[188:191], v[40:43]
	v_mfma_f32_16x16x32_bf16 v[28:31], v[144:147], v[196:199], v[28:31]
	v_mfma_f32_16x16x32_bf16 v[24:27], v[152:155], v[196:199], v[24:27]
	v_mfma_f32_16x16x32_bf16 v[12:15], v[144:147], v[204:207], v[12:15]
	v_mfma_f32_16x16x32_bf16 v[8:11], v[152:155], v[204:207], v[8:11]
	v_mfma_f32_16x16x32_bf16 v[60:63], v[148:151], v[180:183], v[60:63]
	v_mfma_f32_16x16x32_bf16 v[56:59], v[156:159], v[180:183], v[56:59]
	v_mfma_f32_16x16x32_bf16 v[44:47], v[148:151], v[192:195], v[44:47]
	v_mfma_f32_16x16x32_bf16 v[40:43], v[156:159], v[192:195], v[40:43]
	v_mfma_f32_16x16x32_bf16 v[28:31], v[148:151], v[200:203], v[28:31]
	v_mfma_f32_16x16x32_bf16 v[24:27], v[156:159], v[200:203], v[24:27]
	v_mfma_f32_16x16x32_bf16 v[12:15], v[148:151], v[208:211], v[12:15]
	v_mfma_f32_16x16x32_bf16 v[8:11], v[156:159], v[208:211], v[8:11]
	s_setprio 0
	s_setprio 1
	v_mfma_f32_16x16x32_bf16 v[52:55], v[160:163], v[176:179], v[52:55]
	v_mfma_f32_16x16x32_bf16 v[48:51], v[168:171], v[176:179], v[48:51]
	v_mfma_f32_16x16x32_bf16 v[36:39], v[160:163], v[188:191], v[36:39]
	v_mfma_f32_16x16x32_bf16 v[32:35], v[168:171], v[188:191], v[32:35]
	v_mfma_f32_16x16x32_bf16 v[20:23], v[160:163], v[196:199], v[20:23]
	v_mfma_f32_16x16x32_bf16 v[16:19], v[168:171], v[196:199], v[16:19]
	v_mfma_f32_16x16x32_bf16 v[4:7], v[160:163], v[204:207], v[4:7]
	v_mfma_f32_16x16x32_bf16 v[0:3], v[168:171], v[204:207], v[0:3]
	v_mfma_f32_16x16x32_bf16 v[52:55], v[164:167], v[180:183], v[52:55]
	v_mfma_f32_16x16x32_bf16 v[48:51], v[172:175], v[180:183], v[48:51]
	v_mfma_f32_16x16x32_bf16 v[36:39], v[164:167], v[192:195], v[36:39]
	v_mfma_f32_16x16x32_bf16 v[32:35], v[172:175], v[192:195], v[32:35]
	v_mfma_f32_16x16x32_bf16 v[20:23], v[164:167], v[200:203], v[20:23]
	v_mfma_f32_16x16x32_bf16 v[16:19], v[172:175], v[200:203], v[16:19]
	v_mfma_f32_16x16x32_bf16 v[4:7], v[164:167], v[208:211], v[4:7]
	v_mfma_f32_16x16x32_bf16 v[0:3], v[172:175], v[208:211], v[0:3]
	s_setprio 0
	s_add_i32 s55, 0, 0x18000
	s_add_i32 s56, 0, 0x1c000
	v_add_u32_e32 v156, s55, v140
	s_barrier
; #define G_STAGE(bufoff, gbase, voff) do { _Pragma("unroll") for (int _i = 0; _i < 2; ++_i) \
;         __builtin_amdgcn_global_load_lds((const unsigned*)((const char*)(gbase) + voff[_i]), (LAS unsigned*)(lds + (bufoff) + ldsw + _i * 8192), 16, 0, 0); } while (0)
; #define G_LDA(dst, b, h) do { _Pragma("unroll") for (int m = 0; m < 4; ++m) _Pragma("unroll") for (int k = 0; k < 2; ++k) dst[m][k] = *(const LAS bf16x8*)(lds + G_SA(b, h) + aoff + m * 2048 + k * 1024); } while (0)
; #define G_LDB(dst, b, h) do { _Pragma("unroll") for (int n = 0; n < 2; ++n) _Pragma("unroll") for (int k = 0; k < 2; ++k) dst[n][k] = *(const LAS bf16x8*)(lds + G_SB(b, h) + boff + n * 2048 + k * 1024); } while (0)
; #define G_MMA(ai, bj, At_, Bt_) do { __builtin_amdgcn_s_setprio(1); _Pragma("unroll") for (int m = 0; m < 4; ++m) _Pragma("unroll") for (int n = 0; n < 2; ++n) _Pragma("unroll") for (int k = 0; k < 2; ++k) \
;         acc[ai][bj][m][n] = __builtin_amdgcn_mfma_f32_16x16x32_bf16(Bt_[n][k], At_[m][k], acc[ai][bj][m][n], 0, 0, 0); __builtin_amdgcn_s_setprio(0); } while (0)
; #define WAIT_V(n) asm volatile("s_waitcnt vmcnt(" #n ")" ::: "memory")
; #define WAIT_L(n) asm volatile("s_waitcnt lgkmcnt(" #n ")" ::: "memory")
; #define BAR __builtin_amdgcn_s_barrier()
; #define SCHED __builtin_amdgcn_sched_barrier(0)
; template <class Get, class Epi>
; DI void gemm_loop(int ntiles, int ld, char* shm, const Get& get, const Epi& epi) {
;     ...
;             G_LDB(B0, 1, 0); G_LDB(B1, 1, 1); SCHED; G_LDA(At, 1, 0); G_STAGE(G_SA(0, 1), a2 + hstep, voffA);
;             WAIT_V(8); WAIT_L(0); BAR; G_MMA(0, 0, At, B0); G_MMA(0, 1, At, B1); BAR; SCHED;
;             G_LDA(At, 1, 1); G_STAGE(G_SB(1, 0), b3, voffB); G_STAGE(G_SB(1, 1), b3 + hstep, voffB); G_STAGE(G_SA(1, 0), a3, voffA);
	v_add_u32_e32 v172, s56, v140
	ds_read_b128 v[144:147], v156
	ds_read_b128 v[148:151], v156 offset:1024
	ds_read_b128 v[152:155], v156 offset:2048
	ds_read_b128 v[156:159], v156 offset:3072
	ds_read_b128 v[160:163], v172
	ds_read_b128 v[164:167], v172 offset:1024
	ds_read_b128 v[168:171], v172 offset:2048
	ds_read_b128 v[172:175], v172 offset:3072
	s_add_u32 s38, s38, 0x40000
	s_addc_u32 s39, s39, 0
	s_mov_b32 m0, s41
	v_lshl_add_u64 v[216:217], s[38:39], 0, v[134:135]
	ds_read_b128 v[176:179], v143 offset:32768
	ds_read_b128 v[180:183], v143 offset:33792
	ds_read_b128 v[188:191], v143 offset:34816
	ds_read_b128 v[192:195], v143 offset:35840
	ds_read_b128 v[196:199], v143 offset:36864
	ds_read_b128 v[200:203], v143 offset:37888
	ds_read_b128 v[204:207], v143 offset:38912
	ds_read_b128 v[208:211], v143 offset:39936
	global_load_lds_dwordx4 v[216:217], off
	v_lshl_add_u64 v[216:217], s[38:39], 0, v[130:131]
	s_mov_b32 m0, s42
	s_nop 0
	global_load_lds_dwordx4 v[216:217], off
	s_waitcnt vmcnt(8)
	s_waitcnt lgkmcnt(0)
	s_barrier
	s_setprio 1
	s_waitcnt lgkmcnt(0)
	v_mfma_f32_16x16x32_bf16 v[124:127], v[144:147], v[176:179], v[124:127]
	v_mfma_f32_16x16x32_bf16 v[120:123], v[152:155], v[176:179], v[120:123]
	v_mfma_f32_16x16x32_bf16 v[108:111], v[144:147], v[188:191], v[108:111]
	v_mfma_f32_16x16x32_bf16 v[104:107], v[152:155], v[188:191], v[104:107]
	v_mfma_f32_16x16x32_bf16 v[92:95], v[144:147], v[196:199], v[92:95]
	v_mfma_f32_16x16x32_bf16 v[88:91], v[152:155], v[196:199], v[88:91]
	v_mfma_f32_16x16x32_bf16 v[76:79], v[144:147], v[204:207], v[76:79]
	v_mfma_f32_16x16x32_bf16 v[72:75], v[152:155], v[204:207], v[72:75]
	v_mfma_f32_16x16x32_bf16 v[124:127], v[148:151], v[180:183], v[124:127]
	v_mfma_f32_16x16x32_bf16 v[120:123], v[156:159], v[180:183], v[120:123]
	v_mfma_f32_16x16x32_bf16 v[108:111], v[148:151], v[192:195], v[108:111]
	v_mfma_f32_16x16x32_bf16 v[104:107], v[156:159], v[192:195], v[104:107]
	v_mfma_f32_16x16x32_bf16 v[92:95], v[148:151], v[200:203], v[92:95]
	v_mfma_f32_16x16x32_bf16 v[88:91], v[156:159], v[200:203], v[88:91]
	v_mfma_f32_16x16x32_bf16 v[76:79], v[148:151], v[208:211], v[76:79]
	v_mfma_f32_16x16x32_bf16 v[72:75], v[156:159], v[208:211], v[72:75]
	s_setprio 0
	s_setprio 1
	v_mfma_f32_16x16x32_bf16 v[116:119], v[160:163], v[176:179], v[116:119]
	v_mfma_f32_16x16x32_bf16 v[112:115], v[168:171], v[176:179], v[112:115]
	v_mfma_f32_16x16x32_bf16 v[100:103], v[160:163], v[188:191], v[100:103]
	v_mfma_f32_16x16x32_bf16 v[96:99], v[168:171], v[188:191], v[96:99]
	v_mfma_f32_16x16x32_bf16 v[84:87], v[160:163], v[196:199], v[84:87]
	v_mfma_f32_16x16x32_bf16 v[80:83], v[168:171], v[196:199], v[80:83]
	v_mfma_f32_16x16x32_bf16 v[68:71], v[160:163], v[204:207], v[68:71]
	v_mfma_f32_16x16x32_bf16 v[64:67], v[168:171], v[204:207], v[64:67]
	v_mfma_f32_16x16x32_bf16 v[116:119], v[164:167], v[180:183], v[116:119]
	v_mfma_f32_16x16x32_bf16 v[112:115], v[172:175], v[180:183], v[112:115]
	v_mfma_f32_16x16x32_bf16 v[100:103], v[164:167], v[192:195], v[100:103]
	v_mfma_f32_16x16x32_bf16 v[96:99], v[172:175], v[192:195], v[96:99]
	v_mfma_f32_16x16x32_bf16 v[84:87], v[164:167], v[200:203], v[84:87]
	v_mfma_f32_16x16x32_bf16 v[80:83], v[172:175], v[200:203], v[80:83]
	v_mfma_f32_16x16x32_bf16 v[68:71], v[164:167], v[208:211], v[68:71]
	v_mfma_f32_16x16x32_bf16 v[64:67], v[172:175], v[208:211], v[64:67]
	s_setprio 0
	s_add_i32 s38, s55, s26
	v_lshl_add_u64 v[184:185], v[184:185], 0, s[2:3]
	s_mov_b32 m0, s38
	s_barrier
; #define G_STAGE(bufoff, gbase, voff) do { _Pragma("unroll") for (int _i = 0; _i < 2; ++_i) \
;         __builtin_amdgcn_global_load_lds((const unsigned*)((const char*)(gbase) + voff[_i]), (LAS unsigned*)(lds + (bufoff) + ldsw + _i * 8192), 16, 0, 0); } while (0)
; #define G_LDA(dst, b, h) do { _Pragma("unroll") for (int m = 0; m < 4; ++m) _Pragma("unroll") for (int k = 0; k < 2; ++k) dst[m][k] = *(const LAS bf16x8*)(lds + G_SA(b, h) + aoff + m * 2048 + k * 1024); } while (0)
; #define G_MMA(ai, bj, At_, Bt_) do { __builtin_amdgcn_s_setprio(1); _Pragma("unroll") for (int m = 0; m < 4; ++m) _Pragma("unroll") for (int n = 0; n < 2; ++n) _Pragma("unroll") for (int k = 0; k < 2; ++k) \
;         acc[ai][bj][m][n] = __builtin_amdgcn_mfma_f32_16x16x32_bf16(Bt_[n][k], At_[m][k], acc[ai][bj][m][n], 0, 0, 0); __builtin_amdgcn_s_setprio(0); } while (0)
; #define WAIT_V(n) asm volatile("s_waitcnt vmcnt(" #n ")" ::: "memory")
; #define WAIT_L(n) asm volatile("s_waitcnt lgkmcnt(" #n ")" ::: "memory")
; #define BAR __builtin_amdgcn_s_barrier()
; #define SCHED __builtin_amdgcn_sched_barrier(0)
; template <class Get, class Epi>
; DI void gemm_loop(int ntiles, int ld, char* shm, const Get& get, const Epi& epi) {
;     ...
;             G_LDA(At, 1, 1); G_STAGE(G_SB(1, 0), b3, voffB); G_STAGE(G_SB(1, 1), b3 + hstep, voffB); G_STAGE(G_SA(1, 0), a3, voffA);
;             WAIT_V(8); WAIT_L(0); BAR; G_MMA(1, 0, At, B0); G_MMA(1, 1, At, B1); BAR; SCHED;
;         }
	ds_read_b128 v[176:179], v143 offset:49152
	ds_read_b128 v[180:183], v143 offset:50176
	ds_read_b128 v[188:191], v143 offset:51200
	ds_read_b128 v[192:195], v143 offset:52224
	ds_read_b128 v[196:199], v143 offset:53248
	ds_read_b128 v[200:203], v143 offset:54272
	ds_read_b128 v[204:207], v143 offset:55296
	ds_read_b128 v[208:211], v143 offset:56320
	global_load_lds_dwordx4 v[184:185], off
	s_add_i32 m0, s38, 0x2000
	s_add_u32 s14, s14, 0x40080
	v_lshl_add_u64 v[184:185], v[186:187], 0, s[2:3]
	s_addc_u32 s15, s15, 0
	s_add_i32 s38, s56, s26
	global_load_lds_dwordx4 v[184:185], off
	v_lshl_add_u64 v[184:185], s[14:15], 0, v[132:133]
	s_mov_b32 m0, s38
	s_nop 0
	global_load_lds_dwordx4 v[184:185], off
	v_lshl_add_u64 v[184:185], s[14:15], 0, v[128:129]
	s_add_i32 m0, s38, 0x2000
	s_nop 0
	global_load_lds_dwordx4 v[184:185], off
	v_lshl_add_u64 v[184:185], v[212:213], 0, s[2:3]
	s_mov_b32 m0, s43
	s_nop 0
	global_load_lds_dwordx4 v[184:185], off
	v_lshl_add_u64 v[184:185], v[214:215], 0, s[2:3]
	s_mov_b32 m0, s44
	s_nop 0
	global_load_lds_dwordx4 v[184:185], off
	s_waitcnt vmcnt(8)
	s_waitcnt lgkmcnt(0)
	s_barrier
	s_setprio 1
	s_waitcnt lgkmcnt(0)
	v_mfma_f32_16x16x32_bf16 v[60:63], v[144:147], v[176:179], v[60:63]
	v_mfma_f32_16x16x32_bf16 v[56:59], v[152:155], v[176:179], v[56:59]
	v_mfma_f32_16x16x32_bf16 v[44:47], v[144:147], v[188:191], v[44:47]
	v_mfma_f32_16x16x32_bf16 v[40:43], v[152:155], v[188:191], v[40:43]
	v_mfma_f32_16x16x32_bf16 v[28:31], v[144:147], v[196:199], v[28:31]
	v_mfma_f32_16x16x32_bf16 v[24:27], v[152:155], v[196:199], v[24:27]
	v_mfma_f32_16x16x32_bf16 v[12:15], v[144:147], v[204:207], v[12:15]
	v_mfma_f32_16x16x32_bf16 v[8:11], v[152:155], v[204:207], v[8:11]
	v_mfma_f32_16x16x32_bf16 v[60:63], v[148:151], v[180:183], v[60:63]
	v_mfma_f32_16x16x32_bf16 v[56:59], v[156:159], v[180:183], v[56:59]
	v_mfma_f32_16x16x32_bf16 v[44:47], v[148:151], v[192:195], v[44:47]
	v_mfma_f32_16x16x32_bf16 v[40:43], v[156:159], v[192:195], v[40:43]
	v_mfma_f32_16x16x32_bf16 v[28:31], v[148:151], v[200:203], v[28:31]
	v_mfma_f32_16x16x32_bf16 v[24:27], v[156:159], v[200:203], v[24:27]
	v_mfma_f32_16x16x32_bf16 v[12:15], v[148:151], v[208:211], v[12:15]
	v_mfma_f32_16x16x32_bf16 v[8:11], v[156:159], v[208:211], v[8:11]
	s_setprio 0
	s_setprio 1
	v_mfma_f32_16x16x32_bf16 v[52:55], v[160:163], v[176:179], v[52:55]
	v_mfma_f32_16x16x32_bf16 v[48:51], v[168:171], v[176:179], v[48:51]
	v_mfma_f32_16x16x32_bf16 v[36:39], v[160:163], v[188:191], v[36:39]
	v_mfma_f32_16x16x32_bf16 v[32:35], v[168:171], v[188:191], v[32:35]
	v_mfma_f32_16x16x32_bf16 v[20:23], v[160:163], v[196:199], v[20:23]
	v_mfma_f32_16x16x32_bf16 v[16:19], v[168:171], v[196:199], v[16:19]
	v_mfma_f32_16x16x32_bf16 v[4:7], v[160:163], v[204:207], v[4:7]
	v_mfma_f32_16x16x32_bf16 v[0:3], v[168:171], v[204:207], v[0:3]
	v_mfma_f32_16x16x32_bf16 v[52:55], v[164:167], v[180:183], v[52:55]
	v_mfma_f32_16x16x32_bf16 v[48:51], v[172:175], v[180:183], v[48:51]
	v_mfma_f32_16x16x32_bf16 v[36:39], v[164:167], v[192:195], v[36:39]
	v_mfma_f32_16x16x32_bf16 v[32:35], v[172:175], v[192:195], v[32:35]
	v_mfma_f32_16x16x32_bf16 v[20:23], v[164:167], v[200:203], v[20:23]
	v_mfma_f32_16x16x32_bf16 v[16:19], v[172:175], v[200:203], v[16:19]
	v_mfma_f32_16x16x32_bf16 v[4:7], v[164:167], v[208:211], v[4:7]
	v_mfma_f32_16x16x32_bf16 v[0:3], v[172:175], v[208:211], v[0:3]
	s_setprio 0
	s_add_i32 s54, s54, 2
	s_add_u32 s36, s36, 0x100
	s_addc_u32 s37, s37, 0
	s_add_u32 s52, s52, 0x100
	s_addc_u32 s53, s53, 0
	s_cmp_gt_u32 s54, 13
	s_barrier
	s_cbranch_scc0 .LBB0_763

; #define G_STAGE(bufoff, gbase, voff) do { _Pragma("unroll") for (int _i = 0; _i < 2; ++_i) \
;         __builtin_amdgcn_global_load_lds((const unsigned*)((const char*)(gbase) + voff[_i]), (LAS unsigned*)(lds + (bufoff) + ldsw + _i * 8192), 16, 0, 0); } while (0)
; #define G_LDA(dst, b, h) do { _Pragma("unroll") for (int m = 0; m < 4; ++m) _Pragma("unroll") for (int k = 0; k < 2; ++k) dst[m][k] = *(const LAS bf16x8*)(lds + G_SA(b, h) + aoff + m * 2048 + k * 1024); } while (0)
; #define G_LDB(dst, b, h) do { _Pragma("unroll") for (int n = 0; n < 2; ++n) _Pragma("unroll") for (int k = 0; k < 2; ++k) dst[n][k] = *(const LAS bf16x8*)(lds + G_SB(b, h) + boff + n * 2048 + k * 1024); } while (0)
; #define G_MMA(ai, bj, At_, Bt_) do { __builtin_amdgcn_s_setprio(1); _Pragma("unroll") for (int m = 0; m < 4; ++m) _Pragma("unroll") for (int n = 0; n < 2; ++n) _Pragma("unroll") for (int k = 0; k < 2; ++k) \
;         acc[ai][bj][m][n] = __builtin_amdgcn_mfma_f32_16x16x32_bf16(Bt_[n][k], At_[m][k], acc[ai][bj][m][n], 0, 0, 0); __builtin_amdgcn_s_setprio(0); } while (0)
; #define WAIT_V(n) asm volatile("s_waitcnt vmcnt(" #n ")" ::: "memory")
; #define WAIT_L(n) asm volatile("s_waitcnt lgkmcnt(" #n ")" ::: "memory")
; #define BAR __builtin_amdgcn_s_barrier()
; #define SCHED __builtin_amdgcn_sched_barrier(0)
; template <class Get, class Epi>
; DI void gemm_loop(int ntiles, int ld, char* shm, const Get& get, const Epi& epi) {
;     ...
;             const bool last = (t == nt - 2);
;             const char* a1 = cA + (size_t)(t + 1) * kstep;
;             const char* a2 = last ? nA : cA + (size_t)(t + 2) * kstep; const char* b2 = last ? nB : cB + (size_t)(t + 2) * kstep;
;             const char* a3 = a2 + kstep; const char* b3 = b2 + kstep;
;             G_LDB(B0, 0, 0); G_LDB(B1, 0, 1); SCHED; G_LDA(At, 0, 0); G_STAGE(G_SA(1, 1), a1 + hstep, voffA);
;             WAIT_V(8); WAIT_L(0); BAR; G_MMA(0, 0, At, B0); G_MMA(0, 1, At, B1); BAR; SCHED;
;             G_LDA(At, 0, 1); G_STAGE(G_SB(0, 0), b2, voffB); G_STAGE(G_SB(0, 1), b2 + hstep, voffB); G_STAGE(G_SA(0, 0), a2, voffA);
.Lpeel_850:
	ds_read_b128 v[128:131], v169
	ds_read_b128 v[132:135], v169 offset:1024
	ds_read_b128 v[136:139], v169 offset:2048
	ds_read_b128 v[140:143], v169 offset:3072
	ds_read_b128 v[158:161], v170
	ds_read_b128 v[162:165], v170 offset:1024
	ds_read_b128 v[172:175], v170 offset:2048
	ds_read_b128 v[176:179], v170 offset:3072
	s_add_i32 s75, s38, 2
	s_add_u32 s14, s4, 0x100
	s_addc_u32 s15, s5, 0
	s_cmp_eq_u32 s72, s38
	s_cselect_b32 s38, s36, s73
	s_cselect_b32 s41, s35, s15
	s_cselect_b32 s40, s34, s14
	s_cselect_b32 s39, s37, s74
	v_lshl_add_u64 v[144:145], s[4:5], 0, v[154:155]
	s_add_i32 m0, s42, 0xc000
	ds_read_b128 v[180:183], v171
	ds_read_b128 v[188:191], v171 offset:1024
	ds_read_b128 v[192:195], v171 offset:2048
	ds_read_b128 v[196:199], v171 offset:3072
	ds_read_b128 v[200:203], v171 offset:4096
	ds_read_b128 v[204:207], v171 offset:5120
	ds_read_b128 v[208:211], v171 offset:6144
	ds_read_b128 v[212:215], v171 offset:7168
	global_load_lds_dwordx4 v[144:145], off
	v_lshl_add_u64 v[144:145], s[4:5], 0, v[156:157]
	s_add_i32 m0, s42, 0xe000
	s_nop 0
	global_load_lds_dwordx4 v[144:145], off
	s_waitcnt vmcnt(8)
	s_waitcnt lgkmcnt(0)
	s_barrier
	s_setprio 1
	s_waitcnt lgkmcnt(0)
	v_mfma_f32_16x16x32_bf16 v[124:127], v[128:131], v[180:183], 0
	v_mfma_f32_16x16x32_bf16 v[120:123], v[136:139], v[180:183], 0
	v_mfma_f32_16x16x32_bf16 v[116:119], v[128:131], v[192:195], 0
	v_mfma_f32_16x16x32_bf16 v[112:115], v[136:139], v[192:195], 0
	v_mfma_f32_16x16x32_bf16 v[108:111], v[128:131], v[200:203], 0
	v_mfma_f32_16x16x32_bf16 v[104:107], v[136:139], v[200:203], 0
	v_mfma_f32_16x16x32_bf16 v[100:103], v[128:131], v[208:211], 0
	v_mfma_f32_16x16x32_bf16 v[96:99], v[136:139], v[208:211], 0
	v_mfma_f32_16x16x32_bf16 v[124:127], v[132:135], v[188:191], v[124:127]
	v_mfma_f32_16x16x32_bf16 v[120:123], v[140:143], v[188:191], v[120:123]
	v_mfma_f32_16x16x32_bf16 v[116:119], v[132:135], v[196:199], v[116:119]
	v_mfma_f32_16x16x32_bf16 v[112:115], v[140:143], v[196:199], v[112:115]
	v_mfma_f32_16x16x32_bf16 v[108:111], v[132:135], v[204:207], v[108:111]
	v_mfma_f32_16x16x32_bf16 v[104:107], v[140:143], v[204:207], v[104:107]
	v_mfma_f32_16x16x32_bf16 v[100:103], v[132:135], v[212:215], v[100:103]
	v_mfma_f32_16x16x32_bf16 v[96:99], v[140:143], v[212:215], v[96:99]
	s_setprio 0
	s_setprio 1
	v_mfma_f32_16x16x32_bf16 v[60:63], v[158:161], v[180:183], 0
	v_mfma_f32_16x16x32_bf16 v[56:59], v[172:175], v[180:183], 0
	v_mfma_f32_16x16x32_bf16 v[52:55], v[158:161], v[192:195], 0
	v_mfma_f32_16x16x32_bf16 v[48:51], v[172:175], v[192:195], 0
	v_mfma_f32_16x16x32_bf16 v[44:47], v[158:161], v[200:203], 0
	v_mfma_f32_16x16x32_bf16 v[40:43], v[172:175], v[200:203], 0
	v_mfma_f32_16x16x32_bf16 v[36:39], v[158:161], v[208:211], 0
	v_mfma_f32_16x16x32_bf16 v[32:35], v[172:175], v[208:211], 0
	v_mfma_f32_16x16x32_bf16 v[60:63], v[162:165], v[188:191], v[60:63]
	v_mfma_f32_16x16x32_bf16 v[56:59], v[176:179], v[188:191], v[56:59]
	v_mfma_f32_16x16x32_bf16 v[52:55], v[162:165], v[196:199], v[52:55]
	v_mfma_f32_16x16x32_bf16 v[48:51], v[176:179], v[196:199], v[48:51]
	v_mfma_f32_16x16x32_bf16 v[44:47], v[162:165], v[204:207], v[44:47]
	v_mfma_f32_16x16x32_bf16 v[40:43], v[176:179], v[204:207], v[40:43]
	v_mfma_f32_16x16x32_bf16 v[36:39], v[162:165], v[212:215], v[36:39]
	v_mfma_f32_16x16x32_bf16 v[32:35], v[176:179], v[212:215], v[32:35]
	s_setprio 0
	s_add_i32 s4, s50, s26
	v_lshl_add_u64 v[144:145], s[38:39], 0, v[148:149]
	s_mov_b32 m0, s4
	s_barrier
	ds_read_b128 v[180:183], v171 offset:16384
	ds_read_b128 v[188:191], v171 offset:17408
	ds_read_b128 v[192:195], v171 offset:18432
	ds_read_b128 v[196:199], v171 offset:19456
	ds_read_b128 v[200:203], v171 offset:20480
	ds_read_b128 v[204:207], v171 offset:21504
	ds_read_b128 v[208:211], v171 offset:22528
	ds_read_b128 v[212:215], v171 offset:23552
	global_load_lds_dwordx4 v[144:145], off
	s_add_i32 m0, s4, 0x2000
	s_add_u32 s4, s38, 0xb0000
	v_lshl_add_u64 v[166:167], s[38:39], 0, v[152:153]
	s_addc_u32 s5, s39, 0
	s_add_i32 s76, s51, s26
	global_load_lds_dwordx4 v[166:167], off
	v_lshl_add_u64 v[184:185], s[4:5], 0, v[148:149]
	s_mov_b32 m0, s76
	v_lshl_add_u64 v[186:187], s[40:41], 0, v[150:151]
	global_load_lds_dwordx4 v[184:185], off
	v_lshl_add_u64 v[184:185], s[4:5], 0, v[152:153]
	s_add_i32 m0, s76, 0x2000
	s_nop 0
	global_load_lds_dwordx4 v[184:185], off
	v_lshl_add_u64 v[184:185], s[40:41], 0, v[146:147]
	s_mov_b32 m0, s42
	s_nop 0
	global_load_lds_dwordx4 v[184:185], off
	s_mov_b32 m0, s43
	s_nop 0
	global_load_lds_dwordx4 v[186:187], off
	s_waitcnt vmcnt(8)
	s_waitcnt lgkmcnt(0)
	s_barrier
; #define G_STAGE(bufoff, gbase, voff) do { _Pragma("unroll") for (int _i = 0; _i < 2; ++_i) \
;         __builtin_amdgcn_global_load_lds((const unsigned*)((const char*)(gbase) + voff[_i]), (LAS unsigned*)(lds + (bufoff) + ldsw + _i * 8192), 16, 0, 0); } while (0)
; #define G_LDA(dst, b, h) do { _Pragma("unroll") for (int m = 0; m < 4; ++m) _Pragma("unroll") for (int k = 0; k < 2; ++k) dst[m][k] = *(const LAS bf16x8*)(lds + G_SA(b, h) + aoff + m * 2048 + k * 1024); } while (0)
; #define G_LDB(dst, b, h) do { _Pragma("unroll") for (int n = 0; n < 2; ++n) _Pragma("unroll") for (int k = 0; k < 2; ++k) dst[n][k] = *(const LAS bf16x8*)(lds + G_SB(b, h) + boff + n * 2048 + k * 1024); } while (0)
; #define G_MMA(ai, bj, At_, Bt_) do { __builtin_amdgcn_s_setprio(1); _Pragma("unroll") for (int m = 0; m < 4; ++m) _Pragma("unroll") for (int n = 0; n < 2; ++n) _Pragma("unroll") for (int k = 0; k < 2; ++k) \
;         acc[ai][bj][m][n] = __builtin_amdgcn_mfma_f32_16x16x32_bf16(Bt_[n][k], At_[m][k], acc[ai][bj][m][n], 0, 0, 0); __builtin_amdgcn_s_setprio(0); } while (0)
; #define WAIT_V(n) asm volatile("s_waitcnt vmcnt(" #n ")" ::: "memory")
; #define WAIT_L(n) asm volatile("s_waitcnt lgkmcnt(" #n ")" ::: "memory")
; #define BAR __builtin_amdgcn_s_barrier()
; #define SCHED __builtin_amdgcn_sched_barrier(0)
; template <class Get, class Epi>
; DI void gemm_loop(int ntiles, int ld, char* shm, const Get& get, const Epi& epi) {
;     ...
;             WAIT_V(8); WAIT_L(0); BAR; G_MMA(1, 0, At, B0); G_MMA(1, 1, At, B1); BAR; SCHED;
;             G_LDB(B0, 1, 0); G_LDB(B1, 1, 1); SCHED; G_LDA(At, 1, 0); G_STAGE(G_SA(0, 1), a2 + hstep, voffA);
;             WAIT_V(8); WAIT_L(0); BAR; G_MMA(0, 0, At, B0); G_MMA(0, 1, At, B1); BAR; SCHED;
	s_setprio 1
	s_waitcnt lgkmcnt(0)
	v_mfma_f32_16x16x32_bf16 v[92:95], v[128:131], v[180:183], 0
	v_mfma_f32_16x16x32_bf16 v[88:91], v[136:139], v[180:183], 0
	v_mfma_f32_16x16x32_bf16 v[84:87], v[128:131], v[192:195], 0
	v_mfma_f32_16x16x32_bf16 v[80:83], v[136:139], v[192:195], 0
	v_mfma_f32_16x16x32_bf16 v[76:79], v[128:131], v[200:203], 0
	v_mfma_f32_16x16x32_bf16 v[72:75], v[136:139], v[200:203], 0
	v_mfma_f32_16x16x32_bf16 v[68:71], v[128:131], v[208:211], 0
	v_mfma_f32_16x16x32_bf16 v[64:67], v[136:139], v[208:211], 0
	v_mfma_f32_16x16x32_bf16 v[92:95], v[132:135], v[188:191], v[92:95]
	v_mfma_f32_16x16x32_bf16 v[88:91], v[140:143], v[188:191], v[88:91]
	v_mfma_f32_16x16x32_bf16 v[84:87], v[132:135], v[196:199], v[84:87]
	v_mfma_f32_16x16x32_bf16 v[80:83], v[140:143], v[196:199], v[80:83]
	v_mfma_f32_16x16x32_bf16 v[76:79], v[132:135], v[204:207], v[76:79]
	v_mfma_f32_16x16x32_bf16 v[72:75], v[140:143], v[204:207], v[72:75]
	v_mfma_f32_16x16x32_bf16 v[68:71], v[132:135], v[212:215], v[68:71]
	v_mfma_f32_16x16x32_bf16 v[64:67], v[140:143], v[212:215], v[64:67]
	s_setprio 0
	s_setprio 1
	v_mfma_f32_16x16x32_bf16 v[28:31], v[158:161], v[180:183], 0
	v_mfma_f32_16x16x32_bf16 v[24:27], v[172:175], v[180:183], 0
	v_mfma_f32_16x16x32_bf16 v[20:23], v[158:161], v[192:195], 0
	v_mfma_f32_16x16x32_bf16 v[16:19], v[172:175], v[192:195], 0
	v_mfma_f32_16x16x32_bf16 v[12:15], v[158:161], v[200:203], 0
	v_mfma_f32_16x16x32_bf16 v[8:11], v[172:175], v[200:203], 0
	v_mfma_f32_16x16x32_bf16 v[4:7], v[158:161], v[208:211], 0
	v_mfma_f32_16x16x32_bf16 v[0:3], v[172:175], v[208:211], 0
	v_mfma_f32_16x16x32_bf16 v[28:31], v[162:165], v[188:191], v[28:31]
	v_mfma_f32_16x16x32_bf16 v[24:27], v[176:179], v[188:191], v[24:27]
	v_mfma_f32_16x16x32_bf16 v[20:23], v[162:165], v[196:199], v[20:23]
	v_mfma_f32_16x16x32_bf16 v[16:19], v[176:179], v[196:199], v[16:19]
	v_mfma_f32_16x16x32_bf16 v[12:15], v[162:165], v[204:207], v[12:15]
	v_mfma_f32_16x16x32_bf16 v[8:11], v[176:179], v[204:207], v[8:11]
	v_mfma_f32_16x16x32_bf16 v[4:7], v[162:165], v[212:215], v[4:7]
	v_mfma_f32_16x16x32_bf16 v[0:3], v[176:179], v[212:215], v[0:3]
	s_setprio 0
	s_add_i32 s76, 0, 0x18000
	s_add_i32 s78, 0, 0x1c000
	v_add_u32_e32 v140, s76, v168
	s_barrier
	v_add_u32_e32 v176, s78, v168
	ds_read_b128 v[128:131], v140
	ds_read_b128 v[132:135], v140 offset:1024
	ds_read_b128 v[136:139], v140 offset:2048
	ds_read_b128 v[140:143], v140 offset:3072
	ds_read_b128 v[158:161], v176
	ds_read_b128 v[162:165], v176 offset:1024
	ds_read_b128 v[172:175], v176 offset:2048
	ds_read_b128 v[176:179], v176 offset:3072
	s_add_u32 s4, s40, 0xb0000
	s_addc_u32 s5, s41, 0
	s_mov_b32 m0, s44
	v_lshl_add_u64 v[216:217], s[4:5], 0, v[146:147]
	ds_read_b128 v[180:183], v171 offset:32768
	ds_read_b128 v[188:191], v171 offset:33792
	ds_read_b128 v[192:195], v171 offset:34816
	ds_read_b128 v[196:199], v171 offset:35840
	ds_read_b128 v[200:203], v171 offset:36864
	ds_read_b128 v[204:207], v171 offset:37888
	ds_read_b128 v[208:211], v171 offset:38912
	ds_read_b128 v[212:215], v171 offset:39936
	global_load_lds_dwordx4 v[216:217], off
	v_lshl_add_u64 v[216:217], s[4:5], 0, v[150:151]
	s_mov_b32 m0, s45
	s_nop 0
	global_load_lds_dwordx4 v[216:217], off
	s_waitcnt vmcnt(8)
	s_waitcnt lgkmcnt(0)
	s_barrier
	s_setprio 1
	s_waitcnt lgkmcnt(0)
	v_mfma_f32_16x16x32_bf16 v[124:127], v[128:131], v[180:183], v[124:127]
	v_mfma_f32_16x16x32_bf16 v[120:123], v[136:139], v[180:183], v[120:123]
	v_mfma_f32_16x16x32_bf16 v[116:119], v[128:131], v[192:195], v[116:119]
	v_mfma_f32_16x16x32_bf16 v[112:115], v[136:139], v[192:195], v[112:115]
	v_mfma_f32_16x16x32_bf16 v[108:111], v[128:131], v[200:203], v[108:111]
	v_mfma_f32_16x16x32_bf16 v[104:107], v[136:139], v[200:203], v[104:107]
	v_mfma_f32_16x16x32_bf16 v[100:103], v[128:131], v[208:211], v[100:103]
	v_mfma_f32_16x16x32_bf16 v[96:99], v[136:139], v[208:211], v[96:99]
	v_mfma_f32_16x16x32_bf16 v[124:127], v[132:135], v[188:191], v[124:127]
	v_mfma_f32_16x16x32_bf16 v[120:123], v[140:143], v[188:191], v[120:123]
	v_mfma_f32_16x16x32_bf16 v[116:119], v[132:135], v[196:199], v[116:119]
	v_mfma_f32_16x16x32_bf16 v[112:115], v[140:143], v[196:199], v[112:115]
	v_mfma_f32_16x16x32_bf16 v[108:111], v[132:135], v[204:207], v[108:111]
	v_mfma_f32_16x16x32_bf16 v[104:107], v[140:143], v[204:207], v[104:107]
	v_mfma_f32_16x16x32_bf16 v[100:103], v[132:135], v[212:215], v[100:103]
	v_mfma_f32_16x16x32_bf16 v[96:99], v[140:143], v[212:215], v[96:99]
	s_setprio 0
	s_setprio 1
	v_mfma_f32_16x16x32_bf16 v[60:63], v[158:161], v[180:183], v[60:63]
	v_mfma_f32_16x16x32_bf16 v[56:59], v[172:175], v[180:183], v[56:59]
	v_mfma_f32_16x16x32_bf16 v[52:55], v[158:161], v[192:195], v[52:55]
	v_mfma_f32_16x16x32_bf16 v[48:51], v[172:175], v[192:195], v[48:51]
	v_mfma_f32_16x16x32_bf16 v[44:47], v[158:161], v[200:203], v[44:47]
	v_mfma_f32_16x16x32_bf16 v[40:43], v[172:175], v[200:203], v[40:43]
	v_mfma_f32_16x16x32_bf16 v[36:39], v[158:161], v[208:211], v[36:39]
	v_mfma_f32_16x16x32_bf16 v[32:35], v[172:175], v[208:211], v[32:35]
	v_mfma_f32_16x16x32_bf16 v[60:63], v[162:165], v[188:191], v[60:63]
	v_mfma_f32_16x16x32_bf16 v[56:59], v[176:179], v[188:191], v[56:59]
	v_mfma_f32_16x16x32_bf16 v[52:55], v[162:165], v[196:199], v[52:55]
	v_mfma_f32_16x16x32_bf16 v[48:51], v[176:179], v[196:199], v[48:51]
	v_mfma_f32_16x16x32_bf16 v[44:47], v[162:165], v[204:207], v[44:47]
	v_mfma_f32_16x16x32_bf16 v[40:43], v[176:179], v[204:207], v[40:43]
	v_mfma_f32_16x16x32_bf16 v[36:39], v[162:165], v[212:215], v[36:39]
	v_mfma_f32_16x16x32_bf16 v[32:35], v[176:179], v[212:215], v[32:35]
	s_setprio 0
	s_add_i32 s4, s76, s26
	v_lshl_add_u64 v[144:145], v[144:145], 0, s[10:11]
	s_mov_b32 m0, s4
	s_barrier
; #define G_STAGE(bufoff, gbase, voff) do { _Pragma("unroll") for (int _i = 0; _i < 2; ++_i) \
;         __builtin_amdgcn_global_load_lds((const unsigned*)((const char*)(gbase) + voff[_i]), (LAS unsigned*)(lds + (bufoff) + ldsw + _i * 8192), 16, 0, 0); } while (0)
; #define G_LDA(dst, b, h) do { _Pragma("unroll") for (int m = 0; m < 4; ++m) _Pragma("unroll") for (int k = 0; k < 2; ++k) dst[m][k] = *(const LAS bf16x8*)(lds + G_SA(b, h) + aoff + m * 2048 + k * 1024); } while (0)
; #define G_LDB(dst, b, h) do { _Pragma("unroll") for (int n = 0; n < 2; ++n) _Pragma("unroll") for (int k = 0; k < 2; ++k) dst[n][k] = *(const LAS bf16x8*)(lds + G_SB(b, h) + boff + n * 2048 + k * 1024); } while (0)
; #define G_MMA(ai, bj, At_, Bt_) do { __builtin_amdgcn_s_setprio(1); _Pragma("unroll") for (int m = 0; m < 4; ++m) _Pragma("unroll") for (int n = 0; n < 2; ++n) _Pragma("unroll") for (int k = 0; k < 2; ++k) \
;         acc[ai][bj][m][n] = __builtin_amdgcn_mfma_f32_16x16x32_bf16(Bt_[n][k], At_[m][k], acc[ai][bj][m][n], 0, 0, 0); __builtin_amdgcn_s_setprio(0); } while (0)
; #define WAIT_V(n) asm volatile("s_waitcnt vmcnt(" #n ")" ::: "memory")
; #define BAR __builtin_amdgcn_s_barrier()
; template <class Get, class Epi>
; DI void gemm_loop(int ntiles, int ld, char* shm, const Get& get, const Epi& epi) {
;     ...
;             const char* a2 = last ? nA : cA + (size_t)(t + 2) * kstep; const char* b2 = last ? nB : cB + (size_t)(t + 2) * kstep;
;             const char* a3 = a2 + kstep; const char* b3 = b2 + kstep;
;             G_LDB(B0, 0, 0); G_LDB(B1, 0, 1); SCHED; G_LDA(At, 0, 0); G_STAGE(G_SA(1, 1), a1 + hstep, voffA);
;             WAIT_V(8); WAIT_L(0); BAR; G_MMA(0, 0, At, B0); G_MMA(0, 1, At, B1); BAR; SCHED;
;             G_LDA(At, 0, 1); G_STAGE(G_SB(0, 0), b2, voffB); G_STAGE(G_SB(0, 1), b2 + hstep, voffB); G_STAGE(G_SA(0, 0), a2, voffA);
;             WAIT_V(8); WAIT_L(0); BAR; G_MMA(1, 0, At, B0); G_MMA(1, 1, At, B1); BAR; SCHED;
;             G_LDB(B0, 1, 0); G_LDB(B1, 1, 1); SCHED; G_LDA(At, 1, 0); G_STAGE(G_SA(0, 1), a2 + hstep, voffA);
;             WAIT_V(8); WAIT_L(0); BAR; G_MMA(0, 0, At, B0); G_MMA(0, 1, At, B1); BAR; SCHED;
;             G_LDA(At, 1, 1); G_STAGE(G_SB(1, 0), b3, voffB); G_STAGE(G_SB(1, 1), b3 + hstep, voffB); G_STAGE(G_SA(1, 0), a3, voffA);
;             WAIT_V(8); WAIT_L(0); BAR; G_MMA(1, 0, At, B0); G_MMA(1, 1, At, B1); BAR; SCHED;
	ds_read_b128 v[180:183], v171 offset:49152
	ds_read_b128 v[188:191], v171 offset:50176
	ds_read_b128 v[192:195], v171 offset:51200
	ds_read_b128 v[196:199], v171 offset:52224
	ds_read_b128 v[200:203], v171 offset:53248
	ds_read_b128 v[204:207], v171 offset:54272
	ds_read_b128 v[208:211], v171 offset:55296
	ds_read_b128 v[212:215], v171 offset:56320
	global_load_lds_dwordx4 v[144:145], off
	s_add_i32 m0, s4, 0x2000
	s_add_u32 s4, s38, 0xb0080
	v_lshl_add_u64 v[144:145], v[166:167], 0, s[10:11]
	s_addc_u32 s5, s39, 0
	s_add_i32 s38, s78, s26
	global_load_lds_dwordx4 v[144:145], off
	v_lshl_add_u64 v[144:145], s[4:5], 0, v[148:149]
	s_mov_b32 m0, s38
	s_nop 0
	global_load_lds_dwordx4 v[144:145], off
	v_lshl_add_u64 v[144:145], s[4:5], 0, v[152:153]
	s_add_i32 m0, s38, 0x2000
	s_nop 0
	global_load_lds_dwordx4 v[144:145], off
	v_lshl_add_u64 v[144:145], v[184:185], 0, s[10:11]
	s_mov_b32 m0, s48
	s_nop 0
	global_load_lds_dwordx4 v[144:145], off
	v_lshl_add_u64 v[144:145], v[186:187], 0, s[10:11]
	s_mov_b32 m0, s49
	s_nop 0
	global_load_lds_dwordx4 v[144:145], off
	s_waitcnt vmcnt(8)
	s_waitcnt lgkmcnt(0)
	s_barrier
	s_setprio 1
	s_waitcnt lgkmcnt(0)
	v_mfma_f32_16x16x32_bf16 v[92:95], v[128:131], v[180:183], v[92:95]
	v_mfma_f32_16x16x32_bf16 v[88:91], v[136:139], v[180:183], v[88:91]
	v_mfma_f32_16x16x32_bf16 v[84:87], v[128:131], v[192:195], v[84:87]
	v_mfma_f32_16x16x32_bf16 v[80:83], v[136:139], v[192:195], v[80:83]
	v_mfma_f32_16x16x32_bf16 v[76:79], v[128:131], v[200:203], v[76:79]
	v_mfma_f32_16x16x32_bf16 v[72:75], v[136:139], v[200:203], v[72:75]
	v_mfma_f32_16x16x32_bf16 v[68:71], v[128:131], v[208:211], v[68:71]
	v_mfma_f32_16x16x32_bf16 v[64:67], v[136:139], v[208:211], v[64:67]
	v_mfma_f32_16x16x32_bf16 v[92:95], v[132:135], v[188:191], v[92:95]
	v_mfma_f32_16x16x32_bf16 v[88:91], v[140:143], v[188:191], v[88:91]
	v_mfma_f32_16x16x32_bf16 v[84:87], v[132:135], v[196:199], v[84:87]
	v_mfma_f32_16x16x32_bf16 v[80:83], v[140:143], v[196:199], v[80:83]
	v_mfma_f32_16x16x32_bf16 v[76:79], v[132:135], v[204:207], v[76:79]
	v_mfma_f32_16x16x32_bf16 v[72:75], v[140:143], v[204:207], v[72:75]
	v_mfma_f32_16x16x32_bf16 v[68:71], v[132:135], v[212:215], v[68:71]
	v_mfma_f32_16x16x32_bf16 v[64:67], v[140:143], v[212:215], v[64:67]
	s_setprio 0
	s_setprio 1
	v_mfma_f32_16x16x32_bf16 v[28:31], v[158:161], v[180:183], v[28:31]
	v_mfma_f32_16x16x32_bf16 v[24:27], v[172:175], v[180:183], v[24:27]
	v_mfma_f32_16x16x32_bf16 v[20:23], v[158:161], v[192:195], v[20:23]
	v_mfma_f32_16x16x32_bf16 v[16:19], v[172:175], v[192:195], v[16:19]
	v_mfma_f32_16x16x32_bf16 v[12:15], v[158:161], v[200:203], v[12:15]
	v_mfma_f32_16x16x32_bf16 v[8:11], v[172:175], v[200:203], v[8:11]
	v_mfma_f32_16x16x32_bf16 v[4:7], v[158:161], v[208:211], v[4:7]
	v_mfma_f32_16x16x32_bf16 v[0:3], v[172:175], v[208:211], v[0:3]
	v_mfma_f32_16x16x32_bf16 v[28:31], v[162:165], v[188:191], v[28:31]
	v_mfma_f32_16x16x32_bf16 v[24:27], v[176:179], v[188:191], v[24:27]
	v_mfma_f32_16x16x32_bf16 v[20:23], v[162:165], v[196:199], v[20:23]
	v_mfma_f32_16x16x32_bf16 v[16:19], v[176:179], v[196:199], v[16:19]
	v_mfma_f32_16x16x32_bf16 v[12:15], v[162:165], v[204:207], v[12:15]
	v_mfma_f32_16x16x32_bf16 v[8:11], v[176:179], v[204:207], v[8:11]
	v_mfma_f32_16x16x32_bf16 v[4:7], v[162:165], v[212:215], v[4:7]
	v_mfma_f32_16x16x32_bf16 v[0:3], v[176:179], v[212:215], v[0:3]
	s_setprio 0
	s_add_u32 s73, s73, 0x100
	s_addc_u32 s74, s74, 0
	s_cmp_ge_u32 s75, s59
	s_mov_b64 s[4:5], s[14:15]
	s_mov_b32 s38, s75
	s_barrier
	s_cbranch_scc0 .LBB0_850
	s_branch .Lpost_850
.LBB0_850:
	ds_read_b128 v[128:131], v169
	ds_read_b128 v[132:135], v169 offset:1024
	ds_read_b128 v[136:139], v169 offset:2048
	ds_read_b128 v[140:143], v169 offset:3072
	ds_read_b128 v[158:161], v170
	ds_read_b128 v[162:165], v170 offset:1024
	ds_read_b128 v[172:175], v170 offset:2048
	ds_read_b128 v[176:179], v170 offset:3072
	s_add_i32 s75, s38, 2
	s_add_u32 s14, s4, 0x100
	s_addc_u32 s15, s5, 0
	s_cmp_eq_u32 s72, s38
	s_cselect_b32 s38, s36, s73
	s_cselect_b32 s41, s35, s15
	s_cselect_b32 s40, s34, s14
	s_cselect_b32 s39, s37, s74
	v_lshl_add_u64 v[144:145], s[4:5], 0, v[154:155]
	s_add_i32 m0, s42, 0xc000
	ds_read_b128 v[180:183], v171
	ds_read_b128 v[188:191], v171 offset:1024
	ds_read_b128 v[192:195], v171 offset:2048
	ds_read_b128 v[196:199], v171 offset:3072
	ds_read_b128 v[200:203], v171 offset:4096
	ds_read_b128 v[204:207], v171 offset:5120
	ds_read_b128 v[208:211], v171 offset:6144
	ds_read_b128 v[212:215], v171 offset:7168
	global_load_lds_dwordx4 v[144:145], off
	v_lshl_add_u64 v[144:145], s[4:5], 0, v[156:157]
	s_add_i32 m0, s42, 0xe000
	s_nop 0
	global_load_lds_dwordx4 v[144:145], off
	s_waitcnt vmcnt(8)
	s_waitcnt lgkmcnt(0)
	s_barrier
; #define G_STAGE(bufoff, gbase, voff) do { _Pragma("unroll") for (int _i = 0; _i < 2; ++_i) \
;         __builtin_amdgcn_global_load_lds((const unsigned*)((const char*)(gbase) + voff[_i]), (LAS unsigned*)(lds + (bufoff) + ldsw + _i * 8192), 16, 0, 0); } while (0)
; #define G_LDA(dst, b, h) do { _Pragma("unroll") for (int m = 0; m < 4; ++m) _Pragma("unroll") for (int k = 0; k < 2; ++k) dst[m][k] = *(const LAS bf16x8*)(lds + G_SA(b, h) + aoff + m * 2048 + k * 1024); } while (0)
; #define G_LDB(dst, b, h) do { _Pragma("unroll") for (int n = 0; n < 2; ++n) _Pragma("unroll") for (int k = 0; k < 2; ++k) dst[n][k] = *(const LAS bf16x8*)(lds + G_SB(b, h) + boff + n * 2048 + k * 1024); } while (0)
; #define G_MMA(ai, bj, At_, Bt_) do { __builtin_amdgcn_s_setprio(1); _Pragma("unroll") for (int m = 0; m < 4; ++m) _Pragma("unroll") for (int n = 0; n < 2; ++n) _Pragma("unroll") for (int k = 0; k < 2; ++k) \
;         acc[ai][bj][m][n] = __builtin_amdgcn_mfma_f32_16x16x32_bf16(Bt_[n][k], At_[m][k], acc[ai][bj][m][n], 0, 0, 0); __builtin_amdgcn_s_setprio(0); } while (0)
; #define WAIT_V(n) asm volatile("s_waitcnt vmcnt(" #n ")" ::: "memory")
; #define WAIT_L(n) asm volatile("s_waitcnt lgkmcnt(" #n ")" ::: "memory")
; #define BAR __builtin_amdgcn_s_barrier()
; #define SCHED __builtin_amdgcn_sched_barrier(0)
; template <class Get, class Epi>
; DI void gemm_loop(int ntiles, int ld, char* shm, const Get& get, const Epi& epi) {
;     ...
;             WAIT_V(8); WAIT_L(0); BAR; G_MMA(0, 0, At, B0); G_MMA(0, 1, At, B1); BAR; SCHED;
;             G_LDA(At, 0, 1); G_STAGE(G_SB(0, 0), b2, voffB); G_STAGE(G_SB(0, 1), b2 + hstep, voffB); G_STAGE(G_SA(0, 0), a2, voffA);
;             WAIT_V(8); WAIT_L(0); BAR; G_MMA(1, 0, At, B0); G_MMA(1, 1, At, B1); BAR; SCHED;
;             G_LDB(B0, 1, 0); G_LDB(B1, 1, 1); SCHED; G_LDA(At, 1, 0); G_STAGE(G_SA(0, 1), a2 + hstep, voffA);
	s_setprio 1
	s_waitcnt lgkmcnt(0)
	v_mfma_f32_16x16x32_bf16 v[124:127], v[128:131], v[180:183], v[124:127]
	v_mfma_f32_16x16x32_bf16 v[120:123], v[136:139], v[180:183], v[120:123]
	v_mfma_f32_16x16x32_bf16 v[116:119], v[128:131], v[192:195], v[116:119]
	v_mfma_f32_16x16x32_bf16 v[112:115], v[136:139], v[192:195], v[112:115]
	v_mfma_f32_16x16x32_bf16 v[108:111], v[128:131], v[200:203], v[108:111]
	v_mfma_f32_16x16x32_bf16 v[104:107], v[136:139], v[200:203], v[104:107]
	v_mfma_f32_16x16x32_bf16 v[100:103], v[128:131], v[208:211], v[100:103]
	v_mfma_f32_16x16x32_bf16 v[96:99], v[136:139], v[208:211], v[96:99]
	v_mfma_f32_16x16x32_bf16 v[124:127], v[132:135], v[188:191], v[124:127]
	v_mfma_f32_16x16x32_bf16 v[120:123], v[140:143], v[188:191], v[120:123]
	v_mfma_f32_16x16x32_bf16 v[116:119], v[132:135], v[196:199], v[116:119]
	v_mfma_f32_16x16x32_bf16 v[112:115], v[140:143], v[196:199], v[112:115]
	v_mfma_f32_16x16x32_bf16 v[108:111], v[132:135], v[204:207], v[108:111]
	v_mfma_f32_16x16x32_bf16 v[104:107], v[140:143], v[204:207], v[104:107]
	v_mfma_f32_16x16x32_bf16 v[100:103], v[132:135], v[212:215], v[100:103]
	v_mfma_f32_16x16x32_bf16 v[96:99], v[140:143], v[212:215], v[96:99]
	s_setprio 0
	s_setprio 1
	v_mfma_f32_16x16x32_bf16 v[60:63], v[158:161], v[180:183], v[60:63]
	v_mfma_f32_16x16x32_bf16 v[56:59], v[172:175], v[180:183], v[56:59]
	v_mfma_f32_16x16x32_bf16 v[52:55], v[158:161], v[192:195], v[52:55]
	v_mfma_f32_16x16x32_bf16 v[48:51], v[172:175], v[192:195], v[48:51]
	v_mfma_f32_16x16x32_bf16 v[44:47], v[158:161], v[200:203], v[44:47]
	v_mfma_f32_16x16x32_bf16 v[40:43], v[172:175], v[200:203], v[40:43]
	v_mfma_f32_16x16x32_bf16 v[36:39], v[158:161], v[208:211], v[36:39]
	v_mfma_f32_16x16x32_bf16 v[32:35], v[172:175], v[208:211], v[32:35]
	v_mfma_f32_16x16x32_bf16 v[60:63], v[162:165], v[188:191], v[60:63]
	v_mfma_f32_16x16x32_bf16 v[56:59], v[176:179], v[188:191], v[56:59]
	v_mfma_f32_16x16x32_bf16 v[52:55], v[162:165], v[196:199], v[52:55]
	v_mfma_f32_16x16x32_bf16 v[48:51], v[176:179], v[196:199], v[48:51]
	v_mfma_f32_16x16x32_bf16 v[44:47], v[162:165], v[204:207], v[44:47]
	v_mfma_f32_16x16x32_bf16 v[40:43], v[176:179], v[204:207], v[40:43]
	v_mfma_f32_16x16x32_bf16 v[36:39], v[162:165], v[212:215], v[36:39]
	v_mfma_f32_16x16x32_bf16 v[32:35], v[176:179], v[212:215], v[32:35]
	s_setprio 0
	s_add_i32 s4, s50, s26
	v_lshl_add_u64 v[144:145], s[38:39], 0, v[148:149]
	s_mov_b32 m0, s4
	s_barrier
	ds_read_b128 v[180:183], v171 offset:16384
	ds_read_b128 v[188:191], v171 offset:17408
	ds_read_b128 v[192:195], v171 offset:18432
	ds_read_b128 v[196:199], v171 offset:19456
	ds_read_b128 v[200:203], v171 offset:20480
	ds_read_b128 v[204:207], v171 offset:21504
	ds_read_b128 v[208:211], v171 offset:22528
	ds_read_b128 v[212:215], v171 offset:23552
	global_load_lds_dwordx4 v[144:145], off
	s_add_i32 m0, s4, 0x2000
	s_add_u32 s4, s38, 0xb0000
	v_lshl_add_u64 v[166:167], s[38:39], 0, v[152:153]
	s_addc_u32 s5, s39, 0
	s_add_i32 s76, s51, s26
	global_load_lds_dwordx4 v[166:167], off
	v_lshl_add_u64 v[184:185], s[4:5], 0, v[148:149]
	s_mov_b32 m0, s76
	v_lshl_add_u64 v[186:187], s[40:41], 0, v[150:151]
	global_load_lds_dwordx4 v[184:185], off
	v_lshl_add_u64 v[184:185], s[4:5], 0, v[152:153]
	s_add_i32 m0, s76, 0x2000
	s_nop 0
	global_load_lds_dwordx4 v[184:185], off
	v_lshl_add_u64 v[184:185], s[40:41], 0, v[146:147]
	s_mov_b32 m0, s42
	s_nop 0
	global_load_lds_dwordx4 v[184:185], off
	s_mov_b32 m0, s43
	s_nop 0
	global_load_lds_dwordx4 v[186:187], off
	s_waitcnt vmcnt(8)
	s_waitcnt lgkmcnt(0)
	s_barrier
	s_setprio 1
	s_waitcnt lgkmcnt(0)
	v_mfma_f32_16x16x32_bf16 v[92:95], v[128:131], v[180:183], v[92:95]
	v_mfma_f32_16x16x32_bf16 v[88:91], v[136:139], v[180:183], v[88:91]
	v_mfma_f32_16x16x32_bf16 v[84:87], v[128:131], v[192:195], v[84:87]
	v_mfma_f32_16x16x32_bf16 v[80:83], v[136:139], v[192:195], v[80:83]
	v_mfma_f32_16x16x32_bf16 v[76:79], v[128:131], v[200:203], v[76:79]
	v_mfma_f32_16x16x32_bf16 v[72:75], v[136:139], v[200:203], v[72:75]
	v_mfma_f32_16x16x32_bf16 v[68:71], v[128:131], v[208:211], v[68:71]
	v_mfma_f32_16x16x32_bf16 v[64:67], v[136:139], v[208:211], v[64:67]
	v_mfma_f32_16x16x32_bf16 v[92:95], v[132:135], v[188:191], v[92:95]
	v_mfma_f32_16x16x32_bf16 v[88:91], v[140:143], v[188:191], v[88:91]
	v_mfma_f32_16x16x32_bf16 v[84:87], v[132:135], v[196:199], v[84:87]
	v_mfma_f32_16x16x32_bf16 v[80:83], v[140:143], v[196:199], v[80:83]
	v_mfma_f32_16x16x32_bf16 v[76:79], v[132:135], v[204:207], v[76:79]
	v_mfma_f32_16x16x32_bf16 v[72:75], v[140:143], v[204:207], v[72:75]
	v_mfma_f32_16x16x32_bf16 v[68:71], v[132:135], v[212:215], v[68:71]
	v_mfma_f32_16x16x32_bf16 v[64:67], v[140:143], v[212:215], v[64:67]
	s_setprio 0
	s_setprio 1
	v_mfma_f32_16x16x32_bf16 v[28:31], v[158:161], v[180:183], v[28:31]
	v_mfma_f32_16x16x32_bf16 v[24:27], v[172:175], v[180:183], v[24:27]
	v_mfma_f32_16x16x32_bf16 v[20:23], v[158:161], v[192:195], v[20:23]
	v_mfma_f32_16x16x32_bf16 v[16:19], v[172:175], v[192:195], v[16:19]
	v_mfma_f32_16x16x32_bf16 v[12:15], v[158:161], v[200:203], v[12:15]
	v_mfma_f32_16x16x32_bf16 v[8:11], v[172:175], v[200:203], v[8:11]
	v_mfma_f32_16x16x32_bf16 v[4:7], v[158:161], v[208:211], v[4:7]
	v_mfma_f32_16x16x32_bf16 v[0:3], v[172:175], v[208:211], v[0:3]
	v_mfma_f32_16x16x32_bf16 v[28:31], v[162:165], v[188:191], v[28:31]
	v_mfma_f32_16x16x32_bf16 v[24:27], v[176:179], v[188:191], v[24:27]
	v_mfma_f32_16x16x32_bf16 v[20:23], v[162:165], v[196:199], v[20:23]
	v_mfma_f32_16x16x32_bf16 v[16:19], v[176:179], v[196:199], v[16:19]
	v_mfma_f32_16x16x32_bf16 v[12:15], v[162:165], v[204:207], v[12:15]
	v_mfma_f32_16x16x32_bf16 v[8:11], v[176:179], v[204:207], v[8:11]
	v_mfma_f32_16x16x32_bf16 v[4:7], v[162:165], v[212:215], v[4:7]
	v_mfma_f32_16x16x32_bf16 v[0:3], v[176:179], v[212:215], v[0:3]
	s_setprio 0
	s_add_i32 s76, 0, 0x18000
	s_add_i32 s78, 0, 0x1c000
	v_add_u32_e32 v140, s76, v168
	s_barrier
; #define G_STAGE(bufoff, gbase, voff) do { _Pragma("unroll") for (int _i = 0; _i < 2; ++_i) \
;         __builtin_amdgcn_global_load_lds((const unsigned*)((const char*)(gbase) + voff[_i]), (LAS unsigned*)(lds + (bufoff) + ldsw + _i * 8192), 16, 0, 0); } while (0)
; #define G_LDA(dst, b, h) do { _Pragma("unroll") for (int m = 0; m < 4; ++m) _Pragma("unroll") for (int k = 0; k < 2; ++k) dst[m][k] = *(const LAS bf16x8*)(lds + G_SA(b, h) + aoff + m * 2048 + k * 1024); } while (0)
; #define G_LDB(dst, b, h) do { _Pragma("unroll") for (int n = 0; n < 2; ++n) _Pragma("unroll") for (int k = 0; k < 2; ++k) dst[n][k] = *(const LAS bf16x8*)(lds + G_SB(b, h) + boff + n * 2048 + k * 1024); } while (0)
; #define G_MMA(ai, bj, At_, Bt_) do { __builtin_amdgcn_s_setprio(1); _Pragma("unroll") for (int m = 0; m < 4; ++m) _Pragma("unroll") for (int n = 0; n < 2; ++n) _Pragma("unroll") for (int k = 0; k < 2; ++k) \
;         acc[ai][bj][m][n] = __builtin_amdgcn_mfma_f32_16x16x32_bf16(Bt_[n][k], At_[m][k], acc[ai][bj][m][n], 0, 0, 0); __builtin_amdgcn_s_setprio(0); } while (0)
; #define WAIT_V(n) asm volatile("s_waitcnt vmcnt(" #n ")" ::: "memory")
; #define WAIT_L(n) asm volatile("s_waitcnt lgkmcnt(" #n ")" ::: "memory")
; #define BAR __builtin_amdgcn_s_barrier()
; #define SCHED __builtin_amdgcn_sched_barrier(0)
; template <class Get, class Epi>
; DI void gemm_loop(int ntiles, int ld, char* shm, const Get& get, const Epi& epi) {
;     ...
;             G_LDB(B0, 1, 0); G_LDB(B1, 1, 1); SCHED; G_LDA(At, 1, 0); G_STAGE(G_SA(0, 1), a2 + hstep, voffA);
;             WAIT_V(8); WAIT_L(0); BAR; G_MMA(0, 0, At, B0); G_MMA(0, 1, At, B1); BAR; SCHED;
;             G_LDA(At, 1, 1); G_STAGE(G_SB(1, 0), b3, voffB); G_STAGE(G_SB(1, 1), b3 + hstep, voffB); G_STAGE(G_SA(1, 0), a3, voffA);
;             WAIT_V(8); WAIT_L(0); BAR; G_MMA(1, 0, At, B0); G_MMA(1, 1, At, B1); BAR; SCHED;
;         }
	v_add_u32_e32 v176, s78, v168
	ds_read_b128 v[128:131], v140
	ds_read_b128 v[132:135], v140 offset:1024
	ds_read_b128 v[136:139], v140 offset:2048
	ds_read_b128 v[140:143], v140 offset:3072
	ds_read_b128 v[158:161], v176
	ds_read_b128 v[162:165], v176 offset:1024
	ds_read_b128 v[172:175], v176 offset:2048
	ds_read_b128 v[176:179], v176 offset:3072
	s_add_u32 s4, s40, 0xb0000
	s_addc_u32 s5, s41, 0
	s_mov_b32 m0, s44
	v_lshl_add_u64 v[216:217], s[4:5], 0, v[146:147]
	ds_read_b128 v[180:183], v171 offset:32768
	ds_read_b128 v[188:191], v171 offset:33792
	ds_read_b128 v[192:195], v171 offset:34816
	ds_read_b128 v[196:199], v171 offset:35840
	ds_read_b128 v[200:203], v171 offset:36864
	ds_read_b128 v[204:207], v171 offset:37888
	ds_read_b128 v[208:211], v171 offset:38912
	ds_read_b128 v[212:215], v171 offset:39936
	global_load_lds_dwordx4 v[216:217], off
	v_lshl_add_u64 v[216:217], s[4:5], 0, v[150:151]
	s_mov_b32 m0, s45
	s_nop 0
	global_load_lds_dwordx4 v[216:217], off
	s_waitcnt vmcnt(8)
	s_waitcnt lgkmcnt(0)
	s_barrier
	s_setprio 1
	s_waitcnt lgkmcnt(0)
	v_mfma_f32_16x16x32_bf16 v[124:127], v[128:131], v[180:183], v[124:127]
	v_mfma_f32_16x16x32_bf16 v[120:123], v[136:139], v[180:183], v[120:123]
	v_mfma_f32_16x16x32_bf16 v[116:119], v[128:131], v[192:195], v[116:119]
	v_mfma_f32_16x16x32_bf16 v[112:115], v[136:139], v[192:195], v[112:115]
	v_mfma_f32_16x16x32_bf16 v[108:111], v[128:131], v[200:203], v[108:111]
	v_mfma_f32_16x16x32_bf16 v[104:107], v[136:139], v[200:203], v[104:107]
	v_mfma_f32_16x16x32_bf16 v[100:103], v[128:131], v[208:211], v[100:103]
	v_mfma_f32_16x16x32_bf16 v[96:99], v[136:139], v[208:211], v[96:99]
	v_mfma_f32_16x16x32_bf16 v[124:127], v[132:135], v[188:191], v[124:127]
	v_mfma_f32_16x16x32_bf16 v[120:123], v[140:143], v[188:191], v[120:123]
	v_mfma_f32_16x16x32_bf16 v[116:119], v[132:135], v[196:199], v[116:119]
	v_mfma_f32_16x16x32_bf16 v[112:115], v[140:143], v[196:199], v[112:115]
	v_mfma_f32_16x16x32_bf16 v[108:111], v[132:135], v[204:207], v[108:111]
	v_mfma_f32_16x16x32_bf16 v[104:107], v[140:143], v[204:207], v[104:107]
	v_mfma_f32_16x16x32_bf16 v[100:103], v[132:135], v[212:215], v[100:103]
	v_mfma_f32_16x16x32_bf16 v[96:99], v[140:143], v[212:215], v[96:99]
	s_setprio 0
	s_setprio 1
	v_mfma_f32_16x16x32_bf16 v[60:63], v[158:161], v[180:183], v[60:63]
	v_mfma_f32_16x16x32_bf16 v[56:59], v[172:175], v[180:183], v[56:59]
	v_mfma_f32_16x16x32_bf16 v[52:55], v[158:161], v[192:195], v[52:55]
	v_mfma_f32_16x16x32_bf16 v[48:51], v[172:175], v[192:195], v[48:51]
	v_mfma_f32_16x16x32_bf16 v[44:47], v[158:161], v[200:203], v[44:47]
	v_mfma_f32_16x16x32_bf16 v[40:43], v[172:175], v[200:203], v[40:43]
	v_mfma_f32_16x16x32_bf16 v[36:39], v[158:161], v[208:211], v[36:39]
	v_mfma_f32_16x16x32_bf16 v[32:35], v[172:175], v[208:211], v[32:35]
	v_mfma_f32_16x16x32_bf16 v[60:63], v[162:165], v[188:191], v[60:63]
	v_mfma_f32_16x16x32_bf16 v[56:59], v[176:179], v[188:191], v[56:59]
	v_mfma_f32_16x16x32_bf16 v[52:55], v[162:165], v[196:199], v[52:55]
	v_mfma_f32_16x16x32_bf16 v[48:51], v[176:179], v[196:199], v[48:51]
	v_mfma_f32_16x16x32_bf16 v[44:47], v[162:165], v[204:207], v[44:47]
	v_mfma_f32_16x16x32_bf16 v[40:43], v[176:179], v[204:207], v[40:43]
	v_mfma_f32_16x16x32_bf16 v[36:39], v[162:165], v[212:215], v[36:39]
	v_mfma_f32_16x16x32_bf16 v[32:35], v[176:179], v[212:215], v[32:35]
	s_setprio 0
	s_add_i32 s4, s76, s26
	v_lshl_add_u64 v[144:145], v[144:145], 0, s[10:11]
	s_mov_b32 m0, s4
	s_barrier
	ds_read_b128 v[180:183], v171 offset:49152
	ds_read_b128 v[188:191], v171 offset:50176
	ds_read_b128 v[192:195], v171 offset:51200
	ds_read_b128 v[196:199], v171 offset:52224
	ds_read_b128 v[200:203], v171 offset:53248
	ds_read_b128 v[204:207], v171 offset:54272
	ds_read_b128 v[208:211], v171 offset:55296
	ds_read_b128 v[212:215], v171 offset:56320
	global_load_lds_dwordx4 v[144:145], off
	s_add_i32 m0, s4, 0x2000
	s_add_u32 s4, s38, 0xb0080
	v_lshl_add_u64 v[144:145], v[166:167], 0, s[10:11]
	s_addc_u32 s5, s39, 0
	s_add_i32 s38, s78, s26
	global_load_lds_dwordx4 v[144:145], off
	v_lshl_add_u64 v[144:145], s[4:5], 0, v[148:149]
	s_mov_b32 m0, s38
	s_nop 0
	global_load_lds_dwordx4 v[144:145], off
	v_lshl_add_u64 v[144:145], s[4:5], 0, v[152:153]
	s_add_i32 m0, s38, 0x2000
	s_nop 0
	global_load_lds_dwordx4 v[144:145], off
	v_lshl_add_u64 v[144:145], v[184:185], 0, s[10:11]
	s_mov_b32 m0, s48
	s_nop 0
	global_load_lds_dwordx4 v[144:145], off
	v_lshl_add_u64 v[144:145], v[186:187], 0, s[10:11]
	s_mov_b32 m0, s49
	s_nop 0
	global_load_lds_dwordx4 v[144:145], off
	s_waitcnt vmcnt(8)
	s_waitcnt lgkmcnt(0)
	s_barrier
	s_setprio 1
	s_waitcnt lgkmcnt(0)
	v_mfma_f32_16x16x32_bf16 v[92:95], v[128:131], v[180:183], v[92:95]
	v_mfma_f32_16x16x32_bf16 v[88:91], v[136:139], v[180:183], v[88:91]
	v_mfma_f32_16x16x32_bf16 v[84:87], v[128:131], v[192:195], v[84:87]
	v_mfma_f32_16x16x32_bf16 v[80:83], v[136:139], v[192:195], v[80:83]
	v_mfma_f32_16x16x32_bf16 v[76:79], v[128:131], v[200:203], v[76:79]
	v_mfma_f32_16x16x32_bf16 v[72:75], v[136:139], v[200:203], v[72:75]
	v_mfma_f32_16x16x32_bf16 v[68:71], v[128:131], v[208:211], v[68:71]
	v_mfma_f32_16x16x32_bf16 v[64:67], v[136:139], v[208:211], v[64:67]
	v_mfma_f32_16x16x32_bf16 v[92:95], v[132:135], v[188:191], v[92:95]
	v_mfma_f32_16x16x32_bf16 v[88:91], v[140:143], v[188:191], v[88:91]
	v_mfma_f32_16x16x32_bf16 v[84:87], v[132:135], v[196:199], v[84:87]
	v_mfma_f32_16x16x32_bf16 v[80:83], v[140:143], v[196:199], v[80:83]
	v_mfma_f32_16x16x32_bf16 v[76:79], v[132:135], v[204:207], v[76:79]
	v_mfma_f32_16x16x32_bf16 v[72:75], v[140:143], v[204:207], v[72:75]
	v_mfma_f32_16x16x32_bf16 v[68:71], v[132:135], v[212:215], v[68:71]
	v_mfma_f32_16x16x32_bf16 v[64:67], v[140:143], v[212:215], v[64:67]
	s_setprio 0
	s_setprio 1
	v_mfma_f32_16x16x32_bf16 v[28:31], v[158:161], v[180:183], v[28:31]
	v_mfma_f32_16x16x32_bf16 v[24:27], v[172:175], v[180:183], v[24:27]
	v_mfma_f32_16x16x32_bf16 v[20:23], v[158:161], v[192:195], v[20:23]
	v_mfma_f32_16x16x32_bf16 v[16:19], v[172:175], v[192:195], v[16:19]
	v_mfma_f32_16x16x32_bf16 v[12:15], v[158:161], v[200:203], v[12:15]
	v_mfma_f32_16x16x32_bf16 v[8:11], v[172:175], v[200:203], v[8:11]
	v_mfma_f32_16x16x32_bf16 v[4:7], v[158:161], v[208:211], v[4:7]
	v_mfma_f32_16x16x32_bf16 v[0:3], v[172:175], v[208:211], v[0:3]
	v_mfma_f32_16x16x32_bf16 v[28:31], v[162:165], v[188:191], v[28:31]
	v_mfma_f32_16x16x32_bf16 v[24:27], v[176:179], v[188:191], v[24:27]
	v_mfma_f32_16x16x32_bf16 v[20:23], v[162:165], v[196:199], v[20:23]
	v_mfma_f32_16x16x32_bf16 v[16:19], v[176:179], v[196:199], v[16:19]
	v_mfma_f32_16x16x32_bf16 v[12:15], v[162:165], v[204:207], v[12:15]
	v_mfma_f32_16x16x32_bf16 v[8:11], v[176:179], v[204:207], v[8:11]
	v_mfma_f32_16x16x32_bf16 v[4:7], v[162:165], v[212:215], v[4:7]
	v_mfma_f32_16x16x32_bf16 v[0:3], v[176:179], v[212:215], v[0:3]
	s_setprio 0
	s_add_u32 s73, s73, 0x100
	s_addc_u32 s74, s74, 0
	s_cmp_ge_u32 s75, s59
	s_mov_b64 s[4:5], s[14:15]
	s_mov_b32 s38, s75
	s_barrier
	s_cbranch_scc0 .LBB0_850

; #define G_STAGE(bufoff, gbase, voff) do { _Pragma("unroll") for (int _i = 0; _i < 2; ++_i) \
;         __builtin_amdgcn_global_load_lds((const unsigned*)((const char*)(gbase) + voff[_i]), (LAS unsigned*)(lds + (bufoff) + ldsw + _i * 8192), 16, 0, 0); } while (0)
; #define G_LDA(dst, b, h) do { _Pragma("unroll") for (int m = 0; m < 4; ++m) _Pragma("unroll") for (int k = 0; k < 2; ++k) dst[m][k] = *(const LAS bf16x8*)(lds + G_SA(b, h) + aoff + m * 2048 + k * 1024); } while (0)
; #define G_LDB(dst, b, h) do { _Pragma("unroll") for (int n = 0; n < 2; ++n) _Pragma("unroll") for (int k = 0; k < 2; ++k) dst[n][k] = *(const LAS bf16x8*)(lds + G_SB(b, h) + boff + n * 2048 + k * 1024); } while (0)
; #define G_MMA(ai, bj, At_, Bt_) do { __builtin_amdgcn_s_setprio(1); _Pragma("unroll") for (int m = 0; m < 4; ++m) _Pragma("unroll") for (int n = 0; n < 2; ++n) _Pragma("unroll") for (int k = 0; k < 2; ++k) \
;         acc[ai][bj][m][n] = __builtin_amdgcn_mfma_f32_16x16x32_bf16(Bt_[n][k], At_[m][k], acc[ai][bj][m][n], 0, 0, 0); __builtin_amdgcn_s_setprio(0); } while (0)
; #define WAIT_V(n) asm volatile("s_waitcnt vmcnt(" #n ")" ::: "memory")
; #define WAIT_L(n) asm volatile("s_waitcnt lgkmcnt(" #n ")" ::: "memory")
; #define BAR __builtin_amdgcn_s_barrier()
; #define SCHED __builtin_amdgcn_sched_barrier(0)
; template <class Get, class Epi>
; DI void gemm_loop(int ntiles, int ld, char* shm, const Get& get, const Epi& epi) {
;     ...
;             const bool last = (t == nt - 2);
;             const char* a1 = cA + (size_t)(t + 1) * kstep;
;             const char* a2 = last ? nA : cA + (size_t)(t + 2) * kstep; const char* b2 = last ? nB : cB + (size_t)(t + 2) * kstep;
;             const char* a3 = a2 + kstep; const char* b3 = b2 + kstep;
;             G_LDB(B0, 0, 0); G_LDB(B1, 0, 1); SCHED; G_LDA(At, 0, 0); G_STAGE(G_SA(1, 1), a1 + hstep, voffA);
;             WAIT_V(8); WAIT_L(0); BAR; G_MMA(0, 0, At, B0); G_MMA(0, 1, At, B1); BAR; SCHED;
;             G_LDA(At, 0, 1); G_STAGE(G_SB(0, 0), b2, voffB); G_STAGE(G_SB(0, 1), b2 + hstep, voffB); G_STAGE(G_SA(0, 0), a2, voffA);
.Lpeel_1099:
	ds_read_b128 v[140:143], v145
	ds_read_b128 v[148:151], v145 offset:1024
	ds_read_b128 v[152:155], v145 offset:2048
	ds_read_b128 v[156:159], v145 offset:3072
	ds_read_b128 v[160:163], v146
	ds_read_b128 v[164:167], v146 offset:1024
	ds_read_b128 v[168:171], v146 offset:2048
	ds_read_b128 v[172:175], v146 offset:3072
	s_add_u32 s14, s52, 0xfffc0080
	s_addc_u32 s15, s53, -1
	s_cmp_eq_u32 s76, 12
	s_cselect_b32 s47, s39, s15
	s_cselect_b32 s46, s72, s14
	s_cselect_b32 s15, s37, s75
	s_cselect_b32 s14, s73, s74
	v_lshl_add_u64 v[208:209], s[52:53], 0, v[136:137]
	s_add_i32 m0, s45, 0xc000
	ds_read_b128 v[176:179], v147
	ds_read_b128 v[180:183], v147 offset:1024
	ds_read_b128 v[184:187], v147 offset:2048
	ds_read_b128 v[188:191], v147 offset:3072
	ds_read_b128 v[192:195], v147 offset:4096
	ds_read_b128 v[196:199], v147 offset:5120
	ds_read_b128 v[200:203], v147 offset:6144
	ds_read_b128 v[204:207], v147 offset:7168
	global_load_lds_dwordx4 v[208:209], off
	v_lshl_add_u64 v[208:209], s[52:53], 0, v[138:139]
	s_add_i32 m0, s45, 0xe000
	s_nop 0
	global_load_lds_dwordx4 v[208:209], off
	s_waitcnt vmcnt(8)
	s_waitcnt lgkmcnt(0)
	s_barrier
	s_setprio 1
	s_waitcnt lgkmcnt(0)
	v_mfma_f32_16x16x32_bf16 v[124:127], v[140:143], v[176:179], 0
	v_mfma_f32_16x16x32_bf16 v[120:123], v[152:155], v[176:179], 0
	v_mfma_f32_16x16x32_bf16 v[116:119], v[140:143], v[184:187], 0
	v_mfma_f32_16x16x32_bf16 v[112:115], v[152:155], v[184:187], 0
	v_mfma_f32_16x16x32_bf16 v[108:111], v[140:143], v[192:195], 0
	v_mfma_f32_16x16x32_bf16 v[100:103], v[152:155], v[192:195], 0
	v_mfma_f32_16x16x32_bf16 v[92:95], v[140:143], v[200:203], 0
	v_mfma_f32_16x16x32_bf16 v[84:87], v[152:155], v[200:203], 0
	v_mfma_f32_16x16x32_bf16 v[124:127], v[148:151], v[180:183], v[124:127]
	v_mfma_f32_16x16x32_bf16 v[120:123], v[156:159], v[180:183], v[120:123]
	v_mfma_f32_16x16x32_bf16 v[116:119], v[148:151], v[188:191], v[116:119]
	v_mfma_f32_16x16x32_bf16 v[112:115], v[156:159], v[188:191], v[112:115]
	v_mfma_f32_16x16x32_bf16 v[108:111], v[148:151], v[196:199], v[108:111]
	v_mfma_f32_16x16x32_bf16 v[100:103], v[156:159], v[196:199], v[100:103]
	v_mfma_f32_16x16x32_bf16 v[92:95], v[148:151], v[204:207], v[92:95]
	v_mfma_f32_16x16x32_bf16 v[84:87], v[156:159], v[204:207], v[84:87]
	s_setprio 0
	s_setprio 1
	v_mfma_f32_16x16x32_bf16 v[104:107], v[160:163], v[176:179], 0
	v_mfma_f32_16x16x32_bf16 v[96:99], v[168:171], v[176:179], 0
	v_mfma_f32_16x16x32_bf16 v[88:91], v[160:163], v[184:187], 0
	v_mfma_f32_16x16x32_bf16 v[80:83], v[168:171], v[184:187], 0
	v_mfma_f32_16x16x32_bf16 v[76:79], v[160:163], v[192:195], 0
	v_mfma_f32_16x16x32_bf16 v[72:75], v[168:171], v[192:195], 0
	v_mfma_f32_16x16x32_bf16 v[68:71], v[160:163], v[200:203], 0
	v_mfma_f32_16x16x32_bf16 v[64:67], v[168:171], v[200:203], 0
	v_mfma_f32_16x16x32_bf16 v[104:107], v[164:167], v[180:183], v[104:107]
	v_mfma_f32_16x16x32_bf16 v[96:99], v[172:175], v[180:183], v[96:99]
	v_mfma_f32_16x16x32_bf16 v[88:91], v[164:167], v[188:191], v[88:91]
	v_mfma_f32_16x16x32_bf16 v[80:83], v[172:175], v[188:191], v[80:83]
	v_mfma_f32_16x16x32_bf16 v[76:79], v[164:167], v[196:199], v[76:79]
	v_mfma_f32_16x16x32_bf16 v[72:75], v[172:175], v[196:199], v[72:75]
	v_mfma_f32_16x16x32_bf16 v[68:71], v[164:167], v[204:207], v[68:71]
	v_mfma_f32_16x16x32_bf16 v[64:67], v[172:175], v[204:207], v[64:67]
	s_setprio 0
	s_add_i32 s77, s57, s7
	v_lshl_add_u64 v[208:209], s[14:15], 0, v[130:131]
	s_mov_b32 m0, s77
	s_barrier
	ds_read_b128 v[176:179], v147 offset:16384
	ds_read_b128 v[180:183], v147 offset:17408
	ds_read_b128 v[184:187], v147 offset:18432
	ds_read_b128 v[188:191], v147 offset:19456
	ds_read_b128 v[192:195], v147 offset:20480
	ds_read_b128 v[196:199], v147 offset:21504
	ds_read_b128 v[200:203], v147 offset:22528
	ds_read_b128 v[204:207], v147 offset:23552
	global_load_lds_dwordx4 v[208:209], off
	s_add_i32 m0, s77, 0x2000
	s_add_u32 s78, s14, 0x40000
	v_lshl_add_u64 v[210:211], s[14:15], 0, v[134:135]
	s_addc_u32 s79, s15, 0
	s_add_i32 s77, s58, s7
	global_load_lds_dwordx4 v[210:211], off
	v_lshl_add_u64 v[212:213], s[78:79], 0, v[130:131]
	s_mov_b32 m0, s77
	v_lshl_add_u64 v[214:215], s[46:47], 0, v[132:133]
	global_load_lds_dwordx4 v[212:213], off
	v_lshl_add_u64 v[212:213], s[78:79], 0, v[134:135]
	s_add_i32 m0, s77, 0x2000
	s_nop 0
	global_load_lds_dwordx4 v[212:213], off
	v_lshl_add_u64 v[212:213], s[46:47], 0, v[128:129]
	s_mov_b32 m0, s45
	s_nop 0
	global_load_lds_dwordx4 v[212:213], off
	s_mov_b32 m0, s49
	s_nop 0
	global_load_lds_dwordx4 v[214:215], off
	s_waitcnt vmcnt(8)
	s_waitcnt lgkmcnt(0)
	s_barrier
; #define G_STAGE(bufoff, gbase, voff) do { _Pragma("unroll") for (int _i = 0; _i < 2; ++_i) \
;         __builtin_amdgcn_global_load_lds((const unsigned*)((const char*)(gbase) + voff[_i]), (LAS unsigned*)(lds + (bufoff) + ldsw + _i * 8192), 16, 0, 0); } while (0)
; #define G_LDA(dst, b, h) do { _Pragma("unroll") for (int m = 0; m < 4; ++m) _Pragma("unroll") for (int k = 0; k < 2; ++k) dst[m][k] = *(const LAS bf16x8*)(lds + G_SA(b, h) + aoff + m * 2048 + k * 1024); } while (0)
; #define G_LDB(dst, b, h) do { _Pragma("unroll") for (int n = 0; n < 2; ++n) _Pragma("unroll") for (int k = 0; k < 2; ++k) dst[n][k] = *(const LAS bf16x8*)(lds + G_SB(b, h) + boff + n * 2048 + k * 1024); } while (0)
; #define G_MMA(ai, bj, At_, Bt_) do { __builtin_amdgcn_s_setprio(1); _Pragma("unroll") for (int m = 0; m < 4; ++m) _Pragma("unroll") for (int n = 0; n < 2; ++n) _Pragma("unroll") for (int k = 0; k < 2; ++k) \
;         acc[ai][bj][m][n] = __builtin_amdgcn_mfma_f32_16x16x32_bf16(Bt_[n][k], At_[m][k], acc[ai][bj][m][n], 0, 0, 0); __builtin_amdgcn_s_setprio(0); } while (0)
; #define WAIT_V(n) asm volatile("s_waitcnt vmcnt(" #n ")" ::: "memory")
; #define WAIT_L(n) asm volatile("s_waitcnt lgkmcnt(" #n ")" ::: "memory")
; #define BAR __builtin_amdgcn_s_barrier()
; #define SCHED __builtin_amdgcn_sched_barrier(0)
; template <class Get, class Epi>
; DI void gemm_loop(int ntiles, int ld, char* shm, const Get& get, const Epi& epi) {
;     ...
;             WAIT_V(8); WAIT_L(0); BAR; G_MMA(1, 0, At, B0); G_MMA(1, 1, At, B1); BAR; SCHED;
;             G_LDB(B0, 1, 0); G_LDB(B1, 1, 1); SCHED; G_LDA(At, 1, 0); G_STAGE(G_SA(0, 1), a2 + hstep, voffA);
;             WAIT_V(8); WAIT_L(0); BAR; G_MMA(0, 0, At, B0); G_MMA(0, 1, At, B1); BAR; SCHED;
	s_setprio 1
	s_waitcnt lgkmcnt(0)
	v_mfma_f32_16x16x32_bf16 v[60:63], v[140:143], v[176:179], 0
	v_mfma_f32_16x16x32_bf16 v[56:59], v[152:155], v[176:179], 0
	v_mfma_f32_16x16x32_bf16 v[52:55], v[140:143], v[184:187], 0
	v_mfma_f32_16x16x32_bf16 v[48:51], v[152:155], v[184:187], 0
	v_mfma_f32_16x16x32_bf16 v[44:47], v[140:143], v[192:195], 0
	v_mfma_f32_16x16x32_bf16 v[36:39], v[152:155], v[192:195], 0
	v_mfma_f32_16x16x32_bf16 v[28:31], v[140:143], v[200:203], 0
	v_mfma_f32_16x16x32_bf16 v[20:23], v[152:155], v[200:203], 0
	v_mfma_f32_16x16x32_bf16 v[60:63], v[148:151], v[180:183], v[60:63]
	v_mfma_f32_16x16x32_bf16 v[56:59], v[156:159], v[180:183], v[56:59]
	v_mfma_f32_16x16x32_bf16 v[52:55], v[148:151], v[188:191], v[52:55]
	v_mfma_f32_16x16x32_bf16 v[48:51], v[156:159], v[188:191], v[48:51]
	v_mfma_f32_16x16x32_bf16 v[44:47], v[148:151], v[196:199], v[44:47]
	v_mfma_f32_16x16x32_bf16 v[36:39], v[156:159], v[196:199], v[36:39]
	v_mfma_f32_16x16x32_bf16 v[28:31], v[148:151], v[204:207], v[28:31]
	v_mfma_f32_16x16x32_bf16 v[20:23], v[156:159], v[204:207], v[20:23]
	s_setprio 0
	s_setprio 1
	v_mfma_f32_16x16x32_bf16 v[40:43], v[160:163], v[176:179], 0
	v_mfma_f32_16x16x32_bf16 v[32:35], v[168:171], v[176:179], 0
	v_mfma_f32_16x16x32_bf16 v[24:27], v[160:163], v[184:187], 0
	v_mfma_f32_16x16x32_bf16 v[16:19], v[168:171], v[184:187], 0
	v_mfma_f32_16x16x32_bf16 v[12:15], v[160:163], v[192:195], 0
	v_mfma_f32_16x16x32_bf16 v[8:11], v[168:171], v[192:195], 0
	v_mfma_f32_16x16x32_bf16 v[4:7], v[160:163], v[200:203], 0
	v_mfma_f32_16x16x32_bf16 v[0:3], v[168:171], v[200:203], 0
	v_mfma_f32_16x16x32_bf16 v[40:43], v[164:167], v[180:183], v[40:43]
	v_mfma_f32_16x16x32_bf16 v[32:35], v[172:175], v[180:183], v[32:35]
	v_mfma_f32_16x16x32_bf16 v[24:27], v[164:167], v[188:191], v[24:27]
	v_mfma_f32_16x16x32_bf16 v[16:19], v[172:175], v[188:191], v[16:19]
	v_mfma_f32_16x16x32_bf16 v[12:15], v[164:167], v[196:199], v[12:15]
	v_mfma_f32_16x16x32_bf16 v[8:11], v[172:175], v[196:199], v[8:11]
	v_mfma_f32_16x16x32_bf16 v[4:7], v[164:167], v[204:207], v[4:7]
	v_mfma_f32_16x16x32_bf16 v[0:3], v[172:175], v[204:207], v[0:3]
	s_setprio 0
	s_add_i32 s77, 0, 0x18000
	s_add_i32 s78, 0, 0x1c000
	v_add_u32_e32 v156, s77, v144
	s_barrier
	v_add_u32_e32 v172, s78, v144
	ds_read_b128 v[140:143], v156
	ds_read_b128 v[148:151], v156 offset:1024
	ds_read_b128 v[152:155], v156 offset:2048
	ds_read_b128 v[156:159], v156 offset:3072
	ds_read_b128 v[160:163], v172
	ds_read_b128 v[164:167], v172 offset:1024
	ds_read_b128 v[168:171], v172 offset:2048
	ds_read_b128 v[172:175], v172 offset:3072
	s_add_u32 s46, s46, 0x40000
	s_addc_u32 s47, s47, 0
	s_mov_b32 m0, s50
	v_lshl_add_u64 v[216:217], s[46:47], 0, v[128:129]
	ds_read_b128 v[176:179], v147 offset:32768
	ds_read_b128 v[180:183], v147 offset:33792
	ds_read_b128 v[184:187], v147 offset:34816
	ds_read_b128 v[188:191], v147 offset:35840
	ds_read_b128 v[192:195], v147 offset:36864
	ds_read_b128 v[196:199], v147 offset:37888
	ds_read_b128 v[200:203], v147 offset:38912
	ds_read_b128 v[204:207], v147 offset:39936
	global_load_lds_dwordx4 v[216:217], off
	v_lshl_add_u64 v[216:217], s[46:47], 0, v[132:133]
	s_mov_b32 m0, s51
	s_nop 0
	global_load_lds_dwordx4 v[216:217], off
	s_waitcnt vmcnt(8)
	s_waitcnt lgkmcnt(0)
	s_barrier
	s_setprio 1
	s_waitcnt lgkmcnt(0)
	v_mfma_f32_16x16x32_bf16 v[124:127], v[140:143], v[176:179], v[124:127]
	v_mfma_f32_16x16x32_bf16 v[120:123], v[152:155], v[176:179], v[120:123]
	v_mfma_f32_16x16x32_bf16 v[116:119], v[140:143], v[184:187], v[116:119]
	v_mfma_f32_16x16x32_bf16 v[112:115], v[152:155], v[184:187], v[112:115]
	v_mfma_f32_16x16x32_bf16 v[108:111], v[140:143], v[192:195], v[108:111]
	v_mfma_f32_16x16x32_bf16 v[100:103], v[152:155], v[192:195], v[100:103]
	v_mfma_f32_16x16x32_bf16 v[92:95], v[140:143], v[200:203], v[92:95]
	v_mfma_f32_16x16x32_bf16 v[84:87], v[152:155], v[200:203], v[84:87]
	v_mfma_f32_16x16x32_bf16 v[124:127], v[148:151], v[180:183], v[124:127]
	v_mfma_f32_16x16x32_bf16 v[120:123], v[156:159], v[180:183], v[120:123]
	v_mfma_f32_16x16x32_bf16 v[116:119], v[148:151], v[188:191], v[116:119]
	v_mfma_f32_16x16x32_bf16 v[112:115], v[156:159], v[188:191], v[112:115]
	v_mfma_f32_16x16x32_bf16 v[108:111], v[148:151], v[196:199], v[108:111]
	v_mfma_f32_16x16x32_bf16 v[100:103], v[156:159], v[196:199], v[100:103]
	v_mfma_f32_16x16x32_bf16 v[92:95], v[148:151], v[204:207], v[92:95]
	v_mfma_f32_16x16x32_bf16 v[84:87], v[156:159], v[204:207], v[84:87]
	s_setprio 0
	s_setprio 1
	v_mfma_f32_16x16x32_bf16 v[104:107], v[160:163], v[176:179], v[104:107]
	v_mfma_f32_16x16x32_bf16 v[96:99], v[168:171], v[176:179], v[96:99]
	v_mfma_f32_16x16x32_bf16 v[88:91], v[160:163], v[184:187], v[88:91]
	v_mfma_f32_16x16x32_bf16 v[80:83], v[168:171], v[184:187], v[80:83]
	v_mfma_f32_16x16x32_bf16 v[76:79], v[160:163], v[192:195], v[76:79]
	v_mfma_f32_16x16x32_bf16 v[72:75], v[168:171], v[192:195], v[72:75]
	v_mfma_f32_16x16x32_bf16 v[68:71], v[160:163], v[200:203], v[68:71]
	v_mfma_f32_16x16x32_bf16 v[64:67], v[168:171], v[200:203], v[64:67]
	v_mfma_f32_16x16x32_bf16 v[104:107], v[164:167], v[180:183], v[104:107]
	v_mfma_f32_16x16x32_bf16 v[96:99], v[172:175], v[180:183], v[96:99]
	v_mfma_f32_16x16x32_bf16 v[88:91], v[164:167], v[188:191], v[88:91]
	v_mfma_f32_16x16x32_bf16 v[80:83], v[172:175], v[188:191], v[80:83]
	v_mfma_f32_16x16x32_bf16 v[76:79], v[164:167], v[196:199], v[76:79]
	v_mfma_f32_16x16x32_bf16 v[72:75], v[172:175], v[196:199], v[72:75]
	v_mfma_f32_16x16x32_bf16 v[68:71], v[164:167], v[204:207], v[68:71]
	v_mfma_f32_16x16x32_bf16 v[64:67], v[172:175], v[204:207], v[64:67]
	s_setprio 0
	s_add_i32 s46, s77, s7
	v_lshl_add_u64 v[208:209], v[208:209], 0, s[10:11]
	s_mov_b32 m0, s46
	s_barrier
; #define G_STAGE(bufoff, gbase, voff) do { _Pragma("unroll") for (int _i = 0; _i < 2; ++_i) \
;         __builtin_amdgcn_global_load_lds((const unsigned*)((const char*)(gbase) + voff[_i]), (LAS unsigned*)(lds + (bufoff) + ldsw + _i * 8192), 16, 0, 0); } while (0)
; #define G_LDA(dst, b, h) do { _Pragma("unroll") for (int m = 0; m < 4; ++m) _Pragma("unroll") for (int k = 0; k < 2; ++k) dst[m][k] = *(const LAS bf16x8*)(lds + G_SA(b, h) + aoff + m * 2048 + k * 1024); } while (0)
; #define G_LDB(dst, b, h) do { _Pragma("unroll") for (int n = 0; n < 2; ++n) _Pragma("unroll") for (int k = 0; k < 2; ++k) dst[n][k] = *(const LAS bf16x8*)(lds + G_SB(b, h) + boff + n * 2048 + k * 1024); } while (0)
; #define G_MMA(ai, bj, At_, Bt_) do { __builtin_amdgcn_s_setprio(1); _Pragma("unroll") for (int m = 0; m < 4; ++m) _Pragma("unroll") for (int n = 0; n < 2; ++n) _Pragma("unroll") for (int k = 0; k < 2; ++k) \
;         acc[ai][bj][m][n] = __builtin_amdgcn_mfma_f32_16x16x32_bf16(Bt_[n][k], At_[m][k], acc[ai][bj][m][n], 0, 0, 0); __builtin_amdgcn_s_setprio(0); } while (0)
; #define WAIT_V(n) asm volatile("s_waitcnt vmcnt(" #n ")" ::: "memory")
; #define BAR __builtin_amdgcn_s_barrier()
; template <class Get, class Epi>
; DI void gemm_loop(int ntiles, int ld, char* shm, const Get& get, const Epi& epi) {
;     ...
;             const char* a2 = last ? nA : cA + (size_t)(t + 2) * kstep; const char* b2 = last ? nB : cB + (size_t)(t + 2) * kstep;
;             const char* a3 = a2 + kstep; const char* b3 = b2 + kstep;
;             G_LDB(B0, 0, 0); G_LDB(B1, 0, 1); SCHED; G_LDA(At, 0, 0); G_STAGE(G_SA(1, 1), a1 + hstep, voffA);
;             WAIT_V(8); WAIT_L(0); BAR; G_MMA(0, 0, At, B0); G_MMA(0, 1, At, B1); BAR; SCHED;
;             G_LDA(At, 0, 1); G_STAGE(G_SB(0, 0), b2, voffB); G_STAGE(G_SB(0, 1), b2 + hstep, voffB); G_STAGE(G_SA(0, 0), a2, voffA);
;             WAIT_V(8); WAIT_L(0); BAR; G_MMA(1, 0, At, B0); G_MMA(1, 1, At, B1); BAR; SCHED;
;             G_LDB(B0, 1, 0); G_LDB(B1, 1, 1); SCHED; G_LDA(At, 1, 0); G_STAGE(G_SA(0, 1), a2 + hstep, voffA);
;             WAIT_V(8); WAIT_L(0); BAR; G_MMA(0, 0, At, B0); G_MMA(0, 1, At, B1); BAR; SCHED;
;             G_LDA(At, 1, 1); G_STAGE(G_SB(1, 0), b3, voffB); G_STAGE(G_SB(1, 1), b3 + hstep, voffB); G_STAGE(G_SA(1, 0), a3, voffA);
;             WAIT_V(8); WAIT_L(0); BAR; G_MMA(1, 0, At, B0); G_MMA(1, 1, At, B1); BAR; SCHED;
	ds_read_b128 v[176:179], v147 offset:49152
	ds_read_b128 v[180:183], v147 offset:50176
	ds_read_b128 v[184:187], v147 offset:51200
	ds_read_b128 v[188:191], v147 offset:52224
	ds_read_b128 v[192:195], v147 offset:53248
	ds_read_b128 v[196:199], v147 offset:54272
	ds_read_b128 v[200:203], v147 offset:55296
	ds_read_b128 v[204:207], v147 offset:56320
	global_load_lds_dwordx4 v[208:209], off
	s_add_i32 m0, s46, 0x2000
	s_add_u32 s14, s14, 0x40080
	v_lshl_add_u64 v[208:209], v[210:211], 0, s[10:11]
	s_addc_u32 s15, s15, 0
	s_add_i32 s46, s78, s7
	global_load_lds_dwordx4 v[208:209], off
	v_lshl_add_u64 v[208:209], s[14:15], 0, v[130:131]
	s_mov_b32 m0, s46
	s_nop 0
	global_load_lds_dwordx4 v[208:209], off
	v_lshl_add_u64 v[208:209], s[14:15], 0, v[134:135]
	s_add_i32 m0, s46, 0x2000
	s_nop 0
	global_load_lds_dwordx4 v[208:209], off
	v_lshl_add_u64 v[208:209], v[212:213], 0, s[10:11]
	s_mov_b32 m0, s54
	s_nop 0
	global_load_lds_dwordx4 v[208:209], off
	v_lshl_add_u64 v[208:209], v[214:215], 0, s[10:11]
	s_mov_b32 m0, s55
	s_nop 0
	global_load_lds_dwordx4 v[208:209], off
	s_waitcnt vmcnt(8)
	s_waitcnt lgkmcnt(0)
	s_barrier
	s_setprio 1
	s_waitcnt lgkmcnt(0)
	v_mfma_f32_16x16x32_bf16 v[60:63], v[140:143], v[176:179], v[60:63]
	v_mfma_f32_16x16x32_bf16 v[56:59], v[152:155], v[176:179], v[56:59]
	v_mfma_f32_16x16x32_bf16 v[52:55], v[140:143], v[184:187], v[52:55]
	v_mfma_f32_16x16x32_bf16 v[48:51], v[152:155], v[184:187], v[48:51]
	v_mfma_f32_16x16x32_bf16 v[44:47], v[140:143], v[192:195], v[44:47]
	v_mfma_f32_16x16x32_bf16 v[36:39], v[152:155], v[192:195], v[36:39]
	v_mfma_f32_16x16x32_bf16 v[28:31], v[140:143], v[200:203], v[28:31]
	v_mfma_f32_16x16x32_bf16 v[20:23], v[152:155], v[200:203], v[20:23]
	v_mfma_f32_16x16x32_bf16 v[60:63], v[148:151], v[180:183], v[60:63]
	v_mfma_f32_16x16x32_bf16 v[56:59], v[156:159], v[180:183], v[56:59]
	v_mfma_f32_16x16x32_bf16 v[52:55], v[148:151], v[188:191], v[52:55]
	v_mfma_f32_16x16x32_bf16 v[48:51], v[156:159], v[188:191], v[48:51]
	v_mfma_f32_16x16x32_bf16 v[44:47], v[148:151], v[196:199], v[44:47]
	v_mfma_f32_16x16x32_bf16 v[36:39], v[156:159], v[196:199], v[36:39]
	v_mfma_f32_16x16x32_bf16 v[28:31], v[148:151], v[204:207], v[28:31]
	v_mfma_f32_16x16x32_bf16 v[20:23], v[156:159], v[204:207], v[20:23]
	s_setprio 0
	s_setprio 1
	v_mfma_f32_16x16x32_bf16 v[40:43], v[160:163], v[176:179], v[40:43]
	v_mfma_f32_16x16x32_bf16 v[32:35], v[168:171], v[176:179], v[32:35]
	v_mfma_f32_16x16x32_bf16 v[24:27], v[160:163], v[184:187], v[24:27]
	v_mfma_f32_16x16x32_bf16 v[16:19], v[168:171], v[184:187], v[16:19]
	v_mfma_f32_16x16x32_bf16 v[12:15], v[160:163], v[192:195], v[12:15]
	v_mfma_f32_16x16x32_bf16 v[8:11], v[168:171], v[192:195], v[8:11]
	v_mfma_f32_16x16x32_bf16 v[4:7], v[160:163], v[200:203], v[4:7]
	v_mfma_f32_16x16x32_bf16 v[0:3], v[168:171], v[200:203], v[0:3]
	v_mfma_f32_16x16x32_bf16 v[40:43], v[164:167], v[180:183], v[40:43]
	v_mfma_f32_16x16x32_bf16 v[32:35], v[172:175], v[180:183], v[32:35]
	v_mfma_f32_16x16x32_bf16 v[24:27], v[164:167], v[188:191], v[24:27]
	v_mfma_f32_16x16x32_bf16 v[16:19], v[172:175], v[188:191], v[16:19]
	v_mfma_f32_16x16x32_bf16 v[12:15], v[164:167], v[196:199], v[12:15]
	v_mfma_f32_16x16x32_bf16 v[8:11], v[172:175], v[196:199], v[8:11]
	v_mfma_f32_16x16x32_bf16 v[4:7], v[164:167], v[204:207], v[4:7]
	v_mfma_f32_16x16x32_bf16 v[0:3], v[172:175], v[204:207], v[0:3]
	s_setprio 0
	s_add_i32 s76, s76, 2
	s_add_u32 s52, s52, 0x100
	s_addc_u32 s53, s53, 0
	s_add_u32 s74, s74, 0x100
	s_addc_u32 s75, s75, 0
	s_cmp_gt_u32 s76, 13
	s_barrier
	s_cbranch_scc0 .LBB0_1099
	s_branch .Lpost_1099
.LBB0_1099:
	ds_read_b128 v[140:143], v145
	ds_read_b128 v[148:151], v145 offset:1024
	ds_read_b128 v[152:155], v145 offset:2048
	ds_read_b128 v[156:159], v145 offset:3072
	ds_read_b128 v[160:163], v146
	ds_read_b128 v[164:167], v146 offset:1024
	ds_read_b128 v[168:171], v146 offset:2048
	ds_read_b128 v[172:175], v146 offset:3072
	s_add_u32 s14, s52, 0xfffc0080
	s_addc_u32 s15, s53, -1
	s_cmp_eq_u32 s76, 12
	s_cselect_b32 s47, s39, s15
	s_cselect_b32 s46, s72, s14
	s_cselect_b32 s15, s37, s75
	s_cselect_b32 s14, s73, s74
	v_lshl_add_u64 v[208:209], s[52:53], 0, v[136:137]
	s_add_i32 m0, s45, 0xc000
	ds_read_b128 v[176:179], v147
	ds_read_b128 v[180:183], v147 offset:1024
	ds_read_b128 v[184:187], v147 offset:2048
	ds_read_b128 v[188:191], v147 offset:3072
	ds_read_b128 v[192:195], v147 offset:4096
	ds_read_b128 v[196:199], v147 offset:5120
	ds_read_b128 v[200:203], v147 offset:6144
	ds_read_b128 v[204:207], v147 offset:7168
	global_load_lds_dwordx4 v[208:209], off
	v_lshl_add_u64 v[208:209], s[52:53], 0, v[138:139]
	s_add_i32 m0, s45, 0xe000
	s_nop 0
	global_load_lds_dwordx4 v[208:209], off
	s_waitcnt vmcnt(8)
	s_waitcnt lgkmcnt(0)
	s_barrier
; #define G_STAGE(bufoff, gbase, voff) do { _Pragma("unroll") for (int _i = 0; _i < 2; ++_i) \
;         __builtin_amdgcn_global_load_lds((const unsigned*)((const char*)(gbase) + voff[_i]), (LAS unsigned*)(lds + (bufoff) + ldsw + _i * 8192), 16, 0, 0); } while (0)
; #define G_LDA(dst, b, h) do { _Pragma("unroll") for (int m = 0; m < 4; ++m) _Pragma("unroll") for (int k = 0; k < 2; ++k) dst[m][k] = *(const LAS bf16x8*)(lds + G_SA(b, h) + aoff + m * 2048 + k * 1024); } while (0)
; #define G_LDB(dst, b, h) do { _Pragma("unroll") for (int n = 0; n < 2; ++n) _Pragma("unroll") for (int k = 0; k < 2; ++k) dst[n][k] = *(const LAS bf16x8*)(lds + G_SB(b, h) + boff + n * 2048 + k * 1024); } while (0)
; #define G_MMA(ai, bj, At_, Bt_) do { __builtin_amdgcn_s_setprio(1); _Pragma("unroll") for (int m = 0; m < 4; ++m) _Pragma("unroll") for (int n = 0; n < 2; ++n) _Pragma("unroll") for (int k = 0; k < 2; ++k) \
;         acc[ai][bj][m][n] = __builtin_amdgcn_mfma_f32_16x16x32_bf16(Bt_[n][k], At_[m][k], acc[ai][bj][m][n], 0, 0, 0); __builtin_amdgcn_s_setprio(0); } while (0)
; #define WAIT_V(n) asm volatile("s_waitcnt vmcnt(" #n ")" ::: "memory")
; #define WAIT_L(n) asm volatile("s_waitcnt lgkmcnt(" #n ")" ::: "memory")
; #define BAR __builtin_amdgcn_s_barrier()
; #define SCHED __builtin_amdgcn_sched_barrier(0)
; template <class Get, class Epi>
; DI void gemm_loop(int ntiles, int ld, char* shm, const Get& get, const Epi& epi) {
;     ...
;             WAIT_V(8); WAIT_L(0); BAR; G_MMA(0, 0, At, B0); G_MMA(0, 1, At, B1); BAR; SCHED;
;             G_LDA(At, 0, 1); G_STAGE(G_SB(0, 0), b2, voffB); G_STAGE(G_SB(0, 1), b2 + hstep, voffB); G_STAGE(G_SA(0, 0), a2, voffA);
;             WAIT_V(8); WAIT_L(0); BAR; G_MMA(1, 0, At, B0); G_MMA(1, 1, At, B1); BAR; SCHED;
;             G_LDB(B0, 1, 0); G_LDB(B1, 1, 1); SCHED; G_LDA(At, 1, 0); G_STAGE(G_SA(0, 1), a2 + hstep, voffA);
	s_setprio 1
	s_waitcnt lgkmcnt(0)
	v_mfma_f32_16x16x32_bf16 v[124:127], v[140:143], v[176:179], v[124:127]
	v_mfma_f32_16x16x32_bf16 v[120:123], v[152:155], v[176:179], v[120:123]
	v_mfma_f32_16x16x32_bf16 v[116:119], v[140:143], v[184:187], v[116:119]
	v_mfma_f32_16x16x32_bf16 v[112:115], v[152:155], v[184:187], v[112:115]
	v_mfma_f32_16x16x32_bf16 v[108:111], v[140:143], v[192:195], v[108:111]
	v_mfma_f32_16x16x32_bf16 v[100:103], v[152:155], v[192:195], v[100:103]
	v_mfma_f32_16x16x32_bf16 v[92:95], v[140:143], v[200:203], v[92:95]
	v_mfma_f32_16x16x32_bf16 v[84:87], v[152:155], v[200:203], v[84:87]
	v_mfma_f32_16x16x32_bf16 v[124:127], v[148:151], v[180:183], v[124:127]
	v_mfma_f32_16x16x32_bf16 v[120:123], v[156:159], v[180:183], v[120:123]
	v_mfma_f32_16x16x32_bf16 v[116:119], v[148:151], v[188:191], v[116:119]
	v_mfma_f32_16x16x32_bf16 v[112:115], v[156:159], v[188:191], v[112:115]
	v_mfma_f32_16x16x32_bf16 v[108:111], v[148:151], v[196:199], v[108:111]
	v_mfma_f32_16x16x32_bf16 v[100:103], v[156:159], v[196:199], v[100:103]
	v_mfma_f32_16x16x32_bf16 v[92:95], v[148:151], v[204:207], v[92:95]
	v_mfma_f32_16x16x32_bf16 v[84:87], v[156:159], v[204:207], v[84:87]
	s_setprio 0
	s_setprio 1
	v_mfma_f32_16x16x32_bf16 v[104:107], v[160:163], v[176:179], v[104:107]
	v_mfma_f32_16x16x32_bf16 v[96:99], v[168:171], v[176:179], v[96:99]
	v_mfma_f32_16x16x32_bf16 v[88:91], v[160:163], v[184:187], v[88:91]
	v_mfma_f32_16x16x32_bf16 v[80:83], v[168:171], v[184:187], v[80:83]
	v_mfma_f32_16x16x32_bf16 v[76:79], v[160:163], v[192:195], v[76:79]
	v_mfma_f32_16x16x32_bf16 v[72:75], v[168:171], v[192:195], v[72:75]
	v_mfma_f32_16x16x32_bf16 v[68:71], v[160:163], v[200:203], v[68:71]
	v_mfma_f32_16x16x32_bf16 v[64:67], v[168:171], v[200:203], v[64:67]
	v_mfma_f32_16x16x32_bf16 v[104:107], v[164:167], v[180:183], v[104:107]
	v_mfma_f32_16x16x32_bf16 v[96:99], v[172:175], v[180:183], v[96:99]
	v_mfma_f32_16x16x32_bf16 v[88:91], v[164:167], v[188:191], v[88:91]
	v_mfma_f32_16x16x32_bf16 v[80:83], v[172:175], v[188:191], v[80:83]
	v_mfma_f32_16x16x32_bf16 v[76:79], v[164:167], v[196:199], v[76:79]
	v_mfma_f32_16x16x32_bf16 v[72:75], v[172:175], v[196:199], v[72:75]
	v_mfma_f32_16x16x32_bf16 v[68:71], v[164:167], v[204:207], v[68:71]
	v_mfma_f32_16x16x32_bf16 v[64:67], v[172:175], v[204:207], v[64:67]
	s_setprio 0
	s_add_i32 s77, s57, s7
	v_lshl_add_u64 v[208:209], s[14:15], 0, v[130:131]
	s_mov_b32 m0, s77
	s_barrier
	ds_read_b128 v[176:179], v147 offset:16384
	ds_read_b128 v[180:183], v147 offset:17408
	ds_read_b128 v[184:187], v147 offset:18432
	ds_read_b128 v[188:191], v147 offset:19456
	ds_read_b128 v[192:195], v147 offset:20480
	ds_read_b128 v[196:199], v147 offset:21504
	ds_read_b128 v[200:203], v147 offset:22528
	ds_read_b128 v[204:207], v147 offset:23552
	global_load_lds_dwordx4 v[208:209], off
	s_add_i32 m0, s77, 0x2000
	s_add_u32 s78, s14, 0x40000
	v_lshl_add_u64 v[210:211], s[14:15], 0, v[134:135]
	s_addc_u32 s79, s15, 0
	s_add_i32 s77, s58, s7
	global_load_lds_dwordx4 v[210:211], off
	v_lshl_add_u64 v[212:213], s[78:79], 0, v[130:131]
	s_mov_b32 m0, s77
	v_lshl_add_u64 v[214:215], s[46:47], 0, v[132:133]
	global_load_lds_dwordx4 v[212:213], off
	v_lshl_add_u64 v[212:213], s[78:79], 0, v[134:135]
	s_add_i32 m0, s77, 0x2000
	s_nop 0
	global_load_lds_dwordx4 v[212:213], off
	v_lshl_add_u64 v[212:213], s[46:47], 0, v[128:129]
	s_mov_b32 m0, s45
	s_nop 0
	global_load_lds_dwordx4 v[212:213], off
	s_mov_b32 m0, s49
	s_nop 0
	global_load_lds_dwordx4 v[214:215], off
	s_waitcnt vmcnt(8)
	s_waitcnt lgkmcnt(0)
	s_barrier
	s_setprio 1
	s_waitcnt lgkmcnt(0)
	v_mfma_f32_16x16x32_bf16 v[60:63], v[140:143], v[176:179], v[60:63]
	v_mfma_f32_16x16x32_bf16 v[56:59], v[152:155], v[176:179], v[56:59]
	v_mfma_f32_16x16x32_bf16 v[52:55], v[140:143], v[184:187], v[52:55]
	v_mfma_f32_16x16x32_bf16 v[48:51], v[152:155], v[184:187], v[48:51]
	v_mfma_f32_16x16x32_bf16 v[44:47], v[140:143], v[192:195], v[44:47]
	v_mfma_f32_16x16x32_bf16 v[36:39], v[152:155], v[192:195], v[36:39]
	v_mfma_f32_16x16x32_bf16 v[28:31], v[140:143], v[200:203], v[28:31]
	v_mfma_f32_16x16x32_bf16 v[20:23], v[152:155], v[200:203], v[20:23]
	v_mfma_f32_16x16x32_bf16 v[60:63], v[148:151], v[180:183], v[60:63]
	v_mfma_f32_16x16x32_bf16 v[56:59], v[156:159], v[180:183], v[56:59]
	v_mfma_f32_16x16x32_bf16 v[52:55], v[148:151], v[188:191], v[52:55]
	v_mfma_f32_16x16x32_bf16 v[48:51], v[156:159], v[188:191], v[48:51]
	v_mfma_f32_16x16x32_bf16 v[44:47], v[148:151], v[196:199], v[44:47]
	v_mfma_f32_16x16x32_bf16 v[36:39], v[156:159], v[196:199], v[36:39]
	v_mfma_f32_16x16x32_bf16 v[28:31], v[148:151], v[204:207], v[28:31]
	v_mfma_f32_16x16x32_bf16 v[20:23], v[156:159], v[204:207], v[20:23]
	s_setprio 0
	s_setprio 1
	v_mfma_f32_16x16x32_bf16 v[40:43], v[160:163], v[176:179], v[40:43]
	v_mfma_f32_16x16x32_bf16 v[32:35], v[168:171], v[176:179], v[32:35]
	v_mfma_f32_16x16x32_bf16 v[24:27], v[160:163], v[184:187], v[24:27]
	v_mfma_f32_16x16x32_bf16 v[16:19], v[168:171], v[184:187], v[16:19]
	v_mfma_f32_16x16x32_bf16 v[12:15], v[160:163], v[192:195], v[12:15]
	v_mfma_f32_16x16x32_bf16 v[8:11], v[168:171], v[192:195], v[8:11]
	v_mfma_f32_16x16x32_bf16 v[4:7], v[160:163], v[200:203], v[4:7]
	v_mfma_f32_16x16x32_bf16 v[0:3], v[168:171], v[200:203], v[0:3]
	v_mfma_f32_16x16x32_bf16 v[40:43], v[164:167], v[180:183], v[40:43]
	v_mfma_f32_16x16x32_bf16 v[32:35], v[172:175], v[180:183], v[32:35]
	v_mfma_f32_16x16x32_bf16 v[24:27], v[164:167], v[188:191], v[24:27]
	v_mfma_f32_16x16x32_bf16 v[16:19], v[172:175], v[188:191], v[16:19]
	v_mfma_f32_16x16x32_bf16 v[12:15], v[164:167], v[196:199], v[12:15]
	v_mfma_f32_16x16x32_bf16 v[8:11], v[172:175], v[196:199], v[8:11]
	v_mfma_f32_16x16x32_bf16 v[4:7], v[164:167], v[204:207], v[4:7]
	v_mfma_f32_16x16x32_bf16 v[0:3], v[172:175], v[204:207], v[0:3]
	s_setprio 0
	s_add_i32 s77, 0, 0x18000
	s_add_i32 s78, 0, 0x1c000
	v_add_u32_e32 v156, s77, v144
	s_barrier
; #define G_STAGE(bufoff, gbase, voff) do { _Pragma("unroll") for (int _i = 0; _i < 2; ++_i) \
;         __builtin_amdgcn_global_load_lds((const unsigned*)((const char*)(gbase) + voff[_i]), (LAS unsigned*)(lds + (bufoff) + ldsw + _i * 8192), 16, 0, 0); } while (0)
; #define G_LDA(dst, b, h) do { _Pragma("unroll") for (int m = 0; m < 4; ++m) _Pragma("unroll") for (int k = 0; k < 2; ++k) dst[m][k] = *(const LAS bf16x8*)(lds + G_SA(b, h) + aoff + m * 2048 + k * 1024); } while (0)
; #define G_LDB(dst, b, h) do { _Pragma("unroll") for (int n = 0; n < 2; ++n) _Pragma("unroll") for (int k = 0; k < 2; ++k) dst[n][k] = *(const LAS bf16x8*)(lds + G_SB(b, h) + boff + n * 2048 + k * 1024); } while (0)
; #define G_MMA(ai, bj, At_, Bt_) do { __builtin_amdgcn_s_setprio(1); _Pragma("unroll") for (int m = 0; m < 4; ++m) _Pragma("unroll") for (int n = 0; n < 2; ++n) _Pragma("unroll") for (int k = 0; k < 2; ++k) \
;         acc[ai][bj][m][n] = __builtin_amdgcn_mfma_f32_16x16x32_bf16(Bt_[n][k], At_[m][k], acc[ai][bj][m][n], 0, 0, 0); __builtin_amdgcn_s_setprio(0); } while (0)
; #define WAIT_V(n) asm volatile("s_waitcnt vmcnt(" #n ")" ::: "memory")
; #define WAIT_L(n) asm volatile("s_waitcnt lgkmcnt(" #n ")" ::: "memory")
; #define BAR __builtin_amdgcn_s_barrier()
; #define SCHED __builtin_amdgcn_sched_barrier(0)
; template <class Get, class Epi>
; DI void gemm_loop(int ntiles, int ld, char* shm, const Get& get, const Epi& epi) {
;     ...
;             G_LDB(B0, 1, 0); G_LDB(B1, 1, 1); SCHED; G_LDA(At, 1, 0); G_STAGE(G_SA(0, 1), a2 + hstep, voffA);
;             WAIT_V(8); WAIT_L(0); BAR; G_MMA(0, 0, At, B0); G_MMA(0, 1, At, B1); BAR; SCHED;
;             G_LDA(At, 1, 1); G_STAGE(G_SB(1, 0), b3, voffB); G_STAGE(G_SB(1, 1), b3 + hstep, voffB); G_STAGE(G_SA(1, 0), a3, voffA);
	v_add_u32_e32 v172, s78, v144
	ds_read_b128 v[140:143], v156
	ds_read_b128 v[148:151], v156 offset:1024
	ds_read_b128 v[152:155], v156 offset:2048
	ds_read_b128 v[156:159], v156 offset:3072
	ds_read_b128 v[160:163], v172
	ds_read_b128 v[164:167], v172 offset:1024
	ds_read_b128 v[168:171], v172 offset:2048
	ds_read_b128 v[172:175], v172 offset:3072
	s_add_u32 s46, s46, 0x40000
	s_addc_u32 s47, s47, 0
	s_mov_b32 m0, s50
	v_lshl_add_u64 v[216:217], s[46:47], 0, v[128:129]
	ds_read_b128 v[176:179], v147 offset:32768
	ds_read_b128 v[180:183], v147 offset:33792
	ds_read_b128 v[184:187], v147 offset:34816
	ds_read_b128 v[188:191], v147 offset:35840
	ds_read_b128 v[192:195], v147 offset:36864
	ds_read_b128 v[196:199], v147 offset:37888
	ds_read_b128 v[200:203], v147 offset:38912
	ds_read_b128 v[204:207], v147 offset:39936
	global_load_lds_dwordx4 v[216:217], off
	v_lshl_add_u64 v[216:217], s[46:47], 0, v[132:133]
	s_mov_b32 m0, s51
	s_nop 0
	global_load_lds_dwordx4 v[216:217], off
	s_waitcnt vmcnt(8)
	s_waitcnt lgkmcnt(0)
	s_barrier
	s_setprio 1
	s_waitcnt lgkmcnt(0)
	v_mfma_f32_16x16x32_bf16 v[124:127], v[140:143], v[176:179], v[124:127]
	v_mfma_f32_16x16x32_bf16 v[120:123], v[152:155], v[176:179], v[120:123]
	v_mfma_f32_16x16x32_bf16 v[116:119], v[140:143], v[184:187], v[116:119]
	v_mfma_f32_16x16x32_bf16 v[112:115], v[152:155], v[184:187], v[112:115]
	v_mfma_f32_16x16x32_bf16 v[108:111], v[140:143], v[192:195], v[108:111]
	v_mfma_f32_16x16x32_bf16 v[100:103], v[152:155], v[192:195], v[100:103]
	v_mfma_f32_16x16x32_bf16 v[92:95], v[140:143], v[200:203], v[92:95]
	v_mfma_f32_16x16x32_bf16 v[84:87], v[152:155], v[200:203], v[84:87]
	v_mfma_f32_16x16x32_bf16 v[124:127], v[148:151], v[180:183], v[124:127]
	v_mfma_f32_16x16x32_bf16 v[120:123], v[156:159], v[180:183], v[120:123]
	v_mfma_f32_16x16x32_bf16 v[116:119], v[148:151], v[188:191], v[116:119]
	v_mfma_f32_16x16x32_bf16 v[112:115], v[156:159], v[188:191], v[112:115]
	v_mfma_f32_16x16x32_bf16 v[108:111], v[148:151], v[196:199], v[108:111]
	v_mfma_f32_16x16x32_bf16 v[100:103], v[156:159], v[196:199], v[100:103]
	v_mfma_f32_16x16x32_bf16 v[92:95], v[148:151], v[204:207], v[92:95]
	v_mfma_f32_16x16x32_bf16 v[84:87], v[156:159], v[204:207], v[84:87]
	s_setprio 0
	s_setprio 1
	v_mfma_f32_16x16x32_bf16 v[104:107], v[160:163], v[176:179], v[104:107]
	v_mfma_f32_16x16x32_bf16 v[96:99], v[168:171], v[176:179], v[96:99]
	v_mfma_f32_16x16x32_bf16 v[88:91], v[160:163], v[184:187], v[88:91]
	v_mfma_f32_16x16x32_bf16 v[80:83], v[168:171], v[184:187], v[80:83]
	v_mfma_f32_16x16x32_bf16 v[76:79], v[160:163], v[192:195], v[76:79]
	v_mfma_f32_16x16x32_bf16 v[72:75], v[168:171], v[192:195], v[72:75]
	v_mfma_f32_16x16x32_bf16 v[68:71], v[160:163], v[200:203], v[68:71]
	v_mfma_f32_16x16x32_bf16 v[64:67], v[168:171], v[200:203], v[64:67]
	v_mfma_f32_16x16x32_bf16 v[104:107], v[164:167], v[180:183], v[104:107]
	v_mfma_f32_16x16x32_bf16 v[96:99], v[172:175], v[180:183], v[96:99]
	v_mfma_f32_16x16x32_bf16 v[88:91], v[164:167], v[188:191], v[88:91]
	v_mfma_f32_16x16x32_bf16 v[80:83], v[172:175], v[188:191], v[80:83]
	v_mfma_f32_16x16x32_bf16 v[76:79], v[164:167], v[196:199], v[76:79]
	v_mfma_f32_16x16x32_bf16 v[72:75], v[172:175], v[196:199], v[72:75]
	v_mfma_f32_16x16x32_bf16 v[68:71], v[164:167], v[204:207], v[68:71]
	v_mfma_f32_16x16x32_bf16 v[64:67], v[172:175], v[204:207], v[64:67]
	s_setprio 0
	s_add_i32 s46, s77, s7
	v_lshl_add_u64 v[208:209], v[208:209], 0, s[10:11]
	s_mov_b32 m0, s46
	s_barrier
; #define G_STAGE(bufoff, gbase, voff) do { _Pragma("unroll") for (int _i = 0; _i < 2; ++_i) \
;         __builtin_amdgcn_global_load_lds((const unsigned*)((const char*)(gbase) + voff[_i]), (LAS unsigned*)(lds + (bufoff) + ldsw + _i * 8192), 16, 0, 0); } while (0)
; #define G_LDA(dst, b, h) do { _Pragma("unroll") for (int m = 0; m < 4; ++m) _Pragma("unroll") for (int k = 0; k < 2; ++k) dst[m][k] = *(const LAS bf16x8*)(lds + G_SA(b, h) + aoff + m * 2048 + k * 1024); } while (0)
; #define G_MMA(ai, bj, At_, Bt_) do { __builtin_amdgcn_s_setprio(1); _Pragma("unroll") for (int m = 0; m < 4; ++m) _Pragma("unroll") for (int n = 0; n < 2; ++n) _Pragma("unroll") for (int k = 0; k < 2; ++k) \
;         acc[ai][bj][m][n] = __builtin_amdgcn_mfma_f32_16x16x32_bf16(Bt_[n][k], At_[m][k], acc[ai][bj][m][n], 0, 0, 0); __builtin_amdgcn_s_setprio(0); } while (0)
; #define WAIT_V(n) asm volatile("s_waitcnt vmcnt(" #n ")" ::: "memory")
; #define WAIT_L(n) asm volatile("s_waitcnt lgkmcnt(" #n ")" ::: "memory")
; #define BAR __builtin_amdgcn_s_barrier()
; #define SCHED __builtin_amdgcn_sched_barrier(0)
; template <class Get, class Epi>
; DI void gemm_loop(int ntiles, int ld, char* shm, const Get& get, const Epi& epi) {
;     ...
;             G_LDA(At, 1, 1); G_STAGE(G_SB(1, 0), b3, voffB); G_STAGE(G_SB(1, 1), b3 + hstep, voffB); G_STAGE(G_SA(1, 0), a3, voffA);
;             WAIT_V(8); WAIT_L(0); BAR; G_MMA(1, 0, At, B0); G_MMA(1, 1, At, B1); BAR; SCHED;
;         }
	ds_read_b128 v[176:179], v147 offset:49152
	ds_read_b128 v[180:183], v147 offset:50176
	ds_read_b128 v[184:187], v147 offset:51200
	ds_read_b128 v[188:191], v147 offset:52224
	ds_read_b128 v[192:195], v147 offset:53248
	ds_read_b128 v[196:199], v147 offset:54272
	ds_read_b128 v[200:203], v147 offset:55296
	ds_read_b128 v[204:207], v147 offset:56320
	global_load_lds_dwordx4 v[208:209], off
	s_add_i32 m0, s46, 0x2000
	s_add_u32 s14, s14, 0x40080
	v_lshl_add_u64 v[208:209], v[210:211], 0, s[10:11]
	s_addc_u32 s15, s15, 0
	s_add_i32 s46, s78, s7
	global_load_lds_dwordx4 v[208:209], off
	v_lshl_add_u64 v[208:209], s[14:15], 0, v[130:131]
	s_mov_b32 m0, s46
	s_nop 0
	global_load_lds_dwordx4 v[208:209], off
	v_lshl_add_u64 v[208:209], s[14:15], 0, v[134:135]
	s_add_i32 m0, s46, 0x2000
	s_nop 0
	global_load_lds_dwordx4 v[208:209], off
	v_lshl_add_u64 v[208:209], v[212:213], 0, s[10:11]
	s_mov_b32 m0, s54
	s_nop 0
	global_load_lds_dwordx4 v[208:209], off
	v_lshl_add_u64 v[208:209], v[214:215], 0, s[10:11]
	s_mov_b32 m0, s55
	s_nop 0
	global_load_lds_dwordx4 v[208:209], off
	s_waitcnt vmcnt(8)
	s_waitcnt lgkmcnt(0)
	s_barrier
	s_setprio 1
	s_waitcnt lgkmcnt(0)
	v_mfma_f32_16x16x32_bf16 v[60:63], v[140:143], v[176:179], v[60:63]
	v_mfma_f32_16x16x32_bf16 v[56:59], v[152:155], v[176:179], v[56:59]
	v_mfma_f32_16x16x32_bf16 v[52:55], v[140:143], v[184:187], v[52:55]
	v_mfma_f32_16x16x32_bf16 v[48:51], v[152:155], v[184:187], v[48:51]
	v_mfma_f32_16x16x32_bf16 v[44:47], v[140:143], v[192:195], v[44:47]
	v_mfma_f32_16x16x32_bf16 v[36:39], v[152:155], v[192:195], v[36:39]
	v_mfma_f32_16x16x32_bf16 v[28:31], v[140:143], v[200:203], v[28:31]
	v_mfma_f32_16x16x32_bf16 v[20:23], v[152:155], v[200:203], v[20:23]
	v_mfma_f32_16x16x32_bf16 v[60:63], v[148:151], v[180:183], v[60:63]
	v_mfma_f32_16x16x32_bf16 v[56:59], v[156:159], v[180:183], v[56:59]
	v_mfma_f32_16x16x32_bf16 v[52:55], v[148:151], v[188:191], v[52:55]
	v_mfma_f32_16x16x32_bf16 v[48:51], v[156:159], v[188:191], v[48:51]
	v_mfma_f32_16x16x32_bf16 v[44:47], v[148:151], v[196:199], v[44:47]
	v_mfma_f32_16x16x32_bf16 v[36:39], v[156:159], v[196:199], v[36:39]
	v_mfma_f32_16x16x32_bf16 v[28:31], v[148:151], v[204:207], v[28:31]
	v_mfma_f32_16x16x32_bf16 v[20:23], v[156:159], v[204:207], v[20:23]
	s_setprio 0
	s_setprio 1
	v_mfma_f32_16x16x32_bf16 v[40:43], v[160:163], v[176:179], v[40:43]
	v_mfma_f32_16x16x32_bf16 v[32:35], v[168:171], v[176:179], v[32:35]
	v_mfma_f32_16x16x32_bf16 v[24:27], v[160:163], v[184:187], v[24:27]
	v_mfma_f32_16x16x32_bf16 v[16:19], v[168:171], v[184:187], v[16:19]
	v_mfma_f32_16x16x32_bf16 v[12:15], v[160:163], v[192:195], v[12:15]
	v_mfma_f32_16x16x32_bf16 v[8:11], v[168:171], v[192:195], v[8:11]
	v_mfma_f32_16x16x32_bf16 v[4:7], v[160:163], v[200:203], v[4:7]
	v_mfma_f32_16x16x32_bf16 v[0:3], v[168:171], v[200:203], v[0:3]
	v_mfma_f32_16x16x32_bf16 v[40:43], v[164:167], v[180:183], v[40:43]
	v_mfma_f32_16x16x32_bf16 v[32:35], v[172:175], v[180:183], v[32:35]
	v_mfma_f32_16x16x32_bf16 v[24:27], v[164:167], v[188:191], v[24:27]
	v_mfma_f32_16x16x32_bf16 v[16:19], v[172:175], v[188:191], v[16:19]
	v_mfma_f32_16x16x32_bf16 v[12:15], v[164:167], v[196:199], v[12:15]
	v_mfma_f32_16x16x32_bf16 v[8:11], v[172:175], v[196:199], v[8:11]
	v_mfma_f32_16x16x32_bf16 v[4:7], v[164:167], v[204:207], v[4:7]
	v_mfma_f32_16x16x32_bf16 v[0:3], v[172:175], v[204:207], v[0:3]
	s_setprio 0
	s_add_i32 s76, s76, 2
	s_add_u32 s52, s52, 0x100
	s_addc_u32 s53, s53, 0
	s_add_u32 s74, s74, 0x100
	s_addc_u32 s75, s75, 0
	s_cmp_gt_u32 s76, 13
	s_barrier
	s_cbranch_scc0 .LBB0_1099

; #define G_STAGE(bufoff, gbase, voff) do { _Pragma("unroll") for (int _i = 0; _i < 2; ++_i) \
;         __builtin_amdgcn_global_load_lds((const unsigned*)((const char*)(gbase) + voff[_i]), (LAS unsigned*)(lds + (bufoff) + ldsw + _i * 8192), 16, 0, 0); } while (0)
; #define G_LDA(dst, b, h) do { _Pragma("unroll") for (int m = 0; m < 4; ++m) _Pragma("unroll") for (int k = 0; k < 2; ++k) dst[m][k] = *(const LAS bf16x8*)(lds + G_SA(b, h) + aoff + m * 2048 + k * 1024); } while (0)
; #define G_LDB(dst, b, h) do { _Pragma("unroll") for (int n = 0; n < 2; ++n) _Pragma("unroll") for (int k = 0; k < 2; ++k) dst[n][k] = *(const LAS bf16x8*)(lds + G_SB(b, h) + boff + n * 2048 + k * 1024); } while (0)
; #define G_MMA(ai, bj, At_, Bt_) do { __builtin_amdgcn_s_setprio(1); _Pragma("unroll") for (int m = 0; m < 4; ++m) _Pragma("unroll") for (int n = 0; n < 2; ++n) _Pragma("unroll") for (int k = 0; k < 2; ++k) \
;         acc[ai][bj][m][n] = __builtin_amdgcn_mfma_f32_16x16x32_bf16(Bt_[n][k], At_[m][k], acc[ai][bj][m][n], 0, 0, 0); __builtin_amdgcn_s_setprio(0); } while (0)
; #define WAIT_V(n) asm volatile("s_waitcnt vmcnt(" #n ")" ::: "memory")
; #define WAIT_L(n) asm volatile("s_waitcnt lgkmcnt(" #n ")" ::: "memory")
; #define BAR __builtin_amdgcn_s_barrier()
; #define SCHED __builtin_amdgcn_sched_barrier(0)
; template <class Get, class Epi>
; DI void gemm_loop(int ntiles, int ld, char* shm, const Get& get, const Epi& epi) {
;     ...
;             const bool last = (t == nt - 2);
;             const char* a1 = cA + (size_t)(t + 1) * kstep;
;             const char* a2 = last ? nA : cA + (size_t)(t + 2) * kstep; const char* b2 = last ? nB : cB + (size_t)(t + 2) * kstep;
;             const char* a3 = a2 + kstep; const char* b3 = b2 + kstep;
;             G_LDB(B0, 0, 0); G_LDB(B1, 0, 1); SCHED; G_LDA(At, 0, 0); G_STAGE(G_SA(1, 1), a1 + hstep, voffA);
;             WAIT_V(8); WAIT_L(0); BAR; G_MMA(0, 0, At, B0); G_MMA(0, 1, At, B1); BAR; SCHED;
;             G_LDA(At, 0, 1); G_STAGE(G_SB(0, 0), b2, voffB); G_STAGE(G_SB(0, 1), b2 + hstep, voffB); G_STAGE(G_SA(0, 0), a2, voffA);
.Lpeel_1463:
	ds_read_b128 v[128:131], v169
	ds_read_b128 v[132:135], v169 offset:1024
	ds_read_b128 v[136:139], v169 offset:2048
	ds_read_b128 v[140:143], v169 offset:3072
	ds_read_b128 v[158:161], v170
	ds_read_b128 v[162:165], v170 offset:1024
	ds_read_b128 v[172:175], v170 offset:2048
	ds_read_b128 v[176:179], v170 offset:3072
	s_add_i32 s78, s14, 2
	s_add_u32 s15, s48, 0xfffc0080
	s_addc_u32 s46, s49, -1
	s_cmp_eq_u32 s75, s14
	s_cselect_b32 s14, s73, s76
	s_cselect_b32 s47, s3, s46
	s_cselect_b32 s46, s37, s15
	s_cselect_b32 s15, s39, s77
	v_lshl_add_u64 v[144:145], s[48:49], 0, v[154:155]
	s_add_i32 m0, s45, 0xc000
	ds_read_b128 v[180:183], v171
	ds_read_b128 v[184:187], v171 offset:1024
	ds_read_b128 v[188:191], v171 offset:2048
	ds_read_b128 v[192:195], v171 offset:3072
	ds_read_b128 v[196:199], v171 offset:4096
	ds_read_b128 v[200:203], v171 offset:5120
	ds_read_b128 v[204:207], v171 offset:6144
	ds_read_b128 v[208:211], v171 offset:7168
	global_load_lds_dwordx4 v[144:145], off
	v_lshl_add_u64 v[144:145], s[48:49], 0, v[156:157]
	s_add_i32 m0, s45, 0xe000
	s_nop 0
	global_load_lds_dwordx4 v[144:145], off
	s_waitcnt vmcnt(8)
	s_waitcnt lgkmcnt(0)
	s_barrier
	s_setprio 1
	s_waitcnt lgkmcnt(0)
	v_mfma_f32_16x16x32_bf16 v[124:127], v[128:131], v[180:183], 0
	v_mfma_f32_16x16x32_bf16 v[120:123], v[136:139], v[180:183], 0
	v_mfma_f32_16x16x32_bf16 v[116:119], v[128:131], v[188:191], 0
	v_mfma_f32_16x16x32_bf16 v[112:115], v[136:139], v[188:191], 0
	v_mfma_f32_16x16x32_bf16 v[108:111], v[128:131], v[196:199], 0
	v_mfma_f32_16x16x32_bf16 v[104:107], v[136:139], v[196:199], 0
	v_mfma_f32_16x16x32_bf16 v[100:103], v[128:131], v[204:207], 0
	v_mfma_f32_16x16x32_bf16 v[96:99], v[136:139], v[204:207], 0
	v_mfma_f32_16x16x32_bf16 v[124:127], v[132:135], v[184:187], v[124:127]
	v_mfma_f32_16x16x32_bf16 v[120:123], v[140:143], v[184:187], v[120:123]
	v_mfma_f32_16x16x32_bf16 v[116:119], v[132:135], v[192:195], v[116:119]
	v_mfma_f32_16x16x32_bf16 v[112:115], v[140:143], v[192:195], v[112:115]
	v_mfma_f32_16x16x32_bf16 v[108:111], v[132:135], v[200:203], v[108:111]
	v_mfma_f32_16x16x32_bf16 v[104:107], v[140:143], v[200:203], v[104:107]
	v_mfma_f32_16x16x32_bf16 v[100:103], v[132:135], v[208:211], v[100:103]
	v_mfma_f32_16x16x32_bf16 v[96:99], v[140:143], v[208:211], v[96:99]
	s_setprio 0
	s_setprio 1
	v_mfma_f32_16x16x32_bf16 v[60:63], v[158:161], v[180:183], 0
	v_mfma_f32_16x16x32_bf16 v[56:59], v[172:175], v[180:183], 0
	v_mfma_f32_16x16x32_bf16 v[52:55], v[158:161], v[188:191], 0
	v_mfma_f32_16x16x32_bf16 v[48:51], v[172:175], v[188:191], 0
	v_mfma_f32_16x16x32_bf16 v[44:47], v[158:161], v[196:199], 0
	v_mfma_f32_16x16x32_bf16 v[40:43], v[172:175], v[196:199], 0
	v_mfma_f32_16x16x32_bf16 v[36:39], v[158:161], v[204:207], 0
	v_mfma_f32_16x16x32_bf16 v[32:35], v[172:175], v[204:207], 0
	v_mfma_f32_16x16x32_bf16 v[60:63], v[162:165], v[184:187], v[60:63]
	v_mfma_f32_16x16x32_bf16 v[56:59], v[176:179], v[184:187], v[56:59]
	v_mfma_f32_16x16x32_bf16 v[52:55], v[162:165], v[192:195], v[52:55]
	v_mfma_f32_16x16x32_bf16 v[48:51], v[176:179], v[192:195], v[48:51]
	v_mfma_f32_16x16x32_bf16 v[44:47], v[162:165], v[200:203], v[44:47]
	v_mfma_f32_16x16x32_bf16 v[40:43], v[176:179], v[200:203], v[40:43]
	v_mfma_f32_16x16x32_bf16 v[36:39], v[162:165], v[208:211], v[36:39]
	v_mfma_f32_16x16x32_bf16 v[32:35], v[176:179], v[208:211], v[32:35]
	s_setprio 0
	s_add_i32 s79, s57, s7
	v_lshl_add_u64 v[144:145], s[14:15], 0, v[148:149]
	s_mov_b32 m0, s79
	s_barrier
	ds_read_b128 v[180:183], v171 offset:16384
	ds_read_b128 v[184:187], v171 offset:17408
	ds_read_b128 v[188:191], v171 offset:18432
	ds_read_b128 v[192:195], v171 offset:19456
	ds_read_b128 v[196:199], v171 offset:20480
	ds_read_b128 v[200:203], v171 offset:21504
	ds_read_b128 v[204:207], v171 offset:22528
	ds_read_b128 v[208:211], v171 offset:23552
	global_load_lds_dwordx4 v[144:145], off
	s_add_i32 m0, s79, 0x2000
	s_add_u32 s80, s14, 0x40000
	v_lshl_add_u64 v[166:167], s[14:15], 0, v[152:153]
	s_addc_u32 s81, s15, 0
	s_add_i32 s79, s58, s7
	global_load_lds_dwordx4 v[166:167], off
	v_lshl_add_u64 v[212:213], s[80:81], 0, v[148:149]
	s_mov_b32 m0, s79
	v_lshl_add_u64 v[214:215], s[46:47], 0, v[150:151]
	global_load_lds_dwordx4 v[212:213], off
	v_lshl_add_u64 v[212:213], s[80:81], 0, v[152:153]
	s_add_i32 m0, s79, 0x2000
	s_nop 0
	global_load_lds_dwordx4 v[212:213], off
	v_lshl_add_u64 v[212:213], s[46:47], 0, v[146:147]
	s_mov_b32 m0, s45
	s_nop 0
	global_load_lds_dwordx4 v[212:213], off
	s_mov_b32 m0, s50
	s_nop 0
	global_load_lds_dwordx4 v[214:215], off
	s_waitcnt vmcnt(8)
	s_waitcnt lgkmcnt(0)
	s_barrier
; #define G_STAGE(bufoff, gbase, voff) do { _Pragma("unroll") for (int _i = 0; _i < 2; ++_i) \
;         __builtin_amdgcn_global_load_lds((const unsigned*)((const char*)(gbase) + voff[_i]), (LAS unsigned*)(lds + (bufoff) + ldsw + _i * 8192), 16, 0, 0); } while (0)
; #define G_LDA(dst, b, h) do { _Pragma("unroll") for (int m = 0; m < 4; ++m) _Pragma("unroll") for (int k = 0; k < 2; ++k) dst[m][k] = *(const LAS bf16x8*)(lds + G_SA(b, h) + aoff + m * 2048 + k * 1024); } while (0)
; #define G_LDB(dst, b, h) do { _Pragma("unroll") for (int n = 0; n < 2; ++n) _Pragma("unroll") for (int k = 0; k < 2; ++k) dst[n][k] = *(const LAS bf16x8*)(lds + G_SB(b, h) + boff + n * 2048 + k * 1024); } while (0)
; #define G_MMA(ai, bj, At_, Bt_) do { __builtin_amdgcn_s_setprio(1); _Pragma("unroll") for (int m = 0; m < 4; ++m) _Pragma("unroll") for (int n = 0; n < 2; ++n) _Pragma("unroll") for (int k = 0; k < 2; ++k) \
;         acc[ai][bj][m][n] = __builtin_amdgcn_mfma_f32_16x16x32_bf16(Bt_[n][k], At_[m][k], acc[ai][bj][m][n], 0, 0, 0); __builtin_amdgcn_s_setprio(0); } while (0)
; #define WAIT_V(n) asm volatile("s_waitcnt vmcnt(" #n ")" ::: "memory")
; #define WAIT_L(n) asm volatile("s_waitcnt lgkmcnt(" #n ")" ::: "memory")
; #define BAR __builtin_amdgcn_s_barrier()
; #define SCHED __builtin_amdgcn_sched_barrier(0)
; template <class Get, class Epi>
; DI void gemm_loop(int ntiles, int ld, char* shm, const Get& get, const Epi& epi) {
;     ...
;             WAIT_V(8); WAIT_L(0); BAR; G_MMA(1, 0, At, B0); G_MMA(1, 1, At, B1); BAR; SCHED;
;             G_LDB(B0, 1, 0); G_LDB(B1, 1, 1); SCHED; G_LDA(At, 1, 0); G_STAGE(G_SA(0, 1), a2 + hstep, voffA);
;             WAIT_V(8); WAIT_L(0); BAR; G_MMA(0, 0, At, B0); G_MMA(0, 1, At, B1); BAR; SCHED;
	s_setprio 1
	s_waitcnt lgkmcnt(0)
	v_mfma_f32_16x16x32_bf16 v[92:95], v[128:131], v[180:183], 0
	v_mfma_f32_16x16x32_bf16 v[88:91], v[136:139], v[180:183], 0
	v_mfma_f32_16x16x32_bf16 v[84:87], v[128:131], v[188:191], 0
	v_mfma_f32_16x16x32_bf16 v[80:83], v[136:139], v[188:191], 0
	v_mfma_f32_16x16x32_bf16 v[76:79], v[128:131], v[196:199], 0
	v_mfma_f32_16x16x32_bf16 v[72:75], v[136:139], v[196:199], 0
	v_mfma_f32_16x16x32_bf16 v[68:71], v[128:131], v[204:207], 0
	v_mfma_f32_16x16x32_bf16 v[64:67], v[136:139], v[204:207], 0
	v_mfma_f32_16x16x32_bf16 v[92:95], v[132:135], v[184:187], v[92:95]
	v_mfma_f32_16x16x32_bf16 v[88:91], v[140:143], v[184:187], v[88:91]
	v_mfma_f32_16x16x32_bf16 v[84:87], v[132:135], v[192:195], v[84:87]
	v_mfma_f32_16x16x32_bf16 v[80:83], v[140:143], v[192:195], v[80:83]
	v_mfma_f32_16x16x32_bf16 v[76:79], v[132:135], v[200:203], v[76:79]
	v_mfma_f32_16x16x32_bf16 v[72:75], v[140:143], v[200:203], v[72:75]
	v_mfma_f32_16x16x32_bf16 v[68:71], v[132:135], v[208:211], v[68:71]
	v_mfma_f32_16x16x32_bf16 v[64:67], v[140:143], v[208:211], v[64:67]
	s_setprio 0
	s_setprio 1
	v_mfma_f32_16x16x32_bf16 v[28:31], v[158:161], v[180:183], 0
	v_mfma_f32_16x16x32_bf16 v[24:27], v[172:175], v[180:183], 0
	v_mfma_f32_16x16x32_bf16 v[20:23], v[158:161], v[188:191], 0
	v_mfma_f32_16x16x32_bf16 v[16:19], v[172:175], v[188:191], 0
	v_mfma_f32_16x16x32_bf16 v[12:15], v[158:161], v[196:199], 0
	v_mfma_f32_16x16x32_bf16 v[8:11], v[172:175], v[196:199], 0
	v_mfma_f32_16x16x32_bf16 v[4:7], v[158:161], v[204:207], 0
	v_mfma_f32_16x16x32_bf16 v[0:3], v[172:175], v[204:207], 0
	v_mfma_f32_16x16x32_bf16 v[28:31], v[162:165], v[184:187], v[28:31]
	v_mfma_f32_16x16x32_bf16 v[24:27], v[176:179], v[184:187], v[24:27]
	v_mfma_f32_16x16x32_bf16 v[20:23], v[162:165], v[192:195], v[20:23]
	v_mfma_f32_16x16x32_bf16 v[16:19], v[176:179], v[192:195], v[16:19]
	v_mfma_f32_16x16x32_bf16 v[12:15], v[162:165], v[200:203], v[12:15]
	v_mfma_f32_16x16x32_bf16 v[8:11], v[176:179], v[200:203], v[8:11]
	v_mfma_f32_16x16x32_bf16 v[4:7], v[162:165], v[208:211], v[4:7]
	v_mfma_f32_16x16x32_bf16 v[0:3], v[176:179], v[208:211], v[0:3]
	s_setprio 0
	s_add_i32 s79, 0, 0x18000
	s_add_i32 s80, 0, 0x1c000
	v_add_u32_e32 v140, s79, v168
	s_barrier
	v_add_u32_e32 v176, s80, v168
	ds_read_b128 v[128:131], v140
	ds_read_b128 v[132:135], v140 offset:1024
	ds_read_b128 v[136:139], v140 offset:2048
	ds_read_b128 v[140:143], v140 offset:3072
	ds_read_b128 v[158:161], v176
	ds_read_b128 v[162:165], v176 offset:1024
	ds_read_b128 v[172:175], v176 offset:2048
	ds_read_b128 v[176:179], v176 offset:3072
	s_add_u32 s46, s46, 0x40000
	s_addc_u32 s47, s47, 0
	s_mov_b32 m0, s51
	v_lshl_add_u64 v[216:217], s[46:47], 0, v[146:147]
	ds_read_b128 v[180:183], v171 offset:32768
	ds_read_b128 v[184:187], v171 offset:33792
	ds_read_b128 v[188:191], v171 offset:34816
	ds_read_b128 v[192:195], v171 offset:35840
	ds_read_b128 v[196:199], v171 offset:36864
	ds_read_b128 v[200:203], v171 offset:37888
	ds_read_b128 v[204:207], v171 offset:38912
	ds_read_b128 v[208:211], v171 offset:39936
	global_load_lds_dwordx4 v[216:217], off
	v_lshl_add_u64 v[216:217], s[46:47], 0, v[150:151]
	s_mov_b32 m0, s52
	s_nop 0
	global_load_lds_dwordx4 v[216:217], off
	s_waitcnt vmcnt(8)
	s_waitcnt lgkmcnt(0)
	s_barrier
	s_setprio 1
	s_waitcnt lgkmcnt(0)
	v_mfma_f32_16x16x32_bf16 v[124:127], v[128:131], v[180:183], v[124:127]
	v_mfma_f32_16x16x32_bf16 v[120:123], v[136:139], v[180:183], v[120:123]
	v_mfma_f32_16x16x32_bf16 v[116:119], v[128:131], v[188:191], v[116:119]
	v_mfma_f32_16x16x32_bf16 v[112:115], v[136:139], v[188:191], v[112:115]
	v_mfma_f32_16x16x32_bf16 v[108:111], v[128:131], v[196:199], v[108:111]
	v_mfma_f32_16x16x32_bf16 v[104:107], v[136:139], v[196:199], v[104:107]
	v_mfma_f32_16x16x32_bf16 v[100:103], v[128:131], v[204:207], v[100:103]
	v_mfma_f32_16x16x32_bf16 v[96:99], v[136:139], v[204:207], v[96:99]
	v_mfma_f32_16x16x32_bf16 v[124:127], v[132:135], v[184:187], v[124:127]
	v_mfma_f32_16x16x32_bf16 v[120:123], v[140:143], v[184:187], v[120:123]
	v_mfma_f32_16x16x32_bf16 v[116:119], v[132:135], v[192:195], v[116:119]
	v_mfma_f32_16x16x32_bf16 v[112:115], v[140:143], v[192:195], v[112:115]
	v_mfma_f32_16x16x32_bf16 v[108:111], v[132:135], v[200:203], v[108:111]
	v_mfma_f32_16x16x32_bf16 v[104:107], v[140:143], v[200:203], v[104:107]
	v_mfma_f32_16x16x32_bf16 v[100:103], v[132:135], v[208:211], v[100:103]
	v_mfma_f32_16x16x32_bf16 v[96:99], v[140:143], v[208:211], v[96:99]
	s_setprio 0
	s_setprio 1
	v_mfma_f32_16x16x32_bf16 v[60:63], v[158:161], v[180:183], v[60:63]
	v_mfma_f32_16x16x32_bf16 v[56:59], v[172:175], v[180:183], v[56:59]
	v_mfma_f32_16x16x32_bf16 v[52:55], v[158:161], v[188:191], v[52:55]
	v_mfma_f32_16x16x32_bf16 v[48:51], v[172:175], v[188:191], v[48:51]
	v_mfma_f32_16x16x32_bf16 v[44:47], v[158:161], v[196:199], v[44:47]
	v_mfma_f32_16x16x32_bf16 v[40:43], v[172:175], v[196:199], v[40:43]
	v_mfma_f32_16x16x32_bf16 v[36:39], v[158:161], v[204:207], v[36:39]
	v_mfma_f32_16x16x32_bf16 v[32:35], v[172:175], v[204:207], v[32:35]
	v_mfma_f32_16x16x32_bf16 v[60:63], v[162:165], v[184:187], v[60:63]
	v_mfma_f32_16x16x32_bf16 v[56:59], v[176:179], v[184:187], v[56:59]
	v_mfma_f32_16x16x32_bf16 v[52:55], v[162:165], v[192:195], v[52:55]
	v_mfma_f32_16x16x32_bf16 v[48:51], v[176:179], v[192:195], v[48:51]
	v_mfma_f32_16x16x32_bf16 v[44:47], v[162:165], v[200:203], v[44:47]
	v_mfma_f32_16x16x32_bf16 v[40:43], v[176:179], v[200:203], v[40:43]
	v_mfma_f32_16x16x32_bf16 v[36:39], v[162:165], v[208:211], v[36:39]
	v_mfma_f32_16x16x32_bf16 v[32:35], v[176:179], v[208:211], v[32:35]
	s_setprio 0
	s_add_i32 s46, s79, s7
	v_lshl_add_u64 v[144:145], v[144:145], 0, s[10:11]
	s_mov_b32 m0, s46
	s_barrier
; #define G_STAGE(bufoff, gbase, voff) do { _Pragma("unroll") for (int _i = 0; _i < 2; ++_i) \
;         __builtin_amdgcn_global_load_lds((const unsigned*)((const char*)(gbase) + voff[_i]), (LAS unsigned*)(lds + (bufoff) + ldsw + _i * 8192), 16, 0, 0); } while (0)
; #define G_LDA(dst, b, h) do { _Pragma("unroll") for (int m = 0; m < 4; ++m) _Pragma("unroll") for (int k = 0; k < 2; ++k) dst[m][k] = *(const LAS bf16x8*)(lds + G_SA(b, h) + aoff + m * 2048 + k * 1024); } while (0)
; #define G_LDB(dst, b, h) do { _Pragma("unroll") for (int n = 0; n < 2; ++n) _Pragma("unroll") for (int k = 0; k < 2; ++k) dst[n][k] = *(const LAS bf16x8*)(lds + G_SB(b, h) + boff + n * 2048 + k * 1024); } while (0)
; #define G_MMA(ai, bj, At_, Bt_) do { __builtin_amdgcn_s_setprio(1); _Pragma("unroll") for (int m = 0; m < 4; ++m) _Pragma("unroll") for (int n = 0; n < 2; ++n) _Pragma("unroll") for (int k = 0; k < 2; ++k) \
;         acc[ai][bj][m][n] = __builtin_amdgcn_mfma_f32_16x16x32_bf16(Bt_[n][k], At_[m][k], acc[ai][bj][m][n], 0, 0, 0); __builtin_amdgcn_s_setprio(0); } while (0)
; #define WAIT_V(n) asm volatile("s_waitcnt vmcnt(" #n ")" ::: "memory")
; #define BAR __builtin_amdgcn_s_barrier()
; template <class Get, class Epi>
; DI void gemm_loop(int ntiles, int ld, char* shm, const Get& get, const Epi& epi) {
;     ...
;             const char* a2 = last ? nA : cA + (size_t)(t + 2) * kstep; const char* b2 = last ? nB : cB + (size_t)(t + 2) * kstep;
;             const char* a3 = a2 + kstep; const char* b3 = b2 + kstep;
;             G_LDB(B0, 0, 0); G_LDB(B1, 0, 1); SCHED; G_LDA(At, 0, 0); G_STAGE(G_SA(1, 1), a1 + hstep, voffA);
;             WAIT_V(8); WAIT_L(0); BAR; G_MMA(0, 0, At, B0); G_MMA(0, 1, At, B1); BAR; SCHED;
;             G_LDA(At, 0, 1); G_STAGE(G_SB(0, 0), b2, voffB); G_STAGE(G_SB(0, 1), b2 + hstep, voffB); G_STAGE(G_SA(0, 0), a2, voffA);
;             WAIT_V(8); WAIT_L(0); BAR; G_MMA(1, 0, At, B0); G_MMA(1, 1, At, B1); BAR; SCHED;
;             G_LDB(B0, 1, 0); G_LDB(B1, 1, 1); SCHED; G_LDA(At, 1, 0); G_STAGE(G_SA(0, 1), a2 + hstep, voffA);
;             WAIT_V(8); WAIT_L(0); BAR; G_MMA(0, 0, At, B0); G_MMA(0, 1, At, B1); BAR; SCHED;
;             G_LDA(At, 1, 1); G_STAGE(G_SB(1, 0), b3, voffB); G_STAGE(G_SB(1, 1), b3 + hstep, voffB); G_STAGE(G_SA(1, 0), a3, voffA);
;             WAIT_V(8); WAIT_L(0); BAR; G_MMA(1, 0, At, B0); G_MMA(1, 1, At, B1); BAR; SCHED;
	ds_read_b128 v[180:183], v171 offset:49152
	ds_read_b128 v[184:187], v171 offset:50176
	ds_read_b128 v[188:191], v171 offset:51200
	ds_read_b128 v[192:195], v171 offset:52224
	ds_read_b128 v[196:199], v171 offset:53248
	ds_read_b128 v[200:203], v171 offset:54272
	ds_read_b128 v[204:207], v171 offset:55296
	ds_read_b128 v[208:211], v171 offset:56320
	global_load_lds_dwordx4 v[144:145], off
	s_add_i32 m0, s46, 0x2000
	s_add_u32 s14, s14, 0x40080
	v_lshl_add_u64 v[144:145], v[166:167], 0, s[10:11]
	s_addc_u32 s15, s15, 0
	s_add_i32 s46, s80, s7
	global_load_lds_dwordx4 v[144:145], off
	v_lshl_add_u64 v[144:145], s[14:15], 0, v[148:149]
	s_mov_b32 m0, s46
	s_nop 0
	global_load_lds_dwordx4 v[144:145], off
	v_lshl_add_u64 v[144:145], s[14:15], 0, v[152:153]
	s_add_i32 m0, s46, 0x2000
	s_nop 0
	global_load_lds_dwordx4 v[144:145], off
	v_lshl_add_u64 v[144:145], v[212:213], 0, s[10:11]
	s_mov_b32 m0, s55
	s_nop 0
	global_load_lds_dwordx4 v[144:145], off
	v_lshl_add_u64 v[144:145], v[214:215], 0, s[10:11]
	s_mov_b32 m0, s56
	s_nop 0
	global_load_lds_dwordx4 v[144:145], off
	s_waitcnt vmcnt(8)
	s_waitcnt lgkmcnt(0)
	s_barrier
	s_setprio 1
	s_waitcnt lgkmcnt(0)
	v_mfma_f32_16x16x32_bf16 v[92:95], v[128:131], v[180:183], v[92:95]
	v_mfma_f32_16x16x32_bf16 v[88:91], v[136:139], v[180:183], v[88:91]
	v_mfma_f32_16x16x32_bf16 v[84:87], v[128:131], v[188:191], v[84:87]
	v_mfma_f32_16x16x32_bf16 v[80:83], v[136:139], v[188:191], v[80:83]
	v_mfma_f32_16x16x32_bf16 v[76:79], v[128:131], v[196:199], v[76:79]
	v_mfma_f32_16x16x32_bf16 v[72:75], v[136:139], v[196:199], v[72:75]
	v_mfma_f32_16x16x32_bf16 v[68:71], v[128:131], v[204:207], v[68:71]
	v_mfma_f32_16x16x32_bf16 v[64:67], v[136:139], v[204:207], v[64:67]
	v_mfma_f32_16x16x32_bf16 v[92:95], v[132:135], v[184:187], v[92:95]
	v_mfma_f32_16x16x32_bf16 v[88:91], v[140:143], v[184:187], v[88:91]
	v_mfma_f32_16x16x32_bf16 v[84:87], v[132:135], v[192:195], v[84:87]
	v_mfma_f32_16x16x32_bf16 v[80:83], v[140:143], v[192:195], v[80:83]
	v_mfma_f32_16x16x32_bf16 v[76:79], v[132:135], v[200:203], v[76:79]
	v_mfma_f32_16x16x32_bf16 v[72:75], v[140:143], v[200:203], v[72:75]
	v_mfma_f32_16x16x32_bf16 v[68:71], v[132:135], v[208:211], v[68:71]
	v_mfma_f32_16x16x32_bf16 v[64:67], v[140:143], v[208:211], v[64:67]
	s_setprio 0
	s_setprio 1
	v_mfma_f32_16x16x32_bf16 v[28:31], v[158:161], v[180:183], v[28:31]
	v_mfma_f32_16x16x32_bf16 v[24:27], v[172:175], v[180:183], v[24:27]
	v_mfma_f32_16x16x32_bf16 v[20:23], v[158:161], v[188:191], v[20:23]
	v_mfma_f32_16x16x32_bf16 v[16:19], v[172:175], v[188:191], v[16:19]
	v_mfma_f32_16x16x32_bf16 v[12:15], v[158:161], v[196:199], v[12:15]
	v_mfma_f32_16x16x32_bf16 v[8:11], v[172:175], v[196:199], v[8:11]
	v_mfma_f32_16x16x32_bf16 v[4:7], v[158:161], v[204:207], v[4:7]
	v_mfma_f32_16x16x32_bf16 v[0:3], v[172:175], v[204:207], v[0:3]
	v_mfma_f32_16x16x32_bf16 v[28:31], v[162:165], v[184:187], v[28:31]
	v_mfma_f32_16x16x32_bf16 v[24:27], v[176:179], v[184:187], v[24:27]
	v_mfma_f32_16x16x32_bf16 v[20:23], v[162:165], v[192:195], v[20:23]
	v_mfma_f32_16x16x32_bf16 v[16:19], v[176:179], v[192:195], v[16:19]
	v_mfma_f32_16x16x32_bf16 v[12:15], v[162:165], v[200:203], v[12:15]
	v_mfma_f32_16x16x32_bf16 v[8:11], v[176:179], v[200:203], v[8:11]
	v_mfma_f32_16x16x32_bf16 v[4:7], v[162:165], v[208:211], v[4:7]
	v_mfma_f32_16x16x32_bf16 v[0:3], v[176:179], v[208:211], v[0:3]
	s_setprio 0
	s_add_u32 s48, s48, 0x100
	s_addc_u32 s49, s49, 0
	s_add_u32 s76, s76, 0x100
	s_addc_u32 s77, s77, 0
	s_cmp_ge_u32 s78, s74
	s_mov_b32 s14, s78
	s_barrier
	s_cbranch_scc0 .LBB0_1463
	s_branch .Lpost_1463
.LBB0_1463:
	ds_read_b128 v[128:131], v169
	ds_read_b128 v[132:135], v169 offset:1024
	ds_read_b128 v[136:139], v169 offset:2048
	ds_read_b128 v[140:143], v169 offset:3072
	ds_read_b128 v[158:161], v170
	ds_read_b128 v[162:165], v170 offset:1024
	ds_read_b128 v[172:175], v170 offset:2048
	ds_read_b128 v[176:179], v170 offset:3072
	s_add_i32 s78, s14, 2
	s_add_u32 s15, s48, 0xfffc0080
	s_addc_u32 s46, s49, -1
	s_cmp_eq_u32 s75, s14
	s_cselect_b32 s14, s73, s76
	s_cselect_b32 s47, s3, s46
	s_cselect_b32 s46, s37, s15
	s_cselect_b32 s15, s39, s77
	v_lshl_add_u64 v[144:145], s[48:49], 0, v[154:155]
	s_add_i32 m0, s45, 0xc000
	ds_read_b128 v[180:183], v171
	ds_read_b128 v[184:187], v171 offset:1024
	ds_read_b128 v[188:191], v171 offset:2048
	ds_read_b128 v[192:195], v171 offset:3072
	ds_read_b128 v[196:199], v171 offset:4096
	ds_read_b128 v[200:203], v171 offset:5120
	ds_read_b128 v[204:207], v171 offset:6144
	ds_read_b128 v[208:211], v171 offset:7168
	global_load_lds_dwordx4 v[144:145], off
	v_lshl_add_u64 v[144:145], s[48:49], 0, v[156:157]
	s_add_i32 m0, s45, 0xe000
	s_nop 0
	global_load_lds_dwordx4 v[144:145], off
	s_waitcnt vmcnt(8)
	s_waitcnt lgkmcnt(0)
	s_barrier
; #define G_STAGE(bufoff, gbase, voff) do { _Pragma("unroll") for (int _i = 0; _i < 2; ++_i) \
;         __builtin_amdgcn_global_load_lds((const unsigned*)((const char*)(gbase) + voff[_i]), (LAS unsigned*)(lds + (bufoff) + ldsw + _i * 8192), 16, 0, 0); } while (0)
; #define G_LDA(dst, b, h) do { _Pragma("unroll") for (int m = 0; m < 4; ++m) _Pragma("unroll") for (int k = 0; k < 2; ++k) dst[m][k] = *(const LAS bf16x8*)(lds + G_SA(b, h) + aoff + m * 2048 + k * 1024); } while (0)
; #define G_LDB(dst, b, h) do { _Pragma("unroll") for (int n = 0; n < 2; ++n) _Pragma("unroll") for (int k = 0; k < 2; ++k) dst[n][k] = *(const LAS bf16x8*)(lds + G_SB(b, h) + boff + n * 2048 + k * 1024); } while (0)
; #define G_MMA(ai, bj, At_, Bt_) do { __builtin_amdgcn_s_setprio(1); _Pragma("unroll") for (int m = 0; m < 4; ++m) _Pragma("unroll") for (int n = 0; n < 2; ++n) _Pragma("unroll") for (int k = 0; k < 2; ++k) \
;         acc[ai][bj][m][n] = __builtin_amdgcn_mfma_f32_16x16x32_bf16(Bt_[n][k], At_[m][k], acc[ai][bj][m][n], 0, 0, 0); __builtin_amdgcn_s_setprio(0); } while (0)
; #define WAIT_V(n) asm volatile("s_waitcnt vmcnt(" #n ")" ::: "memory")
; #define WAIT_L(n) asm volatile("s_waitcnt lgkmcnt(" #n ")" ::: "memory")
; #define BAR __builtin_amdgcn_s_barrier()
; #define SCHED __builtin_amdgcn_sched_barrier(0)
; template <class Get, class Epi>
; DI void gemm_loop(int ntiles, int ld, char* shm, const Get& get, const Epi& epi) {
;     ...
;             WAIT_V(8); WAIT_L(0); BAR; G_MMA(0, 0, At, B0); G_MMA(0, 1, At, B1); BAR; SCHED;
;             G_LDA(At, 0, 1); G_STAGE(G_SB(0, 0), b2, voffB); G_STAGE(G_SB(0, 1), b2 + hstep, voffB); G_STAGE(G_SA(0, 0), a2, voffA);
;             WAIT_V(8); WAIT_L(0); BAR; G_MMA(1, 0, At, B0); G_MMA(1, 1, At, B1); BAR; SCHED;
;             G_LDB(B0, 1, 0); G_LDB(B1, 1, 1); SCHED; G_LDA(At, 1, 0); G_STAGE(G_SA(0, 1), a2 + hstep, voffA);
	s_setprio 1
	s_waitcnt lgkmcnt(0)
	v_mfma_f32_16x16x32_bf16 v[124:127], v[128:131], v[180:183], v[124:127]
	v_mfma_f32_16x16x32_bf16 v[120:123], v[136:139], v[180:183], v[120:123]
	v_mfma_f32_16x16x32_bf16 v[116:119], v[128:131], v[188:191], v[116:119]
	v_mfma_f32_16x16x32_bf16 v[112:115], v[136:139], v[188:191], v[112:115]
	v_mfma_f32_16x16x32_bf16 v[108:111], v[128:131], v[196:199], v[108:111]
	v_mfma_f32_16x16x32_bf16 v[104:107], v[136:139], v[196:199], v[104:107]
	v_mfma_f32_16x16x32_bf16 v[100:103], v[128:131], v[204:207], v[100:103]
	v_mfma_f32_16x16x32_bf16 v[96:99], v[136:139], v[204:207], v[96:99]
	v_mfma_f32_16x16x32_bf16 v[124:127], v[132:135], v[184:187], v[124:127]
	v_mfma_f32_16x16x32_bf16 v[120:123], v[140:143], v[184:187], v[120:123]
	v_mfma_f32_16x16x32_bf16 v[116:119], v[132:135], v[192:195], v[116:119]
	v_mfma_f32_16x16x32_bf16 v[112:115], v[140:143], v[192:195], v[112:115]
	v_mfma_f32_16x16x32_bf16 v[108:111], v[132:135], v[200:203], v[108:111]
	v_mfma_f32_16x16x32_bf16 v[104:107], v[140:143], v[200:203], v[104:107]
	v_mfma_f32_16x16x32_bf16 v[100:103], v[132:135], v[208:211], v[100:103]
	v_mfma_f32_16x16x32_bf16 v[96:99], v[140:143], v[208:211], v[96:99]
	s_setprio 0
	s_setprio 1
	v_mfma_f32_16x16x32_bf16 v[60:63], v[158:161], v[180:183], v[60:63]
	v_mfma_f32_16x16x32_bf16 v[56:59], v[172:175], v[180:183], v[56:59]
	v_mfma_f32_16x16x32_bf16 v[52:55], v[158:161], v[188:191], v[52:55]
	v_mfma_f32_16x16x32_bf16 v[48:51], v[172:175], v[188:191], v[48:51]
	v_mfma_f32_16x16x32_bf16 v[44:47], v[158:161], v[196:199], v[44:47]
	v_mfma_f32_16x16x32_bf16 v[40:43], v[172:175], v[196:199], v[40:43]
	v_mfma_f32_16x16x32_bf16 v[36:39], v[158:161], v[204:207], v[36:39]
	v_mfma_f32_16x16x32_bf16 v[32:35], v[172:175], v[204:207], v[32:35]
	v_mfma_f32_16x16x32_bf16 v[60:63], v[162:165], v[184:187], v[60:63]
	v_mfma_f32_16x16x32_bf16 v[56:59], v[176:179], v[184:187], v[56:59]
	v_mfma_f32_16x16x32_bf16 v[52:55], v[162:165], v[192:195], v[52:55]
	v_mfma_f32_16x16x32_bf16 v[48:51], v[176:179], v[192:195], v[48:51]
	v_mfma_f32_16x16x32_bf16 v[44:47], v[162:165], v[200:203], v[44:47]
	v_mfma_f32_16x16x32_bf16 v[40:43], v[176:179], v[200:203], v[40:43]
	v_mfma_f32_16x16x32_bf16 v[36:39], v[162:165], v[208:211], v[36:39]
	v_mfma_f32_16x16x32_bf16 v[32:35], v[176:179], v[208:211], v[32:35]
	s_setprio 0
	s_add_i32 s79, s57, s7
	v_lshl_add_u64 v[144:145], s[14:15], 0, v[148:149]
	s_mov_b32 m0, s79
	s_barrier
	ds_read_b128 v[180:183], v171 offset:16384
	ds_read_b128 v[184:187], v171 offset:17408
	ds_read_b128 v[188:191], v171 offset:18432
	ds_read_b128 v[192:195], v171 offset:19456
	ds_read_b128 v[196:199], v171 offset:20480
	ds_read_b128 v[200:203], v171 offset:21504
	ds_read_b128 v[204:207], v171 offset:22528
	ds_read_b128 v[208:211], v171 offset:23552
	global_load_lds_dwordx4 v[144:145], off
	s_add_i32 m0, s79, 0x2000
	s_add_u32 s80, s14, 0x40000
	v_lshl_add_u64 v[166:167], s[14:15], 0, v[152:153]
	s_addc_u32 s81, s15, 0
	s_add_i32 s79, s58, s7
	global_load_lds_dwordx4 v[166:167], off
	v_lshl_add_u64 v[212:213], s[80:81], 0, v[148:149]
	s_mov_b32 m0, s79
	v_lshl_add_u64 v[214:215], s[46:47], 0, v[150:151]
	global_load_lds_dwordx4 v[212:213], off
	v_lshl_add_u64 v[212:213], s[80:81], 0, v[152:153]
	s_add_i32 m0, s79, 0x2000
	s_nop 0
	global_load_lds_dwordx4 v[212:213], off
	v_lshl_add_u64 v[212:213], s[46:47], 0, v[146:147]
	s_mov_b32 m0, s45
	s_nop 0
	global_load_lds_dwordx4 v[212:213], off
	s_mov_b32 m0, s50
	s_nop 0
	global_load_lds_dwordx4 v[214:215], off
	s_waitcnt vmcnt(8)
	s_waitcnt lgkmcnt(0)
	s_barrier
	s_setprio 1
	s_waitcnt lgkmcnt(0)
	v_mfma_f32_16x16x32_bf16 v[92:95], v[128:131], v[180:183], v[92:95]
	v_mfma_f32_16x16x32_bf16 v[88:91], v[136:139], v[180:183], v[88:91]
	v_mfma_f32_16x16x32_bf16 v[84:87], v[128:131], v[188:191], v[84:87]
	v_mfma_f32_16x16x32_bf16 v[80:83], v[136:139], v[188:191], v[80:83]
	v_mfma_f32_16x16x32_bf16 v[76:79], v[128:131], v[196:199], v[76:79]
	v_mfma_f32_16x16x32_bf16 v[72:75], v[136:139], v[196:199], v[72:75]
	v_mfma_f32_16x16x32_bf16 v[68:71], v[128:131], v[204:207], v[68:71]
	v_mfma_f32_16x16x32_bf16 v[64:67], v[136:139], v[204:207], v[64:67]
	v_mfma_f32_16x16x32_bf16 v[92:95], v[132:135], v[184:187], v[92:95]
	v_mfma_f32_16x16x32_bf16 v[88:91], v[140:143], v[184:187], v[88:91]
	v_mfma_f32_16x16x32_bf16 v[84:87], v[132:135], v[192:195], v[84:87]
	v_mfma_f32_16x16x32_bf16 v[80:83], v[140:143], v[192:195], v[80:83]
	v_mfma_f32_16x16x32_bf16 v[76:79], v[132:135], v[200:203], v[76:79]
	v_mfma_f32_16x16x32_bf16 v[72:75], v[140:143], v[200:203], v[72:75]
	v_mfma_f32_16x16x32_bf16 v[68:71], v[132:135], v[208:211], v[68:71]
	v_mfma_f32_16x16x32_bf16 v[64:67], v[140:143], v[208:211], v[64:67]
	s_setprio 0
	s_setprio 1
	v_mfma_f32_16x16x32_bf16 v[28:31], v[158:161], v[180:183], v[28:31]
	v_mfma_f32_16x16x32_bf16 v[24:27], v[172:175], v[180:183], v[24:27]
	v_mfma_f32_16x16x32_bf16 v[20:23], v[158:161], v[188:191], v[20:23]
	v_mfma_f32_16x16x32_bf16 v[16:19], v[172:175], v[188:191], v[16:19]
	v_mfma_f32_16x16x32_bf16 v[12:15], v[158:161], v[196:199], v[12:15]
	v_mfma_f32_16x16x32_bf16 v[8:11], v[172:175], v[196:199], v[8:11]
	v_mfma_f32_16x16x32_bf16 v[4:7], v[158:161], v[204:207], v[4:7]
	v_mfma_f32_16x16x32_bf16 v[0:3], v[172:175], v[204:207], v[0:3]
	v_mfma_f32_16x16x32_bf16 v[28:31], v[162:165], v[184:187], v[28:31]
	v_mfma_f32_16x16x32_bf16 v[24:27], v[176:179], v[184:187], v[24:27]
	v_mfma_f32_16x16x32_bf16 v[20:23], v[162:165], v[192:195], v[20:23]
	v_mfma_f32_16x16x32_bf16 v[16:19], v[176:179], v[192:195], v[16:19]
	v_mfma_f32_16x16x32_bf16 v[12:15], v[162:165], v[200:203], v[12:15]
	v_mfma_f32_16x16x32_bf16 v[8:11], v[176:179], v[200:203], v[8:11]
	v_mfma_f32_16x16x32_bf16 v[4:7], v[162:165], v[208:211], v[4:7]
	v_mfma_f32_16x16x32_bf16 v[0:3], v[176:179], v[208:211], v[0:3]
	s_setprio 0
	s_add_i32 s79, 0, 0x18000
	s_add_i32 s80, 0, 0x1c000
	v_add_u32_e32 v140, s79, v168
	s_barrier
; #define G_STAGE(bufoff, gbase, voff) do { _Pragma("unroll") for (int _i = 0; _i < 2; ++_i) \
;         __builtin_amdgcn_global_load_lds((const unsigned*)((const char*)(gbase) + voff[_i]), (LAS unsigned*)(lds + (bufoff) + ldsw + _i * 8192), 16, 0, 0); } while (0)
; #define G_LDA(dst, b, h) do { _Pragma("unroll") for (int m = 0; m < 4; ++m) _Pragma("unroll") for (int k = 0; k < 2; ++k) dst[m][k] = *(const LAS bf16x8*)(lds + G_SA(b, h) + aoff + m * 2048 + k * 1024); } while (0)
; #define G_LDB(dst, b, h) do { _Pragma("unroll") for (int n = 0; n < 2; ++n) _Pragma("unroll") for (int k = 0; k < 2; ++k) dst[n][k] = *(const LAS bf16x8*)(lds + G_SB(b, h) + boff + n * 2048 + k * 1024); } while (0)
; #define G_MMA(ai, bj, At_, Bt_) do { __builtin_amdgcn_s_setprio(1); _Pragma("unroll") for (int m = 0; m < 4; ++m) _Pragma("unroll") for (int n = 0; n < 2; ++n) _Pragma("unroll") for (int k = 0; k < 2; ++k) \
;         acc[ai][bj][m][n] = __builtin_amdgcn_mfma_f32_16x16x32_bf16(Bt_[n][k], At_[m][k], acc[ai][bj][m][n], 0, 0, 0); __builtin_amdgcn_s_setprio(0); } while (0)
; #define WAIT_V(n) asm volatile("s_waitcnt vmcnt(" #n ")" ::: "memory")
; #define WAIT_L(n) asm volatile("s_waitcnt lgkmcnt(" #n ")" ::: "memory")
; #define BAR __builtin_amdgcn_s_barrier()
; #define SCHED __builtin_amdgcn_sched_barrier(0)
; template <class Get, class Epi>
; DI void gemm_loop(int ntiles, int ld, char* shm, const Get& get, const Epi& epi) {
;     ...
;             G_LDB(B0, 1, 0); G_LDB(B1, 1, 1); SCHED; G_LDA(At, 1, 0); G_STAGE(G_SA(0, 1), a2 + hstep, voffA);
;             WAIT_V(8); WAIT_L(0); BAR; G_MMA(0, 0, At, B0); G_MMA(0, 1, At, B1); BAR; SCHED;
	v_add_u32_e32 v176, s80, v168
	ds_read_b128 v[128:131], v140
	ds_read_b128 v[132:135], v140 offset:1024
	ds_read_b128 v[136:139], v140 offset:2048
	ds_read_b128 v[140:143], v140 offset:3072
	ds_read_b128 v[158:161], v176
	ds_read_b128 v[162:165], v176 offset:1024
	ds_read_b128 v[172:175], v176 offset:2048
	ds_read_b128 v[176:179], v176 offset:3072
	s_add_u32 s46, s46, 0x40000
	s_addc_u32 s47, s47, 0
	s_mov_b32 m0, s51
	v_lshl_add_u64 v[216:217], s[46:47], 0, v[146:147]
	ds_read_b128 v[180:183], v171 offset:32768
	ds_read_b128 v[184:187], v171 offset:33792
	ds_read_b128 v[188:191], v171 offset:34816
	ds_read_b128 v[192:195], v171 offset:35840
	ds_read_b128 v[196:199], v171 offset:36864
	ds_read_b128 v[200:203], v171 offset:37888
	ds_read_b128 v[204:207], v171 offset:38912
	ds_read_b128 v[208:211], v171 offset:39936
	global_load_lds_dwordx4 v[216:217], off
	v_lshl_add_u64 v[216:217], s[46:47], 0, v[150:151]
	s_mov_b32 m0, s52
	s_nop 0
	global_load_lds_dwordx4 v[216:217], off
	s_waitcnt vmcnt(8)
	s_waitcnt lgkmcnt(0)
	s_barrier
	s_setprio 1
	s_waitcnt lgkmcnt(0)
	v_mfma_f32_16x16x32_bf16 v[124:127], v[128:131], v[180:183], v[124:127]
	v_mfma_f32_16x16x32_bf16 v[120:123], v[136:139], v[180:183], v[120:123]
	v_mfma_f32_16x16x32_bf16 v[116:119], v[128:131], v[188:191], v[116:119]
	v_mfma_f32_16x16x32_bf16 v[112:115], v[136:139], v[188:191], v[112:115]
	v_mfma_f32_16x16x32_bf16 v[108:111], v[128:131], v[196:199], v[108:111]
	v_mfma_f32_16x16x32_bf16 v[104:107], v[136:139], v[196:199], v[104:107]
	v_mfma_f32_16x16x32_bf16 v[100:103], v[128:131], v[204:207], v[100:103]
	v_mfma_f32_16x16x32_bf16 v[96:99], v[136:139], v[204:207], v[96:99]
	v_mfma_f32_16x16x32_bf16 v[124:127], v[132:135], v[184:187], v[124:127]
	v_mfma_f32_16x16x32_bf16 v[120:123], v[140:143], v[184:187], v[120:123]
	v_mfma_f32_16x16x32_bf16 v[116:119], v[132:135], v[192:195], v[116:119]
	v_mfma_f32_16x16x32_bf16 v[112:115], v[140:143], v[192:195], v[112:115]
	v_mfma_f32_16x16x32_bf16 v[108:111], v[132:135], v[200:203], v[108:111]
	v_mfma_f32_16x16x32_bf16 v[104:107], v[140:143], v[200:203], v[104:107]
	v_mfma_f32_16x16x32_bf16 v[100:103], v[132:135], v[208:211], v[100:103]
	v_mfma_f32_16x16x32_bf16 v[96:99], v[140:143], v[208:211], v[96:99]
	s_setprio 0
	s_setprio 1
	v_mfma_f32_16x16x32_bf16 v[60:63], v[158:161], v[180:183], v[60:63]
	v_mfma_f32_16x16x32_bf16 v[56:59], v[172:175], v[180:183], v[56:59]
	v_mfma_f32_16x16x32_bf16 v[52:55], v[158:161], v[188:191], v[52:55]
	v_mfma_f32_16x16x32_bf16 v[48:51], v[172:175], v[188:191], v[48:51]
	v_mfma_f32_16x16x32_bf16 v[44:47], v[158:161], v[196:199], v[44:47]
	v_mfma_f32_16x16x32_bf16 v[40:43], v[172:175], v[196:199], v[40:43]
	v_mfma_f32_16x16x32_bf16 v[36:39], v[158:161], v[204:207], v[36:39]
	v_mfma_f32_16x16x32_bf16 v[32:35], v[172:175], v[204:207], v[32:35]
	v_mfma_f32_16x16x32_bf16 v[60:63], v[162:165], v[184:187], v[60:63]
	v_mfma_f32_16x16x32_bf16 v[56:59], v[176:179], v[184:187], v[56:59]
	v_mfma_f32_16x16x32_bf16 v[52:55], v[162:165], v[192:195], v[52:55]
	v_mfma_f32_16x16x32_bf16 v[48:51], v[176:179], v[192:195], v[48:51]
	v_mfma_f32_16x16x32_bf16 v[44:47], v[162:165], v[200:203], v[44:47]
	v_mfma_f32_16x16x32_bf16 v[40:43], v[176:179], v[200:203], v[40:43]
	v_mfma_f32_16x16x32_bf16 v[36:39], v[162:165], v[208:211], v[36:39]
	v_mfma_f32_16x16x32_bf16 v[32:35], v[176:179], v[208:211], v[32:35]
	s_setprio 0
	s_add_i32 s46, s79, s7
	v_lshl_add_u64 v[144:145], v[144:145], 0, s[10:11]
	s_mov_b32 m0, s46
	s_barrier
; #define G_STAGE(bufoff, gbase, voff) do { _Pragma("unroll") for (int _i = 0; _i < 2; ++_i) \
;         __builtin_amdgcn_global_load_lds((const unsigned*)((const char*)(gbase) + voff[_i]), (LAS unsigned*)(lds + (bufoff) + ldsw + _i * 8192), 16, 0, 0); } while (0)
; #define G_LDA(dst, b, h) do { _Pragma("unroll") for (int m = 0; m < 4; ++m) _Pragma("unroll") for (int k = 0; k < 2; ++k) dst[m][k] = *(const LAS bf16x8*)(lds + G_SA(b, h) + aoff + m * 2048 + k * 1024); } while (0)
; #define G_MMA(ai, bj, At_, Bt_) do { __builtin_amdgcn_s_setprio(1); _Pragma("unroll") for (int m = 0; m < 4; ++m) _Pragma("unroll") for (int n = 0; n < 2; ++n) _Pragma("unroll") for (int k = 0; k < 2; ++k) \
;         acc[ai][bj][m][n] = __builtin_amdgcn_mfma_f32_16x16x32_bf16(Bt_[n][k], At_[m][k], acc[ai][bj][m][n], 0, 0, 0); __builtin_amdgcn_s_setprio(0); } while (0)
; #define WAIT_V(n) asm volatile("s_waitcnt vmcnt(" #n ")" ::: "memory")
; #define WAIT_L(n) asm volatile("s_waitcnt lgkmcnt(" #n ")" ::: "memory")
; #define BAR __builtin_amdgcn_s_barrier()
; #define SCHED __builtin_amdgcn_sched_barrier(0)
; template <class Get, class Epi>
; DI void gemm_loop(int ntiles, int ld, char* shm, const Get& get, const Epi& epi) {
;     ...
;             G_LDA(At, 1, 1); G_STAGE(G_SB(1, 0), b3, voffB); G_STAGE(G_SB(1, 1), b3 + hstep, voffB); G_STAGE(G_SA(1, 0), a3, voffA);
;             WAIT_V(8); WAIT_L(0); BAR; G_MMA(1, 0, At, B0); G_MMA(1, 1, At, B1); BAR; SCHED;
;         }
	ds_read_b128 v[180:183], v171 offset:49152
	ds_read_b128 v[184:187], v171 offset:50176
	ds_read_b128 v[188:191], v171 offset:51200
	ds_read_b128 v[192:195], v171 offset:52224
	ds_read_b128 v[196:199], v171 offset:53248
	ds_read_b128 v[200:203], v171 offset:54272
	ds_read_b128 v[204:207], v171 offset:55296
	ds_read_b128 v[208:211], v171 offset:56320
	global_load_lds_dwordx4 v[144:145], off
	s_add_i32 m0, s46, 0x2000
	s_add_u32 s14, s14, 0x40080
	v_lshl_add_u64 v[144:145], v[166:167], 0, s[10:11]
	s_addc_u32 s15, s15, 0
	s_add_i32 s46, s80, s7
	global_load_lds_dwordx4 v[144:145], off
	v_lshl_add_u64 v[144:145], s[14:15], 0, v[148:149]
	s_mov_b32 m0, s46
	s_nop 0
	global_load_lds_dwordx4 v[144:145], off
	v_lshl_add_u64 v[144:145], s[14:15], 0, v[152:153]
	s_add_i32 m0, s46, 0x2000
	s_nop 0
	global_load_lds_dwordx4 v[144:145], off
	v_lshl_add_u64 v[144:145], v[212:213], 0, s[10:11]
	s_mov_b32 m0, s55
	s_nop 0
	global_load_lds_dwordx4 v[144:145], off
	v_lshl_add_u64 v[144:145], v[214:215], 0, s[10:11]
	s_mov_b32 m0, s56
	s_nop 0
	global_load_lds_dwordx4 v[144:145], off
	s_waitcnt vmcnt(8)
	s_waitcnt lgkmcnt(0)
	s_barrier
	s_setprio 1
	s_waitcnt lgkmcnt(0)
	v_mfma_f32_16x16x32_bf16 v[92:95], v[128:131], v[180:183], v[92:95]
	v_mfma_f32_16x16x32_bf16 v[88:91], v[136:139], v[180:183], v[88:91]
	v_mfma_f32_16x16x32_bf16 v[84:87], v[128:131], v[188:191], v[84:87]
	v_mfma_f32_16x16x32_bf16 v[80:83], v[136:139], v[188:191], v[80:83]
	v_mfma_f32_16x16x32_bf16 v[76:79], v[128:131], v[196:199], v[76:79]
	v_mfma_f32_16x16x32_bf16 v[72:75], v[136:139], v[196:199], v[72:75]
	v_mfma_f32_16x16x32_bf16 v[68:71], v[128:131], v[204:207], v[68:71]
	v_mfma_f32_16x16x32_bf16 v[64:67], v[136:139], v[204:207], v[64:67]
	v_mfma_f32_16x16x32_bf16 v[92:95], v[132:135], v[184:187], v[92:95]
	v_mfma_f32_16x16x32_bf16 v[88:91], v[140:143], v[184:187], v[88:91]
	v_mfma_f32_16x16x32_bf16 v[84:87], v[132:135], v[192:195], v[84:87]
	v_mfma_f32_16x16x32_bf16 v[80:83], v[140:143], v[192:195], v[80:83]
	v_mfma_f32_16x16x32_bf16 v[76:79], v[132:135], v[200:203], v[76:79]
	v_mfma_f32_16x16x32_bf16 v[72:75], v[140:143], v[200:203], v[72:75]
	v_mfma_f32_16x16x32_bf16 v[68:71], v[132:135], v[208:211], v[68:71]
	v_mfma_f32_16x16x32_bf16 v[64:67], v[140:143], v[208:211], v[64:67]
	s_setprio 0
	s_setprio 1
	v_mfma_f32_16x16x32_bf16 v[28:31], v[158:161], v[180:183], v[28:31]
	v_mfma_f32_16x16x32_bf16 v[24:27], v[172:175], v[180:183], v[24:27]
	v_mfma_f32_16x16x32_bf16 v[20:23], v[158:161], v[188:191], v[20:23]
	v_mfma_f32_16x16x32_bf16 v[16:19], v[172:175], v[188:191], v[16:19]
	v_mfma_f32_16x16x32_bf16 v[12:15], v[158:161], v[196:199], v[12:15]
	v_mfma_f32_16x16x32_bf16 v[8:11], v[172:175], v[196:199], v[8:11]
	v_mfma_f32_16x16x32_bf16 v[4:7], v[158:161], v[204:207], v[4:7]
	v_mfma_f32_16x16x32_bf16 v[0:3], v[172:175], v[204:207], v[0:3]
	v_mfma_f32_16x16x32_bf16 v[28:31], v[162:165], v[184:187], v[28:31]
	v_mfma_f32_16x16x32_bf16 v[24:27], v[176:179], v[184:187], v[24:27]
	v_mfma_f32_16x16x32_bf16 v[20:23], v[162:165], v[192:195], v[20:23]
	v_mfma_f32_16x16x32_bf16 v[16:19], v[176:179], v[192:195], v[16:19]
	v_mfma_f32_16x16x32_bf16 v[12:15], v[162:165], v[200:203], v[12:15]
	v_mfma_f32_16x16x32_bf16 v[8:11], v[176:179], v[200:203], v[8:11]
	v_mfma_f32_16x16x32_bf16 v[4:7], v[162:165], v[208:211], v[4:7]
	v_mfma_f32_16x16x32_bf16 v[0:3], v[176:179], v[208:211], v[0:3]
	s_setprio 0
	s_add_u32 s48, s48, 0x100
	s_addc_u32 s49, s49, 0
	s_add_u32 s76, s76, 0x100
	s_addc_u32 s77, s77, 0
	s_cmp_ge_u32 s78, s74
	s_mov_b32 s14, s78
	s_barrier
	s_cbranch_scc0 .LBB0_1463

; #define G_STAGE(bufoff, gbase, voff) do { _Pragma("unroll") for (int _i = 0; _i < 2; ++_i) \
;         __builtin_amdgcn_global_load_lds((const unsigned*)((const char*)(gbase) + voff[_i]), (LAS unsigned*)(lds + (bufoff) + ldsw + _i * 8192), 16, 0, 0); } while (0)
; #define G_LDA(dst, b, h) do { _Pragma("unroll") for (int m = 0; m < 4; ++m) _Pragma("unroll") for (int k = 0; k < 2; ++k) dst[m][k] = *(const LAS bf16x8*)(lds + G_SA(b, h) + aoff + m * 2048 + k * 1024); } while (0)
; #define G_LDB(dst, b, h) do { _Pragma("unroll") for (int n = 0; n < 2; ++n) _Pragma("unroll") for (int k = 0; k < 2; ++k) dst[n][k] = *(const LAS bf16x8*)(lds + G_SB(b, h) + boff + n * 2048 + k * 1024); } while (0)
; #define G_MMA(ai, bj, At_, Bt_) do { __builtin_amdgcn_s_setprio(1); _Pragma("unroll") for (int m = 0; m < 4; ++m) _Pragma("unroll") for (int n = 0; n < 2; ++n) _Pragma("unroll") for (int k = 0; k < 2; ++k) \
;         acc[ai][bj][m][n] = __builtin_amdgcn_mfma_f32_16x16x32_bf16(Bt_[n][k], At_[m][k], acc[ai][bj][m][n], 0, 0, 0); __builtin_amdgcn_s_setprio(0); } while (0)
; #define WAIT_V(n) asm volatile("s_waitcnt vmcnt(" #n ")" ::: "memory")
; #define WAIT_L(n) asm volatile("s_waitcnt lgkmcnt(" #n ")" ::: "memory")
; #define BAR __builtin_amdgcn_s_barrier()
; template <class Get, class Epi>
; DI void gemm_loop(int ntiles, int ld, char* shm, const Get& get, const Epi& epi) {
;     ...
;         const int Ln = L + gridDim.x; const bool has_next = Ln < ntiles; if (has_next) nxt = get(Ln);
;         const char* nA = has_next ? (const char*)nxt.A + (size_t)nxt.brow * ld * 2 : cA; const char* nB = has_next ? (const char*)nxt.Bt + (size_t)nxt.bcol * ld * 2 : cB;
;         const int nt = cur.K / BK;
;         for (int t = 0; t < nt; t += 2) {
;             const bool last = (t == nt - 2);
;             const char* a1 = cA + (size_t)(t + 1) * kstep;
;             const char* a2 = last ? nA : cA + (size_t)(t + 2) * kstep; const char* b2 = last ? nB : cB + (size_t)(t + 2) * kstep;
;             const char* a3 = a2 + kstep; const char* b3 = b2 + kstep;
;             G_LDB(B0, 0, 0); G_LDB(B1, 0, 1); SCHED; G_LDA(At, 0, 0); G_STAGE(G_SA(1, 1), a1 + hstep, voffA);
;             WAIT_V(8); WAIT_L(0); BAR; G_MMA(0, 0, At, B0); G_MMA(0, 1, At, B1); BAR; SCHED;
;             G_LDA(At, 0, 1); G_STAGE(G_SB(0, 0), b2, voffB); G_STAGE(G_SB(0, 1), b2 + hstep, voffB); G_STAGE(G_SA(0, 0), a2, voffA);
.Lpeel_1694:
	ds_read_b128 v[144:147], v141
	ds_read_b128 v[148:151], v141 offset:1024
	ds_read_b128 v[152:155], v141 offset:2048
	ds_read_b128 v[156:159], v141 offset:3072
	ds_read_b128 v[160:163], v142
	ds_read_b128 v[164:167], v142 offset:1024
	ds_read_b128 v[168:171], v142 offset:2048
	ds_read_b128 v[172:175], v142 offset:3072
	s_add_u32 s14, s38, 0xfffc0080
	s_addc_u32 s15, s39, -1
	s_cmp_eq_u32 s57, 12
	s_cselect_b32 s41, s9, s15
	s_cselect_b32 s40, s53, s14
	s_cselect_b32 s15, s11, s56
	s_cselect_b32 s14, s54, s55
	v_lshl_add_u64 v[208:209], s[38:39], 0, v[136:137]
	s_add_i32 m0, s35, 0xc000
	ds_read_b128 v[176:179], v143
	ds_read_b128 v[180:183], v143 offset:1024
	ds_read_b128 v[184:187], v143 offset:2048
	ds_read_b128 v[188:191], v143 offset:3072
	ds_read_b128 v[192:195], v143 offset:4096
	ds_read_b128 v[196:199], v143 offset:5120
	ds_read_b128 v[200:203], v143 offset:6144
	ds_read_b128 v[204:207], v143 offset:7168
	global_load_lds_dwordx4 v[208:209], off
	v_lshl_add_u64 v[208:209], s[38:39], 0, v[138:139]
	s_add_i32 m0, s35, 0xe000
	s_nop 0
	global_load_lds_dwordx4 v[208:209], off
	s_waitcnt vmcnt(8)
	s_waitcnt lgkmcnt(0)
	s_barrier
	s_setprio 1
	s_waitcnt lgkmcnt(0)
	v_mfma_f32_16x16x32_bf16 v[124:127], v[144:147], v[176:179], 0
	v_mfma_f32_16x16x32_bf16 v[120:123], v[152:155], v[176:179], 0
	v_mfma_f32_16x16x32_bf16 v[108:111], v[144:147], v[184:187], 0
	v_mfma_f32_16x16x32_bf16 v[104:107], v[152:155], v[184:187], 0
	v_mfma_f32_16x16x32_bf16 v[92:95], v[144:147], v[192:195], 0
	v_mfma_f32_16x16x32_bf16 v[88:91], v[152:155], v[192:195], 0
	v_mfma_f32_16x16x32_bf16 v[76:79], v[144:147], v[200:203], 0
	v_mfma_f32_16x16x32_bf16 v[72:75], v[152:155], v[200:203], 0
	v_mfma_f32_16x16x32_bf16 v[124:127], v[148:151], v[180:183], v[124:127]
	v_mfma_f32_16x16x32_bf16 v[120:123], v[156:159], v[180:183], v[120:123]
	v_mfma_f32_16x16x32_bf16 v[108:111], v[148:151], v[188:191], v[108:111]
	v_mfma_f32_16x16x32_bf16 v[104:107], v[156:159], v[188:191], v[104:107]
	v_mfma_f32_16x16x32_bf16 v[92:95], v[148:151], v[196:199], v[92:95]
	v_mfma_f32_16x16x32_bf16 v[88:91], v[156:159], v[196:199], v[88:91]
	v_mfma_f32_16x16x32_bf16 v[76:79], v[148:151], v[204:207], v[76:79]
	v_mfma_f32_16x16x32_bf16 v[72:75], v[156:159], v[204:207], v[72:75]
	s_setprio 0
	s_setprio 1
	v_mfma_f32_16x16x32_bf16 v[116:119], v[160:163], v[176:179], 0
	v_mfma_f32_16x16x32_bf16 v[112:115], v[168:171], v[176:179], 0
	v_mfma_f32_16x16x32_bf16 v[100:103], v[160:163], v[184:187], 0
	v_mfma_f32_16x16x32_bf16 v[96:99], v[168:171], v[184:187], 0
	v_mfma_f32_16x16x32_bf16 v[84:87], v[160:163], v[192:195], 0
	v_mfma_f32_16x16x32_bf16 v[80:83], v[168:171], v[192:195], 0
	v_mfma_f32_16x16x32_bf16 v[68:71], v[160:163], v[200:203], 0
	v_mfma_f32_16x16x32_bf16 v[64:67], v[168:171], v[200:203], 0
	v_mfma_f32_16x16x32_bf16 v[116:119], v[164:167], v[180:183], v[116:119]
	v_mfma_f32_16x16x32_bf16 v[112:115], v[172:175], v[180:183], v[112:115]
	v_mfma_f32_16x16x32_bf16 v[100:103], v[164:167], v[188:191], v[100:103]
	v_mfma_f32_16x16x32_bf16 v[96:99], v[172:175], v[188:191], v[96:99]
	v_mfma_f32_16x16x32_bf16 v[84:87], v[164:167], v[196:199], v[84:87]
	v_mfma_f32_16x16x32_bf16 v[80:83], v[172:175], v[196:199], v[80:83]
	v_mfma_f32_16x16x32_bf16 v[68:71], v[164:167], v[204:207], v[68:71]
	v_mfma_f32_16x16x32_bf16 v[64:67], v[172:175], v[204:207], v[64:67]
	s_setprio 0
	s_add_i32 s58, s48, s42
	v_lshl_add_u64 v[208:209], s[14:15], 0, v[132:133]
	s_mov_b32 m0, s58
	s_barrier
	ds_read_b128 v[176:179], v143 offset:16384
	ds_read_b128 v[180:183], v143 offset:17408
	ds_read_b128 v[184:187], v143 offset:18432
	ds_read_b128 v[188:191], v143 offset:19456
	ds_read_b128 v[192:195], v143 offset:20480
	ds_read_b128 v[196:199], v143 offset:21504
	ds_read_b128 v[200:203], v143 offset:22528
	ds_read_b128 v[204:207], v143 offset:23552
	global_load_lds_dwordx4 v[208:209], off
	s_add_i32 m0, s58, 0x2000
	s_add_u32 s58, s14, 0x40000
	v_lshl_add_u64 v[210:211], s[14:15], 0, v[128:129]
	s_addc_u32 s59, s15, 0
	s_add_i32 s71, s49, s42
	global_load_lds_dwordx4 v[210:211], off
	v_lshl_add_u64 v[212:213], s[58:59], 0, v[132:133]
	s_mov_b32 m0, s71
	v_lshl_add_u64 v[214:215], s[40:41], 0, v[130:131]
	global_load_lds_dwordx4 v[212:213], off
	v_lshl_add_u64 v[212:213], s[58:59], 0, v[128:129]
	s_add_i32 m0, s71, 0x2000
	s_nop 0
	global_load_lds_dwordx4 v[212:213], off
	v_lshl_add_u64 v[212:213], s[40:41], 0, v[134:135]
	s_mov_b32 m0, s35
	s_nop 0
	global_load_lds_dwordx4 v[212:213], off
	s_mov_b32 m0, s37
	s_nop 0
	global_load_lds_dwordx4 v[214:215], off
	s_waitcnt vmcnt(8)
	s_waitcnt lgkmcnt(0)
	s_barrier
; #define G_STAGE(bufoff, gbase, voff) do { _Pragma("unroll") for (int _i = 0; _i < 2; ++_i) \
;         __builtin_amdgcn_global_load_lds((const unsigned*)((const char*)(gbase) + voff[_i]), (LAS unsigned*)(lds + (bufoff) + ldsw + _i * 8192), 16, 0, 0); } while (0)
; #define G_LDA(dst, b, h) do { _Pragma("unroll") for (int m = 0; m < 4; ++m) _Pragma("unroll") for (int k = 0; k < 2; ++k) dst[m][k] = *(const LAS bf16x8*)(lds + G_SA(b, h) + aoff + m * 2048 + k * 1024); } while (0)
; #define G_LDB(dst, b, h) do { _Pragma("unroll") for (int n = 0; n < 2; ++n) _Pragma("unroll") for (int k = 0; k < 2; ++k) dst[n][k] = *(const LAS bf16x8*)(lds + G_SB(b, h) + boff + n * 2048 + k * 1024); } while (0)
; #define G_MMA(ai, bj, At_, Bt_) do { __builtin_amdgcn_s_setprio(1); _Pragma("unroll") for (int m = 0; m < 4; ++m) _Pragma("unroll") for (int n = 0; n < 2; ++n) _Pragma("unroll") for (int k = 0; k < 2; ++k) \
;         acc[ai][bj][m][n] = __builtin_amdgcn_mfma_f32_16x16x32_bf16(Bt_[n][k], At_[m][k], acc[ai][bj][m][n], 0, 0, 0); __builtin_amdgcn_s_setprio(0); } while (0)
; #define WAIT_V(n) asm volatile("s_waitcnt vmcnt(" #n ")" ::: "memory")
; #define WAIT_L(n) asm volatile("s_waitcnt lgkmcnt(" #n ")" ::: "memory")
; #define BAR __builtin_amdgcn_s_barrier()
; #define SCHED __builtin_amdgcn_sched_barrier(0)
; template <class Get, class Epi>
; DI void gemm_loop(int ntiles, int ld, char* shm, const Get& get, const Epi& epi) {
;     ...
;             WAIT_V(8); WAIT_L(0); BAR; G_MMA(1, 0, At, B0); G_MMA(1, 1, At, B1); BAR; SCHED;
;             G_LDB(B0, 1, 0); G_LDB(B1, 1, 1); SCHED; G_LDA(At, 1, 0); G_STAGE(G_SA(0, 1), a2 + hstep, voffA);
;             WAIT_V(8); WAIT_L(0); BAR; G_MMA(0, 0, At, B0); G_MMA(0, 1, At, B1); BAR; SCHED;
	s_setprio 1
	s_waitcnt lgkmcnt(0)
	v_mfma_f32_16x16x32_bf16 v[60:63], v[144:147], v[176:179], 0
	v_mfma_f32_16x16x32_bf16 v[56:59], v[152:155], v[176:179], 0
	v_mfma_f32_16x16x32_bf16 v[44:47], v[144:147], v[184:187], 0
	v_mfma_f32_16x16x32_bf16 v[40:43], v[152:155], v[184:187], 0
	v_mfma_f32_16x16x32_bf16 v[28:31], v[144:147], v[192:195], 0
	v_mfma_f32_16x16x32_bf16 v[24:27], v[152:155], v[192:195], 0
	v_mfma_f32_16x16x32_bf16 v[12:15], v[144:147], v[200:203], 0
	v_mfma_f32_16x16x32_bf16 v[8:11], v[152:155], v[200:203], 0
	v_mfma_f32_16x16x32_bf16 v[60:63], v[148:151], v[180:183], v[60:63]
	v_mfma_f32_16x16x32_bf16 v[56:59], v[156:159], v[180:183], v[56:59]
	v_mfma_f32_16x16x32_bf16 v[44:47], v[148:151], v[188:191], v[44:47]
	v_mfma_f32_16x16x32_bf16 v[40:43], v[156:159], v[188:191], v[40:43]
	v_mfma_f32_16x16x32_bf16 v[28:31], v[148:151], v[196:199], v[28:31]
	v_mfma_f32_16x16x32_bf16 v[24:27], v[156:159], v[196:199], v[24:27]
	v_mfma_f32_16x16x32_bf16 v[12:15], v[148:151], v[204:207], v[12:15]
	v_mfma_f32_16x16x32_bf16 v[8:11], v[156:159], v[204:207], v[8:11]
	s_setprio 0
	s_setprio 1
	v_mfma_f32_16x16x32_bf16 v[52:55], v[160:163], v[176:179], 0
	v_mfma_f32_16x16x32_bf16 v[48:51], v[168:171], v[176:179], 0
	v_mfma_f32_16x16x32_bf16 v[36:39], v[160:163], v[184:187], 0
	v_mfma_f32_16x16x32_bf16 v[32:35], v[168:171], v[184:187], 0
	v_mfma_f32_16x16x32_bf16 v[20:23], v[160:163], v[192:195], 0
	v_mfma_f32_16x16x32_bf16 v[16:19], v[168:171], v[192:195], 0
	v_mfma_f32_16x16x32_bf16 v[4:7], v[160:163], v[200:203], 0
	v_mfma_f32_16x16x32_bf16 v[0:3], v[168:171], v[200:203], 0
	v_mfma_f32_16x16x32_bf16 v[52:55], v[164:167], v[180:183], v[52:55]
	v_mfma_f32_16x16x32_bf16 v[48:51], v[172:175], v[180:183], v[48:51]
	v_mfma_f32_16x16x32_bf16 v[36:39], v[164:167], v[188:191], v[36:39]
	v_mfma_f32_16x16x32_bf16 v[32:35], v[172:175], v[188:191], v[32:35]
	v_mfma_f32_16x16x32_bf16 v[20:23], v[164:167], v[196:199], v[20:23]
	v_mfma_f32_16x16x32_bf16 v[16:19], v[172:175], v[196:199], v[16:19]
	v_mfma_f32_16x16x32_bf16 v[4:7], v[164:167], v[204:207], v[4:7]
	v_mfma_f32_16x16x32_bf16 v[0:3], v[172:175], v[204:207], v[0:3]
	s_setprio 0
	s_add_i32 s58, 0, 0x18000
	s_add_i32 s59, 0, 0x1c000
	v_add_u32_e32 v156, s58, v140
	s_barrier
	v_add_u32_e32 v172, s59, v140
	ds_read_b128 v[144:147], v156
	ds_read_b128 v[148:151], v156 offset:1024
	ds_read_b128 v[152:155], v156 offset:2048
	ds_read_b128 v[156:159], v156 offset:3072
	ds_read_b128 v[160:163], v172
	ds_read_b128 v[164:167], v172 offset:1024
	ds_read_b128 v[168:171], v172 offset:2048
	ds_read_b128 v[172:175], v172 offset:3072
	s_add_u32 s40, s40, 0x40000
	s_addc_u32 s41, s41, 0
	s_mov_b32 m0, s44
	v_lshl_add_u64 v[216:217], s[40:41], 0, v[134:135]
	ds_read_b128 v[176:179], v143 offset:32768
	ds_read_b128 v[180:183], v143 offset:33792
	ds_read_b128 v[184:187], v143 offset:34816
	ds_read_b128 v[188:191], v143 offset:35840
	ds_read_b128 v[192:195], v143 offset:36864
	ds_read_b128 v[196:199], v143 offset:37888
	ds_read_b128 v[200:203], v143 offset:38912
	ds_read_b128 v[204:207], v143 offset:39936
	global_load_lds_dwordx4 v[216:217], off
	v_lshl_add_u64 v[216:217], s[40:41], 0, v[130:131]
	s_mov_b32 m0, s45
	s_nop 0
	global_load_lds_dwordx4 v[216:217], off
	s_waitcnt vmcnt(8)
	s_waitcnt lgkmcnt(0)
	s_barrier
	s_setprio 1
	s_waitcnt lgkmcnt(0)
	v_mfma_f32_16x16x32_bf16 v[124:127], v[144:147], v[176:179], v[124:127]
	v_mfma_f32_16x16x32_bf16 v[120:123], v[152:155], v[176:179], v[120:123]
	v_mfma_f32_16x16x32_bf16 v[108:111], v[144:147], v[184:187], v[108:111]
	v_mfma_f32_16x16x32_bf16 v[104:107], v[152:155], v[184:187], v[104:107]
	v_mfma_f32_16x16x32_bf16 v[92:95], v[144:147], v[192:195], v[92:95]
	v_mfma_f32_16x16x32_bf16 v[88:91], v[152:155], v[192:195], v[88:91]
	v_mfma_f32_16x16x32_bf16 v[76:79], v[144:147], v[200:203], v[76:79]
	v_mfma_f32_16x16x32_bf16 v[72:75], v[152:155], v[200:203], v[72:75]
	v_mfma_f32_16x16x32_bf16 v[124:127], v[148:151], v[180:183], v[124:127]
	v_mfma_f32_16x16x32_bf16 v[120:123], v[156:159], v[180:183], v[120:123]
	v_mfma_f32_16x16x32_bf16 v[108:111], v[148:151], v[188:191], v[108:111]
	v_mfma_f32_16x16x32_bf16 v[104:107], v[156:159], v[188:191], v[104:107]
	v_mfma_f32_16x16x32_bf16 v[92:95], v[148:151], v[196:199], v[92:95]
	v_mfma_f32_16x16x32_bf16 v[88:91], v[156:159], v[196:199], v[88:91]
	v_mfma_f32_16x16x32_bf16 v[76:79], v[148:151], v[204:207], v[76:79]
	v_mfma_f32_16x16x32_bf16 v[72:75], v[156:159], v[204:207], v[72:75]
	s_setprio 0
	s_setprio 1
	v_mfma_f32_16x16x32_bf16 v[116:119], v[160:163], v[176:179], v[116:119]
	v_mfma_f32_16x16x32_bf16 v[112:115], v[168:171], v[176:179], v[112:115]
	v_mfma_f32_16x16x32_bf16 v[100:103], v[160:163], v[184:187], v[100:103]
	v_mfma_f32_16x16x32_bf16 v[96:99], v[168:171], v[184:187], v[96:99]
	v_mfma_f32_16x16x32_bf16 v[84:87], v[160:163], v[192:195], v[84:87]
	v_mfma_f32_16x16x32_bf16 v[80:83], v[168:171], v[192:195], v[80:83]
	v_mfma_f32_16x16x32_bf16 v[68:71], v[160:163], v[200:203], v[68:71]
	v_mfma_f32_16x16x32_bf16 v[64:67], v[168:171], v[200:203], v[64:67]
	v_mfma_f32_16x16x32_bf16 v[116:119], v[164:167], v[180:183], v[116:119]
	v_mfma_f32_16x16x32_bf16 v[112:115], v[172:175], v[180:183], v[112:115]
	v_mfma_f32_16x16x32_bf16 v[100:103], v[164:167], v[188:191], v[100:103]
	v_mfma_f32_16x16x32_bf16 v[96:99], v[172:175], v[188:191], v[96:99]
	v_mfma_f32_16x16x32_bf16 v[84:87], v[164:167], v[196:199], v[84:87]
	v_mfma_f32_16x16x32_bf16 v[80:83], v[172:175], v[196:199], v[80:83]
	v_mfma_f32_16x16x32_bf16 v[68:71], v[164:167], v[204:207], v[68:71]
	v_mfma_f32_16x16x32_bf16 v[64:67], v[172:175], v[204:207], v[64:67]
	s_setprio 0
	s_add_i32 s40, s58, s42
	v_lshl_add_u64 v[208:209], v[208:209], 0, s[2:3]
	s_mov_b32 m0, s40
	s_barrier
; #define G_STAGE(bufoff, gbase, voff) do { _Pragma("unroll") for (int _i = 0; _i < 2; ++_i) \
;         __builtin_amdgcn_global_load_lds((const unsigned*)((const char*)(gbase) + voff[_i]), (LAS unsigned*)(lds + (bufoff) + ldsw + _i * 8192), 16, 0, 0); } while (0)
; #define G_LDA(dst, b, h) do { _Pragma("unroll") for (int m = 0; m < 4; ++m) _Pragma("unroll") for (int k = 0; k < 2; ++k) dst[m][k] = *(const LAS bf16x8*)(lds + G_SA(b, h) + aoff + m * 2048 + k * 1024); } while (0)
; #define G_LDB(dst, b, h) do { _Pragma("unroll") for (int n = 0; n < 2; ++n) _Pragma("unroll") for (int k = 0; k < 2; ++k) dst[n][k] = *(const LAS bf16x8*)(lds + G_SB(b, h) + boff + n * 2048 + k * 1024); } while (0)
; #define G_MMA(ai, bj, At_, Bt_) do { __builtin_amdgcn_s_setprio(1); _Pragma("unroll") for (int m = 0; m < 4; ++m) _Pragma("unroll") for (int n = 0; n < 2; ++n) _Pragma("unroll") for (int k = 0; k < 2; ++k) \
;         acc[ai][bj][m][n] = __builtin_amdgcn_mfma_f32_16x16x32_bf16(Bt_[n][k], At_[m][k], acc[ai][bj][m][n], 0, 0, 0); __builtin_amdgcn_s_setprio(0); } while (0)
; #define WAIT_V(n) asm volatile("s_waitcnt vmcnt(" #n ")" ::: "memory")
; #define WAIT_L(n) asm volatile("s_waitcnt lgkmcnt(" #n ")" ::: "memory")
; #define BAR __builtin_amdgcn_s_barrier()
; #define SCHED __builtin_amdgcn_sched_barrier(0)
; template <class Get, class Epi>
; DI void gemm_loop(int ntiles, int ld, char* shm, const Get& get, const Epi& epi) {
;     ...
;             G_LDB(B0, 0, 0); G_LDB(B1, 0, 1); SCHED; G_LDA(At, 0, 0); G_STAGE(G_SA(1, 1), a1 + hstep, voffA);
;             WAIT_V(8); WAIT_L(0); BAR; G_MMA(0, 0, At, B0); G_MMA(0, 1, At, B1); BAR; SCHED;
;     ...
;             G_LDA(At, 1, 1); G_STAGE(G_SB(1, 0), b3, voffB); G_STAGE(G_SB(1, 1), b3 + hstep, voffB); G_STAGE(G_SA(1, 0), a3, voffA);
;             WAIT_V(8); WAIT_L(0); BAR; G_MMA(1, 0, At, B0); G_MMA(1, 1, At, B1); BAR; SCHED;
	ds_read_b128 v[176:179], v143 offset:49152
	ds_read_b128 v[180:183], v143 offset:50176
	ds_read_b128 v[184:187], v143 offset:51200
	ds_read_b128 v[188:191], v143 offset:52224
	ds_read_b128 v[192:195], v143 offset:53248
	ds_read_b128 v[196:199], v143 offset:54272
	ds_read_b128 v[200:203], v143 offset:55296
	ds_read_b128 v[204:207], v143 offset:56320
	global_load_lds_dwordx4 v[208:209], off
	s_add_i32 m0, s40, 0x2000
	s_add_u32 s14, s14, 0x40080
	v_lshl_add_u64 v[208:209], v[210:211], 0, s[2:3]
	s_addc_u32 s15, s15, 0
	s_add_i32 s40, s59, s42
	global_load_lds_dwordx4 v[208:209], off
	v_lshl_add_u64 v[208:209], s[14:15], 0, v[132:133]
	s_mov_b32 m0, s40
	s_nop 0
	global_load_lds_dwordx4 v[208:209], off
	v_lshl_add_u64 v[208:209], s[14:15], 0, v[128:129]
	s_add_i32 m0, s40, 0x2000
	s_nop 0
	global_load_lds_dwordx4 v[208:209], off
	v_lshl_add_u64 v[208:209], v[212:213], 0, s[2:3]
	s_mov_b32 m0, s46
	s_nop 0
	global_load_lds_dwordx4 v[208:209], off
	v_lshl_add_u64 v[208:209], v[214:215], 0, s[2:3]
	s_mov_b32 m0, s47
	s_nop 0
	global_load_lds_dwordx4 v[208:209], off
	s_waitcnt vmcnt(8)
	s_waitcnt lgkmcnt(0)
	s_barrier
	s_setprio 1
	s_waitcnt lgkmcnt(0)
	v_mfma_f32_16x16x32_bf16 v[60:63], v[144:147], v[176:179], v[60:63]
	v_mfma_f32_16x16x32_bf16 v[56:59], v[152:155], v[176:179], v[56:59]
	v_mfma_f32_16x16x32_bf16 v[44:47], v[144:147], v[184:187], v[44:47]
	v_mfma_f32_16x16x32_bf16 v[40:43], v[152:155], v[184:187], v[40:43]
	v_mfma_f32_16x16x32_bf16 v[28:31], v[144:147], v[192:195], v[28:31]
	v_mfma_f32_16x16x32_bf16 v[24:27], v[152:155], v[192:195], v[24:27]
	v_mfma_f32_16x16x32_bf16 v[12:15], v[144:147], v[200:203], v[12:15]
	v_mfma_f32_16x16x32_bf16 v[8:11], v[152:155], v[200:203], v[8:11]
	v_mfma_f32_16x16x32_bf16 v[60:63], v[148:151], v[180:183], v[60:63]
	v_mfma_f32_16x16x32_bf16 v[56:59], v[156:159], v[180:183], v[56:59]
	v_mfma_f32_16x16x32_bf16 v[44:47], v[148:151], v[188:191], v[44:47]
	v_mfma_f32_16x16x32_bf16 v[40:43], v[156:159], v[188:191], v[40:43]
	v_mfma_f32_16x16x32_bf16 v[28:31], v[148:151], v[196:199], v[28:31]
	v_mfma_f32_16x16x32_bf16 v[24:27], v[156:159], v[196:199], v[24:27]
	v_mfma_f32_16x16x32_bf16 v[12:15], v[148:151], v[204:207], v[12:15]
	v_mfma_f32_16x16x32_bf16 v[8:11], v[156:159], v[204:207], v[8:11]
	s_setprio 0
	s_setprio 1
	v_mfma_f32_16x16x32_bf16 v[52:55], v[160:163], v[176:179], v[52:55]
	v_mfma_f32_16x16x32_bf16 v[48:51], v[168:171], v[176:179], v[48:51]
	v_mfma_f32_16x16x32_bf16 v[36:39], v[160:163], v[184:187], v[36:39]
	v_mfma_f32_16x16x32_bf16 v[32:35], v[168:171], v[184:187], v[32:35]
	v_mfma_f32_16x16x32_bf16 v[20:23], v[160:163], v[192:195], v[20:23]
	v_mfma_f32_16x16x32_bf16 v[16:19], v[168:171], v[192:195], v[16:19]
	v_mfma_f32_16x16x32_bf16 v[4:7], v[160:163], v[200:203], v[4:7]
	v_mfma_f32_16x16x32_bf16 v[0:3], v[168:171], v[200:203], v[0:3]
	v_mfma_f32_16x16x32_bf16 v[52:55], v[164:167], v[180:183], v[52:55]
	v_mfma_f32_16x16x32_bf16 v[48:51], v[172:175], v[180:183], v[48:51]
	v_mfma_f32_16x16x32_bf16 v[36:39], v[164:167], v[188:191], v[36:39]
	v_mfma_f32_16x16x32_bf16 v[32:35], v[172:175], v[188:191], v[32:35]
	v_mfma_f32_16x16x32_bf16 v[20:23], v[164:167], v[196:199], v[20:23]
	v_mfma_f32_16x16x32_bf16 v[16:19], v[172:175], v[196:199], v[16:19]
	v_mfma_f32_16x16x32_bf16 v[4:7], v[164:167], v[204:207], v[4:7]
	v_mfma_f32_16x16x32_bf16 v[0:3], v[172:175], v[204:207], v[0:3]
	s_setprio 0
	s_add_i32 s57, s57, 2
	s_add_u32 s38, s38, 0x100
	s_addc_u32 s39, s39, 0
	s_add_u32 s55, s55, 0x100
	s_addc_u32 s56, s56, 0
	s_cmp_gt_u32 s57, 13
	s_barrier
	s_cbranch_scc0 .LBB0_1694
	s_branch .Lpost_1694
.LBB0_1694:
	ds_read_b128 v[144:147], v141
	ds_read_b128 v[148:151], v141 offset:1024
	ds_read_b128 v[152:155], v141 offset:2048
	ds_read_b128 v[156:159], v141 offset:3072
	ds_read_b128 v[160:163], v142
	ds_read_b128 v[164:167], v142 offset:1024
	ds_read_b128 v[168:171], v142 offset:2048
	ds_read_b128 v[172:175], v142 offset:3072
	s_add_u32 s14, s38, 0xfffc0080
	s_addc_u32 s15, s39, -1
	s_cmp_eq_u32 s57, 12
	s_cselect_b32 s41, s9, s15
	s_cselect_b32 s40, s53, s14
	s_cselect_b32 s15, s11, s56
	s_cselect_b32 s14, s54, s55
	v_lshl_add_u64 v[208:209], s[38:39], 0, v[136:137]
	s_add_i32 m0, s35, 0xc000
	ds_read_b128 v[176:179], v143
	ds_read_b128 v[180:183], v143 offset:1024
	ds_read_b128 v[184:187], v143 offset:2048
	ds_read_b128 v[188:191], v143 offset:3072
	ds_read_b128 v[192:195], v143 offset:4096
	ds_read_b128 v[196:199], v143 offset:5120
	ds_read_b128 v[200:203], v143 offset:6144
	ds_read_b128 v[204:207], v143 offset:7168
	global_load_lds_dwordx4 v[208:209], off
	v_lshl_add_u64 v[208:209], s[38:39], 0, v[138:139]
	s_add_i32 m0, s35, 0xe000
	s_nop 0
	global_load_lds_dwordx4 v[208:209], off
	s_waitcnt vmcnt(8)
	s_waitcnt lgkmcnt(0)
	s_barrier
; #define G_STAGE(bufoff, gbase, voff) do { _Pragma("unroll") for (int _i = 0; _i < 2; ++_i) \
;         __builtin_amdgcn_global_load_lds((const unsigned*)((const char*)(gbase) + voff[_i]), (LAS unsigned*)(lds + (bufoff) + ldsw + _i * 8192), 16, 0, 0); } while (0)
; #define G_LDA(dst, b, h) do { _Pragma("unroll") for (int m = 0; m < 4; ++m) _Pragma("unroll") for (int k = 0; k < 2; ++k) dst[m][k] = *(const LAS bf16x8*)(lds + G_SA(b, h) + aoff + m * 2048 + k * 1024); } while (0)
; #define G_MMA(ai, bj, At_, Bt_) do { __builtin_amdgcn_s_setprio(1); _Pragma("unroll") for (int m = 0; m < 4; ++m) _Pragma("unroll") for (int n = 0; n < 2; ++n) _Pragma("unroll") for (int k = 0; k < 2; ++k) \
;         acc[ai][bj][m][n] = __builtin_amdgcn_mfma_f32_16x16x32_bf16(Bt_[n][k], At_[m][k], acc[ai][bj][m][n], 0, 0, 0); __builtin_amdgcn_s_setprio(0); } while (0)
; #define WAIT_V(n) asm volatile("s_waitcnt vmcnt(" #n ")" ::: "memory")
; #define WAIT_L(n) asm volatile("s_waitcnt lgkmcnt(" #n ")" ::: "memory")
; #define BAR __builtin_amdgcn_s_barrier()
; #define SCHED __builtin_amdgcn_sched_barrier(0)
; template <class Get, class Epi>
; DI void gemm_loop(int ntiles, int ld, char* shm, const Get& get, const Epi& epi) {
;     ...
;             WAIT_V(8); WAIT_L(0); BAR; G_MMA(0, 0, At, B0); G_MMA(0, 1, At, B1); BAR; SCHED;
;             G_LDA(At, 0, 1); G_STAGE(G_SB(0, 0), b2, voffB); G_STAGE(G_SB(0, 1), b2 + hstep, voffB); G_STAGE(G_SA(0, 0), a2, voffA);
;             WAIT_V(8); WAIT_L(0); BAR; G_MMA(1, 0, At, B0); G_MMA(1, 1, At, B1); BAR; SCHED;
	s_setprio 1
	s_waitcnt lgkmcnt(0)
	v_mfma_f32_16x16x32_bf16 v[124:127], v[144:147], v[176:179], v[124:127]
	v_mfma_f32_16x16x32_bf16 v[120:123], v[152:155], v[176:179], v[120:123]
	v_mfma_f32_16x16x32_bf16 v[108:111], v[144:147], v[184:187], v[108:111]
	v_mfma_f32_16x16x32_bf16 v[104:107], v[152:155], v[184:187], v[104:107]
	v_mfma_f32_16x16x32_bf16 v[92:95], v[144:147], v[192:195], v[92:95]
	v_mfma_f32_16x16x32_bf16 v[88:91], v[152:155], v[192:195], v[88:91]
	v_mfma_f32_16x16x32_bf16 v[76:79], v[144:147], v[200:203], v[76:79]
	v_mfma_f32_16x16x32_bf16 v[72:75], v[152:155], v[200:203], v[72:75]
	v_mfma_f32_16x16x32_bf16 v[124:127], v[148:151], v[180:183], v[124:127]
	v_mfma_f32_16x16x32_bf16 v[120:123], v[156:159], v[180:183], v[120:123]
	v_mfma_f32_16x16x32_bf16 v[108:111], v[148:151], v[188:191], v[108:111]
	v_mfma_f32_16x16x32_bf16 v[104:107], v[156:159], v[188:191], v[104:107]
	v_mfma_f32_16x16x32_bf16 v[92:95], v[148:151], v[196:199], v[92:95]
	v_mfma_f32_16x16x32_bf16 v[88:91], v[156:159], v[196:199], v[88:91]
	v_mfma_f32_16x16x32_bf16 v[76:79], v[148:151], v[204:207], v[76:79]
	v_mfma_f32_16x16x32_bf16 v[72:75], v[156:159], v[204:207], v[72:75]
	s_setprio 0
	s_setprio 1
	v_mfma_f32_16x16x32_bf16 v[116:119], v[160:163], v[176:179], v[116:119]
	v_mfma_f32_16x16x32_bf16 v[112:115], v[168:171], v[176:179], v[112:115]
	v_mfma_f32_16x16x32_bf16 v[100:103], v[160:163], v[184:187], v[100:103]
	v_mfma_f32_16x16x32_bf16 v[96:99], v[168:171], v[184:187], v[96:99]
	v_mfma_f32_16x16x32_bf16 v[84:87], v[160:163], v[192:195], v[84:87]
	v_mfma_f32_16x16x32_bf16 v[80:83], v[168:171], v[192:195], v[80:83]
	v_mfma_f32_16x16x32_bf16 v[68:71], v[160:163], v[200:203], v[68:71]
	v_mfma_f32_16x16x32_bf16 v[64:67], v[168:171], v[200:203], v[64:67]
	v_mfma_f32_16x16x32_bf16 v[116:119], v[164:167], v[180:183], v[116:119]
	v_mfma_f32_16x16x32_bf16 v[112:115], v[172:175], v[180:183], v[112:115]
	v_mfma_f32_16x16x32_bf16 v[100:103], v[164:167], v[188:191], v[100:103]
	v_mfma_f32_16x16x32_bf16 v[96:99], v[172:175], v[188:191], v[96:99]
	v_mfma_f32_16x16x32_bf16 v[84:87], v[164:167], v[196:199], v[84:87]
	v_mfma_f32_16x16x32_bf16 v[80:83], v[172:175], v[196:199], v[80:83]
	v_mfma_f32_16x16x32_bf16 v[68:71], v[164:167], v[204:207], v[68:71]
	v_mfma_f32_16x16x32_bf16 v[64:67], v[172:175], v[204:207], v[64:67]
	s_setprio 0
	s_add_i32 s58, s48, s42
	v_lshl_add_u64 v[208:209], s[14:15], 0, v[132:133]
	s_mov_b32 m0, s58
	s_barrier
	ds_read_b128 v[176:179], v143 offset:16384
	ds_read_b128 v[180:183], v143 offset:17408
	ds_read_b128 v[184:187], v143 offset:18432
	ds_read_b128 v[188:191], v143 offset:19456
	ds_read_b128 v[192:195], v143 offset:20480
	ds_read_b128 v[196:199], v143 offset:21504
	ds_read_b128 v[200:203], v143 offset:22528
	ds_read_b128 v[204:207], v143 offset:23552
	global_load_lds_dwordx4 v[208:209], off
	s_add_i32 m0, s58, 0x2000
	s_add_u32 s58, s14, 0x40000
	v_lshl_add_u64 v[210:211], s[14:15], 0, v[128:129]
	s_addc_u32 s59, s15, 0
	s_add_i32 s71, s49, s42
	global_load_lds_dwordx4 v[210:211], off
	v_lshl_add_u64 v[212:213], s[58:59], 0, v[132:133]
	s_mov_b32 m0, s71
	v_lshl_add_u64 v[214:215], s[40:41], 0, v[130:131]
	global_load_lds_dwordx4 v[212:213], off
	v_lshl_add_u64 v[212:213], s[58:59], 0, v[128:129]
	s_add_i32 m0, s71, 0x2000
	s_nop 0
	global_load_lds_dwordx4 v[212:213], off
	v_lshl_add_u64 v[212:213], s[40:41], 0, v[134:135]
	s_mov_b32 m0, s35
	s_nop 0
	global_load_lds_dwordx4 v[212:213], off
	s_mov_b32 m0, s37
	s_nop 0
	global_load_lds_dwordx4 v[214:215], off
	s_waitcnt vmcnt(8)
	s_waitcnt lgkmcnt(0)
	s_barrier
	s_setprio 1
	s_waitcnt lgkmcnt(0)
	v_mfma_f32_16x16x32_bf16 v[60:63], v[144:147], v[176:179], v[60:63]
	v_mfma_f32_16x16x32_bf16 v[56:59], v[152:155], v[176:179], v[56:59]
	v_mfma_f32_16x16x32_bf16 v[44:47], v[144:147], v[184:187], v[44:47]
	v_mfma_f32_16x16x32_bf16 v[40:43], v[152:155], v[184:187], v[40:43]
	v_mfma_f32_16x16x32_bf16 v[28:31], v[144:147], v[192:195], v[28:31]
	v_mfma_f32_16x16x32_bf16 v[24:27], v[152:155], v[192:195], v[24:27]
	v_mfma_f32_16x16x32_bf16 v[12:15], v[144:147], v[200:203], v[12:15]
	v_mfma_f32_16x16x32_bf16 v[8:11], v[152:155], v[200:203], v[8:11]
	v_mfma_f32_16x16x32_bf16 v[60:63], v[148:151], v[180:183], v[60:63]
	v_mfma_f32_16x16x32_bf16 v[56:59], v[156:159], v[180:183], v[56:59]
	v_mfma_f32_16x16x32_bf16 v[44:47], v[148:151], v[188:191], v[44:47]
	v_mfma_f32_16x16x32_bf16 v[40:43], v[156:159], v[188:191], v[40:43]
	v_mfma_f32_16x16x32_bf16 v[28:31], v[148:151], v[196:199], v[28:31]
	v_mfma_f32_16x16x32_bf16 v[24:27], v[156:159], v[196:199], v[24:27]
	v_mfma_f32_16x16x32_bf16 v[12:15], v[148:151], v[204:207], v[12:15]
	v_mfma_f32_16x16x32_bf16 v[8:11], v[156:159], v[204:207], v[8:11]
	s_setprio 0
	s_setprio 1
	v_mfma_f32_16x16x32_bf16 v[52:55], v[160:163], v[176:179], v[52:55]
	v_mfma_f32_16x16x32_bf16 v[48:51], v[168:171], v[176:179], v[48:51]
	v_mfma_f32_16x16x32_bf16 v[36:39], v[160:163], v[184:187], v[36:39]
	v_mfma_f32_16x16x32_bf16 v[32:35], v[168:171], v[184:187], v[32:35]
	v_mfma_f32_16x16x32_bf16 v[20:23], v[160:163], v[192:195], v[20:23]
	v_mfma_f32_16x16x32_bf16 v[16:19], v[168:171], v[192:195], v[16:19]
	v_mfma_f32_16x16x32_bf16 v[4:7], v[160:163], v[200:203], v[4:7]
	v_mfma_f32_16x16x32_bf16 v[0:3], v[168:171], v[200:203], v[0:3]
	v_mfma_f32_16x16x32_bf16 v[52:55], v[164:167], v[180:183], v[52:55]
	v_mfma_f32_16x16x32_bf16 v[48:51], v[172:175], v[180:183], v[48:51]
	v_mfma_f32_16x16x32_bf16 v[36:39], v[164:167], v[188:191], v[36:39]
	v_mfma_f32_16x16x32_bf16 v[32:35], v[172:175], v[188:191], v[32:35]
	v_mfma_f32_16x16x32_bf16 v[20:23], v[164:167], v[196:199], v[20:23]
	v_mfma_f32_16x16x32_bf16 v[16:19], v[172:175], v[196:199], v[16:19]
	v_mfma_f32_16x16x32_bf16 v[4:7], v[164:167], v[204:207], v[4:7]
	v_mfma_f32_16x16x32_bf16 v[0:3], v[172:175], v[204:207], v[0:3]
	s_setprio 0
	s_add_i32 s58, 0, 0x18000
	s_add_i32 s59, 0, 0x1c000
	v_add_u32_e32 v156, s58, v140
	s_barrier
; #define G_STAGE(bufoff, gbase, voff) do { _Pragma("unroll") for (int _i = 0; _i < 2; ++_i) \
;         __builtin_amdgcn_global_load_lds((const unsigned*)((const char*)(gbase) + voff[_i]), (LAS unsigned*)(lds + (bufoff) + ldsw + _i * 8192), 16, 0, 0); } while (0)
; #define G_LDA(dst, b, h) do { _Pragma("unroll") for (int m = 0; m < 4; ++m) _Pragma("unroll") for (int k = 0; k < 2; ++k) dst[m][k] = *(const LAS bf16x8*)(lds + G_SA(b, h) + aoff + m * 2048 + k * 1024); } while (0)
; #define G_LDB(dst, b, h) do { _Pragma("unroll") for (int n = 0; n < 2; ++n) _Pragma("unroll") for (int k = 0; k < 2; ++k) dst[n][k] = *(const LAS bf16x8*)(lds + G_SB(b, h) + boff + n * 2048 + k * 1024); } while (0)
; #define G_MMA(ai, bj, At_, Bt_) do { __builtin_amdgcn_s_setprio(1); _Pragma("unroll") for (int m = 0; m < 4; ++m) _Pragma("unroll") for (int n = 0; n < 2; ++n) _Pragma("unroll") for (int k = 0; k < 2; ++k) \
;         acc[ai][bj][m][n] = __builtin_amdgcn_mfma_f32_16x16x32_bf16(Bt_[n][k], At_[m][k], acc[ai][bj][m][n], 0, 0, 0); __builtin_amdgcn_s_setprio(0); } while (0)
; #define WAIT_V(n) asm volatile("s_waitcnt vmcnt(" #n ")" ::: "memory")
; #define WAIT_L(n) asm volatile("s_waitcnt lgkmcnt(" #n ")" ::: "memory")
; #define BAR __builtin_amdgcn_s_barrier()
; #define SCHED __builtin_amdgcn_sched_barrier(0)
; template <class Get, class Epi>
; DI void gemm_loop(int ntiles, int ld, char* shm, const Get& get, const Epi& epi) {
;     ...
;             G_LDB(B0, 1, 0); G_LDB(B1, 1, 1); SCHED; G_LDA(At, 1, 0); G_STAGE(G_SA(0, 1), a2 + hstep, voffA);
;             WAIT_V(8); WAIT_L(0); BAR; G_MMA(0, 0, At, B0); G_MMA(0, 1, At, B1); BAR; SCHED;
	v_add_u32_e32 v172, s59, v140
	ds_read_b128 v[144:147], v156
	ds_read_b128 v[148:151], v156 offset:1024
	ds_read_b128 v[152:155], v156 offset:2048
	ds_read_b128 v[156:159], v156 offset:3072
	ds_read_b128 v[160:163], v172
	ds_read_b128 v[164:167], v172 offset:1024
	ds_read_b128 v[168:171], v172 offset:2048
	ds_read_b128 v[172:175], v172 offset:3072
	s_add_u32 s40, s40, 0x40000
	s_addc_u32 s41, s41, 0
	s_mov_b32 m0, s44
	v_lshl_add_u64 v[216:217], s[40:41], 0, v[134:135]
	ds_read_b128 v[176:179], v143 offset:32768
	ds_read_b128 v[180:183], v143 offset:33792
	ds_read_b128 v[184:187], v143 offset:34816
	ds_read_b128 v[188:191], v143 offset:35840
	ds_read_b128 v[192:195], v143 offset:36864
	ds_read_b128 v[196:199], v143 offset:37888
	ds_read_b128 v[200:203], v143 offset:38912
	ds_read_b128 v[204:207], v143 offset:39936
	global_load_lds_dwordx4 v[216:217], off
	v_lshl_add_u64 v[216:217], s[40:41], 0, v[130:131]
	s_mov_b32 m0, s45
	s_nop 0
	global_load_lds_dwordx4 v[216:217], off
	s_waitcnt vmcnt(8)
	s_waitcnt lgkmcnt(0)
	s_barrier
	s_setprio 1
	s_waitcnt lgkmcnt(0)
	v_mfma_f32_16x16x32_bf16 v[124:127], v[144:147], v[176:179], v[124:127]
	v_mfma_f32_16x16x32_bf16 v[120:123], v[152:155], v[176:179], v[120:123]
	v_mfma_f32_16x16x32_bf16 v[108:111], v[144:147], v[184:187], v[108:111]
	v_mfma_f32_16x16x32_bf16 v[104:107], v[152:155], v[184:187], v[104:107]
	v_mfma_f32_16x16x32_bf16 v[92:95], v[144:147], v[192:195], v[92:95]
	v_mfma_f32_16x16x32_bf16 v[88:91], v[152:155], v[192:195], v[88:91]
	v_mfma_f32_16x16x32_bf16 v[76:79], v[144:147], v[200:203], v[76:79]
	v_mfma_f32_16x16x32_bf16 v[72:75], v[152:155], v[200:203], v[72:75]
	v_mfma_f32_16x16x32_bf16 v[124:127], v[148:151], v[180:183], v[124:127]
	v_mfma_f32_16x16x32_bf16 v[120:123], v[156:159], v[180:183], v[120:123]
	v_mfma_f32_16x16x32_bf16 v[108:111], v[148:151], v[188:191], v[108:111]
	v_mfma_f32_16x16x32_bf16 v[104:107], v[156:159], v[188:191], v[104:107]
	v_mfma_f32_16x16x32_bf16 v[92:95], v[148:151], v[196:199], v[92:95]
	v_mfma_f32_16x16x32_bf16 v[88:91], v[156:159], v[196:199], v[88:91]
	v_mfma_f32_16x16x32_bf16 v[76:79], v[148:151], v[204:207], v[76:79]
	v_mfma_f32_16x16x32_bf16 v[72:75], v[156:159], v[204:207], v[72:75]
	s_setprio 0
	s_setprio 1
	v_mfma_f32_16x16x32_bf16 v[116:119], v[160:163], v[176:179], v[116:119]
	v_mfma_f32_16x16x32_bf16 v[112:115], v[168:171], v[176:179], v[112:115]
	v_mfma_f32_16x16x32_bf16 v[100:103], v[160:163], v[184:187], v[100:103]
	v_mfma_f32_16x16x32_bf16 v[96:99], v[168:171], v[184:187], v[96:99]
	v_mfma_f32_16x16x32_bf16 v[84:87], v[160:163], v[192:195], v[84:87]
	v_mfma_f32_16x16x32_bf16 v[80:83], v[168:171], v[192:195], v[80:83]
	v_mfma_f32_16x16x32_bf16 v[68:71], v[160:163], v[200:203], v[68:71]
	v_mfma_f32_16x16x32_bf16 v[64:67], v[168:171], v[200:203], v[64:67]
	v_mfma_f32_16x16x32_bf16 v[116:119], v[164:167], v[180:183], v[116:119]
	v_mfma_f32_16x16x32_bf16 v[112:115], v[172:175], v[180:183], v[112:115]
	v_mfma_f32_16x16x32_bf16 v[100:103], v[164:167], v[188:191], v[100:103]
	v_mfma_f32_16x16x32_bf16 v[96:99], v[172:175], v[188:191], v[96:99]
	v_mfma_f32_16x16x32_bf16 v[84:87], v[164:167], v[196:199], v[84:87]
	v_mfma_f32_16x16x32_bf16 v[80:83], v[172:175], v[196:199], v[80:83]
	v_mfma_f32_16x16x32_bf16 v[68:71], v[164:167], v[204:207], v[68:71]
	v_mfma_f32_16x16x32_bf16 v[64:67], v[172:175], v[204:207], v[64:67]
	s_setprio 0
	s_add_i32 s40, s58, s42
	v_lshl_add_u64 v[208:209], v[208:209], 0, s[2:3]
	s_mov_b32 m0, s40
	s_barrier
; #define G_STAGE(bufoff, gbase, voff) do { _Pragma("unroll") for (int _i = 0; _i < 2; ++_i) \
;         __builtin_amdgcn_global_load_lds((const unsigned*)((const char*)(gbase) + voff[_i]), (LAS unsigned*)(lds + (bufoff) + ldsw + _i * 8192), 16, 0, 0); } while (0)
; #define G_LDA(dst, b, h) do { _Pragma("unroll") for (int m = 0; m < 4; ++m) _Pragma("unroll") for (int k = 0; k < 2; ++k) dst[m][k] = *(const LAS bf16x8*)(lds + G_SA(b, h) + aoff + m * 2048 + k * 1024); } while (0)
; #define G_MMA(ai, bj, At_, Bt_) do { __builtin_amdgcn_s_setprio(1); _Pragma("unroll") for (int m = 0; m < 4; ++m) _Pragma("unroll") for (int n = 0; n < 2; ++n) _Pragma("unroll") for (int k = 0; k < 2; ++k) \
;         acc[ai][bj][m][n] = __builtin_amdgcn_mfma_f32_16x16x32_bf16(Bt_[n][k], At_[m][k], acc[ai][bj][m][n], 0, 0, 0); __builtin_amdgcn_s_setprio(0); } while (0)
; #define WAIT_V(n) asm volatile("s_waitcnt vmcnt(" #n ")" ::: "memory")
; #define WAIT_L(n) asm volatile("s_waitcnt lgkmcnt(" #n ")" ::: "memory")
; #define BAR __builtin_amdgcn_s_barrier()
; #define SCHED __builtin_amdgcn_sched_barrier(0)
; template <class Get, class Epi>
; DI void gemm_loop(int ntiles, int ld, char* shm, const Get& get, const Epi& epi) {
;     ...
;             G_LDA(At, 1, 1); G_STAGE(G_SB(1, 0), b3, voffB); G_STAGE(G_SB(1, 1), b3 + hstep, voffB); G_STAGE(G_SA(1, 0), a3, voffA);
;             WAIT_V(8); WAIT_L(0); BAR; G_MMA(1, 0, At, B0); G_MMA(1, 1, At, B1); BAR; SCHED;
;         }
	ds_read_b128 v[176:179], v143 offset:49152
	ds_read_b128 v[180:183], v143 offset:50176
	ds_read_b128 v[184:187], v143 offset:51200
	ds_read_b128 v[188:191], v143 offset:52224
	ds_read_b128 v[192:195], v143 offset:53248
	ds_read_b128 v[196:199], v143 offset:54272
	ds_read_b128 v[200:203], v143 offset:55296
	ds_read_b128 v[204:207], v143 offset:56320
	global_load_lds_dwordx4 v[208:209], off
	s_add_i32 m0, s40, 0x2000
	s_add_u32 s14, s14, 0x40080
	v_lshl_add_u64 v[208:209], v[210:211], 0, s[2:3]
	s_addc_u32 s15, s15, 0
	s_add_i32 s40, s59, s42
	global_load_lds_dwordx4 v[208:209], off
	v_lshl_add_u64 v[208:209], s[14:15], 0, v[132:133]
	s_mov_b32 m0, s40
	s_nop 0
	global_load_lds_dwordx4 v[208:209], off
	v_lshl_add_u64 v[208:209], s[14:15], 0, v[128:129]
	s_add_i32 m0, s40, 0x2000
	s_nop 0
	global_load_lds_dwordx4 v[208:209], off
	v_lshl_add_u64 v[208:209], v[212:213], 0, s[2:3]
	s_mov_b32 m0, s46
	s_nop 0
	global_load_lds_dwordx4 v[208:209], off
	v_lshl_add_u64 v[208:209], v[214:215], 0, s[2:3]
	s_mov_b32 m0, s47
	s_nop 0
	global_load_lds_dwordx4 v[208:209], off
	s_waitcnt vmcnt(8)
	s_waitcnt lgkmcnt(0)
	s_barrier
	s_setprio 1
	s_waitcnt lgkmcnt(0)
	v_mfma_f32_16x16x32_bf16 v[60:63], v[144:147], v[176:179], v[60:63]
	v_mfma_f32_16x16x32_bf16 v[56:59], v[152:155], v[176:179], v[56:59]
	v_mfma_f32_16x16x32_bf16 v[44:47], v[144:147], v[184:187], v[44:47]
	v_mfma_f32_16x16x32_bf16 v[40:43], v[152:155], v[184:187], v[40:43]
	v_mfma_f32_16x16x32_bf16 v[28:31], v[144:147], v[192:195], v[28:31]
	v_mfma_f32_16x16x32_bf16 v[24:27], v[152:155], v[192:195], v[24:27]
	v_mfma_f32_16x16x32_bf16 v[12:15], v[144:147], v[200:203], v[12:15]
	v_mfma_f32_16x16x32_bf16 v[8:11], v[152:155], v[200:203], v[8:11]
	v_mfma_f32_16x16x32_bf16 v[60:63], v[148:151], v[180:183], v[60:63]
	v_mfma_f32_16x16x32_bf16 v[56:59], v[156:159], v[180:183], v[56:59]
	v_mfma_f32_16x16x32_bf16 v[44:47], v[148:151], v[188:191], v[44:47]
	v_mfma_f32_16x16x32_bf16 v[40:43], v[156:159], v[188:191], v[40:43]
	v_mfma_f32_16x16x32_bf16 v[28:31], v[148:151], v[196:199], v[28:31]
	v_mfma_f32_16x16x32_bf16 v[24:27], v[156:159], v[196:199], v[24:27]
	v_mfma_f32_16x16x32_bf16 v[12:15], v[148:151], v[204:207], v[12:15]
	v_mfma_f32_16x16x32_bf16 v[8:11], v[156:159], v[204:207], v[8:11]
	s_setprio 0
	s_setprio 1
	v_mfma_f32_16x16x32_bf16 v[52:55], v[160:163], v[176:179], v[52:55]
	v_mfma_f32_16x16x32_bf16 v[48:51], v[168:171], v[176:179], v[48:51]
	v_mfma_f32_16x16x32_bf16 v[36:39], v[160:163], v[184:187], v[36:39]
	v_mfma_f32_16x16x32_bf16 v[32:35], v[168:171], v[184:187], v[32:35]
	v_mfma_f32_16x16x32_bf16 v[20:23], v[160:163], v[192:195], v[20:23]
	v_mfma_f32_16x16x32_bf16 v[16:19], v[168:171], v[192:195], v[16:19]
	v_mfma_f32_16x16x32_bf16 v[4:7], v[160:163], v[200:203], v[4:7]
	v_mfma_f32_16x16x32_bf16 v[0:3], v[168:171], v[200:203], v[0:3]
	v_mfma_f32_16x16x32_bf16 v[52:55], v[164:167], v[180:183], v[52:55]
	v_mfma_f32_16x16x32_bf16 v[48:51], v[172:175], v[180:183], v[48:51]
	v_mfma_f32_16x16x32_bf16 v[36:39], v[164:167], v[188:191], v[36:39]
	v_mfma_f32_16x16x32_bf16 v[32:35], v[172:175], v[188:191], v[32:35]
	v_mfma_f32_16x16x32_bf16 v[20:23], v[164:167], v[196:199], v[20:23]
	v_mfma_f32_16x16x32_bf16 v[16:19], v[172:175], v[196:199], v[16:19]
	v_mfma_f32_16x16x32_bf16 v[4:7], v[164:167], v[204:207], v[4:7]
	v_mfma_f32_16x16x32_bf16 v[0:3], v[172:175], v[204:207], v[0:3]
	s_setprio 0
	s_add_i32 s57, s57, 2
	s_add_u32 s38, s38, 0x100
	s_addc_u32 s39, s39, 0
	s_add_u32 s55, s55, 0x100
	s_addc_u32 s56, s56, 0
	s_cmp_gt_u32 s57, 13
	s_barrier
	s_cbranch_scc0 .LBB0_1694

; #define G_STAGE(bufoff, gbase, voff) do { _Pragma("unroll") for (int _i = 0; _i < 2; ++_i) \
;         __builtin_amdgcn_global_load_lds((const unsigned*)((const char*)(gbase) + voff[_i]), (LAS unsigned*)(lds + (bufoff) + ldsw + _i * 8192), 16, 0, 0); } while (0)
; #define G_LDA(dst, b, h) do { _Pragma("unroll") for (int m = 0; m < 4; ++m) _Pragma("unroll") for (int k = 0; k < 2; ++k) dst[m][k] = *(const LAS bf16x8*)(lds + G_SA(b, h) + aoff + m * 2048 + k * 1024); } while (0)
; #define G_LDB(dst, b, h) do { _Pragma("unroll") for (int n = 0; n < 2; ++n) _Pragma("unroll") for (int k = 0; k < 2; ++k) dst[n][k] = *(const LAS bf16x8*)(lds + G_SB(b, h) + boff + n * 2048 + k * 1024); } while (0)
; #define G_MMA(ai, bj, At_, Bt_) do { __builtin_amdgcn_s_setprio(1); _Pragma("unroll") for (int m = 0; m < 4; ++m) _Pragma("unroll") for (int n = 0; n < 2; ++n) _Pragma("unroll") for (int k = 0; k < 2; ++k) \
;         acc[ai][bj][m][n] = __builtin_amdgcn_mfma_f32_16x16x32_bf16(Bt_[n][k], At_[m][k], acc[ai][bj][m][n], 0, 0, 0); __builtin_amdgcn_s_setprio(0); } while (0)
; #define WAIT_V(n) asm volatile("s_waitcnt vmcnt(" #n ")" ::: "memory")
; #define WAIT_L(n) asm volatile("s_waitcnt lgkmcnt(" #n ")" ::: "memory")
; #define BAR __builtin_amdgcn_s_barrier()
; template <class Get, class Epi>
; DI void gemm_loop(int ntiles, int ld, char* shm, const Get& get, const Epi& epi) {
;     ...
;         const int Ln = L + gridDim.x; const bool has_next = Ln < ntiles; if (has_next) nxt = get(Ln);
;         const char* nA = has_next ? (const char*)nxt.A + (size_t)nxt.brow * ld * 2 : cA; const char* nB = has_next ? (const char*)nxt.Bt + (size_t)nxt.bcol * ld * 2 : cB;
;         const int nt = cur.K / BK;
;         for (int t = 0; t < nt; t += 2) {
;             const bool last = (t == nt - 2);
;             const char* a1 = cA + (size_t)(t + 1) * kstep;
;             const char* a2 = last ? nA : cA + (size_t)(t + 2) * kstep; const char* b2 = last ? nB : cB + (size_t)(t + 2) * kstep;
;             const char* a3 = a2 + kstep; const char* b3 = b2 + kstep;
;             G_LDB(B0, 0, 0); G_LDB(B1, 0, 1); SCHED; G_LDA(At, 0, 0); G_STAGE(G_SA(1, 1), a1 + hstep, voffA);
;             WAIT_V(8); WAIT_L(0); BAR; G_MMA(0, 0, At, B0); G_MMA(0, 1, At, B1); BAR; SCHED;
;             G_LDA(At, 0, 1); G_STAGE(G_SB(0, 0), b2, voffB); G_STAGE(G_SB(0, 1), b2 + hstep, voffB); G_STAGE(G_SA(0, 0), a2, voffA);
.Lpeel_1781:
	ds_read_b128 v[128:131], v169
	ds_read_b128 v[132:135], v169 offset:1024
	ds_read_b128 v[136:139], v169 offset:2048
	ds_read_b128 v[140:143], v169 offset:3072
	ds_read_b128 v[158:161], v170
	ds_read_b128 v[162:165], v170 offset:1024
	ds_read_b128 v[172:175], v170 offset:2048
	ds_read_b128 v[176:179], v170 offset:3072
	s_add_i32 s77, s40, 2
	s_add_u32 s14, s4, 0x100
	s_addc_u32 s15, s5, 0
	s_cmp_eq_u32 s74, s40
	s_cselect_b32 s40, s38, s75
	s_cselect_b32 s43, s37, s15
	s_cselect_b32 s42, s36, s14
	s_cselect_b32 s41, s39, s76
	v_lshl_add_u64 v[144:145], s[4:5], 0, v[154:155]
	s_add_i32 m0, s45, 0xc000
	ds_read_b128 v[180:183], v171
	ds_read_b128 v[184:187], v171 offset:1024
	ds_read_b128 v[188:191], v171 offset:2048
	ds_read_b128 v[192:195], v171 offset:3072
	ds_read_b128 v[196:199], v171 offset:4096
	ds_read_b128 v[200:203], v171 offset:5120
	ds_read_b128 v[204:207], v171 offset:6144
	ds_read_b128 v[208:211], v171 offset:7168
	global_load_lds_dwordx4 v[144:145], off
	v_lshl_add_u64 v[144:145], s[4:5], 0, v[156:157]
	s_add_i32 m0, s45, 0xe000
	s_nop 0
	global_load_lds_dwordx4 v[144:145], off
	s_waitcnt vmcnt(8)
	s_waitcnt lgkmcnt(0)
	s_barrier
	s_setprio 1
	s_waitcnt lgkmcnt(0)
	v_mfma_f32_16x16x32_bf16 v[124:127], v[128:131], v[180:183], 0
	v_mfma_f32_16x16x32_bf16 v[120:123], v[136:139], v[180:183], 0
	v_mfma_f32_16x16x32_bf16 v[116:119], v[128:131], v[188:191], 0
	v_mfma_f32_16x16x32_bf16 v[112:115], v[136:139], v[188:191], 0
	v_mfma_f32_16x16x32_bf16 v[108:111], v[128:131], v[196:199], 0
	v_mfma_f32_16x16x32_bf16 v[104:107], v[136:139], v[196:199], 0
	v_mfma_f32_16x16x32_bf16 v[100:103], v[128:131], v[204:207], 0
	v_mfma_f32_16x16x32_bf16 v[96:99], v[136:139], v[204:207], 0
	v_mfma_f32_16x16x32_bf16 v[124:127], v[132:135], v[184:187], v[124:127]
	v_mfma_f32_16x16x32_bf16 v[120:123], v[140:143], v[184:187], v[120:123]
	v_mfma_f32_16x16x32_bf16 v[116:119], v[132:135], v[192:195], v[116:119]
	v_mfma_f32_16x16x32_bf16 v[112:115], v[140:143], v[192:195], v[112:115]
	v_mfma_f32_16x16x32_bf16 v[108:111], v[132:135], v[200:203], v[108:111]
	v_mfma_f32_16x16x32_bf16 v[104:107], v[140:143], v[200:203], v[104:107]
	v_mfma_f32_16x16x32_bf16 v[100:103], v[132:135], v[208:211], v[100:103]
	v_mfma_f32_16x16x32_bf16 v[96:99], v[140:143], v[208:211], v[96:99]
	s_setprio 0
	s_setprio 1
	v_mfma_f32_16x16x32_bf16 v[60:63], v[158:161], v[180:183], 0
	v_mfma_f32_16x16x32_bf16 v[56:59], v[172:175], v[180:183], 0
	v_mfma_f32_16x16x32_bf16 v[52:55], v[158:161], v[188:191], 0
	v_mfma_f32_16x16x32_bf16 v[48:51], v[172:175], v[188:191], 0
	v_mfma_f32_16x16x32_bf16 v[44:47], v[158:161], v[196:199], 0
	v_mfma_f32_16x16x32_bf16 v[40:43], v[172:175], v[196:199], 0
	v_mfma_f32_16x16x32_bf16 v[36:39], v[158:161], v[204:207], 0
	v_mfma_f32_16x16x32_bf16 v[32:35], v[172:175], v[204:207], 0
	v_mfma_f32_16x16x32_bf16 v[60:63], v[162:165], v[184:187], v[60:63]
	v_mfma_f32_16x16x32_bf16 v[56:59], v[176:179], v[184:187], v[56:59]
	v_mfma_f32_16x16x32_bf16 v[52:55], v[162:165], v[192:195], v[52:55]
	v_mfma_f32_16x16x32_bf16 v[48:51], v[176:179], v[192:195], v[48:51]
	v_mfma_f32_16x16x32_bf16 v[44:47], v[162:165], v[200:203], v[44:47]
	v_mfma_f32_16x16x32_bf16 v[40:43], v[176:179], v[200:203], v[40:43]
	v_mfma_f32_16x16x32_bf16 v[36:39], v[162:165], v[208:211], v[36:39]
	v_mfma_f32_16x16x32_bf16 v[32:35], v[176:179], v[208:211], v[32:35]
	s_setprio 0
	s_add_i32 s4, s53, s44
	v_lshl_add_u64 v[144:145], s[40:41], 0, v[148:149]
	s_mov_b32 m0, s4
	s_barrier
	ds_read_b128 v[180:183], v171 offset:16384
	ds_read_b128 v[184:187], v171 offset:17408
	ds_read_b128 v[188:191], v171 offset:18432
	ds_read_b128 v[192:195], v171 offset:19456
	ds_read_b128 v[196:199], v171 offset:20480
	ds_read_b128 v[200:203], v171 offset:21504
	ds_read_b128 v[204:207], v171 offset:22528
	ds_read_b128 v[208:211], v171 offset:23552
	global_load_lds_dwordx4 v[144:145], off
	s_add_i32 m0, s4, 0x2000
	s_add_u32 s4, s40, 0xb0000
	v_lshl_add_u64 v[166:167], s[40:41], 0, v[152:153]
	s_addc_u32 s5, s41, 0
	s_add_i32 s78, s54, s44
	global_load_lds_dwordx4 v[166:167], off
	v_lshl_add_u64 v[212:213], s[4:5], 0, v[148:149]
	s_mov_b32 m0, s78
	v_lshl_add_u64 v[214:215], s[42:43], 0, v[150:151]
	global_load_lds_dwordx4 v[212:213], off
	v_lshl_add_u64 v[212:213], s[4:5], 0, v[152:153]
	s_add_i32 m0, s78, 0x2000
	s_nop 0
	global_load_lds_dwordx4 v[212:213], off
	v_lshl_add_u64 v[212:213], s[42:43], 0, v[146:147]
	s_mov_b32 m0, s45
	s_nop 0
	global_load_lds_dwordx4 v[212:213], off
	s_mov_b32 m0, s46
	s_nop 0
	global_load_lds_dwordx4 v[214:215], off
	s_waitcnt vmcnt(8)
	s_waitcnt lgkmcnt(0)
	s_barrier
; #define G_STAGE(bufoff, gbase, voff) do { _Pragma("unroll") for (int _i = 0; _i < 2; ++_i) \
;         __builtin_amdgcn_global_load_lds((const unsigned*)((const char*)(gbase) + voff[_i]), (LAS unsigned*)(lds + (bufoff) + ldsw + _i * 8192), 16, 0, 0); } while (0)
; #define G_LDA(dst, b, h) do { _Pragma("unroll") for (int m = 0; m < 4; ++m) _Pragma("unroll") for (int k = 0; k < 2; ++k) dst[m][k] = *(const LAS bf16x8*)(lds + G_SA(b, h) + aoff + m * 2048 + k * 1024); } while (0)
; #define G_LDB(dst, b, h) do { _Pragma("unroll") for (int n = 0; n < 2; ++n) _Pragma("unroll") for (int k = 0; k < 2; ++k) dst[n][k] = *(const LAS bf16x8*)(lds + G_SB(b, h) + boff + n * 2048 + k * 1024); } while (0)
; #define G_MMA(ai, bj, At_, Bt_) do { __builtin_amdgcn_s_setprio(1); _Pragma("unroll") for (int m = 0; m < 4; ++m) _Pragma("unroll") for (int n = 0; n < 2; ++n) _Pragma("unroll") for (int k = 0; k < 2; ++k) \
;         acc[ai][bj][m][n] = __builtin_amdgcn_mfma_f32_16x16x32_bf16(Bt_[n][k], At_[m][k], acc[ai][bj][m][n], 0, 0, 0); __builtin_amdgcn_s_setprio(0); } while (0)
; #define WAIT_V(n) asm volatile("s_waitcnt vmcnt(" #n ")" ::: "memory")
; #define WAIT_L(n) asm volatile("s_waitcnt lgkmcnt(" #n ")" ::: "memory")
; #define BAR __builtin_amdgcn_s_barrier()
; #define SCHED __builtin_amdgcn_sched_barrier(0)
; template <class Get, class Epi>
; DI void gemm_loop(int ntiles, int ld, char* shm, const Get& get, const Epi& epi) {
;     ...
;             WAIT_V(8); WAIT_L(0); BAR; G_MMA(1, 0, At, B0); G_MMA(1, 1, At, B1); BAR; SCHED;
;             G_LDB(B0, 1, 0); G_LDB(B1, 1, 1); SCHED; G_LDA(At, 1, 0); G_STAGE(G_SA(0, 1), a2 + hstep, voffA);
;             WAIT_V(8); WAIT_L(0); BAR; G_MMA(0, 0, At, B0); G_MMA(0, 1, At, B1); BAR; SCHED;
	s_setprio 1
	s_waitcnt lgkmcnt(0)
	v_mfma_f32_16x16x32_bf16 v[92:95], v[128:131], v[180:183], 0
	v_mfma_f32_16x16x32_bf16 v[88:91], v[136:139], v[180:183], 0
	v_mfma_f32_16x16x32_bf16 v[84:87], v[128:131], v[188:191], 0
	v_mfma_f32_16x16x32_bf16 v[80:83], v[136:139], v[188:191], 0
	v_mfma_f32_16x16x32_bf16 v[76:79], v[128:131], v[196:199], 0
	v_mfma_f32_16x16x32_bf16 v[72:75], v[136:139], v[196:199], 0
	v_mfma_f32_16x16x32_bf16 v[68:71], v[128:131], v[204:207], 0
	v_mfma_f32_16x16x32_bf16 v[64:67], v[136:139], v[204:207], 0
	v_mfma_f32_16x16x32_bf16 v[92:95], v[132:135], v[184:187], v[92:95]
	v_mfma_f32_16x16x32_bf16 v[88:91], v[140:143], v[184:187], v[88:91]
	v_mfma_f32_16x16x32_bf16 v[84:87], v[132:135], v[192:195], v[84:87]
	v_mfma_f32_16x16x32_bf16 v[80:83], v[140:143], v[192:195], v[80:83]
	v_mfma_f32_16x16x32_bf16 v[76:79], v[132:135], v[200:203], v[76:79]
	v_mfma_f32_16x16x32_bf16 v[72:75], v[140:143], v[200:203], v[72:75]
	v_mfma_f32_16x16x32_bf16 v[68:71], v[132:135], v[208:211], v[68:71]
	v_mfma_f32_16x16x32_bf16 v[64:67], v[140:143], v[208:211], v[64:67]
	s_setprio 0
	s_setprio 1
	v_mfma_f32_16x16x32_bf16 v[28:31], v[158:161], v[180:183], 0
	v_mfma_f32_16x16x32_bf16 v[24:27], v[172:175], v[180:183], 0
	v_mfma_f32_16x16x32_bf16 v[20:23], v[158:161], v[188:191], 0
	v_mfma_f32_16x16x32_bf16 v[16:19], v[172:175], v[188:191], 0
	v_mfma_f32_16x16x32_bf16 v[12:15], v[158:161], v[196:199], 0
	v_mfma_f32_16x16x32_bf16 v[8:11], v[172:175], v[196:199], 0
	v_mfma_f32_16x16x32_bf16 v[4:7], v[158:161], v[204:207], 0
	v_mfma_f32_16x16x32_bf16 v[0:3], v[172:175], v[204:207], 0
	v_mfma_f32_16x16x32_bf16 v[28:31], v[162:165], v[184:187], v[28:31]
	v_mfma_f32_16x16x32_bf16 v[24:27], v[176:179], v[184:187], v[24:27]
	v_mfma_f32_16x16x32_bf16 v[20:23], v[162:165], v[192:195], v[20:23]
	v_mfma_f32_16x16x32_bf16 v[16:19], v[176:179], v[192:195], v[16:19]
	v_mfma_f32_16x16x32_bf16 v[12:15], v[162:165], v[200:203], v[12:15]
	v_mfma_f32_16x16x32_bf16 v[8:11], v[176:179], v[200:203], v[8:11]
	v_mfma_f32_16x16x32_bf16 v[4:7], v[162:165], v[208:211], v[4:7]
	v_mfma_f32_16x16x32_bf16 v[0:3], v[176:179], v[208:211], v[0:3]
	s_setprio 0
	s_add_i32 s78, 0, 0x18000
	s_add_i32 s79, 0, 0x1c000
	v_add_u32_e32 v140, s78, v168
	s_barrier
	v_add_u32_e32 v176, s79, v168
	ds_read_b128 v[128:131], v140
	ds_read_b128 v[132:135], v140 offset:1024
	ds_read_b128 v[136:139], v140 offset:2048
	ds_read_b128 v[140:143], v140 offset:3072
	ds_read_b128 v[158:161], v176
	ds_read_b128 v[162:165], v176 offset:1024
	ds_read_b128 v[172:175], v176 offset:2048
	ds_read_b128 v[176:179], v176 offset:3072
	s_add_u32 s4, s42, 0xb0000
	s_addc_u32 s5, s43, 0
	s_mov_b32 m0, s47
	v_lshl_add_u64 v[216:217], s[4:5], 0, v[146:147]
	ds_read_b128 v[180:183], v171 offset:32768
	ds_read_b128 v[184:187], v171 offset:33792
	ds_read_b128 v[188:191], v171 offset:34816
	ds_read_b128 v[192:195], v171 offset:35840
	ds_read_b128 v[196:199], v171 offset:36864
	ds_read_b128 v[200:203], v171 offset:37888
	ds_read_b128 v[204:207], v171 offset:38912
	ds_read_b128 v[208:211], v171 offset:39936
	global_load_lds_dwordx4 v[216:217], off
	v_lshl_add_u64 v[216:217], s[4:5], 0, v[150:151]
	s_mov_b32 m0, s48
	s_nop 0
	global_load_lds_dwordx4 v[216:217], off
	s_waitcnt vmcnt(8)
	s_waitcnt lgkmcnt(0)
	s_barrier
	s_setprio 1
	s_waitcnt lgkmcnt(0)
	v_mfma_f32_16x16x32_bf16 v[124:127], v[128:131], v[180:183], v[124:127]
	v_mfma_f32_16x16x32_bf16 v[120:123], v[136:139], v[180:183], v[120:123]
	v_mfma_f32_16x16x32_bf16 v[116:119], v[128:131], v[188:191], v[116:119]
	v_mfma_f32_16x16x32_bf16 v[112:115], v[136:139], v[188:191], v[112:115]
	v_mfma_f32_16x16x32_bf16 v[108:111], v[128:131], v[196:199], v[108:111]
	v_mfma_f32_16x16x32_bf16 v[104:107], v[136:139], v[196:199], v[104:107]
	v_mfma_f32_16x16x32_bf16 v[100:103], v[128:131], v[204:207], v[100:103]
	v_mfma_f32_16x16x32_bf16 v[96:99], v[136:139], v[204:207], v[96:99]
	v_mfma_f32_16x16x32_bf16 v[124:127], v[132:135], v[184:187], v[124:127]
	v_mfma_f32_16x16x32_bf16 v[120:123], v[140:143], v[184:187], v[120:123]
	v_mfma_f32_16x16x32_bf16 v[116:119], v[132:135], v[192:195], v[116:119]
	v_mfma_f32_16x16x32_bf16 v[112:115], v[140:143], v[192:195], v[112:115]
	v_mfma_f32_16x16x32_bf16 v[108:111], v[132:135], v[200:203], v[108:111]
	v_mfma_f32_16x16x32_bf16 v[104:107], v[140:143], v[200:203], v[104:107]
	v_mfma_f32_16x16x32_bf16 v[100:103], v[132:135], v[208:211], v[100:103]
	v_mfma_f32_16x16x32_bf16 v[96:99], v[140:143], v[208:211], v[96:99]
	s_setprio 0
	s_setprio 1
	v_mfma_f32_16x16x32_bf16 v[60:63], v[158:161], v[180:183], v[60:63]
	v_mfma_f32_16x16x32_bf16 v[56:59], v[172:175], v[180:183], v[56:59]
	v_mfma_f32_16x16x32_bf16 v[52:55], v[158:161], v[188:191], v[52:55]
	v_mfma_f32_16x16x32_bf16 v[48:51], v[172:175], v[188:191], v[48:51]
	v_mfma_f32_16x16x32_bf16 v[44:47], v[158:161], v[196:199], v[44:47]
	v_mfma_f32_16x16x32_bf16 v[40:43], v[172:175], v[196:199], v[40:43]
	v_mfma_f32_16x16x32_bf16 v[36:39], v[158:161], v[204:207], v[36:39]
	v_mfma_f32_16x16x32_bf16 v[32:35], v[172:175], v[204:207], v[32:35]
	v_mfma_f32_16x16x32_bf16 v[60:63], v[162:165], v[184:187], v[60:63]
	v_mfma_f32_16x16x32_bf16 v[56:59], v[176:179], v[184:187], v[56:59]
	v_mfma_f32_16x16x32_bf16 v[52:55], v[162:165], v[192:195], v[52:55]
	v_mfma_f32_16x16x32_bf16 v[48:51], v[176:179], v[192:195], v[48:51]
	v_mfma_f32_16x16x32_bf16 v[44:47], v[162:165], v[200:203], v[44:47]
	v_mfma_f32_16x16x32_bf16 v[40:43], v[176:179], v[200:203], v[40:43]
	v_mfma_f32_16x16x32_bf16 v[36:39], v[162:165], v[208:211], v[36:39]
	v_mfma_f32_16x16x32_bf16 v[32:35], v[176:179], v[208:211], v[32:35]
	s_setprio 0
	s_add_i32 s4, s78, s44
	v_lshl_add_u64 v[144:145], v[144:145], 0, s[10:11]
	s_mov_b32 m0, s4
	s_barrier
; #define G_STAGE(bufoff, gbase, voff) do { _Pragma("unroll") for (int _i = 0; _i < 2; ++_i) \
;         __builtin_amdgcn_global_load_lds((const unsigned*)((const char*)(gbase) + voff[_i]), (LAS unsigned*)(lds + (bufoff) + ldsw + _i * 8192), 16, 0, 0); } while (0)
; #define G_LDA(dst, b, h) do { _Pragma("unroll") for (int m = 0; m < 4; ++m) _Pragma("unroll") for (int k = 0; k < 2; ++k) dst[m][k] = *(const LAS bf16x8*)(lds + G_SA(b, h) + aoff + m * 2048 + k * 1024); } while (0)
; #define G_LDB(dst, b, h) do { _Pragma("unroll") for (int n = 0; n < 2; ++n) _Pragma("unroll") for (int k = 0; k < 2; ++k) dst[n][k] = *(const LAS bf16x8*)(lds + G_SB(b, h) + boff + n * 2048 + k * 1024); } while (0)
; #define G_MMA(ai, bj, At_, Bt_) do { __builtin_amdgcn_s_setprio(1); _Pragma("unroll") for (int m = 0; m < 4; ++m) _Pragma("unroll") for (int n = 0; n < 2; ++n) _Pragma("unroll") for (int k = 0; k < 2; ++k) \
;         acc[ai][bj][m][n] = __builtin_amdgcn_mfma_f32_16x16x32_bf16(Bt_[n][k], At_[m][k], acc[ai][bj][m][n], 0, 0, 0); __builtin_amdgcn_s_setprio(0); } while (0)
; #define WAIT_V(n) asm volatile("s_waitcnt vmcnt(" #n ")" ::: "memory")
; #define WAIT_L(n) asm volatile("s_waitcnt lgkmcnt(" #n ")" ::: "memory")
; #define BAR __builtin_amdgcn_s_barrier()
; #define SCHED __builtin_amdgcn_sched_barrier(0)
; template <class Get, class Epi>
; DI void gemm_loop(int ntiles, int ld, char* shm, const Get& get, const Epi& epi) {
;     ...
;             G_LDB(B0, 0, 0); G_LDB(B1, 0, 1); SCHED; G_LDA(At, 0, 0); G_STAGE(G_SA(1, 1), a1 + hstep, voffA);
;             WAIT_V(8); WAIT_L(0); BAR; G_MMA(0, 0, At, B0); G_MMA(0, 1, At, B1); BAR; SCHED;
;     ...
;             G_LDA(At, 1, 1); G_STAGE(G_SB(1, 0), b3, voffB); G_STAGE(G_SB(1, 1), b3 + hstep, voffB); G_STAGE(G_SA(1, 0), a3, voffA);
;             WAIT_V(8); WAIT_L(0); BAR; G_MMA(1, 0, At, B0); G_MMA(1, 1, At, B1); BAR; SCHED;
	ds_read_b128 v[180:183], v171 offset:49152
	ds_read_b128 v[184:187], v171 offset:50176
	ds_read_b128 v[188:191], v171 offset:51200
	ds_read_b128 v[192:195], v171 offset:52224
	ds_read_b128 v[196:199], v171 offset:53248
	ds_read_b128 v[200:203], v171 offset:54272
	ds_read_b128 v[204:207], v171 offset:55296
	ds_read_b128 v[208:211], v171 offset:56320
	global_load_lds_dwordx4 v[144:145], off
	s_add_i32 m0, s4, 0x2000
	s_add_u32 s4, s40, 0xb0080
	v_lshl_add_u64 v[144:145], v[166:167], 0, s[10:11]
	s_addc_u32 s5, s41, 0
	s_add_i32 s40, s79, s44
	global_load_lds_dwordx4 v[144:145], off
	v_lshl_add_u64 v[144:145], s[4:5], 0, v[148:149]
	s_mov_b32 m0, s40
	s_nop 0
	global_load_lds_dwordx4 v[144:145], off
	v_lshl_add_u64 v[144:145], s[4:5], 0, v[152:153]
	s_add_i32 m0, s40, 0x2000
	s_nop 0
	global_load_lds_dwordx4 v[144:145], off
	v_lshl_add_u64 v[144:145], v[212:213], 0, s[10:11]
	s_mov_b32 m0, s51
	s_nop 0
	global_load_lds_dwordx4 v[144:145], off
	v_lshl_add_u64 v[144:145], v[214:215], 0, s[10:11]
	s_mov_b32 m0, s52
	s_nop 0
	global_load_lds_dwordx4 v[144:145], off
	s_waitcnt vmcnt(8)
	s_waitcnt lgkmcnt(0)
	s_barrier
	s_setprio 1
	s_waitcnt lgkmcnt(0)
	v_mfma_f32_16x16x32_bf16 v[92:95], v[128:131], v[180:183], v[92:95]
	v_mfma_f32_16x16x32_bf16 v[88:91], v[136:139], v[180:183], v[88:91]
	v_mfma_f32_16x16x32_bf16 v[84:87], v[128:131], v[188:191], v[84:87]
	v_mfma_f32_16x16x32_bf16 v[80:83], v[136:139], v[188:191], v[80:83]
	v_mfma_f32_16x16x32_bf16 v[76:79], v[128:131], v[196:199], v[76:79]
	v_mfma_f32_16x16x32_bf16 v[72:75], v[136:139], v[196:199], v[72:75]
	v_mfma_f32_16x16x32_bf16 v[68:71], v[128:131], v[204:207], v[68:71]
	v_mfma_f32_16x16x32_bf16 v[64:67], v[136:139], v[204:207], v[64:67]
	v_mfma_f32_16x16x32_bf16 v[92:95], v[132:135], v[184:187], v[92:95]
	v_mfma_f32_16x16x32_bf16 v[88:91], v[140:143], v[184:187], v[88:91]
	v_mfma_f32_16x16x32_bf16 v[84:87], v[132:135], v[192:195], v[84:87]
	v_mfma_f32_16x16x32_bf16 v[80:83], v[140:143], v[192:195], v[80:83]
	v_mfma_f32_16x16x32_bf16 v[76:79], v[132:135], v[200:203], v[76:79]
	v_mfma_f32_16x16x32_bf16 v[72:75], v[140:143], v[200:203], v[72:75]
	v_mfma_f32_16x16x32_bf16 v[68:71], v[132:135], v[208:211], v[68:71]
	v_mfma_f32_16x16x32_bf16 v[64:67], v[140:143], v[208:211], v[64:67]
	s_setprio 0
	s_setprio 1
	v_mfma_f32_16x16x32_bf16 v[28:31], v[158:161], v[180:183], v[28:31]
	v_mfma_f32_16x16x32_bf16 v[24:27], v[172:175], v[180:183], v[24:27]
	v_mfma_f32_16x16x32_bf16 v[20:23], v[158:161], v[188:191], v[20:23]
	v_mfma_f32_16x16x32_bf16 v[16:19], v[172:175], v[188:191], v[16:19]
	v_mfma_f32_16x16x32_bf16 v[12:15], v[158:161], v[196:199], v[12:15]
	v_mfma_f32_16x16x32_bf16 v[8:11], v[172:175], v[196:199], v[8:11]
	v_mfma_f32_16x16x32_bf16 v[4:7], v[158:161], v[204:207], v[4:7]
	v_mfma_f32_16x16x32_bf16 v[0:3], v[172:175], v[204:207], v[0:3]
	v_mfma_f32_16x16x32_bf16 v[28:31], v[162:165], v[184:187], v[28:31]
	v_mfma_f32_16x16x32_bf16 v[24:27], v[176:179], v[184:187], v[24:27]
	v_mfma_f32_16x16x32_bf16 v[20:23], v[162:165], v[192:195], v[20:23]
	v_mfma_f32_16x16x32_bf16 v[16:19], v[176:179], v[192:195], v[16:19]
	v_mfma_f32_16x16x32_bf16 v[12:15], v[162:165], v[200:203], v[12:15]
	v_mfma_f32_16x16x32_bf16 v[8:11], v[176:179], v[200:203], v[8:11]
	v_mfma_f32_16x16x32_bf16 v[4:7], v[162:165], v[208:211], v[4:7]
	v_mfma_f32_16x16x32_bf16 v[0:3], v[176:179], v[208:211], v[0:3]
	s_setprio 0
	s_add_u32 s75, s75, 0x100
	s_addc_u32 s76, s76, 0
	s_cmp_ge_u32 s77, s73
	s_mov_b64 s[4:5], s[14:15]
	s_mov_b32 s40, s77
	s_barrier
	s_cbranch_scc0 .LBB0_1781
	s_branch .Lpost_1781
.LBB0_1781:
	ds_read_b128 v[128:131], v169
	ds_read_b128 v[132:135], v169 offset:1024
	ds_read_b128 v[136:139], v169 offset:2048
	ds_read_b128 v[140:143], v169 offset:3072
	ds_read_b128 v[158:161], v170
	ds_read_b128 v[162:165], v170 offset:1024
	ds_read_b128 v[172:175], v170 offset:2048
	ds_read_b128 v[176:179], v170 offset:3072
	s_add_i32 s77, s40, 2
	s_add_u32 s14, s4, 0x100
	s_addc_u32 s15, s5, 0
	s_cmp_eq_u32 s74, s40
	s_cselect_b32 s40, s38, s75
	s_cselect_b32 s43, s37, s15
	s_cselect_b32 s42, s36, s14
	s_cselect_b32 s41, s39, s76
	v_lshl_add_u64 v[144:145], s[4:5], 0, v[154:155]
	s_add_i32 m0, s45, 0xc000
	ds_read_b128 v[180:183], v171
	ds_read_b128 v[184:187], v171 offset:1024
	ds_read_b128 v[188:191], v171 offset:2048
	ds_read_b128 v[192:195], v171 offset:3072
	ds_read_b128 v[196:199], v171 offset:4096
	ds_read_b128 v[200:203], v171 offset:5120
	ds_read_b128 v[204:207], v171 offset:6144
	ds_read_b128 v[208:211], v171 offset:7168
	global_load_lds_dwordx4 v[144:145], off
	v_lshl_add_u64 v[144:145], s[4:5], 0, v[156:157]
	s_add_i32 m0, s45, 0xe000
	s_nop 0
	global_load_lds_dwordx4 v[144:145], off
	s_waitcnt vmcnt(8)
	s_waitcnt lgkmcnt(0)
	s_barrier
; #define G_STAGE(bufoff, gbase, voff) do { _Pragma("unroll") for (int _i = 0; _i < 2; ++_i) \
;         __builtin_amdgcn_global_load_lds((const unsigned*)((const char*)(gbase) + voff[_i]), (LAS unsigned*)(lds + (bufoff) + ldsw + _i * 8192), 16, 0, 0); } while (0)
; #define G_LDA(dst, b, h) do { _Pragma("unroll") for (int m = 0; m < 4; ++m) _Pragma("unroll") for (int k = 0; k < 2; ++k) dst[m][k] = *(const LAS bf16x8*)(lds + G_SA(b, h) + aoff + m * 2048 + k * 1024); } while (0)
; #define G_MMA(ai, bj, At_, Bt_) do { __builtin_amdgcn_s_setprio(1); _Pragma("unroll") for (int m = 0; m < 4; ++m) _Pragma("unroll") for (int n = 0; n < 2; ++n) _Pragma("unroll") for (int k = 0; k < 2; ++k) \
;         acc[ai][bj][m][n] = __builtin_amdgcn_mfma_f32_16x16x32_bf16(Bt_[n][k], At_[m][k], acc[ai][bj][m][n], 0, 0, 0); __builtin_amdgcn_s_setprio(0); } while (0)
; #define WAIT_V(n) asm volatile("s_waitcnt vmcnt(" #n ")" ::: "memory")
; #define WAIT_L(n) asm volatile("s_waitcnt lgkmcnt(" #n ")" ::: "memory")
; #define BAR __builtin_amdgcn_s_barrier()
; #define SCHED __builtin_amdgcn_sched_barrier(0)
; template <class Get, class Epi>
; DI void gemm_loop(int ntiles, int ld, char* shm, const Get& get, const Epi& epi) {
;     ...
;             WAIT_V(8); WAIT_L(0); BAR; G_MMA(0, 0, At, B0); G_MMA(0, 1, At, B1); BAR; SCHED;
;             G_LDA(At, 0, 1); G_STAGE(G_SB(0, 0), b2, voffB); G_STAGE(G_SB(0, 1), b2 + hstep, voffB); G_STAGE(G_SA(0, 0), a2, voffA);
;             WAIT_V(8); WAIT_L(0); BAR; G_MMA(1, 0, At, B0); G_MMA(1, 1, At, B1); BAR; SCHED;
	s_setprio 1
	s_waitcnt lgkmcnt(0)
	v_mfma_f32_16x16x32_bf16 v[124:127], v[128:131], v[180:183], v[124:127]
	v_mfma_f32_16x16x32_bf16 v[120:123], v[136:139], v[180:183], v[120:123]
	v_mfma_f32_16x16x32_bf16 v[116:119], v[128:131], v[188:191], v[116:119]
	v_mfma_f32_16x16x32_bf16 v[112:115], v[136:139], v[188:191], v[112:115]
	v_mfma_f32_16x16x32_bf16 v[108:111], v[128:131], v[196:199], v[108:111]
	v_mfma_f32_16x16x32_bf16 v[104:107], v[136:139], v[196:199], v[104:107]
	v_mfma_f32_16x16x32_bf16 v[100:103], v[128:131], v[204:207], v[100:103]
	v_mfma_f32_16x16x32_bf16 v[96:99], v[136:139], v[204:207], v[96:99]
	v_mfma_f32_16x16x32_bf16 v[124:127], v[132:135], v[184:187], v[124:127]
	v_mfma_f32_16x16x32_bf16 v[120:123], v[140:143], v[184:187], v[120:123]
	v_mfma_f32_16x16x32_bf16 v[116:119], v[132:135], v[192:195], v[116:119]
	v_mfma_f32_16x16x32_bf16 v[112:115], v[140:143], v[192:195], v[112:115]
	v_mfma_f32_16x16x32_bf16 v[108:111], v[132:135], v[200:203], v[108:111]
	v_mfma_f32_16x16x32_bf16 v[104:107], v[140:143], v[200:203], v[104:107]
	v_mfma_f32_16x16x32_bf16 v[100:103], v[132:135], v[208:211], v[100:103]
	v_mfma_f32_16x16x32_bf16 v[96:99], v[140:143], v[208:211], v[96:99]
	s_setprio 0
	s_setprio 1
	v_mfma_f32_16x16x32_bf16 v[60:63], v[158:161], v[180:183], v[60:63]
	v_mfma_f32_16x16x32_bf16 v[56:59], v[172:175], v[180:183], v[56:59]
	v_mfma_f32_16x16x32_bf16 v[52:55], v[158:161], v[188:191], v[52:55]
	v_mfma_f32_16x16x32_bf16 v[48:51], v[172:175], v[188:191], v[48:51]
	v_mfma_f32_16x16x32_bf16 v[44:47], v[158:161], v[196:199], v[44:47]
	v_mfma_f32_16x16x32_bf16 v[40:43], v[172:175], v[196:199], v[40:43]
	v_mfma_f32_16x16x32_bf16 v[36:39], v[158:161], v[204:207], v[36:39]
	v_mfma_f32_16x16x32_bf16 v[32:35], v[172:175], v[204:207], v[32:35]
	v_mfma_f32_16x16x32_bf16 v[60:63], v[162:165], v[184:187], v[60:63]
	v_mfma_f32_16x16x32_bf16 v[56:59], v[176:179], v[184:187], v[56:59]
	v_mfma_f32_16x16x32_bf16 v[52:55], v[162:165], v[192:195], v[52:55]
	v_mfma_f32_16x16x32_bf16 v[48:51], v[176:179], v[192:195], v[48:51]
	v_mfma_f32_16x16x32_bf16 v[44:47], v[162:165], v[200:203], v[44:47]
	v_mfma_f32_16x16x32_bf16 v[40:43], v[176:179], v[200:203], v[40:43]
	v_mfma_f32_16x16x32_bf16 v[36:39], v[162:165], v[208:211], v[36:39]
	v_mfma_f32_16x16x32_bf16 v[32:35], v[176:179], v[208:211], v[32:35]
	s_setprio 0
	s_add_i32 s4, s53, s44
	v_lshl_add_u64 v[144:145], s[40:41], 0, v[148:149]
	s_mov_b32 m0, s4
	s_barrier
	ds_read_b128 v[180:183], v171 offset:16384
	ds_read_b128 v[184:187], v171 offset:17408
	ds_read_b128 v[188:191], v171 offset:18432
	ds_read_b128 v[192:195], v171 offset:19456
	ds_read_b128 v[196:199], v171 offset:20480
	ds_read_b128 v[200:203], v171 offset:21504
	ds_read_b128 v[204:207], v171 offset:22528
	ds_read_b128 v[208:211], v171 offset:23552
	global_load_lds_dwordx4 v[144:145], off
	s_add_i32 m0, s4, 0x2000
	s_add_u32 s4, s40, 0xb0000
	v_lshl_add_u64 v[166:167], s[40:41], 0, v[152:153]
	s_addc_u32 s5, s41, 0
	s_add_i32 s78, s54, s44
	global_load_lds_dwordx4 v[166:167], off
	v_lshl_add_u64 v[212:213], s[4:5], 0, v[148:149]
	s_mov_b32 m0, s78
	v_lshl_add_u64 v[214:215], s[42:43], 0, v[150:151]
	global_load_lds_dwordx4 v[212:213], off
	v_lshl_add_u64 v[212:213], s[4:5], 0, v[152:153]
	s_add_i32 m0, s78, 0x2000
	s_nop 0
	global_load_lds_dwordx4 v[212:213], off
	v_lshl_add_u64 v[212:213], s[42:43], 0, v[146:147]
	s_mov_b32 m0, s45
	s_nop 0
	global_load_lds_dwordx4 v[212:213], off
	s_mov_b32 m0, s46
	s_nop 0
	global_load_lds_dwordx4 v[214:215], off
	s_waitcnt vmcnt(8)
	s_waitcnt lgkmcnt(0)
	s_barrier
	s_setprio 1
	s_waitcnt lgkmcnt(0)
	v_mfma_f32_16x16x32_bf16 v[92:95], v[128:131], v[180:183], v[92:95]
	v_mfma_f32_16x16x32_bf16 v[88:91], v[136:139], v[180:183], v[88:91]
	v_mfma_f32_16x16x32_bf16 v[84:87], v[128:131], v[188:191], v[84:87]
	v_mfma_f32_16x16x32_bf16 v[80:83], v[136:139], v[188:191], v[80:83]
	v_mfma_f32_16x16x32_bf16 v[76:79], v[128:131], v[196:199], v[76:79]
	v_mfma_f32_16x16x32_bf16 v[72:75], v[136:139], v[196:199], v[72:75]
	v_mfma_f32_16x16x32_bf16 v[68:71], v[128:131], v[204:207], v[68:71]
	v_mfma_f32_16x16x32_bf16 v[64:67], v[136:139], v[204:207], v[64:67]
	v_mfma_f32_16x16x32_bf16 v[92:95], v[132:135], v[184:187], v[92:95]
	v_mfma_f32_16x16x32_bf16 v[88:91], v[140:143], v[184:187], v[88:91]
	v_mfma_f32_16x16x32_bf16 v[84:87], v[132:135], v[192:195], v[84:87]
	v_mfma_f32_16x16x32_bf16 v[80:83], v[140:143], v[192:195], v[80:83]
	v_mfma_f32_16x16x32_bf16 v[76:79], v[132:135], v[200:203], v[76:79]
	v_mfma_f32_16x16x32_bf16 v[72:75], v[140:143], v[200:203], v[72:75]
	v_mfma_f32_16x16x32_bf16 v[68:71], v[132:135], v[208:211], v[68:71]
	v_mfma_f32_16x16x32_bf16 v[64:67], v[140:143], v[208:211], v[64:67]
	s_setprio 0
	s_setprio 1
	v_mfma_f32_16x16x32_bf16 v[28:31], v[158:161], v[180:183], v[28:31]
	v_mfma_f32_16x16x32_bf16 v[24:27], v[172:175], v[180:183], v[24:27]
	v_mfma_f32_16x16x32_bf16 v[20:23], v[158:161], v[188:191], v[20:23]
	v_mfma_f32_16x16x32_bf16 v[16:19], v[172:175], v[188:191], v[16:19]
	v_mfma_f32_16x16x32_bf16 v[12:15], v[158:161], v[196:199], v[12:15]
	v_mfma_f32_16x16x32_bf16 v[8:11], v[172:175], v[196:199], v[8:11]
	v_mfma_f32_16x16x32_bf16 v[4:7], v[158:161], v[204:207], v[4:7]
	v_mfma_f32_16x16x32_bf16 v[0:3], v[172:175], v[204:207], v[0:3]
	v_mfma_f32_16x16x32_bf16 v[28:31], v[162:165], v[184:187], v[28:31]
	v_mfma_f32_16x16x32_bf16 v[24:27], v[176:179], v[184:187], v[24:27]
	v_mfma_f32_16x16x32_bf16 v[20:23], v[162:165], v[192:195], v[20:23]
	v_mfma_f32_16x16x32_bf16 v[16:19], v[176:179], v[192:195], v[16:19]
	v_mfma_f32_16x16x32_bf16 v[12:15], v[162:165], v[200:203], v[12:15]
	v_mfma_f32_16x16x32_bf16 v[8:11], v[176:179], v[200:203], v[8:11]
	v_mfma_f32_16x16x32_bf16 v[4:7], v[162:165], v[208:211], v[4:7]
	v_mfma_f32_16x16x32_bf16 v[0:3], v[176:179], v[208:211], v[0:3]
	s_setprio 0
	s_add_i32 s78, 0, 0x18000
	s_add_i32 s79, 0, 0x1c000
	v_add_u32_e32 v140, s78, v168
	s_barrier
; #define G_STAGE(bufoff, gbase, voff) do { _Pragma("unroll") for (int _i = 0; _i < 2; ++_i) \
;         __builtin_amdgcn_global_load_lds((const unsigned*)((const char*)(gbase) + voff[_i]), (LAS unsigned*)(lds + (bufoff) + ldsw + _i * 8192), 16, 0, 0); } while (0)
; #define G_LDA(dst, b, h) do { _Pragma("unroll") for (int m = 0; m < 4; ++m) _Pragma("unroll") for (int k = 0; k < 2; ++k) dst[m][k] = *(const LAS bf16x8*)(lds + G_SA(b, h) + aoff + m * 2048 + k * 1024); } while (0)
; #define G_LDB(dst, b, h) do { _Pragma("unroll") for (int n = 0; n < 2; ++n) _Pragma("unroll") for (int k = 0; k < 2; ++k) dst[n][k] = *(const LAS bf16x8*)(lds + G_SB(b, h) + boff + n * 2048 + k * 1024); } while (0)
; #define G_MMA(ai, bj, At_, Bt_) do { __builtin_amdgcn_s_setprio(1); _Pragma("unroll") for (int m = 0; m < 4; ++m) _Pragma("unroll") for (int n = 0; n < 2; ++n) _Pragma("unroll") for (int k = 0; k < 2; ++k) \
;         acc[ai][bj][m][n] = __builtin_amdgcn_mfma_f32_16x16x32_bf16(Bt_[n][k], At_[m][k], acc[ai][bj][m][n], 0, 0, 0); __builtin_amdgcn_s_setprio(0); } while (0)
; #define WAIT_V(n) asm volatile("s_waitcnt vmcnt(" #n ")" ::: "memory")
; #define WAIT_L(n) asm volatile("s_waitcnt lgkmcnt(" #n ")" ::: "memory")
; #define BAR __builtin_amdgcn_s_barrier()
; #define SCHED __builtin_amdgcn_sched_barrier(0)
; template <class Get, class Epi>
; DI void gemm_loop(int ntiles, int ld, char* shm, const Get& get, const Epi& epi) {
;     ...
;             G_LDB(B0, 1, 0); G_LDB(B1, 1, 1); SCHED; G_LDA(At, 1, 0); G_STAGE(G_SA(0, 1), a2 + hstep, voffA);
;             WAIT_V(8); WAIT_L(0); BAR; G_MMA(0, 0, At, B0); G_MMA(0, 1, At, B1); BAR; SCHED;
;             G_LDA(At, 1, 1); G_STAGE(G_SB(1, 0), b3, voffB); G_STAGE(G_SB(1, 1), b3 + hstep, voffB); G_STAGE(G_SA(1, 0), a3, voffA);
;             WAIT_V(8); WAIT_L(0); BAR; G_MMA(1, 0, At, B0); G_MMA(1, 1, At, B1); BAR; SCHED;
;         }
	v_add_u32_e32 v176, s79, v168
	ds_read_b128 v[128:131], v140
	ds_read_b128 v[132:135], v140 offset:1024
	ds_read_b128 v[136:139], v140 offset:2048
	ds_read_b128 v[140:143], v140 offset:3072
	ds_read_b128 v[158:161], v176
	ds_read_b128 v[162:165], v176 offset:1024
	ds_read_b128 v[172:175], v176 offset:2048
	ds_read_b128 v[176:179], v176 offset:3072
	s_add_u32 s4, s42, 0xb0000
	s_addc_u32 s5, s43, 0
	s_mov_b32 m0, s47
	v_lshl_add_u64 v[216:217], s[4:5], 0, v[146:147]
	ds_read_b128 v[180:183], v171 offset:32768
	ds_read_b128 v[184:187], v171 offset:33792
	ds_read_b128 v[188:191], v171 offset:34816
	ds_read_b128 v[192:195], v171 offset:35840
	ds_read_b128 v[196:199], v171 offset:36864
	ds_read_b128 v[200:203], v171 offset:37888
	ds_read_b128 v[204:207], v171 offset:38912
	ds_read_b128 v[208:211], v171 offset:39936
	global_load_lds_dwordx4 v[216:217], off
	v_lshl_add_u64 v[216:217], s[4:5], 0, v[150:151]
	s_mov_b32 m0, s48
	s_nop 0
	global_load_lds_dwordx4 v[216:217], off
	s_waitcnt vmcnt(8)
	s_waitcnt lgkmcnt(0)
	s_barrier
	s_setprio 1
	s_waitcnt lgkmcnt(0)
	v_mfma_f32_16x16x32_bf16 v[124:127], v[128:131], v[180:183], v[124:127]
	v_mfma_f32_16x16x32_bf16 v[120:123], v[136:139], v[180:183], v[120:123]
	v_mfma_f32_16x16x32_bf16 v[116:119], v[128:131], v[188:191], v[116:119]
	v_mfma_f32_16x16x32_bf16 v[112:115], v[136:139], v[188:191], v[112:115]
	v_mfma_f32_16x16x32_bf16 v[108:111], v[128:131], v[196:199], v[108:111]
	v_mfma_f32_16x16x32_bf16 v[104:107], v[136:139], v[196:199], v[104:107]
	v_mfma_f32_16x16x32_bf16 v[100:103], v[128:131], v[204:207], v[100:103]
	v_mfma_f32_16x16x32_bf16 v[96:99], v[136:139], v[204:207], v[96:99]
	v_mfma_f32_16x16x32_bf16 v[124:127], v[132:135], v[184:187], v[124:127]
	v_mfma_f32_16x16x32_bf16 v[120:123], v[140:143], v[184:187], v[120:123]
	v_mfma_f32_16x16x32_bf16 v[116:119], v[132:135], v[192:195], v[116:119]
	v_mfma_f32_16x16x32_bf16 v[112:115], v[140:143], v[192:195], v[112:115]
	v_mfma_f32_16x16x32_bf16 v[108:111], v[132:135], v[200:203], v[108:111]
	v_mfma_f32_16x16x32_bf16 v[104:107], v[140:143], v[200:203], v[104:107]
	v_mfma_f32_16x16x32_bf16 v[100:103], v[132:135], v[208:211], v[100:103]
	v_mfma_f32_16x16x32_bf16 v[96:99], v[140:143], v[208:211], v[96:99]
	s_setprio 0
	s_setprio 1
	v_mfma_f32_16x16x32_bf16 v[60:63], v[158:161], v[180:183], v[60:63]
	v_mfma_f32_16x16x32_bf16 v[56:59], v[172:175], v[180:183], v[56:59]
	v_mfma_f32_16x16x32_bf16 v[52:55], v[158:161], v[188:191], v[52:55]
	v_mfma_f32_16x16x32_bf16 v[48:51], v[172:175], v[188:191], v[48:51]
	v_mfma_f32_16x16x32_bf16 v[44:47], v[158:161], v[196:199], v[44:47]
	v_mfma_f32_16x16x32_bf16 v[40:43], v[172:175], v[196:199], v[40:43]
	v_mfma_f32_16x16x32_bf16 v[36:39], v[158:161], v[204:207], v[36:39]
	v_mfma_f32_16x16x32_bf16 v[32:35], v[172:175], v[204:207], v[32:35]
	v_mfma_f32_16x16x32_bf16 v[60:63], v[162:165], v[184:187], v[60:63]
	v_mfma_f32_16x16x32_bf16 v[56:59], v[176:179], v[184:187], v[56:59]
	v_mfma_f32_16x16x32_bf16 v[52:55], v[162:165], v[192:195], v[52:55]
	v_mfma_f32_16x16x32_bf16 v[48:51], v[176:179], v[192:195], v[48:51]
	v_mfma_f32_16x16x32_bf16 v[44:47], v[162:165], v[200:203], v[44:47]
	v_mfma_f32_16x16x32_bf16 v[40:43], v[176:179], v[200:203], v[40:43]
	v_mfma_f32_16x16x32_bf16 v[36:39], v[162:165], v[208:211], v[36:39]
	v_mfma_f32_16x16x32_bf16 v[32:35], v[176:179], v[208:211], v[32:35]
	s_setprio 0
	s_add_i32 s4, s78, s44
	v_lshl_add_u64 v[144:145], v[144:145], 0, s[10:11]
	s_mov_b32 m0, s4
	s_barrier
	ds_read_b128 v[180:183], v171 offset:49152
	ds_read_b128 v[184:187], v171 offset:50176
	ds_read_b128 v[188:191], v171 offset:51200
	ds_read_b128 v[192:195], v171 offset:52224
	ds_read_b128 v[196:199], v171 offset:53248
	ds_read_b128 v[200:203], v171 offset:54272
	ds_read_b128 v[204:207], v171 offset:55296
	ds_read_b128 v[208:211], v171 offset:56320
	global_load_lds_dwordx4 v[144:145], off
	s_add_i32 m0, s4, 0x2000
	s_add_u32 s4, s40, 0xb0080
	v_lshl_add_u64 v[144:145], v[166:167], 0, s[10:11]
	s_addc_u32 s5, s41, 0
	s_add_i32 s40, s79, s44
	global_load_lds_dwordx4 v[144:145], off
	v_lshl_add_u64 v[144:145], s[4:5], 0, v[148:149]
	s_mov_b32 m0, s40
	s_nop 0
	global_load_lds_dwordx4 v[144:145], off
	v_lshl_add_u64 v[144:145], s[4:5], 0, v[152:153]
	s_add_i32 m0, s40, 0x2000
	s_nop 0
	global_load_lds_dwordx4 v[144:145], off
	v_lshl_add_u64 v[144:145], v[212:213], 0, s[10:11]
	s_mov_b32 m0, s51
	s_nop 0
	global_load_lds_dwordx4 v[144:145], off
	v_lshl_add_u64 v[144:145], v[214:215], 0, s[10:11]
	s_mov_b32 m0, s52
	s_nop 0
	global_load_lds_dwordx4 v[144:145], off
	s_waitcnt vmcnt(8)
	s_waitcnt lgkmcnt(0)
	s_barrier
	s_setprio 1
	s_waitcnt lgkmcnt(0)
	v_mfma_f32_16x16x32_bf16 v[92:95], v[128:131], v[180:183], v[92:95]
	v_mfma_f32_16x16x32_bf16 v[88:91], v[136:139], v[180:183], v[88:91]
	v_mfma_f32_16x16x32_bf16 v[84:87], v[128:131], v[188:191], v[84:87]
	v_mfma_f32_16x16x32_bf16 v[80:83], v[136:139], v[188:191], v[80:83]
	v_mfma_f32_16x16x32_bf16 v[76:79], v[128:131], v[196:199], v[76:79]
	v_mfma_f32_16x16x32_bf16 v[72:75], v[136:139], v[196:199], v[72:75]
	v_mfma_f32_16x16x32_bf16 v[68:71], v[128:131], v[204:207], v[68:71]
	v_mfma_f32_16x16x32_bf16 v[64:67], v[136:139], v[204:207], v[64:67]
	v_mfma_f32_16x16x32_bf16 v[92:95], v[132:135], v[184:187], v[92:95]
	v_mfma_f32_16x16x32_bf16 v[88:91], v[140:143], v[184:187], v[88:91]
	v_mfma_f32_16x16x32_bf16 v[84:87], v[132:135], v[192:195], v[84:87]
	v_mfma_f32_16x16x32_bf16 v[80:83], v[140:143], v[192:195], v[80:83]
	v_mfma_f32_16x16x32_bf16 v[76:79], v[132:135], v[200:203], v[76:79]
	v_mfma_f32_16x16x32_bf16 v[72:75], v[140:143], v[200:203], v[72:75]
	v_mfma_f32_16x16x32_bf16 v[68:71], v[132:135], v[208:211], v[68:71]
	v_mfma_f32_16x16x32_bf16 v[64:67], v[140:143], v[208:211], v[64:67]
	s_setprio 0
	s_setprio 1
	v_mfma_f32_16x16x32_bf16 v[28:31], v[158:161], v[180:183], v[28:31]
	v_mfma_f32_16x16x32_bf16 v[24:27], v[172:175], v[180:183], v[24:27]
	v_mfma_f32_16x16x32_bf16 v[20:23], v[158:161], v[188:191], v[20:23]
	v_mfma_f32_16x16x32_bf16 v[16:19], v[172:175], v[188:191], v[16:19]
	v_mfma_f32_16x16x32_bf16 v[12:15], v[158:161], v[196:199], v[12:15]
	v_mfma_f32_16x16x32_bf16 v[8:11], v[172:175], v[196:199], v[8:11]
	v_mfma_f32_16x16x32_bf16 v[4:7], v[158:161], v[204:207], v[4:7]
	v_mfma_f32_16x16x32_bf16 v[0:3], v[172:175], v[204:207], v[0:3]
	v_mfma_f32_16x16x32_bf16 v[28:31], v[162:165], v[184:187], v[28:31]
	v_mfma_f32_16x16x32_bf16 v[24:27], v[176:179], v[184:187], v[24:27]
	v_mfma_f32_16x16x32_bf16 v[20:23], v[162:165], v[192:195], v[20:23]
	v_mfma_f32_16x16x32_bf16 v[16:19], v[176:179], v[192:195], v[16:19]
	v_mfma_f32_16x16x32_bf16 v[12:15], v[162:165], v[200:203], v[12:15]
	v_mfma_f32_16x16x32_bf16 v[8:11], v[176:179], v[200:203], v[8:11]
	v_mfma_f32_16x16x32_bf16 v[4:7], v[162:165], v[208:211], v[4:7]
	v_mfma_f32_16x16x32_bf16 v[0:3], v[176:179], v[208:211], v[0:3]
	s_setprio 0
	s_add_u32 s75, s75, 0x100
	s_addc_u32 s76, s76, 0
	s_cmp_ge_u32 s77, s73
	s_mov_b64 s[4:5], s[14:15]
	s_mov_b32 s40, s77
	s_barrier
	s_cbranch_scc0 .LBB0_1781

; #define G_STAGE(bufoff, gbase, voff) do { _Pragma("unroll") for (int _i = 0; _i < 2; ++_i) \
;         __builtin_amdgcn_global_load_lds((const unsigned*)((const char*)(gbase) + voff[_i]), (LAS unsigned*)(lds + (bufoff) + ldsw + _i * 8192), 16, 0, 0); } while (0)
; #define G_LDA(dst, b, h) do { _Pragma("unroll") for (int m = 0; m < 4; ++m) _Pragma("unroll") for (int k = 0; k < 2; ++k) dst[m][k] = *(const LAS bf16x8*)(lds + G_SA(b, h) + aoff + m * 2048 + k * 1024); } while (0)
; #define G_LDB(dst, b, h) do { _Pragma("unroll") for (int n = 0; n < 2; ++n) _Pragma("unroll") for (int k = 0; k < 2; ++k) dst[n][k] = *(const LAS bf16x8*)(lds + G_SB(b, h) + boff + n * 2048 + k * 1024); } while (0)
; #define G_MMA(ai, bj, At_, Bt_) do { __builtin_amdgcn_s_setprio(1); _Pragma("unroll") for (int m = 0; m < 4; ++m) _Pragma("unroll") for (int n = 0; n < 2; ++n) _Pragma("unroll") for (int k = 0; k < 2; ++k) \
;         acc[ai][bj][m][n] = __builtin_amdgcn_mfma_f32_16x16x32_bf16(Bt_[n][k], At_[m][k], acc[ai][bj][m][n], 0, 0, 0); __builtin_amdgcn_s_setprio(0); } while (0)
; #define WAIT_V(n) asm volatile("s_waitcnt vmcnt(" #n ")" ::: "memory")
; #define WAIT_L(n) asm volatile("s_waitcnt lgkmcnt(" #n ")" ::: "memory")
; #define BAR __builtin_amdgcn_s_barrier()
; template <class Get, class Epi>
; DI void gemm_loop(int ntiles, int ld, char* shm, const Get& get, const Epi& epi) {
;     ...
;         const int Ln = L + gridDim.x; const bool has_next = Ln < ntiles; if (has_next) nxt = get(Ln);
;         const char* nA = has_next ? (const char*)nxt.A + (size_t)nxt.brow * ld * 2 : cA; const char* nB = has_next ? (const char*)nxt.Bt + (size_t)nxt.bcol * ld * 2 : cB;
;         const int nt = cur.K / BK;
;         for (int t = 0; t < nt; t += 2) {
;             const bool last = (t == nt - 2);
;             const char* a1 = cA + (size_t)(t + 1) * kstep;
;             const char* a2 = last ? nA : cA + (size_t)(t + 2) * kstep; const char* b2 = last ? nB : cB + (size_t)(t + 2) * kstep;
;             const char* a3 = a2 + kstep; const char* b3 = b2 + kstep;
;             G_LDB(B0, 0, 0); G_LDB(B1, 0, 1); SCHED; G_LDA(At, 0, 0); G_STAGE(G_SA(1, 1), a1 + hstep, voffA);
;             WAIT_V(8); WAIT_L(0); BAR; G_MMA(0, 0, At, B0); G_MMA(0, 1, At, B1); BAR; SCHED;
;             G_LDA(At, 0, 1); G_STAGE(G_SB(0, 0), b2, voffB); G_STAGE(G_SB(0, 1), b2 + hstep, voffB); G_STAGE(G_SA(0, 0), a2, voffA);
.Lpeel_2022:
	ds_read_b128 v[96:99], v173
	ds_read_b128 v[108:111], v173 offset:1024
	ds_read_b128 v[150:153], v173 offset:2048
	ds_read_b128 v[154:157], v173 offset:3072
	ds_read_b128 v[158:161], v174
	ds_read_b128 v[162:165], v174 offset:1024
	ds_read_b128 v[166:169], v174 offset:2048
	ds_read_b128 v[180:183], v174 offset:3072
	s_add_u32 s6, s4, 0xfffc0080
	s_addc_u32 s7, s5, -1
	s_cmp_eq_u32 s56, 12
	s_cselect_b32 s15, s3, s7
	s_cselect_b32 s14, s41, s6
	s_cselect_b32 s7, s43, s55
	s_cselect_b32 s6, s53, s54
	v_lshl_add_u64 v[170:171], s[4:5], 0, v[146:147]
	s_add_i32 m0, s50, 0xc000
	ds_read_b128 v[184:187], v175
	ds_read_b128 v[188:191], v175 offset:1024
	ds_read_b128 v[192:195], v175 offset:2048
	ds_read_b128 v[196:199], v175 offset:3072
	ds_read_b128 v[200:203], v175 offset:4096
	ds_read_b128 v[204:207], v175 offset:5120
	ds_read_b128 v[208:211], v175 offset:6144
	ds_read_b128 v[212:215], v175 offset:7168
	global_load_lds_dwordx4 v[170:171], off
	v_lshl_add_u64 v[170:171], s[4:5], 0, v[148:149]
	s_add_i32 m0, s50, 0xe000
	s_nop 0
	global_load_lds_dwordx4 v[170:171], off
	s_waitcnt vmcnt(8)
	s_waitcnt lgkmcnt(0)
	s_barrier
	s_setprio 1
	s_waitcnt lgkmcnt(0)
	v_mfma_f32_16x16x32_bf16 v[132:135], v[96:99], v[184:187], 0
	v_mfma_f32_16x16x32_bf16 v[124:127], v[150:153], v[184:187], 0
	v_mfma_f32_16x16x32_bf16 v[128:131], v[96:99], v[192:195], 0
	v_mfma_f32_16x16x32_bf16 v[120:123], v[150:153], v[192:195], 0
	v_mfma_f32_16x16x32_bf16 v[116:119], v[96:99], v[200:203], 0
	v_mfma_f32_16x16x32_bf16 v[104:107], v[150:153], v[200:203], 0
	v_mfma_f32_16x16x32_bf16 v[112:115], v[96:99], v[208:211], 0
	v_mfma_f32_16x16x32_bf16 v[100:103], v[150:153], v[208:211], 0
	v_mfma_f32_16x16x32_bf16 v[132:135], v[108:111], v[188:191], v[132:135]
	v_mfma_f32_16x16x32_bf16 v[124:127], v[154:157], v[188:191], v[124:127]
	v_mfma_f32_16x16x32_bf16 v[128:131], v[108:111], v[196:199], v[128:131]
	v_mfma_f32_16x16x32_bf16 v[120:123], v[154:157], v[196:199], v[120:123]
	v_mfma_f32_16x16x32_bf16 v[116:119], v[108:111], v[204:207], v[116:119]
	v_mfma_f32_16x16x32_bf16 v[104:107], v[154:157], v[204:207], v[104:107]
	v_mfma_f32_16x16x32_bf16 v[112:115], v[108:111], v[212:215], v[112:115]
	v_mfma_f32_16x16x32_bf16 v[100:103], v[154:157], v[212:215], v[100:103]
	s_setprio 0
	s_setprio 1
	v_mfma_f32_16x16x32_bf16 v[60:63], v[158:161], v[184:187], 0
	v_mfma_f32_16x16x32_bf16 v[52:55], v[166:169], v[184:187], 0
	v_mfma_f32_16x16x32_bf16 v[56:59], v[158:161], v[192:195], 0
	v_mfma_f32_16x16x32_bf16 v[48:51], v[166:169], v[192:195], 0
	v_mfma_f32_16x16x32_bf16 v[44:47], v[158:161], v[200:203], 0
	v_mfma_f32_16x16x32_bf16 v[36:39], v[166:169], v[200:203], 0
	v_mfma_f32_16x16x32_bf16 v[40:43], v[158:161], v[208:211], 0
	v_mfma_f32_16x16x32_bf16 v[32:35], v[166:169], v[208:211], 0
	v_mfma_f32_16x16x32_bf16 v[60:63], v[162:165], v[188:191], v[60:63]
	v_mfma_f32_16x16x32_bf16 v[52:55], v[180:183], v[188:191], v[52:55]
	v_mfma_f32_16x16x32_bf16 v[56:59], v[162:165], v[196:199], v[56:59]
	v_mfma_f32_16x16x32_bf16 v[48:51], v[180:183], v[196:199], v[48:51]
	v_mfma_f32_16x16x32_bf16 v[44:47], v[162:165], v[204:207], v[44:47]
	v_mfma_f32_16x16x32_bf16 v[36:39], v[180:183], v[204:207], v[36:39]
	v_mfma_f32_16x16x32_bf16 v[40:43], v[162:165], v[212:215], v[40:43]
	v_mfma_f32_16x16x32_bf16 v[32:35], v[180:183], v[212:215], v[32:35]
	s_setprio 0
	s_add_i32 s57, s75, s46
	v_lshl_add_u64 v[170:171], s[6:7], 0, v[140:141]
	s_mov_b32 m0, s57
	s_barrier
	ds_read_b128 v[184:187], v175 offset:16384
	ds_read_b128 v[188:191], v175 offset:17408
	ds_read_b128 v[192:195], v175 offset:18432
	ds_read_b128 v[196:199], v175 offset:19456
	ds_read_b128 v[200:203], v175 offset:20480
	ds_read_b128 v[204:207], v175 offset:21504
	ds_read_b128 v[208:211], v175 offset:22528
	ds_read_b128 v[212:215], v175 offset:23552
	global_load_lds_dwordx4 v[170:171], off
	s_add_i32 m0, s57, 0x2000
	s_add_u32 s58, s6, 0x40000
	v_lshl_add_u64 v[216:217], s[6:7], 0, v[136:137]
	s_addc_u32 s59, s7, 0
	s_add_i32 s57, s76, s46
	global_load_lds_dwordx4 v[216:217], off
	v_lshl_add_u64 v[218:219], s[58:59], 0, v[140:141]
	s_mov_b32 m0, s57
	v_lshl_add_u64 v[220:221], s[14:15], 0, v[138:139]
	global_load_lds_dwordx4 v[218:219], off
	v_lshl_add_u64 v[218:219], s[58:59], 0, v[136:137]
	s_add_i32 m0, s57, 0x2000
	s_nop 0
	global_load_lds_dwordx4 v[218:219], off
	v_lshl_add_u64 v[218:219], s[14:15], 0, v[142:143]
	s_mov_b32 m0, s50
	s_nop 0
	global_load_lds_dwordx4 v[218:219], off
	s_mov_b32 m0, s51
	s_nop 0
	global_load_lds_dwordx4 v[220:221], off
	s_waitcnt vmcnt(8)
	s_waitcnt lgkmcnt(0)
	s_barrier
; #define G_STAGE(bufoff, gbase, voff) do { _Pragma("unroll") for (int _i = 0; _i < 2; ++_i) \
;         __builtin_amdgcn_global_load_lds((const unsigned*)((const char*)(gbase) + voff[_i]), (LAS unsigned*)(lds + (bufoff) + ldsw + _i * 8192), 16, 0, 0); } while (0)
; #define G_LDA(dst, b, h) do { _Pragma("unroll") for (int m = 0; m < 4; ++m) _Pragma("unroll") for (int k = 0; k < 2; ++k) dst[m][k] = *(const LAS bf16x8*)(lds + G_SA(b, h) + aoff + m * 2048 + k * 1024); } while (0)
; #define G_LDB(dst, b, h) do { _Pragma("unroll") for (int n = 0; n < 2; ++n) _Pragma("unroll") for (int k = 0; k < 2; ++k) dst[n][k] = *(const LAS bf16x8*)(lds + G_SB(b, h) + boff + n * 2048 + k * 1024); } while (0)
; #define G_MMA(ai, bj, At_, Bt_) do { __builtin_amdgcn_s_setprio(1); _Pragma("unroll") for (int m = 0; m < 4; ++m) _Pragma("unroll") for (int n = 0; n < 2; ++n) _Pragma("unroll") for (int k = 0; k < 2; ++k) \
;         acc[ai][bj][m][n] = __builtin_amdgcn_mfma_f32_16x16x32_bf16(Bt_[n][k], At_[m][k], acc[ai][bj][m][n], 0, 0, 0); __builtin_amdgcn_s_setprio(0); } while (0)
; #define WAIT_V(n) asm volatile("s_waitcnt vmcnt(" #n ")" ::: "memory")
; #define WAIT_L(n) asm volatile("s_waitcnt lgkmcnt(" #n ")" ::: "memory")
; #define BAR __builtin_amdgcn_s_barrier()
; #define SCHED __builtin_amdgcn_sched_barrier(0)
; template <class Get, class Epi>
; DI void gemm_loop(int ntiles, int ld, char* shm, const Get& get, const Epi& epi) {
;     ...
;             WAIT_V(8); WAIT_L(0); BAR; G_MMA(1, 0, At, B0); G_MMA(1, 1, At, B1); BAR; SCHED;
;             G_LDB(B0, 1, 0); G_LDB(B1, 1, 1); SCHED; G_LDA(At, 1, 0); G_STAGE(G_SA(0, 1), a2 + hstep, voffA);
;             WAIT_V(8); WAIT_L(0); BAR; G_MMA(0, 0, At, B0); G_MMA(0, 1, At, B1); BAR; SCHED;
	s_setprio 1
	s_waitcnt lgkmcnt(0)
	v_mfma_f32_16x16x32_bf16 v[92:95], v[96:99], v[184:187], 0
	v_mfma_f32_16x16x32_bf16 v[84:87], v[150:153], v[184:187], 0
	v_mfma_f32_16x16x32_bf16 v[88:91], v[96:99], v[192:195], 0
	v_mfma_f32_16x16x32_bf16 v[80:83], v[150:153], v[192:195], 0
	v_mfma_f32_16x16x32_bf16 v[76:79], v[96:99], v[200:203], 0
	v_mfma_f32_16x16x32_bf16 v[68:71], v[150:153], v[200:203], 0
	v_mfma_f32_16x16x32_bf16 v[72:75], v[96:99], v[208:211], 0
	v_mfma_f32_16x16x32_bf16 v[64:67], v[150:153], v[208:211], 0
	v_mfma_f32_16x16x32_bf16 v[92:95], v[108:111], v[188:191], v[92:95]
	v_mfma_f32_16x16x32_bf16 v[84:87], v[154:157], v[188:191], v[84:87]
	v_mfma_f32_16x16x32_bf16 v[88:91], v[108:111], v[196:199], v[88:91]
	v_mfma_f32_16x16x32_bf16 v[80:83], v[154:157], v[196:199], v[80:83]
	v_mfma_f32_16x16x32_bf16 v[76:79], v[108:111], v[204:207], v[76:79]
	v_mfma_f32_16x16x32_bf16 v[68:71], v[154:157], v[204:207], v[68:71]
	v_mfma_f32_16x16x32_bf16 v[72:75], v[108:111], v[212:215], v[72:75]
	v_mfma_f32_16x16x32_bf16 v[64:67], v[154:157], v[212:215], v[64:67]
	s_setprio 0
	s_setprio 1
	v_mfma_f32_16x16x32_bf16 v[28:31], v[158:161], v[184:187], 0
	v_mfma_f32_16x16x32_bf16 v[20:23], v[166:169], v[184:187], 0
	v_mfma_f32_16x16x32_bf16 v[24:27], v[158:161], v[192:195], 0
	v_mfma_f32_16x16x32_bf16 v[16:19], v[166:169], v[192:195], 0
	v_mfma_f32_16x16x32_bf16 v[12:15], v[158:161], v[200:203], 0
	v_mfma_f32_16x16x32_bf16 v[4:7], v[166:169], v[200:203], 0
	v_mfma_f32_16x16x32_bf16 v[8:11], v[158:161], v[208:211], 0
	v_mfma_f32_16x16x32_bf16 v[0:3], v[166:169], v[208:211], 0
	v_mfma_f32_16x16x32_bf16 v[28:31], v[162:165], v[188:191], v[28:31]
	v_mfma_f32_16x16x32_bf16 v[20:23], v[180:183], v[188:191], v[20:23]
	v_mfma_f32_16x16x32_bf16 v[24:27], v[162:165], v[196:199], v[24:27]
	v_mfma_f32_16x16x32_bf16 v[16:19], v[180:183], v[196:199], v[16:19]
	v_mfma_f32_16x16x32_bf16 v[12:15], v[162:165], v[204:207], v[12:15]
	v_mfma_f32_16x16x32_bf16 v[4:7], v[180:183], v[204:207], v[4:7]
	v_mfma_f32_16x16x32_bf16 v[8:11], v[162:165], v[212:215], v[8:11]
	v_mfma_f32_16x16x32_bf16 v[0:3], v[180:183], v[212:215], v[0:3]
	s_setprio 0
	s_add_i32 s57, 0, 0x18000
	v_add_u32_e32 v144, s57, v172
	s_add_i32 s58, 0, 0x1c000
	s_barrier
	ds_read_b128 v[96:99], v144
	ds_read_b128 v[108:111], v144 offset:1024
	ds_read_b128 v[150:153], v144 offset:2048
	ds_read_b128 v[154:157], v144 offset:3072
	v_add_u32_e32 v144, s58, v172
	ds_read_b128 v[158:161], v144
	ds_read_b128 v[162:165], v144 offset:1024
	ds_read_b128 v[166:169], v144 offset:2048
	ds_read_b128 v[180:183], v144 offset:3072
	s_add_u32 s14, s14, 0x40000
	s_addc_u32 s15, s15, 0
	s_mov_b32 m0, s71
	v_lshl_add_u64 v[222:223], s[14:15], 0, v[142:143]
	ds_read_b128 v[184:187], v175 offset:32768
	ds_read_b128 v[188:191], v175 offset:33792
	ds_read_b128 v[192:195], v175 offset:34816
	ds_read_b128 v[196:199], v175 offset:35840
	ds_read_b128 v[200:203], v175 offset:36864
	ds_read_b128 v[204:207], v175 offset:37888
	ds_read_b128 v[208:211], v175 offset:38912
	ds_read_b128 v[212:215], v175 offset:39936
	global_load_lds_dwordx4 v[222:223], off
	v_lshl_add_u64 v[222:223], s[14:15], 0, v[138:139]
	s_mov_b32 m0, s72
	s_nop 0
	global_load_lds_dwordx4 v[222:223], off
	s_waitcnt vmcnt(8)
	s_waitcnt lgkmcnt(0)
	s_barrier
	s_setprio 1
	s_waitcnt lgkmcnt(0)
	v_mfma_f32_16x16x32_bf16 v[132:135], v[96:99], v[184:187], v[132:135]
	v_mfma_f32_16x16x32_bf16 v[124:127], v[150:153], v[184:187], v[124:127]
	v_mfma_f32_16x16x32_bf16 v[128:131], v[96:99], v[192:195], v[128:131]
	v_mfma_f32_16x16x32_bf16 v[120:123], v[150:153], v[192:195], v[120:123]
	v_mfma_f32_16x16x32_bf16 v[116:119], v[96:99], v[200:203], v[116:119]
	v_mfma_f32_16x16x32_bf16 v[104:107], v[150:153], v[200:203], v[104:107]
	v_mfma_f32_16x16x32_bf16 v[112:115], v[96:99], v[208:211], v[112:115]
	v_mfma_f32_16x16x32_bf16 v[100:103], v[150:153], v[208:211], v[100:103]
	v_mfma_f32_16x16x32_bf16 v[132:135], v[108:111], v[188:191], v[132:135]
	v_mfma_f32_16x16x32_bf16 v[124:127], v[154:157], v[188:191], v[124:127]
	v_mfma_f32_16x16x32_bf16 v[128:131], v[108:111], v[196:199], v[128:131]
	v_mfma_f32_16x16x32_bf16 v[120:123], v[154:157], v[196:199], v[120:123]
	v_mfma_f32_16x16x32_bf16 v[116:119], v[108:111], v[204:207], v[116:119]
	v_mfma_f32_16x16x32_bf16 v[104:107], v[154:157], v[204:207], v[104:107]
	v_mfma_f32_16x16x32_bf16 v[112:115], v[108:111], v[212:215], v[112:115]
	v_mfma_f32_16x16x32_bf16 v[100:103], v[154:157], v[212:215], v[100:103]
	s_setprio 0
	s_setprio 1
	v_mfma_f32_16x16x32_bf16 v[60:63], v[158:161], v[184:187], v[60:63]
	v_mfma_f32_16x16x32_bf16 v[52:55], v[166:169], v[184:187], v[52:55]
	v_mfma_f32_16x16x32_bf16 v[56:59], v[158:161], v[192:195], v[56:59]
	v_mfma_f32_16x16x32_bf16 v[48:51], v[166:169], v[192:195], v[48:51]
	v_mfma_f32_16x16x32_bf16 v[44:47], v[158:161], v[200:203], v[44:47]
	v_mfma_f32_16x16x32_bf16 v[36:39], v[166:169], v[200:203], v[36:39]
	v_mfma_f32_16x16x32_bf16 v[40:43], v[158:161], v[208:211], v[40:43]
	v_mfma_f32_16x16x32_bf16 v[32:35], v[166:169], v[208:211], v[32:35]
	v_mfma_f32_16x16x32_bf16 v[60:63], v[162:165], v[188:191], v[60:63]
	v_mfma_f32_16x16x32_bf16 v[52:55], v[180:183], v[188:191], v[52:55]
	v_mfma_f32_16x16x32_bf16 v[56:59], v[162:165], v[196:199], v[56:59]
	v_mfma_f32_16x16x32_bf16 v[48:51], v[180:183], v[196:199], v[48:51]
	v_mfma_f32_16x16x32_bf16 v[44:47], v[162:165], v[204:207], v[44:47]
	v_mfma_f32_16x16x32_bf16 v[36:39], v[180:183], v[204:207], v[36:39]
	v_mfma_f32_16x16x32_bf16 v[40:43], v[162:165], v[212:215], v[40:43]
	v_mfma_f32_16x16x32_bf16 v[32:35], v[180:183], v[212:215], v[32:35]
	s_setprio 0
	s_add_i32 s14, s57, s46
	v_lshl_add_u64 v[170:171], v[170:171], 0, s[10:11]
	s_mov_b32 m0, s14
	s_barrier
; #define G_STAGE(bufoff, gbase, voff) do { _Pragma("unroll") for (int _i = 0; _i < 2; ++_i) \
;         __builtin_amdgcn_global_load_lds((const unsigned*)((const char*)(gbase) + voff[_i]), (LAS unsigned*)(lds + (bufoff) + ldsw + _i * 8192), 16, 0, 0); } while (0)
; #define G_LDA(dst, b, h) do { _Pragma("unroll") for (int m = 0; m < 4; ++m) _Pragma("unroll") for (int k = 0; k < 2; ++k) dst[m][k] = *(const LAS bf16x8*)(lds + G_SA(b, h) + aoff + m * 2048 + k * 1024); } while (0)
; #define G_LDB(dst, b, h) do { _Pragma("unroll") for (int n = 0; n < 2; ++n) _Pragma("unroll") for (int k = 0; k < 2; ++k) dst[n][k] = *(const LAS bf16x8*)(lds + G_SB(b, h) + boff + n * 2048 + k * 1024); } while (0)
; #define G_MMA(ai, bj, At_, Bt_) do { __builtin_amdgcn_s_setprio(1); _Pragma("unroll") for (int m = 0; m < 4; ++m) _Pragma("unroll") for (int n = 0; n < 2; ++n) _Pragma("unroll") for (int k = 0; k < 2; ++k) \
;         acc[ai][bj][m][n] = __builtin_amdgcn_mfma_f32_16x16x32_bf16(Bt_[n][k], At_[m][k], acc[ai][bj][m][n], 0, 0, 0); __builtin_amdgcn_s_setprio(0); } while (0)
; #define WAIT_V(n) asm volatile("s_waitcnt vmcnt(" #n ")" ::: "memory")
; #define WAIT_L(n) asm volatile("s_waitcnt lgkmcnt(" #n ")" ::: "memory")
; #define BAR __builtin_amdgcn_s_barrier()
; #define SCHED __builtin_amdgcn_sched_barrier(0)
; template <class Get, class Epi>
; DI void gemm_loop(int ntiles, int ld, char* shm, const Get& get, const Epi& epi) {
;     ...
;             G_LDB(B0, 0, 0); G_LDB(B1, 0, 1); SCHED; G_LDA(At, 0, 0); G_STAGE(G_SA(1, 1), a1 + hstep, voffA);
;             WAIT_V(8); WAIT_L(0); BAR; G_MMA(0, 0, At, B0); G_MMA(0, 1, At, B1); BAR; SCHED;
;     ...
;             G_LDA(At, 1, 1); G_STAGE(G_SB(1, 0), b3, voffB); G_STAGE(G_SB(1, 1), b3 + hstep, voffB); G_STAGE(G_SA(1, 0), a3, voffA);
;             WAIT_V(8); WAIT_L(0); BAR; G_MMA(1, 0, At, B0); G_MMA(1, 1, At, B1); BAR; SCHED;
	ds_read_b128 v[184:187], v175 offset:49152
	ds_read_b128 v[188:191], v175 offset:50176
	ds_read_b128 v[192:195], v175 offset:51200
	ds_read_b128 v[196:199], v175 offset:52224
	ds_read_b128 v[200:203], v175 offset:53248
	ds_read_b128 v[204:207], v175 offset:54272
	ds_read_b128 v[208:211], v175 offset:55296
	ds_read_b128 v[212:215], v175 offset:56320
	global_load_lds_dwordx4 v[170:171], off
	s_add_i32 m0, s14, 0x2000
	s_add_u32 s6, s6, 0x40080
	v_lshl_add_u64 v[170:171], v[216:217], 0, s[10:11]
	s_addc_u32 s7, s7, 0
	s_add_i32 s14, s58, s46
	global_load_lds_dwordx4 v[170:171], off
	v_lshl_add_u64 v[170:171], s[6:7], 0, v[140:141]
	s_mov_b32 m0, s14
	s_nop 0
	global_load_lds_dwordx4 v[170:171], off
	v_lshl_add_u64 v[170:171], s[6:7], 0, v[136:137]
	s_add_i32 m0, s14, 0x2000
	s_nop 0
	global_load_lds_dwordx4 v[170:171], off
	v_lshl_add_u64 v[170:171], v[218:219], 0, s[10:11]
	s_mov_b32 m0, s73
	s_nop 0
	global_load_lds_dwordx4 v[170:171], off
	v_lshl_add_u64 v[170:171], v[220:221], 0, s[10:11]
	s_mov_b32 m0, s74
	s_nop 0
	global_load_lds_dwordx4 v[170:171], off
	s_waitcnt vmcnt(8)
	s_waitcnt lgkmcnt(0)
	s_barrier
	s_setprio 1
	s_waitcnt lgkmcnt(0)
	v_mfma_f32_16x16x32_bf16 v[92:95], v[96:99], v[184:187], v[92:95]
	v_mfma_f32_16x16x32_bf16 v[84:87], v[150:153], v[184:187], v[84:87]
	v_mfma_f32_16x16x32_bf16 v[88:91], v[96:99], v[192:195], v[88:91]
	v_mfma_f32_16x16x32_bf16 v[80:83], v[150:153], v[192:195], v[80:83]
	v_mfma_f32_16x16x32_bf16 v[76:79], v[96:99], v[200:203], v[76:79]
	v_mfma_f32_16x16x32_bf16 v[68:71], v[150:153], v[200:203], v[68:71]
	v_mfma_f32_16x16x32_bf16 v[72:75], v[96:99], v[208:211], v[72:75]
	v_mfma_f32_16x16x32_bf16 v[64:67], v[150:153], v[208:211], v[64:67]
	v_mfma_f32_16x16x32_bf16 v[92:95], v[108:111], v[188:191], v[92:95]
	v_mfma_f32_16x16x32_bf16 v[84:87], v[154:157], v[188:191], v[84:87]
	v_mfma_f32_16x16x32_bf16 v[88:91], v[108:111], v[196:199], v[88:91]
	v_mfma_f32_16x16x32_bf16 v[80:83], v[154:157], v[196:199], v[80:83]
	v_mfma_f32_16x16x32_bf16 v[76:79], v[108:111], v[204:207], v[76:79]
	v_mfma_f32_16x16x32_bf16 v[68:71], v[154:157], v[204:207], v[68:71]
	v_mfma_f32_16x16x32_bf16 v[72:75], v[108:111], v[212:215], v[72:75]
	v_mfma_f32_16x16x32_bf16 v[64:67], v[154:157], v[212:215], v[64:67]
	s_setprio 0
	s_setprio 1
	v_mfma_f32_16x16x32_bf16 v[28:31], v[158:161], v[184:187], v[28:31]
	v_mfma_f32_16x16x32_bf16 v[20:23], v[166:169], v[184:187], v[20:23]
	v_mfma_f32_16x16x32_bf16 v[24:27], v[158:161], v[192:195], v[24:27]
	v_mfma_f32_16x16x32_bf16 v[16:19], v[166:169], v[192:195], v[16:19]
	v_mfma_f32_16x16x32_bf16 v[12:15], v[158:161], v[200:203], v[12:15]
	v_mfma_f32_16x16x32_bf16 v[4:7], v[166:169], v[200:203], v[4:7]
	v_mfma_f32_16x16x32_bf16 v[8:11], v[158:161], v[208:211], v[8:11]
	v_mfma_f32_16x16x32_bf16 v[0:3], v[166:169], v[208:211], v[0:3]
	v_mfma_f32_16x16x32_bf16 v[28:31], v[162:165], v[188:191], v[28:31]
	v_mfma_f32_16x16x32_bf16 v[20:23], v[180:183], v[188:191], v[20:23]
	v_mfma_f32_16x16x32_bf16 v[24:27], v[162:165], v[196:199], v[24:27]
	v_mfma_f32_16x16x32_bf16 v[16:19], v[180:183], v[196:199], v[16:19]
	v_mfma_f32_16x16x32_bf16 v[12:15], v[162:165], v[204:207], v[12:15]
	v_mfma_f32_16x16x32_bf16 v[4:7], v[180:183], v[204:207], v[4:7]
	v_mfma_f32_16x16x32_bf16 v[8:11], v[162:165], v[212:215], v[8:11]
	v_mfma_f32_16x16x32_bf16 v[0:3], v[180:183], v[212:215], v[0:3]
	s_setprio 0
	s_add_i32 s56, s56, 2
	s_add_u32 s4, s4, 0x100
	s_addc_u32 s5, s5, 0
	s_add_u32 s54, s54, 0x100
	s_addc_u32 s55, s55, 0
	s_cmp_gt_u32 s56, 13
	s_barrier
	s_cbranch_scc0 .LBB0_2022
	s_branch .Lpost_2022
.LBB0_2022:
	ds_read_b128 v[96:99], v173
	ds_read_b128 v[108:111], v173 offset:1024
	ds_read_b128 v[150:153], v173 offset:2048
	ds_read_b128 v[154:157], v173 offset:3072
	ds_read_b128 v[158:161], v174
	ds_read_b128 v[162:165], v174 offset:1024
	ds_read_b128 v[166:169], v174 offset:2048
	ds_read_b128 v[180:183], v174 offset:3072
	s_add_u32 s6, s4, 0xfffc0080
	s_addc_u32 s7, s5, -1
	s_cmp_eq_u32 s56, 12
	s_cselect_b32 s15, s3, s7
	s_cselect_b32 s14, s41, s6
	s_cselect_b32 s7, s43, s55
	s_cselect_b32 s6, s53, s54
	v_lshl_add_u64 v[170:171], s[4:5], 0, v[146:147]
	s_add_i32 m0, s50, 0xc000
	ds_read_b128 v[184:187], v175
	ds_read_b128 v[188:191], v175 offset:1024
	ds_read_b128 v[192:195], v175 offset:2048
	ds_read_b128 v[196:199], v175 offset:3072
	ds_read_b128 v[200:203], v175 offset:4096
	ds_read_b128 v[204:207], v175 offset:5120
	ds_read_b128 v[208:211], v175 offset:6144
	ds_read_b128 v[212:215], v175 offset:7168
	global_load_lds_dwordx4 v[170:171], off
	v_lshl_add_u64 v[170:171], s[4:5], 0, v[148:149]
	s_add_i32 m0, s50, 0xe000
	s_nop 0
	global_load_lds_dwordx4 v[170:171], off
	s_waitcnt vmcnt(8)
	s_waitcnt lgkmcnt(0)
	s_barrier
; #define G_STAGE(bufoff, gbase, voff) do { _Pragma("unroll") for (int _i = 0; _i < 2; ++_i) \
;         __builtin_amdgcn_global_load_lds((const unsigned*)((const char*)(gbase) + voff[_i]), (LAS unsigned*)(lds + (bufoff) + ldsw + _i * 8192), 16, 0, 0); } while (0)
; #define G_LDA(dst, b, h) do { _Pragma("unroll") for (int m = 0; m < 4; ++m) _Pragma("unroll") for (int k = 0; k < 2; ++k) dst[m][k] = *(const LAS bf16x8*)(lds + G_SA(b, h) + aoff + m * 2048 + k * 1024); } while (0)
; #define G_MMA(ai, bj, At_, Bt_) do { __builtin_amdgcn_s_setprio(1); _Pragma("unroll") for (int m = 0; m < 4; ++m) _Pragma("unroll") for (int n = 0; n < 2; ++n) _Pragma("unroll") for (int k = 0; k < 2; ++k) \
;         acc[ai][bj][m][n] = __builtin_amdgcn_mfma_f32_16x16x32_bf16(Bt_[n][k], At_[m][k], acc[ai][bj][m][n], 0, 0, 0); __builtin_amdgcn_s_setprio(0); } while (0)
; #define WAIT_V(n) asm volatile("s_waitcnt vmcnt(" #n ")" ::: "memory")
; #define WAIT_L(n) asm volatile("s_waitcnt lgkmcnt(" #n ")" ::: "memory")
; #define BAR __builtin_amdgcn_s_barrier()
; #define SCHED __builtin_amdgcn_sched_barrier(0)
; template <class Get, class Epi>
; DI void gemm_loop(int ntiles, int ld, char* shm, const Get& get, const Epi& epi) {
;     ...
;             WAIT_V(8); WAIT_L(0); BAR; G_MMA(0, 0, At, B0); G_MMA(0, 1, At, B1); BAR; SCHED;
;             G_LDA(At, 0, 1); G_STAGE(G_SB(0, 0), b2, voffB); G_STAGE(G_SB(0, 1), b2 + hstep, voffB); G_STAGE(G_SA(0, 0), a2, voffA);
;             WAIT_V(8); WAIT_L(0); BAR; G_MMA(1, 0, At, B0); G_MMA(1, 1, At, B1); BAR; SCHED;
	s_setprio 1
	s_waitcnt lgkmcnt(0)
	v_mfma_f32_16x16x32_bf16 v[132:135], v[96:99], v[184:187], v[132:135]
	v_mfma_f32_16x16x32_bf16 v[124:127], v[150:153], v[184:187], v[124:127]
	v_mfma_f32_16x16x32_bf16 v[128:131], v[96:99], v[192:195], v[128:131]
	v_mfma_f32_16x16x32_bf16 v[120:123], v[150:153], v[192:195], v[120:123]
	v_mfma_f32_16x16x32_bf16 v[116:119], v[96:99], v[200:203], v[116:119]
	v_mfma_f32_16x16x32_bf16 v[104:107], v[150:153], v[200:203], v[104:107]
	v_mfma_f32_16x16x32_bf16 v[112:115], v[96:99], v[208:211], v[112:115]
	v_mfma_f32_16x16x32_bf16 v[100:103], v[150:153], v[208:211], v[100:103]
	v_mfma_f32_16x16x32_bf16 v[132:135], v[108:111], v[188:191], v[132:135]
	v_mfma_f32_16x16x32_bf16 v[124:127], v[154:157], v[188:191], v[124:127]
	v_mfma_f32_16x16x32_bf16 v[128:131], v[108:111], v[196:199], v[128:131]
	v_mfma_f32_16x16x32_bf16 v[120:123], v[154:157], v[196:199], v[120:123]
	v_mfma_f32_16x16x32_bf16 v[116:119], v[108:111], v[204:207], v[116:119]
	v_mfma_f32_16x16x32_bf16 v[104:107], v[154:157], v[204:207], v[104:107]
	v_mfma_f32_16x16x32_bf16 v[112:115], v[108:111], v[212:215], v[112:115]
	v_mfma_f32_16x16x32_bf16 v[100:103], v[154:157], v[212:215], v[100:103]
	s_setprio 0
	s_setprio 1
	v_mfma_f32_16x16x32_bf16 v[60:63], v[158:161], v[184:187], v[60:63]
	v_mfma_f32_16x16x32_bf16 v[52:55], v[166:169], v[184:187], v[52:55]
	v_mfma_f32_16x16x32_bf16 v[56:59], v[158:161], v[192:195], v[56:59]
	v_mfma_f32_16x16x32_bf16 v[48:51], v[166:169], v[192:195], v[48:51]
	v_mfma_f32_16x16x32_bf16 v[44:47], v[158:161], v[200:203], v[44:47]
	v_mfma_f32_16x16x32_bf16 v[36:39], v[166:169], v[200:203], v[36:39]
	v_mfma_f32_16x16x32_bf16 v[40:43], v[158:161], v[208:211], v[40:43]
	v_mfma_f32_16x16x32_bf16 v[32:35], v[166:169], v[208:211], v[32:35]
	v_mfma_f32_16x16x32_bf16 v[60:63], v[162:165], v[188:191], v[60:63]
	v_mfma_f32_16x16x32_bf16 v[52:55], v[180:183], v[188:191], v[52:55]
	v_mfma_f32_16x16x32_bf16 v[56:59], v[162:165], v[196:199], v[56:59]
	v_mfma_f32_16x16x32_bf16 v[48:51], v[180:183], v[196:199], v[48:51]
	v_mfma_f32_16x16x32_bf16 v[44:47], v[162:165], v[204:207], v[44:47]
	v_mfma_f32_16x16x32_bf16 v[36:39], v[180:183], v[204:207], v[36:39]
	v_mfma_f32_16x16x32_bf16 v[40:43], v[162:165], v[212:215], v[40:43]
	v_mfma_f32_16x16x32_bf16 v[32:35], v[180:183], v[212:215], v[32:35]
	s_setprio 0
	s_add_i32 s57, s75, s46
	v_lshl_add_u64 v[170:171], s[6:7], 0, v[140:141]
	s_mov_b32 m0, s57
	s_barrier
	ds_read_b128 v[184:187], v175 offset:16384
	ds_read_b128 v[188:191], v175 offset:17408
	ds_read_b128 v[192:195], v175 offset:18432
	ds_read_b128 v[196:199], v175 offset:19456
	ds_read_b128 v[200:203], v175 offset:20480
	ds_read_b128 v[204:207], v175 offset:21504
	ds_read_b128 v[208:211], v175 offset:22528
	ds_read_b128 v[212:215], v175 offset:23552
	global_load_lds_dwordx4 v[170:171], off
	s_add_i32 m0, s57, 0x2000
	s_add_u32 s58, s6, 0x40000
	v_lshl_add_u64 v[216:217], s[6:7], 0, v[136:137]
	s_addc_u32 s59, s7, 0
	s_add_i32 s57, s76, s46
	global_load_lds_dwordx4 v[216:217], off
	v_lshl_add_u64 v[218:219], s[58:59], 0, v[140:141]
	s_mov_b32 m0, s57
	v_lshl_add_u64 v[220:221], s[14:15], 0, v[138:139]
	global_load_lds_dwordx4 v[218:219], off
	v_lshl_add_u64 v[218:219], s[58:59], 0, v[136:137]
	s_add_i32 m0, s57, 0x2000
	s_nop 0
	global_load_lds_dwordx4 v[218:219], off
	v_lshl_add_u64 v[218:219], s[14:15], 0, v[142:143]
	s_mov_b32 m0, s50
	s_nop 0
	global_load_lds_dwordx4 v[218:219], off
	s_mov_b32 m0, s51
	s_nop 0
	global_load_lds_dwordx4 v[220:221], off
	s_waitcnt vmcnt(8)
	s_waitcnt lgkmcnt(0)
	s_barrier
	s_setprio 1
	s_waitcnt lgkmcnt(0)
	v_mfma_f32_16x16x32_bf16 v[92:95], v[96:99], v[184:187], v[92:95]
	v_mfma_f32_16x16x32_bf16 v[84:87], v[150:153], v[184:187], v[84:87]
	v_mfma_f32_16x16x32_bf16 v[88:91], v[96:99], v[192:195], v[88:91]
	v_mfma_f32_16x16x32_bf16 v[80:83], v[150:153], v[192:195], v[80:83]
	v_mfma_f32_16x16x32_bf16 v[76:79], v[96:99], v[200:203], v[76:79]
	v_mfma_f32_16x16x32_bf16 v[68:71], v[150:153], v[200:203], v[68:71]
	v_mfma_f32_16x16x32_bf16 v[72:75], v[96:99], v[208:211], v[72:75]
	v_mfma_f32_16x16x32_bf16 v[64:67], v[150:153], v[208:211], v[64:67]
	v_mfma_f32_16x16x32_bf16 v[92:95], v[108:111], v[188:191], v[92:95]
	v_mfma_f32_16x16x32_bf16 v[84:87], v[154:157], v[188:191], v[84:87]
	v_mfma_f32_16x16x32_bf16 v[88:91], v[108:111], v[196:199], v[88:91]
	v_mfma_f32_16x16x32_bf16 v[80:83], v[154:157], v[196:199], v[80:83]
	v_mfma_f32_16x16x32_bf16 v[76:79], v[108:111], v[204:207], v[76:79]
	v_mfma_f32_16x16x32_bf16 v[68:71], v[154:157], v[204:207], v[68:71]
	v_mfma_f32_16x16x32_bf16 v[72:75], v[108:111], v[212:215], v[72:75]
	v_mfma_f32_16x16x32_bf16 v[64:67], v[154:157], v[212:215], v[64:67]
	s_setprio 0
	s_setprio 1
	v_mfma_f32_16x16x32_bf16 v[28:31], v[158:161], v[184:187], v[28:31]
	v_mfma_f32_16x16x32_bf16 v[20:23], v[166:169], v[184:187], v[20:23]
	v_mfma_f32_16x16x32_bf16 v[24:27], v[158:161], v[192:195], v[24:27]
	v_mfma_f32_16x16x32_bf16 v[16:19], v[166:169], v[192:195], v[16:19]
	v_mfma_f32_16x16x32_bf16 v[12:15], v[158:161], v[200:203], v[12:15]
	v_mfma_f32_16x16x32_bf16 v[4:7], v[166:169], v[200:203], v[4:7]
	v_mfma_f32_16x16x32_bf16 v[8:11], v[158:161], v[208:211], v[8:11]
	v_mfma_f32_16x16x32_bf16 v[0:3], v[166:169], v[208:211], v[0:3]
	v_mfma_f32_16x16x32_bf16 v[28:31], v[162:165], v[188:191], v[28:31]
	v_mfma_f32_16x16x32_bf16 v[20:23], v[180:183], v[188:191], v[20:23]
	v_mfma_f32_16x16x32_bf16 v[24:27], v[162:165], v[196:199], v[24:27]
	v_mfma_f32_16x16x32_bf16 v[16:19], v[180:183], v[196:199], v[16:19]
	v_mfma_f32_16x16x32_bf16 v[12:15], v[162:165], v[204:207], v[12:15]
	v_mfma_f32_16x16x32_bf16 v[4:7], v[180:183], v[204:207], v[4:7]
	v_mfma_f32_16x16x32_bf16 v[8:11], v[162:165], v[212:215], v[8:11]
	v_mfma_f32_16x16x32_bf16 v[0:3], v[180:183], v[212:215], v[0:3]
	s_setprio 0
	s_add_i32 s57, 0, 0x18000
	v_add_u32_e32 v144, s57, v172
	s_add_i32 s58, 0, 0x1c000
	s_barrier
; #define G_STAGE(bufoff, gbase, voff) do { _Pragma("unroll") for (int _i = 0; _i < 2; ++_i) \
;         __builtin_amdgcn_global_load_lds((const unsigned*)((const char*)(gbase) + voff[_i]), (LAS unsigned*)(lds + (bufoff) + ldsw + _i * 8192), 16, 0, 0); } while (0)
; #define G_LDA(dst, b, h) do { _Pragma("unroll") for (int m = 0; m < 4; ++m) _Pragma("unroll") for (int k = 0; k < 2; ++k) dst[m][k] = *(const LAS bf16x8*)(lds + G_SA(b, h) + aoff + m * 2048 + k * 1024); } while (0)
; #define G_LDB(dst, b, h) do { _Pragma("unroll") for (int n = 0; n < 2; ++n) _Pragma("unroll") for (int k = 0; k < 2; ++k) dst[n][k] = *(const LAS bf16x8*)(lds + G_SB(b, h) + boff + n * 2048 + k * 1024); } while (0)
; #define G_MMA(ai, bj, At_, Bt_) do { __builtin_amdgcn_s_setprio(1); _Pragma("unroll") for (int m = 0; m < 4; ++m) _Pragma("unroll") for (int n = 0; n < 2; ++n) _Pragma("unroll") for (int k = 0; k < 2; ++k) \
;         acc[ai][bj][m][n] = __builtin_amdgcn_mfma_f32_16x16x32_bf16(Bt_[n][k], At_[m][k], acc[ai][bj][m][n], 0, 0, 0); __builtin_amdgcn_s_setprio(0); } while (0)
; #define WAIT_V(n) asm volatile("s_waitcnt vmcnt(" #n ")" ::: "memory")
; #define WAIT_L(n) asm volatile("s_waitcnt lgkmcnt(" #n ")" ::: "memory")
; #define BAR __builtin_amdgcn_s_barrier()
; #define SCHED __builtin_amdgcn_sched_barrier(0)
; template <class Get, class Epi>
; DI void gemm_loop(int ntiles, int ld, char* shm, const Get& get, const Epi& epi) {
;     ...
;             G_LDB(B0, 1, 0); G_LDB(B1, 1, 1); SCHED; G_LDA(At, 1, 0); G_STAGE(G_SA(0, 1), a2 + hstep, voffA);
;             WAIT_V(8); WAIT_L(0); BAR; G_MMA(0, 0, At, B0); G_MMA(0, 1, At, B1); BAR; SCHED;
;             G_LDA(At, 1, 1); G_STAGE(G_SB(1, 0), b3, voffB); G_STAGE(G_SB(1, 1), b3 + hstep, voffB); G_STAGE(G_SA(1, 0), a3, voffA);
;             WAIT_V(8); WAIT_L(0); BAR; G_MMA(1, 0, At, B0); G_MMA(1, 1, At, B1); BAR; SCHED;
;         }
	ds_read_b128 v[96:99], v144
	ds_read_b128 v[108:111], v144 offset:1024
	ds_read_b128 v[150:153], v144 offset:2048
	ds_read_b128 v[154:157], v144 offset:3072
	v_add_u32_e32 v144, s58, v172
	ds_read_b128 v[158:161], v144
	ds_read_b128 v[162:165], v144 offset:1024
	ds_read_b128 v[166:169], v144 offset:2048
	ds_read_b128 v[180:183], v144 offset:3072
	s_add_u32 s14, s14, 0x40000
	s_addc_u32 s15, s15, 0
	s_mov_b32 m0, s71
	v_lshl_add_u64 v[222:223], s[14:15], 0, v[142:143]
	ds_read_b128 v[184:187], v175 offset:32768
	ds_read_b128 v[188:191], v175 offset:33792
	ds_read_b128 v[192:195], v175 offset:34816
	ds_read_b128 v[196:199], v175 offset:35840
	ds_read_b128 v[200:203], v175 offset:36864
	ds_read_b128 v[204:207], v175 offset:37888
	ds_read_b128 v[208:211], v175 offset:38912
	ds_read_b128 v[212:215], v175 offset:39936
	global_load_lds_dwordx4 v[222:223], off
	v_lshl_add_u64 v[222:223], s[14:15], 0, v[138:139]
	s_mov_b32 m0, s72
	s_nop 0
	global_load_lds_dwordx4 v[222:223], off
	s_waitcnt vmcnt(8)
	s_waitcnt lgkmcnt(0)
	s_barrier
	s_setprio 1
	s_waitcnt lgkmcnt(0)
	v_mfma_f32_16x16x32_bf16 v[132:135], v[96:99], v[184:187], v[132:135]
	v_mfma_f32_16x16x32_bf16 v[124:127], v[150:153], v[184:187], v[124:127]
	v_mfma_f32_16x16x32_bf16 v[128:131], v[96:99], v[192:195], v[128:131]
	v_mfma_f32_16x16x32_bf16 v[120:123], v[150:153], v[192:195], v[120:123]
	v_mfma_f32_16x16x32_bf16 v[116:119], v[96:99], v[200:203], v[116:119]
	v_mfma_f32_16x16x32_bf16 v[104:107], v[150:153], v[200:203], v[104:107]
	v_mfma_f32_16x16x32_bf16 v[112:115], v[96:99], v[208:211], v[112:115]
	v_mfma_f32_16x16x32_bf16 v[100:103], v[150:153], v[208:211], v[100:103]
	v_mfma_f32_16x16x32_bf16 v[132:135], v[108:111], v[188:191], v[132:135]
	v_mfma_f32_16x16x32_bf16 v[124:127], v[154:157], v[188:191], v[124:127]
	v_mfma_f32_16x16x32_bf16 v[128:131], v[108:111], v[196:199], v[128:131]
	v_mfma_f32_16x16x32_bf16 v[120:123], v[154:157], v[196:199], v[120:123]
	v_mfma_f32_16x16x32_bf16 v[116:119], v[108:111], v[204:207], v[116:119]
	v_mfma_f32_16x16x32_bf16 v[104:107], v[154:157], v[204:207], v[104:107]
	v_mfma_f32_16x16x32_bf16 v[112:115], v[108:111], v[212:215], v[112:115]
	v_mfma_f32_16x16x32_bf16 v[100:103], v[154:157], v[212:215], v[100:103]
	s_setprio 0
	s_setprio 1
	v_mfma_f32_16x16x32_bf16 v[60:63], v[158:161], v[184:187], v[60:63]
	v_mfma_f32_16x16x32_bf16 v[52:55], v[166:169], v[184:187], v[52:55]
	v_mfma_f32_16x16x32_bf16 v[56:59], v[158:161], v[192:195], v[56:59]
	v_mfma_f32_16x16x32_bf16 v[48:51], v[166:169], v[192:195], v[48:51]
	v_mfma_f32_16x16x32_bf16 v[44:47], v[158:161], v[200:203], v[44:47]
	v_mfma_f32_16x16x32_bf16 v[36:39], v[166:169], v[200:203], v[36:39]
	v_mfma_f32_16x16x32_bf16 v[40:43], v[158:161], v[208:211], v[40:43]
	v_mfma_f32_16x16x32_bf16 v[32:35], v[166:169], v[208:211], v[32:35]
	v_mfma_f32_16x16x32_bf16 v[60:63], v[162:165], v[188:191], v[60:63]
	v_mfma_f32_16x16x32_bf16 v[52:55], v[180:183], v[188:191], v[52:55]
	v_mfma_f32_16x16x32_bf16 v[56:59], v[162:165], v[196:199], v[56:59]
	v_mfma_f32_16x16x32_bf16 v[48:51], v[180:183], v[196:199], v[48:51]
	v_mfma_f32_16x16x32_bf16 v[44:47], v[162:165], v[204:207], v[44:47]
	v_mfma_f32_16x16x32_bf16 v[36:39], v[180:183], v[204:207], v[36:39]
	v_mfma_f32_16x16x32_bf16 v[40:43], v[162:165], v[212:215], v[40:43]
	v_mfma_f32_16x16x32_bf16 v[32:35], v[180:183], v[212:215], v[32:35]
	s_setprio 0
	s_add_i32 s14, s57, s46
	v_lshl_add_u64 v[170:171], v[170:171], 0, s[10:11]
	s_mov_b32 m0, s14
	s_barrier
	ds_read_b128 v[184:187], v175 offset:49152
	ds_read_b128 v[188:191], v175 offset:50176
	ds_read_b128 v[192:195], v175 offset:51200
	ds_read_b128 v[196:199], v175 offset:52224
	ds_read_b128 v[200:203], v175 offset:53248
	ds_read_b128 v[204:207], v175 offset:54272
	ds_read_b128 v[208:211], v175 offset:55296
	ds_read_b128 v[212:215], v175 offset:56320
	global_load_lds_dwordx4 v[170:171], off
	s_add_i32 m0, s14, 0x2000
	s_add_u32 s6, s6, 0x40080
	v_lshl_add_u64 v[170:171], v[216:217], 0, s[10:11]
	s_addc_u32 s7, s7, 0
	s_add_i32 s14, s58, s46
	global_load_lds_dwordx4 v[170:171], off
	v_lshl_add_u64 v[170:171], s[6:7], 0, v[140:141]
	s_mov_b32 m0, s14
	s_nop 0
	global_load_lds_dwordx4 v[170:171], off
	v_lshl_add_u64 v[170:171], s[6:7], 0, v[136:137]
	s_add_i32 m0, s14, 0x2000
	s_nop 0
	global_load_lds_dwordx4 v[170:171], off
	v_lshl_add_u64 v[170:171], v[218:219], 0, s[10:11]
	s_mov_b32 m0, s73
	s_nop 0
	global_load_lds_dwordx4 v[170:171], off
	v_lshl_add_u64 v[170:171], v[220:221], 0, s[10:11]
	s_mov_b32 m0, s74
	s_nop 0
	global_load_lds_dwordx4 v[170:171], off
	s_waitcnt vmcnt(8)
	s_waitcnt lgkmcnt(0)
	s_barrier
	s_setprio 1
	s_waitcnt lgkmcnt(0)
	v_mfma_f32_16x16x32_bf16 v[92:95], v[96:99], v[184:187], v[92:95]
	v_mfma_f32_16x16x32_bf16 v[84:87], v[150:153], v[184:187], v[84:87]
	v_mfma_f32_16x16x32_bf16 v[88:91], v[96:99], v[192:195], v[88:91]
	v_mfma_f32_16x16x32_bf16 v[80:83], v[150:153], v[192:195], v[80:83]
	v_mfma_f32_16x16x32_bf16 v[76:79], v[96:99], v[200:203], v[76:79]
	v_mfma_f32_16x16x32_bf16 v[68:71], v[150:153], v[200:203], v[68:71]
	v_mfma_f32_16x16x32_bf16 v[72:75], v[96:99], v[208:211], v[72:75]
	v_mfma_f32_16x16x32_bf16 v[64:67], v[150:153], v[208:211], v[64:67]
	v_mfma_f32_16x16x32_bf16 v[92:95], v[108:111], v[188:191], v[92:95]
	v_mfma_f32_16x16x32_bf16 v[84:87], v[154:157], v[188:191], v[84:87]
	v_mfma_f32_16x16x32_bf16 v[88:91], v[108:111], v[196:199], v[88:91]
	v_mfma_f32_16x16x32_bf16 v[80:83], v[154:157], v[196:199], v[80:83]
	v_mfma_f32_16x16x32_bf16 v[76:79], v[108:111], v[204:207], v[76:79]
	v_mfma_f32_16x16x32_bf16 v[68:71], v[154:157], v[204:207], v[68:71]
	v_mfma_f32_16x16x32_bf16 v[72:75], v[108:111], v[212:215], v[72:75]
	v_mfma_f32_16x16x32_bf16 v[64:67], v[154:157], v[212:215], v[64:67]
	s_setprio 0
	s_setprio 1
	v_mfma_f32_16x16x32_bf16 v[28:31], v[158:161], v[184:187], v[28:31]
	v_mfma_f32_16x16x32_bf16 v[20:23], v[166:169], v[184:187], v[20:23]
	v_mfma_f32_16x16x32_bf16 v[24:27], v[158:161], v[192:195], v[24:27]
	v_mfma_f32_16x16x32_bf16 v[16:19], v[166:169], v[192:195], v[16:19]
	v_mfma_f32_16x16x32_bf16 v[12:15], v[158:161], v[200:203], v[12:15]
	v_mfma_f32_16x16x32_bf16 v[4:7], v[166:169], v[200:203], v[4:7]
	v_mfma_f32_16x16x32_bf16 v[8:11], v[158:161], v[208:211], v[8:11]
	v_mfma_f32_16x16x32_bf16 v[0:3], v[166:169], v[208:211], v[0:3]
	v_mfma_f32_16x16x32_bf16 v[28:31], v[162:165], v[188:191], v[28:31]
	v_mfma_f32_16x16x32_bf16 v[20:23], v[180:183], v[188:191], v[20:23]
	v_mfma_f32_16x16x32_bf16 v[24:27], v[162:165], v[196:199], v[24:27]
	v_mfma_f32_16x16x32_bf16 v[16:19], v[180:183], v[196:199], v[16:19]
	v_mfma_f32_16x16x32_bf16 v[12:15], v[162:165], v[204:207], v[12:15]
	v_mfma_f32_16x16x32_bf16 v[4:7], v[180:183], v[204:207], v[4:7]
	v_mfma_f32_16x16x32_bf16 v[8:11], v[162:165], v[212:215], v[8:11]
	v_mfma_f32_16x16x32_bf16 v[0:3], v[180:183], v[212:215], v[0:3]
	s_setprio 0
	s_add_i32 s56, s56, 2
	s_add_u32 s4, s4, 0x100
	s_addc_u32 s5, s5, 0
	s_add_u32 s54, s54, 0x100
	s_addc_u32 s55, s55, 0
	s_cmp_gt_u32 s56, 13
	s_barrier
	s_cbranch_scc0 .LBB0_2022

; #define G_STAGE(bufoff, gbase, voff) do { _Pragma("unroll") for (int _i = 0; _i < 2; ++_i) \
;         __builtin_amdgcn_global_load_lds((const unsigned*)((const char*)(gbase) + voff[_i]), (LAS unsigned*)(lds + (bufoff) + ldsw + _i * 8192), 16, 0, 0); } while (0)
; #define G_LDA(dst, b, h) do { _Pragma("unroll") for (int m = 0; m < 4; ++m) _Pragma("unroll") for (int k = 0; k < 2; ++k) dst[m][k] = *(const LAS bf16x8*)(lds + G_SA(b, h) + aoff + m * 2048 + k * 1024); } while (0)
; #define G_LDB(dst, b, h) do { _Pragma("unroll") for (int n = 0; n < 2; ++n) _Pragma("unroll") for (int k = 0; k < 2; ++k) dst[n][k] = *(const LAS bf16x8*)(lds + G_SB(b, h) + boff + n * 2048 + k * 1024); } while (0)
; #define G_MMA(ai, bj, At_, Bt_) do { __builtin_amdgcn_s_setprio(1); _Pragma("unroll") for (int m = 0; m < 4; ++m) _Pragma("unroll") for (int n = 0; n < 2; ++n) _Pragma("unroll") for (int k = 0; k < 2; ++k) \
;         acc[ai][bj][m][n] = __builtin_amdgcn_mfma_f32_16x16x32_bf16(Bt_[n][k], At_[m][k], acc[ai][bj][m][n], 0, 0, 0); __builtin_amdgcn_s_setprio(0); } while (0)
; #define WAIT_V(n) asm volatile("s_waitcnt vmcnt(" #n ")" ::: "memory")
; #define WAIT_L(n) asm volatile("s_waitcnt lgkmcnt(" #n ")" ::: "memory")
; #define BAR __builtin_amdgcn_s_barrier()
; template <class Get, class Epi>
; DI void gemm_loop(int ntiles, int ld, char* shm, const Get& get, const Epi& epi) {
;     ...
;         const int Ln = L + gridDim.x; const bool has_next = Ln < ntiles; if (has_next) nxt = get(Ln);
;         const char* nA = has_next ? (const char*)nxt.A + (size_t)nxt.brow * ld * 2 : cA; const char* nB = has_next ? (const char*)nxt.Bt + (size_t)nxt.bcol * ld * 2 : cB;
;         const int nt = cur.K / BK;
;         for (int t = 0; t < nt; t += 2) {
;             const bool last = (t == nt - 2);
;             const char* a1 = cA + (size_t)(t + 1) * kstep;
;             const char* a2 = last ? nA : cA + (size_t)(t + 2) * kstep; const char* b2 = last ? nB : cB + (size_t)(t + 2) * kstep;
;             const char* a3 = a2 + kstep; const char* b3 = b2 + kstep;
;             G_LDB(B0, 0, 0); G_LDB(B1, 0, 1); SCHED; G_LDA(At, 0, 0); G_STAGE(G_SA(1, 1), a1 + hstep, voffA);
;             WAIT_V(8); WAIT_L(0); BAR; G_MMA(0, 0, At, B0); G_MMA(0, 1, At, B1); BAR; SCHED;
;             G_LDA(At, 0, 1); G_STAGE(G_SB(0, 0), b2, voffB); G_STAGE(G_SB(0, 1), b2 + hstep, voffB); G_STAGE(G_SA(0, 0), a2, voffA);
.Lpeel_2574:
	ds_read_b128 v[128:131], v169
	ds_read_b128 v[132:135], v169 offset:1024
	ds_read_b128 v[136:139], v169 offset:2048
	ds_read_b128 v[140:143], v169 offset:3072
	ds_read_b128 v[158:161], v170
	ds_read_b128 v[162:165], v170 offset:1024
	ds_read_b128 v[172:175], v170 offset:2048
	ds_read_b128 v[176:179], v170 offset:3072
	s_add_i32 s82, s14, 2
	s_add_u32 s15, s52, 0xfffc0080
	s_addc_u32 s46, s53, -1
	s_cmp_eq_u32 s79, s14
	s_cselect_b32 s14, s77, s80
	s_cselect_b32 s47, s3, s46
	s_cselect_b32 s46, s41, s15
	s_cselect_b32 s15, s43, s81
	v_lshl_add_u64 v[144:145], s[52:53], 0, v[154:155]
	s_add_i32 m0, s51, 0xc000
	ds_read_b128 v[180:183], v171
	ds_read_b128 v[184:187], v171 offset:1024
	ds_read_b128 v[188:191], v171 offset:2048
	ds_read_b128 v[192:195], v171 offset:3072
	ds_read_b128 v[196:199], v171 offset:4096
	ds_read_b128 v[200:203], v171 offset:5120
	ds_read_b128 v[204:207], v171 offset:6144
	ds_read_b128 v[208:211], v171 offset:7168
	global_load_lds_dwordx4 v[144:145], off
	v_lshl_add_u64 v[144:145], s[52:53], 0, v[156:157]
	s_add_i32 m0, s51, 0xe000
	s_nop 0
	global_load_lds_dwordx4 v[144:145], off
	s_waitcnt vmcnt(8)
	s_waitcnt lgkmcnt(0)
	s_barrier
	s_setprio 1
	s_waitcnt lgkmcnt(0)
	v_mfma_f32_16x16x32_bf16 v[124:127], v[128:131], v[180:183], 0
	v_mfma_f32_16x16x32_bf16 v[120:123], v[136:139], v[180:183], 0
	v_mfma_f32_16x16x32_bf16 v[116:119], v[128:131], v[188:191], 0
	v_mfma_f32_16x16x32_bf16 v[112:115], v[136:139], v[188:191], 0
	v_mfma_f32_16x16x32_bf16 v[108:111], v[128:131], v[196:199], 0
	v_mfma_f32_16x16x32_bf16 v[104:107], v[136:139], v[196:199], 0
	v_mfma_f32_16x16x32_bf16 v[100:103], v[128:131], v[204:207], 0
	v_mfma_f32_16x16x32_bf16 v[96:99], v[136:139], v[204:207], 0
	v_mfma_f32_16x16x32_bf16 v[124:127], v[132:135], v[184:187], v[124:127]
	v_mfma_f32_16x16x32_bf16 v[120:123], v[140:143], v[184:187], v[120:123]
	v_mfma_f32_16x16x32_bf16 v[116:119], v[132:135], v[192:195], v[116:119]
	v_mfma_f32_16x16x32_bf16 v[112:115], v[140:143], v[192:195], v[112:115]
	v_mfma_f32_16x16x32_bf16 v[108:111], v[132:135], v[200:203], v[108:111]
	v_mfma_f32_16x16x32_bf16 v[104:107], v[140:143], v[200:203], v[104:107]
	v_mfma_f32_16x16x32_bf16 v[100:103], v[132:135], v[208:211], v[100:103]
	v_mfma_f32_16x16x32_bf16 v[96:99], v[140:143], v[208:211], v[96:99]
	s_setprio 0
	s_setprio 1
	v_mfma_f32_16x16x32_bf16 v[60:63], v[158:161], v[180:183], 0
	v_mfma_f32_16x16x32_bf16 v[56:59], v[172:175], v[180:183], 0
	v_mfma_f32_16x16x32_bf16 v[52:55], v[158:161], v[188:191], 0
	v_mfma_f32_16x16x32_bf16 v[48:51], v[172:175], v[188:191], 0
	v_mfma_f32_16x16x32_bf16 v[44:47], v[158:161], v[196:199], 0
	v_mfma_f32_16x16x32_bf16 v[40:43], v[172:175], v[196:199], 0
	v_mfma_f32_16x16x32_bf16 v[36:39], v[158:161], v[204:207], 0
	v_mfma_f32_16x16x32_bf16 v[32:35], v[172:175], v[204:207], 0
	v_mfma_f32_16x16x32_bf16 v[60:63], v[162:165], v[184:187], v[60:63]
	v_mfma_f32_16x16x32_bf16 v[56:59], v[176:179], v[184:187], v[56:59]
	v_mfma_f32_16x16x32_bf16 v[52:55], v[162:165], v[192:195], v[52:55]
	v_mfma_f32_16x16x32_bf16 v[48:51], v[176:179], v[192:195], v[48:51]
	v_mfma_f32_16x16x32_bf16 v[44:47], v[162:165], v[200:203], v[44:47]
	v_mfma_f32_16x16x32_bf16 v[40:43], v[176:179], v[200:203], v[40:43]
	v_mfma_f32_16x16x32_bf16 v[36:39], v[162:165], v[208:211], v[36:39]
	v_mfma_f32_16x16x32_bf16 v[32:35], v[176:179], v[208:211], v[32:35]
	s_setprio 0
	s_add_i32 s83, s72, s31
	v_lshl_add_u64 v[144:145], s[14:15], 0, v[148:149]
	s_mov_b32 m0, s83
	s_barrier
	ds_read_b128 v[180:183], v171 offset:16384
	ds_read_b128 v[184:187], v171 offset:17408
	ds_read_b128 v[188:191], v171 offset:18432
	ds_read_b128 v[192:195], v171 offset:19456
	ds_read_b128 v[196:199], v171 offset:20480
	ds_read_b128 v[200:203], v171 offset:21504
	ds_read_b128 v[204:207], v171 offset:22528
	ds_read_b128 v[208:211], v171 offset:23552
	global_load_lds_dwordx4 v[144:145], off
	s_add_i32 m0, s83, 0x2000
	s_add_u32 s84, s14, 0x40000
	v_lshl_add_u64 v[166:167], s[14:15], 0, v[152:153]
	s_addc_u32 s85, s15, 0
	s_add_i32 s83, s73, s31
	global_load_lds_dwordx4 v[166:167], off
	v_lshl_add_u64 v[212:213], s[84:85], 0, v[148:149]
	s_mov_b32 m0, s83
	v_lshl_add_u64 v[214:215], s[46:47], 0, v[150:151]
	global_load_lds_dwordx4 v[212:213], off
	v_lshl_add_u64 v[212:213], s[84:85], 0, v[152:153]
	s_add_i32 m0, s83, 0x2000
	s_nop 0
	global_load_lds_dwordx4 v[212:213], off
	v_lshl_add_u64 v[212:213], s[46:47], 0, v[146:147]
	s_mov_b32 m0, s51
	s_nop 0
	global_load_lds_dwordx4 v[212:213], off
	s_mov_b32 m0, s54
	s_nop 0
	global_load_lds_dwordx4 v[214:215], off
	s_waitcnt vmcnt(8)
	s_waitcnt lgkmcnt(0)
	s_barrier
; #define G_STAGE(bufoff, gbase, voff) do { _Pragma("unroll") for (int _i = 0; _i < 2; ++_i) \
;         __builtin_amdgcn_global_load_lds((const unsigned*)((const char*)(gbase) + voff[_i]), (LAS unsigned*)(lds + (bufoff) + ldsw + _i * 8192), 16, 0, 0); } while (0)
; #define G_LDA(dst, b, h) do { _Pragma("unroll") for (int m = 0; m < 4; ++m) _Pragma("unroll") for (int k = 0; k < 2; ++k) dst[m][k] = *(const LAS bf16x8*)(lds + G_SA(b, h) + aoff + m * 2048 + k * 1024); } while (0)
; #define G_LDB(dst, b, h) do { _Pragma("unroll") for (int n = 0; n < 2; ++n) _Pragma("unroll") for (int k = 0; k < 2; ++k) dst[n][k] = *(const LAS bf16x8*)(lds + G_SB(b, h) + boff + n * 2048 + k * 1024); } while (0)
; #define G_MMA(ai, bj, At_, Bt_) do { __builtin_amdgcn_s_setprio(1); _Pragma("unroll") for (int m = 0; m < 4; ++m) _Pragma("unroll") for (int n = 0; n < 2; ++n) _Pragma("unroll") for (int k = 0; k < 2; ++k) \
;         acc[ai][bj][m][n] = __builtin_amdgcn_mfma_f32_16x16x32_bf16(Bt_[n][k], At_[m][k], acc[ai][bj][m][n], 0, 0, 0); __builtin_amdgcn_s_setprio(0); } while (0)
; #define WAIT_V(n) asm volatile("s_waitcnt vmcnt(" #n ")" ::: "memory")
; #define WAIT_L(n) asm volatile("s_waitcnt lgkmcnt(" #n ")" ::: "memory")
; #define BAR __builtin_amdgcn_s_barrier()
; #define SCHED __builtin_amdgcn_sched_barrier(0)
; template <class Get, class Epi>
; DI void gemm_loop(int ntiles, int ld, char* shm, const Get& get, const Epi& epi) {
;     ...
;             WAIT_V(8); WAIT_L(0); BAR; G_MMA(1, 0, At, B0); G_MMA(1, 1, At, B1); BAR; SCHED;
;             G_LDB(B0, 1, 0); G_LDB(B1, 1, 1); SCHED; G_LDA(At, 1, 0); G_STAGE(G_SA(0, 1), a2 + hstep, voffA);
;             WAIT_V(8); WAIT_L(0); BAR; G_MMA(0, 0, At, B0); G_MMA(0, 1, At, B1); BAR; SCHED;
	s_setprio 1
	s_waitcnt lgkmcnt(0)
	v_mfma_f32_16x16x32_bf16 v[92:95], v[128:131], v[180:183], 0
	v_mfma_f32_16x16x32_bf16 v[88:91], v[136:139], v[180:183], 0
	v_mfma_f32_16x16x32_bf16 v[84:87], v[128:131], v[188:191], 0
	v_mfma_f32_16x16x32_bf16 v[80:83], v[136:139], v[188:191], 0
	v_mfma_f32_16x16x32_bf16 v[76:79], v[128:131], v[196:199], 0
	v_mfma_f32_16x16x32_bf16 v[72:75], v[136:139], v[196:199], 0
	v_mfma_f32_16x16x32_bf16 v[68:71], v[128:131], v[204:207], 0
	v_mfma_f32_16x16x32_bf16 v[64:67], v[136:139], v[204:207], 0
	v_mfma_f32_16x16x32_bf16 v[92:95], v[132:135], v[184:187], v[92:95]
	v_mfma_f32_16x16x32_bf16 v[88:91], v[140:143], v[184:187], v[88:91]
	v_mfma_f32_16x16x32_bf16 v[84:87], v[132:135], v[192:195], v[84:87]
	v_mfma_f32_16x16x32_bf16 v[80:83], v[140:143], v[192:195], v[80:83]
	v_mfma_f32_16x16x32_bf16 v[76:79], v[132:135], v[200:203], v[76:79]
	v_mfma_f32_16x16x32_bf16 v[72:75], v[140:143], v[200:203], v[72:75]
	v_mfma_f32_16x16x32_bf16 v[68:71], v[132:135], v[208:211], v[68:71]
	v_mfma_f32_16x16x32_bf16 v[64:67], v[140:143], v[208:211], v[64:67]
	s_setprio 0
	s_setprio 1
	v_mfma_f32_16x16x32_bf16 v[28:31], v[158:161], v[180:183], 0
	v_mfma_f32_16x16x32_bf16 v[24:27], v[172:175], v[180:183], 0
	v_mfma_f32_16x16x32_bf16 v[20:23], v[158:161], v[188:191], 0
	v_mfma_f32_16x16x32_bf16 v[16:19], v[172:175], v[188:191], 0
	v_mfma_f32_16x16x32_bf16 v[12:15], v[158:161], v[196:199], 0
	v_mfma_f32_16x16x32_bf16 v[8:11], v[172:175], v[196:199], 0
	v_mfma_f32_16x16x32_bf16 v[4:7], v[158:161], v[204:207], 0
	v_mfma_f32_16x16x32_bf16 v[0:3], v[172:175], v[204:207], 0
	v_mfma_f32_16x16x32_bf16 v[28:31], v[162:165], v[184:187], v[28:31]
	v_mfma_f32_16x16x32_bf16 v[24:27], v[176:179], v[184:187], v[24:27]
	v_mfma_f32_16x16x32_bf16 v[20:23], v[162:165], v[192:195], v[20:23]
	v_mfma_f32_16x16x32_bf16 v[16:19], v[176:179], v[192:195], v[16:19]
	v_mfma_f32_16x16x32_bf16 v[12:15], v[162:165], v[200:203], v[12:15]
	v_mfma_f32_16x16x32_bf16 v[8:11], v[176:179], v[200:203], v[8:11]
	v_mfma_f32_16x16x32_bf16 v[4:7], v[162:165], v[208:211], v[4:7]
	v_mfma_f32_16x16x32_bf16 v[0:3], v[176:179], v[208:211], v[0:3]
	s_setprio 0
	s_add_i32 s83, 0, 0x18000
	s_add_i32 s84, 0, 0x1c000
	v_add_u32_e32 v140, s83, v168
	s_barrier
	v_add_u32_e32 v176, s84, v168
	ds_read_b128 v[128:131], v140
	ds_read_b128 v[132:135], v140 offset:1024
	ds_read_b128 v[136:139], v140 offset:2048
	ds_read_b128 v[140:143], v140 offset:3072
	ds_read_b128 v[158:161], v176
	ds_read_b128 v[162:165], v176 offset:1024
	ds_read_b128 v[172:175], v176 offset:2048
	ds_read_b128 v[176:179], v176 offset:3072
	s_add_u32 s46, s46, 0x40000
	s_addc_u32 s47, s47, 0
	s_mov_b32 m0, s55
	v_lshl_add_u64 v[216:217], s[46:47], 0, v[146:147]
	ds_read_b128 v[180:183], v171 offset:32768
	ds_read_b128 v[184:187], v171 offset:33792
	ds_read_b128 v[188:191], v171 offset:34816
	ds_read_b128 v[192:195], v171 offset:35840
	ds_read_b128 v[196:199], v171 offset:36864
	ds_read_b128 v[200:203], v171 offset:37888
	ds_read_b128 v[204:207], v171 offset:38912
	ds_read_b128 v[208:211], v171 offset:39936
	global_load_lds_dwordx4 v[216:217], off
	v_lshl_add_u64 v[216:217], s[46:47], 0, v[150:151]
	s_mov_b32 m0, s56
	s_nop 0
	global_load_lds_dwordx4 v[216:217], off
	s_waitcnt vmcnt(8)
	s_waitcnt lgkmcnt(0)
	s_barrier
	s_setprio 1
	s_waitcnt lgkmcnt(0)
	v_mfma_f32_16x16x32_bf16 v[124:127], v[128:131], v[180:183], v[124:127]
	v_mfma_f32_16x16x32_bf16 v[120:123], v[136:139], v[180:183], v[120:123]
	v_mfma_f32_16x16x32_bf16 v[116:119], v[128:131], v[188:191], v[116:119]
	v_mfma_f32_16x16x32_bf16 v[112:115], v[136:139], v[188:191], v[112:115]
	v_mfma_f32_16x16x32_bf16 v[108:111], v[128:131], v[196:199], v[108:111]
	v_mfma_f32_16x16x32_bf16 v[104:107], v[136:139], v[196:199], v[104:107]
	v_mfma_f32_16x16x32_bf16 v[100:103], v[128:131], v[204:207], v[100:103]
	v_mfma_f32_16x16x32_bf16 v[96:99], v[136:139], v[204:207], v[96:99]
	v_mfma_f32_16x16x32_bf16 v[124:127], v[132:135], v[184:187], v[124:127]
	v_mfma_f32_16x16x32_bf16 v[120:123], v[140:143], v[184:187], v[120:123]
	v_mfma_f32_16x16x32_bf16 v[116:119], v[132:135], v[192:195], v[116:119]
	v_mfma_f32_16x16x32_bf16 v[112:115], v[140:143], v[192:195], v[112:115]
	v_mfma_f32_16x16x32_bf16 v[108:111], v[132:135], v[200:203], v[108:111]
	v_mfma_f32_16x16x32_bf16 v[104:107], v[140:143], v[200:203], v[104:107]
	v_mfma_f32_16x16x32_bf16 v[100:103], v[132:135], v[208:211], v[100:103]
	v_mfma_f32_16x16x32_bf16 v[96:99], v[140:143], v[208:211], v[96:99]
	s_setprio 0
	s_setprio 1
	v_mfma_f32_16x16x32_bf16 v[60:63], v[158:161], v[180:183], v[60:63]
	v_mfma_f32_16x16x32_bf16 v[56:59], v[172:175], v[180:183], v[56:59]
	v_mfma_f32_16x16x32_bf16 v[52:55], v[158:161], v[188:191], v[52:55]
	v_mfma_f32_16x16x32_bf16 v[48:51], v[172:175], v[188:191], v[48:51]
	v_mfma_f32_16x16x32_bf16 v[44:47], v[158:161], v[196:199], v[44:47]
	v_mfma_f32_16x16x32_bf16 v[40:43], v[172:175], v[196:199], v[40:43]
	v_mfma_f32_16x16x32_bf16 v[36:39], v[158:161], v[204:207], v[36:39]
	v_mfma_f32_16x16x32_bf16 v[32:35], v[172:175], v[204:207], v[32:35]
	v_mfma_f32_16x16x32_bf16 v[60:63], v[162:165], v[184:187], v[60:63]
	v_mfma_f32_16x16x32_bf16 v[56:59], v[176:179], v[184:187], v[56:59]
	v_mfma_f32_16x16x32_bf16 v[52:55], v[162:165], v[192:195], v[52:55]
	v_mfma_f32_16x16x32_bf16 v[48:51], v[176:179], v[192:195], v[48:51]
	v_mfma_f32_16x16x32_bf16 v[44:47], v[162:165], v[200:203], v[44:47]
	v_mfma_f32_16x16x32_bf16 v[40:43], v[176:179], v[200:203], v[40:43]
	v_mfma_f32_16x16x32_bf16 v[36:39], v[162:165], v[208:211], v[36:39]
	v_mfma_f32_16x16x32_bf16 v[32:35], v[176:179], v[208:211], v[32:35]
	s_setprio 0
	s_add_i32 s46, s83, s31
	v_lshl_add_u64 v[144:145], v[144:145], 0, s[8:9]
	s_mov_b32 m0, s46
	s_barrier
; #define G_STAGE(bufoff, gbase, voff) do { _Pragma("unroll") for (int _i = 0; _i < 2; ++_i) \
;         __builtin_amdgcn_global_load_lds((const unsigned*)((const char*)(gbase) + voff[_i]), (LAS unsigned*)(lds + (bufoff) + ldsw + _i * 8192), 16, 0, 0); } while (0)
; #define G_LDA(dst, b, h) do { _Pragma("unroll") for (int m = 0; m < 4; ++m) _Pragma("unroll") for (int k = 0; k < 2; ++k) dst[m][k] = *(const LAS bf16x8*)(lds + G_SA(b, h) + aoff + m * 2048 + k * 1024); } while (0)
; #define G_LDB(dst, b, h) do { _Pragma("unroll") for (int n = 0; n < 2; ++n) _Pragma("unroll") for (int k = 0; k < 2; ++k) dst[n][k] = *(const LAS bf16x8*)(lds + G_SB(b, h) + boff + n * 2048 + k * 1024); } while (0)
; #define G_MMA(ai, bj, At_, Bt_) do { __builtin_amdgcn_s_setprio(1); _Pragma("unroll") for (int m = 0; m < 4; ++m) _Pragma("unroll") for (int n = 0; n < 2; ++n) _Pragma("unroll") for (int k = 0; k < 2; ++k) \
;         acc[ai][bj][m][n] = __builtin_amdgcn_mfma_f32_16x16x32_bf16(Bt_[n][k], At_[m][k], acc[ai][bj][m][n], 0, 0, 0); __builtin_amdgcn_s_setprio(0); } while (0)
; #define WAIT_V(n) asm volatile("s_waitcnt vmcnt(" #n ")" ::: "memory")
; #define WAIT_L(n) asm volatile("s_waitcnt lgkmcnt(" #n ")" ::: "memory")
; #define BAR __builtin_amdgcn_s_barrier()
; #define SCHED __builtin_amdgcn_sched_barrier(0)
; template <class Get, class Epi>
; DI void gemm_loop(int ntiles, int ld, char* shm, const Get& get, const Epi& epi) {
;     ...
;             G_LDB(B0, 0, 0); G_LDB(B1, 0, 1); SCHED; G_LDA(At, 0, 0); G_STAGE(G_SA(1, 1), a1 + hstep, voffA);
;             WAIT_V(8); WAIT_L(0); BAR; G_MMA(0, 0, At, B0); G_MMA(0, 1, At, B1); BAR; SCHED;
;     ...
;             G_LDA(At, 1, 1); G_STAGE(G_SB(1, 0), b3, voffB); G_STAGE(G_SB(1, 1), b3 + hstep, voffB); G_STAGE(G_SA(1, 0), a3, voffA);
;             WAIT_V(8); WAIT_L(0); BAR; G_MMA(1, 0, At, B0); G_MMA(1, 1, At, B1); BAR; SCHED;
	ds_read_b128 v[180:183], v171 offset:49152
	ds_read_b128 v[184:187], v171 offset:50176
	ds_read_b128 v[188:191], v171 offset:51200
	ds_read_b128 v[192:195], v171 offset:52224
	ds_read_b128 v[196:199], v171 offset:53248
	ds_read_b128 v[200:203], v171 offset:54272
	ds_read_b128 v[204:207], v171 offset:55296
	ds_read_b128 v[208:211], v171 offset:56320
	global_load_lds_dwordx4 v[144:145], off
	s_add_i32 m0, s46, 0x2000
	s_add_u32 s14, s14, 0x40080
	v_lshl_add_u64 v[144:145], v[166:167], 0, s[8:9]
	s_addc_u32 s15, s15, 0
	s_add_i32 s46, s84, s31
	global_load_lds_dwordx4 v[144:145], off
	v_lshl_add_u64 v[144:145], s[14:15], 0, v[148:149]
	s_mov_b32 m0, s46
	s_nop 0
	global_load_lds_dwordx4 v[144:145], off
	v_lshl_add_u64 v[144:145], s[14:15], 0, v[152:153]
	s_add_i32 m0, s46, 0x2000
	s_nop 0
	global_load_lds_dwordx4 v[144:145], off
	v_lshl_add_u64 v[144:145], v[212:213], 0, s[8:9]
	s_mov_b32 m0, s59
	s_nop 0
	global_load_lds_dwordx4 v[144:145], off
	v_lshl_add_u64 v[144:145], v[214:215], 0, s[8:9]
	s_mov_b32 m0, s71
	s_nop 0
	global_load_lds_dwordx4 v[144:145], off
	s_waitcnt vmcnt(8)
	s_waitcnt lgkmcnt(0)
	s_barrier
	s_setprio 1
	s_waitcnt lgkmcnt(0)
	v_mfma_f32_16x16x32_bf16 v[92:95], v[128:131], v[180:183], v[92:95]
	v_mfma_f32_16x16x32_bf16 v[88:91], v[136:139], v[180:183], v[88:91]
	v_mfma_f32_16x16x32_bf16 v[84:87], v[128:131], v[188:191], v[84:87]
	v_mfma_f32_16x16x32_bf16 v[80:83], v[136:139], v[188:191], v[80:83]
	v_mfma_f32_16x16x32_bf16 v[76:79], v[128:131], v[196:199], v[76:79]
	v_mfma_f32_16x16x32_bf16 v[72:75], v[136:139], v[196:199], v[72:75]
	v_mfma_f32_16x16x32_bf16 v[68:71], v[128:131], v[204:207], v[68:71]
	v_mfma_f32_16x16x32_bf16 v[64:67], v[136:139], v[204:207], v[64:67]
	v_mfma_f32_16x16x32_bf16 v[92:95], v[132:135], v[184:187], v[92:95]
	v_mfma_f32_16x16x32_bf16 v[88:91], v[140:143], v[184:187], v[88:91]
	v_mfma_f32_16x16x32_bf16 v[84:87], v[132:135], v[192:195], v[84:87]
	v_mfma_f32_16x16x32_bf16 v[80:83], v[140:143], v[192:195], v[80:83]
	v_mfma_f32_16x16x32_bf16 v[76:79], v[132:135], v[200:203], v[76:79]
	v_mfma_f32_16x16x32_bf16 v[72:75], v[140:143], v[200:203], v[72:75]
	v_mfma_f32_16x16x32_bf16 v[68:71], v[132:135], v[208:211], v[68:71]
	v_mfma_f32_16x16x32_bf16 v[64:67], v[140:143], v[208:211], v[64:67]
	s_setprio 0
	s_setprio 1
	v_mfma_f32_16x16x32_bf16 v[28:31], v[158:161], v[180:183], v[28:31]
	v_mfma_f32_16x16x32_bf16 v[24:27], v[172:175], v[180:183], v[24:27]
	v_mfma_f32_16x16x32_bf16 v[20:23], v[158:161], v[188:191], v[20:23]
	v_mfma_f32_16x16x32_bf16 v[16:19], v[172:175], v[188:191], v[16:19]
	v_mfma_f32_16x16x32_bf16 v[12:15], v[158:161], v[196:199], v[12:15]
	v_mfma_f32_16x16x32_bf16 v[8:11], v[172:175], v[196:199], v[8:11]
	v_mfma_f32_16x16x32_bf16 v[4:7], v[158:161], v[204:207], v[4:7]
	v_mfma_f32_16x16x32_bf16 v[0:3], v[172:175], v[204:207], v[0:3]
	v_mfma_f32_16x16x32_bf16 v[28:31], v[162:165], v[184:187], v[28:31]
	v_mfma_f32_16x16x32_bf16 v[24:27], v[176:179], v[184:187], v[24:27]
	v_mfma_f32_16x16x32_bf16 v[20:23], v[162:165], v[192:195], v[20:23]
	v_mfma_f32_16x16x32_bf16 v[16:19], v[176:179], v[192:195], v[16:19]
	v_mfma_f32_16x16x32_bf16 v[12:15], v[162:165], v[200:203], v[12:15]
	v_mfma_f32_16x16x32_bf16 v[8:11], v[176:179], v[200:203], v[8:11]
	v_mfma_f32_16x16x32_bf16 v[4:7], v[162:165], v[208:211], v[4:7]
	v_mfma_f32_16x16x32_bf16 v[0:3], v[176:179], v[208:211], v[0:3]
	s_setprio 0
	s_add_u32 s52, s52, 0x100
	s_addc_u32 s53, s53, 0
	s_add_u32 s80, s80, 0x100
	s_addc_u32 s81, s81, 0
	s_cmp_ge_u32 s82, s78
	s_mov_b32 s14, s82
	s_barrier
	s_cbranch_scc0 .LBB0_2574
	s_branch .Lpost_2574
.LBB0_2574:
	ds_read_b128 v[128:131], v169
	ds_read_b128 v[132:135], v169 offset:1024
	ds_read_b128 v[136:139], v169 offset:2048
	ds_read_b128 v[140:143], v169 offset:3072
	ds_read_b128 v[158:161], v170
	ds_read_b128 v[162:165], v170 offset:1024
	ds_read_b128 v[172:175], v170 offset:2048
	ds_read_b128 v[176:179], v170 offset:3072
	s_add_i32 s82, s14, 2
	s_add_u32 s15, s52, 0xfffc0080
	s_addc_u32 s46, s53, -1
	s_cmp_eq_u32 s79, s14
	s_cselect_b32 s14, s77, s80
	s_cselect_b32 s47, s3, s46
	s_cselect_b32 s46, s41, s15
	s_cselect_b32 s15, s43, s81
	v_lshl_add_u64 v[144:145], s[52:53], 0, v[154:155]
	s_add_i32 m0, s51, 0xc000
	ds_read_b128 v[180:183], v171
	ds_read_b128 v[184:187], v171 offset:1024
	ds_read_b128 v[188:191], v171 offset:2048
	ds_read_b128 v[192:195], v171 offset:3072
	ds_read_b128 v[196:199], v171 offset:4096
	ds_read_b128 v[200:203], v171 offset:5120
	ds_read_b128 v[204:207], v171 offset:6144
	ds_read_b128 v[208:211], v171 offset:7168
	global_load_lds_dwordx4 v[144:145], off
	v_lshl_add_u64 v[144:145], s[52:53], 0, v[156:157]
	s_add_i32 m0, s51, 0xe000
	s_nop 0
	global_load_lds_dwordx4 v[144:145], off
	s_waitcnt vmcnt(8)
	s_waitcnt lgkmcnt(0)
	s_barrier
; #define G_STAGE(bufoff, gbase, voff) do { _Pragma("unroll") for (int _i = 0; _i < 2; ++_i) \
;         __builtin_amdgcn_global_load_lds((const unsigned*)((const char*)(gbase) + voff[_i]), (LAS unsigned*)(lds + (bufoff) + ldsw + _i * 8192), 16, 0, 0); } while (0)
; #define G_LDA(dst, b, h) do { _Pragma("unroll") for (int m = 0; m < 4; ++m) _Pragma("unroll") for (int k = 0; k < 2; ++k) dst[m][k] = *(const LAS bf16x8*)(lds + G_SA(b, h) + aoff + m * 2048 + k * 1024); } while (0)
; #define G_MMA(ai, bj, At_, Bt_) do { __builtin_amdgcn_s_setprio(1); _Pragma("unroll") for (int m = 0; m < 4; ++m) _Pragma("unroll") for (int n = 0; n < 2; ++n) _Pragma("unroll") for (int k = 0; k < 2; ++k) \
;         acc[ai][bj][m][n] = __builtin_amdgcn_mfma_f32_16x16x32_bf16(Bt_[n][k], At_[m][k], acc[ai][bj][m][n], 0, 0, 0); __builtin_amdgcn_s_setprio(0); } while (0)
; #define WAIT_V(n) asm volatile("s_waitcnt vmcnt(" #n ")" ::: "memory")
; #define WAIT_L(n) asm volatile("s_waitcnt lgkmcnt(" #n ")" ::: "memory")
; #define BAR __builtin_amdgcn_s_barrier()
; #define SCHED __builtin_amdgcn_sched_barrier(0)
; template <class Get, class Epi>
; DI void gemm_loop(int ntiles, int ld, char* shm, const Get& get, const Epi& epi) {
;     ...
;             WAIT_V(8); WAIT_L(0); BAR; G_MMA(0, 0, At, B0); G_MMA(0, 1, At, B1); BAR; SCHED;
;             G_LDA(At, 0, 1); G_STAGE(G_SB(0, 0), b2, voffB); G_STAGE(G_SB(0, 1), b2 + hstep, voffB); G_STAGE(G_SA(0, 0), a2, voffA);
;             WAIT_V(8); WAIT_L(0); BAR; G_MMA(1, 0, At, B0); G_MMA(1, 1, At, B1); BAR; SCHED;
	s_setprio 1
	s_waitcnt lgkmcnt(0)
	v_mfma_f32_16x16x32_bf16 v[124:127], v[128:131], v[180:183], v[124:127]
	v_mfma_f32_16x16x32_bf16 v[120:123], v[136:139], v[180:183], v[120:123]
	v_mfma_f32_16x16x32_bf16 v[116:119], v[128:131], v[188:191], v[116:119]
	v_mfma_f32_16x16x32_bf16 v[112:115], v[136:139], v[188:191], v[112:115]
	v_mfma_f32_16x16x32_bf16 v[108:111], v[128:131], v[196:199], v[108:111]
	v_mfma_f32_16x16x32_bf16 v[104:107], v[136:139], v[196:199], v[104:107]
	v_mfma_f32_16x16x32_bf16 v[100:103], v[128:131], v[204:207], v[100:103]
	v_mfma_f32_16x16x32_bf16 v[96:99], v[136:139], v[204:207], v[96:99]
	v_mfma_f32_16x16x32_bf16 v[124:127], v[132:135], v[184:187], v[124:127]
	v_mfma_f32_16x16x32_bf16 v[120:123], v[140:143], v[184:187], v[120:123]
	v_mfma_f32_16x16x32_bf16 v[116:119], v[132:135], v[192:195], v[116:119]
	v_mfma_f32_16x16x32_bf16 v[112:115], v[140:143], v[192:195], v[112:115]
	v_mfma_f32_16x16x32_bf16 v[108:111], v[132:135], v[200:203], v[108:111]
	v_mfma_f32_16x16x32_bf16 v[104:107], v[140:143], v[200:203], v[104:107]
	v_mfma_f32_16x16x32_bf16 v[100:103], v[132:135], v[208:211], v[100:103]
	v_mfma_f32_16x16x32_bf16 v[96:99], v[140:143], v[208:211], v[96:99]
	s_setprio 0
	s_setprio 1
	v_mfma_f32_16x16x32_bf16 v[60:63], v[158:161], v[180:183], v[60:63]
	v_mfma_f32_16x16x32_bf16 v[56:59], v[172:175], v[180:183], v[56:59]
	v_mfma_f32_16x16x32_bf16 v[52:55], v[158:161], v[188:191], v[52:55]
	v_mfma_f32_16x16x32_bf16 v[48:51], v[172:175], v[188:191], v[48:51]
	v_mfma_f32_16x16x32_bf16 v[44:47], v[158:161], v[196:199], v[44:47]
	v_mfma_f32_16x16x32_bf16 v[40:43], v[172:175], v[196:199], v[40:43]
	v_mfma_f32_16x16x32_bf16 v[36:39], v[158:161], v[204:207], v[36:39]
	v_mfma_f32_16x16x32_bf16 v[32:35], v[172:175], v[204:207], v[32:35]
	v_mfma_f32_16x16x32_bf16 v[60:63], v[162:165], v[184:187], v[60:63]
	v_mfma_f32_16x16x32_bf16 v[56:59], v[176:179], v[184:187], v[56:59]
	v_mfma_f32_16x16x32_bf16 v[52:55], v[162:165], v[192:195], v[52:55]
	v_mfma_f32_16x16x32_bf16 v[48:51], v[176:179], v[192:195], v[48:51]
	v_mfma_f32_16x16x32_bf16 v[44:47], v[162:165], v[200:203], v[44:47]
	v_mfma_f32_16x16x32_bf16 v[40:43], v[176:179], v[200:203], v[40:43]
	v_mfma_f32_16x16x32_bf16 v[36:39], v[162:165], v[208:211], v[36:39]
	v_mfma_f32_16x16x32_bf16 v[32:35], v[176:179], v[208:211], v[32:35]
	s_setprio 0
	s_add_i32 s83, s72, s31
	v_lshl_add_u64 v[144:145], s[14:15], 0, v[148:149]
	s_mov_b32 m0, s83
	s_barrier
	ds_read_b128 v[180:183], v171 offset:16384
	ds_read_b128 v[184:187], v171 offset:17408
	ds_read_b128 v[188:191], v171 offset:18432
	ds_read_b128 v[192:195], v171 offset:19456
	ds_read_b128 v[196:199], v171 offset:20480
	ds_read_b128 v[200:203], v171 offset:21504
	ds_read_b128 v[204:207], v171 offset:22528
	ds_read_b128 v[208:211], v171 offset:23552
	global_load_lds_dwordx4 v[144:145], off
	s_add_i32 m0, s83, 0x2000
	s_add_u32 s84, s14, 0x40000
	v_lshl_add_u64 v[166:167], s[14:15], 0, v[152:153]
	s_addc_u32 s85, s15, 0
	s_add_i32 s83, s73, s31
	global_load_lds_dwordx4 v[166:167], off
	v_lshl_add_u64 v[212:213], s[84:85], 0, v[148:149]
	s_mov_b32 m0, s83
	v_lshl_add_u64 v[214:215], s[46:47], 0, v[150:151]
	global_load_lds_dwordx4 v[212:213], off
	v_lshl_add_u64 v[212:213], s[84:85], 0, v[152:153]
	s_add_i32 m0, s83, 0x2000
	s_nop 0
	global_load_lds_dwordx4 v[212:213], off
	v_lshl_add_u64 v[212:213], s[46:47], 0, v[146:147]
	s_mov_b32 m0, s51
	s_nop 0
	global_load_lds_dwordx4 v[212:213], off
	s_mov_b32 m0, s54
	s_nop 0
	global_load_lds_dwordx4 v[214:215], off
	s_waitcnt vmcnt(8)
	s_waitcnt lgkmcnt(0)
	s_barrier
	s_setprio 1
	s_waitcnt lgkmcnt(0)
	v_mfma_f32_16x16x32_bf16 v[92:95], v[128:131], v[180:183], v[92:95]
	v_mfma_f32_16x16x32_bf16 v[88:91], v[136:139], v[180:183], v[88:91]
	v_mfma_f32_16x16x32_bf16 v[84:87], v[128:131], v[188:191], v[84:87]
	v_mfma_f32_16x16x32_bf16 v[80:83], v[136:139], v[188:191], v[80:83]
	v_mfma_f32_16x16x32_bf16 v[76:79], v[128:131], v[196:199], v[76:79]
	v_mfma_f32_16x16x32_bf16 v[72:75], v[136:139], v[196:199], v[72:75]
	v_mfma_f32_16x16x32_bf16 v[68:71], v[128:131], v[204:207], v[68:71]
	v_mfma_f32_16x16x32_bf16 v[64:67], v[136:139], v[204:207], v[64:67]
	v_mfma_f32_16x16x32_bf16 v[92:95], v[132:135], v[184:187], v[92:95]
	v_mfma_f32_16x16x32_bf16 v[88:91], v[140:143], v[184:187], v[88:91]
	v_mfma_f32_16x16x32_bf16 v[84:87], v[132:135], v[192:195], v[84:87]
	v_mfma_f32_16x16x32_bf16 v[80:83], v[140:143], v[192:195], v[80:83]
	v_mfma_f32_16x16x32_bf16 v[76:79], v[132:135], v[200:203], v[76:79]
	v_mfma_f32_16x16x32_bf16 v[72:75], v[140:143], v[200:203], v[72:75]
	v_mfma_f32_16x16x32_bf16 v[68:71], v[132:135], v[208:211], v[68:71]
	v_mfma_f32_16x16x32_bf16 v[64:67], v[140:143], v[208:211], v[64:67]
	s_setprio 0
	s_setprio 1
	v_mfma_f32_16x16x32_bf16 v[28:31], v[158:161], v[180:183], v[28:31]
	v_mfma_f32_16x16x32_bf16 v[24:27], v[172:175], v[180:183], v[24:27]
	v_mfma_f32_16x16x32_bf16 v[20:23], v[158:161], v[188:191], v[20:23]
	v_mfma_f32_16x16x32_bf16 v[16:19], v[172:175], v[188:191], v[16:19]
	v_mfma_f32_16x16x32_bf16 v[12:15], v[158:161], v[196:199], v[12:15]
	v_mfma_f32_16x16x32_bf16 v[8:11], v[172:175], v[196:199], v[8:11]
	v_mfma_f32_16x16x32_bf16 v[4:7], v[158:161], v[204:207], v[4:7]
	v_mfma_f32_16x16x32_bf16 v[0:3], v[172:175], v[204:207], v[0:3]
	v_mfma_f32_16x16x32_bf16 v[28:31], v[162:165], v[184:187], v[28:31]
	v_mfma_f32_16x16x32_bf16 v[24:27], v[176:179], v[184:187], v[24:27]
	v_mfma_f32_16x16x32_bf16 v[20:23], v[162:165], v[192:195], v[20:23]
	v_mfma_f32_16x16x32_bf16 v[16:19], v[176:179], v[192:195], v[16:19]
	v_mfma_f32_16x16x32_bf16 v[12:15], v[162:165], v[200:203], v[12:15]
	v_mfma_f32_16x16x32_bf16 v[8:11], v[176:179], v[200:203], v[8:11]
	v_mfma_f32_16x16x32_bf16 v[4:7], v[162:165], v[208:211], v[4:7]
	v_mfma_f32_16x16x32_bf16 v[0:3], v[176:179], v[208:211], v[0:3]
	s_setprio 0
	s_add_i32 s83, 0, 0x18000
	s_add_i32 s84, 0, 0x1c000
	v_add_u32_e32 v140, s83, v168
	s_barrier
; #define G_STAGE(bufoff, gbase, voff) do { _Pragma("unroll") for (int _i = 0; _i < 2; ++_i) \
;         __builtin_amdgcn_global_load_lds((const unsigned*)((const char*)(gbase) + voff[_i]), (LAS unsigned*)(lds + (bufoff) + ldsw + _i * 8192), 16, 0, 0); } while (0)
; #define G_LDA(dst, b, h) do { _Pragma("unroll") for (int m = 0; m < 4; ++m) _Pragma("unroll") for (int k = 0; k < 2; ++k) dst[m][k] = *(const LAS bf16x8*)(lds + G_SA(b, h) + aoff + m * 2048 + k * 1024); } while (0)
; #define G_LDB(dst, b, h) do { _Pragma("unroll") for (int n = 0; n < 2; ++n) _Pragma("unroll") for (int k = 0; k < 2; ++k) dst[n][k] = *(const LAS bf16x8*)(lds + G_SB(b, h) + boff + n * 2048 + k * 1024); } while (0)
; #define G_MMA(ai, bj, At_, Bt_) do { __builtin_amdgcn_s_setprio(1); _Pragma("unroll") for (int m = 0; m < 4; ++m) _Pragma("unroll") for (int n = 0; n < 2; ++n) _Pragma("unroll") for (int k = 0; k < 2; ++k) \
;         acc[ai][bj][m][n] = __builtin_amdgcn_mfma_f32_16x16x32_bf16(Bt_[n][k], At_[m][k], acc[ai][bj][m][n], 0, 0, 0); __builtin_amdgcn_s_setprio(0); } while (0)
; #define WAIT_V(n) asm volatile("s_waitcnt vmcnt(" #n ")" ::: "memory")
; #define WAIT_L(n) asm volatile("s_waitcnt lgkmcnt(" #n ")" ::: "memory")
; #define BAR __builtin_amdgcn_s_barrier()
; #define SCHED __builtin_amdgcn_sched_barrier(0)
; template <class Get, class Epi>
; DI void gemm_loop(int ntiles, int ld, char* shm, const Get& get, const Epi& epi) {
;     ...
;             G_LDB(B0, 1, 0); G_LDB(B1, 1, 1); SCHED; G_LDA(At, 1, 0); G_STAGE(G_SA(0, 1), a2 + hstep, voffA);
;             WAIT_V(8); WAIT_L(0); BAR; G_MMA(0, 0, At, B0); G_MMA(0, 1, At, B1); BAR; SCHED;
	v_add_u32_e32 v176, s84, v168
	ds_read_b128 v[128:131], v140
	ds_read_b128 v[132:135], v140 offset:1024
	ds_read_b128 v[136:139], v140 offset:2048
	ds_read_b128 v[140:143], v140 offset:3072
	ds_read_b128 v[158:161], v176
	ds_read_b128 v[162:165], v176 offset:1024
	ds_read_b128 v[172:175], v176 offset:2048
	ds_read_b128 v[176:179], v176 offset:3072
	s_add_u32 s46, s46, 0x40000
	s_addc_u32 s47, s47, 0
	s_mov_b32 m0, s55
	v_lshl_add_u64 v[216:217], s[46:47], 0, v[146:147]
	ds_read_b128 v[180:183], v171 offset:32768
	ds_read_b128 v[184:187], v171 offset:33792
	ds_read_b128 v[188:191], v171 offset:34816
	ds_read_b128 v[192:195], v171 offset:35840
	ds_read_b128 v[196:199], v171 offset:36864
	ds_read_b128 v[200:203], v171 offset:37888
	ds_read_b128 v[204:207], v171 offset:38912
	ds_read_b128 v[208:211], v171 offset:39936
	global_load_lds_dwordx4 v[216:217], off
	v_lshl_add_u64 v[216:217], s[46:47], 0, v[150:151]
	s_mov_b32 m0, s56
	s_nop 0
	global_load_lds_dwordx4 v[216:217], off
	s_waitcnt vmcnt(8)
	s_waitcnt lgkmcnt(0)
	s_barrier
	s_setprio 1
	s_waitcnt lgkmcnt(0)
	v_mfma_f32_16x16x32_bf16 v[124:127], v[128:131], v[180:183], v[124:127]
	v_mfma_f32_16x16x32_bf16 v[120:123], v[136:139], v[180:183], v[120:123]
	v_mfma_f32_16x16x32_bf16 v[116:119], v[128:131], v[188:191], v[116:119]
	v_mfma_f32_16x16x32_bf16 v[112:115], v[136:139], v[188:191], v[112:115]
	v_mfma_f32_16x16x32_bf16 v[108:111], v[128:131], v[196:199], v[108:111]
	v_mfma_f32_16x16x32_bf16 v[104:107], v[136:139], v[196:199], v[104:107]
	v_mfma_f32_16x16x32_bf16 v[100:103], v[128:131], v[204:207], v[100:103]
	v_mfma_f32_16x16x32_bf16 v[96:99], v[136:139], v[204:207], v[96:99]
	v_mfma_f32_16x16x32_bf16 v[124:127], v[132:135], v[184:187], v[124:127]
	v_mfma_f32_16x16x32_bf16 v[120:123], v[140:143], v[184:187], v[120:123]
	v_mfma_f32_16x16x32_bf16 v[116:119], v[132:135], v[192:195], v[116:119]
	v_mfma_f32_16x16x32_bf16 v[112:115], v[140:143], v[192:195], v[112:115]
	v_mfma_f32_16x16x32_bf16 v[108:111], v[132:135], v[200:203], v[108:111]
	v_mfma_f32_16x16x32_bf16 v[104:107], v[140:143], v[200:203], v[104:107]
	v_mfma_f32_16x16x32_bf16 v[100:103], v[132:135], v[208:211], v[100:103]
	v_mfma_f32_16x16x32_bf16 v[96:99], v[140:143], v[208:211], v[96:99]
	s_setprio 0
	s_setprio 1
	v_mfma_f32_16x16x32_bf16 v[60:63], v[158:161], v[180:183], v[60:63]
	v_mfma_f32_16x16x32_bf16 v[56:59], v[172:175], v[180:183], v[56:59]
	v_mfma_f32_16x16x32_bf16 v[52:55], v[158:161], v[188:191], v[52:55]
	v_mfma_f32_16x16x32_bf16 v[48:51], v[172:175], v[188:191], v[48:51]
	v_mfma_f32_16x16x32_bf16 v[44:47], v[158:161], v[196:199], v[44:47]
	v_mfma_f32_16x16x32_bf16 v[40:43], v[172:175], v[196:199], v[40:43]
	v_mfma_f32_16x16x32_bf16 v[36:39], v[158:161], v[204:207], v[36:39]
	v_mfma_f32_16x16x32_bf16 v[32:35], v[172:175], v[204:207], v[32:35]
	v_mfma_f32_16x16x32_bf16 v[60:63], v[162:165], v[184:187], v[60:63]
	v_mfma_f32_16x16x32_bf16 v[56:59], v[176:179], v[184:187], v[56:59]
	v_mfma_f32_16x16x32_bf16 v[52:55], v[162:165], v[192:195], v[52:55]
	v_mfma_f32_16x16x32_bf16 v[48:51], v[176:179], v[192:195], v[48:51]
	v_mfma_f32_16x16x32_bf16 v[44:47], v[162:165], v[200:203], v[44:47]
	v_mfma_f32_16x16x32_bf16 v[40:43], v[176:179], v[200:203], v[40:43]
	v_mfma_f32_16x16x32_bf16 v[36:39], v[162:165], v[208:211], v[36:39]
	v_mfma_f32_16x16x32_bf16 v[32:35], v[176:179], v[208:211], v[32:35]
	s_setprio 0
	s_add_i32 s46, s83, s31
	v_lshl_add_u64 v[144:145], v[144:145], 0, s[8:9]
	s_mov_b32 m0, s46
	s_barrier
; #define G_STAGE(bufoff, gbase, voff) do { _Pragma("unroll") for (int _i = 0; _i < 2; ++_i) \
;         __builtin_amdgcn_global_load_lds((const unsigned*)((const char*)(gbase) + voff[_i]), (LAS unsigned*)(lds + (bufoff) + ldsw + _i * 8192), 16, 0, 0); } while (0)
; #define G_LDA(dst, b, h) do { _Pragma("unroll") for (int m = 0; m < 4; ++m) _Pragma("unroll") for (int k = 0; k < 2; ++k) dst[m][k] = *(const LAS bf16x8*)(lds + G_SA(b, h) + aoff + m * 2048 + k * 1024); } while (0)
; #define G_MMA(ai, bj, At_, Bt_) do { __builtin_amdgcn_s_setprio(1); _Pragma("unroll") for (int m = 0; m < 4; ++m) _Pragma("unroll") for (int n = 0; n < 2; ++n) _Pragma("unroll") for (int k = 0; k < 2; ++k) \
;         acc[ai][bj][m][n] = __builtin_amdgcn_mfma_f32_16x16x32_bf16(Bt_[n][k], At_[m][k], acc[ai][bj][m][n], 0, 0, 0); __builtin_amdgcn_s_setprio(0); } while (0)
; #define WAIT_V(n) asm volatile("s_waitcnt vmcnt(" #n ")" ::: "memory")
; #define WAIT_L(n) asm volatile("s_waitcnt lgkmcnt(" #n ")" ::: "memory")
; #define BAR __builtin_amdgcn_s_barrier()
; #define SCHED __builtin_amdgcn_sched_barrier(0)
; template <class Get, class Epi>
; DI void gemm_loop(int ntiles, int ld, char* shm, const Get& get, const Epi& epi) {
;     ...
;             G_LDA(At, 1, 1); G_STAGE(G_SB(1, 0), b3, voffB); G_STAGE(G_SB(1, 1), b3 + hstep, voffB); G_STAGE(G_SA(1, 0), a3, voffA);
;             WAIT_V(8); WAIT_L(0); BAR; G_MMA(1, 0, At, B0); G_MMA(1, 1, At, B1); BAR; SCHED;
;         }
	ds_read_b128 v[180:183], v171 offset:49152
	ds_read_b128 v[184:187], v171 offset:50176
	ds_read_b128 v[188:191], v171 offset:51200
	ds_read_b128 v[192:195], v171 offset:52224
	ds_read_b128 v[196:199], v171 offset:53248
	ds_read_b128 v[200:203], v171 offset:54272
	ds_read_b128 v[204:207], v171 offset:55296
	ds_read_b128 v[208:211], v171 offset:56320
	global_load_lds_dwordx4 v[144:145], off
	s_add_i32 m0, s46, 0x2000
	s_add_u32 s14, s14, 0x40080
	v_lshl_add_u64 v[144:145], v[166:167], 0, s[8:9]
	s_addc_u32 s15, s15, 0
	s_add_i32 s46, s84, s31
	global_load_lds_dwordx4 v[144:145], off
	v_lshl_add_u64 v[144:145], s[14:15], 0, v[148:149]
	s_mov_b32 m0, s46
	s_nop 0
	global_load_lds_dwordx4 v[144:145], off
	v_lshl_add_u64 v[144:145], s[14:15], 0, v[152:153]
	s_add_i32 m0, s46, 0x2000
	s_nop 0
	global_load_lds_dwordx4 v[144:145], off
	v_lshl_add_u64 v[144:145], v[212:213], 0, s[8:9]
	s_mov_b32 m0, s59
	s_nop 0
	global_load_lds_dwordx4 v[144:145], off
	v_lshl_add_u64 v[144:145], v[214:215], 0, s[8:9]
	s_mov_b32 m0, s71
	s_nop 0
	global_load_lds_dwordx4 v[144:145], off
	s_waitcnt vmcnt(8)
	s_waitcnt lgkmcnt(0)
	s_barrier
	s_setprio 1
	s_waitcnt lgkmcnt(0)
	v_mfma_f32_16x16x32_bf16 v[92:95], v[128:131], v[180:183], v[92:95]
	v_mfma_f32_16x16x32_bf16 v[88:91], v[136:139], v[180:183], v[88:91]
	v_mfma_f32_16x16x32_bf16 v[84:87], v[128:131], v[188:191], v[84:87]
	v_mfma_f32_16x16x32_bf16 v[80:83], v[136:139], v[188:191], v[80:83]
	v_mfma_f32_16x16x32_bf16 v[76:79], v[128:131], v[196:199], v[76:79]
	v_mfma_f32_16x16x32_bf16 v[72:75], v[136:139], v[196:199], v[72:75]
	v_mfma_f32_16x16x32_bf16 v[68:71], v[128:131], v[204:207], v[68:71]
	v_mfma_f32_16x16x32_bf16 v[64:67], v[136:139], v[204:207], v[64:67]
	v_mfma_f32_16x16x32_bf16 v[92:95], v[132:135], v[184:187], v[92:95]
	v_mfma_f32_16x16x32_bf16 v[88:91], v[140:143], v[184:187], v[88:91]
	v_mfma_f32_16x16x32_bf16 v[84:87], v[132:135], v[192:195], v[84:87]
	v_mfma_f32_16x16x32_bf16 v[80:83], v[140:143], v[192:195], v[80:83]
	v_mfma_f32_16x16x32_bf16 v[76:79], v[132:135], v[200:203], v[76:79]
	v_mfma_f32_16x16x32_bf16 v[72:75], v[140:143], v[200:203], v[72:75]
	v_mfma_f32_16x16x32_bf16 v[68:71], v[132:135], v[208:211], v[68:71]
	v_mfma_f32_16x16x32_bf16 v[64:67], v[140:143], v[208:211], v[64:67]
	s_setprio 0
	s_setprio 1
	v_mfma_f32_16x16x32_bf16 v[28:31], v[158:161], v[180:183], v[28:31]
	v_mfma_f32_16x16x32_bf16 v[24:27], v[172:175], v[180:183], v[24:27]
	v_mfma_f32_16x16x32_bf16 v[20:23], v[158:161], v[188:191], v[20:23]
	v_mfma_f32_16x16x32_bf16 v[16:19], v[172:175], v[188:191], v[16:19]
	v_mfma_f32_16x16x32_bf16 v[12:15], v[158:161], v[196:199], v[12:15]
	v_mfma_f32_16x16x32_bf16 v[8:11], v[172:175], v[196:199], v[8:11]
	v_mfma_f32_16x16x32_bf16 v[4:7], v[158:161], v[204:207], v[4:7]
	v_mfma_f32_16x16x32_bf16 v[0:3], v[172:175], v[204:207], v[0:3]
	v_mfma_f32_16x16x32_bf16 v[28:31], v[162:165], v[184:187], v[28:31]
	v_mfma_f32_16x16x32_bf16 v[24:27], v[176:179], v[184:187], v[24:27]
	v_mfma_f32_16x16x32_bf16 v[20:23], v[162:165], v[192:195], v[20:23]
	v_mfma_f32_16x16x32_bf16 v[16:19], v[176:179], v[192:195], v[16:19]
	v_mfma_f32_16x16x32_bf16 v[12:15], v[162:165], v[200:203], v[12:15]
	v_mfma_f32_16x16x32_bf16 v[8:11], v[176:179], v[200:203], v[8:11]
	v_mfma_f32_16x16x32_bf16 v[4:7], v[162:165], v[208:211], v[4:7]
	v_mfma_f32_16x16x32_bf16 v[0:3], v[176:179], v[208:211], v[0:3]
	s_setprio 0
	s_add_u32 s52, s52, 0x100
	s_addc_u32 s53, s53, 0
	s_add_u32 s80, s80, 0x100
	s_addc_u32 s81, s81, 0
	s_cmp_ge_u32 s82, s78
	s_mov_b32 s14, s82
	s_barrier
	s_cbranch_scc0 .LBB0_2574

; #define G_STAGE(bufoff, gbase, voff) do { _Pragma("unroll") for (int _i = 0; _i < 2; ++_i) \
;         __builtin_amdgcn_global_load_lds((const unsigned*)((const char*)(gbase) + voff[_i]), (LAS unsigned*)(lds + (bufoff) + ldsw + _i * 8192), 16, 0, 0); } while (0)
; #define G_LDA(dst, b, h) do { _Pragma("unroll") for (int m = 0; m < 4; ++m) _Pragma("unroll") for (int k = 0; k < 2; ++k) dst[m][k] = *(const LAS bf16x8*)(lds + G_SA(b, h) + aoff + m * 2048 + k * 1024); } while (0)
; #define G_LDB(dst, b, h) do { _Pragma("unroll") for (int n = 0; n < 2; ++n) _Pragma("unroll") for (int k = 0; k < 2; ++k) dst[n][k] = *(const LAS bf16x8*)(lds + G_SB(b, h) + boff + n * 2048 + k * 1024); } while (0)
; #define G_MMA(ai, bj, At_, Bt_) do { __builtin_amdgcn_s_setprio(1); _Pragma("unroll") for (int m = 0; m < 4; ++m) _Pragma("unroll") for (int n = 0; n < 2; ++n) _Pragma("unroll") for (int k = 0; k < 2; ++k) \
;         acc[ai][bj][m][n] = __builtin_amdgcn_mfma_f32_16x16x32_bf16(Bt_[n][k], At_[m][k], acc[ai][bj][m][n], 0, 0, 0); __builtin_amdgcn_s_setprio(0); } while (0)
; #define WAIT_V(n) asm volatile("s_waitcnt vmcnt(" #n ")" ::: "memory")
; #define WAIT_L(n) asm volatile("s_waitcnt lgkmcnt(" #n ")" ::: "memory")
; #define BAR __builtin_amdgcn_s_barrier()
; #define SCHED __builtin_amdgcn_sched_barrier(0)
; template <class Get, class Epi>
; DI void gemm_loop(int ntiles, int ld, char* shm, const Get& get, const Epi& epi) {
;     ...
;         for (int t = 0; t < nt; t += 2) {
;             const bool last = (t == nt - 2);
;             const char* a1 = cA + (size_t)(t + 1) * kstep;
;             const char* a2 = last ? nA : cA + (size_t)(t + 2) * kstep; const char* b2 = last ? nB : cB + (size_t)(t + 2) * kstep;
;             const char* a3 = a2 + kstep; const char* b3 = b2 + kstep;
;             G_LDB(B0, 0, 0); G_LDB(B1, 0, 1); SCHED; G_LDA(At, 0, 0); G_STAGE(G_SA(1, 1), a1 + hstep, voffA);
;             WAIT_V(8); WAIT_L(0); BAR; G_MMA(0, 0, At, B0); G_MMA(0, 1, At, B1); BAR; SCHED;
;             G_LDA(At, 0, 1); G_STAGE(G_SB(0, 0), b2, voffB); G_STAGE(G_SB(0, 1), b2 + hstep, voffB); G_STAGE(G_SA(0, 0), a2, voffA);
;             WAIT_V(8); WAIT_L(0); BAR; G_MMA(1, 0, At, B0); G_MMA(1, 1, At, B1); BAR; SCHED;
.Lpeel_2892:
	ds_read_b128 v[128:131], v169
	ds_read_b128 v[132:135], v169 offset:1024
	ds_read_b128 v[136:139], v169 offset:2048
	ds_read_b128 v[140:143], v169 offset:3072
	ds_read_b128 v[158:161], v170
	ds_read_b128 v[162:165], v170 offset:1024
	ds_read_b128 v[172:175], v170 offset:2048
	ds_read_b128 v[176:179], v170 offset:3072
	s_add_i32 s83, s44, 2
	s_add_u32 s14, s4, 0x100
	s_addc_u32 s15, s5, 0
	s_cmp_eq_u32 s80, s44
	s_cselect_b32 s44, s42, s81
	s_cselect_b32 s47, s41, s15
	s_cselect_b32 s46, s40, s14
	s_cselect_b32 s45, s43, s82
	v_lshl_add_u64 v[144:145], s[4:5], 0, v[154:155]
	s_add_i32 m0, s49, 0xc000
	ds_read_b128 v[180:183], v171
	ds_read_b128 v[184:187], v171 offset:1024
	ds_read_b128 v[188:191], v171 offset:2048
	ds_read_b128 v[192:195], v171 offset:3072
	ds_read_b128 v[196:199], v171 offset:4096
	ds_read_b128 v[200:203], v171 offset:5120
	ds_read_b128 v[204:207], v171 offset:6144
	ds_read_b128 v[208:211], v171 offset:7168
	global_load_lds_dwordx4 v[144:145], off
	v_lshl_add_u64 v[144:145], s[4:5], 0, v[156:157]
	s_add_i32 m0, s49, 0xe000
	s_nop 0
	global_load_lds_dwordx4 v[144:145], off
	s_waitcnt vmcnt(8)
	s_waitcnt lgkmcnt(0)
	s_barrier
	s_setprio 1
	s_waitcnt lgkmcnt(0)
	v_mfma_f32_16x16x32_bf16 v[124:127], v[128:131], v[180:183], 0
	v_mfma_f32_16x16x32_bf16 v[120:123], v[136:139], v[180:183], 0
	v_mfma_f32_16x16x32_bf16 v[116:119], v[128:131], v[188:191], 0
	v_mfma_f32_16x16x32_bf16 v[112:115], v[136:139], v[188:191], 0
	v_mfma_f32_16x16x32_bf16 v[108:111], v[128:131], v[196:199], 0
	v_mfma_f32_16x16x32_bf16 v[104:107], v[136:139], v[196:199], 0
	v_mfma_f32_16x16x32_bf16 v[100:103], v[128:131], v[204:207], 0
	v_mfma_f32_16x16x32_bf16 v[96:99], v[136:139], v[204:207], 0
	v_mfma_f32_16x16x32_bf16 v[124:127], v[132:135], v[184:187], v[124:127]
	v_mfma_f32_16x16x32_bf16 v[120:123], v[140:143], v[184:187], v[120:123]
	v_mfma_f32_16x16x32_bf16 v[116:119], v[132:135], v[192:195], v[116:119]
	v_mfma_f32_16x16x32_bf16 v[112:115], v[140:143], v[192:195], v[112:115]
	v_mfma_f32_16x16x32_bf16 v[108:111], v[132:135], v[200:203], v[108:111]
	v_mfma_f32_16x16x32_bf16 v[104:107], v[140:143], v[200:203], v[104:107]
	v_mfma_f32_16x16x32_bf16 v[100:103], v[132:135], v[208:211], v[100:103]
	v_mfma_f32_16x16x32_bf16 v[96:99], v[140:143], v[208:211], v[96:99]
	s_setprio 0
	s_setprio 1
	v_mfma_f32_16x16x32_bf16 v[60:63], v[158:161], v[180:183], 0
	v_mfma_f32_16x16x32_bf16 v[56:59], v[172:175], v[180:183], 0
	v_mfma_f32_16x16x32_bf16 v[52:55], v[158:161], v[188:191], 0
	v_mfma_f32_16x16x32_bf16 v[48:51], v[172:175], v[188:191], 0
	v_mfma_f32_16x16x32_bf16 v[44:47], v[158:161], v[196:199], 0
	v_mfma_f32_16x16x32_bf16 v[40:43], v[172:175], v[196:199], 0
	v_mfma_f32_16x16x32_bf16 v[36:39], v[158:161], v[204:207], 0
	v_mfma_f32_16x16x32_bf16 v[32:35], v[172:175], v[204:207], 0
	v_mfma_f32_16x16x32_bf16 v[60:63], v[162:165], v[184:187], v[60:63]
	v_mfma_f32_16x16x32_bf16 v[56:59], v[176:179], v[184:187], v[56:59]
	v_mfma_f32_16x16x32_bf16 v[52:55], v[162:165], v[192:195], v[52:55]
	v_mfma_f32_16x16x32_bf16 v[48:51], v[176:179], v[192:195], v[48:51]
	v_mfma_f32_16x16x32_bf16 v[44:47], v[162:165], v[200:203], v[44:47]
	v_mfma_f32_16x16x32_bf16 v[40:43], v[176:179], v[200:203], v[40:43]
	v_mfma_f32_16x16x32_bf16 v[36:39], v[162:165], v[208:211], v[36:39]
	v_mfma_f32_16x16x32_bf16 v[32:35], v[176:179], v[208:211], v[32:35]
	s_setprio 0
	s_add_i32 s4, s58, s48
	v_lshl_add_u64 v[144:145], s[44:45], 0, v[148:149]
	s_mov_b32 m0, s4
	s_barrier
	ds_read_b128 v[180:183], v171 offset:16384
	ds_read_b128 v[184:187], v171 offset:17408
	ds_read_b128 v[188:191], v171 offset:18432
	ds_read_b128 v[192:195], v171 offset:19456
	ds_read_b128 v[196:199], v171 offset:20480
	ds_read_b128 v[200:203], v171 offset:21504
	ds_read_b128 v[204:207], v171 offset:22528
	ds_read_b128 v[208:211], v171 offset:23552
	global_load_lds_dwordx4 v[144:145], off
	s_add_i32 m0, s4, 0x2000
	s_add_u32 s4, s44, 0xb0000
	v_lshl_add_u64 v[166:167], s[44:45], 0, v[152:153]
	s_addc_u32 s5, s45, 0
	s_add_i32 s84, s59, s48
	global_load_lds_dwordx4 v[166:167], off
	v_lshl_add_u64 v[212:213], s[4:5], 0, v[148:149]
	s_mov_b32 m0, s84
	v_lshl_add_u64 v[214:215], s[46:47], 0, v[150:151]
	global_load_lds_dwordx4 v[212:213], off
	v_lshl_add_u64 v[212:213], s[4:5], 0, v[152:153]
	s_add_i32 m0, s84, 0x2000
	s_nop 0
	global_load_lds_dwordx4 v[212:213], off
	v_lshl_add_u64 v[212:213], s[46:47], 0, v[146:147]
	s_mov_b32 m0, s49
	s_nop 0
	global_load_lds_dwordx4 v[212:213], off
	s_mov_b32 m0, s50
	s_nop 0
	global_load_lds_dwordx4 v[214:215], off
	s_waitcnt vmcnt(8)
	s_waitcnt lgkmcnt(0)
	s_barrier
; #define G_STAGE(bufoff, gbase, voff) do { _Pragma("unroll") for (int _i = 0; _i < 2; ++_i) \
;         __builtin_amdgcn_global_load_lds((const unsigned*)((const char*)(gbase) + voff[_i]), (LAS unsigned*)(lds + (bufoff) + ldsw + _i * 8192), 16, 0, 0); } while (0)
; #define G_LDA(dst, b, h) do { _Pragma("unroll") for (int m = 0; m < 4; ++m) _Pragma("unroll") for (int k = 0; k < 2; ++k) dst[m][k] = *(const LAS bf16x8*)(lds + G_SA(b, h) + aoff + m * 2048 + k * 1024); } while (0)
; #define G_LDB(dst, b, h) do { _Pragma("unroll") for (int n = 0; n < 2; ++n) _Pragma("unroll") for (int k = 0; k < 2; ++k) dst[n][k] = *(const LAS bf16x8*)(lds + G_SB(b, h) + boff + n * 2048 + k * 1024); } while (0)
; #define G_MMA(ai, bj, At_, Bt_) do { __builtin_amdgcn_s_setprio(1); _Pragma("unroll") for (int m = 0; m < 4; ++m) _Pragma("unroll") for (int n = 0; n < 2; ++n) _Pragma("unroll") for (int k = 0; k < 2; ++k) \
;         acc[ai][bj][m][n] = __builtin_amdgcn_mfma_f32_16x16x32_bf16(Bt_[n][k], At_[m][k], acc[ai][bj][m][n], 0, 0, 0); __builtin_amdgcn_s_setprio(0); } while (0)
; #define WAIT_V(n) asm volatile("s_waitcnt vmcnt(" #n ")" ::: "memory")
; #define WAIT_L(n) asm volatile("s_waitcnt lgkmcnt(" #n ")" ::: "memory")
; #define BAR __builtin_amdgcn_s_barrier()
; #define SCHED __builtin_amdgcn_sched_barrier(0)
; template <class Get, class Epi>
; DI void gemm_loop(int ntiles, int ld, char* shm, const Get& get, const Epi& epi) {
;     ...
;             G_LDA(At, 0, 1); G_STAGE(G_SB(0, 0), b2, voffB); G_STAGE(G_SB(0, 1), b2 + hstep, voffB); G_STAGE(G_SA(0, 0), a2, voffA);
;             WAIT_V(8); WAIT_L(0); BAR; G_MMA(1, 0, At, B0); G_MMA(1, 1, At, B1); BAR; SCHED;
;             G_LDB(B0, 1, 0); G_LDB(B1, 1, 1); SCHED; G_LDA(At, 1, 0); G_STAGE(G_SA(0, 1), a2 + hstep, voffA);
;             WAIT_V(8); WAIT_L(0); BAR; G_MMA(0, 0, At, B0); G_MMA(0, 1, At, B1); BAR; SCHED;
;             G_LDA(At, 1, 1); G_STAGE(G_SB(1, 0), b3, voffB); G_STAGE(G_SB(1, 1), b3 + hstep, voffB); G_STAGE(G_SA(1, 0), a3, voffA);
	s_setprio 1
	s_waitcnt lgkmcnt(0)
	v_mfma_f32_16x16x32_bf16 v[92:95], v[128:131], v[180:183], 0
	v_mfma_f32_16x16x32_bf16 v[88:91], v[136:139], v[180:183], 0
	v_mfma_f32_16x16x32_bf16 v[84:87], v[128:131], v[188:191], 0
	v_mfma_f32_16x16x32_bf16 v[80:83], v[136:139], v[188:191], 0
	v_mfma_f32_16x16x32_bf16 v[76:79], v[128:131], v[196:199], 0
	v_mfma_f32_16x16x32_bf16 v[72:75], v[136:139], v[196:199], 0
	v_mfma_f32_16x16x32_bf16 v[68:71], v[128:131], v[204:207], 0
	v_mfma_f32_16x16x32_bf16 v[64:67], v[136:139], v[204:207], 0
	v_mfma_f32_16x16x32_bf16 v[92:95], v[132:135], v[184:187], v[92:95]
	v_mfma_f32_16x16x32_bf16 v[88:91], v[140:143], v[184:187], v[88:91]
	v_mfma_f32_16x16x32_bf16 v[84:87], v[132:135], v[192:195], v[84:87]
	v_mfma_f32_16x16x32_bf16 v[80:83], v[140:143], v[192:195], v[80:83]
	v_mfma_f32_16x16x32_bf16 v[76:79], v[132:135], v[200:203], v[76:79]
	v_mfma_f32_16x16x32_bf16 v[72:75], v[140:143], v[200:203], v[72:75]
	v_mfma_f32_16x16x32_bf16 v[68:71], v[132:135], v[208:211], v[68:71]
	v_mfma_f32_16x16x32_bf16 v[64:67], v[140:143], v[208:211], v[64:67]
	s_setprio 0
	s_setprio 1
	v_mfma_f32_16x16x32_bf16 v[28:31], v[158:161], v[180:183], 0
	v_mfma_f32_16x16x32_bf16 v[24:27], v[172:175], v[180:183], 0
	v_mfma_f32_16x16x32_bf16 v[20:23], v[158:161], v[188:191], 0
	v_mfma_f32_16x16x32_bf16 v[16:19], v[172:175], v[188:191], 0
	v_mfma_f32_16x16x32_bf16 v[12:15], v[158:161], v[196:199], 0
	v_mfma_f32_16x16x32_bf16 v[8:11], v[172:175], v[196:199], 0
	v_mfma_f32_16x16x32_bf16 v[4:7], v[158:161], v[204:207], 0
	v_mfma_f32_16x16x32_bf16 v[0:3], v[172:175], v[204:207], 0
	v_mfma_f32_16x16x32_bf16 v[28:31], v[162:165], v[184:187], v[28:31]
	v_mfma_f32_16x16x32_bf16 v[24:27], v[176:179], v[184:187], v[24:27]
	v_mfma_f32_16x16x32_bf16 v[20:23], v[162:165], v[192:195], v[20:23]
	v_mfma_f32_16x16x32_bf16 v[16:19], v[176:179], v[192:195], v[16:19]
	v_mfma_f32_16x16x32_bf16 v[12:15], v[162:165], v[200:203], v[12:15]
	v_mfma_f32_16x16x32_bf16 v[8:11], v[176:179], v[200:203], v[8:11]
	v_mfma_f32_16x16x32_bf16 v[4:7], v[162:165], v[208:211], v[4:7]
	v_mfma_f32_16x16x32_bf16 v[0:3], v[176:179], v[208:211], v[0:3]
	s_setprio 0
	s_add_i32 s84, 0, 0x18000
	s_add_i32 s85, 0, 0x1c000
	v_add_u32_e32 v140, s84, v168
	s_barrier
	v_add_u32_e32 v176, s85, v168
	ds_read_b128 v[128:131], v140
	ds_read_b128 v[132:135], v140 offset:1024
	ds_read_b128 v[136:139], v140 offset:2048
	ds_read_b128 v[140:143], v140 offset:3072
	ds_read_b128 v[158:161], v176
	ds_read_b128 v[162:165], v176 offset:1024
	ds_read_b128 v[172:175], v176 offset:2048
	ds_read_b128 v[176:179], v176 offset:3072
	s_add_u32 s4, s46, 0xb0000
	s_addc_u32 s5, s47, 0
	s_mov_b32 m0, s51
	v_lshl_add_u64 v[216:217], s[4:5], 0, v[146:147]
	ds_read_b128 v[180:183], v171 offset:32768
	ds_read_b128 v[184:187], v171 offset:33792
	ds_read_b128 v[188:191], v171 offset:34816
	ds_read_b128 v[192:195], v171 offset:35840
	ds_read_b128 v[196:199], v171 offset:36864
	ds_read_b128 v[200:203], v171 offset:37888
	ds_read_b128 v[204:207], v171 offset:38912
	ds_read_b128 v[208:211], v171 offset:39936
	global_load_lds_dwordx4 v[216:217], off
	v_lshl_add_u64 v[216:217], s[4:5], 0, v[150:151]
	s_mov_b32 m0, s52
	s_nop 0
	global_load_lds_dwordx4 v[216:217], off
	s_waitcnt vmcnt(8)
	s_waitcnt lgkmcnt(0)
	s_barrier
	s_setprio 1
	s_waitcnt lgkmcnt(0)
	v_mfma_f32_16x16x32_bf16 v[124:127], v[128:131], v[180:183], v[124:127]
	v_mfma_f32_16x16x32_bf16 v[120:123], v[136:139], v[180:183], v[120:123]
	v_mfma_f32_16x16x32_bf16 v[116:119], v[128:131], v[188:191], v[116:119]
	v_mfma_f32_16x16x32_bf16 v[112:115], v[136:139], v[188:191], v[112:115]
	v_mfma_f32_16x16x32_bf16 v[108:111], v[128:131], v[196:199], v[108:111]
	v_mfma_f32_16x16x32_bf16 v[104:107], v[136:139], v[196:199], v[104:107]
	v_mfma_f32_16x16x32_bf16 v[100:103], v[128:131], v[204:207], v[100:103]
	v_mfma_f32_16x16x32_bf16 v[96:99], v[136:139], v[204:207], v[96:99]
	v_mfma_f32_16x16x32_bf16 v[124:127], v[132:135], v[184:187], v[124:127]
	v_mfma_f32_16x16x32_bf16 v[120:123], v[140:143], v[184:187], v[120:123]
	v_mfma_f32_16x16x32_bf16 v[116:119], v[132:135], v[192:195], v[116:119]
	v_mfma_f32_16x16x32_bf16 v[112:115], v[140:143], v[192:195], v[112:115]
	v_mfma_f32_16x16x32_bf16 v[108:111], v[132:135], v[200:203], v[108:111]
	v_mfma_f32_16x16x32_bf16 v[104:107], v[140:143], v[200:203], v[104:107]
	v_mfma_f32_16x16x32_bf16 v[100:103], v[132:135], v[208:211], v[100:103]
	v_mfma_f32_16x16x32_bf16 v[96:99], v[140:143], v[208:211], v[96:99]
	s_setprio 0
	s_setprio 1
	v_mfma_f32_16x16x32_bf16 v[60:63], v[158:161], v[180:183], v[60:63]
	v_mfma_f32_16x16x32_bf16 v[56:59], v[172:175], v[180:183], v[56:59]
	v_mfma_f32_16x16x32_bf16 v[52:55], v[158:161], v[188:191], v[52:55]
	v_mfma_f32_16x16x32_bf16 v[48:51], v[172:175], v[188:191], v[48:51]
	v_mfma_f32_16x16x32_bf16 v[44:47], v[158:161], v[196:199], v[44:47]
	v_mfma_f32_16x16x32_bf16 v[40:43], v[172:175], v[196:199], v[40:43]
	v_mfma_f32_16x16x32_bf16 v[36:39], v[158:161], v[204:207], v[36:39]
	v_mfma_f32_16x16x32_bf16 v[32:35], v[172:175], v[204:207], v[32:35]
	v_mfma_f32_16x16x32_bf16 v[60:63], v[162:165], v[184:187], v[60:63]
	v_mfma_f32_16x16x32_bf16 v[56:59], v[176:179], v[184:187], v[56:59]
	v_mfma_f32_16x16x32_bf16 v[52:55], v[162:165], v[192:195], v[52:55]
	v_mfma_f32_16x16x32_bf16 v[48:51], v[176:179], v[192:195], v[48:51]
	v_mfma_f32_16x16x32_bf16 v[44:47], v[162:165], v[200:203], v[44:47]
	v_mfma_f32_16x16x32_bf16 v[40:43], v[176:179], v[200:203], v[40:43]
	v_mfma_f32_16x16x32_bf16 v[36:39], v[162:165], v[208:211], v[36:39]
	v_mfma_f32_16x16x32_bf16 v[32:35], v[176:179], v[208:211], v[32:35]
	s_setprio 0
	s_add_i32 s4, s84, s48
	v_lshl_add_u64 v[144:145], v[144:145], 0, s[10:11]
	s_mov_b32 m0, s4
	s_barrier
; #define G_STAGE(bufoff, gbase, voff) do { _Pragma("unroll") for (int _i = 0; _i < 2; ++_i) \
;         __builtin_amdgcn_global_load_lds((const unsigned*)((const char*)(gbase) + voff[_i]), (LAS unsigned*)(lds + (bufoff) + ldsw + _i * 8192), 16, 0, 0); } while (0)
; #define G_LDA(dst, b, h) do { _Pragma("unroll") for (int m = 0; m < 4; ++m) _Pragma("unroll") for (int k = 0; k < 2; ++k) dst[m][k] = *(const LAS bf16x8*)(lds + G_SA(b, h) + aoff + m * 2048 + k * 1024); } while (0)
; #define G_LDB(dst, b, h) do { _Pragma("unroll") for (int n = 0; n < 2; ++n) _Pragma("unroll") for (int k = 0; k < 2; ++k) dst[n][k] = *(const LAS bf16x8*)(lds + G_SB(b, h) + boff + n * 2048 + k * 1024); } while (0)
; #define G_MMA(ai, bj, At_, Bt_) do { __builtin_amdgcn_s_setprio(1); _Pragma("unroll") for (int m = 0; m < 4; ++m) _Pragma("unroll") for (int n = 0; n < 2; ++n) _Pragma("unroll") for (int k = 0; k < 2; ++k) \
;         acc[ai][bj][m][n] = __builtin_amdgcn_mfma_f32_16x16x32_bf16(Bt_[n][k], At_[m][k], acc[ai][bj][m][n], 0, 0, 0); __builtin_amdgcn_s_setprio(0); } while (0)
; #define WAIT_V(n) asm volatile("s_waitcnt vmcnt(" #n ")" ::: "memory")
; #define WAIT_L(n) asm volatile("s_waitcnt lgkmcnt(" #n ")" ::: "memory")
; #define BAR __builtin_amdgcn_s_barrier()
; #define SCHED __builtin_amdgcn_sched_barrier(0)
; template <class Get, class Epi>
; DI void gemm_loop(int ntiles, int ld, char* shm, const Get& get, const Epi& epi) {
;     ...
;         for (int t = 0; t < nt; t += 2) {
;             const bool last = (t == nt - 2);
;             const char* a1 = cA + (size_t)(t + 1) * kstep;
;             const char* a2 = last ? nA : cA + (size_t)(t + 2) * kstep; const char* b2 = last ? nB : cB + (size_t)(t + 2) * kstep;
;             const char* a3 = a2 + kstep; const char* b3 = b2 + kstep;
;             G_LDB(B0, 0, 0); G_LDB(B1, 0, 1); SCHED; G_LDA(At, 0, 0); G_STAGE(G_SA(1, 1), a1 + hstep, voffA);
;             WAIT_V(8); WAIT_L(0); BAR; G_MMA(0, 0, At, B0); G_MMA(0, 1, At, B1); BAR; SCHED;
;     ...
;             G_LDA(At, 1, 1); G_STAGE(G_SB(1, 0), b3, voffB); G_STAGE(G_SB(1, 1), b3 + hstep, voffB); G_STAGE(G_SA(1, 0), a3, voffA);
;             WAIT_V(8); WAIT_L(0); BAR; G_MMA(1, 0, At, B0); G_MMA(1, 1, At, B1); BAR; SCHED;
;         }
	ds_read_b128 v[180:183], v171 offset:49152
	ds_read_b128 v[184:187], v171 offset:50176
	ds_read_b128 v[188:191], v171 offset:51200
	ds_read_b128 v[192:195], v171 offset:52224
	ds_read_b128 v[196:199], v171 offset:53248
	ds_read_b128 v[200:203], v171 offset:54272
	ds_read_b128 v[204:207], v171 offset:55296
	ds_read_b128 v[208:211], v171 offset:56320
	global_load_lds_dwordx4 v[144:145], off
	s_add_i32 m0, s4, 0x2000
	s_add_u32 s4, s44, 0xb0080
	v_lshl_add_u64 v[144:145], v[166:167], 0, s[10:11]
	s_addc_u32 s5, s45, 0
	s_add_i32 s44, s85, s48
	global_load_lds_dwordx4 v[144:145], off
	v_lshl_add_u64 v[144:145], s[4:5], 0, v[148:149]
	s_mov_b32 m0, s44
	s_nop 0
	global_load_lds_dwordx4 v[144:145], off
	v_lshl_add_u64 v[144:145], s[4:5], 0, v[152:153]
	s_add_i32 m0, s44, 0x2000
	s_nop 0
	global_load_lds_dwordx4 v[144:145], off
	v_lshl_add_u64 v[144:145], v[212:213], 0, s[10:11]
	s_mov_b32 m0, s55
	s_nop 0
	global_load_lds_dwordx4 v[144:145], off
	v_lshl_add_u64 v[144:145], v[214:215], 0, s[10:11]
	s_mov_b32 m0, s56
	s_nop 0
	global_load_lds_dwordx4 v[144:145], off
	s_waitcnt vmcnt(8)
	s_waitcnt lgkmcnt(0)
	s_barrier
	s_setprio 1
	s_waitcnt lgkmcnt(0)
	v_mfma_f32_16x16x32_bf16 v[92:95], v[128:131], v[180:183], v[92:95]
	v_mfma_f32_16x16x32_bf16 v[88:91], v[136:139], v[180:183], v[88:91]
	v_mfma_f32_16x16x32_bf16 v[84:87], v[128:131], v[188:191], v[84:87]
	v_mfma_f32_16x16x32_bf16 v[80:83], v[136:139], v[188:191], v[80:83]
	v_mfma_f32_16x16x32_bf16 v[76:79], v[128:131], v[196:199], v[76:79]
	v_mfma_f32_16x16x32_bf16 v[72:75], v[136:139], v[196:199], v[72:75]
	v_mfma_f32_16x16x32_bf16 v[68:71], v[128:131], v[204:207], v[68:71]
	v_mfma_f32_16x16x32_bf16 v[64:67], v[136:139], v[204:207], v[64:67]
	v_mfma_f32_16x16x32_bf16 v[92:95], v[132:135], v[184:187], v[92:95]
	v_mfma_f32_16x16x32_bf16 v[88:91], v[140:143], v[184:187], v[88:91]
	v_mfma_f32_16x16x32_bf16 v[84:87], v[132:135], v[192:195], v[84:87]
	v_mfma_f32_16x16x32_bf16 v[80:83], v[140:143], v[192:195], v[80:83]
	v_mfma_f32_16x16x32_bf16 v[76:79], v[132:135], v[200:203], v[76:79]
	v_mfma_f32_16x16x32_bf16 v[72:75], v[140:143], v[200:203], v[72:75]
	v_mfma_f32_16x16x32_bf16 v[68:71], v[132:135], v[208:211], v[68:71]
	v_mfma_f32_16x16x32_bf16 v[64:67], v[140:143], v[208:211], v[64:67]
	s_setprio 0
	s_setprio 1
	v_mfma_f32_16x16x32_bf16 v[28:31], v[158:161], v[180:183], v[28:31]
	v_mfma_f32_16x16x32_bf16 v[24:27], v[172:175], v[180:183], v[24:27]
	v_mfma_f32_16x16x32_bf16 v[20:23], v[158:161], v[188:191], v[20:23]
	v_mfma_f32_16x16x32_bf16 v[16:19], v[172:175], v[188:191], v[16:19]
	v_mfma_f32_16x16x32_bf16 v[12:15], v[158:161], v[196:199], v[12:15]
	v_mfma_f32_16x16x32_bf16 v[8:11], v[172:175], v[196:199], v[8:11]
	v_mfma_f32_16x16x32_bf16 v[4:7], v[158:161], v[204:207], v[4:7]
	v_mfma_f32_16x16x32_bf16 v[0:3], v[172:175], v[204:207], v[0:3]
	v_mfma_f32_16x16x32_bf16 v[28:31], v[162:165], v[184:187], v[28:31]
	v_mfma_f32_16x16x32_bf16 v[24:27], v[176:179], v[184:187], v[24:27]
	v_mfma_f32_16x16x32_bf16 v[20:23], v[162:165], v[192:195], v[20:23]
	v_mfma_f32_16x16x32_bf16 v[16:19], v[176:179], v[192:195], v[16:19]
	v_mfma_f32_16x16x32_bf16 v[12:15], v[162:165], v[200:203], v[12:15]
	v_mfma_f32_16x16x32_bf16 v[8:11], v[176:179], v[200:203], v[8:11]
	v_mfma_f32_16x16x32_bf16 v[4:7], v[162:165], v[208:211], v[4:7]
	v_mfma_f32_16x16x32_bf16 v[0:3], v[176:179], v[208:211], v[0:3]
	s_setprio 0
	s_add_u32 s81, s81, 0x100
	s_addc_u32 s82, s82, 0
	s_cmp_ge_u32 s83, s79
	s_mov_b64 s[4:5], s[14:15]
	s_mov_b32 s44, s83
	s_barrier
	s_cbranch_scc0 .LBB0_2892
	s_branch .Lpost_2892
.LBB0_2892:
	ds_read_b128 v[128:131], v169
	ds_read_b128 v[132:135], v169 offset:1024
	ds_read_b128 v[136:139], v169 offset:2048
	ds_read_b128 v[140:143], v169 offset:3072
	ds_read_b128 v[158:161], v170
	ds_read_b128 v[162:165], v170 offset:1024
	ds_read_b128 v[172:175], v170 offset:2048
	ds_read_b128 v[176:179], v170 offset:3072
	s_add_i32 s83, s44, 2
	s_add_u32 s14, s4, 0x100
	s_addc_u32 s15, s5, 0
	s_cmp_eq_u32 s80, s44
	s_cselect_b32 s44, s42, s81
	s_cselect_b32 s47, s41, s15
	s_cselect_b32 s46, s40, s14
	s_cselect_b32 s45, s43, s82
	v_lshl_add_u64 v[144:145], s[4:5], 0, v[154:155]
	s_add_i32 m0, s49, 0xc000
	ds_read_b128 v[180:183], v171
	ds_read_b128 v[184:187], v171 offset:1024
	ds_read_b128 v[188:191], v171 offset:2048
	ds_read_b128 v[192:195], v171 offset:3072
	ds_read_b128 v[196:199], v171 offset:4096
	ds_read_b128 v[200:203], v171 offset:5120
	ds_read_b128 v[204:207], v171 offset:6144
	ds_read_b128 v[208:211], v171 offset:7168
	global_load_lds_dwordx4 v[144:145], off
	v_lshl_add_u64 v[144:145], s[4:5], 0, v[156:157]
	s_add_i32 m0, s49, 0xe000
	s_nop 0
	global_load_lds_dwordx4 v[144:145], off
	s_waitcnt vmcnt(8)
	s_waitcnt lgkmcnt(0)
	s_barrier
; #define G_STAGE(bufoff, gbase, voff) do { _Pragma("unroll") for (int _i = 0; _i < 2; ++_i) \
;         __builtin_amdgcn_global_load_lds((const unsigned*)((const char*)(gbase) + voff[_i]), (LAS unsigned*)(lds + (bufoff) + ldsw + _i * 8192), 16, 0, 0); } while (0)
; #define G_LDA(dst, b, h) do { _Pragma("unroll") for (int m = 0; m < 4; ++m) _Pragma("unroll") for (int k = 0; k < 2; ++k) dst[m][k] = *(const LAS bf16x8*)(lds + G_SA(b, h) + aoff + m * 2048 + k * 1024); } while (0)
; #define G_LDB(dst, b, h) do { _Pragma("unroll") for (int n = 0; n < 2; ++n) _Pragma("unroll") for (int k = 0; k < 2; ++k) dst[n][k] = *(const LAS bf16x8*)(lds + G_SB(b, h) + boff + n * 2048 + k * 1024); } while (0)
; #define G_MMA(ai, bj, At_, Bt_) do { __builtin_amdgcn_s_setprio(1); _Pragma("unroll") for (int m = 0; m < 4; ++m) _Pragma("unroll") for (int n = 0; n < 2; ++n) _Pragma("unroll") for (int k = 0; k < 2; ++k) \
;         acc[ai][bj][m][n] = __builtin_amdgcn_mfma_f32_16x16x32_bf16(Bt_[n][k], At_[m][k], acc[ai][bj][m][n], 0, 0, 0); __builtin_amdgcn_s_setprio(0); } while (0)
; #define WAIT_V(n) asm volatile("s_waitcnt vmcnt(" #n ")" ::: "memory")
; #define WAIT_L(n) asm volatile("s_waitcnt lgkmcnt(" #n ")" ::: "memory")
; #define BAR __builtin_amdgcn_s_barrier()
; #define SCHED __builtin_amdgcn_sched_barrier(0)
; template <class Get, class Epi>
; DI void gemm_loop(int ntiles, int ld, char* shm, const Get& get, const Epi& epi) {
;     ...
;             G_LDB(B0, 0, 0); G_LDB(B1, 0, 1); SCHED; G_LDA(At, 0, 0); G_STAGE(G_SA(1, 1), a1 + hstep, voffA);
;             WAIT_V(8); WAIT_L(0); BAR; G_MMA(0, 0, At, B0); G_MMA(0, 1, At, B1); BAR; SCHED;
;             G_LDA(At, 0, 1); G_STAGE(G_SB(0, 0), b2, voffB); G_STAGE(G_SB(0, 1), b2 + hstep, voffB); G_STAGE(G_SA(0, 0), a2, voffA);
;             WAIT_V(8); WAIT_L(0); BAR; G_MMA(1, 0, At, B0); G_MMA(1, 1, At, B1); BAR; SCHED;
;             G_LDB(B0, 1, 0); G_LDB(B1, 1, 1); SCHED; G_LDA(At, 1, 0); G_STAGE(G_SA(0, 1), a2 + hstep, voffA);
;             WAIT_V(8); WAIT_L(0); BAR; G_MMA(0, 0, At, B0); G_MMA(0, 1, At, B1); BAR; SCHED;
	s_setprio 1
	s_waitcnt lgkmcnt(0)
	v_mfma_f32_16x16x32_bf16 v[124:127], v[128:131], v[180:183], v[124:127]
	v_mfma_f32_16x16x32_bf16 v[120:123], v[136:139], v[180:183], v[120:123]
	v_mfma_f32_16x16x32_bf16 v[116:119], v[128:131], v[188:191], v[116:119]
	v_mfma_f32_16x16x32_bf16 v[112:115], v[136:139], v[188:191], v[112:115]
	v_mfma_f32_16x16x32_bf16 v[108:111], v[128:131], v[196:199], v[108:111]
	v_mfma_f32_16x16x32_bf16 v[104:107], v[136:139], v[196:199], v[104:107]
	v_mfma_f32_16x16x32_bf16 v[100:103], v[128:131], v[204:207], v[100:103]
	v_mfma_f32_16x16x32_bf16 v[96:99], v[136:139], v[204:207], v[96:99]
	v_mfma_f32_16x16x32_bf16 v[124:127], v[132:135], v[184:187], v[124:127]
	v_mfma_f32_16x16x32_bf16 v[120:123], v[140:143], v[184:187], v[120:123]
	v_mfma_f32_16x16x32_bf16 v[116:119], v[132:135], v[192:195], v[116:119]
	v_mfma_f32_16x16x32_bf16 v[112:115], v[140:143], v[192:195], v[112:115]
	v_mfma_f32_16x16x32_bf16 v[108:111], v[132:135], v[200:203], v[108:111]
	v_mfma_f32_16x16x32_bf16 v[104:107], v[140:143], v[200:203], v[104:107]
	v_mfma_f32_16x16x32_bf16 v[100:103], v[132:135], v[208:211], v[100:103]
	v_mfma_f32_16x16x32_bf16 v[96:99], v[140:143], v[208:211], v[96:99]
	s_setprio 0
	s_setprio 1
	v_mfma_f32_16x16x32_bf16 v[60:63], v[158:161], v[180:183], v[60:63]
	v_mfma_f32_16x16x32_bf16 v[56:59], v[172:175], v[180:183], v[56:59]
	v_mfma_f32_16x16x32_bf16 v[52:55], v[158:161], v[188:191], v[52:55]
	v_mfma_f32_16x16x32_bf16 v[48:51], v[172:175], v[188:191], v[48:51]
	v_mfma_f32_16x16x32_bf16 v[44:47], v[158:161], v[196:199], v[44:47]
	v_mfma_f32_16x16x32_bf16 v[40:43], v[172:175], v[196:199], v[40:43]
	v_mfma_f32_16x16x32_bf16 v[36:39], v[158:161], v[204:207], v[36:39]
	v_mfma_f32_16x16x32_bf16 v[32:35], v[172:175], v[204:207], v[32:35]
	v_mfma_f32_16x16x32_bf16 v[60:63], v[162:165], v[184:187], v[60:63]
	v_mfma_f32_16x16x32_bf16 v[56:59], v[176:179], v[184:187], v[56:59]
	v_mfma_f32_16x16x32_bf16 v[52:55], v[162:165], v[192:195], v[52:55]
	v_mfma_f32_16x16x32_bf16 v[48:51], v[176:179], v[192:195], v[48:51]
	v_mfma_f32_16x16x32_bf16 v[44:47], v[162:165], v[200:203], v[44:47]
	v_mfma_f32_16x16x32_bf16 v[40:43], v[176:179], v[200:203], v[40:43]
	v_mfma_f32_16x16x32_bf16 v[36:39], v[162:165], v[208:211], v[36:39]
	v_mfma_f32_16x16x32_bf16 v[32:35], v[176:179], v[208:211], v[32:35]
	s_setprio 0
	s_add_i32 s4, s58, s48
	v_lshl_add_u64 v[144:145], s[44:45], 0, v[148:149]
	s_mov_b32 m0, s4
	s_barrier
	ds_read_b128 v[180:183], v171 offset:16384
	ds_read_b128 v[184:187], v171 offset:17408
	ds_read_b128 v[188:191], v171 offset:18432
	ds_read_b128 v[192:195], v171 offset:19456
	ds_read_b128 v[196:199], v171 offset:20480
	ds_read_b128 v[200:203], v171 offset:21504
	ds_read_b128 v[204:207], v171 offset:22528
	ds_read_b128 v[208:211], v171 offset:23552
	global_load_lds_dwordx4 v[144:145], off
	s_add_i32 m0, s4, 0x2000
	s_add_u32 s4, s44, 0xb0000
	v_lshl_add_u64 v[166:167], s[44:45], 0, v[152:153]
	s_addc_u32 s5, s45, 0
	s_add_i32 s84, s59, s48
	global_load_lds_dwordx4 v[166:167], off
	v_lshl_add_u64 v[212:213], s[4:5], 0, v[148:149]
	s_mov_b32 m0, s84
	v_lshl_add_u64 v[214:215], s[46:47], 0, v[150:151]
	global_load_lds_dwordx4 v[212:213], off
	v_lshl_add_u64 v[212:213], s[4:5], 0, v[152:153]
	s_add_i32 m0, s84, 0x2000
	s_nop 0
	global_load_lds_dwordx4 v[212:213], off
	v_lshl_add_u64 v[212:213], s[46:47], 0, v[146:147]
	s_mov_b32 m0, s49
	s_nop 0
	global_load_lds_dwordx4 v[212:213], off
	s_mov_b32 m0, s50
	s_nop 0
	global_load_lds_dwordx4 v[214:215], off
	s_waitcnt vmcnt(8)
	s_waitcnt lgkmcnt(0)
	s_barrier
	s_setprio 1
	s_waitcnt lgkmcnt(0)
	v_mfma_f32_16x16x32_bf16 v[92:95], v[128:131], v[180:183], v[92:95]
	v_mfma_f32_16x16x32_bf16 v[88:91], v[136:139], v[180:183], v[88:91]
	v_mfma_f32_16x16x32_bf16 v[84:87], v[128:131], v[188:191], v[84:87]
	v_mfma_f32_16x16x32_bf16 v[80:83], v[136:139], v[188:191], v[80:83]
	v_mfma_f32_16x16x32_bf16 v[76:79], v[128:131], v[196:199], v[76:79]
	v_mfma_f32_16x16x32_bf16 v[72:75], v[136:139], v[196:199], v[72:75]
	v_mfma_f32_16x16x32_bf16 v[68:71], v[128:131], v[204:207], v[68:71]
	v_mfma_f32_16x16x32_bf16 v[64:67], v[136:139], v[204:207], v[64:67]
	v_mfma_f32_16x16x32_bf16 v[92:95], v[132:135], v[184:187], v[92:95]
	v_mfma_f32_16x16x32_bf16 v[88:91], v[140:143], v[184:187], v[88:91]
	v_mfma_f32_16x16x32_bf16 v[84:87], v[132:135], v[192:195], v[84:87]
	v_mfma_f32_16x16x32_bf16 v[80:83], v[140:143], v[192:195], v[80:83]
	v_mfma_f32_16x16x32_bf16 v[76:79], v[132:135], v[200:203], v[76:79]
	v_mfma_f32_16x16x32_bf16 v[72:75], v[140:143], v[200:203], v[72:75]
	v_mfma_f32_16x16x32_bf16 v[68:71], v[132:135], v[208:211], v[68:71]
	v_mfma_f32_16x16x32_bf16 v[64:67], v[140:143], v[208:211], v[64:67]
	s_setprio 0
	s_setprio 1
	v_mfma_f32_16x16x32_bf16 v[28:31], v[158:161], v[180:183], v[28:31]
	v_mfma_f32_16x16x32_bf16 v[24:27], v[172:175], v[180:183], v[24:27]
	v_mfma_f32_16x16x32_bf16 v[20:23], v[158:161], v[188:191], v[20:23]
	v_mfma_f32_16x16x32_bf16 v[16:19], v[172:175], v[188:191], v[16:19]
	v_mfma_f32_16x16x32_bf16 v[12:15], v[158:161], v[196:199], v[12:15]
	v_mfma_f32_16x16x32_bf16 v[8:11], v[172:175], v[196:199], v[8:11]
	v_mfma_f32_16x16x32_bf16 v[4:7], v[158:161], v[204:207], v[4:7]
	v_mfma_f32_16x16x32_bf16 v[0:3], v[172:175], v[204:207], v[0:3]
	v_mfma_f32_16x16x32_bf16 v[28:31], v[162:165], v[184:187], v[28:31]
	v_mfma_f32_16x16x32_bf16 v[24:27], v[176:179], v[184:187], v[24:27]
	v_mfma_f32_16x16x32_bf16 v[20:23], v[162:165], v[192:195], v[20:23]
	v_mfma_f32_16x16x32_bf16 v[16:19], v[176:179], v[192:195], v[16:19]
	v_mfma_f32_16x16x32_bf16 v[12:15], v[162:165], v[200:203], v[12:15]
	v_mfma_f32_16x16x32_bf16 v[8:11], v[176:179], v[200:203], v[8:11]
	v_mfma_f32_16x16x32_bf16 v[4:7], v[162:165], v[208:211], v[4:7]
	v_mfma_f32_16x16x32_bf16 v[0:3], v[176:179], v[208:211], v[0:3]
	s_setprio 0
	s_add_i32 s84, 0, 0x18000
	s_add_i32 s85, 0, 0x1c000
	v_add_u32_e32 v140, s84, v168
	s_barrier
; #define G_STAGE(bufoff, gbase, voff) do { _Pragma("unroll") for (int _i = 0; _i < 2; ++_i) \
;         __builtin_amdgcn_global_load_lds((const unsigned*)((const char*)(gbase) + voff[_i]), (LAS unsigned*)(lds + (bufoff) + ldsw + _i * 8192), 16, 0, 0); } while (0)
; #define G_LDA(dst, b, h) do { _Pragma("unroll") for (int m = 0; m < 4; ++m) _Pragma("unroll") for (int k = 0; k < 2; ++k) dst[m][k] = *(const LAS bf16x8*)(lds + G_SA(b, h) + aoff + m * 2048 + k * 1024); } while (0)
; #define G_LDB(dst, b, h) do { _Pragma("unroll") for (int n = 0; n < 2; ++n) _Pragma("unroll") for (int k = 0; k < 2; ++k) dst[n][k] = *(const LAS bf16x8*)(lds + G_SB(b, h) + boff + n * 2048 + k * 1024); } while (0)
; #define G_MMA(ai, bj, At_, Bt_) do { __builtin_amdgcn_s_setprio(1); _Pragma("unroll") for (int m = 0; m < 4; ++m) _Pragma("unroll") for (int n = 0; n < 2; ++n) _Pragma("unroll") for (int k = 0; k < 2; ++k) \
;         acc[ai][bj][m][n] = __builtin_amdgcn_mfma_f32_16x16x32_bf16(Bt_[n][k], At_[m][k], acc[ai][bj][m][n], 0, 0, 0); __builtin_amdgcn_s_setprio(0); } while (0)
; #define WAIT_V(n) asm volatile("s_waitcnt vmcnt(" #n ")" ::: "memory")
; #define WAIT_L(n) asm volatile("s_waitcnt lgkmcnt(" #n ")" ::: "memory")
; #define BAR __builtin_amdgcn_s_barrier()
; #define SCHED __builtin_amdgcn_sched_barrier(0)
; template <class Get, class Epi>
; DI void gemm_loop(int ntiles, int ld, char* shm, const Get& get, const Epi& epi) {
;     ...
;             G_LDB(B0, 1, 0); G_LDB(B1, 1, 1); SCHED; G_LDA(At, 1, 0); G_STAGE(G_SA(0, 1), a2 + hstep, voffA);
;             WAIT_V(8); WAIT_L(0); BAR; G_MMA(0, 0, At, B0); G_MMA(0, 1, At, B1); BAR; SCHED;
;             G_LDA(At, 1, 1); G_STAGE(G_SB(1, 0), b3, voffB); G_STAGE(G_SB(1, 1), b3 + hstep, voffB); G_STAGE(G_SA(1, 0), a3, voffA);
;             WAIT_V(8); WAIT_L(0); BAR; G_MMA(1, 0, At, B0); G_MMA(1, 1, At, B1); BAR; SCHED;
;         }
	v_add_u32_e32 v176, s85, v168
	ds_read_b128 v[128:131], v140
	ds_read_b128 v[132:135], v140 offset:1024
	ds_read_b128 v[136:139], v140 offset:2048
	ds_read_b128 v[140:143], v140 offset:3072
	ds_read_b128 v[158:161], v176
	ds_read_b128 v[162:165], v176 offset:1024
	ds_read_b128 v[172:175], v176 offset:2048
	ds_read_b128 v[176:179], v176 offset:3072
	s_add_u32 s4, s46, 0xb0000
	s_addc_u32 s5, s47, 0
	s_mov_b32 m0, s51
	v_lshl_add_u64 v[216:217], s[4:5], 0, v[146:147]
	ds_read_b128 v[180:183], v171 offset:32768
	ds_read_b128 v[184:187], v171 offset:33792
	ds_read_b128 v[188:191], v171 offset:34816
	ds_read_b128 v[192:195], v171 offset:35840
	ds_read_b128 v[196:199], v171 offset:36864
	ds_read_b128 v[200:203], v171 offset:37888
	ds_read_b128 v[204:207], v171 offset:38912
	ds_read_b128 v[208:211], v171 offset:39936
	global_load_lds_dwordx4 v[216:217], off
	v_lshl_add_u64 v[216:217], s[4:5], 0, v[150:151]
	s_mov_b32 m0, s52
	s_nop 0
	global_load_lds_dwordx4 v[216:217], off
	s_waitcnt vmcnt(8)
	s_waitcnt lgkmcnt(0)
	s_barrier
	s_setprio 1
	s_waitcnt lgkmcnt(0)
	v_mfma_f32_16x16x32_bf16 v[124:127], v[128:131], v[180:183], v[124:127]
	v_mfma_f32_16x16x32_bf16 v[120:123], v[136:139], v[180:183], v[120:123]
	v_mfma_f32_16x16x32_bf16 v[116:119], v[128:131], v[188:191], v[116:119]
	v_mfma_f32_16x16x32_bf16 v[112:115], v[136:139], v[188:191], v[112:115]
	v_mfma_f32_16x16x32_bf16 v[108:111], v[128:131], v[196:199], v[108:111]
	v_mfma_f32_16x16x32_bf16 v[104:107], v[136:139], v[196:199], v[104:107]
	v_mfma_f32_16x16x32_bf16 v[100:103], v[128:131], v[204:207], v[100:103]
	v_mfma_f32_16x16x32_bf16 v[96:99], v[136:139], v[204:207], v[96:99]
	v_mfma_f32_16x16x32_bf16 v[124:127], v[132:135], v[184:187], v[124:127]
	v_mfma_f32_16x16x32_bf16 v[120:123], v[140:143], v[184:187], v[120:123]
	v_mfma_f32_16x16x32_bf16 v[116:119], v[132:135], v[192:195], v[116:119]
	v_mfma_f32_16x16x32_bf16 v[112:115], v[140:143], v[192:195], v[112:115]
	v_mfma_f32_16x16x32_bf16 v[108:111], v[132:135], v[200:203], v[108:111]
	v_mfma_f32_16x16x32_bf16 v[104:107], v[140:143], v[200:203], v[104:107]
	v_mfma_f32_16x16x32_bf16 v[100:103], v[132:135], v[208:211], v[100:103]
	v_mfma_f32_16x16x32_bf16 v[96:99], v[140:143], v[208:211], v[96:99]
	s_setprio 0
	s_setprio 1
	v_mfma_f32_16x16x32_bf16 v[60:63], v[158:161], v[180:183], v[60:63]
	v_mfma_f32_16x16x32_bf16 v[56:59], v[172:175], v[180:183], v[56:59]
	v_mfma_f32_16x16x32_bf16 v[52:55], v[158:161], v[188:191], v[52:55]
	v_mfma_f32_16x16x32_bf16 v[48:51], v[172:175], v[188:191], v[48:51]
	v_mfma_f32_16x16x32_bf16 v[44:47], v[158:161], v[196:199], v[44:47]
	v_mfma_f32_16x16x32_bf16 v[40:43], v[172:175], v[196:199], v[40:43]
	v_mfma_f32_16x16x32_bf16 v[36:39], v[158:161], v[204:207], v[36:39]
	v_mfma_f32_16x16x32_bf16 v[32:35], v[172:175], v[204:207], v[32:35]
	v_mfma_f32_16x16x32_bf16 v[60:63], v[162:165], v[184:187], v[60:63]
	v_mfma_f32_16x16x32_bf16 v[56:59], v[176:179], v[184:187], v[56:59]
	v_mfma_f32_16x16x32_bf16 v[52:55], v[162:165], v[192:195], v[52:55]
	v_mfma_f32_16x16x32_bf16 v[48:51], v[176:179], v[192:195], v[48:51]
	v_mfma_f32_16x16x32_bf16 v[44:47], v[162:165], v[200:203], v[44:47]
	v_mfma_f32_16x16x32_bf16 v[40:43], v[176:179], v[200:203], v[40:43]
	v_mfma_f32_16x16x32_bf16 v[36:39], v[162:165], v[208:211], v[36:39]
	v_mfma_f32_16x16x32_bf16 v[32:35], v[176:179], v[208:211], v[32:35]
	s_setprio 0
	s_add_i32 s4, s84, s48
	v_lshl_add_u64 v[144:145], v[144:145], 0, s[10:11]
	s_mov_b32 m0, s4
	s_barrier
	ds_read_b128 v[180:183], v171 offset:49152
	ds_read_b128 v[184:187], v171 offset:50176
	ds_read_b128 v[188:191], v171 offset:51200
	ds_read_b128 v[192:195], v171 offset:52224
	ds_read_b128 v[196:199], v171 offset:53248
	ds_read_b128 v[200:203], v171 offset:54272
	ds_read_b128 v[204:207], v171 offset:55296
	ds_read_b128 v[208:211], v171 offset:56320
	global_load_lds_dwordx4 v[144:145], off
	s_add_i32 m0, s4, 0x2000
	s_add_u32 s4, s44, 0xb0080
	v_lshl_add_u64 v[144:145], v[166:167], 0, s[10:11]
	s_addc_u32 s5, s45, 0
	s_add_i32 s44, s85, s48
	global_load_lds_dwordx4 v[144:145], off
	v_lshl_add_u64 v[144:145], s[4:5], 0, v[148:149]
	s_mov_b32 m0, s44
	s_nop 0
	global_load_lds_dwordx4 v[144:145], off
	v_lshl_add_u64 v[144:145], s[4:5], 0, v[152:153]
	s_add_i32 m0, s44, 0x2000
	s_nop 0
	global_load_lds_dwordx4 v[144:145], off
	v_lshl_add_u64 v[144:145], v[212:213], 0, s[10:11]
	s_mov_b32 m0, s55
	s_nop 0
	global_load_lds_dwordx4 v[144:145], off
	v_lshl_add_u64 v[144:145], v[214:215], 0, s[10:11]
	s_mov_b32 m0, s56
	s_nop 0
	global_load_lds_dwordx4 v[144:145], off
	s_waitcnt vmcnt(8)
	s_waitcnt lgkmcnt(0)
	s_barrier
	s_setprio 1
	s_waitcnt lgkmcnt(0)
	v_mfma_f32_16x16x32_bf16 v[92:95], v[128:131], v[180:183], v[92:95]
	v_mfma_f32_16x16x32_bf16 v[88:91], v[136:139], v[180:183], v[88:91]
	v_mfma_f32_16x16x32_bf16 v[84:87], v[128:131], v[188:191], v[84:87]
	v_mfma_f32_16x16x32_bf16 v[80:83], v[136:139], v[188:191], v[80:83]
	v_mfma_f32_16x16x32_bf16 v[76:79], v[128:131], v[196:199], v[76:79]
	v_mfma_f32_16x16x32_bf16 v[72:75], v[136:139], v[196:199], v[72:75]
	v_mfma_f32_16x16x32_bf16 v[68:71], v[128:131], v[204:207], v[68:71]
	v_mfma_f32_16x16x32_bf16 v[64:67], v[136:139], v[204:207], v[64:67]
	v_mfma_f32_16x16x32_bf16 v[92:95], v[132:135], v[184:187], v[92:95]
	v_mfma_f32_16x16x32_bf16 v[88:91], v[140:143], v[184:187], v[88:91]
	v_mfma_f32_16x16x32_bf16 v[84:87], v[132:135], v[192:195], v[84:87]
	v_mfma_f32_16x16x32_bf16 v[80:83], v[140:143], v[192:195], v[80:83]
	v_mfma_f32_16x16x32_bf16 v[76:79], v[132:135], v[200:203], v[76:79]
	v_mfma_f32_16x16x32_bf16 v[72:75], v[140:143], v[200:203], v[72:75]
	v_mfma_f32_16x16x32_bf16 v[68:71], v[132:135], v[208:211], v[68:71]
	v_mfma_f32_16x16x32_bf16 v[64:67], v[140:143], v[208:211], v[64:67]
	s_setprio 0
	s_setprio 1
	v_mfma_f32_16x16x32_bf16 v[28:31], v[158:161], v[180:183], v[28:31]
	v_mfma_f32_16x16x32_bf16 v[24:27], v[172:175], v[180:183], v[24:27]
	v_mfma_f32_16x16x32_bf16 v[20:23], v[158:161], v[188:191], v[20:23]
	v_mfma_f32_16x16x32_bf16 v[16:19], v[172:175], v[188:191], v[16:19]
	v_mfma_f32_16x16x32_bf16 v[12:15], v[158:161], v[196:199], v[12:15]
	v_mfma_f32_16x16x32_bf16 v[8:11], v[172:175], v[196:199], v[8:11]
	v_mfma_f32_16x16x32_bf16 v[4:7], v[158:161], v[204:207], v[4:7]
	v_mfma_f32_16x16x32_bf16 v[0:3], v[172:175], v[204:207], v[0:3]
	v_mfma_f32_16x16x32_bf16 v[28:31], v[162:165], v[184:187], v[28:31]
	v_mfma_f32_16x16x32_bf16 v[24:27], v[176:179], v[184:187], v[24:27]
	v_mfma_f32_16x16x32_bf16 v[20:23], v[162:165], v[192:195], v[20:23]
	v_mfma_f32_16x16x32_bf16 v[16:19], v[176:179], v[192:195], v[16:19]
	v_mfma_f32_16x16x32_bf16 v[12:15], v[162:165], v[200:203], v[12:15]
	v_mfma_f32_16x16x32_bf16 v[8:11], v[176:179], v[200:203], v[8:11]
	v_mfma_f32_16x16x32_bf16 v[4:7], v[162:165], v[208:211], v[4:7]
	v_mfma_f32_16x16x32_bf16 v[0:3], v[176:179], v[208:211], v[0:3]
	s_setprio 0
	s_add_u32 s81, s81, 0x100
	s_addc_u32 s82, s82, 0
	s_cmp_ge_u32 s83, s79
	s_mov_b64 s[4:5], s[14:15]
	s_mov_b32 s44, s83
	s_barrier
	s_cbranch_scc0 .LBB0_2892

; #define G_STAGE(bufoff, gbase, voff) do { _Pragma("unroll") for (int _i = 0; _i < 2; ++_i) \
;         __builtin_amdgcn_global_load_lds((const unsigned*)((const char*)(gbase) + voff[_i]), (LAS unsigned*)(lds + (bufoff) + ldsw + _i * 8192), 16, 0, 0); } while (0)
; #define G_LDA(dst, b, h) do { _Pragma("unroll") for (int m = 0; m < 4; ++m) _Pragma("unroll") for (int k = 0; k < 2; ++k) dst[m][k] = *(const LAS bf16x8*)(lds + G_SA(b, h) + aoff + m * 2048 + k * 1024); } while (0)
; #define G_LDB(dst, b, h) do { _Pragma("unroll") for (int n = 0; n < 2; ++n) _Pragma("unroll") for (int k = 0; k < 2; ++k) dst[n][k] = *(const LAS bf16x8*)(lds + G_SB(b, h) + boff + n * 2048 + k * 1024); } while (0)
; #define G_MMA(ai, bj, At_, Bt_) do { __builtin_amdgcn_s_setprio(1); _Pragma("unroll") for (int m = 0; m < 4; ++m) _Pragma("unroll") for (int n = 0; n < 2; ++n) _Pragma("unroll") for (int k = 0; k < 2; ++k) \
;         acc[ai][bj][m][n] = __builtin_amdgcn_mfma_f32_16x16x32_bf16(Bt_[n][k], At_[m][k], acc[ai][bj][m][n], 0, 0, 0); __builtin_amdgcn_s_setprio(0); } while (0)
; #define WAIT_V(n) asm volatile("s_waitcnt vmcnt(" #n ")" ::: "memory")
; #define WAIT_L(n) asm volatile("s_waitcnt lgkmcnt(" #n ")" ::: "memory")
; #define BAR __builtin_amdgcn_s_barrier()
; #define SCHED __builtin_amdgcn_sched_barrier(0)
; template <class Get, class Epi>
; DI void gemm_loop(int ntiles, int ld, char* shm, const Get& get, const Epi& epi) {
;     ...
;         for (int t = 0; t < nt; t += 2) {
;             const bool last = (t == nt - 2);
;             const char* a1 = cA + (size_t)(t + 1) * kstep;
;             const char* a2 = last ? nA : cA + (size_t)(t + 2) * kstep; const char* b2 = last ? nB : cB + (size_t)(t + 2) * kstep;
;             const char* a3 = a2 + kstep; const char* b3 = b2 + kstep;
;             G_LDB(B0, 0, 0); G_LDB(B1, 0, 1); SCHED; G_LDA(At, 0, 0); G_STAGE(G_SA(1, 1), a1 + hstep, voffA);
;             WAIT_V(8); WAIT_L(0); BAR; G_MMA(0, 0, At, B0); G_MMA(0, 1, At, B1); BAR; SCHED;
;             G_LDA(At, 0, 1); G_STAGE(G_SB(0, 0), b2, voffB); G_STAGE(G_SB(0, 1), b2 + hstep, voffB); G_STAGE(G_SA(0, 0), a2, voffA);
;             WAIT_V(8); WAIT_L(0); BAR; G_MMA(1, 0, At, B0); G_MMA(1, 1, At, B1); BAR; SCHED;
.Lpeel_3141:
	ds_read_b128 v[144:147], v141
	ds_read_b128 v[148:151], v141 offset:1024
	ds_read_b128 v[152:155], v141 offset:2048
	ds_read_b128 v[156:159], v141 offset:3072
	ds_read_b128 v[160:163], v142
	ds_read_b128 v[164:167], v142 offset:1024
	ds_read_b128 v[168:171], v142 offset:2048
	ds_read_b128 v[172:175], v142 offset:3072
	s_add_u32 s14, s48, 0xfffc0080
	s_addc_u32 s15, s49, -1
	s_cmp_eq_u32 s70, 12
	s_cselect_b32 s47, s11, s15
	s_cselect_b32 s46, s39, s14
	s_cselect_b32 s15, s41, s65
	s_cselect_b32 s14, s63, s64
	v_lshl_add_u64 v[208:209], s[48:49], 0, v[136:137]
	s_add_i32 m0, s35, 0xc000
	ds_read_b128 v[176:179], v143
	ds_read_b128 v[180:183], v143 offset:1024
	ds_read_b128 v[184:187], v143 offset:2048
	ds_read_b128 v[188:191], v143 offset:3072
	ds_read_b128 v[192:195], v143 offset:4096
	ds_read_b128 v[196:199], v143 offset:5120
	ds_read_b128 v[200:203], v143 offset:6144
	ds_read_b128 v[204:207], v143 offset:7168
	global_load_lds_dwordx4 v[208:209], off
	v_lshl_add_u64 v[208:209], s[48:49], 0, v[138:139]
	s_add_i32 m0, s35, 0xe000
	s_nop 0
	global_load_lds_dwordx4 v[208:209], off
	s_waitcnt vmcnt(8)
	s_waitcnt lgkmcnt(0)
	s_barrier
	s_setprio 1
	s_waitcnt lgkmcnt(0)
	v_mfma_f32_16x16x32_bf16 v[124:127], v[144:147], v[176:179], 0
	v_mfma_f32_16x16x32_bf16 v[120:123], v[152:155], v[176:179], 0
	v_mfma_f32_16x16x32_bf16 v[116:119], v[144:147], v[184:187], 0
	v_mfma_f32_16x16x32_bf16 v[112:115], v[152:155], v[184:187], 0
	v_mfma_f32_16x16x32_bf16 v[100:103], v[144:147], v[192:195], 0
	v_mfma_f32_16x16x32_bf16 v[96:99], v[152:155], v[192:195], 0
	v_mfma_f32_16x16x32_bf16 v[84:87], v[144:147], v[200:203], 0
	v_mfma_f32_16x16x32_bf16 v[80:83], v[152:155], v[200:203], 0
	v_mfma_f32_16x16x32_bf16 v[124:127], v[148:151], v[180:183], v[124:127]
	v_mfma_f32_16x16x32_bf16 v[120:123], v[156:159], v[180:183], v[120:123]
	v_mfma_f32_16x16x32_bf16 v[116:119], v[148:151], v[188:191], v[116:119]
	v_mfma_f32_16x16x32_bf16 v[112:115], v[156:159], v[188:191], v[112:115]
	v_mfma_f32_16x16x32_bf16 v[100:103], v[148:151], v[196:199], v[100:103]
	v_mfma_f32_16x16x32_bf16 v[96:99], v[156:159], v[196:199], v[96:99]
	v_mfma_f32_16x16x32_bf16 v[84:87], v[148:151], v[204:207], v[84:87]
	v_mfma_f32_16x16x32_bf16 v[80:83], v[156:159], v[204:207], v[80:83]
	s_setprio 0
	s_setprio 1
	v_mfma_f32_16x16x32_bf16 v[108:111], v[160:163], v[176:179], 0
	v_mfma_f32_16x16x32_bf16 v[104:107], v[168:171], v[176:179], 0
	v_mfma_f32_16x16x32_bf16 v[92:95], v[160:163], v[184:187], 0
	v_mfma_f32_16x16x32_bf16 v[88:91], v[168:171], v[184:187], 0
	v_mfma_f32_16x16x32_bf16 v[76:79], v[160:163], v[192:195], 0
	v_mfma_f32_16x16x32_bf16 v[72:75], v[168:171], v[192:195], 0
	v_mfma_f32_16x16x32_bf16 v[68:71], v[160:163], v[200:203], 0
	v_mfma_f32_16x16x32_bf16 v[64:67], v[168:171], v[200:203], 0
	v_mfma_f32_16x16x32_bf16 v[108:111], v[164:167], v[180:183], v[108:111]
	v_mfma_f32_16x16x32_bf16 v[104:107], v[172:175], v[180:183], v[104:107]
	v_mfma_f32_16x16x32_bf16 v[92:95], v[164:167], v[188:191], v[92:95]
	v_mfma_f32_16x16x32_bf16 v[88:91], v[172:175], v[188:191], v[88:91]
	v_mfma_f32_16x16x32_bf16 v[76:79], v[164:167], v[196:199], v[76:79]
	v_mfma_f32_16x16x32_bf16 v[72:75], v[172:175], v[196:199], v[72:75]
	v_mfma_f32_16x16x32_bf16 v[68:71], v[164:167], v[204:207], v[68:71]
	v_mfma_f32_16x16x32_bf16 v[64:67], v[172:175], v[204:207], v[64:67]
	s_setprio 0
	s_add_i32 s71, s57, s50
	v_lshl_add_u64 v[208:209], s[14:15], 0, v[130:131]
	s_mov_b32 m0, s71
	s_barrier
	ds_read_b128 v[176:179], v143 offset:16384
	ds_read_b128 v[180:183], v143 offset:17408
	ds_read_b128 v[184:187], v143 offset:18432
	ds_read_b128 v[188:191], v143 offset:19456
	ds_read_b128 v[192:195], v143 offset:20480
	ds_read_b128 v[196:199], v143 offset:21504
	ds_read_b128 v[200:203], v143 offset:22528
	ds_read_b128 v[204:207], v143 offset:23552
	global_load_lds_dwordx4 v[208:209], off
	s_add_i32 m0, s71, 0x2000
	s_add_u32 s72, s14, 0x40000
	v_lshl_add_u64 v[210:211], s[14:15], 0, v[134:135]
	s_addc_u32 s73, s15, 0
	s_add_i32 s71, s58, s50
	global_load_lds_dwordx4 v[210:211], off
	v_lshl_add_u64 v[212:213], s[72:73], 0, v[130:131]
	s_mov_b32 m0, s71
	v_lshl_add_u64 v[214:215], s[46:47], 0, v[132:133]
	global_load_lds_dwordx4 v[212:213], off
	v_lshl_add_u64 v[212:213], s[72:73], 0, v[134:135]
	s_add_i32 m0, s71, 0x2000
	s_nop 0
	global_load_lds_dwordx4 v[212:213], off
	v_lshl_add_u64 v[212:213], s[46:47], 0, v[128:129]
	s_mov_b32 m0, s35
	s_nop 0
	global_load_lds_dwordx4 v[212:213], off
	s_mov_b32 m0, s51
	s_nop 0
	global_load_lds_dwordx4 v[214:215], off
	s_waitcnt vmcnt(8)
	s_waitcnt lgkmcnt(0)
	s_barrier
; #define G_STAGE(bufoff, gbase, voff) do { _Pragma("unroll") for (int _i = 0; _i < 2; ++_i) \
;         __builtin_amdgcn_global_load_lds((const unsigned*)((const char*)(gbase) + voff[_i]), (LAS unsigned*)(lds + (bufoff) + ldsw + _i * 8192), 16, 0, 0); } while (0)
; #define G_LDA(dst, b, h) do { _Pragma("unroll") for (int m = 0; m < 4; ++m) _Pragma("unroll") for (int k = 0; k < 2; ++k) dst[m][k] = *(const LAS bf16x8*)(lds + G_SA(b, h) + aoff + m * 2048 + k * 1024); } while (0)
; #define G_LDB(dst, b, h) do { _Pragma("unroll") for (int n = 0; n < 2; ++n) _Pragma("unroll") for (int k = 0; k < 2; ++k) dst[n][k] = *(const LAS bf16x8*)(lds + G_SB(b, h) + boff + n * 2048 + k * 1024); } while (0)
; #define G_MMA(ai, bj, At_, Bt_) do { __builtin_amdgcn_s_setprio(1); _Pragma("unroll") for (int m = 0; m < 4; ++m) _Pragma("unroll") for (int n = 0; n < 2; ++n) _Pragma("unroll") for (int k = 0; k < 2; ++k) \
;         acc[ai][bj][m][n] = __builtin_amdgcn_mfma_f32_16x16x32_bf16(Bt_[n][k], At_[m][k], acc[ai][bj][m][n], 0, 0, 0); __builtin_amdgcn_s_setprio(0); } while (0)
; #define WAIT_V(n) asm volatile("s_waitcnt vmcnt(" #n ")" ::: "memory")
; #define WAIT_L(n) asm volatile("s_waitcnt lgkmcnt(" #n ")" ::: "memory")
; #define BAR __builtin_amdgcn_s_barrier()
; #define SCHED __builtin_amdgcn_sched_barrier(0)
; template <class Get, class Epi>
; DI void gemm_loop(int ntiles, int ld, char* shm, const Get& get, const Epi& epi) {
;     ...
;             G_LDA(At, 0, 1); G_STAGE(G_SB(0, 0), b2, voffB); G_STAGE(G_SB(0, 1), b2 + hstep, voffB); G_STAGE(G_SA(0, 0), a2, voffA);
;             WAIT_V(8); WAIT_L(0); BAR; G_MMA(1, 0, At, B0); G_MMA(1, 1, At, B1); BAR; SCHED;
;             G_LDB(B0, 1, 0); G_LDB(B1, 1, 1); SCHED; G_LDA(At, 1, 0); G_STAGE(G_SA(0, 1), a2 + hstep, voffA);
;             WAIT_V(8); WAIT_L(0); BAR; G_MMA(0, 0, At, B0); G_MMA(0, 1, At, B1); BAR; SCHED;
;             G_LDA(At, 1, 1); G_STAGE(G_SB(1, 0), b3, voffB); G_STAGE(G_SB(1, 1), b3 + hstep, voffB); G_STAGE(G_SA(1, 0), a3, voffA);
	s_setprio 1
	s_waitcnt lgkmcnt(0)
	v_mfma_f32_16x16x32_bf16 v[60:63], v[144:147], v[176:179], 0
	v_mfma_f32_16x16x32_bf16 v[56:59], v[152:155], v[176:179], 0
	v_mfma_f32_16x16x32_bf16 v[52:55], v[144:147], v[184:187], 0
	v_mfma_f32_16x16x32_bf16 v[48:51], v[152:155], v[184:187], 0
	v_mfma_f32_16x16x32_bf16 v[36:39], v[144:147], v[192:195], 0
	v_mfma_f32_16x16x32_bf16 v[32:35], v[152:155], v[192:195], 0
	v_mfma_f32_16x16x32_bf16 v[20:23], v[144:147], v[200:203], 0
	v_mfma_f32_16x16x32_bf16 v[16:19], v[152:155], v[200:203], 0
	v_mfma_f32_16x16x32_bf16 v[60:63], v[148:151], v[180:183], v[60:63]
	v_mfma_f32_16x16x32_bf16 v[56:59], v[156:159], v[180:183], v[56:59]
	v_mfma_f32_16x16x32_bf16 v[52:55], v[148:151], v[188:191], v[52:55]
	v_mfma_f32_16x16x32_bf16 v[48:51], v[156:159], v[188:191], v[48:51]
	v_mfma_f32_16x16x32_bf16 v[36:39], v[148:151], v[196:199], v[36:39]
	v_mfma_f32_16x16x32_bf16 v[32:35], v[156:159], v[196:199], v[32:35]
	v_mfma_f32_16x16x32_bf16 v[20:23], v[148:151], v[204:207], v[20:23]
	v_mfma_f32_16x16x32_bf16 v[16:19], v[156:159], v[204:207], v[16:19]
	s_setprio 0
	s_setprio 1
	v_mfma_f32_16x16x32_bf16 v[44:47], v[160:163], v[176:179], 0
	v_mfma_f32_16x16x32_bf16 v[40:43], v[168:171], v[176:179], 0
	v_mfma_f32_16x16x32_bf16 v[28:31], v[160:163], v[184:187], 0
	v_mfma_f32_16x16x32_bf16 v[24:27], v[168:171], v[184:187], 0
	v_mfma_f32_16x16x32_bf16 v[12:15], v[160:163], v[192:195], 0
	v_mfma_f32_16x16x32_bf16 v[8:11], v[168:171], v[192:195], 0
	v_mfma_f32_16x16x32_bf16 v[4:7], v[160:163], v[200:203], 0
	v_mfma_f32_16x16x32_bf16 v[0:3], v[168:171], v[200:203], 0
	v_mfma_f32_16x16x32_bf16 v[44:47], v[164:167], v[180:183], v[44:47]
	v_mfma_f32_16x16x32_bf16 v[40:43], v[172:175], v[180:183], v[40:43]
	v_mfma_f32_16x16x32_bf16 v[28:31], v[164:167], v[188:191], v[28:31]
	v_mfma_f32_16x16x32_bf16 v[24:27], v[172:175], v[188:191], v[24:27]
	v_mfma_f32_16x16x32_bf16 v[12:15], v[164:167], v[196:199], v[12:15]
	v_mfma_f32_16x16x32_bf16 v[8:11], v[172:175], v[196:199], v[8:11]
	v_mfma_f32_16x16x32_bf16 v[4:7], v[164:167], v[204:207], v[4:7]
	v_mfma_f32_16x16x32_bf16 v[0:3], v[172:175], v[204:207], v[0:3]
	s_setprio 0
	s_add_i32 s71, 0, 0x18000
	s_add_i32 s72, 0, 0x1c000
	v_add_u32_e32 v156, s71, v140
	s_barrier
	v_add_u32_e32 v172, s72, v140
	ds_read_b128 v[144:147], v156
	ds_read_b128 v[148:151], v156 offset:1024
	ds_read_b128 v[152:155], v156 offset:2048
	ds_read_b128 v[156:159], v156 offset:3072
	ds_read_b128 v[160:163], v172
	ds_read_b128 v[164:167], v172 offset:1024
	ds_read_b128 v[168:171], v172 offset:2048
	ds_read_b128 v[172:175], v172 offset:3072
	s_add_u32 s46, s46, 0x40000
	s_addc_u32 s47, s47, 0
	s_mov_b32 m0, s52
	v_lshl_add_u64 v[216:217], s[46:47], 0, v[128:129]
	ds_read_b128 v[176:179], v143 offset:32768
	ds_read_b128 v[180:183], v143 offset:33792
	ds_read_b128 v[184:187], v143 offset:34816
	ds_read_b128 v[188:191], v143 offset:35840
	ds_read_b128 v[192:195], v143 offset:36864
	ds_read_b128 v[196:199], v143 offset:37888
	ds_read_b128 v[200:203], v143 offset:38912
	ds_read_b128 v[204:207], v143 offset:39936
	global_load_lds_dwordx4 v[216:217], off
	v_lshl_add_u64 v[216:217], s[46:47], 0, v[132:133]
	s_mov_b32 m0, s53
	s_nop 0
	global_load_lds_dwordx4 v[216:217], off
	s_waitcnt vmcnt(8)
	s_waitcnt lgkmcnt(0)
	s_barrier
	s_setprio 1
	s_waitcnt lgkmcnt(0)
	v_mfma_f32_16x16x32_bf16 v[124:127], v[144:147], v[176:179], v[124:127]
	v_mfma_f32_16x16x32_bf16 v[120:123], v[152:155], v[176:179], v[120:123]
	v_mfma_f32_16x16x32_bf16 v[116:119], v[144:147], v[184:187], v[116:119]
	v_mfma_f32_16x16x32_bf16 v[112:115], v[152:155], v[184:187], v[112:115]
	v_mfma_f32_16x16x32_bf16 v[100:103], v[144:147], v[192:195], v[100:103]
	v_mfma_f32_16x16x32_bf16 v[96:99], v[152:155], v[192:195], v[96:99]
	v_mfma_f32_16x16x32_bf16 v[84:87], v[144:147], v[200:203], v[84:87]
	v_mfma_f32_16x16x32_bf16 v[80:83], v[152:155], v[200:203], v[80:83]
	v_mfma_f32_16x16x32_bf16 v[124:127], v[148:151], v[180:183], v[124:127]
	v_mfma_f32_16x16x32_bf16 v[120:123], v[156:159], v[180:183], v[120:123]
	v_mfma_f32_16x16x32_bf16 v[116:119], v[148:151], v[188:191], v[116:119]
	v_mfma_f32_16x16x32_bf16 v[112:115], v[156:159], v[188:191], v[112:115]
	v_mfma_f32_16x16x32_bf16 v[100:103], v[148:151], v[196:199], v[100:103]
	v_mfma_f32_16x16x32_bf16 v[96:99], v[156:159], v[196:199], v[96:99]
	v_mfma_f32_16x16x32_bf16 v[84:87], v[148:151], v[204:207], v[84:87]
	v_mfma_f32_16x16x32_bf16 v[80:83], v[156:159], v[204:207], v[80:83]
	s_setprio 0
	s_setprio 1
	v_mfma_f32_16x16x32_bf16 v[108:111], v[160:163], v[176:179], v[108:111]
	v_mfma_f32_16x16x32_bf16 v[104:107], v[168:171], v[176:179], v[104:107]
	v_mfma_f32_16x16x32_bf16 v[92:95], v[160:163], v[184:187], v[92:95]
	v_mfma_f32_16x16x32_bf16 v[88:91], v[168:171], v[184:187], v[88:91]
	v_mfma_f32_16x16x32_bf16 v[76:79], v[160:163], v[192:195], v[76:79]
	v_mfma_f32_16x16x32_bf16 v[72:75], v[168:171], v[192:195], v[72:75]
	v_mfma_f32_16x16x32_bf16 v[68:71], v[160:163], v[200:203], v[68:71]
	v_mfma_f32_16x16x32_bf16 v[64:67], v[168:171], v[200:203], v[64:67]
	v_mfma_f32_16x16x32_bf16 v[108:111], v[164:167], v[180:183], v[108:111]
	v_mfma_f32_16x16x32_bf16 v[104:107], v[172:175], v[180:183], v[104:107]
	v_mfma_f32_16x16x32_bf16 v[92:95], v[164:167], v[188:191], v[92:95]
	v_mfma_f32_16x16x32_bf16 v[88:91], v[172:175], v[188:191], v[88:91]
	v_mfma_f32_16x16x32_bf16 v[76:79], v[164:167], v[196:199], v[76:79]
	v_mfma_f32_16x16x32_bf16 v[72:75], v[172:175], v[196:199], v[72:75]
	v_mfma_f32_16x16x32_bf16 v[68:71], v[164:167], v[204:207], v[68:71]
	v_mfma_f32_16x16x32_bf16 v[64:67], v[172:175], v[204:207], v[64:67]
	s_setprio 0
	s_add_i32 s46, s71, s50
	v_lshl_add_u64 v[208:209], v[208:209], 0, s[8:9]
	s_mov_b32 m0, s46
	s_barrier
; #define G_STAGE(bufoff, gbase, voff) do { _Pragma("unroll") for (int _i = 0; _i < 2; ++_i) \
;         __builtin_amdgcn_global_load_lds((const unsigned*)((const char*)(gbase) + voff[_i]), (LAS unsigned*)(lds + (bufoff) + ldsw + _i * 8192), 16, 0, 0); } while (0)
; #define G_LDA(dst, b, h) do { _Pragma("unroll") for (int m = 0; m < 4; ++m) _Pragma("unroll") for (int k = 0; k < 2; ++k) dst[m][k] = *(const LAS bf16x8*)(lds + G_SA(b, h) + aoff + m * 2048 + k * 1024); } while (0)
; #define G_LDB(dst, b, h) do { _Pragma("unroll") for (int n = 0; n < 2; ++n) _Pragma("unroll") for (int k = 0; k < 2; ++k) dst[n][k] = *(const LAS bf16x8*)(lds + G_SB(b, h) + boff + n * 2048 + k * 1024); } while (0)
; #define G_MMA(ai, bj, At_, Bt_) do { __builtin_amdgcn_s_setprio(1); _Pragma("unroll") for (int m = 0; m < 4; ++m) _Pragma("unroll") for (int n = 0; n < 2; ++n) _Pragma("unroll") for (int k = 0; k < 2; ++k) \
;         acc[ai][bj][m][n] = __builtin_amdgcn_mfma_f32_16x16x32_bf16(Bt_[n][k], At_[m][k], acc[ai][bj][m][n], 0, 0, 0); __builtin_amdgcn_s_setprio(0); } while (0)
; #define WAIT_V(n) asm volatile("s_waitcnt vmcnt(" #n ")" ::: "memory")
; #define WAIT_L(n) asm volatile("s_waitcnt lgkmcnt(" #n ")" ::: "memory")
; #define BAR __builtin_amdgcn_s_barrier()
; #define SCHED __builtin_amdgcn_sched_barrier(0)
; template <class Get, class Epi>
; DI void gemm_loop(int ntiles, int ld, char* shm, const Get& get, const Epi& epi) {
;     ...
;         for (int t = 0; t < nt; t += 2) {
;             const bool last = (t == nt - 2);
;             const char* a1 = cA + (size_t)(t + 1) * kstep;
;             const char* a2 = last ? nA : cA + (size_t)(t + 2) * kstep; const char* b2 = last ? nB : cB + (size_t)(t + 2) * kstep;
;             const char* a3 = a2 + kstep; const char* b3 = b2 + kstep;
;             G_LDB(B0, 0, 0); G_LDB(B1, 0, 1); SCHED; G_LDA(At, 0, 0); G_STAGE(G_SA(1, 1), a1 + hstep, voffA);
;             WAIT_V(8); WAIT_L(0); BAR; G_MMA(0, 0, At, B0); G_MMA(0, 1, At, B1); BAR; SCHED;
;     ...
;             G_LDA(At, 1, 1); G_STAGE(G_SB(1, 0), b3, voffB); G_STAGE(G_SB(1, 1), b3 + hstep, voffB); G_STAGE(G_SA(1, 0), a3, voffA);
;             WAIT_V(8); WAIT_L(0); BAR; G_MMA(1, 0, At, B0); G_MMA(1, 1, At, B1); BAR; SCHED;
;         }
	ds_read_b128 v[176:179], v143 offset:49152
	ds_read_b128 v[180:183], v143 offset:50176
	ds_read_b128 v[184:187], v143 offset:51200
	ds_read_b128 v[188:191], v143 offset:52224
	ds_read_b128 v[192:195], v143 offset:53248
	ds_read_b128 v[196:199], v143 offset:54272
	ds_read_b128 v[200:203], v143 offset:55296
	ds_read_b128 v[204:207], v143 offset:56320
	global_load_lds_dwordx4 v[208:209], off
	s_add_i32 m0, s46, 0x2000
	s_add_u32 s14, s14, 0x40080
	v_lshl_add_u64 v[208:209], v[210:211], 0, s[8:9]
	s_addc_u32 s15, s15, 0
	s_add_i32 s46, s72, s50
	global_load_lds_dwordx4 v[208:209], off
	v_lshl_add_u64 v[208:209], s[14:15], 0, v[130:131]
	s_mov_b32 m0, s46
	s_nop 0
	global_load_lds_dwordx4 v[208:209], off
	v_lshl_add_u64 v[208:209], s[14:15], 0, v[134:135]
	s_add_i32 m0, s46, 0x2000
	s_nop 0
	global_load_lds_dwordx4 v[208:209], off
	v_lshl_add_u64 v[208:209], v[212:213], 0, s[8:9]
	s_mov_b32 m0, s55
	s_nop 0
	global_load_lds_dwordx4 v[208:209], off
	v_lshl_add_u64 v[208:209], v[214:215], 0, s[8:9]
	s_mov_b32 m0, s56
	s_nop 0
	global_load_lds_dwordx4 v[208:209], off
	s_waitcnt vmcnt(8)
	s_waitcnt lgkmcnt(0)
	s_barrier
	s_setprio 1
	s_waitcnt lgkmcnt(0)
	v_mfma_f32_16x16x32_bf16 v[60:63], v[144:147], v[176:179], v[60:63]
	v_mfma_f32_16x16x32_bf16 v[56:59], v[152:155], v[176:179], v[56:59]
	v_mfma_f32_16x16x32_bf16 v[52:55], v[144:147], v[184:187], v[52:55]
	v_mfma_f32_16x16x32_bf16 v[48:51], v[152:155], v[184:187], v[48:51]
	v_mfma_f32_16x16x32_bf16 v[36:39], v[144:147], v[192:195], v[36:39]
	v_mfma_f32_16x16x32_bf16 v[32:35], v[152:155], v[192:195], v[32:35]
	v_mfma_f32_16x16x32_bf16 v[20:23], v[144:147], v[200:203], v[20:23]
	v_mfma_f32_16x16x32_bf16 v[16:19], v[152:155], v[200:203], v[16:19]
	v_mfma_f32_16x16x32_bf16 v[60:63], v[148:151], v[180:183], v[60:63]
	v_mfma_f32_16x16x32_bf16 v[56:59], v[156:159], v[180:183], v[56:59]
	v_mfma_f32_16x16x32_bf16 v[52:55], v[148:151], v[188:191], v[52:55]
	v_mfma_f32_16x16x32_bf16 v[48:51], v[156:159], v[188:191], v[48:51]
	v_mfma_f32_16x16x32_bf16 v[36:39], v[148:151], v[196:199], v[36:39]
	v_mfma_f32_16x16x32_bf16 v[32:35], v[156:159], v[196:199], v[32:35]
	v_mfma_f32_16x16x32_bf16 v[20:23], v[148:151], v[204:207], v[20:23]
	v_mfma_f32_16x16x32_bf16 v[16:19], v[156:159], v[204:207], v[16:19]
	s_setprio 0
	s_setprio 1
	v_mfma_f32_16x16x32_bf16 v[44:47], v[160:163], v[176:179], v[44:47]
	v_mfma_f32_16x16x32_bf16 v[40:43], v[168:171], v[176:179], v[40:43]
	v_mfma_f32_16x16x32_bf16 v[28:31], v[160:163], v[184:187], v[28:31]
	v_mfma_f32_16x16x32_bf16 v[24:27], v[168:171], v[184:187], v[24:27]
	v_mfma_f32_16x16x32_bf16 v[12:15], v[160:163], v[192:195], v[12:15]
	v_mfma_f32_16x16x32_bf16 v[8:11], v[168:171], v[192:195], v[8:11]
	v_mfma_f32_16x16x32_bf16 v[4:7], v[160:163], v[200:203], v[4:7]
	v_mfma_f32_16x16x32_bf16 v[0:3], v[168:171], v[200:203], v[0:3]
	v_mfma_f32_16x16x32_bf16 v[44:47], v[164:167], v[180:183], v[44:47]
	v_mfma_f32_16x16x32_bf16 v[40:43], v[172:175], v[180:183], v[40:43]
	v_mfma_f32_16x16x32_bf16 v[28:31], v[164:167], v[188:191], v[28:31]
	v_mfma_f32_16x16x32_bf16 v[24:27], v[172:175], v[188:191], v[24:27]
	v_mfma_f32_16x16x32_bf16 v[12:15], v[164:167], v[196:199], v[12:15]
	v_mfma_f32_16x16x32_bf16 v[8:11], v[172:175], v[196:199], v[8:11]
	v_mfma_f32_16x16x32_bf16 v[4:7], v[164:167], v[204:207], v[4:7]
	v_mfma_f32_16x16x32_bf16 v[0:3], v[172:175], v[204:207], v[0:3]
	s_setprio 0
	s_add_i32 s70, s70, 2
	s_add_u32 s48, s48, 0x100
	s_addc_u32 s49, s49, 0
	s_add_u32 s64, s64, 0x100
	s_addc_u32 s65, s65, 0
	s_cmp_gt_u32 s70, 13
	s_barrier
	s_cbranch_scc0 .LBB0_3141
	s_branch .Lpost_3141
.LBB0_3141:
	ds_read_b128 v[144:147], v141
	ds_read_b128 v[148:151], v141 offset:1024
	ds_read_b128 v[152:155], v141 offset:2048
	ds_read_b128 v[156:159], v141 offset:3072
	ds_read_b128 v[160:163], v142
	ds_read_b128 v[164:167], v142 offset:1024
	ds_read_b128 v[168:171], v142 offset:2048
	ds_read_b128 v[172:175], v142 offset:3072
	s_add_u32 s14, s48, 0xfffc0080
	s_addc_u32 s15, s49, -1
	s_cmp_eq_u32 s70, 12
	s_cselect_b32 s47, s11, s15
	s_cselect_b32 s46, s39, s14
	s_cselect_b32 s15, s41, s65
	s_cselect_b32 s14, s63, s64
	v_lshl_add_u64 v[208:209], s[48:49], 0, v[136:137]
	s_add_i32 m0, s35, 0xc000
	ds_read_b128 v[176:179], v143
	ds_read_b128 v[180:183], v143 offset:1024
	ds_read_b128 v[184:187], v143 offset:2048
	ds_read_b128 v[188:191], v143 offset:3072
	ds_read_b128 v[192:195], v143 offset:4096
	ds_read_b128 v[196:199], v143 offset:5120
	ds_read_b128 v[200:203], v143 offset:6144
	ds_read_b128 v[204:207], v143 offset:7168
	global_load_lds_dwordx4 v[208:209], off
	v_lshl_add_u64 v[208:209], s[48:49], 0, v[138:139]
	s_add_i32 m0, s35, 0xe000
	s_nop 0
	global_load_lds_dwordx4 v[208:209], off
	s_waitcnt vmcnt(8)
	s_waitcnt lgkmcnt(0)
	s_barrier
; #define G_STAGE(bufoff, gbase, voff) do { _Pragma("unroll") for (int _i = 0; _i < 2; ++_i) \
;         __builtin_amdgcn_global_load_lds((const unsigned*)((const char*)(gbase) + voff[_i]), (LAS unsigned*)(lds + (bufoff) + ldsw + _i * 8192), 16, 0, 0); } while (0)
; #define G_LDA(dst, b, h) do { _Pragma("unroll") for (int m = 0; m < 4; ++m) _Pragma("unroll") for (int k = 0; k < 2; ++k) dst[m][k] = *(const LAS bf16x8*)(lds + G_SA(b, h) + aoff + m * 2048 + k * 1024); } while (0)
; #define G_LDB(dst, b, h) do { _Pragma("unroll") for (int n = 0; n < 2; ++n) _Pragma("unroll") for (int k = 0; k < 2; ++k) dst[n][k] = *(const LAS bf16x8*)(lds + G_SB(b, h) + boff + n * 2048 + k * 1024); } while (0)
; #define G_MMA(ai, bj, At_, Bt_) do { __builtin_amdgcn_s_setprio(1); _Pragma("unroll") for (int m = 0; m < 4; ++m) _Pragma("unroll") for (int n = 0; n < 2; ++n) _Pragma("unroll") for (int k = 0; k < 2; ++k) \
;         acc[ai][bj][m][n] = __builtin_amdgcn_mfma_f32_16x16x32_bf16(Bt_[n][k], At_[m][k], acc[ai][bj][m][n], 0, 0, 0); __builtin_amdgcn_s_setprio(0); } while (0)
; #define WAIT_V(n) asm volatile("s_waitcnt vmcnt(" #n ")" ::: "memory")
; #define WAIT_L(n) asm volatile("s_waitcnt lgkmcnt(" #n ")" ::: "memory")
; #define BAR __builtin_amdgcn_s_barrier()
; #define SCHED __builtin_amdgcn_sched_barrier(0)
; template <class Get, class Epi>
; DI void gemm_loop(int ntiles, int ld, char* shm, const Get& get, const Epi& epi) {
;     ...
;             G_LDB(B0, 0, 0); G_LDB(B1, 0, 1); SCHED; G_LDA(At, 0, 0); G_STAGE(G_SA(1, 1), a1 + hstep, voffA);
;             WAIT_V(8); WAIT_L(0); BAR; G_MMA(0, 0, At, B0); G_MMA(0, 1, At, B1); BAR; SCHED;
;             G_LDA(At, 0, 1); G_STAGE(G_SB(0, 0), b2, voffB); G_STAGE(G_SB(0, 1), b2 + hstep, voffB); G_STAGE(G_SA(0, 0), a2, voffA);
;             WAIT_V(8); WAIT_L(0); BAR; G_MMA(1, 0, At, B0); G_MMA(1, 1, At, B1); BAR; SCHED;
;             G_LDB(B0, 1, 0); G_LDB(B1, 1, 1); SCHED; G_LDA(At, 1, 0); G_STAGE(G_SA(0, 1), a2 + hstep, voffA);
;             WAIT_V(8); WAIT_L(0); BAR; G_MMA(0, 0, At, B0); G_MMA(0, 1, At, B1); BAR; SCHED;
	s_setprio 1
	s_waitcnt lgkmcnt(0)
	v_mfma_f32_16x16x32_bf16 v[124:127], v[144:147], v[176:179], v[124:127]
	v_mfma_f32_16x16x32_bf16 v[120:123], v[152:155], v[176:179], v[120:123]
	v_mfma_f32_16x16x32_bf16 v[116:119], v[144:147], v[184:187], v[116:119]
	v_mfma_f32_16x16x32_bf16 v[112:115], v[152:155], v[184:187], v[112:115]
	v_mfma_f32_16x16x32_bf16 v[100:103], v[144:147], v[192:195], v[100:103]
	v_mfma_f32_16x16x32_bf16 v[96:99], v[152:155], v[192:195], v[96:99]
	v_mfma_f32_16x16x32_bf16 v[84:87], v[144:147], v[200:203], v[84:87]
	v_mfma_f32_16x16x32_bf16 v[80:83], v[152:155], v[200:203], v[80:83]
	v_mfma_f32_16x16x32_bf16 v[124:127], v[148:151], v[180:183], v[124:127]
	v_mfma_f32_16x16x32_bf16 v[120:123], v[156:159], v[180:183], v[120:123]
	v_mfma_f32_16x16x32_bf16 v[116:119], v[148:151], v[188:191], v[116:119]
	v_mfma_f32_16x16x32_bf16 v[112:115], v[156:159], v[188:191], v[112:115]
	v_mfma_f32_16x16x32_bf16 v[100:103], v[148:151], v[196:199], v[100:103]
	v_mfma_f32_16x16x32_bf16 v[96:99], v[156:159], v[196:199], v[96:99]
	v_mfma_f32_16x16x32_bf16 v[84:87], v[148:151], v[204:207], v[84:87]
	v_mfma_f32_16x16x32_bf16 v[80:83], v[156:159], v[204:207], v[80:83]
	s_setprio 0
	s_setprio 1
	v_mfma_f32_16x16x32_bf16 v[108:111], v[160:163], v[176:179], v[108:111]
	v_mfma_f32_16x16x32_bf16 v[104:107], v[168:171], v[176:179], v[104:107]
	v_mfma_f32_16x16x32_bf16 v[92:95], v[160:163], v[184:187], v[92:95]
	v_mfma_f32_16x16x32_bf16 v[88:91], v[168:171], v[184:187], v[88:91]
	v_mfma_f32_16x16x32_bf16 v[76:79], v[160:163], v[192:195], v[76:79]
	v_mfma_f32_16x16x32_bf16 v[72:75], v[168:171], v[192:195], v[72:75]
	v_mfma_f32_16x16x32_bf16 v[68:71], v[160:163], v[200:203], v[68:71]
	v_mfma_f32_16x16x32_bf16 v[64:67], v[168:171], v[200:203], v[64:67]
	v_mfma_f32_16x16x32_bf16 v[108:111], v[164:167], v[180:183], v[108:111]
	v_mfma_f32_16x16x32_bf16 v[104:107], v[172:175], v[180:183], v[104:107]
	v_mfma_f32_16x16x32_bf16 v[92:95], v[164:167], v[188:191], v[92:95]
	v_mfma_f32_16x16x32_bf16 v[88:91], v[172:175], v[188:191], v[88:91]
	v_mfma_f32_16x16x32_bf16 v[76:79], v[164:167], v[196:199], v[76:79]
	v_mfma_f32_16x16x32_bf16 v[72:75], v[172:175], v[196:199], v[72:75]
	v_mfma_f32_16x16x32_bf16 v[68:71], v[164:167], v[204:207], v[68:71]
	v_mfma_f32_16x16x32_bf16 v[64:67], v[172:175], v[204:207], v[64:67]
	s_setprio 0
	s_add_i32 s71, s57, s50
	v_lshl_add_u64 v[208:209], s[14:15], 0, v[130:131]
	s_mov_b32 m0, s71
	s_barrier
	ds_read_b128 v[176:179], v143 offset:16384
	ds_read_b128 v[180:183], v143 offset:17408
	ds_read_b128 v[184:187], v143 offset:18432
	ds_read_b128 v[188:191], v143 offset:19456
	ds_read_b128 v[192:195], v143 offset:20480
	ds_read_b128 v[196:199], v143 offset:21504
	ds_read_b128 v[200:203], v143 offset:22528
	ds_read_b128 v[204:207], v143 offset:23552
	global_load_lds_dwordx4 v[208:209], off
	s_add_i32 m0, s71, 0x2000
	s_add_u32 s72, s14, 0x40000
	v_lshl_add_u64 v[210:211], s[14:15], 0, v[134:135]
	s_addc_u32 s73, s15, 0
	s_add_i32 s71, s58, s50
	global_load_lds_dwordx4 v[210:211], off
	v_lshl_add_u64 v[212:213], s[72:73], 0, v[130:131]
	s_mov_b32 m0, s71
	v_lshl_add_u64 v[214:215], s[46:47], 0, v[132:133]
	global_load_lds_dwordx4 v[212:213], off
	v_lshl_add_u64 v[212:213], s[72:73], 0, v[134:135]
	s_add_i32 m0, s71, 0x2000
	s_nop 0
	global_load_lds_dwordx4 v[212:213], off
	v_lshl_add_u64 v[212:213], s[46:47], 0, v[128:129]
	s_mov_b32 m0, s35
	s_nop 0
	global_load_lds_dwordx4 v[212:213], off
	s_mov_b32 m0, s51
	s_nop 0
	global_load_lds_dwordx4 v[214:215], off
	s_waitcnt vmcnt(8)
	s_waitcnt lgkmcnt(0)
	s_barrier
	s_setprio 1
	s_waitcnt lgkmcnt(0)
	v_mfma_f32_16x16x32_bf16 v[60:63], v[144:147], v[176:179], v[60:63]
	v_mfma_f32_16x16x32_bf16 v[56:59], v[152:155], v[176:179], v[56:59]
	v_mfma_f32_16x16x32_bf16 v[52:55], v[144:147], v[184:187], v[52:55]
	v_mfma_f32_16x16x32_bf16 v[48:51], v[152:155], v[184:187], v[48:51]
	v_mfma_f32_16x16x32_bf16 v[36:39], v[144:147], v[192:195], v[36:39]
	v_mfma_f32_16x16x32_bf16 v[32:35], v[152:155], v[192:195], v[32:35]
	v_mfma_f32_16x16x32_bf16 v[20:23], v[144:147], v[200:203], v[20:23]
	v_mfma_f32_16x16x32_bf16 v[16:19], v[152:155], v[200:203], v[16:19]
	v_mfma_f32_16x16x32_bf16 v[60:63], v[148:151], v[180:183], v[60:63]
	v_mfma_f32_16x16x32_bf16 v[56:59], v[156:159], v[180:183], v[56:59]
	v_mfma_f32_16x16x32_bf16 v[52:55], v[148:151], v[188:191], v[52:55]
	v_mfma_f32_16x16x32_bf16 v[48:51], v[156:159], v[188:191], v[48:51]
	v_mfma_f32_16x16x32_bf16 v[36:39], v[148:151], v[196:199], v[36:39]
	v_mfma_f32_16x16x32_bf16 v[32:35], v[156:159], v[196:199], v[32:35]
	v_mfma_f32_16x16x32_bf16 v[20:23], v[148:151], v[204:207], v[20:23]
	v_mfma_f32_16x16x32_bf16 v[16:19], v[156:159], v[204:207], v[16:19]
	s_setprio 0
	s_setprio 1
	v_mfma_f32_16x16x32_bf16 v[44:47], v[160:163], v[176:179], v[44:47]
	v_mfma_f32_16x16x32_bf16 v[40:43], v[168:171], v[176:179], v[40:43]
	v_mfma_f32_16x16x32_bf16 v[28:31], v[160:163], v[184:187], v[28:31]
	v_mfma_f32_16x16x32_bf16 v[24:27], v[168:171], v[184:187], v[24:27]
	v_mfma_f32_16x16x32_bf16 v[12:15], v[160:163], v[192:195], v[12:15]
	v_mfma_f32_16x16x32_bf16 v[8:11], v[168:171], v[192:195], v[8:11]
	v_mfma_f32_16x16x32_bf16 v[4:7], v[160:163], v[200:203], v[4:7]
	v_mfma_f32_16x16x32_bf16 v[0:3], v[168:171], v[200:203], v[0:3]
	v_mfma_f32_16x16x32_bf16 v[44:47], v[164:167], v[180:183], v[44:47]
	v_mfma_f32_16x16x32_bf16 v[40:43], v[172:175], v[180:183], v[40:43]
	v_mfma_f32_16x16x32_bf16 v[28:31], v[164:167], v[188:191], v[28:31]
	v_mfma_f32_16x16x32_bf16 v[24:27], v[172:175], v[188:191], v[24:27]
	v_mfma_f32_16x16x32_bf16 v[12:15], v[164:167], v[196:199], v[12:15]
	v_mfma_f32_16x16x32_bf16 v[8:11], v[172:175], v[196:199], v[8:11]
	v_mfma_f32_16x16x32_bf16 v[4:7], v[164:167], v[204:207], v[4:7]
	v_mfma_f32_16x16x32_bf16 v[0:3], v[172:175], v[204:207], v[0:3]
	s_setprio 0
	s_add_i32 s71, 0, 0x18000
	s_add_i32 s72, 0, 0x1c000
	v_add_u32_e32 v156, s71, v140
	s_barrier
; #define G_STAGE(bufoff, gbase, voff) do { _Pragma("unroll") for (int _i = 0; _i < 2; ++_i) \
;         __builtin_amdgcn_global_load_lds((const unsigned*)((const char*)(gbase) + voff[_i]), (LAS unsigned*)(lds + (bufoff) + ldsw + _i * 8192), 16, 0, 0); } while (0)
; #define G_LDA(dst, b, h) do { _Pragma("unroll") for (int m = 0; m < 4; ++m) _Pragma("unroll") for (int k = 0; k < 2; ++k) dst[m][k] = *(const LAS bf16x8*)(lds + G_SA(b, h) + aoff + m * 2048 + k * 1024); } while (0)
; #define G_LDB(dst, b, h) do { _Pragma("unroll") for (int n = 0; n < 2; ++n) _Pragma("unroll") for (int k = 0; k < 2; ++k) dst[n][k] = *(const LAS bf16x8*)(lds + G_SB(b, h) + boff + n * 2048 + k * 1024); } while (0)
; #define G_MMA(ai, bj, At_, Bt_) do { __builtin_amdgcn_s_setprio(1); _Pragma("unroll") for (int m = 0; m < 4; ++m) _Pragma("unroll") for (int n = 0; n < 2; ++n) _Pragma("unroll") for (int k = 0; k < 2; ++k) \
;         acc[ai][bj][m][n] = __builtin_amdgcn_mfma_f32_16x16x32_bf16(Bt_[n][k], At_[m][k], acc[ai][bj][m][n], 0, 0, 0); __builtin_amdgcn_s_setprio(0); } while (0)
; #define WAIT_V(n) asm volatile("s_waitcnt vmcnt(" #n ")" ::: "memory")
; #define WAIT_L(n) asm volatile("s_waitcnt lgkmcnt(" #n ")" ::: "memory")
; #define BAR __builtin_amdgcn_s_barrier()
; #define SCHED __builtin_amdgcn_sched_barrier(0)
; template <class Get, class Epi>
; DI void gemm_loop(int ntiles, int ld, char* shm, const Get& get, const Epi& epi) {
;     ...
;             G_LDB(B0, 1, 0); G_LDB(B1, 1, 1); SCHED; G_LDA(At, 1, 0); G_STAGE(G_SA(0, 1), a2 + hstep, voffA);
;             WAIT_V(8); WAIT_L(0); BAR; G_MMA(0, 0, At, B0); G_MMA(0, 1, At, B1); BAR; SCHED;
	v_add_u32_e32 v172, s72, v140
	ds_read_b128 v[144:147], v156
	ds_read_b128 v[148:151], v156 offset:1024
	ds_read_b128 v[152:155], v156 offset:2048
	ds_read_b128 v[156:159], v156 offset:3072
	ds_read_b128 v[160:163], v172
	ds_read_b128 v[164:167], v172 offset:1024
	ds_read_b128 v[168:171], v172 offset:2048
	ds_read_b128 v[172:175], v172 offset:3072
	s_add_u32 s46, s46, 0x40000
	s_addc_u32 s47, s47, 0
	s_mov_b32 m0, s52
	v_lshl_add_u64 v[216:217], s[46:47], 0, v[128:129]
	ds_read_b128 v[176:179], v143 offset:32768
	ds_read_b128 v[180:183], v143 offset:33792
	ds_read_b128 v[184:187], v143 offset:34816
	ds_read_b128 v[188:191], v143 offset:35840
	ds_read_b128 v[192:195], v143 offset:36864
	ds_read_b128 v[196:199], v143 offset:37888
	ds_read_b128 v[200:203], v143 offset:38912
	ds_read_b128 v[204:207], v143 offset:39936
	global_load_lds_dwordx4 v[216:217], off
	v_lshl_add_u64 v[216:217], s[46:47], 0, v[132:133]
	s_mov_b32 m0, s53
	s_nop 0
	global_load_lds_dwordx4 v[216:217], off
	s_waitcnt vmcnt(8)
	s_waitcnt lgkmcnt(0)
	s_barrier
	s_setprio 1
	s_waitcnt lgkmcnt(0)
	v_mfma_f32_16x16x32_bf16 v[124:127], v[144:147], v[176:179], v[124:127]
	v_mfma_f32_16x16x32_bf16 v[120:123], v[152:155], v[176:179], v[120:123]
	v_mfma_f32_16x16x32_bf16 v[116:119], v[144:147], v[184:187], v[116:119]
	v_mfma_f32_16x16x32_bf16 v[112:115], v[152:155], v[184:187], v[112:115]
	v_mfma_f32_16x16x32_bf16 v[100:103], v[144:147], v[192:195], v[100:103]
	v_mfma_f32_16x16x32_bf16 v[96:99], v[152:155], v[192:195], v[96:99]
	v_mfma_f32_16x16x32_bf16 v[84:87], v[144:147], v[200:203], v[84:87]
	v_mfma_f32_16x16x32_bf16 v[80:83], v[152:155], v[200:203], v[80:83]
	v_mfma_f32_16x16x32_bf16 v[124:127], v[148:151], v[180:183], v[124:127]
	v_mfma_f32_16x16x32_bf16 v[120:123], v[156:159], v[180:183], v[120:123]
	v_mfma_f32_16x16x32_bf16 v[116:119], v[148:151], v[188:191], v[116:119]
	v_mfma_f32_16x16x32_bf16 v[112:115], v[156:159], v[188:191], v[112:115]
	v_mfma_f32_16x16x32_bf16 v[100:103], v[148:151], v[196:199], v[100:103]
	v_mfma_f32_16x16x32_bf16 v[96:99], v[156:159], v[196:199], v[96:99]
	v_mfma_f32_16x16x32_bf16 v[84:87], v[148:151], v[204:207], v[84:87]
	v_mfma_f32_16x16x32_bf16 v[80:83], v[156:159], v[204:207], v[80:83]
	s_setprio 0
	s_setprio 1
	v_mfma_f32_16x16x32_bf16 v[108:111], v[160:163], v[176:179], v[108:111]
	v_mfma_f32_16x16x32_bf16 v[104:107], v[168:171], v[176:179], v[104:107]
	v_mfma_f32_16x16x32_bf16 v[92:95], v[160:163], v[184:187], v[92:95]
	v_mfma_f32_16x16x32_bf16 v[88:91], v[168:171], v[184:187], v[88:91]
	v_mfma_f32_16x16x32_bf16 v[76:79], v[160:163], v[192:195], v[76:79]
	v_mfma_f32_16x16x32_bf16 v[72:75], v[168:171], v[192:195], v[72:75]
	v_mfma_f32_16x16x32_bf16 v[68:71], v[160:163], v[200:203], v[68:71]
	v_mfma_f32_16x16x32_bf16 v[64:67], v[168:171], v[200:203], v[64:67]
	v_mfma_f32_16x16x32_bf16 v[108:111], v[164:167], v[180:183], v[108:111]
	v_mfma_f32_16x16x32_bf16 v[104:107], v[172:175], v[180:183], v[104:107]
	v_mfma_f32_16x16x32_bf16 v[92:95], v[164:167], v[188:191], v[92:95]
	v_mfma_f32_16x16x32_bf16 v[88:91], v[172:175], v[188:191], v[88:91]
	v_mfma_f32_16x16x32_bf16 v[76:79], v[164:167], v[196:199], v[76:79]
	v_mfma_f32_16x16x32_bf16 v[72:75], v[172:175], v[196:199], v[72:75]
	v_mfma_f32_16x16x32_bf16 v[68:71], v[164:167], v[204:207], v[68:71]
	v_mfma_f32_16x16x32_bf16 v[64:67], v[172:175], v[204:207], v[64:67]
	s_setprio 0
	s_add_i32 s46, s71, s50
	v_lshl_add_u64 v[208:209], v[208:209], 0, s[8:9]
	s_mov_b32 m0, s46
	s_barrier
; #define G_STAGE(bufoff, gbase, voff) do { _Pragma("unroll") for (int _i = 0; _i < 2; ++_i) \
;         __builtin_amdgcn_global_load_lds((const unsigned*)((const char*)(gbase) + voff[_i]), (LAS unsigned*)(lds + (bufoff) + ldsw + _i * 8192), 16, 0, 0); } while (0)
; #define G_LDA(dst, b, h) do { _Pragma("unroll") for (int m = 0; m < 4; ++m) _Pragma("unroll") for (int k = 0; k < 2; ++k) dst[m][k] = *(const LAS bf16x8*)(lds + G_SA(b, h) + aoff + m * 2048 + k * 1024); } while (0)
; #define G_MMA(ai, bj, At_, Bt_) do { __builtin_amdgcn_s_setprio(1); _Pragma("unroll") for (int m = 0; m < 4; ++m) _Pragma("unroll") for (int n = 0; n < 2; ++n) _Pragma("unroll") for (int k = 0; k < 2; ++k) \
;         acc[ai][bj][m][n] = __builtin_amdgcn_mfma_f32_16x16x32_bf16(Bt_[n][k], At_[m][k], acc[ai][bj][m][n], 0, 0, 0); __builtin_amdgcn_s_setprio(0); } while (0)
; #define WAIT_V(n) asm volatile("s_waitcnt vmcnt(" #n ")" ::: "memory")
; #define WAIT_L(n) asm volatile("s_waitcnt lgkmcnt(" #n ")" ::: "memory")
; #define BAR __builtin_amdgcn_s_barrier()
; #define SCHED __builtin_amdgcn_sched_barrier(0)
; template <class Get, class Epi>
; DI void gemm_loop(int ntiles, int ld, char* shm, const Get& get, const Epi& epi) {
;     ...
;             G_LDA(At, 1, 1); G_STAGE(G_SB(1, 0), b3, voffB); G_STAGE(G_SB(1, 1), b3 + hstep, voffB); G_STAGE(G_SA(1, 0), a3, voffA);
;             WAIT_V(8); WAIT_L(0); BAR; G_MMA(1, 0, At, B0); G_MMA(1, 1, At, B1); BAR; SCHED;
;         }
	ds_read_b128 v[176:179], v143 offset:49152
	ds_read_b128 v[180:183], v143 offset:50176
	ds_read_b128 v[184:187], v143 offset:51200
	ds_read_b128 v[188:191], v143 offset:52224
	ds_read_b128 v[192:195], v143 offset:53248
	ds_read_b128 v[196:199], v143 offset:54272
	ds_read_b128 v[200:203], v143 offset:55296
	ds_read_b128 v[204:207], v143 offset:56320
	global_load_lds_dwordx4 v[208:209], off
	s_add_i32 m0, s46, 0x2000
	s_add_u32 s14, s14, 0x40080
	v_lshl_add_u64 v[208:209], v[210:211], 0, s[8:9]
	s_addc_u32 s15, s15, 0
	s_add_i32 s46, s72, s50
	global_load_lds_dwordx4 v[208:209], off
	v_lshl_add_u64 v[208:209], s[14:15], 0, v[130:131]
	s_mov_b32 m0, s46
	s_nop 0
	global_load_lds_dwordx4 v[208:209], off
	v_lshl_add_u64 v[208:209], s[14:15], 0, v[134:135]
	s_add_i32 m0, s46, 0x2000
	s_nop 0
	global_load_lds_dwordx4 v[208:209], off
	v_lshl_add_u64 v[208:209], v[212:213], 0, s[8:9]
	s_mov_b32 m0, s55
	s_nop 0
	global_load_lds_dwordx4 v[208:209], off
	v_lshl_add_u64 v[208:209], v[214:215], 0, s[8:9]
	s_mov_b32 m0, s56
	s_nop 0
	global_load_lds_dwordx4 v[208:209], off
	s_waitcnt vmcnt(8)
	s_waitcnt lgkmcnt(0)
	s_barrier
	s_setprio 1
	s_waitcnt lgkmcnt(0)
	v_mfma_f32_16x16x32_bf16 v[60:63], v[144:147], v[176:179], v[60:63]
	v_mfma_f32_16x16x32_bf16 v[56:59], v[152:155], v[176:179], v[56:59]
	v_mfma_f32_16x16x32_bf16 v[52:55], v[144:147], v[184:187], v[52:55]
	v_mfma_f32_16x16x32_bf16 v[48:51], v[152:155], v[184:187], v[48:51]
	v_mfma_f32_16x16x32_bf16 v[36:39], v[144:147], v[192:195], v[36:39]
	v_mfma_f32_16x16x32_bf16 v[32:35], v[152:155], v[192:195], v[32:35]
	v_mfma_f32_16x16x32_bf16 v[20:23], v[144:147], v[200:203], v[20:23]
	v_mfma_f32_16x16x32_bf16 v[16:19], v[152:155], v[200:203], v[16:19]
	v_mfma_f32_16x16x32_bf16 v[60:63], v[148:151], v[180:183], v[60:63]
	v_mfma_f32_16x16x32_bf16 v[56:59], v[156:159], v[180:183], v[56:59]
	v_mfma_f32_16x16x32_bf16 v[52:55], v[148:151], v[188:191], v[52:55]
	v_mfma_f32_16x16x32_bf16 v[48:51], v[156:159], v[188:191], v[48:51]
	v_mfma_f32_16x16x32_bf16 v[36:39], v[148:151], v[196:199], v[36:39]
	v_mfma_f32_16x16x32_bf16 v[32:35], v[156:159], v[196:199], v[32:35]
	v_mfma_f32_16x16x32_bf16 v[20:23], v[148:151], v[204:207], v[20:23]
	v_mfma_f32_16x16x32_bf16 v[16:19], v[156:159], v[204:207], v[16:19]
	s_setprio 0
	s_setprio 1
	v_mfma_f32_16x16x32_bf16 v[44:47], v[160:163], v[176:179], v[44:47]
	v_mfma_f32_16x16x32_bf16 v[40:43], v[168:171], v[176:179], v[40:43]
	v_mfma_f32_16x16x32_bf16 v[28:31], v[160:163], v[184:187], v[28:31]
	v_mfma_f32_16x16x32_bf16 v[24:27], v[168:171], v[184:187], v[24:27]
	v_mfma_f32_16x16x32_bf16 v[12:15], v[160:163], v[192:195], v[12:15]
	v_mfma_f32_16x16x32_bf16 v[8:11], v[168:171], v[192:195], v[8:11]
	v_mfma_f32_16x16x32_bf16 v[4:7], v[160:163], v[200:203], v[4:7]
	v_mfma_f32_16x16x32_bf16 v[0:3], v[168:171], v[200:203], v[0:3]
	v_mfma_f32_16x16x32_bf16 v[44:47], v[164:167], v[180:183], v[44:47]
	v_mfma_f32_16x16x32_bf16 v[40:43], v[172:175], v[180:183], v[40:43]
	v_mfma_f32_16x16x32_bf16 v[28:31], v[164:167], v[188:191], v[28:31]
	v_mfma_f32_16x16x32_bf16 v[24:27], v[172:175], v[188:191], v[24:27]
	v_mfma_f32_16x16x32_bf16 v[12:15], v[164:167], v[196:199], v[12:15]
	v_mfma_f32_16x16x32_bf16 v[8:11], v[172:175], v[196:199], v[8:11]
	v_mfma_f32_16x16x32_bf16 v[4:7], v[164:167], v[204:207], v[4:7]
	v_mfma_f32_16x16x32_bf16 v[0:3], v[172:175], v[204:207], v[0:3]
	s_setprio 0
	s_add_i32 s70, s70, 2
	s_add_u32 s48, s48, 0x100
	s_addc_u32 s49, s49, 0
	s_add_u32 s64, s64, 0x100
	s_addc_u32 s65, s65, 0
	s_cmp_gt_u32 s70, 13
	s_barrier
	s_cbranch_scc0 .LBB0_3141

; #define G_STAGE(bufoff, gbase, voff) do { _Pragma("unroll") for (int _i = 0; _i < 2; ++_i) \
;         __builtin_amdgcn_global_load_lds((const unsigned*)((const char*)(gbase) + voff[_i]), (LAS unsigned*)(lds + (bufoff) + ldsw + _i * 8192), 16, 0, 0); } while (0)
; #define G_LDA(dst, b, h) do { _Pragma("unroll") for (int m = 0; m < 4; ++m) _Pragma("unroll") for (int k = 0; k < 2; ++k) dst[m][k] = *(const LAS bf16x8*)(lds + G_SA(b, h) + aoff + m * 2048 + k * 1024); } while (0)
; #define G_LDB(dst, b, h) do { _Pragma("unroll") for (int n = 0; n < 2; ++n) _Pragma("unroll") for (int k = 0; k < 2; ++k) dst[n][k] = *(const LAS bf16x8*)(lds + G_SB(b, h) + boff + n * 2048 + k * 1024); } while (0)
; #define G_MMA(ai, bj, At_, Bt_) do { __builtin_amdgcn_s_setprio(1); _Pragma("unroll") for (int m = 0; m < 4; ++m) _Pragma("unroll") for (int n = 0; n < 2; ++n) _Pragma("unroll") for (int k = 0; k < 2; ++k) \
;         acc[ai][bj][m][n] = __builtin_amdgcn_mfma_f32_16x16x32_bf16(Bt_[n][k], At_[m][k], acc[ai][bj][m][n], 0, 0, 0); __builtin_amdgcn_s_setprio(0); } while (0)
; #define WAIT_V(n) asm volatile("s_waitcnt vmcnt(" #n ")" ::: "memory")
; #define WAIT_L(n) asm volatile("s_waitcnt lgkmcnt(" #n ")" ::: "memory")
; #define BAR __builtin_amdgcn_s_barrier()
; #define SCHED __builtin_amdgcn_sched_barrier(0)
; template <class Get, class Epi>
; DI void gemm_loop(int ntiles, int ld, char* shm, const Get& get, const Epi& epi) {
;     ...
;         for (int t = 0; t < nt; t += 2) {
;             const bool last = (t == nt - 2);
;             const char* a1 = cA + (size_t)(t + 1) * kstep;
;             const char* a2 = last ? nA : cA + (size_t)(t + 2) * kstep; const char* b2 = last ? nB : cB + (size_t)(t + 2) * kstep;
;             const char* a3 = a2 + kstep; const char* b3 = b2 + kstep;
;             G_LDB(B0, 0, 0); G_LDB(B1, 0, 1); SCHED; G_LDA(At, 0, 0); G_STAGE(G_SA(1, 1), a1 + hstep, voffA);
;             WAIT_V(8); WAIT_L(0); BAR; G_MMA(0, 0, At, B0); G_MMA(0, 1, At, B1); BAR; SCHED;
;             G_LDA(At, 0, 1); G_STAGE(G_SB(0, 0), b2, voffB); G_STAGE(G_SB(0, 1), b2 + hstep, voffB); G_STAGE(G_SA(0, 0), a2, voffA);
;             WAIT_V(8); WAIT_L(0); BAR; G_MMA(1, 0, At, B0); G_MMA(1, 1, At, B1); BAR; SCHED;
.Lpeel_3466:
	ds_read_b128 v[128:131], v169
	ds_read_b128 v[132:135], v169 offset:1024
	ds_read_b128 v[136:139], v169 offset:2048
	ds_read_b128 v[140:143], v169 offset:3072
	ds_read_b128 v[158:161], v170
	ds_read_b128 v[162:165], v170 offset:1024
	ds_read_b128 v[172:175], v170 offset:2048
	ds_read_b128 v[176:179], v170 offset:3072
	s_add_u32 s14, s44, 0xfffc0080
	s_addc_u32 s15, s45, -1
	s_cmp_eq_u32 s71, 12
	s_cselect_b32 s47, s3, s15
	s_cselect_b32 s46, s35, s14
	s_cselect_b32 s15, s37, s70
	s_cselect_b32 s14, s64, s65
	v_lshl_add_u64 v[144:145], s[44:45], 0, v[154:155]
	s_add_i32 m0, s43, 0xc000
	ds_read_b128 v[180:183], v171
	ds_read_b128 v[184:187], v171 offset:1024
	ds_read_b128 v[188:191], v171 offset:2048
	ds_read_b128 v[192:195], v171 offset:3072
	ds_read_b128 v[196:199], v171 offset:4096
	ds_read_b128 v[200:203], v171 offset:5120
	ds_read_b128 v[204:207], v171 offset:6144
	ds_read_b128 v[208:211], v171 offset:7168
	global_load_lds_dwordx4 v[144:145], off
	v_lshl_add_u64 v[144:145], s[44:45], 0, v[156:157]
	s_add_i32 m0, s43, 0xe000
	s_nop 0
	global_load_lds_dwordx4 v[144:145], off
	s_waitcnt vmcnt(8)
	s_waitcnt lgkmcnt(0)
	s_barrier
	s_setprio 1
	s_waitcnt lgkmcnt(0)
	v_mfma_f32_16x16x32_bf16 v[124:127], v[128:131], v[180:183], 0
	v_mfma_f32_16x16x32_bf16 v[120:123], v[136:139], v[180:183], 0
	v_mfma_f32_16x16x32_bf16 v[116:119], v[128:131], v[188:191], 0
	v_mfma_f32_16x16x32_bf16 v[112:115], v[136:139], v[188:191], 0
	v_mfma_f32_16x16x32_bf16 v[108:111], v[128:131], v[196:199], 0
	v_mfma_f32_16x16x32_bf16 v[104:107], v[136:139], v[196:199], 0
	v_mfma_f32_16x16x32_bf16 v[100:103], v[128:131], v[204:207], 0
	v_mfma_f32_16x16x32_bf16 v[96:99], v[136:139], v[204:207], 0
	v_mfma_f32_16x16x32_bf16 v[124:127], v[132:135], v[184:187], v[124:127]
	v_mfma_f32_16x16x32_bf16 v[120:123], v[140:143], v[184:187], v[120:123]
	v_mfma_f32_16x16x32_bf16 v[116:119], v[132:135], v[192:195], v[116:119]
	v_mfma_f32_16x16x32_bf16 v[112:115], v[140:143], v[192:195], v[112:115]
	v_mfma_f32_16x16x32_bf16 v[108:111], v[132:135], v[200:203], v[108:111]
	v_mfma_f32_16x16x32_bf16 v[104:107], v[140:143], v[200:203], v[104:107]
	v_mfma_f32_16x16x32_bf16 v[100:103], v[132:135], v[208:211], v[100:103]
	v_mfma_f32_16x16x32_bf16 v[96:99], v[140:143], v[208:211], v[96:99]
	s_setprio 0
	s_setprio 1
	v_mfma_f32_16x16x32_bf16 v[60:63], v[158:161], v[180:183], 0
	v_mfma_f32_16x16x32_bf16 v[56:59], v[172:175], v[180:183], 0
	v_mfma_f32_16x16x32_bf16 v[52:55], v[158:161], v[188:191], 0
	v_mfma_f32_16x16x32_bf16 v[48:51], v[172:175], v[188:191], 0
	v_mfma_f32_16x16x32_bf16 v[44:47], v[158:161], v[196:199], 0
	v_mfma_f32_16x16x32_bf16 v[40:43], v[172:175], v[196:199], 0
	v_mfma_f32_16x16x32_bf16 v[36:39], v[158:161], v[204:207], 0
	v_mfma_f32_16x16x32_bf16 v[32:35], v[172:175], v[204:207], 0
	v_mfma_f32_16x16x32_bf16 v[60:63], v[162:165], v[184:187], v[60:63]
	v_mfma_f32_16x16x32_bf16 v[56:59], v[176:179], v[184:187], v[56:59]
	v_mfma_f32_16x16x32_bf16 v[52:55], v[162:165], v[192:195], v[52:55]
	v_mfma_f32_16x16x32_bf16 v[48:51], v[176:179], v[192:195], v[48:51]
	v_mfma_f32_16x16x32_bf16 v[44:47], v[162:165], v[200:203], v[44:47]
	v_mfma_f32_16x16x32_bf16 v[40:43], v[176:179], v[200:203], v[40:43]
	v_mfma_f32_16x16x32_bf16 v[36:39], v[162:165], v[208:211], v[36:39]
	v_mfma_f32_16x16x32_bf16 v[32:35], v[176:179], v[208:211], v[32:35]
	s_setprio 0
	s_add_i32 s72, s56, s48
	v_lshl_add_u64 v[144:145], s[14:15], 0, v[148:149]
	s_mov_b32 m0, s72
	s_barrier
	ds_read_b128 v[180:183], v171 offset:16384
	ds_read_b128 v[184:187], v171 offset:17408
	ds_read_b128 v[188:191], v171 offset:18432
	ds_read_b128 v[192:195], v171 offset:19456
	ds_read_b128 v[196:199], v171 offset:20480
	ds_read_b128 v[200:203], v171 offset:21504
	ds_read_b128 v[204:207], v171 offset:22528
	ds_read_b128 v[208:211], v171 offset:23552
	global_load_lds_dwordx4 v[144:145], off
	s_add_i32 m0, s72, 0x2000
	s_add_u32 s72, s14, 0x40000
	v_lshl_add_u64 v[166:167], s[14:15], 0, v[152:153]
	s_addc_u32 s73, s15, 0
	s_add_i32 s74, s57, s48
	global_load_lds_dwordx4 v[166:167], off
	v_lshl_add_u64 v[212:213], s[72:73], 0, v[148:149]
	s_mov_b32 m0, s74
	v_lshl_add_u64 v[214:215], s[46:47], 0, v[150:151]
	global_load_lds_dwordx4 v[212:213], off
	v_lshl_add_u64 v[212:213], s[72:73], 0, v[152:153]
	s_add_i32 m0, s74, 0x2000
	s_nop 0
	global_load_lds_dwordx4 v[212:213], off
	v_lshl_add_u64 v[212:213], s[46:47], 0, v[146:147]
	s_mov_b32 m0, s43
	s_nop 0
	global_load_lds_dwordx4 v[212:213], off
	s_mov_b32 m0, s49
	s_nop 0
	global_load_lds_dwordx4 v[214:215], off
	s_waitcnt vmcnt(8)
	s_waitcnt lgkmcnt(0)
	s_barrier
; #define G_STAGE(bufoff, gbase, voff) do { _Pragma("unroll") for (int _i = 0; _i < 2; ++_i) \
;         __builtin_amdgcn_global_load_lds((const unsigned*)((const char*)(gbase) + voff[_i]), (LAS unsigned*)(lds + (bufoff) + ldsw + _i * 8192), 16, 0, 0); } while (0)
; #define G_LDA(dst, b, h) do { _Pragma("unroll") for (int m = 0; m < 4; ++m) _Pragma("unroll") for (int k = 0; k < 2; ++k) dst[m][k] = *(const LAS bf16x8*)(lds + G_SA(b, h) + aoff + m * 2048 + k * 1024); } while (0)
; #define G_LDB(dst, b, h) do { _Pragma("unroll") for (int n = 0; n < 2; ++n) _Pragma("unroll") for (int k = 0; k < 2; ++k) dst[n][k] = *(const LAS bf16x8*)(lds + G_SB(b, h) + boff + n * 2048 + k * 1024); } while (0)
; #define G_MMA(ai, bj, At_, Bt_) do { __builtin_amdgcn_s_setprio(1); _Pragma("unroll") for (int m = 0; m < 4; ++m) _Pragma("unroll") for (int n = 0; n < 2; ++n) _Pragma("unroll") for (int k = 0; k < 2; ++k) \
;         acc[ai][bj][m][n] = __builtin_amdgcn_mfma_f32_16x16x32_bf16(Bt_[n][k], At_[m][k], acc[ai][bj][m][n], 0, 0, 0); __builtin_amdgcn_s_setprio(0); } while (0)
; #define WAIT_V(n) asm volatile("s_waitcnt vmcnt(" #n ")" ::: "memory")
; #define WAIT_L(n) asm volatile("s_waitcnt lgkmcnt(" #n ")" ::: "memory")
; #define BAR __builtin_amdgcn_s_barrier()
; #define SCHED __builtin_amdgcn_sched_barrier(0)
; template <class Get, class Epi>
; DI void gemm_loop(int ntiles, int ld, char* shm, const Get& get, const Epi& epi) {
;     ...
;             G_LDA(At, 0, 1); G_STAGE(G_SB(0, 0), b2, voffB); G_STAGE(G_SB(0, 1), b2 + hstep, voffB); G_STAGE(G_SA(0, 0), a2, voffA);
;             WAIT_V(8); WAIT_L(0); BAR; G_MMA(1, 0, At, B0); G_MMA(1, 1, At, B1); BAR; SCHED;
;             G_LDB(B0, 1, 0); G_LDB(B1, 1, 1); SCHED; G_LDA(At, 1, 0); G_STAGE(G_SA(0, 1), a2 + hstep, voffA);
;             WAIT_V(8); WAIT_L(0); BAR; G_MMA(0, 0, At, B0); G_MMA(0, 1, At, B1); BAR; SCHED;
;             G_LDA(At, 1, 1); G_STAGE(G_SB(1, 0), b3, voffB); G_STAGE(G_SB(1, 1), b3 + hstep, voffB); G_STAGE(G_SA(1, 0), a3, voffA);
	s_setprio 1
	s_waitcnt lgkmcnt(0)
	v_mfma_f32_16x16x32_bf16 v[92:95], v[128:131], v[180:183], 0
	v_mfma_f32_16x16x32_bf16 v[88:91], v[136:139], v[180:183], 0
	v_mfma_f32_16x16x32_bf16 v[84:87], v[128:131], v[188:191], 0
	v_mfma_f32_16x16x32_bf16 v[80:83], v[136:139], v[188:191], 0
	v_mfma_f32_16x16x32_bf16 v[76:79], v[128:131], v[196:199], 0
	v_mfma_f32_16x16x32_bf16 v[72:75], v[136:139], v[196:199], 0
	v_mfma_f32_16x16x32_bf16 v[68:71], v[128:131], v[204:207], 0
	v_mfma_f32_16x16x32_bf16 v[64:67], v[136:139], v[204:207], 0
	v_mfma_f32_16x16x32_bf16 v[92:95], v[132:135], v[184:187], v[92:95]
	v_mfma_f32_16x16x32_bf16 v[88:91], v[140:143], v[184:187], v[88:91]
	v_mfma_f32_16x16x32_bf16 v[84:87], v[132:135], v[192:195], v[84:87]
	v_mfma_f32_16x16x32_bf16 v[80:83], v[140:143], v[192:195], v[80:83]
	v_mfma_f32_16x16x32_bf16 v[76:79], v[132:135], v[200:203], v[76:79]
	v_mfma_f32_16x16x32_bf16 v[72:75], v[140:143], v[200:203], v[72:75]
	v_mfma_f32_16x16x32_bf16 v[68:71], v[132:135], v[208:211], v[68:71]
	v_mfma_f32_16x16x32_bf16 v[64:67], v[140:143], v[208:211], v[64:67]
	s_setprio 0
	s_setprio 1
	v_mfma_f32_16x16x32_bf16 v[28:31], v[158:161], v[180:183], 0
	v_mfma_f32_16x16x32_bf16 v[24:27], v[172:175], v[180:183], 0
	v_mfma_f32_16x16x32_bf16 v[20:23], v[158:161], v[188:191], 0
	v_mfma_f32_16x16x32_bf16 v[16:19], v[172:175], v[188:191], 0
	v_mfma_f32_16x16x32_bf16 v[12:15], v[158:161], v[196:199], 0
	v_mfma_f32_16x16x32_bf16 v[8:11], v[172:175], v[196:199], 0
	v_mfma_f32_16x16x32_bf16 v[4:7], v[158:161], v[204:207], 0
	v_mfma_f32_16x16x32_bf16 v[0:3], v[172:175], v[204:207], 0
	v_mfma_f32_16x16x32_bf16 v[28:31], v[162:165], v[184:187], v[28:31]
	v_mfma_f32_16x16x32_bf16 v[24:27], v[176:179], v[184:187], v[24:27]
	v_mfma_f32_16x16x32_bf16 v[20:23], v[162:165], v[192:195], v[20:23]
	v_mfma_f32_16x16x32_bf16 v[16:19], v[176:179], v[192:195], v[16:19]
	v_mfma_f32_16x16x32_bf16 v[12:15], v[162:165], v[200:203], v[12:15]
	v_mfma_f32_16x16x32_bf16 v[8:11], v[176:179], v[200:203], v[8:11]
	v_mfma_f32_16x16x32_bf16 v[4:7], v[162:165], v[208:211], v[4:7]
	v_mfma_f32_16x16x32_bf16 v[0:3], v[176:179], v[208:211], v[0:3]
	s_setprio 0
	s_add_i32 s72, 0, 0x18000
	s_add_i32 s73, 0, 0x1c000
	v_add_u32_e32 v140, s72, v168
	s_barrier
	v_add_u32_e32 v176, s73, v168
	ds_read_b128 v[128:131], v140
	ds_read_b128 v[132:135], v140 offset:1024
	ds_read_b128 v[136:139], v140 offset:2048
	ds_read_b128 v[140:143], v140 offset:3072
	ds_read_b128 v[158:161], v176
	ds_read_b128 v[162:165], v176 offset:1024
	ds_read_b128 v[172:175], v176 offset:2048
	ds_read_b128 v[176:179], v176 offset:3072
	s_add_u32 s46, s46, 0x40000
	s_addc_u32 s47, s47, 0
	s_mov_b32 m0, s50
	v_lshl_add_u64 v[216:217], s[46:47], 0, v[146:147]
	ds_read_b128 v[180:183], v171 offset:32768
	ds_read_b128 v[184:187], v171 offset:33792
	ds_read_b128 v[188:191], v171 offset:34816
	ds_read_b128 v[192:195], v171 offset:35840
	ds_read_b128 v[196:199], v171 offset:36864
	ds_read_b128 v[200:203], v171 offset:37888
	ds_read_b128 v[204:207], v171 offset:38912
	ds_read_b128 v[208:211], v171 offset:39936
	global_load_lds_dwordx4 v[216:217], off
	v_lshl_add_u64 v[216:217], s[46:47], 0, v[150:151]
	s_mov_b32 m0, s51
	s_nop 0
	global_load_lds_dwordx4 v[216:217], off
	s_waitcnt vmcnt(8)
	s_waitcnt lgkmcnt(0)
	s_barrier
	s_setprio 1
	s_waitcnt lgkmcnt(0)
	v_mfma_f32_16x16x32_bf16 v[124:127], v[128:131], v[180:183], v[124:127]
	v_mfma_f32_16x16x32_bf16 v[120:123], v[136:139], v[180:183], v[120:123]
	v_mfma_f32_16x16x32_bf16 v[116:119], v[128:131], v[188:191], v[116:119]
	v_mfma_f32_16x16x32_bf16 v[112:115], v[136:139], v[188:191], v[112:115]
	v_mfma_f32_16x16x32_bf16 v[108:111], v[128:131], v[196:199], v[108:111]
	v_mfma_f32_16x16x32_bf16 v[104:107], v[136:139], v[196:199], v[104:107]
	v_mfma_f32_16x16x32_bf16 v[100:103], v[128:131], v[204:207], v[100:103]
	v_mfma_f32_16x16x32_bf16 v[96:99], v[136:139], v[204:207], v[96:99]
	v_mfma_f32_16x16x32_bf16 v[124:127], v[132:135], v[184:187], v[124:127]
	v_mfma_f32_16x16x32_bf16 v[120:123], v[140:143], v[184:187], v[120:123]
	v_mfma_f32_16x16x32_bf16 v[116:119], v[132:135], v[192:195], v[116:119]
	v_mfma_f32_16x16x32_bf16 v[112:115], v[140:143], v[192:195], v[112:115]
	v_mfma_f32_16x16x32_bf16 v[108:111], v[132:135], v[200:203], v[108:111]
	v_mfma_f32_16x16x32_bf16 v[104:107], v[140:143], v[200:203], v[104:107]
	v_mfma_f32_16x16x32_bf16 v[100:103], v[132:135], v[208:211], v[100:103]
	v_mfma_f32_16x16x32_bf16 v[96:99], v[140:143], v[208:211], v[96:99]
	s_setprio 0
	s_setprio 1
	v_mfma_f32_16x16x32_bf16 v[60:63], v[158:161], v[180:183], v[60:63]
	v_mfma_f32_16x16x32_bf16 v[56:59], v[172:175], v[180:183], v[56:59]
	v_mfma_f32_16x16x32_bf16 v[52:55], v[158:161], v[188:191], v[52:55]
	v_mfma_f32_16x16x32_bf16 v[48:51], v[172:175], v[188:191], v[48:51]
	v_mfma_f32_16x16x32_bf16 v[44:47], v[158:161], v[196:199], v[44:47]
	v_mfma_f32_16x16x32_bf16 v[40:43], v[172:175], v[196:199], v[40:43]
	v_mfma_f32_16x16x32_bf16 v[36:39], v[158:161], v[204:207], v[36:39]
	v_mfma_f32_16x16x32_bf16 v[32:35], v[172:175], v[204:207], v[32:35]
	v_mfma_f32_16x16x32_bf16 v[60:63], v[162:165], v[184:187], v[60:63]
	v_mfma_f32_16x16x32_bf16 v[56:59], v[176:179], v[184:187], v[56:59]
	v_mfma_f32_16x16x32_bf16 v[52:55], v[162:165], v[192:195], v[52:55]
	v_mfma_f32_16x16x32_bf16 v[48:51], v[176:179], v[192:195], v[48:51]
	v_mfma_f32_16x16x32_bf16 v[44:47], v[162:165], v[200:203], v[44:47]
	v_mfma_f32_16x16x32_bf16 v[40:43], v[176:179], v[200:203], v[40:43]
	v_mfma_f32_16x16x32_bf16 v[36:39], v[162:165], v[208:211], v[36:39]
	v_mfma_f32_16x16x32_bf16 v[32:35], v[176:179], v[208:211], v[32:35]
	s_setprio 0
	s_add_i32 s46, s72, s48
	v_lshl_add_u64 v[144:145], v[144:145], 0, s[4:5]
	s_mov_b32 m0, s46
	s_barrier
; #define G_STAGE(bufoff, gbase, voff) do { _Pragma("unroll") for (int _i = 0; _i < 2; ++_i) \
;         __builtin_amdgcn_global_load_lds((const unsigned*)((const char*)(gbase) + voff[_i]), (LAS unsigned*)(lds + (bufoff) + ldsw + _i * 8192), 16, 0, 0); } while (0)
; #define G_LDA(dst, b, h) do { _Pragma("unroll") for (int m = 0; m < 4; ++m) _Pragma("unroll") for (int k = 0; k < 2; ++k) dst[m][k] = *(const LAS bf16x8*)(lds + G_SA(b, h) + aoff + m * 2048 + k * 1024); } while (0)
; #define G_LDB(dst, b, h) do { _Pragma("unroll") for (int n = 0; n < 2; ++n) _Pragma("unroll") for (int k = 0; k < 2; ++k) dst[n][k] = *(const LAS bf16x8*)(lds + G_SB(b, h) + boff + n * 2048 + k * 1024); } while (0)
; #define G_MMA(ai, bj, At_, Bt_) do { __builtin_amdgcn_s_setprio(1); _Pragma("unroll") for (int m = 0; m < 4; ++m) _Pragma("unroll") for (int n = 0; n < 2; ++n) _Pragma("unroll") for (int k = 0; k < 2; ++k) \
;         acc[ai][bj][m][n] = __builtin_amdgcn_mfma_f32_16x16x32_bf16(Bt_[n][k], At_[m][k], acc[ai][bj][m][n], 0, 0, 0); __builtin_amdgcn_s_setprio(0); } while (0)
; #define WAIT_V(n) asm volatile("s_waitcnt vmcnt(" #n ")" ::: "memory")
; #define WAIT_L(n) asm volatile("s_waitcnt lgkmcnt(" #n ")" ::: "memory")
; #define BAR __builtin_amdgcn_s_barrier()
; #define SCHED __builtin_amdgcn_sched_barrier(0)
; template <class Get, class Epi>
; DI void gemm_loop(int ntiles, int ld, char* shm, const Get& get, const Epi& epi) {
;     ...
;         for (int t = 0; t < nt; t += 2) {
;             const bool last = (t == nt - 2);
;             const char* a1 = cA + (size_t)(t + 1) * kstep;
;             const char* a2 = last ? nA : cA + (size_t)(t + 2) * kstep; const char* b2 = last ? nB : cB + (size_t)(t + 2) * kstep;
;             const char* a3 = a2 + kstep; const char* b3 = b2 + kstep;
;             G_LDB(B0, 0, 0); G_LDB(B1, 0, 1); SCHED; G_LDA(At, 0, 0); G_STAGE(G_SA(1, 1), a1 + hstep, voffA);
;             WAIT_V(8); WAIT_L(0); BAR; G_MMA(0, 0, At, B0); G_MMA(0, 1, At, B1); BAR; SCHED;
;     ...
;             G_LDA(At, 1, 1); G_STAGE(G_SB(1, 0), b3, voffB); G_STAGE(G_SB(1, 1), b3 + hstep, voffB); G_STAGE(G_SA(1, 0), a3, voffA);
;             WAIT_V(8); WAIT_L(0); BAR; G_MMA(1, 0, At, B0); G_MMA(1, 1, At, B1); BAR; SCHED;
;         }
	ds_read_b128 v[180:183], v171 offset:49152
	ds_read_b128 v[184:187], v171 offset:50176
	ds_read_b128 v[188:191], v171 offset:51200
	ds_read_b128 v[192:195], v171 offset:52224
	ds_read_b128 v[196:199], v171 offset:53248
	ds_read_b128 v[200:203], v171 offset:54272
	ds_read_b128 v[204:207], v171 offset:55296
	ds_read_b128 v[208:211], v171 offset:56320
	global_load_lds_dwordx4 v[144:145], off
	s_add_i32 m0, s46, 0x2000
	s_add_u32 s14, s14, 0x40080
	v_lshl_add_u64 v[144:145], v[166:167], 0, s[4:5]
	s_addc_u32 s15, s15, 0
	s_add_i32 s46, s73, s48
	global_load_lds_dwordx4 v[144:145], off
	v_lshl_add_u64 v[144:145], s[14:15], 0, v[148:149]
	s_mov_b32 m0, s46
	s_nop 0
	global_load_lds_dwordx4 v[144:145], off
	v_lshl_add_u64 v[144:145], s[14:15], 0, v[152:153]
	s_add_i32 m0, s46, 0x2000
	s_nop 0
	global_load_lds_dwordx4 v[144:145], off
	v_lshl_add_u64 v[144:145], v[212:213], 0, s[4:5]
	s_mov_b32 m0, s54
	s_nop 0
	global_load_lds_dwordx4 v[144:145], off
	v_lshl_add_u64 v[144:145], v[214:215], 0, s[4:5]
	s_mov_b32 m0, s55
	s_nop 0
	global_load_lds_dwordx4 v[144:145], off
	s_waitcnt vmcnt(8)
	s_waitcnt lgkmcnt(0)
	s_barrier
	s_setprio 1
	s_waitcnt lgkmcnt(0)
	v_mfma_f32_16x16x32_bf16 v[92:95], v[128:131], v[180:183], v[92:95]
	v_mfma_f32_16x16x32_bf16 v[88:91], v[136:139], v[180:183], v[88:91]
	v_mfma_f32_16x16x32_bf16 v[84:87], v[128:131], v[188:191], v[84:87]
	v_mfma_f32_16x16x32_bf16 v[80:83], v[136:139], v[188:191], v[80:83]
	v_mfma_f32_16x16x32_bf16 v[76:79], v[128:131], v[196:199], v[76:79]
	v_mfma_f32_16x16x32_bf16 v[72:75], v[136:139], v[196:199], v[72:75]
	v_mfma_f32_16x16x32_bf16 v[68:71], v[128:131], v[204:207], v[68:71]
	v_mfma_f32_16x16x32_bf16 v[64:67], v[136:139], v[204:207], v[64:67]
	v_mfma_f32_16x16x32_bf16 v[92:95], v[132:135], v[184:187], v[92:95]
	v_mfma_f32_16x16x32_bf16 v[88:91], v[140:143], v[184:187], v[88:91]
	v_mfma_f32_16x16x32_bf16 v[84:87], v[132:135], v[192:195], v[84:87]
	v_mfma_f32_16x16x32_bf16 v[80:83], v[140:143], v[192:195], v[80:83]
	v_mfma_f32_16x16x32_bf16 v[76:79], v[132:135], v[200:203], v[76:79]
	v_mfma_f32_16x16x32_bf16 v[72:75], v[140:143], v[200:203], v[72:75]
	v_mfma_f32_16x16x32_bf16 v[68:71], v[132:135], v[208:211], v[68:71]
	v_mfma_f32_16x16x32_bf16 v[64:67], v[140:143], v[208:211], v[64:67]
	s_setprio 0
	s_setprio 1
	v_mfma_f32_16x16x32_bf16 v[28:31], v[158:161], v[180:183], v[28:31]
	v_mfma_f32_16x16x32_bf16 v[24:27], v[172:175], v[180:183], v[24:27]
	v_mfma_f32_16x16x32_bf16 v[20:23], v[158:161], v[188:191], v[20:23]
	v_mfma_f32_16x16x32_bf16 v[16:19], v[172:175], v[188:191], v[16:19]
	v_mfma_f32_16x16x32_bf16 v[12:15], v[158:161], v[196:199], v[12:15]
	v_mfma_f32_16x16x32_bf16 v[8:11], v[172:175], v[196:199], v[8:11]
	v_mfma_f32_16x16x32_bf16 v[4:7], v[158:161], v[204:207], v[4:7]
	v_mfma_f32_16x16x32_bf16 v[0:3], v[172:175], v[204:207], v[0:3]
	v_mfma_f32_16x16x32_bf16 v[28:31], v[162:165], v[184:187], v[28:31]
	v_mfma_f32_16x16x32_bf16 v[24:27], v[176:179], v[184:187], v[24:27]
	v_mfma_f32_16x16x32_bf16 v[20:23], v[162:165], v[192:195], v[20:23]
	v_mfma_f32_16x16x32_bf16 v[16:19], v[176:179], v[192:195], v[16:19]
	v_mfma_f32_16x16x32_bf16 v[12:15], v[162:165], v[200:203], v[12:15]
	v_mfma_f32_16x16x32_bf16 v[8:11], v[176:179], v[200:203], v[8:11]
	v_mfma_f32_16x16x32_bf16 v[4:7], v[162:165], v[208:211], v[4:7]
	v_mfma_f32_16x16x32_bf16 v[0:3], v[176:179], v[208:211], v[0:3]
	s_setprio 0
	s_add_i32 s71, s71, 2
	s_add_u32 s44, s44, 0x100
	s_addc_u32 s45, s45, 0
	s_add_u32 s65, s65, 0x100
	s_addc_u32 s70, s70, 0
	s_cmp_gt_u32 s71, 13
	s_barrier
	s_cbranch_scc0 .LBB0_3466
	s_branch .Lpost_3466
.LBB0_3466:
	ds_read_b128 v[128:131], v169
	ds_read_b128 v[132:135], v169 offset:1024
	ds_read_b128 v[136:139], v169 offset:2048
	ds_read_b128 v[140:143], v169 offset:3072
	ds_read_b128 v[158:161], v170
	ds_read_b128 v[162:165], v170 offset:1024
	ds_read_b128 v[172:175], v170 offset:2048
	ds_read_b128 v[176:179], v170 offset:3072
	s_add_u32 s14, s44, 0xfffc0080
	s_addc_u32 s15, s45, -1
	s_cmp_eq_u32 s71, 12
	s_cselect_b32 s47, s3, s15
	s_cselect_b32 s46, s35, s14
	s_cselect_b32 s15, s37, s70
	s_cselect_b32 s14, s64, s65
	v_lshl_add_u64 v[144:145], s[44:45], 0, v[154:155]
	s_add_i32 m0, s43, 0xc000
	ds_read_b128 v[180:183], v171
	ds_read_b128 v[184:187], v171 offset:1024
	ds_read_b128 v[188:191], v171 offset:2048
	ds_read_b128 v[192:195], v171 offset:3072
	ds_read_b128 v[196:199], v171 offset:4096
	ds_read_b128 v[200:203], v171 offset:5120
	ds_read_b128 v[204:207], v171 offset:6144
	ds_read_b128 v[208:211], v171 offset:7168
	global_load_lds_dwordx4 v[144:145], off
	v_lshl_add_u64 v[144:145], s[44:45], 0, v[156:157]
	s_add_i32 m0, s43, 0xe000
	s_nop 0
	global_load_lds_dwordx4 v[144:145], off
	s_waitcnt vmcnt(8)
	s_waitcnt lgkmcnt(0)
	s_barrier
; #define G_STAGE(bufoff, gbase, voff) do { _Pragma("unroll") for (int _i = 0; _i < 2; ++_i) \
;         __builtin_amdgcn_global_load_lds((const unsigned*)((const char*)(gbase) + voff[_i]), (LAS unsigned*)(lds + (bufoff) + ldsw + _i * 8192), 16, 0, 0); } while (0)
; #define G_LDA(dst, b, h) do { _Pragma("unroll") for (int m = 0; m < 4; ++m) _Pragma("unroll") for (int k = 0; k < 2; ++k) dst[m][k] = *(const LAS bf16x8*)(lds + G_SA(b, h) + aoff + m * 2048 + k * 1024); } while (0)
; #define G_LDB(dst, b, h) do { _Pragma("unroll") for (int n = 0; n < 2; ++n) _Pragma("unroll") for (int k = 0; k < 2; ++k) dst[n][k] = *(const LAS bf16x8*)(lds + G_SB(b, h) + boff + n * 2048 + k * 1024); } while (0)
; #define G_MMA(ai, bj, At_, Bt_) do { __builtin_amdgcn_s_setprio(1); _Pragma("unroll") for (int m = 0; m < 4; ++m) _Pragma("unroll") for (int n = 0; n < 2; ++n) _Pragma("unroll") for (int k = 0; k < 2; ++k) \
;         acc[ai][bj][m][n] = __builtin_amdgcn_mfma_f32_16x16x32_bf16(Bt_[n][k], At_[m][k], acc[ai][bj][m][n], 0, 0, 0); __builtin_amdgcn_s_setprio(0); } while (0)
; #define WAIT_V(n) asm volatile("s_waitcnt vmcnt(" #n ")" ::: "memory")
; #define WAIT_L(n) asm volatile("s_waitcnt lgkmcnt(" #n ")" ::: "memory")
; #define BAR __builtin_amdgcn_s_barrier()
; #define SCHED __builtin_amdgcn_sched_barrier(0)
; template <class Get, class Epi>
; DI void gemm_loop(int ntiles, int ld, char* shm, const Get& get, const Epi& epi) {
;     ...
;             G_LDB(B0, 0, 0); G_LDB(B1, 0, 1); SCHED; G_LDA(At, 0, 0); G_STAGE(G_SA(1, 1), a1 + hstep, voffA);
;             WAIT_V(8); WAIT_L(0); BAR; G_MMA(0, 0, At, B0); G_MMA(0, 1, At, B1); BAR; SCHED;
;             G_LDA(At, 0, 1); G_STAGE(G_SB(0, 0), b2, voffB); G_STAGE(G_SB(0, 1), b2 + hstep, voffB); G_STAGE(G_SA(0, 0), a2, voffA);
;             WAIT_V(8); WAIT_L(0); BAR; G_MMA(1, 0, At, B0); G_MMA(1, 1, At, B1); BAR; SCHED;
;             G_LDB(B0, 1, 0); G_LDB(B1, 1, 1); SCHED; G_LDA(At, 1, 0); G_STAGE(G_SA(0, 1), a2 + hstep, voffA);
;             WAIT_V(8); WAIT_L(0); BAR; G_MMA(0, 0, At, B0); G_MMA(0, 1, At, B1); BAR; SCHED;
	s_setprio 1
	s_waitcnt lgkmcnt(0)
	v_mfma_f32_16x16x32_bf16 v[124:127], v[128:131], v[180:183], v[124:127]
	v_mfma_f32_16x16x32_bf16 v[120:123], v[136:139], v[180:183], v[120:123]
	v_mfma_f32_16x16x32_bf16 v[116:119], v[128:131], v[188:191], v[116:119]
	v_mfma_f32_16x16x32_bf16 v[112:115], v[136:139], v[188:191], v[112:115]
	v_mfma_f32_16x16x32_bf16 v[108:111], v[128:131], v[196:199], v[108:111]
	v_mfma_f32_16x16x32_bf16 v[104:107], v[136:139], v[196:199], v[104:107]
	v_mfma_f32_16x16x32_bf16 v[100:103], v[128:131], v[204:207], v[100:103]
	v_mfma_f32_16x16x32_bf16 v[96:99], v[136:139], v[204:207], v[96:99]
	v_mfma_f32_16x16x32_bf16 v[124:127], v[132:135], v[184:187], v[124:127]
	v_mfma_f32_16x16x32_bf16 v[120:123], v[140:143], v[184:187], v[120:123]
	v_mfma_f32_16x16x32_bf16 v[116:119], v[132:135], v[192:195], v[116:119]
	v_mfma_f32_16x16x32_bf16 v[112:115], v[140:143], v[192:195], v[112:115]
	v_mfma_f32_16x16x32_bf16 v[108:111], v[132:135], v[200:203], v[108:111]
	v_mfma_f32_16x16x32_bf16 v[104:107], v[140:143], v[200:203], v[104:107]
	v_mfma_f32_16x16x32_bf16 v[100:103], v[132:135], v[208:211], v[100:103]
	v_mfma_f32_16x16x32_bf16 v[96:99], v[140:143], v[208:211], v[96:99]
	s_setprio 0
	s_setprio 1
	v_mfma_f32_16x16x32_bf16 v[60:63], v[158:161], v[180:183], v[60:63]
	v_mfma_f32_16x16x32_bf16 v[56:59], v[172:175], v[180:183], v[56:59]
	v_mfma_f32_16x16x32_bf16 v[52:55], v[158:161], v[188:191], v[52:55]
	v_mfma_f32_16x16x32_bf16 v[48:51], v[172:175], v[188:191], v[48:51]
	v_mfma_f32_16x16x32_bf16 v[44:47], v[158:161], v[196:199], v[44:47]
	v_mfma_f32_16x16x32_bf16 v[40:43], v[172:175], v[196:199], v[40:43]
	v_mfma_f32_16x16x32_bf16 v[36:39], v[158:161], v[204:207], v[36:39]
	v_mfma_f32_16x16x32_bf16 v[32:35], v[172:175], v[204:207], v[32:35]
	v_mfma_f32_16x16x32_bf16 v[60:63], v[162:165], v[184:187], v[60:63]
	v_mfma_f32_16x16x32_bf16 v[56:59], v[176:179], v[184:187], v[56:59]
	v_mfma_f32_16x16x32_bf16 v[52:55], v[162:165], v[192:195], v[52:55]
	v_mfma_f32_16x16x32_bf16 v[48:51], v[176:179], v[192:195], v[48:51]
	v_mfma_f32_16x16x32_bf16 v[44:47], v[162:165], v[200:203], v[44:47]
	v_mfma_f32_16x16x32_bf16 v[40:43], v[176:179], v[200:203], v[40:43]
	v_mfma_f32_16x16x32_bf16 v[36:39], v[162:165], v[208:211], v[36:39]
	v_mfma_f32_16x16x32_bf16 v[32:35], v[176:179], v[208:211], v[32:35]
	s_setprio 0
	s_add_i32 s72, s56, s48
	v_lshl_add_u64 v[144:145], s[14:15], 0, v[148:149]
	s_mov_b32 m0, s72
	s_barrier
	ds_read_b128 v[180:183], v171 offset:16384
	ds_read_b128 v[184:187], v171 offset:17408
	ds_read_b128 v[188:191], v171 offset:18432
	ds_read_b128 v[192:195], v171 offset:19456
	ds_read_b128 v[196:199], v171 offset:20480
	ds_read_b128 v[200:203], v171 offset:21504
	ds_read_b128 v[204:207], v171 offset:22528
	ds_read_b128 v[208:211], v171 offset:23552
	global_load_lds_dwordx4 v[144:145], off
	s_add_i32 m0, s72, 0x2000
	s_add_u32 s72, s14, 0x40000
	v_lshl_add_u64 v[166:167], s[14:15], 0, v[152:153]
	s_addc_u32 s73, s15, 0
	s_add_i32 s74, s57, s48
	global_load_lds_dwordx4 v[166:167], off
	v_lshl_add_u64 v[212:213], s[72:73], 0, v[148:149]
	s_mov_b32 m0, s74
	v_lshl_add_u64 v[214:215], s[46:47], 0, v[150:151]
	global_load_lds_dwordx4 v[212:213], off
	v_lshl_add_u64 v[212:213], s[72:73], 0, v[152:153]
	s_add_i32 m0, s74, 0x2000
	s_nop 0
	global_load_lds_dwordx4 v[212:213], off
	v_lshl_add_u64 v[212:213], s[46:47], 0, v[146:147]
	s_mov_b32 m0, s43
	s_nop 0
	global_load_lds_dwordx4 v[212:213], off
	s_mov_b32 m0, s49
	s_nop 0
	global_load_lds_dwordx4 v[214:215], off
	s_waitcnt vmcnt(8)
	s_waitcnt lgkmcnt(0)
	s_barrier
	s_setprio 1
	s_waitcnt lgkmcnt(0)
	v_mfma_f32_16x16x32_bf16 v[92:95], v[128:131], v[180:183], v[92:95]
	v_mfma_f32_16x16x32_bf16 v[88:91], v[136:139], v[180:183], v[88:91]
	v_mfma_f32_16x16x32_bf16 v[84:87], v[128:131], v[188:191], v[84:87]
	v_mfma_f32_16x16x32_bf16 v[80:83], v[136:139], v[188:191], v[80:83]
	v_mfma_f32_16x16x32_bf16 v[76:79], v[128:131], v[196:199], v[76:79]
	v_mfma_f32_16x16x32_bf16 v[72:75], v[136:139], v[196:199], v[72:75]
	v_mfma_f32_16x16x32_bf16 v[68:71], v[128:131], v[204:207], v[68:71]
	v_mfma_f32_16x16x32_bf16 v[64:67], v[136:139], v[204:207], v[64:67]
	v_mfma_f32_16x16x32_bf16 v[92:95], v[132:135], v[184:187], v[92:95]
	v_mfma_f32_16x16x32_bf16 v[88:91], v[140:143], v[184:187], v[88:91]
	v_mfma_f32_16x16x32_bf16 v[84:87], v[132:135], v[192:195], v[84:87]
	v_mfma_f32_16x16x32_bf16 v[80:83], v[140:143], v[192:195], v[80:83]
	v_mfma_f32_16x16x32_bf16 v[76:79], v[132:135], v[200:203], v[76:79]
	v_mfma_f32_16x16x32_bf16 v[72:75], v[140:143], v[200:203], v[72:75]
	v_mfma_f32_16x16x32_bf16 v[68:71], v[132:135], v[208:211], v[68:71]
	v_mfma_f32_16x16x32_bf16 v[64:67], v[140:143], v[208:211], v[64:67]
	s_setprio 0
	s_setprio 1
	v_mfma_f32_16x16x32_bf16 v[28:31], v[158:161], v[180:183], v[28:31]
	v_mfma_f32_16x16x32_bf16 v[24:27], v[172:175], v[180:183], v[24:27]
	v_mfma_f32_16x16x32_bf16 v[20:23], v[158:161], v[188:191], v[20:23]
	v_mfma_f32_16x16x32_bf16 v[16:19], v[172:175], v[188:191], v[16:19]
	v_mfma_f32_16x16x32_bf16 v[12:15], v[158:161], v[196:199], v[12:15]
	v_mfma_f32_16x16x32_bf16 v[8:11], v[172:175], v[196:199], v[8:11]
	v_mfma_f32_16x16x32_bf16 v[4:7], v[158:161], v[204:207], v[4:7]
	v_mfma_f32_16x16x32_bf16 v[0:3], v[172:175], v[204:207], v[0:3]
	v_mfma_f32_16x16x32_bf16 v[28:31], v[162:165], v[184:187], v[28:31]
	v_mfma_f32_16x16x32_bf16 v[24:27], v[176:179], v[184:187], v[24:27]
	v_mfma_f32_16x16x32_bf16 v[20:23], v[162:165], v[192:195], v[20:23]
	v_mfma_f32_16x16x32_bf16 v[16:19], v[176:179], v[192:195], v[16:19]
	v_mfma_f32_16x16x32_bf16 v[12:15], v[162:165], v[200:203], v[12:15]
	v_mfma_f32_16x16x32_bf16 v[8:11], v[176:179], v[200:203], v[8:11]
	v_mfma_f32_16x16x32_bf16 v[4:7], v[162:165], v[208:211], v[4:7]
	v_mfma_f32_16x16x32_bf16 v[0:3], v[176:179], v[208:211], v[0:3]
	s_setprio 0
	s_add_i32 s72, 0, 0x18000
	s_add_i32 s73, 0, 0x1c000
	v_add_u32_e32 v140, s72, v168
	s_barrier
; #define G_STAGE(bufoff, gbase, voff) do { _Pragma("unroll") for (int _i = 0; _i < 2; ++_i) \
;         __builtin_amdgcn_global_load_lds((const unsigned*)((const char*)(gbase) + voff[_i]), (LAS unsigned*)(lds + (bufoff) + ldsw + _i * 8192), 16, 0, 0); } while (0)
; #define G_LDA(dst, b, h) do { _Pragma("unroll") for (int m = 0; m < 4; ++m) _Pragma("unroll") for (int k = 0; k < 2; ++k) dst[m][k] = *(const LAS bf16x8*)(lds + G_SA(b, h) + aoff + m * 2048 + k * 1024); } while (0)
; #define G_LDB(dst, b, h) do { _Pragma("unroll") for (int n = 0; n < 2; ++n) _Pragma("unroll") for (int k = 0; k < 2; ++k) dst[n][k] = *(const LAS bf16x8*)(lds + G_SB(b, h) + boff + n * 2048 + k * 1024); } while (0)
; #define G_MMA(ai, bj, At_, Bt_) do { __builtin_amdgcn_s_setprio(1); _Pragma("unroll") for (int m = 0; m < 4; ++m) _Pragma("unroll") for (int n = 0; n < 2; ++n) _Pragma("unroll") for (int k = 0; k < 2; ++k) \
;         acc[ai][bj][m][n] = __builtin_amdgcn_mfma_f32_16x16x32_bf16(Bt_[n][k], At_[m][k], acc[ai][bj][m][n], 0, 0, 0); __builtin_amdgcn_s_setprio(0); } while (0)
; #define WAIT_V(n) asm volatile("s_waitcnt vmcnt(" #n ")" ::: "memory")
; #define WAIT_L(n) asm volatile("s_waitcnt lgkmcnt(" #n ")" ::: "memory")
; #define BAR __builtin_amdgcn_s_barrier()
; #define SCHED __builtin_amdgcn_sched_barrier(0)
; template <class Get, class Epi>
; DI void gemm_loop(int ntiles, int ld, char* shm, const Get& get, const Epi& epi) {
;     ...
;             G_LDB(B0, 1, 0); G_LDB(B1, 1, 1); SCHED; G_LDA(At, 1, 0); G_STAGE(G_SA(0, 1), a2 + hstep, voffA);
;             WAIT_V(8); WAIT_L(0); BAR; G_MMA(0, 0, At, B0); G_MMA(0, 1, At, B1); BAR; SCHED;
	v_add_u32_e32 v176, s73, v168
	ds_read_b128 v[128:131], v140
	ds_read_b128 v[132:135], v140 offset:1024
	ds_read_b128 v[136:139], v140 offset:2048
	ds_read_b128 v[140:143], v140 offset:3072
	ds_read_b128 v[158:161], v176
	ds_read_b128 v[162:165], v176 offset:1024
	ds_read_b128 v[172:175], v176 offset:2048
	ds_read_b128 v[176:179], v176 offset:3072
	s_add_u32 s46, s46, 0x40000
	s_addc_u32 s47, s47, 0
	s_mov_b32 m0, s50
	v_lshl_add_u64 v[216:217], s[46:47], 0, v[146:147]
	ds_read_b128 v[180:183], v171 offset:32768
	ds_read_b128 v[184:187], v171 offset:33792
	ds_read_b128 v[188:191], v171 offset:34816
	ds_read_b128 v[192:195], v171 offset:35840
	ds_read_b128 v[196:199], v171 offset:36864
	ds_read_b128 v[200:203], v171 offset:37888
	ds_read_b128 v[204:207], v171 offset:38912
	ds_read_b128 v[208:211], v171 offset:39936
	global_load_lds_dwordx4 v[216:217], off
	v_lshl_add_u64 v[216:217], s[46:47], 0, v[150:151]
	s_mov_b32 m0, s51
	s_nop 0
	global_load_lds_dwordx4 v[216:217], off
	s_waitcnt vmcnt(8)
	s_waitcnt lgkmcnt(0)
	s_barrier
	s_setprio 1
	s_waitcnt lgkmcnt(0)
	v_mfma_f32_16x16x32_bf16 v[124:127], v[128:131], v[180:183], v[124:127]
	v_mfma_f32_16x16x32_bf16 v[120:123], v[136:139], v[180:183], v[120:123]
	v_mfma_f32_16x16x32_bf16 v[116:119], v[128:131], v[188:191], v[116:119]
	v_mfma_f32_16x16x32_bf16 v[112:115], v[136:139], v[188:191], v[112:115]
	v_mfma_f32_16x16x32_bf16 v[108:111], v[128:131], v[196:199], v[108:111]
	v_mfma_f32_16x16x32_bf16 v[104:107], v[136:139], v[196:199], v[104:107]
	v_mfma_f32_16x16x32_bf16 v[100:103], v[128:131], v[204:207], v[100:103]
	v_mfma_f32_16x16x32_bf16 v[96:99], v[136:139], v[204:207], v[96:99]
	v_mfma_f32_16x16x32_bf16 v[124:127], v[132:135], v[184:187], v[124:127]
	v_mfma_f32_16x16x32_bf16 v[120:123], v[140:143], v[184:187], v[120:123]
	v_mfma_f32_16x16x32_bf16 v[116:119], v[132:135], v[192:195], v[116:119]
	v_mfma_f32_16x16x32_bf16 v[112:115], v[140:143], v[192:195], v[112:115]
	v_mfma_f32_16x16x32_bf16 v[108:111], v[132:135], v[200:203], v[108:111]
	v_mfma_f32_16x16x32_bf16 v[104:107], v[140:143], v[200:203], v[104:107]
	v_mfma_f32_16x16x32_bf16 v[100:103], v[132:135], v[208:211], v[100:103]
	v_mfma_f32_16x16x32_bf16 v[96:99], v[140:143], v[208:211], v[96:99]
	s_setprio 0
	s_setprio 1
	v_mfma_f32_16x16x32_bf16 v[60:63], v[158:161], v[180:183], v[60:63]
	v_mfma_f32_16x16x32_bf16 v[56:59], v[172:175], v[180:183], v[56:59]
	v_mfma_f32_16x16x32_bf16 v[52:55], v[158:161], v[188:191], v[52:55]
	v_mfma_f32_16x16x32_bf16 v[48:51], v[172:175], v[188:191], v[48:51]
	v_mfma_f32_16x16x32_bf16 v[44:47], v[158:161], v[196:199], v[44:47]
	v_mfma_f32_16x16x32_bf16 v[40:43], v[172:175], v[196:199], v[40:43]
	v_mfma_f32_16x16x32_bf16 v[36:39], v[158:161], v[204:207], v[36:39]
	v_mfma_f32_16x16x32_bf16 v[32:35], v[172:175], v[204:207], v[32:35]
	v_mfma_f32_16x16x32_bf16 v[60:63], v[162:165], v[184:187], v[60:63]
	v_mfma_f32_16x16x32_bf16 v[56:59], v[176:179], v[184:187], v[56:59]
	v_mfma_f32_16x16x32_bf16 v[52:55], v[162:165], v[192:195], v[52:55]
	v_mfma_f32_16x16x32_bf16 v[48:51], v[176:179], v[192:195], v[48:51]
	v_mfma_f32_16x16x32_bf16 v[44:47], v[162:165], v[200:203], v[44:47]
	v_mfma_f32_16x16x32_bf16 v[40:43], v[176:179], v[200:203], v[40:43]
	v_mfma_f32_16x16x32_bf16 v[36:39], v[162:165], v[208:211], v[36:39]
	v_mfma_f32_16x16x32_bf16 v[32:35], v[176:179], v[208:211], v[32:35]
	s_setprio 0
	s_add_i32 s46, s72, s48
	v_lshl_add_u64 v[144:145], v[144:145], 0, s[4:5]
	s_mov_b32 m0, s46
	s_barrier
; #define G_STAGE(bufoff, gbase, voff) do { _Pragma("unroll") for (int _i = 0; _i < 2; ++_i) \
;         __builtin_amdgcn_global_load_lds((const unsigned*)((const char*)(gbase) + voff[_i]), (LAS unsigned*)(lds + (bufoff) + ldsw + _i * 8192), 16, 0, 0); } while (0)
; #define G_LDA(dst, b, h) do { _Pragma("unroll") for (int m = 0; m < 4; ++m) _Pragma("unroll") for (int k = 0; k < 2; ++k) dst[m][k] = *(const LAS bf16x8*)(lds + G_SA(b, h) + aoff + m * 2048 + k * 1024); } while (0)
; #define G_MMA(ai, bj, At_, Bt_) do { __builtin_amdgcn_s_setprio(1); _Pragma("unroll") for (int m = 0; m < 4; ++m) _Pragma("unroll") for (int n = 0; n < 2; ++n) _Pragma("unroll") for (int k = 0; k < 2; ++k) \
;         acc[ai][bj][m][n] = __builtin_amdgcn_mfma_f32_16x16x32_bf16(Bt_[n][k], At_[m][k], acc[ai][bj][m][n], 0, 0, 0); __builtin_amdgcn_s_setprio(0); } while (0)
; #define WAIT_V(n) asm volatile("s_waitcnt vmcnt(" #n ")" ::: "memory")
; #define WAIT_L(n) asm volatile("s_waitcnt lgkmcnt(" #n ")" ::: "memory")
; #define BAR __builtin_amdgcn_s_barrier()
; #define SCHED __builtin_amdgcn_sched_barrier(0)
; template <class Get, class Epi>
; DI void gemm_loop(int ntiles, int ld, char* shm, const Get& get, const Epi& epi) {
;     ...
;             G_LDA(At, 1, 1); G_STAGE(G_SB(1, 0), b3, voffB); G_STAGE(G_SB(1, 1), b3 + hstep, voffB); G_STAGE(G_SA(1, 0), a3, voffA);
;             WAIT_V(8); WAIT_L(0); BAR; G_MMA(1, 0, At, B0); G_MMA(1, 1, At, B1); BAR; SCHED;
;         }
	ds_read_b128 v[180:183], v171 offset:49152
	ds_read_b128 v[184:187], v171 offset:50176
	ds_read_b128 v[188:191], v171 offset:51200
	ds_read_b128 v[192:195], v171 offset:52224
	ds_read_b128 v[196:199], v171 offset:53248
	ds_read_b128 v[200:203], v171 offset:54272
	ds_read_b128 v[204:207], v171 offset:55296
	ds_read_b128 v[208:211], v171 offset:56320
	global_load_lds_dwordx4 v[144:145], off
	s_add_i32 m0, s46, 0x2000
	s_add_u32 s14, s14, 0x40080
	v_lshl_add_u64 v[144:145], v[166:167], 0, s[4:5]
	s_addc_u32 s15, s15, 0
	s_add_i32 s46, s73, s48
	global_load_lds_dwordx4 v[144:145], off
	v_lshl_add_u64 v[144:145], s[14:15], 0, v[148:149]
	s_mov_b32 m0, s46
	s_nop 0
	global_load_lds_dwordx4 v[144:145], off
	v_lshl_add_u64 v[144:145], s[14:15], 0, v[152:153]
	s_add_i32 m0, s46, 0x2000
	s_nop 0
	global_load_lds_dwordx4 v[144:145], off
	v_lshl_add_u64 v[144:145], v[212:213], 0, s[4:5]
	s_mov_b32 m0, s54
	s_nop 0
	global_load_lds_dwordx4 v[144:145], off
	v_lshl_add_u64 v[144:145], v[214:215], 0, s[4:5]
	s_mov_b32 m0, s55
	s_nop 0
	global_load_lds_dwordx4 v[144:145], off
	s_waitcnt vmcnt(8)
	s_waitcnt lgkmcnt(0)
	s_barrier
	s_setprio 1
	s_waitcnt lgkmcnt(0)
	v_mfma_f32_16x16x32_bf16 v[92:95], v[128:131], v[180:183], v[92:95]
	v_mfma_f32_16x16x32_bf16 v[88:91], v[136:139], v[180:183], v[88:91]
	v_mfma_f32_16x16x32_bf16 v[84:87], v[128:131], v[188:191], v[84:87]
	v_mfma_f32_16x16x32_bf16 v[80:83], v[136:139], v[188:191], v[80:83]
	v_mfma_f32_16x16x32_bf16 v[76:79], v[128:131], v[196:199], v[76:79]
	v_mfma_f32_16x16x32_bf16 v[72:75], v[136:139], v[196:199], v[72:75]
	v_mfma_f32_16x16x32_bf16 v[68:71], v[128:131], v[204:207], v[68:71]
	v_mfma_f32_16x16x32_bf16 v[64:67], v[136:139], v[204:207], v[64:67]
	v_mfma_f32_16x16x32_bf16 v[92:95], v[132:135], v[184:187], v[92:95]
	v_mfma_f32_16x16x32_bf16 v[88:91], v[140:143], v[184:187], v[88:91]
	v_mfma_f32_16x16x32_bf16 v[84:87], v[132:135], v[192:195], v[84:87]
	v_mfma_f32_16x16x32_bf16 v[80:83], v[140:143], v[192:195], v[80:83]
	v_mfma_f32_16x16x32_bf16 v[76:79], v[132:135], v[200:203], v[76:79]
	v_mfma_f32_16x16x32_bf16 v[72:75], v[140:143], v[200:203], v[72:75]
	v_mfma_f32_16x16x32_bf16 v[68:71], v[132:135], v[208:211], v[68:71]
	v_mfma_f32_16x16x32_bf16 v[64:67], v[140:143], v[208:211], v[64:67]
	s_setprio 0
	s_setprio 1
	v_mfma_f32_16x16x32_bf16 v[28:31], v[158:161], v[180:183], v[28:31]
	v_mfma_f32_16x16x32_bf16 v[24:27], v[172:175], v[180:183], v[24:27]
	v_mfma_f32_16x16x32_bf16 v[20:23], v[158:161], v[188:191], v[20:23]
	v_mfma_f32_16x16x32_bf16 v[16:19], v[172:175], v[188:191], v[16:19]
	v_mfma_f32_16x16x32_bf16 v[12:15], v[158:161], v[196:199], v[12:15]
	v_mfma_f32_16x16x32_bf16 v[8:11], v[172:175], v[196:199], v[8:11]
	v_mfma_f32_16x16x32_bf16 v[4:7], v[158:161], v[204:207], v[4:7]
	v_mfma_f32_16x16x32_bf16 v[0:3], v[172:175], v[204:207], v[0:3]
	v_mfma_f32_16x16x32_bf16 v[28:31], v[162:165], v[184:187], v[28:31]
	v_mfma_f32_16x16x32_bf16 v[24:27], v[176:179], v[184:187], v[24:27]
	v_mfma_f32_16x16x32_bf16 v[20:23], v[162:165], v[192:195], v[20:23]
	v_mfma_f32_16x16x32_bf16 v[16:19], v[176:179], v[192:195], v[16:19]
	v_mfma_f32_16x16x32_bf16 v[12:15], v[162:165], v[200:203], v[12:15]
	v_mfma_f32_16x16x32_bf16 v[8:11], v[176:179], v[200:203], v[8:11]
	v_mfma_f32_16x16x32_bf16 v[4:7], v[162:165], v[208:211], v[4:7]
	v_mfma_f32_16x16x32_bf16 v[0:3], v[176:179], v[208:211], v[0:3]
	s_setprio 0
	s_add_i32 s71, s71, 2
	s_add_u32 s44, s44, 0x100
	s_addc_u32 s45, s45, 0
	s_add_u32 s65, s65, 0x100
	s_addc_u32 s70, s70, 0
	s_cmp_gt_u32 s71, 13
	s_barrier
	s_cbranch_scc0 .LBB0_3466

; #define G_STAGE(bufoff, gbase, voff) do { _Pragma("unroll") for (int _i = 0; _i < 2; ++_i) \
;         __builtin_amdgcn_global_load_lds((const unsigned*)((const char*)(gbase) + voff[_i]), (LAS unsigned*)(lds + (bufoff) + ldsw + _i * 8192), 16, 0, 0); } while (0)
; #define G_LDA(dst, b, h) do { _Pragma("unroll") for (int m = 0; m < 4; ++m) _Pragma("unroll") for (int k = 0; k < 2; ++k) dst[m][k] = *(const LAS bf16x8*)(lds + G_SA(b, h) + aoff + m * 2048 + k * 1024); } while (0)
; #define G_LDB(dst, b, h) do { _Pragma("unroll") for (int n = 0; n < 2; ++n) _Pragma("unroll") for (int k = 0; k < 2; ++k) dst[n][k] = *(const LAS bf16x8*)(lds + G_SB(b, h) + boff + n * 2048 + k * 1024); } while (0)
; #define G_MMA(ai, bj, At_, Bt_) do { __builtin_amdgcn_s_setprio(1); _Pragma("unroll") for (int m = 0; m < 4; ++m) _Pragma("unroll") for (int n = 0; n < 2; ++n) _Pragma("unroll") for (int k = 0; k < 2; ++k) \
;         acc[ai][bj][m][n] = __builtin_amdgcn_mfma_f32_16x16x32_bf16(Bt_[n][k], At_[m][k], acc[ai][bj][m][n], 0, 0, 0); __builtin_amdgcn_s_setprio(0); } while (0)
; #define WAIT_V(n) asm volatile("s_waitcnt vmcnt(" #n ")" ::: "memory")
; #define WAIT_L(n) asm volatile("s_waitcnt lgkmcnt(" #n ")" ::: "memory")
; #define BAR __builtin_amdgcn_s_barrier()
; #define SCHED __builtin_amdgcn_sched_barrier(0)
; template <class Get, class Epi>
; DI void gemm_loop(int ntiles, int ld, char* shm, const Get& get, const Epi& epi) {
;     ...
;         for (int t = 0; t < nt; t += 2) {
;             const bool last = (t == nt - 2);
;             const char* a1 = cA + (size_t)(t + 1) * kstep;
;             const char* a2 = last ? nA : cA + (size_t)(t + 2) * kstep; const char* b2 = last ? nB : cB + (size_t)(t + 2) * kstep;
;             const char* a3 = a2 + kstep; const char* b3 = b2 + kstep;
;             G_LDB(B0, 0, 0); G_LDB(B1, 0, 1); SCHED; G_LDA(At, 0, 0); G_STAGE(G_SA(1, 1), a1 + hstep, voffA);
;             WAIT_V(8); WAIT_L(0); BAR; G_MMA(0, 0, At, B0); G_MMA(0, 1, At, B1); BAR; SCHED;
;             G_LDA(At, 0, 1); G_STAGE(G_SB(0, 0), b2, voffB); G_STAGE(G_SB(0, 1), b2 + hstep, voffB); G_STAGE(G_SA(0, 0), a2, voffA);
;             WAIT_V(8); WAIT_L(0); BAR; G_MMA(1, 0, At, B0); G_MMA(1, 1, At, B1); BAR; SCHED;
.Lpeel_3679:
	ds_read_b128 v[144:147], v141
	ds_read_b128 v[148:151], v141 offset:1024
	ds_read_b128 v[152:155], v141 offset:2048
	ds_read_b128 v[156:159], v141 offset:3072
	ds_read_b128 v[160:163], v142
	ds_read_b128 v[164:167], v142 offset:1024
	ds_read_b128 v[168:171], v142 offset:2048
	ds_read_b128 v[172:175], v142 offset:3072
	s_add_u32 s14, s34, 0xfffc0080
	s_addc_u32 s15, s35, -1
	s_cmp_eq_u32 s53, 12
	s_cselect_b32 s37, s9, s15
	s_cselect_b32 s36, s49, s14
	s_cselect_b32 s15, s11, s52
	s_cselect_b32 s14, s50, s51
	v_lshl_add_u64 v[208:209], s[34:35], 0, v[136:137]
	s_add_i32 m0, s25, 0xc000
	ds_read_b128 v[176:179], v143
	ds_read_b128 v[180:183], v143 offset:1024
	ds_read_b128 v[184:187], v143 offset:2048
	ds_read_b128 v[188:191], v143 offset:3072
	ds_read_b128 v[192:195], v143 offset:4096
	ds_read_b128 v[196:199], v143 offset:5120
	ds_read_b128 v[200:203], v143 offset:6144
	ds_read_b128 v[204:207], v143 offset:7168
	global_load_lds_dwordx4 v[208:209], off
	v_lshl_add_u64 v[208:209], s[34:35], 0, v[138:139]
	s_add_i32 m0, s25, 0xe000
	s_nop 0
	global_load_lds_dwordx4 v[208:209], off
	s_waitcnt vmcnt(8)
	s_waitcnt lgkmcnt(0)
	s_barrier
	s_setprio 1
	s_waitcnt lgkmcnt(0)
	v_mfma_f32_16x16x32_bf16 v[124:127], v[144:147], v[176:179], 0
	v_mfma_f32_16x16x32_bf16 v[120:123], v[152:155], v[176:179], 0
	v_mfma_f32_16x16x32_bf16 v[108:111], v[144:147], v[184:187], 0
	v_mfma_f32_16x16x32_bf16 v[104:107], v[152:155], v[184:187], 0
	v_mfma_f32_16x16x32_bf16 v[92:95], v[144:147], v[192:195], 0
	v_mfma_f32_16x16x32_bf16 v[88:91], v[152:155], v[192:195], 0
	v_mfma_f32_16x16x32_bf16 v[76:79], v[144:147], v[200:203], 0
	v_mfma_f32_16x16x32_bf16 v[72:75], v[152:155], v[200:203], 0
	v_mfma_f32_16x16x32_bf16 v[124:127], v[148:151], v[180:183], v[124:127]
	v_mfma_f32_16x16x32_bf16 v[120:123], v[156:159], v[180:183], v[120:123]
	v_mfma_f32_16x16x32_bf16 v[108:111], v[148:151], v[188:191], v[108:111]
	v_mfma_f32_16x16x32_bf16 v[104:107], v[156:159], v[188:191], v[104:107]
	v_mfma_f32_16x16x32_bf16 v[92:95], v[148:151], v[196:199], v[92:95]
	v_mfma_f32_16x16x32_bf16 v[88:91], v[156:159], v[196:199], v[88:91]
	v_mfma_f32_16x16x32_bf16 v[76:79], v[148:151], v[204:207], v[76:79]
	v_mfma_f32_16x16x32_bf16 v[72:75], v[156:159], v[204:207], v[72:75]
	s_setprio 0
	s_setprio 1
	v_mfma_f32_16x16x32_bf16 v[116:119], v[160:163], v[176:179], 0
	v_mfma_f32_16x16x32_bf16 v[112:115], v[168:171], v[176:179], 0
	v_mfma_f32_16x16x32_bf16 v[100:103], v[160:163], v[184:187], 0
	v_mfma_f32_16x16x32_bf16 v[96:99], v[168:171], v[184:187], 0
	v_mfma_f32_16x16x32_bf16 v[84:87], v[160:163], v[192:195], 0
	v_mfma_f32_16x16x32_bf16 v[80:83], v[168:171], v[192:195], 0
	v_mfma_f32_16x16x32_bf16 v[68:71], v[160:163], v[200:203], 0
	v_mfma_f32_16x16x32_bf16 v[64:67], v[168:171], v[200:203], 0
	v_mfma_f32_16x16x32_bf16 v[116:119], v[164:167], v[180:183], v[116:119]
	v_mfma_f32_16x16x32_bf16 v[112:115], v[172:175], v[180:183], v[112:115]
	v_mfma_f32_16x16x32_bf16 v[100:103], v[164:167], v[188:191], v[100:103]
	v_mfma_f32_16x16x32_bf16 v[96:99], v[172:175], v[188:191], v[96:99]
	v_mfma_f32_16x16x32_bf16 v[84:87], v[164:167], v[196:199], v[84:87]
	v_mfma_f32_16x16x32_bf16 v[80:83], v[172:175], v[196:199], v[80:83]
	v_mfma_f32_16x16x32_bf16 v[68:71], v[164:167], v[204:207], v[68:71]
	v_mfma_f32_16x16x32_bf16 v[64:67], v[172:175], v[204:207], v[64:67]
	s_setprio 0
	s_add_i32 s54, s44, s38
	v_lshl_add_u64 v[208:209], s[14:15], 0, v[132:133]
	s_mov_b32 m0, s54
	s_barrier
	ds_read_b128 v[176:179], v143 offset:16384
	ds_read_b128 v[180:183], v143 offset:17408
	ds_read_b128 v[184:187], v143 offset:18432
	ds_read_b128 v[188:191], v143 offset:19456
	ds_read_b128 v[192:195], v143 offset:20480
	ds_read_b128 v[196:199], v143 offset:21504
	ds_read_b128 v[200:203], v143 offset:22528
	ds_read_b128 v[204:207], v143 offset:23552
	global_load_lds_dwordx4 v[208:209], off
	s_add_i32 m0, s54, 0x2000
	s_add_u32 s54, s14, 0x40000
	v_lshl_add_u64 v[210:211], s[14:15], 0, v[128:129]
	s_addc_u32 s55, s15, 0
	s_add_i32 s56, s45, s38
	global_load_lds_dwordx4 v[210:211], off
	v_lshl_add_u64 v[212:213], s[54:55], 0, v[132:133]
	s_mov_b32 m0, s56
	v_lshl_add_u64 v[214:215], s[36:37], 0, v[130:131]
	global_load_lds_dwordx4 v[212:213], off
	v_lshl_add_u64 v[212:213], s[54:55], 0, v[128:129]
	s_add_i32 m0, s56, 0x2000
	s_nop 0
	global_load_lds_dwordx4 v[212:213], off
	v_lshl_add_u64 v[212:213], s[36:37], 0, v[134:135]
	s_mov_b32 m0, s25
	s_nop 0
	global_load_lds_dwordx4 v[212:213], off
	s_mov_b32 m0, s31
	s_nop 0
	global_load_lds_dwordx4 v[214:215], off
	s_waitcnt vmcnt(8)
	s_waitcnt lgkmcnt(0)
	s_barrier
; #define G_STAGE(bufoff, gbase, voff) do { _Pragma("unroll") for (int _i = 0; _i < 2; ++_i) \
;         __builtin_amdgcn_global_load_lds((const unsigned*)((const char*)(gbase) + voff[_i]), (LAS unsigned*)(lds + (bufoff) + ldsw + _i * 8192), 16, 0, 0); } while (0)
; #define G_LDA(dst, b, h) do { _Pragma("unroll") for (int m = 0; m < 4; ++m) _Pragma("unroll") for (int k = 0; k < 2; ++k) dst[m][k] = *(const LAS bf16x8*)(lds + G_SA(b, h) + aoff + m * 2048 + k * 1024); } while (0)
; #define G_LDB(dst, b, h) do { _Pragma("unroll") for (int n = 0; n < 2; ++n) _Pragma("unroll") for (int k = 0; k < 2; ++k) dst[n][k] = *(const LAS bf16x8*)(lds + G_SB(b, h) + boff + n * 2048 + k * 1024); } while (0)
; #define G_MMA(ai, bj, At_, Bt_) do { __builtin_amdgcn_s_setprio(1); _Pragma("unroll") for (int m = 0; m < 4; ++m) _Pragma("unroll") for (int n = 0; n < 2; ++n) _Pragma("unroll") for (int k = 0; k < 2; ++k) \
;         acc[ai][bj][m][n] = __builtin_amdgcn_mfma_f32_16x16x32_bf16(Bt_[n][k], At_[m][k], acc[ai][bj][m][n], 0, 0, 0); __builtin_amdgcn_s_setprio(0); } while (0)
; #define WAIT_V(n) asm volatile("s_waitcnt vmcnt(" #n ")" ::: "memory")
; #define WAIT_L(n) asm volatile("s_waitcnt lgkmcnt(" #n ")" ::: "memory")
; #define BAR __builtin_amdgcn_s_barrier()
; #define SCHED __builtin_amdgcn_sched_barrier(0)
; template <class Get, class Epi>
; DI void gemm_loop(int ntiles, int ld, char* shm, const Get& get, const Epi& epi) {
;     ...
;             G_LDA(At, 0, 1); G_STAGE(G_SB(0, 0), b2, voffB); G_STAGE(G_SB(0, 1), b2 + hstep, voffB); G_STAGE(G_SA(0, 0), a2, voffA);
;             WAIT_V(8); WAIT_L(0); BAR; G_MMA(1, 0, At, B0); G_MMA(1, 1, At, B1); BAR; SCHED;
;             G_LDB(B0, 1, 0); G_LDB(B1, 1, 1); SCHED; G_LDA(At, 1, 0); G_STAGE(G_SA(0, 1), a2 + hstep, voffA);
;             WAIT_V(8); WAIT_L(0); BAR; G_MMA(0, 0, At, B0); G_MMA(0, 1, At, B1); BAR; SCHED;
;             G_LDA(At, 1, 1); G_STAGE(G_SB(1, 0), b3, voffB); G_STAGE(G_SB(1, 1), b3 + hstep, voffB); G_STAGE(G_SA(1, 0), a3, voffA);
	s_setprio 1
	s_waitcnt lgkmcnt(0)
	v_mfma_f32_16x16x32_bf16 v[60:63], v[144:147], v[176:179], 0
	v_mfma_f32_16x16x32_bf16 v[56:59], v[152:155], v[176:179], 0
	v_mfma_f32_16x16x32_bf16 v[44:47], v[144:147], v[184:187], 0
	v_mfma_f32_16x16x32_bf16 v[40:43], v[152:155], v[184:187], 0
	v_mfma_f32_16x16x32_bf16 v[28:31], v[144:147], v[192:195], 0
	v_mfma_f32_16x16x32_bf16 v[24:27], v[152:155], v[192:195], 0
	v_mfma_f32_16x16x32_bf16 v[12:15], v[144:147], v[200:203], 0
	v_mfma_f32_16x16x32_bf16 v[8:11], v[152:155], v[200:203], 0
	v_mfma_f32_16x16x32_bf16 v[60:63], v[148:151], v[180:183], v[60:63]
	v_mfma_f32_16x16x32_bf16 v[56:59], v[156:159], v[180:183], v[56:59]
	v_mfma_f32_16x16x32_bf16 v[44:47], v[148:151], v[188:191], v[44:47]
	v_mfma_f32_16x16x32_bf16 v[40:43], v[156:159], v[188:191], v[40:43]
	v_mfma_f32_16x16x32_bf16 v[28:31], v[148:151], v[196:199], v[28:31]
	v_mfma_f32_16x16x32_bf16 v[24:27], v[156:159], v[196:199], v[24:27]
	v_mfma_f32_16x16x32_bf16 v[12:15], v[148:151], v[204:207], v[12:15]
	v_mfma_f32_16x16x32_bf16 v[8:11], v[156:159], v[204:207], v[8:11]
	s_setprio 0
	s_setprio 1
	v_mfma_f32_16x16x32_bf16 v[52:55], v[160:163], v[176:179], 0
	v_mfma_f32_16x16x32_bf16 v[48:51], v[168:171], v[176:179], 0
	v_mfma_f32_16x16x32_bf16 v[36:39], v[160:163], v[184:187], 0
	v_mfma_f32_16x16x32_bf16 v[32:35], v[168:171], v[184:187], 0
	v_mfma_f32_16x16x32_bf16 v[20:23], v[160:163], v[192:195], 0
	v_mfma_f32_16x16x32_bf16 v[16:19], v[168:171], v[192:195], 0
	v_mfma_f32_16x16x32_bf16 v[4:7], v[160:163], v[200:203], 0
	v_mfma_f32_16x16x32_bf16 v[0:3], v[168:171], v[200:203], 0
	v_mfma_f32_16x16x32_bf16 v[52:55], v[164:167], v[180:183], v[52:55]
	v_mfma_f32_16x16x32_bf16 v[48:51], v[172:175], v[180:183], v[48:51]
	v_mfma_f32_16x16x32_bf16 v[36:39], v[164:167], v[188:191], v[36:39]
	v_mfma_f32_16x16x32_bf16 v[32:35], v[172:175], v[188:191], v[32:35]
	v_mfma_f32_16x16x32_bf16 v[20:23], v[164:167], v[196:199], v[20:23]
	v_mfma_f32_16x16x32_bf16 v[16:19], v[172:175], v[196:199], v[16:19]
	v_mfma_f32_16x16x32_bf16 v[4:7], v[164:167], v[204:207], v[4:7]
	v_mfma_f32_16x16x32_bf16 v[0:3], v[172:175], v[204:207], v[0:3]
	s_setprio 0
	s_add_i32 s54, 0, 0x18000
	s_add_i32 s55, 0, 0x1c000
	v_add_u32_e32 v156, s54, v140
	s_barrier
	v_add_u32_e32 v172, s55, v140
	ds_read_b128 v[144:147], v156
	ds_read_b128 v[148:151], v156 offset:1024
	ds_read_b128 v[152:155], v156 offset:2048
	ds_read_b128 v[156:159], v156 offset:3072
	ds_read_b128 v[160:163], v172
	ds_read_b128 v[164:167], v172 offset:1024
	ds_read_b128 v[168:171], v172 offset:2048
	ds_read_b128 v[172:175], v172 offset:3072
	s_add_u32 s36, s36, 0x40000
	s_addc_u32 s37, s37, 0
	s_mov_b32 m0, s40
	v_lshl_add_u64 v[216:217], s[36:37], 0, v[134:135]
	ds_read_b128 v[176:179], v143 offset:32768
	ds_read_b128 v[180:183], v143 offset:33792
	ds_read_b128 v[184:187], v143 offset:34816
	ds_read_b128 v[188:191], v143 offset:35840
	ds_read_b128 v[192:195], v143 offset:36864
	ds_read_b128 v[196:199], v143 offset:37888
	ds_read_b128 v[200:203], v143 offset:38912
	ds_read_b128 v[204:207], v143 offset:39936
	global_load_lds_dwordx4 v[216:217], off
	v_lshl_add_u64 v[216:217], s[36:37], 0, v[130:131]
	s_mov_b32 m0, s41
	s_nop 0
	global_load_lds_dwordx4 v[216:217], off
	s_waitcnt vmcnt(8)
	s_waitcnt lgkmcnt(0)
	s_barrier
	s_setprio 1
	s_waitcnt lgkmcnt(0)
	v_mfma_f32_16x16x32_bf16 v[124:127], v[144:147], v[176:179], v[124:127]
	v_mfma_f32_16x16x32_bf16 v[120:123], v[152:155], v[176:179], v[120:123]
	v_mfma_f32_16x16x32_bf16 v[108:111], v[144:147], v[184:187], v[108:111]
	v_mfma_f32_16x16x32_bf16 v[104:107], v[152:155], v[184:187], v[104:107]
	v_mfma_f32_16x16x32_bf16 v[92:95], v[144:147], v[192:195], v[92:95]
	v_mfma_f32_16x16x32_bf16 v[88:91], v[152:155], v[192:195], v[88:91]
	v_mfma_f32_16x16x32_bf16 v[76:79], v[144:147], v[200:203], v[76:79]
	v_mfma_f32_16x16x32_bf16 v[72:75], v[152:155], v[200:203], v[72:75]
	v_mfma_f32_16x16x32_bf16 v[124:127], v[148:151], v[180:183], v[124:127]
	v_mfma_f32_16x16x32_bf16 v[120:123], v[156:159], v[180:183], v[120:123]
	v_mfma_f32_16x16x32_bf16 v[108:111], v[148:151], v[188:191], v[108:111]
	v_mfma_f32_16x16x32_bf16 v[104:107], v[156:159], v[188:191], v[104:107]
	v_mfma_f32_16x16x32_bf16 v[92:95], v[148:151], v[196:199], v[92:95]
	v_mfma_f32_16x16x32_bf16 v[88:91], v[156:159], v[196:199], v[88:91]
	v_mfma_f32_16x16x32_bf16 v[76:79], v[148:151], v[204:207], v[76:79]
	v_mfma_f32_16x16x32_bf16 v[72:75], v[156:159], v[204:207], v[72:75]
	s_setprio 0
	s_setprio 1
	v_mfma_f32_16x16x32_bf16 v[116:119], v[160:163], v[176:179], v[116:119]
	v_mfma_f32_16x16x32_bf16 v[112:115], v[168:171], v[176:179], v[112:115]
	v_mfma_f32_16x16x32_bf16 v[100:103], v[160:163], v[184:187], v[100:103]
	v_mfma_f32_16x16x32_bf16 v[96:99], v[168:171], v[184:187], v[96:99]
	v_mfma_f32_16x16x32_bf16 v[84:87], v[160:163], v[192:195], v[84:87]
	v_mfma_f32_16x16x32_bf16 v[80:83], v[168:171], v[192:195], v[80:83]
	v_mfma_f32_16x16x32_bf16 v[68:71], v[160:163], v[200:203], v[68:71]
	v_mfma_f32_16x16x32_bf16 v[64:67], v[168:171], v[200:203], v[64:67]
	v_mfma_f32_16x16x32_bf16 v[116:119], v[164:167], v[180:183], v[116:119]
	v_mfma_f32_16x16x32_bf16 v[112:115], v[172:175], v[180:183], v[112:115]
	v_mfma_f32_16x16x32_bf16 v[100:103], v[164:167], v[188:191], v[100:103]
	v_mfma_f32_16x16x32_bf16 v[96:99], v[172:175], v[188:191], v[96:99]
	v_mfma_f32_16x16x32_bf16 v[84:87], v[164:167], v[196:199], v[84:87]
	v_mfma_f32_16x16x32_bf16 v[80:83], v[172:175], v[196:199], v[80:83]
	v_mfma_f32_16x16x32_bf16 v[68:71], v[164:167], v[204:207], v[68:71]
	v_mfma_f32_16x16x32_bf16 v[64:67], v[172:175], v[204:207], v[64:67]
	s_setprio 0
	s_add_i32 s36, s54, s38
	v_lshl_add_u64 v[208:209], v[208:209], 0, s[2:3]
	s_mov_b32 m0, s36
	s_barrier
; #define G_STAGE(bufoff, gbase, voff) do { _Pragma("unroll") for (int _i = 0; _i < 2; ++_i) \
;         __builtin_amdgcn_global_load_lds((const unsigned*)((const char*)(gbase) + voff[_i]), (LAS unsigned*)(lds + (bufoff) + ldsw + _i * 8192), 16, 0, 0); } while (0)
; #define G_LDA(dst, b, h) do { _Pragma("unroll") for (int m = 0; m < 4; ++m) _Pragma("unroll") for (int k = 0; k < 2; ++k) dst[m][k] = *(const LAS bf16x8*)(lds + G_SA(b, h) + aoff + m * 2048 + k * 1024); } while (0)
; #define G_LDB(dst, b, h) do { _Pragma("unroll") for (int n = 0; n < 2; ++n) _Pragma("unroll") for (int k = 0; k < 2; ++k) dst[n][k] = *(const LAS bf16x8*)(lds + G_SB(b, h) + boff + n * 2048 + k * 1024); } while (0)
; #define G_MMA(ai, bj, At_, Bt_) do { __builtin_amdgcn_s_setprio(1); _Pragma("unroll") for (int m = 0; m < 4; ++m) _Pragma("unroll") for (int n = 0; n < 2; ++n) _Pragma("unroll") for (int k = 0; k < 2; ++k) \
;         acc[ai][bj][m][n] = __builtin_amdgcn_mfma_f32_16x16x32_bf16(Bt_[n][k], At_[m][k], acc[ai][bj][m][n], 0, 0, 0); __builtin_amdgcn_s_setprio(0); } while (0)
; #define WAIT_V(n) asm volatile("s_waitcnt vmcnt(" #n ")" ::: "memory")
; #define WAIT_L(n) asm volatile("s_waitcnt lgkmcnt(" #n ")" ::: "memory")
; #define BAR __builtin_amdgcn_s_barrier()
; #define SCHED __builtin_amdgcn_sched_barrier(0)
; template <class Get, class Epi>
; DI void gemm_loop(int ntiles, int ld, char* shm, const Get& get, const Epi& epi) {
;     ...
;         for (int t = 0; t < nt; t += 2) {
;             const bool last = (t == nt - 2);
;             const char* a1 = cA + (size_t)(t + 1) * kstep;
;             const char* a2 = last ? nA : cA + (size_t)(t + 2) * kstep; const char* b2 = last ? nB : cB + (size_t)(t + 2) * kstep;
;             const char* a3 = a2 + kstep; const char* b3 = b2 + kstep;
;             G_LDB(B0, 0, 0); G_LDB(B1, 0, 1); SCHED; G_LDA(At, 0, 0); G_STAGE(G_SA(1, 1), a1 + hstep, voffA);
;             WAIT_V(8); WAIT_L(0); BAR; G_MMA(0, 0, At, B0); G_MMA(0, 1, At, B1); BAR; SCHED;
;     ...
;             G_LDA(At, 1, 1); G_STAGE(G_SB(1, 0), b3, voffB); G_STAGE(G_SB(1, 1), b3 + hstep, voffB); G_STAGE(G_SA(1, 0), a3, voffA);
;             WAIT_V(8); WAIT_L(0); BAR; G_MMA(1, 0, At, B0); G_MMA(1, 1, At, B1); BAR; SCHED;
;         }
	ds_read_b128 v[176:179], v143 offset:49152
	ds_read_b128 v[180:183], v143 offset:50176
	ds_read_b128 v[184:187], v143 offset:51200
	ds_read_b128 v[188:191], v143 offset:52224
	ds_read_b128 v[192:195], v143 offset:53248
	ds_read_b128 v[196:199], v143 offset:54272
	ds_read_b128 v[200:203], v143 offset:55296
	ds_read_b128 v[204:207], v143 offset:56320
	global_load_lds_dwordx4 v[208:209], off
	s_add_i32 m0, s36, 0x2000
	s_add_u32 s14, s14, 0x40080
	v_lshl_add_u64 v[208:209], v[210:211], 0, s[2:3]
	s_addc_u32 s15, s15, 0
	s_add_i32 s36, s55, s38
	global_load_lds_dwordx4 v[208:209], off
	v_lshl_add_u64 v[208:209], s[14:15], 0, v[132:133]
	s_mov_b32 m0, s36
	s_nop 0
	global_load_lds_dwordx4 v[208:209], off
	v_lshl_add_u64 v[208:209], s[14:15], 0, v[128:129]
	s_add_i32 m0, s36, 0x2000
	s_nop 0
	global_load_lds_dwordx4 v[208:209], off
	v_lshl_add_u64 v[208:209], v[212:213], 0, s[2:3]
	s_mov_b32 m0, s42
	s_nop 0
	global_load_lds_dwordx4 v[208:209], off
	v_lshl_add_u64 v[208:209], v[214:215], 0, s[2:3]
	s_mov_b32 m0, s43
	s_nop 0
	global_load_lds_dwordx4 v[208:209], off
	s_waitcnt vmcnt(8)
	s_waitcnt lgkmcnt(0)
	s_barrier
	s_setprio 1
	s_waitcnt lgkmcnt(0)
	v_mfma_f32_16x16x32_bf16 v[60:63], v[144:147], v[176:179], v[60:63]
	v_mfma_f32_16x16x32_bf16 v[56:59], v[152:155], v[176:179], v[56:59]
	v_mfma_f32_16x16x32_bf16 v[44:47], v[144:147], v[184:187], v[44:47]
	v_mfma_f32_16x16x32_bf16 v[40:43], v[152:155], v[184:187], v[40:43]
	v_mfma_f32_16x16x32_bf16 v[28:31], v[144:147], v[192:195], v[28:31]
	v_mfma_f32_16x16x32_bf16 v[24:27], v[152:155], v[192:195], v[24:27]
	v_mfma_f32_16x16x32_bf16 v[12:15], v[144:147], v[200:203], v[12:15]
	v_mfma_f32_16x16x32_bf16 v[8:11], v[152:155], v[200:203], v[8:11]
	v_mfma_f32_16x16x32_bf16 v[60:63], v[148:151], v[180:183], v[60:63]
	v_mfma_f32_16x16x32_bf16 v[56:59], v[156:159], v[180:183], v[56:59]
	v_mfma_f32_16x16x32_bf16 v[44:47], v[148:151], v[188:191], v[44:47]
	v_mfma_f32_16x16x32_bf16 v[40:43], v[156:159], v[188:191], v[40:43]
	v_mfma_f32_16x16x32_bf16 v[28:31], v[148:151], v[196:199], v[28:31]
	v_mfma_f32_16x16x32_bf16 v[24:27], v[156:159], v[196:199], v[24:27]
	v_mfma_f32_16x16x32_bf16 v[12:15], v[148:151], v[204:207], v[12:15]
	v_mfma_f32_16x16x32_bf16 v[8:11], v[156:159], v[204:207], v[8:11]
	s_setprio 0
	s_setprio 1
	v_mfma_f32_16x16x32_bf16 v[52:55], v[160:163], v[176:179], v[52:55]
	v_mfma_f32_16x16x32_bf16 v[48:51], v[168:171], v[176:179], v[48:51]
	v_mfma_f32_16x16x32_bf16 v[36:39], v[160:163], v[184:187], v[36:39]
	v_mfma_f32_16x16x32_bf16 v[32:35], v[168:171], v[184:187], v[32:35]
	v_mfma_f32_16x16x32_bf16 v[20:23], v[160:163], v[192:195], v[20:23]
	v_mfma_f32_16x16x32_bf16 v[16:19], v[168:171], v[192:195], v[16:19]
	v_mfma_f32_16x16x32_bf16 v[4:7], v[160:163], v[200:203], v[4:7]
	v_mfma_f32_16x16x32_bf16 v[0:3], v[168:171], v[200:203], v[0:3]
	v_mfma_f32_16x16x32_bf16 v[52:55], v[164:167], v[180:183], v[52:55]
	v_mfma_f32_16x16x32_bf16 v[48:51], v[172:175], v[180:183], v[48:51]
	v_mfma_f32_16x16x32_bf16 v[36:39], v[164:167], v[188:191], v[36:39]
	v_mfma_f32_16x16x32_bf16 v[32:35], v[172:175], v[188:191], v[32:35]
	v_mfma_f32_16x16x32_bf16 v[20:23], v[164:167], v[196:199], v[20:23]
	v_mfma_f32_16x16x32_bf16 v[16:19], v[172:175], v[196:199], v[16:19]
	v_mfma_f32_16x16x32_bf16 v[4:7], v[164:167], v[204:207], v[4:7]
	v_mfma_f32_16x16x32_bf16 v[0:3], v[172:175], v[204:207], v[0:3]
	s_setprio 0
	s_add_i32 s53, s53, 2
	s_add_u32 s34, s34, 0x100
	s_addc_u32 s35, s35, 0
	s_add_u32 s51, s51, 0x100
	s_addc_u32 s52, s52, 0
	s_cmp_gt_u32 s53, 13
	s_barrier
	s_cbranch_scc0 .LBB0_3679
	s_branch .Lpost_3679
.LBB0_3679:
	ds_read_b128 v[144:147], v141
	ds_read_b128 v[148:151], v141 offset:1024
	ds_read_b128 v[152:155], v141 offset:2048
	ds_read_b128 v[156:159], v141 offset:3072
	ds_read_b128 v[160:163], v142
	ds_read_b128 v[164:167], v142 offset:1024
	ds_read_b128 v[168:171], v142 offset:2048
	ds_read_b128 v[172:175], v142 offset:3072
	s_add_u32 s14, s34, 0xfffc0080
	s_addc_u32 s15, s35, -1
	s_cmp_eq_u32 s53, 12
	s_cselect_b32 s37, s9, s15
	s_cselect_b32 s36, s49, s14
	s_cselect_b32 s15, s11, s52
	s_cselect_b32 s14, s50, s51
	v_lshl_add_u64 v[208:209], s[34:35], 0, v[136:137]
	s_add_i32 m0, s25, 0xc000
	ds_read_b128 v[176:179], v143
	ds_read_b128 v[180:183], v143 offset:1024
	ds_read_b128 v[184:187], v143 offset:2048
	ds_read_b128 v[188:191], v143 offset:3072
	ds_read_b128 v[192:195], v143 offset:4096
	ds_read_b128 v[196:199], v143 offset:5120
	ds_read_b128 v[200:203], v143 offset:6144
	ds_read_b128 v[204:207], v143 offset:7168
	global_load_lds_dwordx4 v[208:209], off
	v_lshl_add_u64 v[208:209], s[34:35], 0, v[138:139]
	s_add_i32 m0, s25, 0xe000
	s_nop 0
	global_load_lds_dwordx4 v[208:209], off
	s_waitcnt vmcnt(8)
	s_waitcnt lgkmcnt(0)
	s_barrier
; #define G_STAGE(bufoff, gbase, voff) do { _Pragma("unroll") for (int _i = 0; _i < 2; ++_i) \
;         __builtin_amdgcn_global_load_lds((const unsigned*)((const char*)(gbase) + voff[_i]), (LAS unsigned*)(lds + (bufoff) + ldsw + _i * 8192), 16, 0, 0); } while (0)
; #define G_LDA(dst, b, h) do { _Pragma("unroll") for (int m = 0; m < 4; ++m) _Pragma("unroll") for (int k = 0; k < 2; ++k) dst[m][k] = *(const LAS bf16x8*)(lds + G_SA(b, h) + aoff + m * 2048 + k * 1024); } while (0)
; #define G_LDB(dst, b, h) do { _Pragma("unroll") for (int n = 0; n < 2; ++n) _Pragma("unroll") for (int k = 0; k < 2; ++k) dst[n][k] = *(const LAS bf16x8*)(lds + G_SB(b, h) + boff + n * 2048 + k * 1024); } while (0)
; #define G_MMA(ai, bj, At_, Bt_) do { __builtin_amdgcn_s_setprio(1); _Pragma("unroll") for (int m = 0; m < 4; ++m) _Pragma("unroll") for (int n = 0; n < 2; ++n) _Pragma("unroll") for (int k = 0; k < 2; ++k) \
;         acc[ai][bj][m][n] = __builtin_amdgcn_mfma_f32_16x16x32_bf16(Bt_[n][k], At_[m][k], acc[ai][bj][m][n], 0, 0, 0); __builtin_amdgcn_s_setprio(0); } while (0)
; #define WAIT_V(n) asm volatile("s_waitcnt vmcnt(" #n ")" ::: "memory")
; #define WAIT_L(n) asm volatile("s_waitcnt lgkmcnt(" #n ")" ::: "memory")
; #define BAR __builtin_amdgcn_s_barrier()
; #define SCHED __builtin_amdgcn_sched_barrier(0)
; template <class Get, class Epi>
; DI void gemm_loop(int ntiles, int ld, char* shm, const Get& get, const Epi& epi) {
;     ...
;             G_LDB(B0, 0, 0); G_LDB(B1, 0, 1); SCHED; G_LDA(At, 0, 0); G_STAGE(G_SA(1, 1), a1 + hstep, voffA);
;             WAIT_V(8); WAIT_L(0); BAR; G_MMA(0, 0, At, B0); G_MMA(0, 1, At, B1); BAR; SCHED;
;             G_LDA(At, 0, 1); G_STAGE(G_SB(0, 0), b2, voffB); G_STAGE(G_SB(0, 1), b2 + hstep, voffB); G_STAGE(G_SA(0, 0), a2, voffA);
;             WAIT_V(8); WAIT_L(0); BAR; G_MMA(1, 0, At, B0); G_MMA(1, 1, At, B1); BAR; SCHED;
;             G_LDB(B0, 1, 0); G_LDB(B1, 1, 1); SCHED; G_LDA(At, 1, 0); G_STAGE(G_SA(0, 1), a2 + hstep, voffA);
;             WAIT_V(8); WAIT_L(0); BAR; G_MMA(0, 0, At, B0); G_MMA(0, 1, At, B1); BAR; SCHED;
	s_setprio 1
	s_waitcnt lgkmcnt(0)
	v_mfma_f32_16x16x32_bf16 v[124:127], v[144:147], v[176:179], v[124:127]
	v_mfma_f32_16x16x32_bf16 v[120:123], v[152:155], v[176:179], v[120:123]
	v_mfma_f32_16x16x32_bf16 v[108:111], v[144:147], v[184:187], v[108:111]
	v_mfma_f32_16x16x32_bf16 v[104:107], v[152:155], v[184:187], v[104:107]
	v_mfma_f32_16x16x32_bf16 v[92:95], v[144:147], v[192:195], v[92:95]
	v_mfma_f32_16x16x32_bf16 v[88:91], v[152:155], v[192:195], v[88:91]
	v_mfma_f32_16x16x32_bf16 v[76:79], v[144:147], v[200:203], v[76:79]
	v_mfma_f32_16x16x32_bf16 v[72:75], v[152:155], v[200:203], v[72:75]
	v_mfma_f32_16x16x32_bf16 v[124:127], v[148:151], v[180:183], v[124:127]
	v_mfma_f32_16x16x32_bf16 v[120:123], v[156:159], v[180:183], v[120:123]
	v_mfma_f32_16x16x32_bf16 v[108:111], v[148:151], v[188:191], v[108:111]
	v_mfma_f32_16x16x32_bf16 v[104:107], v[156:159], v[188:191], v[104:107]
	v_mfma_f32_16x16x32_bf16 v[92:95], v[148:151], v[196:199], v[92:95]
	v_mfma_f32_16x16x32_bf16 v[88:91], v[156:159], v[196:199], v[88:91]
	v_mfma_f32_16x16x32_bf16 v[76:79], v[148:151], v[204:207], v[76:79]
	v_mfma_f32_16x16x32_bf16 v[72:75], v[156:159], v[204:207], v[72:75]
	s_setprio 0
	s_setprio 1
	v_mfma_f32_16x16x32_bf16 v[116:119], v[160:163], v[176:179], v[116:119]
	v_mfma_f32_16x16x32_bf16 v[112:115], v[168:171], v[176:179], v[112:115]
	v_mfma_f32_16x16x32_bf16 v[100:103], v[160:163], v[184:187], v[100:103]
	v_mfma_f32_16x16x32_bf16 v[96:99], v[168:171], v[184:187], v[96:99]
	v_mfma_f32_16x16x32_bf16 v[84:87], v[160:163], v[192:195], v[84:87]
	v_mfma_f32_16x16x32_bf16 v[80:83], v[168:171], v[192:195], v[80:83]
	v_mfma_f32_16x16x32_bf16 v[68:71], v[160:163], v[200:203], v[68:71]
	v_mfma_f32_16x16x32_bf16 v[64:67], v[168:171], v[200:203], v[64:67]
	v_mfma_f32_16x16x32_bf16 v[116:119], v[164:167], v[180:183], v[116:119]
	v_mfma_f32_16x16x32_bf16 v[112:115], v[172:175], v[180:183], v[112:115]
	v_mfma_f32_16x16x32_bf16 v[100:103], v[164:167], v[188:191], v[100:103]
	v_mfma_f32_16x16x32_bf16 v[96:99], v[172:175], v[188:191], v[96:99]
	v_mfma_f32_16x16x32_bf16 v[84:87], v[164:167], v[196:199], v[84:87]
	v_mfma_f32_16x16x32_bf16 v[80:83], v[172:175], v[196:199], v[80:83]
	v_mfma_f32_16x16x32_bf16 v[68:71], v[164:167], v[204:207], v[68:71]
	v_mfma_f32_16x16x32_bf16 v[64:67], v[172:175], v[204:207], v[64:67]
	s_setprio 0
	s_add_i32 s54, s44, s38
	v_lshl_add_u64 v[208:209], s[14:15], 0, v[132:133]
	s_mov_b32 m0, s54
	s_barrier
	ds_read_b128 v[176:179], v143 offset:16384
	ds_read_b128 v[180:183], v143 offset:17408
	ds_read_b128 v[184:187], v143 offset:18432
	ds_read_b128 v[188:191], v143 offset:19456
	ds_read_b128 v[192:195], v143 offset:20480
	ds_read_b128 v[196:199], v143 offset:21504
	ds_read_b128 v[200:203], v143 offset:22528
	ds_read_b128 v[204:207], v143 offset:23552
	global_load_lds_dwordx4 v[208:209], off
	s_add_i32 m0, s54, 0x2000
	s_add_u32 s54, s14, 0x40000
	v_lshl_add_u64 v[210:211], s[14:15], 0, v[128:129]
	s_addc_u32 s55, s15, 0
	s_add_i32 s56, s45, s38
	global_load_lds_dwordx4 v[210:211], off
	v_lshl_add_u64 v[212:213], s[54:55], 0, v[132:133]
	s_mov_b32 m0, s56
	v_lshl_add_u64 v[214:215], s[36:37], 0, v[130:131]
	global_load_lds_dwordx4 v[212:213], off
	v_lshl_add_u64 v[212:213], s[54:55], 0, v[128:129]
	s_add_i32 m0, s56, 0x2000
	s_nop 0
	global_load_lds_dwordx4 v[212:213], off
	v_lshl_add_u64 v[212:213], s[36:37], 0, v[134:135]
	s_mov_b32 m0, s25
	s_nop 0
	global_load_lds_dwordx4 v[212:213], off
	s_mov_b32 m0, s31
	s_nop 0
	global_load_lds_dwordx4 v[214:215], off
	s_waitcnt vmcnt(8)
	s_waitcnt lgkmcnt(0)
	s_barrier
	s_setprio 1
	s_waitcnt lgkmcnt(0)
	v_mfma_f32_16x16x32_bf16 v[60:63], v[144:147], v[176:179], v[60:63]
	v_mfma_f32_16x16x32_bf16 v[56:59], v[152:155], v[176:179], v[56:59]
	v_mfma_f32_16x16x32_bf16 v[44:47], v[144:147], v[184:187], v[44:47]
	v_mfma_f32_16x16x32_bf16 v[40:43], v[152:155], v[184:187], v[40:43]
	v_mfma_f32_16x16x32_bf16 v[28:31], v[144:147], v[192:195], v[28:31]
	v_mfma_f32_16x16x32_bf16 v[24:27], v[152:155], v[192:195], v[24:27]
	v_mfma_f32_16x16x32_bf16 v[12:15], v[144:147], v[200:203], v[12:15]
	v_mfma_f32_16x16x32_bf16 v[8:11], v[152:155], v[200:203], v[8:11]
	v_mfma_f32_16x16x32_bf16 v[60:63], v[148:151], v[180:183], v[60:63]
	v_mfma_f32_16x16x32_bf16 v[56:59], v[156:159], v[180:183], v[56:59]
	v_mfma_f32_16x16x32_bf16 v[44:47], v[148:151], v[188:191], v[44:47]
	v_mfma_f32_16x16x32_bf16 v[40:43], v[156:159], v[188:191], v[40:43]
	v_mfma_f32_16x16x32_bf16 v[28:31], v[148:151], v[196:199], v[28:31]
	v_mfma_f32_16x16x32_bf16 v[24:27], v[156:159], v[196:199], v[24:27]
	v_mfma_f32_16x16x32_bf16 v[12:15], v[148:151], v[204:207], v[12:15]
	v_mfma_f32_16x16x32_bf16 v[8:11], v[156:159], v[204:207], v[8:11]
	s_setprio 0
	s_setprio 1
	v_mfma_f32_16x16x32_bf16 v[52:55], v[160:163], v[176:179], v[52:55]
	v_mfma_f32_16x16x32_bf16 v[48:51], v[168:171], v[176:179], v[48:51]
	v_mfma_f32_16x16x32_bf16 v[36:39], v[160:163], v[184:187], v[36:39]
	v_mfma_f32_16x16x32_bf16 v[32:35], v[168:171], v[184:187], v[32:35]
	v_mfma_f32_16x16x32_bf16 v[20:23], v[160:163], v[192:195], v[20:23]
	v_mfma_f32_16x16x32_bf16 v[16:19], v[168:171], v[192:195], v[16:19]
	v_mfma_f32_16x16x32_bf16 v[4:7], v[160:163], v[200:203], v[4:7]
	v_mfma_f32_16x16x32_bf16 v[0:3], v[168:171], v[200:203], v[0:3]
	v_mfma_f32_16x16x32_bf16 v[52:55], v[164:167], v[180:183], v[52:55]
	v_mfma_f32_16x16x32_bf16 v[48:51], v[172:175], v[180:183], v[48:51]
	v_mfma_f32_16x16x32_bf16 v[36:39], v[164:167], v[188:191], v[36:39]
	v_mfma_f32_16x16x32_bf16 v[32:35], v[172:175], v[188:191], v[32:35]
	v_mfma_f32_16x16x32_bf16 v[20:23], v[164:167], v[196:199], v[20:23]
	v_mfma_f32_16x16x32_bf16 v[16:19], v[172:175], v[196:199], v[16:19]
	v_mfma_f32_16x16x32_bf16 v[4:7], v[164:167], v[204:207], v[4:7]
	v_mfma_f32_16x16x32_bf16 v[0:3], v[172:175], v[204:207], v[0:3]
	s_setprio 0
	s_add_i32 s54, 0, 0x18000
	s_add_i32 s55, 0, 0x1c000
	v_add_u32_e32 v156, s54, v140
	s_barrier
; #define G_STAGE(bufoff, gbase, voff) do { _Pragma("unroll") for (int _i = 0; _i < 2; ++_i) \
;         __builtin_amdgcn_global_load_lds((const unsigned*)((const char*)(gbase) + voff[_i]), (LAS unsigned*)(lds + (bufoff) + ldsw + _i * 8192), 16, 0, 0); } while (0)
; #define G_LDA(dst, b, h) do { _Pragma("unroll") for (int m = 0; m < 4; ++m) _Pragma("unroll") for (int k = 0; k < 2; ++k) dst[m][k] = *(const LAS bf16x8*)(lds + G_SA(b, h) + aoff + m * 2048 + k * 1024); } while (0)
; #define G_LDB(dst, b, h) do { _Pragma("unroll") for (int n = 0; n < 2; ++n) _Pragma("unroll") for (int k = 0; k < 2; ++k) dst[n][k] = *(const LAS bf16x8*)(lds + G_SB(b, h) + boff + n * 2048 + k * 1024); } while (0)
; #define G_MMA(ai, bj, At_, Bt_) do { __builtin_amdgcn_s_setprio(1); _Pragma("unroll") for (int m = 0; m < 4; ++m) _Pragma("unroll") for (int n = 0; n < 2; ++n) _Pragma("unroll") for (int k = 0; k < 2; ++k) \
;         acc[ai][bj][m][n] = __builtin_amdgcn_mfma_f32_16x16x32_bf16(Bt_[n][k], At_[m][k], acc[ai][bj][m][n], 0, 0, 0); __builtin_amdgcn_s_setprio(0); } while (0)
; #define WAIT_V(n) asm volatile("s_waitcnt vmcnt(" #n ")" ::: "memory")
; #define WAIT_L(n) asm volatile("s_waitcnt lgkmcnt(" #n ")" ::: "memory")
; #define BAR __builtin_amdgcn_s_barrier()
; #define SCHED __builtin_amdgcn_sched_barrier(0)
; template <class Get, class Epi>
; DI void gemm_loop(int ntiles, int ld, char* shm, const Get& get, const Epi& epi) {
;     ...
;             G_LDB(B0, 1, 0); G_LDB(B1, 1, 1); SCHED; G_LDA(At, 1, 0); G_STAGE(G_SA(0, 1), a2 + hstep, voffA);
;             WAIT_V(8); WAIT_L(0); BAR; G_MMA(0, 0, At, B0); G_MMA(0, 1, At, B1); BAR; SCHED;
	v_add_u32_e32 v172, s55, v140
	ds_read_b128 v[144:147], v156
	ds_read_b128 v[148:151], v156 offset:1024
	ds_read_b128 v[152:155], v156 offset:2048
	ds_read_b128 v[156:159], v156 offset:3072
	ds_read_b128 v[160:163], v172
	ds_read_b128 v[164:167], v172 offset:1024
	ds_read_b128 v[168:171], v172 offset:2048
	ds_read_b128 v[172:175], v172 offset:3072
	s_add_u32 s36, s36, 0x40000
	s_addc_u32 s37, s37, 0
	s_mov_b32 m0, s40
	v_lshl_add_u64 v[216:217], s[36:37], 0, v[134:135]
	ds_read_b128 v[176:179], v143 offset:32768
	ds_read_b128 v[180:183], v143 offset:33792
	ds_read_b128 v[184:187], v143 offset:34816
	ds_read_b128 v[188:191], v143 offset:35840
	ds_read_b128 v[192:195], v143 offset:36864
	ds_read_b128 v[196:199], v143 offset:37888
	ds_read_b128 v[200:203], v143 offset:38912
	ds_read_b128 v[204:207], v143 offset:39936
	global_load_lds_dwordx4 v[216:217], off
	v_lshl_add_u64 v[216:217], s[36:37], 0, v[130:131]
	s_mov_b32 m0, s41
	s_nop 0
	global_load_lds_dwordx4 v[216:217], off
	s_waitcnt vmcnt(8)
	s_waitcnt lgkmcnt(0)
	s_barrier
	s_setprio 1
	s_waitcnt lgkmcnt(0)
	v_mfma_f32_16x16x32_bf16 v[124:127], v[144:147], v[176:179], v[124:127]
	v_mfma_f32_16x16x32_bf16 v[120:123], v[152:155], v[176:179], v[120:123]
	v_mfma_f32_16x16x32_bf16 v[108:111], v[144:147], v[184:187], v[108:111]
	v_mfma_f32_16x16x32_bf16 v[104:107], v[152:155], v[184:187], v[104:107]
	v_mfma_f32_16x16x32_bf16 v[92:95], v[144:147], v[192:195], v[92:95]
	v_mfma_f32_16x16x32_bf16 v[88:91], v[152:155], v[192:195], v[88:91]
	v_mfma_f32_16x16x32_bf16 v[76:79], v[144:147], v[200:203], v[76:79]
	v_mfma_f32_16x16x32_bf16 v[72:75], v[152:155], v[200:203], v[72:75]
	v_mfma_f32_16x16x32_bf16 v[124:127], v[148:151], v[180:183], v[124:127]
	v_mfma_f32_16x16x32_bf16 v[120:123], v[156:159], v[180:183], v[120:123]
	v_mfma_f32_16x16x32_bf16 v[108:111], v[148:151], v[188:191], v[108:111]
	v_mfma_f32_16x16x32_bf16 v[104:107], v[156:159], v[188:191], v[104:107]
	v_mfma_f32_16x16x32_bf16 v[92:95], v[148:151], v[196:199], v[92:95]
	v_mfma_f32_16x16x32_bf16 v[88:91], v[156:159], v[196:199], v[88:91]
	v_mfma_f32_16x16x32_bf16 v[76:79], v[148:151], v[204:207], v[76:79]
	v_mfma_f32_16x16x32_bf16 v[72:75], v[156:159], v[204:207], v[72:75]
	s_setprio 0
	s_setprio 1
	v_mfma_f32_16x16x32_bf16 v[116:119], v[160:163], v[176:179], v[116:119]
	v_mfma_f32_16x16x32_bf16 v[112:115], v[168:171], v[176:179], v[112:115]
	v_mfma_f32_16x16x32_bf16 v[100:103], v[160:163], v[184:187], v[100:103]
	v_mfma_f32_16x16x32_bf16 v[96:99], v[168:171], v[184:187], v[96:99]
	v_mfma_f32_16x16x32_bf16 v[84:87], v[160:163], v[192:195], v[84:87]
	v_mfma_f32_16x16x32_bf16 v[80:83], v[168:171], v[192:195], v[80:83]
	v_mfma_f32_16x16x32_bf16 v[68:71], v[160:163], v[200:203], v[68:71]
	v_mfma_f32_16x16x32_bf16 v[64:67], v[168:171], v[200:203], v[64:67]
	v_mfma_f32_16x16x32_bf16 v[116:119], v[164:167], v[180:183], v[116:119]
	v_mfma_f32_16x16x32_bf16 v[112:115], v[172:175], v[180:183], v[112:115]
	v_mfma_f32_16x16x32_bf16 v[100:103], v[164:167], v[188:191], v[100:103]
	v_mfma_f32_16x16x32_bf16 v[96:99], v[172:175], v[188:191], v[96:99]
	v_mfma_f32_16x16x32_bf16 v[84:87], v[164:167], v[196:199], v[84:87]
	v_mfma_f32_16x16x32_bf16 v[80:83], v[172:175], v[196:199], v[80:83]
	v_mfma_f32_16x16x32_bf16 v[68:71], v[164:167], v[204:207], v[68:71]
	v_mfma_f32_16x16x32_bf16 v[64:67], v[172:175], v[204:207], v[64:67]
	s_setprio 0
	s_add_i32 s36, s54, s38
	v_lshl_add_u64 v[208:209], v[208:209], 0, s[2:3]
	s_mov_b32 m0, s36
	s_barrier
; #define G_STAGE(bufoff, gbase, voff) do { _Pragma("unroll") for (int _i = 0; _i < 2; ++_i) \
;         __builtin_amdgcn_global_load_lds((const unsigned*)((const char*)(gbase) + voff[_i]), (LAS unsigned*)(lds + (bufoff) + ldsw + _i * 8192), 16, 0, 0); } while (0)
; #define G_LDA(dst, b, h) do { _Pragma("unroll") for (int m = 0; m < 4; ++m) _Pragma("unroll") for (int k = 0; k < 2; ++k) dst[m][k] = *(const LAS bf16x8*)(lds + G_SA(b, h) + aoff + m * 2048 + k * 1024); } while (0)
; #define G_MMA(ai, bj, At_, Bt_) do { __builtin_amdgcn_s_setprio(1); _Pragma("unroll") for (int m = 0; m < 4; ++m) _Pragma("unroll") for (int n = 0; n < 2; ++n) _Pragma("unroll") for (int k = 0; k < 2; ++k) \
;         acc[ai][bj][m][n] = __builtin_amdgcn_mfma_f32_16x16x32_bf16(Bt_[n][k], At_[m][k], acc[ai][bj][m][n], 0, 0, 0); __builtin_amdgcn_s_setprio(0); } while (0)
; #define WAIT_V(n) asm volatile("s_waitcnt vmcnt(" #n ")" ::: "memory")
; #define WAIT_L(n) asm volatile("s_waitcnt lgkmcnt(" #n ")" ::: "memory")
; #define BAR __builtin_amdgcn_s_barrier()
; #define SCHED __builtin_amdgcn_sched_barrier(0)
; template <class Get, class Epi>
; DI void gemm_loop(int ntiles, int ld, char* shm, const Get& get, const Epi& epi) {
;     ...
;             G_LDA(At, 1, 1); G_STAGE(G_SB(1, 0), b3, voffB); G_STAGE(G_SB(1, 1), b3 + hstep, voffB); G_STAGE(G_SA(1, 0), a3, voffA);
;             WAIT_V(8); WAIT_L(0); BAR; G_MMA(1, 0, At, B0); G_MMA(1, 1, At, B1); BAR; SCHED;
;         }
	ds_read_b128 v[176:179], v143 offset:49152
	ds_read_b128 v[180:183], v143 offset:50176
	ds_read_b128 v[184:187], v143 offset:51200
	ds_read_b128 v[188:191], v143 offset:52224
	ds_read_b128 v[192:195], v143 offset:53248
	ds_read_b128 v[196:199], v143 offset:54272
	ds_read_b128 v[200:203], v143 offset:55296
	ds_read_b128 v[204:207], v143 offset:56320
	global_load_lds_dwordx4 v[208:209], off
	s_add_i32 m0, s36, 0x2000
	s_add_u32 s14, s14, 0x40080
	v_lshl_add_u64 v[208:209], v[210:211], 0, s[2:3]
	s_addc_u32 s15, s15, 0
	s_add_i32 s36, s55, s38
	global_load_lds_dwordx4 v[208:209], off
	v_lshl_add_u64 v[208:209], s[14:15], 0, v[132:133]
	s_mov_b32 m0, s36
	s_nop 0
	global_load_lds_dwordx4 v[208:209], off
	v_lshl_add_u64 v[208:209], s[14:15], 0, v[128:129]
	s_add_i32 m0, s36, 0x2000
	s_nop 0
	global_load_lds_dwordx4 v[208:209], off
	v_lshl_add_u64 v[208:209], v[212:213], 0, s[2:3]
	s_mov_b32 m0, s42
	s_nop 0
	global_load_lds_dwordx4 v[208:209], off
	v_lshl_add_u64 v[208:209], v[214:215], 0, s[2:3]
	s_mov_b32 m0, s43
	s_nop 0
	global_load_lds_dwordx4 v[208:209], off
	s_waitcnt vmcnt(8)
	s_waitcnt lgkmcnt(0)
	s_barrier
	s_setprio 1
	s_waitcnt lgkmcnt(0)
	v_mfma_f32_16x16x32_bf16 v[60:63], v[144:147], v[176:179], v[60:63]
	v_mfma_f32_16x16x32_bf16 v[56:59], v[152:155], v[176:179], v[56:59]
	v_mfma_f32_16x16x32_bf16 v[44:47], v[144:147], v[184:187], v[44:47]
	v_mfma_f32_16x16x32_bf16 v[40:43], v[152:155], v[184:187], v[40:43]
	v_mfma_f32_16x16x32_bf16 v[28:31], v[144:147], v[192:195], v[28:31]
	v_mfma_f32_16x16x32_bf16 v[24:27], v[152:155], v[192:195], v[24:27]
	v_mfma_f32_16x16x32_bf16 v[12:15], v[144:147], v[200:203], v[12:15]
	v_mfma_f32_16x16x32_bf16 v[8:11], v[152:155], v[200:203], v[8:11]
	v_mfma_f32_16x16x32_bf16 v[60:63], v[148:151], v[180:183], v[60:63]
	v_mfma_f32_16x16x32_bf16 v[56:59], v[156:159], v[180:183], v[56:59]
	v_mfma_f32_16x16x32_bf16 v[44:47], v[148:151], v[188:191], v[44:47]
	v_mfma_f32_16x16x32_bf16 v[40:43], v[156:159], v[188:191], v[40:43]
	v_mfma_f32_16x16x32_bf16 v[28:31], v[148:151], v[196:199], v[28:31]
	v_mfma_f32_16x16x32_bf16 v[24:27], v[156:159], v[196:199], v[24:27]
	v_mfma_f32_16x16x32_bf16 v[12:15], v[148:151], v[204:207], v[12:15]
	v_mfma_f32_16x16x32_bf16 v[8:11], v[156:159], v[204:207], v[8:11]
	s_setprio 0
	s_setprio 1
	v_mfma_f32_16x16x32_bf16 v[52:55], v[160:163], v[176:179], v[52:55]
	v_mfma_f32_16x16x32_bf16 v[48:51], v[168:171], v[176:179], v[48:51]
	v_mfma_f32_16x16x32_bf16 v[36:39], v[160:163], v[184:187], v[36:39]
	v_mfma_f32_16x16x32_bf16 v[32:35], v[168:171], v[184:187], v[32:35]
	v_mfma_f32_16x16x32_bf16 v[20:23], v[160:163], v[192:195], v[20:23]
	v_mfma_f32_16x16x32_bf16 v[16:19], v[168:171], v[192:195], v[16:19]
	v_mfma_f32_16x16x32_bf16 v[4:7], v[160:163], v[200:203], v[4:7]
	v_mfma_f32_16x16x32_bf16 v[0:3], v[168:171], v[200:203], v[0:3]
	v_mfma_f32_16x16x32_bf16 v[52:55], v[164:167], v[180:183], v[52:55]
	v_mfma_f32_16x16x32_bf16 v[48:51], v[172:175], v[180:183], v[48:51]
	v_mfma_f32_16x16x32_bf16 v[36:39], v[164:167], v[188:191], v[36:39]
	v_mfma_f32_16x16x32_bf16 v[32:35], v[172:175], v[188:191], v[32:35]
	v_mfma_f32_16x16x32_bf16 v[20:23], v[164:167], v[196:199], v[20:23]
	v_mfma_f32_16x16x32_bf16 v[16:19], v[172:175], v[196:199], v[16:19]
	v_mfma_f32_16x16x32_bf16 v[4:7], v[164:167], v[204:207], v[4:7]
	v_mfma_f32_16x16x32_bf16 v[0:3], v[172:175], v[204:207], v[0:3]
	s_setprio 0
	s_add_i32 s53, s53, 2
	s_add_u32 s34, s34, 0x100
	s_addc_u32 s35, s35, 0
	s_add_u32 s51, s51, 0x100
	s_addc_u32 s52, s52, 0
	s_cmp_gt_u32 s53, 13
	s_barrier
	s_cbranch_scc0 .LBB0_3679

; #define G_STAGE(bufoff, gbase, voff) do { _Pragma("unroll") for (int _i = 0; _i < 2; ++_i) \
;         __builtin_amdgcn_global_load_lds((const unsigned*)((const char*)(gbase) + voff[_i]), (LAS unsigned*)(lds + (bufoff) + ldsw + _i * 8192), 16, 0, 0); } while (0)
; #define G_LDA(dst, b, h) do { _Pragma("unroll") for (int m = 0; m < 4; ++m) _Pragma("unroll") for (int k = 0; k < 2; ++k) dst[m][k] = *(const LAS bf16x8*)(lds + G_SA(b, h) + aoff + m * 2048 + k * 1024); } while (0)
; #define G_LDB(dst, b, h) do { _Pragma("unroll") for (int n = 0; n < 2; ++n) _Pragma("unroll") for (int k = 0; k < 2; ++k) dst[n][k] = *(const LAS bf16x8*)(lds + G_SB(b, h) + boff + n * 2048 + k * 1024); } while (0)
; #define G_MMA(ai, bj, At_, Bt_) do { __builtin_amdgcn_s_setprio(1); _Pragma("unroll") for (int m = 0; m < 4; ++m) _Pragma("unroll") for (int n = 0; n < 2; ++n) _Pragma("unroll") for (int k = 0; k < 2; ++k) \
;         acc[ai][bj][m][n] = __builtin_amdgcn_mfma_f32_16x16x32_bf16(Bt_[n][k], At_[m][k], acc[ai][bj][m][n], 0, 0, 0); __builtin_amdgcn_s_setprio(0); } while (0)
; #define WAIT_V(n) asm volatile("s_waitcnt vmcnt(" #n ")" ::: "memory")
; #define WAIT_L(n) asm volatile("s_waitcnt lgkmcnt(" #n ")" ::: "memory")
; #define BAR __builtin_amdgcn_s_barrier()
; #define SCHED __builtin_amdgcn_sched_barrier(0)
; template <class Get, class Epi>
; DI void gemm_loop(int ntiles, int ld, char* shm, const Get& get, const Epi& epi) {
;     ...
;         for (int t = 0; t < nt; t += 2) {
;             const bool last = (t == nt - 2);
;             const char* a1 = cA + (size_t)(t + 1) * kstep;
;             const char* a2 = last ? nA : cA + (size_t)(t + 2) * kstep; const char* b2 = last ? nB : cB + (size_t)(t + 2) * kstep;
;             const char* a3 = a2 + kstep; const char* b3 = b2 + kstep;
;             G_LDB(B0, 0, 0); G_LDB(B1, 0, 1); SCHED; G_LDA(At, 0, 0); G_STAGE(G_SA(1, 1), a1 + hstep, voffA);
;             WAIT_V(8); WAIT_L(0); BAR; G_MMA(0, 0, At, B0); G_MMA(0, 1, At, B1); BAR; SCHED;
;             G_LDA(At, 0, 1); G_STAGE(G_SB(0, 0), b2, voffB); G_STAGE(G_SB(0, 1), b2 + hstep, voffB); G_STAGE(G_SA(0, 0), a2, voffA);
;             WAIT_V(8); WAIT_L(0); BAR; G_MMA(1, 0, At, B0); G_MMA(1, 1, At, B1); BAR; SCHED;
.Lpeel_3759:
	ds_read_b128 v[128:131], v169
	ds_read_b128 v[132:135], v169 offset:1024
	ds_read_b128 v[136:139], v169 offset:2048
	ds_read_b128 v[140:143], v169 offset:3072
	ds_read_b128 v[158:161], v170
	ds_read_b128 v[162:165], v170 offset:1024
	ds_read_b128 v[172:175], v170 offset:2048
	ds_read_b128 v[176:179], v170 offset:3072
	s_add_u32 s24, s2, 0x100
	s_addc_u32 s25, s3, 0
	s_cmp_eq_u32 s54, 40
	s_cselect_b32 s35, s21, s25
	s_cselect_b32 s34, s20, s24
	s_cselect_b32 s31, s23, s53
	s_cselect_b32 s30, s22, s52
	v_lshl_add_u64 v[144:145], s[2:3], 0, v[154:155]
	s_add_i32 m0, s36, 0xc000
	ds_read_b128 v[180:183], v171
	ds_read_b128 v[184:187], v171 offset:1024
	ds_read_b128 v[188:191], v171 offset:2048
	ds_read_b128 v[192:195], v171 offset:3072
	ds_read_b128 v[196:199], v171 offset:4096
	ds_read_b128 v[200:203], v171 offset:5120
	ds_read_b128 v[204:207], v171 offset:6144
	ds_read_b128 v[208:211], v171 offset:7168
	global_load_lds_dwordx4 v[144:145], off
	v_lshl_add_u64 v[144:145], s[2:3], 0, v[156:157]
	s_add_i32 m0, s36, 0xe000
	s_nop 0
	global_load_lds_dwordx4 v[144:145], off
	s_waitcnt vmcnt(8)
	s_waitcnt lgkmcnt(0)
	s_barrier
	s_setprio 1
	s_waitcnt lgkmcnt(0)
	v_mfma_f32_16x16x32_bf16 v[124:127], v[128:131], v[180:183], 0
	v_mfma_f32_16x16x32_bf16 v[120:123], v[136:139], v[180:183], 0
	v_mfma_f32_16x16x32_bf16 v[116:119], v[128:131], v[188:191], 0
	v_mfma_f32_16x16x32_bf16 v[112:115], v[136:139], v[188:191], 0
	v_mfma_f32_16x16x32_bf16 v[108:111], v[128:131], v[196:199], 0
	v_mfma_f32_16x16x32_bf16 v[104:107], v[136:139], v[196:199], 0
	v_mfma_f32_16x16x32_bf16 v[100:103], v[128:131], v[204:207], 0
	v_mfma_f32_16x16x32_bf16 v[96:99], v[136:139], v[204:207], 0
	v_mfma_f32_16x16x32_bf16 v[124:127], v[132:135], v[184:187], v[124:127]
	v_mfma_f32_16x16x32_bf16 v[120:123], v[140:143], v[184:187], v[120:123]
	v_mfma_f32_16x16x32_bf16 v[116:119], v[132:135], v[192:195], v[116:119]
	v_mfma_f32_16x16x32_bf16 v[112:115], v[140:143], v[192:195], v[112:115]
	v_mfma_f32_16x16x32_bf16 v[108:111], v[132:135], v[200:203], v[108:111]
	v_mfma_f32_16x16x32_bf16 v[104:107], v[140:143], v[200:203], v[104:107]
	v_mfma_f32_16x16x32_bf16 v[100:103], v[132:135], v[208:211], v[100:103]
	v_mfma_f32_16x16x32_bf16 v[96:99], v[140:143], v[208:211], v[96:99]
	s_setprio 0
	s_setprio 1
	v_mfma_f32_16x16x32_bf16 v[60:63], v[158:161], v[180:183], 0
	v_mfma_f32_16x16x32_bf16 v[56:59], v[172:175], v[180:183], 0
	v_mfma_f32_16x16x32_bf16 v[52:55], v[158:161], v[188:191], 0
	v_mfma_f32_16x16x32_bf16 v[48:51], v[172:175], v[188:191], 0
	v_mfma_f32_16x16x32_bf16 v[44:47], v[158:161], v[196:199], 0
	v_mfma_f32_16x16x32_bf16 v[40:43], v[172:175], v[196:199], 0
	v_mfma_f32_16x16x32_bf16 v[36:39], v[158:161], v[204:207], 0
	v_mfma_f32_16x16x32_bf16 v[32:35], v[172:175], v[204:207], 0
	v_mfma_f32_16x16x32_bf16 v[60:63], v[162:165], v[184:187], v[60:63]
	v_mfma_f32_16x16x32_bf16 v[56:59], v[176:179], v[184:187], v[56:59]
	v_mfma_f32_16x16x32_bf16 v[52:55], v[162:165], v[192:195], v[52:55]
	v_mfma_f32_16x16x32_bf16 v[48:51], v[176:179], v[192:195], v[48:51]
	v_mfma_f32_16x16x32_bf16 v[44:47], v[162:165], v[200:203], v[44:47]
	v_mfma_f32_16x16x32_bf16 v[40:43], v[176:179], v[200:203], v[40:43]
	v_mfma_f32_16x16x32_bf16 v[36:39], v[162:165], v[208:211], v[36:39]
	v_mfma_f32_16x16x32_bf16 v[32:35], v[176:179], v[208:211], v[32:35]
	s_setprio 0
	s_add_i32 s2, s44, s33
	v_lshl_add_u64 v[144:145], s[30:31], 0, v[148:149]
	s_mov_b32 m0, s2
	s_barrier
	ds_read_b128 v[180:183], v171 offset:16384
	ds_read_b128 v[184:187], v171 offset:17408
	ds_read_b128 v[188:191], v171 offset:18432
	ds_read_b128 v[192:195], v171 offset:19456
	ds_read_b128 v[196:199], v171 offset:20480
	ds_read_b128 v[200:203], v171 offset:21504
	ds_read_b128 v[204:207], v171 offset:22528
	ds_read_b128 v[208:211], v171 offset:23552
	global_load_lds_dwordx4 v[144:145], off
	s_add_i32 m0, s2, 0x2000
	s_add_u32 s2, s30, 0xb0000
	v_lshl_add_u64 v[166:167], s[30:31], 0, v[152:153]
	s_addc_u32 s3, s31, 0
	s_add_i32 s55, s45, s33
	global_load_lds_dwordx4 v[166:167], off
	v_lshl_add_u64 v[212:213], s[2:3], 0, v[148:149]
	s_mov_b32 m0, s55
	v_lshl_add_u64 v[214:215], s[34:35], 0, v[150:151]
	global_load_lds_dwordx4 v[212:213], off
	v_lshl_add_u64 v[212:213], s[2:3], 0, v[152:153]
	s_add_i32 m0, s55, 0x2000
	s_nop 0
	global_load_lds_dwordx4 v[212:213], off
	v_lshl_add_u64 v[212:213], s[34:35], 0, v[146:147]
	s_mov_b32 m0, s36
	s_nop 0
	global_load_lds_dwordx4 v[212:213], off
	s_mov_b32 m0, s37
	s_nop 0
	global_load_lds_dwordx4 v[214:215], off
	s_waitcnt vmcnt(8)
	s_waitcnt lgkmcnt(0)
	s_barrier
; #define G_STAGE(bufoff, gbase, voff) do { _Pragma("unroll") for (int _i = 0; _i < 2; ++_i) \
;         __builtin_amdgcn_global_load_lds((const unsigned*)((const char*)(gbase) + voff[_i]), (LAS unsigned*)(lds + (bufoff) + ldsw + _i * 8192), 16, 0, 0); } while (0)
; #define G_LDA(dst, b, h) do { _Pragma("unroll") for (int m = 0; m < 4; ++m) _Pragma("unroll") for (int k = 0; k < 2; ++k) dst[m][k] = *(const LAS bf16x8*)(lds + G_SA(b, h) + aoff + m * 2048 + k * 1024); } while (0)
; #define G_LDB(dst, b, h) do { _Pragma("unroll") for (int n = 0; n < 2; ++n) _Pragma("unroll") for (int k = 0; k < 2; ++k) dst[n][k] = *(const LAS bf16x8*)(lds + G_SB(b, h) + boff + n * 2048 + k * 1024); } while (0)
; #define G_MMA(ai, bj, At_, Bt_) do { __builtin_amdgcn_s_setprio(1); _Pragma("unroll") for (int m = 0; m < 4; ++m) _Pragma("unroll") for (int n = 0; n < 2; ++n) _Pragma("unroll") for (int k = 0; k < 2; ++k) \
;         acc[ai][bj][m][n] = __builtin_amdgcn_mfma_f32_16x16x32_bf16(Bt_[n][k], At_[m][k], acc[ai][bj][m][n], 0, 0, 0); __builtin_amdgcn_s_setprio(0); } while (0)
; #define WAIT_V(n) asm volatile("s_waitcnt vmcnt(" #n ")" ::: "memory")
; #define WAIT_L(n) asm volatile("s_waitcnt lgkmcnt(" #n ")" ::: "memory")
; #define BAR __builtin_amdgcn_s_barrier()
; #define SCHED __builtin_amdgcn_sched_barrier(0)
; template <class Get, class Epi>
; DI void gemm_loop(int ntiles, int ld, char* shm, const Get& get, const Epi& epi) {
;     ...
;             G_LDA(At, 0, 1); G_STAGE(G_SB(0, 0), b2, voffB); G_STAGE(G_SB(0, 1), b2 + hstep, voffB); G_STAGE(G_SA(0, 0), a2, voffA);
;             WAIT_V(8); WAIT_L(0); BAR; G_MMA(1, 0, At, B0); G_MMA(1, 1, At, B1); BAR; SCHED;
;             G_LDB(B0, 1, 0); G_LDB(B1, 1, 1); SCHED; G_LDA(At, 1, 0); G_STAGE(G_SA(0, 1), a2 + hstep, voffA);
;             WAIT_V(8); WAIT_L(0); BAR; G_MMA(0, 0, At, B0); G_MMA(0, 1, At, B1); BAR; SCHED;
;             G_LDA(At, 1, 1); G_STAGE(G_SB(1, 0), b3, voffB); G_STAGE(G_SB(1, 1), b3 + hstep, voffB); G_STAGE(G_SA(1, 0), a3, voffA);
	s_setprio 1
	s_waitcnt lgkmcnt(0)
	v_mfma_f32_16x16x32_bf16 v[92:95], v[128:131], v[180:183], 0
	v_mfma_f32_16x16x32_bf16 v[88:91], v[136:139], v[180:183], 0
	v_mfma_f32_16x16x32_bf16 v[84:87], v[128:131], v[188:191], 0
	v_mfma_f32_16x16x32_bf16 v[80:83], v[136:139], v[188:191], 0
	v_mfma_f32_16x16x32_bf16 v[76:79], v[128:131], v[196:199], 0
	v_mfma_f32_16x16x32_bf16 v[72:75], v[136:139], v[196:199], 0
	v_mfma_f32_16x16x32_bf16 v[68:71], v[128:131], v[204:207], 0
	v_mfma_f32_16x16x32_bf16 v[64:67], v[136:139], v[204:207], 0
	v_mfma_f32_16x16x32_bf16 v[92:95], v[132:135], v[184:187], v[92:95]
	v_mfma_f32_16x16x32_bf16 v[88:91], v[140:143], v[184:187], v[88:91]
	v_mfma_f32_16x16x32_bf16 v[84:87], v[132:135], v[192:195], v[84:87]
	v_mfma_f32_16x16x32_bf16 v[80:83], v[140:143], v[192:195], v[80:83]
	v_mfma_f32_16x16x32_bf16 v[76:79], v[132:135], v[200:203], v[76:79]
	v_mfma_f32_16x16x32_bf16 v[72:75], v[140:143], v[200:203], v[72:75]
	v_mfma_f32_16x16x32_bf16 v[68:71], v[132:135], v[208:211], v[68:71]
	v_mfma_f32_16x16x32_bf16 v[64:67], v[140:143], v[208:211], v[64:67]
	s_setprio 0
	s_setprio 1
	v_mfma_f32_16x16x32_bf16 v[28:31], v[158:161], v[180:183], 0
	v_mfma_f32_16x16x32_bf16 v[24:27], v[172:175], v[180:183], 0
	v_mfma_f32_16x16x32_bf16 v[20:23], v[158:161], v[188:191], 0
	v_mfma_f32_16x16x32_bf16 v[16:19], v[172:175], v[188:191], 0
	v_mfma_f32_16x16x32_bf16 v[12:15], v[158:161], v[196:199], 0
	v_mfma_f32_16x16x32_bf16 v[8:11], v[172:175], v[196:199], 0
	v_mfma_f32_16x16x32_bf16 v[4:7], v[158:161], v[204:207], 0
	v_mfma_f32_16x16x32_bf16 v[0:3], v[172:175], v[204:207], 0
	v_mfma_f32_16x16x32_bf16 v[28:31], v[162:165], v[184:187], v[28:31]
	v_mfma_f32_16x16x32_bf16 v[24:27], v[176:179], v[184:187], v[24:27]
	v_mfma_f32_16x16x32_bf16 v[20:23], v[162:165], v[192:195], v[20:23]
	v_mfma_f32_16x16x32_bf16 v[16:19], v[176:179], v[192:195], v[16:19]
	v_mfma_f32_16x16x32_bf16 v[12:15], v[162:165], v[200:203], v[12:15]
	v_mfma_f32_16x16x32_bf16 v[8:11], v[176:179], v[200:203], v[8:11]
	v_mfma_f32_16x16x32_bf16 v[4:7], v[162:165], v[208:211], v[4:7]
	v_mfma_f32_16x16x32_bf16 v[0:3], v[176:179], v[208:211], v[0:3]
	s_setprio 0
	s_add_i32 s55, 0, 0x18000
	s_add_i32 s56, 0, 0x1c000
	v_add_u32_e32 v140, s55, v168
	s_barrier
	v_add_u32_e32 v176, s56, v168
	ds_read_b128 v[128:131], v140
	ds_read_b128 v[132:135], v140 offset:1024
	ds_read_b128 v[136:139], v140 offset:2048
	ds_read_b128 v[140:143], v140 offset:3072
	ds_read_b128 v[158:161], v176
	ds_read_b128 v[162:165], v176 offset:1024
	ds_read_b128 v[172:175], v176 offset:2048
	ds_read_b128 v[176:179], v176 offset:3072
	s_add_u32 s2, s34, 0xb0000
	s_addc_u32 s3, s35, 0
	s_mov_b32 m0, s38
	v_lshl_add_u64 v[216:217], s[2:3], 0, v[146:147]
	ds_read_b128 v[180:183], v171 offset:32768
	ds_read_b128 v[184:187], v171 offset:33792
	ds_read_b128 v[188:191], v171 offset:34816
	ds_read_b128 v[192:195], v171 offset:35840
	ds_read_b128 v[196:199], v171 offset:36864
	ds_read_b128 v[200:203], v171 offset:37888
	ds_read_b128 v[204:207], v171 offset:38912
	ds_read_b128 v[208:211], v171 offset:39936
	global_load_lds_dwordx4 v[216:217], off
	v_lshl_add_u64 v[216:217], s[2:3], 0, v[150:151]
	s_mov_b32 m0, s39
	s_nop 0
	global_load_lds_dwordx4 v[216:217], off
	s_waitcnt vmcnt(8)
	s_waitcnt lgkmcnt(0)
	s_barrier
	s_setprio 1
	s_waitcnt lgkmcnt(0)
	v_mfma_f32_16x16x32_bf16 v[124:127], v[128:131], v[180:183], v[124:127]
	v_mfma_f32_16x16x32_bf16 v[120:123], v[136:139], v[180:183], v[120:123]
	v_mfma_f32_16x16x32_bf16 v[116:119], v[128:131], v[188:191], v[116:119]
	v_mfma_f32_16x16x32_bf16 v[112:115], v[136:139], v[188:191], v[112:115]
	v_mfma_f32_16x16x32_bf16 v[108:111], v[128:131], v[196:199], v[108:111]
	v_mfma_f32_16x16x32_bf16 v[104:107], v[136:139], v[196:199], v[104:107]
	v_mfma_f32_16x16x32_bf16 v[100:103], v[128:131], v[204:207], v[100:103]
	v_mfma_f32_16x16x32_bf16 v[96:99], v[136:139], v[204:207], v[96:99]
	v_mfma_f32_16x16x32_bf16 v[124:127], v[132:135], v[184:187], v[124:127]
	v_mfma_f32_16x16x32_bf16 v[120:123], v[140:143], v[184:187], v[120:123]
	v_mfma_f32_16x16x32_bf16 v[116:119], v[132:135], v[192:195], v[116:119]
	v_mfma_f32_16x16x32_bf16 v[112:115], v[140:143], v[192:195], v[112:115]
	v_mfma_f32_16x16x32_bf16 v[108:111], v[132:135], v[200:203], v[108:111]
	v_mfma_f32_16x16x32_bf16 v[104:107], v[140:143], v[200:203], v[104:107]
	v_mfma_f32_16x16x32_bf16 v[100:103], v[132:135], v[208:211], v[100:103]
	v_mfma_f32_16x16x32_bf16 v[96:99], v[140:143], v[208:211], v[96:99]
	s_setprio 0
	s_setprio 1
	v_mfma_f32_16x16x32_bf16 v[60:63], v[158:161], v[180:183], v[60:63]
	v_mfma_f32_16x16x32_bf16 v[56:59], v[172:175], v[180:183], v[56:59]
	v_mfma_f32_16x16x32_bf16 v[52:55], v[158:161], v[188:191], v[52:55]
	v_mfma_f32_16x16x32_bf16 v[48:51], v[172:175], v[188:191], v[48:51]
	v_mfma_f32_16x16x32_bf16 v[44:47], v[158:161], v[196:199], v[44:47]
	v_mfma_f32_16x16x32_bf16 v[40:43], v[172:175], v[196:199], v[40:43]
	v_mfma_f32_16x16x32_bf16 v[36:39], v[158:161], v[204:207], v[36:39]
	v_mfma_f32_16x16x32_bf16 v[32:35], v[172:175], v[204:207], v[32:35]
	v_mfma_f32_16x16x32_bf16 v[60:63], v[162:165], v[184:187], v[60:63]
	v_mfma_f32_16x16x32_bf16 v[56:59], v[176:179], v[184:187], v[56:59]
	v_mfma_f32_16x16x32_bf16 v[52:55], v[162:165], v[192:195], v[52:55]
	v_mfma_f32_16x16x32_bf16 v[48:51], v[176:179], v[192:195], v[48:51]
	v_mfma_f32_16x16x32_bf16 v[44:47], v[162:165], v[200:203], v[44:47]
	v_mfma_f32_16x16x32_bf16 v[40:43], v[176:179], v[200:203], v[40:43]
	v_mfma_f32_16x16x32_bf16 v[36:39], v[162:165], v[208:211], v[36:39]
	v_mfma_f32_16x16x32_bf16 v[32:35], v[176:179], v[208:211], v[32:35]
	s_setprio 0
	s_add_i32 s2, s55, s33
	v_lshl_add_u64 v[144:145], v[144:145], 0, s[6:7]
	s_mov_b32 m0, s2
	s_barrier
; #define G_STAGE(bufoff, gbase, voff) do { _Pragma("unroll") for (int _i = 0; _i < 2; ++_i) \
;         __builtin_amdgcn_global_load_lds((const unsigned*)((const char*)(gbase) + voff[_i]), (LAS unsigned*)(lds + (bufoff) + ldsw + _i * 8192), 16, 0, 0); } while (0)
; #define G_LDA(dst, b, h) do { _Pragma("unroll") for (int m = 0; m < 4; ++m) _Pragma("unroll") for (int k = 0; k < 2; ++k) dst[m][k] = *(const LAS bf16x8*)(lds + G_SA(b, h) + aoff + m * 2048 + k * 1024); } while (0)
; #define G_LDB(dst, b, h) do { _Pragma("unroll") for (int n = 0; n < 2; ++n) _Pragma("unroll") for (int k = 0; k < 2; ++k) dst[n][k] = *(const LAS bf16x8*)(lds + G_SB(b, h) + boff + n * 2048 + k * 1024); } while (0)
; #define WAIT_V(n) asm volatile("s_waitcnt vmcnt(" #n ")" ::: "memory")
; #define WAIT_L(n) asm volatile("s_waitcnt lgkmcnt(" #n ")" ::: "memory")
; #define BAR __builtin_amdgcn_s_barrier()
; #define SCHED __builtin_amdgcn_sched_barrier(0)
; template <class Get, class Epi>
; DI void gemm_loop(int ntiles, int ld, char* shm, const Get& get, const Epi& epi) {
;     ...
;         for (int t = 0; t < nt; t += 2) {
;             const bool last = (t == nt - 2);
;             const char* a1 = cA + (size_t)(t + 1) * kstep;
;             const char* a2 = last ? nA : cA + (size_t)(t + 2) * kstep; const char* b2 = last ? nB : cB + (size_t)(t + 2) * kstep;
;             const char* a3 = a2 + kstep; const char* b3 = b2 + kstep;
;             G_LDB(B0, 0, 0); G_LDB(B1, 0, 1); SCHED; G_LDA(At, 0, 0); G_STAGE(G_SA(1, 1), a1 + hstep, voffA);
;             WAIT_V(8); WAIT_L(0); BAR; G_MMA(0, 0, At, B0); G_MMA(0, 1, At, B1); BAR; SCHED;
;             G_LDA(At, 0, 1); G_STAGE(G_SB(0, 0), b2, voffB); G_STAGE(G_SB(0, 1), b2 + hstep, voffB); G_STAGE(G_SA(0, 0), a2, voffA);
;             WAIT_V(8); WAIT_L(0); BAR; G_MMA(1, 0, At, B0); G_MMA(1, 1, At, B1); BAR; SCHED;
;             G_LDB(B0, 1, 0); G_LDB(B1, 1, 1); SCHED; G_LDA(At, 1, 0); G_STAGE(G_SA(0, 1), a2 + hstep, voffA);
;             WAIT_V(8); WAIT_L(0); BAR; G_MMA(0, 0, At, B0); G_MMA(0, 1, At, B1); BAR; SCHED;
;             G_LDA(At, 1, 1); G_STAGE(G_SB(1, 0), b3, voffB); G_STAGE(G_SB(1, 1), b3 + hstep, voffB); G_STAGE(G_SA(1, 0), a3, voffA);
;             WAIT_V(8); WAIT_L(0); BAR; G_MMA(1, 0, At, B0); G_MMA(1, 1, At, B1); BAR; SCHED;
	ds_read_b128 v[180:183], v171 offset:49152
	ds_read_b128 v[184:187], v171 offset:50176
	ds_read_b128 v[188:191], v171 offset:51200
	ds_read_b128 v[192:195], v171 offset:52224
	ds_read_b128 v[196:199], v171 offset:53248
	ds_read_b128 v[200:203], v171 offset:54272
	ds_read_b128 v[204:207], v171 offset:55296
	ds_read_b128 v[208:211], v171 offset:56320
	global_load_lds_dwordx4 v[144:145], off
	s_add_i32 m0, s2, 0x2000
	s_add_u32 s2, s30, 0xb0080
	v_lshl_add_u64 v[144:145], v[166:167], 0, s[6:7]
	s_addc_u32 s3, s31, 0
	s_add_i32 s30, s56, s33
	global_load_lds_dwordx4 v[144:145], off
	v_lshl_add_u64 v[144:145], s[2:3], 0, v[148:149]
	s_mov_b32 m0, s30
	s_nop 0
	global_load_lds_dwordx4 v[144:145], off
	v_lshl_add_u64 v[144:145], s[2:3], 0, v[152:153]
	s_add_i32 m0, s30, 0x2000
	s_nop 0
	global_load_lds_dwordx4 v[144:145], off
	v_lshl_add_u64 v[144:145], v[212:213], 0, s[6:7]
	s_mov_b32 m0, s42
	s_nop 0
	global_load_lds_dwordx4 v[144:145], off
	v_lshl_add_u64 v[144:145], v[214:215], 0, s[6:7]
	s_mov_b32 m0, s43
	s_nop 0
	global_load_lds_dwordx4 v[144:145], off
	s_waitcnt vmcnt(8)
	s_waitcnt lgkmcnt(0)
	s_barrier
	s_setprio 1
	s_waitcnt lgkmcnt(0)
	v_mfma_f32_16x16x32_bf16 v[92:95], v[128:131], v[180:183], v[92:95]
	v_mfma_f32_16x16x32_bf16 v[88:91], v[136:139], v[180:183], v[88:91]
	v_mfma_f32_16x16x32_bf16 v[84:87], v[128:131], v[188:191], v[84:87]
	v_mfma_f32_16x16x32_bf16 v[80:83], v[136:139], v[188:191], v[80:83]
	v_mfma_f32_16x16x32_bf16 v[76:79], v[128:131], v[196:199], v[76:79]
	v_mfma_f32_16x16x32_bf16 v[72:75], v[136:139], v[196:199], v[72:75]
	v_mfma_f32_16x16x32_bf16 v[68:71], v[128:131], v[204:207], v[68:71]
	v_mfma_f32_16x16x32_bf16 v[64:67], v[136:139], v[204:207], v[64:67]
	v_mfma_f32_16x16x32_bf16 v[92:95], v[132:135], v[184:187], v[92:95]
	v_mfma_f32_16x16x32_bf16 v[88:91], v[140:143], v[184:187], v[88:91]
	v_mfma_f32_16x16x32_bf16 v[84:87], v[132:135], v[192:195], v[84:87]
	v_mfma_f32_16x16x32_bf16 v[80:83], v[140:143], v[192:195], v[80:83]
	v_mfma_f32_16x16x32_bf16 v[76:79], v[132:135], v[200:203], v[76:79]
	v_mfma_f32_16x16x32_bf16 v[72:75], v[140:143], v[200:203], v[72:75]
	v_mfma_f32_16x16x32_bf16 v[68:71], v[132:135], v[208:211], v[68:71]
	v_mfma_f32_16x16x32_bf16 v[64:67], v[140:143], v[208:211], v[64:67]
	s_setprio 0
	s_setprio 1
	v_mfma_f32_16x16x32_bf16 v[28:31], v[158:161], v[180:183], v[28:31]
	v_mfma_f32_16x16x32_bf16 v[24:27], v[172:175], v[180:183], v[24:27]
	v_mfma_f32_16x16x32_bf16 v[20:23], v[158:161], v[188:191], v[20:23]
	v_mfma_f32_16x16x32_bf16 v[16:19], v[172:175], v[188:191], v[16:19]
	v_mfma_f32_16x16x32_bf16 v[12:15], v[158:161], v[196:199], v[12:15]
	v_mfma_f32_16x16x32_bf16 v[8:11], v[172:175], v[196:199], v[8:11]
	v_mfma_f32_16x16x32_bf16 v[4:7], v[158:161], v[204:207], v[4:7]
	v_mfma_f32_16x16x32_bf16 v[0:3], v[172:175], v[204:207], v[0:3]
	v_mfma_f32_16x16x32_bf16 v[28:31], v[162:165], v[184:187], v[28:31]
	v_mfma_f32_16x16x32_bf16 v[24:27], v[176:179], v[184:187], v[24:27]
	v_mfma_f32_16x16x32_bf16 v[20:23], v[162:165], v[192:195], v[20:23]
	v_mfma_f32_16x16x32_bf16 v[16:19], v[176:179], v[192:195], v[16:19]
	v_mfma_f32_16x16x32_bf16 v[12:15], v[162:165], v[200:203], v[12:15]
	v_mfma_f32_16x16x32_bf16 v[8:11], v[176:179], v[200:203], v[8:11]
	v_mfma_f32_16x16x32_bf16 v[4:7], v[162:165], v[208:211], v[4:7]
	v_mfma_f32_16x16x32_bf16 v[0:3], v[176:179], v[208:211], v[0:3]
	s_setprio 0
	s_add_i32 s54, s54, 2
	s_add_u32 s52, s52, 0x100
	s_addc_u32 s53, s53, 0
	s_cmp_gt_u32 s54, 41
	s_mov_b64 s[2:3], s[24:25]
	s_barrier
	s_cbranch_scc0 .LBB0_3759
	s_branch .Lpost_3759
.LBB0_3759:
	ds_read_b128 v[128:131], v169
	ds_read_b128 v[132:135], v169 offset:1024
	ds_read_b128 v[136:139], v169 offset:2048
	ds_read_b128 v[140:143], v169 offset:3072
	ds_read_b128 v[158:161], v170
	ds_read_b128 v[162:165], v170 offset:1024
	ds_read_b128 v[172:175], v170 offset:2048
	ds_read_b128 v[176:179], v170 offset:3072
	s_add_u32 s24, s2, 0x100
	s_addc_u32 s25, s3, 0
	s_cmp_eq_u32 s54, 40
	s_cselect_b32 s35, s21, s25
	s_cselect_b32 s34, s20, s24
	s_cselect_b32 s31, s23, s53
	s_cselect_b32 s30, s22, s52
	v_lshl_add_u64 v[144:145], s[2:3], 0, v[154:155]
	s_add_i32 m0, s36, 0xc000
	ds_read_b128 v[180:183], v171
	ds_read_b128 v[184:187], v171 offset:1024
	ds_read_b128 v[188:191], v171 offset:2048
	ds_read_b128 v[192:195], v171 offset:3072
	ds_read_b128 v[196:199], v171 offset:4096
	ds_read_b128 v[200:203], v171 offset:5120
	ds_read_b128 v[204:207], v171 offset:6144
	ds_read_b128 v[208:211], v171 offset:7168
	global_load_lds_dwordx4 v[144:145], off
	v_lshl_add_u64 v[144:145], s[2:3], 0, v[156:157]
	s_add_i32 m0, s36, 0xe000
	s_nop 0
	global_load_lds_dwordx4 v[144:145], off
	s_waitcnt vmcnt(8)
	s_waitcnt lgkmcnt(0)
	s_barrier
; #define G_STAGE(bufoff, gbase, voff) do { _Pragma("unroll") for (int _i = 0; _i < 2; ++_i) \
;         __builtin_amdgcn_global_load_lds((const unsigned*)((const char*)(gbase) + voff[_i]), (LAS unsigned*)(lds + (bufoff) + ldsw + _i * 8192), 16, 0, 0); } while (0)
; #define G_LDA(dst, b, h) do { _Pragma("unroll") for (int m = 0; m < 4; ++m) _Pragma("unroll") for (int k = 0; k < 2; ++k) dst[m][k] = *(const LAS bf16x8*)(lds + G_SA(b, h) + aoff + m * 2048 + k * 1024); } while (0)
; #define G_LDB(dst, b, h) do { _Pragma("unroll") for (int n = 0; n < 2; ++n) _Pragma("unroll") for (int k = 0; k < 2; ++k) dst[n][k] = *(const LAS bf16x8*)(lds + G_SB(b, h) + boff + n * 2048 + k * 1024); } while (0)
; #define G_MMA(ai, bj, At_, Bt_) do { __builtin_amdgcn_s_setprio(1); _Pragma("unroll") for (int m = 0; m < 4; ++m) _Pragma("unroll") for (int n = 0; n < 2; ++n) _Pragma("unroll") for (int k = 0; k < 2; ++k) \
;         acc[ai][bj][m][n] = __builtin_amdgcn_mfma_f32_16x16x32_bf16(Bt_[n][k], At_[m][k], acc[ai][bj][m][n], 0, 0, 0); __builtin_amdgcn_s_setprio(0); } while (0)
; #define WAIT_V(n) asm volatile("s_waitcnt vmcnt(" #n ")" ::: "memory")
; #define WAIT_L(n) asm volatile("s_waitcnt lgkmcnt(" #n ")" ::: "memory")
; #define BAR __builtin_amdgcn_s_barrier()
; #define SCHED __builtin_amdgcn_sched_barrier(0)
; template <class Get, class Epi>
; DI void gemm_loop(int ntiles, int ld, char* shm, const Get& get, const Epi& epi) {
;     ...
;             G_LDB(B0, 0, 0); G_LDB(B1, 0, 1); SCHED; G_LDA(At, 0, 0); G_STAGE(G_SA(1, 1), a1 + hstep, voffA);
;             WAIT_V(8); WAIT_L(0); BAR; G_MMA(0, 0, At, B0); G_MMA(0, 1, At, B1); BAR; SCHED;
;             G_LDA(At, 0, 1); G_STAGE(G_SB(0, 0), b2, voffB); G_STAGE(G_SB(0, 1), b2 + hstep, voffB); G_STAGE(G_SA(0, 0), a2, voffA);
;             WAIT_V(8); WAIT_L(0); BAR; G_MMA(1, 0, At, B0); G_MMA(1, 1, At, B1); BAR; SCHED;
;             G_LDB(B0, 1, 0); G_LDB(B1, 1, 1); SCHED; G_LDA(At, 1, 0); G_STAGE(G_SA(0, 1), a2 + hstep, voffA);
;             WAIT_V(8); WAIT_L(0); BAR; G_MMA(0, 0, At, B0); G_MMA(0, 1, At, B1); BAR; SCHED;
;             G_LDA(At, 1, 1); G_STAGE(G_SB(1, 0), b3, voffB); G_STAGE(G_SB(1, 1), b3 + hstep, voffB); G_STAGE(G_SA(1, 0), a3, voffA);
;             WAIT_V(8); WAIT_L(0); BAR; G_MMA(1, 0, At, B0); G_MMA(1, 1, At, B1); BAR; SCHED;
	s_setprio 1
	s_waitcnt lgkmcnt(0)
	v_mfma_f32_16x16x32_bf16 v[124:127], v[128:131], v[180:183], v[124:127]
	v_mfma_f32_16x16x32_bf16 v[120:123], v[136:139], v[180:183], v[120:123]
	v_mfma_f32_16x16x32_bf16 v[116:119], v[128:131], v[188:191], v[116:119]
	v_mfma_f32_16x16x32_bf16 v[112:115], v[136:139], v[188:191], v[112:115]
	v_mfma_f32_16x16x32_bf16 v[108:111], v[128:131], v[196:199], v[108:111]
	v_mfma_f32_16x16x32_bf16 v[104:107], v[136:139], v[196:199], v[104:107]
	v_mfma_f32_16x16x32_bf16 v[100:103], v[128:131], v[204:207], v[100:103]
	v_mfma_f32_16x16x32_bf16 v[96:99], v[136:139], v[204:207], v[96:99]
	v_mfma_f32_16x16x32_bf16 v[124:127], v[132:135], v[184:187], v[124:127]
	v_mfma_f32_16x16x32_bf16 v[120:123], v[140:143], v[184:187], v[120:123]
	v_mfma_f32_16x16x32_bf16 v[116:119], v[132:135], v[192:195], v[116:119]
	v_mfma_f32_16x16x32_bf16 v[112:115], v[140:143], v[192:195], v[112:115]
	v_mfma_f32_16x16x32_bf16 v[108:111], v[132:135], v[200:203], v[108:111]
	v_mfma_f32_16x16x32_bf16 v[104:107], v[140:143], v[200:203], v[104:107]
	v_mfma_f32_16x16x32_bf16 v[100:103], v[132:135], v[208:211], v[100:103]
	v_mfma_f32_16x16x32_bf16 v[96:99], v[140:143], v[208:211], v[96:99]
	s_setprio 0
	s_setprio 1
	v_mfma_f32_16x16x32_bf16 v[60:63], v[158:161], v[180:183], v[60:63]
	v_mfma_f32_16x16x32_bf16 v[56:59], v[172:175], v[180:183], v[56:59]
	v_mfma_f32_16x16x32_bf16 v[52:55], v[158:161], v[188:191], v[52:55]
	v_mfma_f32_16x16x32_bf16 v[48:51], v[172:175], v[188:191], v[48:51]
	v_mfma_f32_16x16x32_bf16 v[44:47], v[158:161], v[196:199], v[44:47]
	v_mfma_f32_16x16x32_bf16 v[40:43], v[172:175], v[196:199], v[40:43]
	v_mfma_f32_16x16x32_bf16 v[36:39], v[158:161], v[204:207], v[36:39]
	v_mfma_f32_16x16x32_bf16 v[32:35], v[172:175], v[204:207], v[32:35]
	v_mfma_f32_16x16x32_bf16 v[60:63], v[162:165], v[184:187], v[60:63]
	v_mfma_f32_16x16x32_bf16 v[56:59], v[176:179], v[184:187], v[56:59]
	v_mfma_f32_16x16x32_bf16 v[52:55], v[162:165], v[192:195], v[52:55]
	v_mfma_f32_16x16x32_bf16 v[48:51], v[176:179], v[192:195], v[48:51]
	v_mfma_f32_16x16x32_bf16 v[44:47], v[162:165], v[200:203], v[44:47]
	v_mfma_f32_16x16x32_bf16 v[40:43], v[176:179], v[200:203], v[40:43]
	v_mfma_f32_16x16x32_bf16 v[36:39], v[162:165], v[208:211], v[36:39]
	v_mfma_f32_16x16x32_bf16 v[32:35], v[176:179], v[208:211], v[32:35]
	s_setprio 0
	s_add_i32 s2, s44, s33
	v_lshl_add_u64 v[144:145], s[30:31], 0, v[148:149]
	s_mov_b32 m0, s2
	s_barrier
	ds_read_b128 v[180:183], v171 offset:16384
	ds_read_b128 v[184:187], v171 offset:17408
	ds_read_b128 v[188:191], v171 offset:18432
	ds_read_b128 v[192:195], v171 offset:19456
	ds_read_b128 v[196:199], v171 offset:20480
	ds_read_b128 v[200:203], v171 offset:21504
	ds_read_b128 v[204:207], v171 offset:22528
	ds_read_b128 v[208:211], v171 offset:23552
	global_load_lds_dwordx4 v[144:145], off
	s_add_i32 m0, s2, 0x2000
	s_add_u32 s2, s30, 0xb0000
	v_lshl_add_u64 v[166:167], s[30:31], 0, v[152:153]
	s_addc_u32 s3, s31, 0
	s_add_i32 s55, s45, s33
	global_load_lds_dwordx4 v[166:167], off
	v_lshl_add_u64 v[212:213], s[2:3], 0, v[148:149]
	s_mov_b32 m0, s55
	v_lshl_add_u64 v[214:215], s[34:35], 0, v[150:151]
	global_load_lds_dwordx4 v[212:213], off
	v_lshl_add_u64 v[212:213], s[2:3], 0, v[152:153]
	s_add_i32 m0, s55, 0x2000
	s_nop 0
	global_load_lds_dwordx4 v[212:213], off
	v_lshl_add_u64 v[212:213], s[34:35], 0, v[146:147]
	s_mov_b32 m0, s36
	s_nop 0
	global_load_lds_dwordx4 v[212:213], off
	s_mov_b32 m0, s37
	s_nop 0
	global_load_lds_dwordx4 v[214:215], off
	s_waitcnt vmcnt(8)
	s_waitcnt lgkmcnt(0)
	s_barrier
	s_setprio 1
	s_waitcnt lgkmcnt(0)
	v_mfma_f32_16x16x32_bf16 v[92:95], v[128:131], v[180:183], v[92:95]
	v_mfma_f32_16x16x32_bf16 v[88:91], v[136:139], v[180:183], v[88:91]
	v_mfma_f32_16x16x32_bf16 v[84:87], v[128:131], v[188:191], v[84:87]
	v_mfma_f32_16x16x32_bf16 v[80:83], v[136:139], v[188:191], v[80:83]
	v_mfma_f32_16x16x32_bf16 v[76:79], v[128:131], v[196:199], v[76:79]
	v_mfma_f32_16x16x32_bf16 v[72:75], v[136:139], v[196:199], v[72:75]
	v_mfma_f32_16x16x32_bf16 v[68:71], v[128:131], v[204:207], v[68:71]
	v_mfma_f32_16x16x32_bf16 v[64:67], v[136:139], v[204:207], v[64:67]
	v_mfma_f32_16x16x32_bf16 v[92:95], v[132:135], v[184:187], v[92:95]
	v_mfma_f32_16x16x32_bf16 v[88:91], v[140:143], v[184:187], v[88:91]
	v_mfma_f32_16x16x32_bf16 v[84:87], v[132:135], v[192:195], v[84:87]
	v_mfma_f32_16x16x32_bf16 v[80:83], v[140:143], v[192:195], v[80:83]
	v_mfma_f32_16x16x32_bf16 v[76:79], v[132:135], v[200:203], v[76:79]
	v_mfma_f32_16x16x32_bf16 v[72:75], v[140:143], v[200:203], v[72:75]
	v_mfma_f32_16x16x32_bf16 v[68:71], v[132:135], v[208:211], v[68:71]
	v_mfma_f32_16x16x32_bf16 v[64:67], v[140:143], v[208:211], v[64:67]
	s_setprio 0
	s_setprio 1
	v_mfma_f32_16x16x32_bf16 v[28:31], v[158:161], v[180:183], v[28:31]
	v_mfma_f32_16x16x32_bf16 v[24:27], v[172:175], v[180:183], v[24:27]
	v_mfma_f32_16x16x32_bf16 v[20:23], v[158:161], v[188:191], v[20:23]
	v_mfma_f32_16x16x32_bf16 v[16:19], v[172:175], v[188:191], v[16:19]
	v_mfma_f32_16x16x32_bf16 v[12:15], v[158:161], v[196:199], v[12:15]
	v_mfma_f32_16x16x32_bf16 v[8:11], v[172:175], v[196:199], v[8:11]
	v_mfma_f32_16x16x32_bf16 v[4:7], v[158:161], v[204:207], v[4:7]
	v_mfma_f32_16x16x32_bf16 v[0:3], v[172:175], v[204:207], v[0:3]
	v_mfma_f32_16x16x32_bf16 v[28:31], v[162:165], v[184:187], v[28:31]
	v_mfma_f32_16x16x32_bf16 v[24:27], v[176:179], v[184:187], v[24:27]
	v_mfma_f32_16x16x32_bf16 v[20:23], v[162:165], v[192:195], v[20:23]
	v_mfma_f32_16x16x32_bf16 v[16:19], v[176:179], v[192:195], v[16:19]
	v_mfma_f32_16x16x32_bf16 v[12:15], v[162:165], v[200:203], v[12:15]
	v_mfma_f32_16x16x32_bf16 v[8:11], v[176:179], v[200:203], v[8:11]
	v_mfma_f32_16x16x32_bf16 v[4:7], v[162:165], v[208:211], v[4:7]
	v_mfma_f32_16x16x32_bf16 v[0:3], v[176:179], v[208:211], v[0:3]
	s_setprio 0
	s_add_i32 s55, 0, 0x18000
	s_add_i32 s56, 0, 0x1c000
	v_add_u32_e32 v140, s55, v168
	s_barrier
; #define G_STAGE(bufoff, gbase, voff) do { _Pragma("unroll") for (int _i = 0; _i < 2; ++_i) \
;         __builtin_amdgcn_global_load_lds((const unsigned*)((const char*)(gbase) + voff[_i]), (LAS unsigned*)(lds + (bufoff) + ldsw + _i * 8192), 16, 0, 0); } while (0)
; #define G_LDA(dst, b, h) do { _Pragma("unroll") for (int m = 0; m < 4; ++m) _Pragma("unroll") for (int k = 0; k < 2; ++k) dst[m][k] = *(const LAS bf16x8*)(lds + G_SA(b, h) + aoff + m * 2048 + k * 1024); } while (0)
; #define G_LDB(dst, b, h) do { _Pragma("unroll") for (int n = 0; n < 2; ++n) _Pragma("unroll") for (int k = 0; k < 2; ++k) dst[n][k] = *(const LAS bf16x8*)(lds + G_SB(b, h) + boff + n * 2048 + k * 1024); } while (0)
; #define G_MMA(ai, bj, At_, Bt_) do { __builtin_amdgcn_s_setprio(1); _Pragma("unroll") for (int m = 0; m < 4; ++m) _Pragma("unroll") for (int n = 0; n < 2; ++n) _Pragma("unroll") for (int k = 0; k < 2; ++k) \
;         acc[ai][bj][m][n] = __builtin_amdgcn_mfma_f32_16x16x32_bf16(Bt_[n][k], At_[m][k], acc[ai][bj][m][n], 0, 0, 0); __builtin_amdgcn_s_setprio(0); } while (0)
; #define WAIT_V(n) asm volatile("s_waitcnt vmcnt(" #n ")" ::: "memory")
; #define WAIT_L(n) asm volatile("s_waitcnt lgkmcnt(" #n ")" ::: "memory")
; #define BAR __builtin_amdgcn_s_barrier()
; #define SCHED __builtin_amdgcn_sched_barrier(0)
; template <class Get, class Epi>
; DI void gemm_loop(int ntiles, int ld, char* shm, const Get& get, const Epi& epi) {
;     ...
;             G_LDB(B0, 0, 0); G_LDB(B1, 0, 1); SCHED; G_LDA(At, 0, 0); G_STAGE(G_SA(1, 1), a1 + hstep, voffA);
;             WAIT_V(8); WAIT_L(0); BAR; G_MMA(0, 0, At, B0); G_MMA(0, 1, At, B1); BAR; SCHED;
;             G_LDA(At, 0, 1); G_STAGE(G_SB(0, 0), b2, voffB); G_STAGE(G_SB(0, 1), b2 + hstep, voffB); G_STAGE(G_SA(0, 0), a2, voffA);
;             WAIT_V(8); WAIT_L(0); BAR; G_MMA(1, 0, At, B0); G_MMA(1, 1, At, B1); BAR; SCHED;
;             G_LDB(B0, 1, 0); G_LDB(B1, 1, 1); SCHED; G_LDA(At, 1, 0); G_STAGE(G_SA(0, 1), a2 + hstep, voffA);
;             WAIT_V(8); WAIT_L(0); BAR; G_MMA(0, 0, At, B0); G_MMA(0, 1, At, B1); BAR; SCHED;
;             G_LDA(At, 1, 1); G_STAGE(G_SB(1, 0), b3, voffB); G_STAGE(G_SB(1, 1), b3 + hstep, voffB); G_STAGE(G_SA(1, 0), a3, voffA);
;             WAIT_V(8); WAIT_L(0); BAR; G_MMA(1, 0, At, B0); G_MMA(1, 1, At, B1); BAR; SCHED;
	v_add_u32_e32 v176, s56, v168
	ds_read_b128 v[128:131], v140
	ds_read_b128 v[132:135], v140 offset:1024
	ds_read_b128 v[136:139], v140 offset:2048
	ds_read_b128 v[140:143], v140 offset:3072
	ds_read_b128 v[158:161], v176
	ds_read_b128 v[162:165], v176 offset:1024
	ds_read_b128 v[172:175], v176 offset:2048
	ds_read_b128 v[176:179], v176 offset:3072
	s_add_u32 s2, s34, 0xb0000
	s_addc_u32 s3, s35, 0
	s_mov_b32 m0, s38
	v_lshl_add_u64 v[216:217], s[2:3], 0, v[146:147]
	ds_read_b128 v[180:183], v171 offset:32768
	ds_read_b128 v[184:187], v171 offset:33792
	ds_read_b128 v[188:191], v171 offset:34816
	ds_read_b128 v[192:195], v171 offset:35840
	ds_read_b128 v[196:199], v171 offset:36864
	ds_read_b128 v[200:203], v171 offset:37888
	ds_read_b128 v[204:207], v171 offset:38912
	ds_read_b128 v[208:211], v171 offset:39936
	global_load_lds_dwordx4 v[216:217], off
	v_lshl_add_u64 v[216:217], s[2:3], 0, v[150:151]
	s_mov_b32 m0, s39
	s_nop 0
	global_load_lds_dwordx4 v[216:217], off
	s_waitcnt vmcnt(8)
	s_waitcnt lgkmcnt(0)
	s_barrier
	s_setprio 1
	s_waitcnt lgkmcnt(0)
	v_mfma_f32_16x16x32_bf16 v[124:127], v[128:131], v[180:183], v[124:127]
	v_mfma_f32_16x16x32_bf16 v[120:123], v[136:139], v[180:183], v[120:123]
	v_mfma_f32_16x16x32_bf16 v[116:119], v[128:131], v[188:191], v[116:119]
	v_mfma_f32_16x16x32_bf16 v[112:115], v[136:139], v[188:191], v[112:115]
	v_mfma_f32_16x16x32_bf16 v[108:111], v[128:131], v[196:199], v[108:111]
	v_mfma_f32_16x16x32_bf16 v[104:107], v[136:139], v[196:199], v[104:107]
	v_mfma_f32_16x16x32_bf16 v[100:103], v[128:131], v[204:207], v[100:103]
	v_mfma_f32_16x16x32_bf16 v[96:99], v[136:139], v[204:207], v[96:99]
	v_mfma_f32_16x16x32_bf16 v[124:127], v[132:135], v[184:187], v[124:127]
	v_mfma_f32_16x16x32_bf16 v[120:123], v[140:143], v[184:187], v[120:123]
	v_mfma_f32_16x16x32_bf16 v[116:119], v[132:135], v[192:195], v[116:119]
	v_mfma_f32_16x16x32_bf16 v[112:115], v[140:143], v[192:195], v[112:115]
	v_mfma_f32_16x16x32_bf16 v[108:111], v[132:135], v[200:203], v[108:111]
	v_mfma_f32_16x16x32_bf16 v[104:107], v[140:143], v[200:203], v[104:107]
	v_mfma_f32_16x16x32_bf16 v[100:103], v[132:135], v[208:211], v[100:103]
	v_mfma_f32_16x16x32_bf16 v[96:99], v[140:143], v[208:211], v[96:99]
	s_setprio 0
	s_setprio 1
	v_mfma_f32_16x16x32_bf16 v[60:63], v[158:161], v[180:183], v[60:63]
	v_mfma_f32_16x16x32_bf16 v[56:59], v[172:175], v[180:183], v[56:59]
	v_mfma_f32_16x16x32_bf16 v[52:55], v[158:161], v[188:191], v[52:55]
	v_mfma_f32_16x16x32_bf16 v[48:51], v[172:175], v[188:191], v[48:51]
	v_mfma_f32_16x16x32_bf16 v[44:47], v[158:161], v[196:199], v[44:47]
	v_mfma_f32_16x16x32_bf16 v[40:43], v[172:175], v[196:199], v[40:43]
	v_mfma_f32_16x16x32_bf16 v[36:39], v[158:161], v[204:207], v[36:39]
	v_mfma_f32_16x16x32_bf16 v[32:35], v[172:175], v[204:207], v[32:35]
	v_mfma_f32_16x16x32_bf16 v[60:63], v[162:165], v[184:187], v[60:63]
	v_mfma_f32_16x16x32_bf16 v[56:59], v[176:179], v[184:187], v[56:59]
	v_mfma_f32_16x16x32_bf16 v[52:55], v[162:165], v[192:195], v[52:55]
	v_mfma_f32_16x16x32_bf16 v[48:51], v[176:179], v[192:195], v[48:51]
	v_mfma_f32_16x16x32_bf16 v[44:47], v[162:165], v[200:203], v[44:47]
	v_mfma_f32_16x16x32_bf16 v[40:43], v[176:179], v[200:203], v[40:43]
	v_mfma_f32_16x16x32_bf16 v[36:39], v[162:165], v[208:211], v[36:39]
	v_mfma_f32_16x16x32_bf16 v[32:35], v[176:179], v[208:211], v[32:35]
	s_setprio 0
	s_add_i32 s2, s55, s33
	v_lshl_add_u64 v[144:145], v[144:145], 0, s[6:7]
	s_mov_b32 m0, s2
	s_barrier
	ds_read_b128 v[180:183], v171 offset:49152
	ds_read_b128 v[184:187], v171 offset:50176
	ds_read_b128 v[188:191], v171 offset:51200
	ds_read_b128 v[192:195], v171 offset:52224
	ds_read_b128 v[196:199], v171 offset:53248
	ds_read_b128 v[200:203], v171 offset:54272
	ds_read_b128 v[204:207], v171 offset:55296
	ds_read_b128 v[208:211], v171 offset:56320
	global_load_lds_dwordx4 v[144:145], off
	s_add_i32 m0, s2, 0x2000
	s_add_u32 s2, s30, 0xb0080
	v_lshl_add_u64 v[144:145], v[166:167], 0, s[6:7]
	s_addc_u32 s3, s31, 0
	s_add_i32 s30, s56, s33
	global_load_lds_dwordx4 v[144:145], off
	v_lshl_add_u64 v[144:145], s[2:3], 0, v[148:149]
	s_mov_b32 m0, s30
	s_nop 0
	global_load_lds_dwordx4 v[144:145], off
	v_lshl_add_u64 v[144:145], s[2:3], 0, v[152:153]
	s_add_i32 m0, s30, 0x2000
	s_nop 0
	global_load_lds_dwordx4 v[144:145], off
	v_lshl_add_u64 v[144:145], v[212:213], 0, s[6:7]
	s_mov_b32 m0, s42
	s_nop 0
	global_load_lds_dwordx4 v[144:145], off
	v_lshl_add_u64 v[144:145], v[214:215], 0, s[6:7]
	s_mov_b32 m0, s43
	s_nop 0
	global_load_lds_dwordx4 v[144:145], off
	s_waitcnt vmcnt(8)
	s_waitcnt lgkmcnt(0)
	s_barrier
	s_setprio 1
	s_waitcnt lgkmcnt(0)
	v_mfma_f32_16x16x32_bf16 v[92:95], v[128:131], v[180:183], v[92:95]
	v_mfma_f32_16x16x32_bf16 v[88:91], v[136:139], v[180:183], v[88:91]
	v_mfma_f32_16x16x32_bf16 v[84:87], v[128:131], v[188:191], v[84:87]
	v_mfma_f32_16x16x32_bf16 v[80:83], v[136:139], v[188:191], v[80:83]
	v_mfma_f32_16x16x32_bf16 v[76:79], v[128:131], v[196:199], v[76:79]
	v_mfma_f32_16x16x32_bf16 v[72:75], v[136:139], v[196:199], v[72:75]
	v_mfma_f32_16x16x32_bf16 v[68:71], v[128:131], v[204:207], v[68:71]
	v_mfma_f32_16x16x32_bf16 v[64:67], v[136:139], v[204:207], v[64:67]
	v_mfma_f32_16x16x32_bf16 v[92:95], v[132:135], v[184:187], v[92:95]
	v_mfma_f32_16x16x32_bf16 v[88:91], v[140:143], v[184:187], v[88:91]
	v_mfma_f32_16x16x32_bf16 v[84:87], v[132:135], v[192:195], v[84:87]
	v_mfma_f32_16x16x32_bf16 v[80:83], v[140:143], v[192:195], v[80:83]
	v_mfma_f32_16x16x32_bf16 v[76:79], v[132:135], v[200:203], v[76:79]
	v_mfma_f32_16x16x32_bf16 v[72:75], v[140:143], v[200:203], v[72:75]
	v_mfma_f32_16x16x32_bf16 v[68:71], v[132:135], v[208:211], v[68:71]
	v_mfma_f32_16x16x32_bf16 v[64:67], v[140:143], v[208:211], v[64:67]
	s_setprio 0
	s_setprio 1
	v_mfma_f32_16x16x32_bf16 v[28:31], v[158:161], v[180:183], v[28:31]
	v_mfma_f32_16x16x32_bf16 v[24:27], v[172:175], v[180:183], v[24:27]
	v_mfma_f32_16x16x32_bf16 v[20:23], v[158:161], v[188:191], v[20:23]
	v_mfma_f32_16x16x32_bf16 v[16:19], v[172:175], v[188:191], v[16:19]
	v_mfma_f32_16x16x32_bf16 v[12:15], v[158:161], v[196:199], v[12:15]
	v_mfma_f32_16x16x32_bf16 v[8:11], v[172:175], v[196:199], v[8:11]
	v_mfma_f32_16x16x32_bf16 v[4:7], v[158:161], v[204:207], v[4:7]
	v_mfma_f32_16x16x32_bf16 v[0:3], v[172:175], v[204:207], v[0:3]
	v_mfma_f32_16x16x32_bf16 v[28:31], v[162:165], v[184:187], v[28:31]
	v_mfma_f32_16x16x32_bf16 v[24:27], v[176:179], v[184:187], v[24:27]
	v_mfma_f32_16x16x32_bf16 v[20:23], v[162:165], v[192:195], v[20:23]
	v_mfma_f32_16x16x32_bf16 v[16:19], v[176:179], v[192:195], v[16:19]
	v_mfma_f32_16x16x32_bf16 v[12:15], v[162:165], v[200:203], v[12:15]
	v_mfma_f32_16x16x32_bf16 v[8:11], v[176:179], v[200:203], v[8:11]
	v_mfma_f32_16x16x32_bf16 v[4:7], v[162:165], v[208:211], v[4:7]
	v_mfma_f32_16x16x32_bf16 v[0:3], v[176:179], v[208:211], v[0:3]
	s_setprio 0
	s_add_i32 s54, s54, 2
	s_add_u32 s52, s52, 0x100
	s_addc_u32 s53, s53, 0
	s_cmp_gt_u32 s54, 41
	s_mov_b64 s[2:3], s[24:25]
	s_barrier
	s_cbranch_scc0 .LBB0_3759
